# all remaining flat_load/flat_store issued as global_load/global_store (same addresses)
# baseline (speedup 1.0000x reference)
; #define LAS __attribute__((address_space(3)))
; DI unsigned pk2(float lo, float hi) { typedef float v2f __attribute__((ext_vector_type(2))); typedef __bf16 v2b __attribute__((ext_vector_type(2))); v2f v = {lo, hi}; v2b b = __builtin_convertvector(v, v2b); return __builtin_bit_cast(unsigned, b); }
; DI bf16_t* dest_rows(int mode, int n0, int K, bf16_t* d0, bf16_t* d1) {
;     if (mode == 1) { const int isu = n0 >= FF ? 1 : 0, c = n0 - isu * FF; return d0 + (size_t)((c >> 7) * 256 + isu * 128 + (c & 127)) * K; }
;     if (mode == 2) {
;         if (n0 < 1664) return d0 + (size_t)n0 * K;
;         if (n0 < 1696) return d0 + (size_t)(2176 + n0 - 1664) * K;
;         if (n0 < 2208) return d0 + (size_t)(1664 + n0 - 1696) * K;
;         return d1 + (size_t)(n0 - 2208) * K;
;     }
;     return d0 + (size_t)n0 * K;
; }
;     if (nb1 < 0) nb1 = N / 32;
;     const int nblk = nb1 - nb0, nitems = (K / 64) * nblk;
;     for (int item = gw; item < nitems; item += ngw) {
;         const int kb = item / nblk, nb = nb0 + item % nblk, k0 = 64 * kb, n0 = 32 * nb;
;         float tv[32];
; #pragma unroll
;         for (int i = 0; i < 32; ++i) { const int kk = 2 * i + (lane >> 5); tv[i] = W[(size_t)(k0 + kk) * N + n0 + (lane & 31)]; }
; #pragma unroll
;         for (int i = 0; i < 32; ++i) { const int kk = 2 * i + (lane >> 5); float v = tv[i]; if (gk) v *= gk[k0 + kk]; scr[kk * 33 + (lane & 31)] = v; }
;         asm volatile("s_waitcnt lgkmcnt(0)" ::: "memory");
;         bf16_t* dst = dest_rows(mode, n0, K, d0, d1);
;         const int c = lane & 7;
; #pragma unroll
;         for (int jj = 0; jj < 4; ++jj) { const int n = (lane >> 3) + 8 * jj; const LAS float* s = scr + (8 * c) * 33 + n;
;             u32x4 o; o.x = pk2(s[0 * 33], s[1 * 33]); o.y = pk2(s[2 * 33], s[3 * 33]); o.z = pk2(s[4 * 33], s[5 * 33]); o.w = pk2(s[6 * 33], s[7 * 33]);
;             *(u32x4*)(dst + (size_t)n * K + k0 + 8 * c) = o; }
;         asm volatile("s_waitcnt lgkmcnt(0)" ::: "memory");
;     }
.LBB0_20:
	s_mulk_i32 s36, 0xff50
	s_add_i32 s11, s34, s36
	s_cmpk_gt_i32 s11, 0x57
	s_cselect_b32 s11, 0xfffff500, 0
	s_cselect_b32 s12, 0x80, 0
	s_add_i32 s11, s11, s14
	s_add_i32 s11, s11, s35
	s_lshl_b32 s11, s11, 1
	s_and_b32 s10, s10, 0x60
	s_and_b32 s11, s11, 0xffffff00
	s_or_b32 s10, s12, s10
	s_waitcnt vmcnt(0)
	v_add_u32_e32 v5, 0x400, v9
	s_or_b32 s10, s10, s11
	ds_write2_b32 v5, v18, v19 offset0:8 offset1:74
	s_ashr_i32 s11, s10, 31
	s_waitcnt lgkmcnt(0)
	s_lshl_b64 s[10:11], s[10:11], 11
	s_add_u32 s10, s8, s10
	ds_read_b32 v5, v44
	s_waitcnt vmcnt(2)
	ds_read_b32 v7, v44 offset:132
	ds_read_b32 v9, v44 offset:264
	ds_read_b32 v11, v44 offset:396
	ds_read_b32 v13, v44 offset:528
	ds_read_b32 v18, v44 offset:660
	ds_read_b32 v19, v44 offset:792
	ds_read_b32 v22, v44 offset:924
	s_addc_u32 s11, s9, s11
	s_lshl_b64 s[6:7], s[6:7], 1
	s_add_u32 s6, s10, s6
	s_addc_u32 s7, s11, s7
	v_lshl_add_u64 v[20:21], s[6:7], 0, v[2:3]
	s_waitcnt vmcnt(1) lgkmcnt(0)
	v_cvt_pk_bf16_f32 v16, v5, v7
	v_mov_b32_e32 v7, v3
	s_waitcnt vmcnt(0) lgkmcnt(4)
	v_cvt_pk_bf16_f32 v17, v9, v11
	s_waitcnt lgkmcnt(2)
	v_cvt_pk_bf16_f32 v18, v13, v18
	s_waitcnt lgkmcnt(0)
	v_cvt_pk_bf16_f32 v19, v19, v22
	v_lshl_add_u64 v[22:23], v[20:21], 0, v[6:7]
	global_store_dwordx4 v[22:23], v[16:19], off
	ds_read_b32 v5, v44 offset:32
	ds_read_b32 v7, v44 offset:164
	ds_read_b32 v9, v44 offset:296
	ds_read_b32 v11, v44 offset:428
	ds_read_b32 v13, v44 offset:560
	ds_read_b32 v18, v44 offset:692
	ds_read_b32 v19, v44 offset:824
	ds_read_b32 v22, v44 offset:956
	s_waitcnt lgkmcnt(0)
	v_cvt_pk_bf16_f32 v17, v9, v11
	v_mov_b32_e32 v9, v3
	v_cvt_pk_bf16_f32 v16, v5, v7
	v_cvt_pk_bf16_f32 v18, v13, v18
	v_cvt_pk_bf16_f32 v19, v19, v22
	v_lshl_add_u64 v[22:23], v[20:21], 0, v[8:9]
	global_store_dwordx4 v[22:23], v[16:19], off
	ds_read_b32 v5, v44 offset:64
	ds_read_b32 v7, v44 offset:196
	ds_read_b32 v9, v44 offset:328
	ds_read_b32 v11, v44 offset:460
	ds_read_b32 v13, v44 offset:592
	ds_read_b32 v18, v44 offset:724
	ds_read_b32 v19, v44 offset:856
	ds_read_b32 v22, v44 offset:988
	s_waitcnt lgkmcnt(0)
	v_cvt_pk_bf16_f32 v17, v9, v11
	v_mov_b32_e32 v11, v3
	v_cvt_pk_bf16_f32 v16, v5, v7
	v_cvt_pk_bf16_f32 v18, v13, v18
	v_cvt_pk_bf16_f32 v19, v19, v22
	v_lshl_add_u64 v[22:23], v[20:21], 0, v[10:11]
	global_store_dwordx4 v[22:23], v[16:19], off
	ds_read_b32 v5, v44 offset:96
	ds_read_b32 v7, v44 offset:228
	ds_read_b32 v9, v44 offset:360
	ds_read_b32 v11, v44 offset:492
	ds_read_b32 v13, v44 offset:624
	ds_read_b32 v18, v44 offset:756
	ds_read_b32 v19, v44 offset:888
	ds_read_b32 v22, v44 offset:1020
	s_waitcnt lgkmcnt(0)
	v_cvt_pk_bf16_f32 v16, v5, v7
	v_cvt_pk_bf16_f32 v17, v9, v11
	v_cvt_pk_bf16_f32 v18, v13, v18
	v_mov_b32_e32 v13, v3
	v_cvt_pk_bf16_f32 v19, v19, v22
	v_lshl_add_u64 v[20:21], v[20:21], 0, v[12:13]
	global_store_dwordx4 v[20:21], v[16:19], off
	s_waitcnt lgkmcnt(0)
	s_add_i32 s34, s34, s88
	s_add_i32 s14, s14, s15
	s_cmpk_lt_i32 s34, 0xb00
	s_cbranch_scc0 .LBB0_53

;     ...
;     for (int item = gw; item < nitems; item += ngw) {
;         const int kb = item / nblk, nb = nb0 + item % nblk, k0 = 64 * kb, n0 = 32 * nb;
;         float tv[32];
; #pragma unroll
;         for (int i = 0; i < 32; ++i) { const int kk = 2 * i + (lane >> 5); tv[i] = W[(size_t)(k0 + kk) * N + n0 + (lane & 31)]; }
.LBB0_55:
	s_ashr_i32 s2, s33, 31
	s_lshr_b32 s2, s2, 27
	s_add_i32 s2, s33, s2
	s_ashr_i32 s3, s2, 5
	s_lshl_b32 s2, s3, 6
	s_lshl_b32 s3, s3, 10
	v_or_b32_e32 v22, s2, v0
	s_sub_i32 s6, s14, s3
	v_or_b32_e32 v24, 2, v22
	v_or_b32_e32 v38, 12, v22
	v_or_b32_e32 v40, 14, v22
	v_or_b32_e32 v42, 16, v22
	v_or_b32_e32 v58, 18, v22
	v_or_b32_e32 v64, 20, v22
	v_or_b32_e32 v66, 22, v22
	v_or_b32_e32 v68, 24, v22
	v_or_b32_e32 v70, 26, v22
	v_or_b32_e32 v72, 28, v22
	v_or_b32_e32 v74, 30, v22
	v_or_b32_e32 v76, 32, v22
	v_or_b32_e32 v78, 34, v22
	v_or_b32_e32 v80, 36, v22
	s_ashr_i32 s7, s6, 31
	v_ashrrev_i32_e32 v23, 31, v22
	v_or_b32_e32 v26, 4, v22
	v_or_b32_e32 v28, 6, v22
	v_or_b32_e32 v30, 8, v22
	v_or_b32_e32 v32, 10, v22
	v_or_b32_e32 v82, 38, v22
	v_or_b32_e32 v84, 40, v22
	v_or_b32_e32 v86, 42, v22
	v_or_b32_e32 v88, 44, v22
	v_or_b32_e32 v90, 46, v22
	v_or_b32_e32 v92, 48, v22
	v_or_b32_e32 v94, 50, v22
	v_or_b32_e32 v96, 52, v22
	v_or_b32_e32 v98, 54, v22
	v_or_b32_e32 v100, 56, v22
	v_or_b32_e32 v102, 58, v22
	v_or_b32_e32 v104, 60, v22
	v_or_b32_e32 v106, 62, v22
	v_ashrrev_i32_e32 v25, 31, v24
	v_ashrrev_i32_e32 v39, 31, v38
	v_ashrrev_i32_e32 v41, 31, v40
	v_ashrrev_i32_e32 v43, 31, v42
	v_ashrrev_i32_e32 v59, 31, v58
	v_ashrrev_i32_e32 v65, 31, v64
	v_ashrrev_i32_e32 v67, 31, v66
	v_ashrrev_i32_e32 v69, 31, v68
	v_ashrrev_i32_e32 v71, 31, v70
	v_ashrrev_i32_e32 v73, 31, v72
	v_ashrrev_i32_e32 v75, 31, v74
	v_ashrrev_i32_e32 v77, 31, v76
	v_ashrrev_i32_e32 v79, 31, v78
	v_ashrrev_i32_e32 v81, 31, v80
	v_lshlrev_b64 v[22:23], 12, v[22:23]
	v_ashrrev_i32_e32 v27, 31, v26
	v_ashrrev_i32_e32 v29, 31, v28
	v_ashrrev_i32_e32 v31, 31, v30
	v_ashrrev_i32_e32 v33, 31, v32
	v_ashrrev_i32_e32 v83, 31, v82
	v_ashrrev_i32_e32 v85, 31, v84
	v_ashrrev_i32_e32 v87, 31, v86
	v_ashrrev_i32_e32 v89, 31, v88
	v_ashrrev_i32_e32 v91, 31, v90
	v_ashrrev_i32_e32 v93, 31, v92
	v_ashrrev_i32_e32 v95, 31, v94
	v_ashrrev_i32_e32 v97, 31, v96
	v_ashrrev_i32_e32 v99, 31, v98
	v_ashrrev_i32_e32 v101, 31, v100
	v_ashrrev_i32_e32 v103, 31, v102
	v_ashrrev_i32_e32 v105, 31, v104
	v_ashrrev_i32_e32 v107, 31, v106
	v_lshl_add_u64 v[108:109], s[6:7], 2, v[14:15]
	v_lshlrev_b64 v[24:25], 12, v[24:25]
	v_lshlrev_b64 v[38:39], 12, v[38:39]
	v_lshlrev_b64 v[40:41], 12, v[40:41]
	v_lshlrev_b64 v[42:43], 12, v[42:43]
	v_lshlrev_b64 v[58:59], 12, v[58:59]
	v_lshlrev_b64 v[64:65], 12, v[64:65]
	v_lshlrev_b64 v[66:67], 12, v[66:67]
	v_lshlrev_b64 v[68:69], 12, v[68:69]
	v_lshlrev_b64 v[70:71], 12, v[70:71]
	v_lshlrev_b64 v[72:73], 12, v[72:73]
	v_lshlrev_b64 v[74:75], 12, v[74:75]
	v_lshlrev_b64 v[76:77], 12, v[76:77]
	v_lshlrev_b64 v[78:79], 12, v[78:79]
	v_lshlrev_b64 v[80:81], 12, v[80:81]
	v_lshl_add_u64 v[22:23], v[108:109], 0, v[22:23]
	v_lshlrev_b64 v[26:27], 12, v[26:27]
	v_lshlrev_b64 v[28:29], 12, v[28:29]
	v_lshlrev_b64 v[30:31], 12, v[30:31]
	v_lshlrev_b64 v[32:33], 12, v[32:33]
	v_lshlrev_b64 v[82:83], 12, v[82:83]
	v_lshlrev_b64 v[84:85], 12, v[84:85]
	v_lshlrev_b64 v[86:87], 12, v[86:87]
	v_lshlrev_b64 v[88:89], 12, v[88:89]
	v_lshlrev_b64 v[90:91], 12, v[90:91]
	v_lshlrev_b64 v[92:93], 12, v[92:93]
	v_lshlrev_b64 v[94:95], 12, v[94:95]
	v_lshlrev_b64 v[96:97], 12, v[96:97]
	v_lshlrev_b64 v[98:99], 12, v[98:99]
	v_lshlrev_b64 v[100:101], 12, v[100:101]
	v_lshlrev_b64 v[102:103], 12, v[102:103]
	v_lshlrev_b64 v[104:105], 12, v[104:105]
	v_lshlrev_b64 v[106:107], 12, v[106:107]
	v_lshl_add_u64 v[24:25], v[108:109], 0, v[24:25]
	v_lshl_add_u64 v[38:39], v[108:109], 0, v[38:39]
	v_lshl_add_u64 v[40:41], v[108:109], 0, v[40:41]
	v_lshl_add_u64 v[42:43], v[108:109], 0, v[42:43]
	v_lshl_add_u64 v[58:59], v[108:109], 0, v[58:59]
	v_lshl_add_u64 v[64:65], v[108:109], 0, v[64:65]
	v_lshl_add_u64 v[66:67], v[108:109], 0, v[66:67]
	v_lshl_add_u64 v[68:69], v[108:109], 0, v[68:69]
	v_lshl_add_u64 v[70:71], v[108:109], 0, v[70:71]
	v_lshl_add_u64 v[72:73], v[108:109], 0, v[72:73]
	v_lshl_add_u64 v[74:75], v[108:109], 0, v[74:75]
	v_lshl_add_u64 v[76:77], v[108:109], 0, v[76:77]
	v_lshl_add_u64 v[78:79], v[108:109], 0, v[78:79]
	v_lshl_add_u64 v[80:81], v[108:109], 0, v[80:81]
	v_lshl_add_u64 v[26:27], v[108:109], 0, v[26:27]
	v_lshl_add_u64 v[28:29], v[108:109], 0, v[28:29]
	v_lshl_add_u64 v[30:31], v[108:109], 0, v[30:31]
	v_lshl_add_u64 v[32:33], v[108:109], 0, v[32:33]
	v_lshl_add_u64 v[82:83], v[108:109], 0, v[82:83]
	v_lshl_add_u64 v[84:85], v[108:109], 0, v[84:85]
	v_lshl_add_u64 v[86:87], v[108:109], 0, v[86:87]
	v_lshl_add_u64 v[88:89], v[108:109], 0, v[88:89]
	v_lshl_add_u64 v[90:91], v[108:109], 0, v[90:91]
	v_lshl_add_u64 v[92:93], v[108:109], 0, v[92:93]
	v_lshl_add_u64 v[94:95], v[108:109], 0, v[94:95]
	v_lshl_add_u64 v[96:97], v[108:109], 0, v[96:97]
	v_lshl_add_u64 v[98:99], v[108:109], 0, v[98:99]
	v_lshl_add_u64 v[100:101], v[108:109], 0, v[100:101]
	v_lshl_add_u64 v[102:103], v[108:109], 0, v[102:103]
	v_lshl_add_u64 v[104:105], v[108:109], 0, v[104:105]
	v_lshl_add_u64 v[106:107], v[108:109], 0, v[106:107]
	global_load_dword v21, v[22:23], off
	s_nop 0
	global_load_dword v22, v[24:25], off
	global_load_dword v23, v[26:27], off
	s_nop 0
	global_load_dword v24, v[28:29], off
	global_load_dword v25, v[30:31], off
	global_load_dword v37, v[32:33], off
	s_nop 0
	global_load_dword v38, v[38:39], off
	s_nop 0
	global_load_dword v39, v[40:41], off
	s_nop 0
	global_load_dword v40, v[42:43], off
	global_load_dword v41, v[58:59], off
	s_nop 0
	global_load_dword v42, v[64:65], off
	global_load_dword v43, v[66:67], off
	global_load_dword v58, v[68:69], off
	global_load_dword v59, v[70:71], off
	s_nop 0
	global_load_dword v64, v[72:73], off
	global_load_dword v65, v[74:75], off
	global_load_dword v66, v[76:77], off
	global_load_dword v67, v[78:79], off
	global_load_dword v68, v[80:81], off
	global_load_dword v69, v[82:83], off
	global_load_dword v70, v[84:85], off
	global_load_dword v71, v[86:87], off
	global_load_dword v72, v[88:89], off
	global_load_dword v73, v[90:91], off
	global_load_dword v74, v[92:93], off
	global_load_dword v75, v[94:95], off
	global_load_dword v76, v[96:97], off
	global_load_dword v77, v[98:99], off
	global_load_dword v78, v[100:101], off
	global_load_dword v79, v[102:103], off
	global_load_dword v80, v[104:105], off
	global_load_dword v81, v[106:107], off
	s_lshl_b64 s[6:7], s[6:7], 11
	s_waitcnt vmcnt(0)
; #define LAS __attribute__((address_space(3)))
; DI unsigned pk2(float lo, float hi) { typedef float v2f __attribute__((ext_vector_type(2))); typedef __bf16 v2b __attribute__((ext_vector_type(2))); v2f v = {lo, hi}; v2b b = __builtin_convertvector(v, v2b); return __builtin_bit_cast(unsigned, b); }
;     ...
;         for (int i = 0; i < 32; ++i) { const int kk = 2 * i + (lane >> 5); float v = tv[i]; if (gk) v *= gk[k0 + kk]; scr[kk * 33 + (lane & 31)] = v; }
;         asm volatile("s_waitcnt lgkmcnt(0)" ::: "memory");
;         bf16_t* dst = dest_rows(mode, n0, K, d0, d1);
;         const int c = lane & 7;
; #pragma unroll
;         for (int jj = 0; jj < 4; ++jj) { const int n = (lane >> 3) + 8 * jj; const LAS float* s = scr + (8 * c) * 33 + n;
;             u32x4 o; o.x = pk2(s[0 * 33], s[1 * 33]); o.y = pk2(s[2 * 33], s[3 * 33]); o.z = pk2(s[4 * 33], s[5 * 33]); o.w = pk2(s[6 * 33], s[7 * 33]);
;             *(u32x4*)(dst + (size_t)n * K + k0 + 8 * c) = o; }
;         asm volatile("s_waitcnt lgkmcnt(0)" ::: "memory");
;     }
	ds_write2_b32 v45, v21, v22 offset1:66
	ds_write2_b32 v45, v23, v24 offset0:132 offset1:198
	ds_write2_b32 v1, v25, v37 offset0:8 offset1:74
	ds_write2_b32 v1, v38, v39 offset0:140 offset1:206
	ds_write2_b32 v5, v40, v41 offset0:16 offset1:82
	ds_write2_b32 v5, v42, v43 offset0:148 offset1:214
	ds_write2_b32 v16, v58, v59 offset0:24 offset1:90
	ds_write2_b32 v16, v64, v65 offset0:156 offset1:222
	ds_write2_b32 v17, v66, v67 offset0:32 offset1:98
	ds_write2_b32 v17, v68, v69 offset0:164 offset1:230
	ds_write2_b32 v18, v70, v71 offset0:40 offset1:106
	ds_write2_b32 v18, v72, v73 offset0:172 offset1:238
	ds_write2_b32 v19, v74, v75 offset0:48 offset1:114
	ds_write2_b32 v19, v76, v77 offset0:180 offset1:246
	ds_write2_b32 v20, v78, v79 offset0:56 offset1:122
	ds_write2_b32 v20, v80, v81 offset0:188 offset1:254
	s_add_u32 s6, s12, s6
	s_waitcnt lgkmcnt(0)
	s_addc_u32 s7, s13, s7
	s_ashr_i32 s3, s2, 31
	ds_read_b32 v21, v44
	ds_read_b32 v22, v44 offset:132
	ds_read_b32 v23, v44 offset:264
	ds_read_b32 v24, v44 offset:396
	ds_read_b32 v25, v44 offset:528
	ds_read_b32 v37, v44 offset:660
	ds_read_b32 v38, v44 offset:792
	ds_read_b32 v39, v44 offset:924
	s_lshl_b64 s[2:3], s[2:3], 1
	s_add_u32 s2, s6, s2
	s_addc_u32 s3, s7, s3
	v_lshl_add_u64 v[26:27], s[2:3], 0, v[2:3]
	v_lshl_add_u64 v[28:29], v[26:27], 0, v[6:7]
	s_waitcnt lgkmcnt(0)
	v_cvt_pk_bf16_f32 v22, v21, v22
	v_cvt_pk_bf16_f32 v23, v23, v24
	v_cvt_pk_bf16_f32 v24, v25, v37
	v_cvt_pk_bf16_f32 v25, v38, v39
	global_store_dwordx4 v[28:29], v[22:25], off
	ds_read_b32 v21, v44 offset:32
	ds_read_b32 v22, v44 offset:164
	ds_read_b32 v23, v44 offset:296
	ds_read_b32 v24, v44 offset:428
	ds_read_b32 v25, v44 offset:560
	ds_read_b32 v28, v44 offset:692
	ds_read_b32 v29, v44 offset:824
	ds_read_b32 v37, v44 offset:956
	v_lshl_add_u64 v[30:31], v[26:27], 0, v[8:9]
	s_waitcnt lgkmcnt(0)
	v_cvt_pk_bf16_f32 v22, v21, v22
	v_cvt_pk_bf16_f32 v23, v23, v24
	v_cvt_pk_bf16_f32 v24, v25, v28
	v_cvt_pk_bf16_f32 v25, v29, v37
	global_store_dwordx4 v[30:31], v[22:25], off
	ds_read_b32 v21, v44 offset:64
	ds_read_b32 v22, v44 offset:196
	ds_read_b32 v23, v44 offset:328
	ds_read_b32 v24, v44 offset:460
	ds_read_b32 v25, v44 offset:592
	ds_read_b32 v28, v44 offset:724
	ds_read_b32 v29, v44 offset:856
	ds_read_b32 v30, v44 offset:988
	v_lshl_add_u64 v[32:33], v[26:27], 0, v[10:11]
	s_waitcnt lgkmcnt(0)
	v_cvt_pk_bf16_f32 v22, v21, v22
	v_cvt_pk_bf16_f32 v23, v23, v24
	v_cvt_pk_bf16_f32 v24, v25, v28
	v_cvt_pk_bf16_f32 v25, v29, v30
	global_store_dwordx4 v[32:33], v[22:25], off
	ds_read_b32 v21, v44 offset:96
	ds_read_b32 v22, v44 offset:228
	ds_read_b32 v23, v44 offset:360
	ds_read_b32 v24, v44 offset:492
	ds_read_b32 v25, v44 offset:624
	ds_read_b32 v28, v44 offset:756
	ds_read_b32 v29, v44 offset:888
	ds_read_b32 v30, v44 offset:1020
	v_lshl_add_u64 v[26:27], v[26:27], 0, v[12:13]
	s_waitcnt lgkmcnt(0)
	v_cvt_pk_bf16_f32 v22, v21, v22
	v_cvt_pk_bf16_f32 v23, v23, v24
	v_cvt_pk_bf16_f32 v24, v25, v28
	v_cvt_pk_bf16_f32 v25, v29, v30
	global_store_dwordx4 v[26:27], v[22:25], off
	s_waitcnt lgkmcnt(0)
	s_add_i32 s33, s33, s88
	s_add_i32 s14, s14, s15
	s_cmpk_lt_i32 s33, 0x200
	s_cbranch_scc1 .LBB0_55

;     ...
;     for (int item = gw; item < nitems; item += ngw) {
;         const int kb = item / nblk, nb = nb0 + item % nblk, k0 = 64 * kb, n0 = 32 * nb;
;         float tv[32];
; #pragma unroll
;         for (int i = 0; i < 32; ++i) { const int kk = 2 * i + (lane >> 5); tv[i] = W[(size_t)(k0 + kk) * N + n0 + (lane & 31)]; }
.LBB0_59:
	s_ashr_i32 s2, s37, 31
	s_lshr_b32 s2, s2, 27
	s_add_i32 s2, s37, s2
	s_ashr_i32 s3, s2, 5
	s_lshl_b32 s2, s3, 6
	s_lshl_b32 s3, s3, 10
	v_or_b32_e32 v20, s2, v0
	s_sub_i32 s14, s33, s3
	v_or_b32_e32 v22, 2, v20
	v_or_b32_e32 v30, 10, v20
	v_or_b32_e32 v32, 12, v20
	v_or_b32_e32 v38, 14, v20
	v_or_b32_e32 v40, 16, v20
	v_or_b32_e32 v42, 18, v20
	v_or_b32_e32 v58, 20, v20
	v_or_b32_e32 v64, 22, v20
	v_or_b32_e32 v66, 24, v20
	v_or_b32_e32 v68, 26, v20
	v_or_b32_e32 v70, 28, v20
	v_or_b32_e32 v72, 30, v20
	v_or_b32_e32 v74, 32, v20
	v_or_b32_e32 v76, 34, v20
	v_or_b32_e32 v78, 36, v20
	s_ashr_i32 s15, s14, 31
	v_ashrrev_i32_e32 v21, 31, v20
	v_or_b32_e32 v24, 4, v20
	v_or_b32_e32 v26, 6, v20
	v_or_b32_e32 v28, 8, v20
	v_or_b32_e32 v80, 38, v20
	v_or_b32_e32 v82, 40, v20
	v_or_b32_e32 v84, 42, v20
	v_or_b32_e32 v86, 44, v20
	v_or_b32_e32 v88, 46, v20
	v_or_b32_e32 v90, 48, v20
	v_or_b32_e32 v92, 50, v20
	v_or_b32_e32 v94, 52, v20
	v_or_b32_e32 v96, 54, v20
	v_or_b32_e32 v98, 56, v20
	v_or_b32_e32 v100, 58, v20
	v_or_b32_e32 v102, 60, v20
	v_or_b32_e32 v104, 62, v20
	v_ashrrev_i32_e32 v23, 31, v22
	v_ashrrev_i32_e32 v31, 31, v30
	v_ashrrev_i32_e32 v33, 31, v32
	v_ashrrev_i32_e32 v39, 31, v38
	v_ashrrev_i32_e32 v41, 31, v40
	v_ashrrev_i32_e32 v43, 31, v42
	v_ashrrev_i32_e32 v59, 31, v58
	v_ashrrev_i32_e32 v65, 31, v64
	v_ashrrev_i32_e32 v67, 31, v66
	v_ashrrev_i32_e32 v69, 31, v68
	v_ashrrev_i32_e32 v71, 31, v70
	v_ashrrev_i32_e32 v73, 31, v72
	v_ashrrev_i32_e32 v75, 31, v74
	v_ashrrev_i32_e32 v77, 31, v76
	v_ashrrev_i32_e32 v79, 31, v78
	v_lshl_add_u64 v[106:107], s[14:15], 2, v[16:17]
	v_lshlrev_b64 v[20:21], 12, v[20:21]
	v_ashrrev_i32_e32 v25, 31, v24
	v_ashrrev_i32_e32 v27, 31, v26
	v_ashrrev_i32_e32 v29, 31, v28
	v_ashrrev_i32_e32 v81, 31, v80
	v_ashrrev_i32_e32 v83, 31, v82
	v_ashrrev_i32_e32 v85, 31, v84
	v_ashrrev_i32_e32 v87, 31, v86
	v_ashrrev_i32_e32 v89, 31, v88
	v_ashrrev_i32_e32 v91, 31, v90
	v_ashrrev_i32_e32 v93, 31, v92
	v_ashrrev_i32_e32 v95, 31, v94
	v_ashrrev_i32_e32 v97, 31, v96
	v_ashrrev_i32_e32 v99, 31, v98
	v_ashrrev_i32_e32 v101, 31, v100
	v_ashrrev_i32_e32 v103, 31, v102
	v_ashrrev_i32_e32 v105, 31, v104
	v_lshlrev_b64 v[22:23], 12, v[22:23]
	v_lshlrev_b64 v[30:31], 12, v[30:31]
	v_lshlrev_b64 v[32:33], 12, v[32:33]
	v_lshlrev_b64 v[38:39], 12, v[38:39]
	v_lshlrev_b64 v[40:41], 12, v[40:41]
	v_lshlrev_b64 v[42:43], 12, v[42:43]
	v_lshlrev_b64 v[58:59], 12, v[58:59]
	v_lshlrev_b64 v[64:65], 12, v[64:65]
	v_lshlrev_b64 v[66:67], 12, v[66:67]
	v_lshlrev_b64 v[68:69], 12, v[68:69]
	v_lshlrev_b64 v[70:71], 12, v[70:71]
	v_lshlrev_b64 v[72:73], 12, v[72:73]
	v_lshlrev_b64 v[74:75], 12, v[74:75]
	v_lshlrev_b64 v[76:77], 12, v[76:77]
	v_lshlrev_b64 v[78:79], 12, v[78:79]
	v_lshl_add_u64 v[20:21], v[106:107], 0, v[20:21]
	v_lshlrev_b64 v[24:25], 12, v[24:25]
	v_lshlrev_b64 v[26:27], 12, v[26:27]
	v_lshlrev_b64 v[28:29], 12, v[28:29]
	v_lshlrev_b64 v[80:81], 12, v[80:81]
	v_lshlrev_b64 v[82:83], 12, v[82:83]
	v_lshlrev_b64 v[84:85], 12, v[84:85]
	v_lshlrev_b64 v[86:87], 12, v[86:87]
	v_lshlrev_b64 v[88:89], 12, v[88:89]
	v_lshlrev_b64 v[90:91], 12, v[90:91]
	v_lshlrev_b64 v[92:93], 12, v[92:93]
	v_lshlrev_b64 v[94:95], 12, v[94:95]
	v_lshlrev_b64 v[96:97], 12, v[96:97]
	v_lshlrev_b64 v[98:99], 12, v[98:99]
	v_lshlrev_b64 v[100:101], 12, v[100:101]
	v_lshlrev_b64 v[102:103], 12, v[102:103]
	v_lshlrev_b64 v[104:105], 12, v[104:105]
	v_lshl_add_u64 v[22:23], v[106:107], 0, v[22:23]
	v_lshl_add_u64 v[30:31], v[106:107], 0, v[30:31]
	v_lshl_add_u64 v[32:33], v[106:107], 0, v[32:33]
	v_lshl_add_u64 v[38:39], v[106:107], 0, v[38:39]
	v_lshl_add_u64 v[40:41], v[106:107], 0, v[40:41]
	v_lshl_add_u64 v[42:43], v[106:107], 0, v[42:43]
	v_lshl_add_u64 v[58:59], v[106:107], 0, v[58:59]
	v_lshl_add_u64 v[64:65], v[106:107], 0, v[64:65]
	v_lshl_add_u64 v[66:67], v[106:107], 0, v[66:67]
	v_lshl_add_u64 v[68:69], v[106:107], 0, v[68:69]
	v_lshl_add_u64 v[70:71], v[106:107], 0, v[70:71]
	v_lshl_add_u64 v[72:73], v[106:107], 0, v[72:73]
	v_lshl_add_u64 v[74:75], v[106:107], 0, v[74:75]
	v_lshl_add_u64 v[76:77], v[106:107], 0, v[76:77]
	v_lshl_add_u64 v[78:79], v[106:107], 0, v[78:79]
	v_lshl_add_u64 v[24:25], v[106:107], 0, v[24:25]
	v_lshl_add_u64 v[26:27], v[106:107], 0, v[26:27]
	v_lshl_add_u64 v[28:29], v[106:107], 0, v[28:29]
	v_lshl_add_u64 v[80:81], v[106:107], 0, v[80:81]
	v_lshl_add_u64 v[82:83], v[106:107], 0, v[82:83]
	v_lshl_add_u64 v[84:85], v[106:107], 0, v[84:85]
	v_lshl_add_u64 v[86:87], v[106:107], 0, v[86:87]
	v_lshl_add_u64 v[88:89], v[106:107], 0, v[88:89]
	v_lshl_add_u64 v[90:91], v[106:107], 0, v[90:91]
	v_lshl_add_u64 v[92:93], v[106:107], 0, v[92:93]
	v_lshl_add_u64 v[94:95], v[106:107], 0, v[94:95]
	v_lshl_add_u64 v[96:97], v[106:107], 0, v[96:97]
	v_lshl_add_u64 v[98:99], v[106:107], 0, v[98:99]
	v_lshl_add_u64 v[100:101], v[106:107], 0, v[100:101]
	v_lshl_add_u64 v[102:103], v[106:107], 0, v[102:103]
	v_lshl_add_u64 v[104:105], v[106:107], 0, v[104:105]
	global_load_dword v19, v[20:21], off
	s_nop 0
	global_load_dword v22, v[22:23], off
	s_nop 0
	global_load_dword v23, v[24:25], off
	global_load_dword v37, v[26:27], off
	global_load_dword v106, v[28:29], off
	s_nop 0
	global_load_dword v31, v[30:31], off
	s_nop 0
	global_load_dword v32, v[32:33], off
	s_nop 0
	global_load_dword v33, v[38:39], off
	s_nop 0
	global_load_dword v38, v[40:41], off
	global_load_dword v39, v[42:43], off
	s_nop 0
	global_load_dword v40, v[58:59], off
	global_load_dword v41, v[64:65], off
	global_load_dword v42, v[66:67], off
	global_load_dword v43, v[68:69], off
	s_nop 0
	global_load_dword v58, v[70:71], off
	global_load_dword v59, v[72:73], off
	global_load_dword v64, v[74:75], off
	global_load_dword v65, v[76:77], off
	global_load_dword v66, v[78:79], off
	global_load_dword v67, v[80:81], off
	global_load_dword v68, v[82:83], off
	global_load_dword v69, v[84:85], off
	global_load_dword v70, v[86:87], off
	global_load_dword v71, v[88:89], off
	global_load_dword v72, v[90:91], off
	global_load_dword v73, v[92:93], off
	global_load_dword v74, v[94:95], off
	global_load_dword v75, v[96:97], off
	global_load_dword v76, v[98:99], off
	global_load_dword v77, v[100:101], off
	global_load_dword v78, v[102:103], off
	global_load_dword v79, v[104:105], off
	s_mul_hi_i32 s3, s14, 0x1600
	s_mulk_i32 s14, 0x1600
	s_add_u32 s14, s12, s14
	s_addc_u32 s15, s13, s3
	s_ashr_i32 s3, s2, 31
	s_lshl_b64 s[2:3], s[2:3], 1
	s_add_u32 s2, s14, s2
	s_addc_u32 s3, s15, s3
	s_waitcnt vmcnt(0)
; #define LAS __attribute__((address_space(3)))
; DI unsigned pk2(float lo, float hi) { typedef float v2f __attribute__((ext_vector_type(2))); typedef __bf16 v2b __attribute__((ext_vector_type(2))); v2f v = {lo, hi}; v2b b = __builtin_convertvector(v, v2b); return __builtin_bit_cast(unsigned, b); }
;     ...
;         for (int i = 0; i < 32; ++i) { const int kk = 2 * i + (lane >> 5); float v = tv[i]; if (gk) v *= gk[k0 + kk]; scr[kk * 33 + (lane & 31)] = v; }
;         asm volatile("s_waitcnt lgkmcnt(0)" ::: "memory");
;         bf16_t* dst = dest_rows(mode, n0, K, d0, d1);
;         const int c = lane & 7;
; #pragma unroll
;         for (int jj = 0; jj < 4; ++jj) { const int n = (lane >> 3) + 8 * jj; const LAS float* s = scr + (8 * c) * 33 + n;
;             u32x4 o; o.x = pk2(s[0 * 33], s[1 * 33]); o.y = pk2(s[2 * 33], s[3 * 33]); o.z = pk2(s[4 * 33], s[5 * 33]); o.w = pk2(s[6 * 33], s[7 * 33]);
;             *(u32x4*)(dst + (size_t)n * K + k0 + 8 * c) = o; }
;         asm volatile("s_waitcnt lgkmcnt(0)" ::: "memory");
;     }
	ds_write2_b32 v45, v19, v22 offset1:66
	ds_write2_b32 v45, v23, v37 offset0:132 offset1:198
	ds_write2_b32 v1, v106, v31 offset0:8 offset1:74
	ds_write2_b32 v1, v32, v33 offset0:140 offset1:206
	ds_write2_b32 v5, v38, v39 offset0:16 offset1:82
	ds_write2_b32 v5, v40, v41 offset0:148 offset1:214
	ds_write2_b32 v7, v42, v43 offset0:24 offset1:90
	ds_write2_b32 v7, v58, v59 offset0:156 offset1:222
	ds_write2_b32 v9, v64, v65 offset0:32 offset1:98
	ds_write2_b32 v9, v66, v67 offset0:164 offset1:230
	ds_write2_b32 v11, v68, v69 offset0:40 offset1:106
	ds_write2_b32 v11, v70, v71 offset0:172 offset1:238
	ds_write2_b32 v13, v72, v73 offset0:48 offset1:114
	ds_write2_b32 v13, v74, v75 offset0:180 offset1:246
	ds_write2_b32 v18, v76, v77 offset0:56 offset1:122
	ds_write2_b32 v18, v78, v79 offset0:188 offset1:254
	v_lshl_add_u64 v[20:21], s[2:3], 0, v[2:3]
	s_waitcnt lgkmcnt(0)
	v_lshl_add_u64 v[24:25], v[20:21], 0, v[14:15]
	ds_read_b32 v19, v44
	ds_read_b32 v20, v44 offset:132
	ds_read_b32 v21, v44 offset:264
	ds_read_b32 v22, v44 offset:396
	ds_read_b32 v23, v44 offset:528
	ds_read_b32 v31, v44 offset:660
	ds_read_b32 v32, v44 offset:792
	ds_read_b32 v33, v44 offset:924
	v_add_co_u32_e32 v26, vcc, s35, v24
	s_waitcnt lgkmcnt(0)
	v_cvt_pk_bf16_f32 v20, v19, v20
	v_addc_co_u32_e32 v27, vcc, 0, v25, vcc
	v_add_co_u32_e32 v28, vcc, s36, v24
	v_cvt_pk_bf16_f32 v21, v21, v22
	v_cvt_pk_bf16_f32 v22, v23, v31
	v_cvt_pk_bf16_f32 v23, v32, v33
	v_addc_co_u32_e32 v29, vcc, 0, v25, vcc
	global_store_dwordx4 v[24:25], v[20:23], off
	v_add_co_u32_e32 v30, vcc, 0x21000, v24
	ds_read_b32 v19, v44 offset:32
	ds_read_b32 v20, v44 offset:164
	ds_read_b32 v21, v44 offset:296
	ds_read_b32 v22, v44 offset:428
	ds_read_b32 v23, v44 offset:560
	ds_read_b32 v24, v44 offset:692
	ds_read_b32 v31, v44 offset:824
	ds_read_b32 v32, v44 offset:956
	s_waitcnt lgkmcnt(0)
	v_cvt_pk_bf16_f32 v20, v19, v20
	v_cvt_pk_bf16_f32 v21, v21, v22
	v_cvt_pk_bf16_f32 v22, v23, v24
	s_add_i32 s37, s37, s88
	v_cvt_pk_bf16_f32 v23, v31, v32
	global_store_dwordx4 v[26:27], v[20:23], off
	ds_read_b32 v19, v44 offset:64
	ds_read_b32 v20, v44 offset:196
	ds_read_b32 v21, v44 offset:328
	ds_read_b32 v22, v44 offset:460
	ds_read_b32 v23, v44 offset:592
	ds_read_b32 v24, v44 offset:724
	ds_read_b32 v26, v44 offset:856
	ds_read_b32 v27, v44 offset:988
	s_waitcnt lgkmcnt(0)
	v_cvt_pk_bf16_f32 v20, v19, v20
	v_cvt_pk_bf16_f32 v21, v21, v22
	v_cvt_pk_bf16_f32 v22, v23, v24
	v_addc_co_u32_e32 v31, vcc, 0, v25, vcc
	v_cvt_pk_bf16_f32 v23, v26, v27
	global_store_dwordx4 v[28:29], v[20:23], off
	ds_read_b32 v19, v44 offset:96
	ds_read_b32 v20, v44 offset:228
	ds_read_b32 v21, v44 offset:360
	ds_read_b32 v22, v44 offset:492
	ds_read_b32 v23, v44 offset:624
	ds_read_b32 v24, v44 offset:756
	ds_read_b32 v26, v44 offset:888
	ds_read_b32 v27, v44 offset:1020
	s_waitcnt lgkmcnt(0)
	v_cvt_pk_bf16_f32 v20, v19, v20
	v_cvt_pk_bf16_f32 v21, v21, v22
	v_cvt_pk_bf16_f32 v22, v23, v24
	s_add_i32 s33, s33, s34
	v_cvt_pk_bf16_f32 v23, v26, v27
	global_store_dwordx4 v[30:31], v[20:23], off
	s_waitcnt lgkmcnt(0)
	s_cmpk_lt_i32 s37, 0x580
	s_cbranch_scc1 .LBB0_59

; #define LAS __attribute__((address_space(3)))
; DI unsigned pk2(float lo, float hi) { typedef float v2f __attribute__((ext_vector_type(2))); typedef __bf16 v2b __attribute__((ext_vector_type(2))); v2f v = {lo, hi}; v2b b = __builtin_convertvector(v, v2b); return __builtin_bit_cast(unsigned, b); }
;     ...
;         bf16_t* dst = dest_rows(mode, n0, K, d0, d1);
;         const int c = lane & 7;
; #pragma unroll
;         for (int jj = 0; jj < 4; ++jj) { const int n = (lane >> 3) + 8 * jj; const LAS float* s = scr + (8 * c) * 33 + n;
;             u32x4 o; o.x = pk2(s[0 * 33], s[1 * 33]); o.y = pk2(s[2 * 33], s[3 * 33]); o.z = pk2(s[4 * 33], s[5 * 33]); o.w = pk2(s[6 * 33], s[7 * 33]);
;             *(u32x4*)(dst + (size_t)n * K + k0 + 8 * c) = o; }
;         asm volatile("s_waitcnt lgkmcnt(0)" ::: "memory");
;     }
.LBB0_65:
	s_ashr_i32 s61, s60, 31
	ds_read_b32 v7, v44
	ds_read_b32 v9, v44 offset:132
	ds_read_b32 v11, v44 offset:264
	ds_read_b32 v13, v44 offset:396
	ds_read_b32 v20, v44 offset:528
	ds_read_b32 v21, v44 offset:660
	ds_read_b32 v24, v44 offset:792
	ds_read_b32 v25, v44 offset:924
	s_lshl_b64 s[12:13], s[60:61], 1
	s_add_u32 s2, s2, s12
	s_addc_u32 s3, s3, s13
	v_lshl_add_u64 v[22:23], s[2:3], 0, v[2:3]
	s_waitcnt lgkmcnt(0)
	v_cvt_pk_bf16_f32 v18, v7, v9
	v_mov_b32_e32 v7, v3
	v_cvt_pk_bf16_f32 v19, v11, v13
	v_cvt_pk_bf16_f32 v20, v20, v21
	v_cvt_pk_bf16_f32 v21, v24, v25
	v_lshl_add_u64 v[24:25], v[22:23], 0, v[6:7]
	global_store_dwordx4 v[24:25], v[18:21], off
	ds_read_b32 v7, v44 offset:32
	ds_read_b32 v9, v44 offset:164
	ds_read_b32 v11, v44 offset:296
	ds_read_b32 v13, v44 offset:428
	ds_read_b32 v20, v44 offset:560
	ds_read_b32 v21, v44 offset:692
	ds_read_b32 v24, v44 offset:824
	ds_read_b32 v25, v44 offset:956
	s_waitcnt lgkmcnt(0)
	v_cvt_pk_bf16_f32 v18, v7, v9
	v_mov_b32_e32 v9, v3
	v_cvt_pk_bf16_f32 v19, v11, v13
	v_cvt_pk_bf16_f32 v20, v20, v21
	v_cvt_pk_bf16_f32 v21, v24, v25
	v_lshl_add_u64 v[24:25], v[22:23], 0, v[8:9]
	global_store_dwordx4 v[24:25], v[18:21], off
	ds_read_b32 v7, v44 offset:64
	ds_read_b32 v9, v44 offset:196
	ds_read_b32 v11, v44 offset:328
	ds_read_b32 v13, v44 offset:460
	ds_read_b32 v20, v44 offset:592
	ds_read_b32 v21, v44 offset:724
	ds_read_b32 v24, v44 offset:856
	ds_read_b32 v25, v44 offset:988
	s_waitcnt lgkmcnt(0)
	v_cvt_pk_bf16_f32 v19, v11, v13
	v_mov_b32_e32 v11, v3
	v_cvt_pk_bf16_f32 v18, v7, v9
	v_cvt_pk_bf16_f32 v20, v20, v21
	v_cvt_pk_bf16_f32 v21, v24, v25
	v_lshl_add_u64 v[24:25], v[22:23], 0, v[10:11]
	global_store_dwordx4 v[24:25], v[18:21], off
	ds_read_b32 v7, v44 offset:96
	ds_read_b32 v9, v44 offset:228
	ds_read_b32 v11, v44 offset:360
	ds_read_b32 v13, v44 offset:492
	ds_read_b32 v20, v44 offset:624
	ds_read_b32 v21, v44 offset:756
	ds_read_b32 v24, v44 offset:888
	ds_read_b32 v25, v44 offset:1020
	s_waitcnt lgkmcnt(0)
	v_cvt_pk_bf16_f32 v19, v11, v13
	v_mov_b32_e32 v13, v3
	v_cvt_pk_bf16_f32 v18, v7, v9
	v_cvt_pk_bf16_f32 v20, v20, v21
	v_cvt_pk_bf16_f32 v21, v24, v25
	v_lshl_add_u64 v[22:23], v[22:23], 0, v[12:13]
	global_store_dwordx4 v[22:23], v[18:21], off
	s_waitcnt lgkmcnt(0)
	s_add_i32 s44, s44, s88
	s_add_i32 s39, s39, s40
	s_add_i32 s41, s41, s42
	s_cmpk_gt_i32 s44, 0xa4f
	s_cbranch_scc1 .LBB0_110

; #define LAS __attribute__((address_space(3)))
; DI unsigned pk2(float lo, float hi) { typedef float v2f __attribute__((ext_vector_type(2))); typedef __bf16 v2b __attribute__((ext_vector_type(2))); v2f v = {lo, hi}; v2b b = __builtin_convertvector(v, v2b); return __builtin_bit_cast(unsigned, b); }
;     ...
;         for (int i = 0; i < 32; ++i) { const int kk = 2 * i + (lane >> 5); float v = tv[i]; if (gk) v *= gk[k0 + kk]; scr[kk * 33 + (lane & 31)] = v; }
;         asm volatile("s_waitcnt lgkmcnt(0)" ::: "memory");
;         bf16_t* dst = dest_rows(mode, n0, K, d0, d1);
;         const int c = lane & 7;
; #pragma unroll
;         for (int jj = 0; jj < 4; ++jj) { const int n = (lane >> 3) + 8 * jj; const LAS float* s = scr + (8 * c) * 33 + n;
;             u32x4 o; o.x = pk2(s[0 * 33], s[1 * 33]); o.y = pk2(s[2 * 33], s[3 * 33]); o.z = pk2(s[4 * 33], s[5 * 33]); o.w = pk2(s[6 * 33], s[7 * 33]);
;             *(u32x4*)(dst + (size_t)n * K + k0 + 8 * c) = o; }
;         asm volatile("s_waitcnt lgkmcnt(0)" ::: "memory");
;     }
.LBB0_112:
	v_add_u32_e32 v5, 0x400, v9
	ds_write2_b32 v5, v22, v23 offset0:8 offset1:74
	s_waitcnt lgkmcnt(0)
	s_mul_i32 s13, s34, 0x300
	s_mul_hi_i32 s12, s34, 0x300
	s_add_u32 s34, s33, s13
	ds_read_b32 v5, v44
	ds_read_b32 v7, v44 offset:132
	ds_read_b32 v9, v44 offset:264
	ds_read_b32 v11, v44 offset:396
	ds_read_b32 v13, v44 offset:528
	ds_read_b32 v19, v44 offset:660
	ds_read_b32 v23, v44 offset:792
	ds_read_b32 v26, v44 offset:924
	s_addc_u32 s35, s36, s12
	s_lshl_b64 s[12:13], s[14:15], 1
	s_add_u32 s12, s34, s12
	s_addc_u32 s13, s35, s13
	v_lshl_add_u64 v[24:25], s[12:13], 0, v[2:3]
	s_waitcnt lgkmcnt(0)
	v_cvt_pk_bf16_f32 v22, v13, v19
	v_mov_b32_e32 v19, v3
	v_cvt_pk_bf16_f32 v20, v5, v7
	v_cvt_pk_bf16_f32 v21, v9, v11
	v_cvt_pk_bf16_f32 v23, v23, v26
	v_lshl_add_u64 v[24:25], v[24:25], 0, v[18:19]
	global_store_dwordx4 v[24:25], v[20:23], off
	ds_read_b32 v5, v44 offset:32
	ds_read_b32 v7, v44 offset:164
	ds_read_b32 v9, v44 offset:296
	ds_read_b32 v11, v44 offset:428
	ds_read_b32 v13, v44 offset:560
	ds_read_b32 v19, v44 offset:692
	ds_read_b32 v23, v44 offset:824
	ds_read_b32 v26, v44 offset:956
	s_waitcnt lgkmcnt(0)
	v_cvt_pk_bf16_f32 v20, v5, v7
	v_cvt_pk_bf16_f32 v21, v9, v11
	v_cvt_pk_bf16_f32 v22, v13, v19
	s_add_i32 s42, s42, s88
	v_cvt_pk_bf16_f32 v23, v23, v26
	v_add_co_u32_e32 v26, vcc, s40, v24
	s_add_i32 s37, s37, s38
	s_nop 0
	v_addc_co_u32_e32 v27, vcc, 0, v25, vcc
	global_store_dwordx4 v[26:27], v[20:23], off offset:2048
	ds_read_b32 v5, v44 offset:64
	ds_read_b32 v7, v44 offset:196
	ds_read_b32 v9, v44 offset:328
	ds_read_b32 v11, v44 offset:460
	ds_read_b32 v13, v44 offset:592
	ds_read_b32 v19, v44 offset:724
	ds_read_b32 v23, v44 offset:856
	ds_read_b32 v26, v44 offset:988
	s_waitcnt lgkmcnt(0)
	v_cvt_pk_bf16_f32 v20, v5, v7
	v_cvt_pk_bf16_f32 v21, v9, v11
	v_cvt_pk_bf16_f32 v22, v13, v19
	s_cmpk_lt_i32 s42, 0x90
	v_cvt_pk_bf16_f32 v23, v23, v26
	v_add_co_u32_e32 v26, vcc, s41, v24
	s_nop 1
	v_addc_co_u32_e32 v27, vcc, 0, v25, vcc
	global_store_dwordx4 v[26:27], v[20:23], off
	ds_read_b32 v5, v44 offset:96
	ds_read_b32 v7, v44 offset:228
	ds_read_b32 v9, v44 offset:360
	ds_read_b32 v11, v44 offset:492
	ds_read_b32 v13, v44 offset:624
	ds_read_b32 v19, v44 offset:756
	ds_read_b32 v23, v44 offset:888
	ds_read_b32 v26, v44 offset:1020
	v_add_co_u32_e32 v24, vcc, 0x4000, v24
	s_waitcnt lgkmcnt(0)
	v_cvt_pk_bf16_f32 v20, v5, v7
	v_cvt_pk_bf16_f32 v21, v9, v11
	v_cvt_pk_bf16_f32 v22, v13, v19
	v_cvt_pk_bf16_f32 v23, v23, v26
	v_addc_co_u32_e32 v25, vcc, 0, v25, vcc
	global_store_dwordx4 v[24:25], v[20:23], off offset:2048
	s_waitcnt lgkmcnt(0)
	s_cbranch_scc0 .LBB0_145

; #define LAS __attribute__((address_space(3)))
; DI unsigned pk2(float lo, float hi) { typedef float v2f __attribute__((ext_vector_type(2))); typedef __bf16 v2b __attribute__((ext_vector_type(2))); v2f v = {lo, hi}; v2b b = __builtin_convertvector(v, v2b); return __builtin_bit_cast(unsigned, b); }
;     ...
;         for (int i = 0; i < 32; ++i) { const int kk = 2 * i + (lane >> 5); float v = tv[i]; if (gk) v *= gk[k0 + kk]; scr[kk * 33 + (lane & 31)] = v; }
;         asm volatile("s_waitcnt lgkmcnt(0)" ::: "memory");
;         bf16_t* dst = dest_rows(mode, n0, K, d0, d1);
;         const int c = lane & 7;
; #pragma unroll
;         for (int jj = 0; jj < 4; ++jj) { const int n = (lane >> 3) + 8 * jj; const LAS float* s = scr + (8 * c) * 33 + n;
;             u32x4 o; o.x = pk2(s[0 * 33], s[1 * 33]); o.y = pk2(s[2 * 33], s[3 * 33]); o.z = pk2(s[4 * 33], s[5 * 33]); o.w = pk2(s[6 * 33], s[7 * 33]);
;             *(u32x4*)(dst + (size_t)n * K + k0 + 8 * c) = o; }
;         asm volatile("s_waitcnt lgkmcnt(0)" ::: "memory");
;     }
.LBB0_147:
	v_add_u32_e32 v5, 0x400, v9
	ds_write2_b32 v5, v28, v29 offset0:8 offset1:74
	s_waitcnt lgkmcnt(0)
	s_lshl_b64 s[12:13], s[34:35], 9
	s_add_u32 s34, s33, s12
	ds_read_b32 v5, v44
	ds_read_b32 v7, v44 offset:132
	ds_read_b32 v9, v44 offset:264
	ds_read_b32 v11, v44 offset:396
	ds_read_b32 v13, v44 offset:528
	ds_read_b32 v19, v44 offset:660
	ds_read_b32 v21, v44 offset:792
	ds_read_b32 v23, v44 offset:924
	s_addc_u32 s35, s36, s13
	s_lshl_b64 s[12:13], s[14:15], 1
	s_add_u32 s12, s34, s12
	s_addc_u32 s13, s35, s13
	v_lshl_add_u64 v[30:31], s[12:13], 0, v[2:3]
	s_waitcnt lgkmcnt(0)
	v_cvt_pk_bf16_f32 v28, v13, v19
	v_mov_b32_e32 v19, v3
	v_cvt_pk_bf16_f32 v26, v5, v7
	v_cvt_pk_bf16_f32 v27, v9, v11
	v_cvt_pk_bf16_f32 v29, v21, v23
	v_lshl_add_u64 v[32:33], v[30:31], 0, v[18:19]
	global_store_dwordx4 v[32:33], v[26:29], off
	ds_read_b32 v5, v44 offset:32
	ds_read_b32 v7, v44 offset:164
	ds_read_b32 v9, v44 offset:296
	ds_read_b32 v11, v44 offset:428
	ds_read_b32 v13, v44 offset:560
	ds_read_b32 v19, v44 offset:692
	ds_read_b32 v21, v44 offset:824
	ds_read_b32 v23, v44 offset:956
	s_waitcnt lgkmcnt(0)
	v_cvt_pk_bf16_f32 v26, v5, v7
	v_cvt_pk_bf16_f32 v27, v9, v11
	v_cvt_pk_bf16_f32 v28, v13, v19
	v_mov_b32_e32 v25, v3
	v_cvt_pk_bf16_f32 v29, v21, v23
	v_mov_b32_e32 v21, v3
	v_lshl_add_u64 v[32:33], v[30:31], 0, v[20:21]
	global_store_dwordx4 v[32:33], v[26:29], off
	ds_read_b32 v5, v44 offset:64
	ds_read_b32 v7, v44 offset:196
	ds_read_b32 v9, v44 offset:328
	ds_read_b32 v11, v44 offset:460
	ds_read_b32 v13, v44 offset:592
	ds_read_b32 v19, v44 offset:724
	ds_read_b32 v21, v44 offset:856
	ds_read_b32 v23, v44 offset:988
	s_waitcnt lgkmcnt(0)
	v_cvt_pk_bf16_f32 v26, v5, v7
	v_cvt_pk_bf16_f32 v27, v9, v11
	v_cvt_pk_bf16_f32 v28, v13, v19
	s_add_i32 s39, s39, s88
	v_cvt_pk_bf16_f32 v29, v21, v23
	v_mov_b32_e32 v23, v3
	v_lshl_add_u64 v[32:33], v[30:31], 0, v[22:23]
	global_store_dwordx4 v[32:33], v[26:29], off
	ds_read_b32 v5, v44 offset:96
	ds_read_b32 v7, v44 offset:228
	ds_read_b32 v9, v44 offset:360
	ds_read_b32 v11, v44 offset:492
	ds_read_b32 v13, v44 offset:624
	ds_read_b32 v19, v44 offset:756
	ds_read_b32 v21, v44 offset:888
	ds_read_b32 v23, v44 offset:1020
	s_waitcnt lgkmcnt(0)
	v_cvt_pk_bf16_f32 v26, v5, v7
	v_cvt_pk_bf16_f32 v27, v9, v11
	v_cvt_pk_bf16_f32 v28, v13, v19
	v_lshl_add_u64 v[30:31], v[30:31], 0, v[24:25]
	v_cvt_pk_bf16_f32 v29, v21, v23
	global_store_dwordx4 v[30:31], v[26:29], off
	s_waitcnt lgkmcnt(0)
	s_add_i32 s37, s37, s38
	s_cmpk_lt_i32 s39, 0x80
	s_cbranch_scc0 .LBB0_180

;     ...
;     for (int item = gw; item < nitems; item += ngw) {
;         const int kb = item / nblk, nb = nb0 + item % nblk, k0 = 64 * kb, n0 = 32 * nb;
;         float tv[32];
; #pragma unroll
;         for (int i = 0; i < 32; ++i) { const int kk = 2 * i + (lane >> 5); tv[i] = W[(size_t)(k0 + kk) * N + n0 + (lane & 31)]; }
.LBB0_182:
	s_ashr_i32 s2, s36, 31
	s_lshr_b32 s2, s2, 27
	s_add_i32 s2, s36, s2
	s_ashr_i32 s3, s2, 5
	s_lshl_b32 s2, s3, 6
	s_lshl_b32 s3, s3, 10
	v_or_b32_e32 v28, s2, v0
	s_sub_i32 s14, s35, s3
	v_or_b32_e32 v30, 2, v28
	v_or_b32_e32 v40, 12, v28
	v_or_b32_e32 v42, 14, v28
	v_or_b32_e32 v60, 16, v28
	v_or_b32_e32 v62, 18, v28
	v_or_b32_e32 v64, 20, v28
	v_or_b32_e32 v66, 22, v28
	v_or_b32_e32 v68, 24, v28
	v_or_b32_e32 v70, 26, v28
	v_or_b32_e32 v72, 28, v28
	v_or_b32_e32 v74, 30, v28
	v_or_b32_e32 v76, 32, v28
	v_or_b32_e32 v78, 34, v28
	v_or_b32_e32 v80, 36, v28
	s_ashr_i32 s15, s14, 31
	v_ashrrev_i32_e32 v29, 31, v28
	v_or_b32_e32 v32, 4, v28
	v_or_b32_e32 v34, 6, v28
	v_or_b32_e32 v36, 8, v28
	v_or_b32_e32 v38, 10, v28
	v_or_b32_e32 v82, 38, v28
	v_or_b32_e32 v84, 40, v28
	v_or_b32_e32 v86, 42, v28
	v_or_b32_e32 v88, 44, v28
	v_or_b32_e32 v90, 46, v28
	v_or_b32_e32 v92, 48, v28
	v_or_b32_e32 v94, 50, v28
	v_or_b32_e32 v96, 52, v28
	v_or_b32_e32 v98, 54, v28
	v_or_b32_e32 v100, 56, v28
	v_or_b32_e32 v102, 58, v28
	v_or_b32_e32 v104, 60, v28
	v_or_b32_e32 v106, 62, v28
	v_ashrrev_i32_e32 v31, 31, v30
	v_ashrrev_i32_e32 v41, 31, v40
	v_ashrrev_i32_e32 v43, 31, v42
	v_ashrrev_i32_e32 v61, 31, v60
	v_ashrrev_i32_e32 v63, 31, v62
	v_ashrrev_i32_e32 v65, 31, v64
	v_ashrrev_i32_e32 v67, 31, v66
	v_ashrrev_i32_e32 v69, 31, v68
	v_ashrrev_i32_e32 v71, 31, v70
	v_ashrrev_i32_e32 v73, 31, v72
	v_ashrrev_i32_e32 v75, 31, v74
	v_ashrrev_i32_e32 v77, 31, v76
	v_ashrrev_i32_e32 v79, 31, v78
	v_ashrrev_i32_e32 v81, 31, v80
	v_lshl_add_u64 v[108:109], s[14:15], 2, v[24:25]
	v_lshlrev_b64 v[28:29], 12, v[28:29]
	v_ashrrev_i32_e32 v33, 31, v32
	v_ashrrev_i32_e32 v35, 31, v34
	v_ashrrev_i32_e32 v37, 31, v36
	v_ashrrev_i32_e32 v39, 31, v38
	v_ashrrev_i32_e32 v83, 31, v82
	v_ashrrev_i32_e32 v85, 31, v84
	v_ashrrev_i32_e32 v87, 31, v86
	v_ashrrev_i32_e32 v89, 31, v88
	v_ashrrev_i32_e32 v91, 31, v90
	v_ashrrev_i32_e32 v93, 31, v92
	v_ashrrev_i32_e32 v95, 31, v94
	v_ashrrev_i32_e32 v97, 31, v96
	v_ashrrev_i32_e32 v99, 31, v98
	v_ashrrev_i32_e32 v101, 31, v100
	v_ashrrev_i32_e32 v103, 31, v102
	v_ashrrev_i32_e32 v105, 31, v104
	v_ashrrev_i32_e32 v107, 31, v106
	v_lshlrev_b64 v[30:31], 12, v[30:31]
	v_lshlrev_b64 v[40:41], 12, v[40:41]
	v_lshlrev_b64 v[42:43], 12, v[42:43]
	v_lshlrev_b64 v[60:61], 12, v[60:61]
	v_lshlrev_b64 v[62:63], 12, v[62:63]
	v_lshlrev_b64 v[64:65], 12, v[64:65]
	v_lshlrev_b64 v[66:67], 12, v[66:67]
	v_lshlrev_b64 v[68:69], 12, v[68:69]
	v_lshlrev_b64 v[70:71], 12, v[70:71]
	v_lshlrev_b64 v[72:73], 12, v[72:73]
	v_lshlrev_b64 v[74:75], 12, v[74:75]
	v_lshlrev_b64 v[76:77], 12, v[76:77]
	v_lshlrev_b64 v[78:79], 12, v[78:79]
	v_lshlrev_b64 v[80:81], 12, v[80:81]
	v_lshl_add_u64 v[28:29], v[108:109], 0, v[28:29]
	v_lshlrev_b64 v[32:33], 12, v[32:33]
	v_lshlrev_b64 v[34:35], 12, v[34:35]
	v_lshlrev_b64 v[36:37], 12, v[36:37]
	v_lshlrev_b64 v[38:39], 12, v[38:39]
	v_lshlrev_b64 v[82:83], 12, v[82:83]
	v_lshlrev_b64 v[84:85], 12, v[84:85]
	v_lshlrev_b64 v[86:87], 12, v[86:87]
	v_lshlrev_b64 v[88:89], 12, v[88:89]
	v_lshlrev_b64 v[90:91], 12, v[90:91]
	v_lshlrev_b64 v[92:93], 12, v[92:93]
	v_lshlrev_b64 v[94:95], 12, v[94:95]
	v_lshlrev_b64 v[96:97], 12, v[96:97]
	v_lshlrev_b64 v[98:99], 12, v[98:99]
	v_lshlrev_b64 v[100:101], 12, v[100:101]
	v_lshlrev_b64 v[102:103], 12, v[102:103]
	v_lshlrev_b64 v[104:105], 12, v[104:105]
	v_lshlrev_b64 v[106:107], 12, v[106:107]
	v_lshl_add_u64 v[30:31], v[108:109], 0, v[30:31]
	v_lshl_add_u64 v[40:41], v[108:109], 0, v[40:41]
	v_lshl_add_u64 v[42:43], v[108:109], 0, v[42:43]
	v_lshl_add_u64 v[60:61], v[108:109], 0, v[60:61]
	v_lshl_add_u64 v[62:63], v[108:109], 0, v[62:63]
	v_lshl_add_u64 v[64:65], v[108:109], 0, v[64:65]
	v_lshl_add_u64 v[66:67], v[108:109], 0, v[66:67]
	v_lshl_add_u64 v[68:69], v[108:109], 0, v[68:69]
	v_lshl_add_u64 v[70:71], v[108:109], 0, v[70:71]
	v_lshl_add_u64 v[72:73], v[108:109], 0, v[72:73]
	v_lshl_add_u64 v[74:75], v[108:109], 0, v[74:75]
	v_lshl_add_u64 v[76:77], v[108:109], 0, v[76:77]
	v_lshl_add_u64 v[78:79], v[108:109], 0, v[78:79]
	v_lshl_add_u64 v[80:81], v[108:109], 0, v[80:81]
	v_lshl_add_u64 v[32:33], v[108:109], 0, v[32:33]
	v_lshl_add_u64 v[34:35], v[108:109], 0, v[34:35]
	v_lshl_add_u64 v[36:37], v[108:109], 0, v[36:37]
	v_lshl_add_u64 v[38:39], v[108:109], 0, v[38:39]
	v_lshl_add_u64 v[82:83], v[108:109], 0, v[82:83]
	v_lshl_add_u64 v[84:85], v[108:109], 0, v[84:85]
	v_lshl_add_u64 v[86:87], v[108:109], 0, v[86:87]
	v_lshl_add_u64 v[88:89], v[108:109], 0, v[88:89]
	v_lshl_add_u64 v[90:91], v[108:109], 0, v[90:91]
	v_lshl_add_u64 v[92:93], v[108:109], 0, v[92:93]
	v_lshl_add_u64 v[94:95], v[108:109], 0, v[94:95]
	v_lshl_add_u64 v[96:97], v[108:109], 0, v[96:97]
	v_lshl_add_u64 v[98:99], v[108:109], 0, v[98:99]
	v_lshl_add_u64 v[100:101], v[108:109], 0, v[100:101]
	v_lshl_add_u64 v[102:103], v[108:109], 0, v[102:103]
	v_lshl_add_u64 v[104:105], v[108:109], 0, v[104:105]
	v_lshl_add_u64 v[106:107], v[108:109], 0, v[106:107]
	global_load_dword v27, v[28:29], off
	s_nop 0
	global_load_dword v28, v[30:31], off
	global_load_dword v29, v[32:33], off
	s_nop 0
	global_load_dword v30, v[34:35], off
	global_load_dword v31, v[36:37], off
	global_load_dword v108, v[38:39], off
	s_nop 0
	global_load_dword v40, v[40:41], off
	s_nop 0
	global_load_dword v41, v[42:43], off
	s_nop 0
	global_load_dword v42, v[60:61], off
	global_load_dword v43, v[62:63], off
	s_nop 0
	global_load_dword v60, v[64:65], off
	global_load_dword v61, v[66:67], off
	global_load_dword v62, v[68:69], off
	global_load_dword v63, v[70:71], off
	s_nop 0
	global_load_dword v64, v[72:73], off
	global_load_dword v65, v[74:75], off
	global_load_dword v66, v[76:77], off
	global_load_dword v67, v[78:79], off
	global_load_dword v68, v[80:81], off
	global_load_dword v69, v[82:83], off
	global_load_dword v70, v[84:85], off
	global_load_dword v71, v[86:87], off
	global_load_dword v72, v[88:89], off
	global_load_dword v73, v[90:91], off
	global_load_dword v74, v[92:93], off
	global_load_dword v75, v[94:95], off
	global_load_dword v76, v[96:97], off
	global_load_dword v77, v[98:99], off
	global_load_dword v78, v[100:101], off
	global_load_dword v79, v[102:103], off
	global_load_dword v80, v[104:105], off
	global_load_dword v81, v[106:107], off
	s_lshl_b64 s[14:15], s[14:15], 10
	s_waitcnt vmcnt(0)
; #define LAS __attribute__((address_space(3)))
; DI unsigned pk2(float lo, float hi) { typedef float v2f __attribute__((ext_vector_type(2))); typedef __bf16 v2b __attribute__((ext_vector_type(2))); v2f v = {lo, hi}; v2b b = __builtin_convertvector(v, v2b); return __builtin_bit_cast(unsigned, b); }
;     ...
;     for (int item = gw; item < nitems; item += ngw) {
;         const int kb = item / nblk, nb = nb0 + item % nblk, k0 = 64 * kb, n0 = 32 * nb;
;         float tv[32];
; #pragma unroll
;         for (int i = 0; i < 32; ++i) { const int kk = 2 * i + (lane >> 5); tv[i] = W[(size_t)(k0 + kk) * N + n0 + (lane & 31)]; }
; #pragma unroll
;         for (int i = 0; i < 32; ++i) { const int kk = 2 * i + (lane >> 5); float v = tv[i]; if (gk) v *= gk[k0 + kk]; scr[kk * 33 + (lane & 31)] = v; }
;         asm volatile("s_waitcnt lgkmcnt(0)" ::: "memory");
;         bf16_t* dst = dest_rows(mode, n0, K, d0, d1);
;         const int c = lane & 7;
; #pragma unroll
;         for (int jj = 0; jj < 4; ++jj) { const int n = (lane >> 3) + 8 * jj; const LAS float* s = scr + (8 * c) * 33 + n;
;             u32x4 o; o.x = pk2(s[0 * 33], s[1 * 33]); o.y = pk2(s[2 * 33], s[3 * 33]); o.z = pk2(s[4 * 33], s[5 * 33]); o.w = pk2(s[6 * 33], s[7 * 33]);
;             *(u32x4*)(dst + (size_t)n * K + k0 + 8 * c) = o; }
;         asm volatile("s_waitcnt lgkmcnt(0)" ::: "memory");
;     }
	ds_write2_b32 v45, v27, v28 offset1:66
	ds_write2_b32 v45, v29, v30 offset0:132 offset1:198
	ds_write2_b32 v1, v31, v108 offset0:8 offset1:74
	ds_write2_b32 v1, v40, v41 offset0:140 offset1:206
	ds_write2_b32 v5, v42, v43 offset0:16 offset1:82
	ds_write2_b32 v5, v60, v61 offset0:148 offset1:214
	ds_write2_b32 v7, v62, v63 offset0:24 offset1:90
	ds_write2_b32 v7, v64, v65 offset0:156 offset1:222
	ds_write2_b32 v9, v66, v67 offset0:32 offset1:98
	ds_write2_b32 v9, v68, v69 offset0:164 offset1:230
	ds_write2_b32 v11, v70, v71 offset0:40 offset1:106
	ds_write2_b32 v11, v72, v73 offset0:172 offset1:238
	ds_write2_b32 v13, v74, v75 offset0:48 offset1:114
	ds_write2_b32 v13, v76, v77 offset0:180 offset1:246
	ds_write2_b32 v26, v78, v79 offset0:56 offset1:122
	ds_write2_b32 v26, v80, v81 offset0:188 offset1:254
	s_add_u32 s14, s33, s14
	s_waitcnt lgkmcnt(0)
	s_addc_u32 s15, s34, s15
	s_ashr_i32 s3, s2, 31
	ds_read_b32 v27, v44
	ds_read_b32 v28, v44 offset:132
	ds_read_b32 v29, v44 offset:264
	ds_read_b32 v30, v44 offset:396
	ds_read_b32 v31, v44 offset:528
	ds_read_b32 v40, v44 offset:660
	ds_read_b32 v41, v44 offset:792
	ds_read_b32 v42, v44 offset:924
	s_lshl_b64 s[2:3], s[2:3], 1
	s_add_u32 s2, s14, s2
	s_addc_u32 s3, s15, s3
	v_lshl_add_u64 v[32:33], s[2:3], 0, v[2:3]
	v_lshl_add_u64 v[34:35], v[32:33], 0, v[16:17]
	s_waitcnt lgkmcnt(0)
	v_cvt_pk_bf16_f32 v28, v27, v28
	v_cvt_pk_bf16_f32 v29, v29, v30
	v_cvt_pk_bf16_f32 v30, v31, v40
	v_cvt_pk_bf16_f32 v31, v41, v42
	global_store_dwordx4 v[34:35], v[28:31], off
	ds_read_b32 v27, v44 offset:32
	ds_read_b32 v28, v44 offset:164
	ds_read_b32 v29, v44 offset:296
	ds_read_b32 v30, v44 offset:428
	ds_read_b32 v31, v44 offset:560
	ds_read_b32 v34, v44 offset:692
	ds_read_b32 v35, v44 offset:824
	ds_read_b32 v40, v44 offset:956
	v_lshl_add_u64 v[36:37], v[32:33], 0, v[18:19]
	s_waitcnt lgkmcnt(0)
	v_cvt_pk_bf16_f32 v28, v27, v28
	v_cvt_pk_bf16_f32 v29, v29, v30
	v_cvt_pk_bf16_f32 v30, v31, v34
	v_cvt_pk_bf16_f32 v31, v35, v40
	global_store_dwordx4 v[36:37], v[28:31], off
	ds_read_b32 v27, v44 offset:64
	ds_read_b32 v28, v44 offset:196
	ds_read_b32 v29, v44 offset:328
	ds_read_b32 v30, v44 offset:460
	ds_read_b32 v31, v44 offset:592
	ds_read_b32 v34, v44 offset:724
	ds_read_b32 v35, v44 offset:856
	ds_read_b32 v36, v44 offset:988
	v_lshl_add_u64 v[38:39], v[32:33], 0, v[20:21]
	s_waitcnt lgkmcnt(0)
	v_cvt_pk_bf16_f32 v28, v27, v28
	v_cvt_pk_bf16_f32 v29, v29, v30
	v_cvt_pk_bf16_f32 v30, v31, v34
	v_cvt_pk_bf16_f32 v31, v35, v36
	global_store_dwordx4 v[38:39], v[28:31], off
	ds_read_b32 v27, v44 offset:96
	ds_read_b32 v28, v44 offset:228
	ds_read_b32 v29, v44 offset:360
	ds_read_b32 v30, v44 offset:492
	ds_read_b32 v31, v44 offset:624
	ds_read_b32 v34, v44 offset:756
	ds_read_b32 v35, v44 offset:888
	ds_read_b32 v36, v44 offset:1020
	v_lshl_add_u64 v[32:33], v[32:33], 0, v[22:23]
	s_waitcnt lgkmcnt(0)
	v_cvt_pk_bf16_f32 v28, v27, v28
	v_cvt_pk_bf16_f32 v29, v29, v30
	v_cvt_pk_bf16_f32 v30, v31, v34
	v_cvt_pk_bf16_f32 v31, v35, v36
	global_store_dwordx4 v[32:33], v[28:31], off
	s_waitcnt lgkmcnt(0)
	s_add_i32 s36, s36, s88
	s_add_i32 s35, s35, s13
	s_cmpk_lt_i32 s36, 0x100
	s_cbranch_scc1 .LBB0_182
	v_mov_b32_e32 v3, 0
	v_readlane_b32 s16, v249, 1
	v_mov_b32_e32 v5, v3
	v_readlane_b32 s17, v249, 2
	s_add_u32 s33, s8, 0x2000000
	v_readlane_b32 s2, v249, 54
	v_lshl_add_u64 v[24:25], s[16:17], 0, v[4:5]
	s_addc_u32 s34, s9, 0
	s_mov_b32 s35, s12
	s_mov_b32 s36, s2
	v_readlane_b32 s18, v249, 3
	v_readlane_b32 s19, v249, 4
	v_readlane_b32 s20, v249, 5
	v_readlane_b32 s21, v249, 6
	v_readlane_b32 s22, v249, 7
	v_readlane_b32 s23, v249, 8
	v_readlane_b32 s24, v249, 9
	v_readlane_b32 s25, v249, 10
	v_readlane_b32 s26, v249, 11
	v_readlane_b32 s27, v249, 12
	v_readlane_b32 s28, v249, 13
	v_readlane_b32 s29, v249, 14
	v_readlane_b32 s30, v249, 15
	v_readlane_b32 s31, v249, 16
	v_readlane_b32 s3, v249, 55
.LBB0_184:
	s_ashr_i32 s2, s36, 31
	s_lshr_b32 s2, s2, 27
	s_add_i32 s2, s36, s2
	s_ashr_i32 s3, s2, 5
	s_lshl_b32 s2, s3, 6
	s_lshl_b32 s3, s3, 10
	v_or_b32_e32 v26, s2, v0
	s_sub_i32 s14, s35, s3
	v_or_b32_e32 v28, 2, v26
	v_or_b32_e32 v38, 12, v26
	v_or_b32_e32 v40, 14, v26
	v_or_b32_e32 v42, 16, v26
	v_or_b32_e32 v60, 18, v26
	v_or_b32_e32 v62, 20, v26
	v_or_b32_e32 v64, 22, v26
	v_or_b32_e32 v66, 24, v26
	v_or_b32_e32 v68, 26, v26
	v_or_b32_e32 v70, 28, v26
	v_or_b32_e32 v72, 30, v26
	v_or_b32_e32 v74, 32, v26
	s_ashr_i32 s15, s14, 31
	v_ashrrev_i32_e32 v27, 31, v26
	v_or_b32_e32 v30, 4, v26
	v_or_b32_e32 v32, 6, v26
	v_or_b32_e32 v34, 8, v26
	v_or_b32_e32 v36, 10, v26
	v_or_b32_e32 v76, 34, v26
	v_or_b32_e32 v78, 36, v26
	v_or_b32_e32 v80, 38, v26
	v_or_b32_e32 v82, 40, v26
	v_or_b32_e32 v84, 42, v26
	v_or_b32_e32 v86, 44, v26
	v_or_b32_e32 v88, 46, v26
	v_or_b32_e32 v90, 48, v26
	v_or_b32_e32 v92, 50, v26
	v_or_b32_e32 v94, 52, v26
	v_or_b32_e32 v96, 54, v26
	v_or_b32_e32 v98, 56, v26
	v_or_b32_e32 v100, 58, v26
	v_or_b32_e32 v102, 60, v26
	v_or_b32_e32 v104, 62, v26
	v_ashrrev_i32_e32 v29, 31, v28
	v_ashrrev_i32_e32 v39, 31, v38
	v_ashrrev_i32_e32 v41, 31, v40
	v_ashrrev_i32_e32 v43, 31, v42
	v_ashrrev_i32_e32 v61, 31, v60
	v_ashrrev_i32_e32 v63, 31, v62
	v_ashrrev_i32_e32 v65, 31, v64
	v_ashrrev_i32_e32 v67, 31, v66
	v_ashrrev_i32_e32 v69, 31, v68
	v_ashrrev_i32_e32 v71, 31, v70
	v_ashrrev_i32_e32 v73, 31, v72
	v_ashrrev_i32_e32 v75, 31, v74
	v_lshl_add_u64 v[106:107], s[14:15], 2, v[24:25]
	v_lshlrev_b64 v[26:27], 12, v[26:27]
	v_ashrrev_i32_e32 v31, 31, v30
	v_ashrrev_i32_e32 v33, 31, v32
	v_ashrrev_i32_e32 v35, 31, v34
	v_ashrrev_i32_e32 v37, 31, v36
	v_ashrrev_i32_e32 v77, 31, v76
;     ...
;     for (int item = gw; item < nitems; item += ngw) {
;         const int kb = item / nblk, nb = nb0 + item % nblk, k0 = 64 * kb, n0 = 32 * nb;
;         float tv[32];
; #pragma unroll
;         for (int i = 0; i < 32; ++i) { const int kk = 2 * i + (lane >> 5); tv[i] = W[(size_t)(k0 + kk) * N + n0 + (lane & 31)]; }
; #pragma unroll
;         for (int i = 0; i < 32; ++i) { const int kk = 2 * i + (lane >> 5); float v = tv[i]; if (gk) v *= gk[k0 + kk]; scr[kk * 33 + (lane & 31)] = v; }
	v_ashrrev_i32_e32 v79, 31, v78
	v_ashrrev_i32_e32 v81, 31, v80
	v_ashrrev_i32_e32 v83, 31, v82
	v_ashrrev_i32_e32 v85, 31, v84
	v_ashrrev_i32_e32 v87, 31, v86
	v_ashrrev_i32_e32 v89, 31, v88
	v_ashrrev_i32_e32 v91, 31, v90
	v_ashrrev_i32_e32 v93, 31, v92
	v_ashrrev_i32_e32 v95, 31, v94
	v_ashrrev_i32_e32 v97, 31, v96
	v_ashrrev_i32_e32 v99, 31, v98
	v_ashrrev_i32_e32 v101, 31, v100
	v_ashrrev_i32_e32 v103, 31, v102
	v_ashrrev_i32_e32 v105, 31, v104
	v_lshlrev_b64 v[28:29], 12, v[28:29]
	v_lshlrev_b64 v[38:39], 12, v[38:39]
	v_lshlrev_b64 v[40:41], 12, v[40:41]
	v_lshlrev_b64 v[42:43], 12, v[42:43]
	v_lshlrev_b64 v[60:61], 12, v[60:61]
	v_lshlrev_b64 v[62:63], 12, v[62:63]
	v_lshlrev_b64 v[64:65], 12, v[64:65]
	v_lshlrev_b64 v[66:67], 12, v[66:67]
	v_lshlrev_b64 v[68:69], 12, v[68:69]
	v_lshlrev_b64 v[70:71], 12, v[70:71]
	v_lshlrev_b64 v[72:73], 12, v[72:73]
	v_lshlrev_b64 v[74:75], 12, v[74:75]
	v_lshl_add_u64 v[26:27], v[106:107], 0, v[26:27]
	v_lshlrev_b64 v[30:31], 12, v[30:31]
	v_lshlrev_b64 v[32:33], 12, v[32:33]
	v_lshlrev_b64 v[34:35], 12, v[34:35]
	v_lshlrev_b64 v[36:37], 12, v[36:37]
	v_lshlrev_b64 v[76:77], 12, v[76:77]
	v_lshlrev_b64 v[78:79], 12, v[78:79]
	v_lshlrev_b64 v[80:81], 12, v[80:81]
	v_lshlrev_b64 v[82:83], 12, v[82:83]
	v_lshlrev_b64 v[84:85], 12, v[84:85]
	v_lshlrev_b64 v[86:87], 12, v[86:87]
	v_lshlrev_b64 v[88:89], 12, v[88:89]
	v_lshlrev_b64 v[90:91], 12, v[90:91]
	v_lshlrev_b64 v[92:93], 12, v[92:93]
	v_lshlrev_b64 v[94:95], 12, v[94:95]
	v_lshlrev_b64 v[96:97], 12, v[96:97]
	v_lshlrev_b64 v[98:99], 12, v[98:99]
	v_lshlrev_b64 v[100:101], 12, v[100:101]
	v_lshlrev_b64 v[102:103], 12, v[102:103]
	v_lshlrev_b64 v[104:105], 12, v[104:105]
	v_lshl_add_u64 v[28:29], v[106:107], 0, v[28:29]
	v_lshl_add_u64 v[38:39], v[106:107], 0, v[38:39]
	v_lshl_add_u64 v[40:41], v[106:107], 0, v[40:41]
	v_lshl_add_u64 v[42:43], v[106:107], 0, v[42:43]
	v_lshl_add_u64 v[60:61], v[106:107], 0, v[60:61]
	v_lshl_add_u64 v[62:63], v[106:107], 0, v[62:63]
	v_lshl_add_u64 v[64:65], v[106:107], 0, v[64:65]
	v_lshl_add_u64 v[66:67], v[106:107], 0, v[66:67]
	v_lshl_add_u64 v[68:69], v[106:107], 0, v[68:69]
	v_lshl_add_u64 v[70:71], v[106:107], 0, v[70:71]
	v_lshl_add_u64 v[72:73], v[106:107], 0, v[72:73]
	v_lshl_add_u64 v[74:75], v[106:107], 0, v[74:75]
	v_lshl_add_u64 v[30:31], v[106:107], 0, v[30:31]
	v_lshl_add_u64 v[32:33], v[106:107], 0, v[32:33]
	v_lshl_add_u64 v[34:35], v[106:107], 0, v[34:35]
	v_lshl_add_u64 v[36:37], v[106:107], 0, v[36:37]
	v_lshl_add_u64 v[76:77], v[106:107], 0, v[76:77]
	v_lshl_add_u64 v[78:79], v[106:107], 0, v[78:79]
	v_lshl_add_u64 v[80:81], v[106:107], 0, v[80:81]
	v_lshl_add_u64 v[82:83], v[106:107], 0, v[82:83]
	v_lshl_add_u64 v[84:85], v[106:107], 0, v[84:85]
	v_lshl_add_u64 v[86:87], v[106:107], 0, v[86:87]
	v_lshl_add_u64 v[88:89], v[106:107], 0, v[88:89]
	v_lshl_add_u64 v[90:91], v[106:107], 0, v[90:91]
	v_lshl_add_u64 v[92:93], v[106:107], 0, v[92:93]
	v_lshl_add_u64 v[94:95], v[106:107], 0, v[94:95]
	v_lshl_add_u64 v[96:97], v[106:107], 0, v[96:97]
	v_lshl_add_u64 v[98:99], v[106:107], 0, v[98:99]
	v_lshl_add_u64 v[100:101], v[106:107], 0, v[100:101]
	v_lshl_add_u64 v[102:103], v[106:107], 0, v[102:103]
	v_lshl_add_u64 v[104:105], v[106:107], 0, v[104:105]
	global_load_dword v1, v[26:27], off
	global_load_dword v5, v[28:29], off
	global_load_dword v7, v[30:31], off
	global_load_dword v9, v[32:33], off
	global_load_dword v11, v[34:35], off
	global_load_dword v13, v[36:37], off
	global_load_dword v26, v[38:39], off
	global_load_dword v27, v[40:41], off
	global_load_dword v28, v[42:43], off
	global_load_dword v29, v[60:61], off
	s_nop 0
	global_load_dword v38, v[62:63], off
	global_load_dword v39, v[64:65], off
	global_load_dword v40, v[66:67], off
	global_load_dword v41, v[68:69], off
	global_load_dword v42, v[70:71], off
	global_load_dword v43, v[72:73], off
	global_load_dword v60, v[74:75], off
	global_load_dword v61, v[76:77], off
	global_load_dword v62, v[78:79], off
	global_load_dword v63, v[80:81], off
	global_load_dword v64, v[82:83], off
	global_load_dword v65, v[84:85], off
	global_load_dword v66, v[86:87], off
	global_load_dword v67, v[88:89], off
	global_load_dword v68, v[90:91], off
	global_load_dword v69, v[92:93], off
	global_load_dword v70, v[94:95], off
	global_load_dword v71, v[96:97], off
	global_load_dword v72, v[98:99], off
	global_load_dword v73, v[100:101], off
	global_load_dword v74, v[102:103], off
	global_load_dword v75, v[104:105], off
	s_lshl_b64 s[14:15], s[14:15], 10
	s_add_u32 s14, s33, s14
	s_addc_u32 s15, s34, s15
	s_ashr_i32 s3, s2, 31
	s_lshl_b64 s[2:3], s[2:3], 1
	s_add_u32 s2, s14, s2
	v_add_u32_e32 v76, 0x400, v45
	v_add_u32_e32 v77, 0x800, v45
	v_add_u32_e32 v78, 0xc00, v45
	v_add_u32_e32 v79, 0x1000, v45
	v_add_u32_e32 v80, 0x1400, v45
	v_add_u32_e32 v81, 0x1800, v45
	v_add_u32_e32 v82, 0x1c00, v45
	s_addc_u32 s3, s15, s3
	s_waitcnt vmcnt(0)
	ds_write2_b32 v45, v1, v5 offset1:66
	ds_write2_b32 v45, v7, v9 offset0:132 offset1:198
	ds_write2_b32 v76, v11, v13 offset0:8 offset1:74
	ds_write2_b32 v76, v26, v27 offset0:140 offset1:206
	ds_write2_b32 v77, v28, v29 offset0:16 offset1:82
	ds_write2_b32 v77, v38, v39 offset0:148 offset1:214
	ds_write2_b32 v78, v40, v41 offset0:24 offset1:90
	ds_write2_b32 v78, v42, v43 offset0:156 offset1:222
	ds_write2_b32 v79, v60, v61 offset0:32 offset1:98
	ds_write2_b32 v79, v62, v63 offset0:164 offset1:230
	ds_write2_b32 v80, v64, v65 offset0:40 offset1:106
	ds_write2_b32 v80, v66, v67 offset0:172 offset1:238
	ds_write2_b32 v81, v68, v69 offset0:48 offset1:114
	ds_write2_b32 v81, v70, v71 offset0:180 offset1:246
	ds_write2_b32 v82, v72, v73 offset0:56 offset1:122
	ds_write2_b32 v82, v74, v75 offset0:188 offset1:254
	v_mov_b32_e32 v17, v3
	v_mov_b32_e32 v19, v3
	v_lshl_add_u64 v[30:31], s[2:3], 0, v[2:3]
	s_waitcnt lgkmcnt(0)
; #define LAS __attribute__((address_space(3)))
; DI unsigned pk2(float lo, float hi) { typedef float v2f __attribute__((ext_vector_type(2))); typedef __bf16 v2b __attribute__((ext_vector_type(2))); v2f v = {lo, hi}; v2b b = __builtin_convertvector(v, v2b); return __builtin_bit_cast(unsigned, b); }
;     ...
;     for (int item = gw; item < nitems; item += ngw) {
;         const int kb = item / nblk, nb = nb0 + item % nblk, k0 = 64 * kb, n0 = 32 * nb;
;         float tv[32];
; #pragma unroll
;         for (int i = 0; i < 32; ++i) { const int kk = 2 * i + (lane >> 5); tv[i] = W[(size_t)(k0 + kk) * N + n0 + (lane & 31)]; }
; #pragma unroll
;         for (int i = 0; i < 32; ++i) { const int kk = 2 * i + (lane >> 5); float v = tv[i]; if (gk) v *= gk[k0 + kk]; scr[kk * 33 + (lane & 31)] = v; }
;         asm volatile("s_waitcnt lgkmcnt(0)" ::: "memory");
;         bf16_t* dst = dest_rows(mode, n0, K, d0, d1);
;         const int c = lane & 7;
; #pragma unroll
;         for (int jj = 0; jj < 4; ++jj) { const int n = (lane >> 3) + 8 * jj; const LAS float* s = scr + (8 * c) * 33 + n;
;             u32x4 o; o.x = pk2(s[0 * 33], s[1 * 33]); o.y = pk2(s[2 * 33], s[3 * 33]); o.z = pk2(s[4 * 33], s[5 * 33]); o.w = pk2(s[6 * 33], s[7 * 33]);
;             *(u32x4*)(dst + (size_t)n * K + k0 + 8 * c) = o; }
;         asm volatile("s_waitcnt lgkmcnt(0)" ::: "memory");
;     }
	v_lshl_add_u64 v[32:33], v[30:31], 0, v[16:17]
	v_lshl_add_u64 v[34:35], v[30:31], 0, v[18:19]
	ds_read_b32 v1, v44
	ds_read_b32 v5, v44 offset:132
	ds_read_b32 v7, v44 offset:264
	ds_read_b32 v9, v44 offset:396
	ds_read_b32 v11, v44 offset:528
	ds_read_b32 v13, v44 offset:660
	ds_read_b32 v17, v44 offset:792
	ds_read_b32 v19, v44 offset:924
	s_waitcnt lgkmcnt(0)
	v_cvt_pk_bf16_f32 v26, v1, v5
	v_cvt_pk_bf16_f32 v27, v7, v9
	v_cvt_pk_bf16_f32 v28, v11, v13
	v_mov_b32_e32 v21, v3
	v_cvt_pk_bf16_f32 v29, v17, v19
	global_store_dwordx4 v[32:33], v[26:29], off
	ds_read_b32 v1, v44 offset:32
	ds_read_b32 v5, v44 offset:164
	ds_read_b32 v7, v44 offset:296
	ds_read_b32 v9, v44 offset:428
	ds_read_b32 v11, v44 offset:560
	ds_read_b32 v13, v44 offset:692
	ds_read_b32 v17, v44 offset:824
	ds_read_b32 v19, v44 offset:956
	s_waitcnt lgkmcnt(0)
	v_cvt_pk_bf16_f32 v26, v1, v5
	v_cvt_pk_bf16_f32 v27, v7, v9
	v_cvt_pk_bf16_f32 v28, v11, v13
	v_lshl_add_u64 v[36:37], v[30:31], 0, v[20:21]
	v_cvt_pk_bf16_f32 v29, v17, v19
	global_store_dwordx4 v[34:35], v[26:29], off
	ds_read_b32 v1, v44 offset:64
	ds_read_b32 v5, v44 offset:196
	ds_read_b32 v7, v44 offset:328
	ds_read_b32 v9, v44 offset:460
	ds_read_b32 v11, v44 offset:592
	ds_read_b32 v13, v44 offset:724
	ds_read_b32 v17, v44 offset:856
	ds_read_b32 v19, v44 offset:988
	s_waitcnt lgkmcnt(0)
	v_cvt_pk_bf16_f32 v26, v1, v5
	v_cvt_pk_bf16_f32 v27, v7, v9
	v_cvt_pk_bf16_f32 v28, v11, v13
	v_mov_b32_e32 v23, v3
	v_cvt_pk_bf16_f32 v29, v17, v19
	global_store_dwordx4 v[36:37], v[26:29], off
	ds_read_b32 v1, v44 offset:96
	ds_read_b32 v5, v44 offset:228
	ds_read_b32 v7, v44 offset:360
	ds_read_b32 v9, v44 offset:492
	ds_read_b32 v11, v44 offset:624
	ds_read_b32 v13, v44 offset:756
	ds_read_b32 v17, v44 offset:888
	ds_read_b32 v19, v44 offset:1020
	v_lshl_add_u64 v[30:31], v[30:31], 0, v[22:23]
	s_waitcnt lgkmcnt(0)
	v_cvt_pk_bf16_f32 v26, v1, v5
	v_cvt_pk_bf16_f32 v27, v7, v9
	v_cvt_pk_bf16_f32 v28, v11, v13
	v_cvt_pk_bf16_f32 v29, v17, v19
	global_store_dwordx4 v[30:31], v[26:29], off
	s_waitcnt lgkmcnt(0)
	s_add_i32 s36, s36, s88
	s_add_i32 s35, s35, s13
	s_cmpk_lt_i32 s36, 0x100
	s_cbranch_scc1 .LBB0_184
	v_mov_b32_e32 v3, 0
	v_readlane_b32 s16, v249, 1
	v_mov_b32_e32 v5, v3
	v_readlane_b32 s18, v249, 3
	v_readlane_b32 s19, v249, 4
	s_add_u32 s33, s8, 0x2100000
	v_readlane_b32 s2, v249, 54
	v_lshl_add_u64 v[24:25], s[18:19], 0, v[4:5]
	s_addc_u32 s34, s9, 0
	s_mov_b32 s35, s2
	v_readlane_b32 s17, v249, 2
	v_readlane_b32 s20, v249, 5
	v_readlane_b32 s21, v249, 6
	v_readlane_b32 s22, v249, 7
	v_readlane_b32 s23, v249, 8
	v_readlane_b32 s24, v249, 9
	v_readlane_b32 s25, v249, 10
	v_readlane_b32 s26, v249, 11
	v_readlane_b32 s27, v249, 12
	v_readlane_b32 s28, v249, 13
	v_readlane_b32 s29, v249, 14
	v_readlane_b32 s30, v249, 15
	v_readlane_b32 s31, v249, 16
	v_readlane_b32 s3, v249, 55
.LBB0_186:
	s_ashr_i32 s2, s35, 31
	s_lshr_b32 s2, s2, 27
	s_add_i32 s2, s35, s2
	s_ashr_i32 s3, s2, 5
	s_lshl_b32 s2, s3, 6
	s_lshl_b32 s3, s3, 10
	v_or_b32_e32 v26, s2, v0
	s_sub_i32 s14, s12, s3
	v_or_b32_e32 v28, 2, v26
	v_or_b32_e32 v38, 12, v26
	v_or_b32_e32 v40, 14, v26
	v_or_b32_e32 v42, 16, v26
	v_or_b32_e32 v60, 18, v26
	v_or_b32_e32 v62, 20, v26
	v_or_b32_e32 v64, 22, v26
	v_or_b32_e32 v66, 24, v26
	v_or_b32_e32 v68, 26, v26
	v_or_b32_e32 v70, 28, v26
	v_or_b32_e32 v72, 30, v26
	v_or_b32_e32 v74, 32, v26
	s_ashr_i32 s15, s14, 31
	v_ashrrev_i32_e32 v27, 31, v26
	v_or_b32_e32 v30, 4, v26
	v_or_b32_e32 v32, 6, v26
	v_or_b32_e32 v34, 8, v26
	v_or_b32_e32 v36, 10, v26
	v_or_b32_e32 v76, 34, v26
	v_or_b32_e32 v78, 36, v26
	v_or_b32_e32 v80, 38, v26
	v_or_b32_e32 v82, 40, v26
	v_or_b32_e32 v84, 42, v26
	v_or_b32_e32 v86, 44, v26
	v_or_b32_e32 v88, 46, v26
	v_or_b32_e32 v90, 48, v26
	v_or_b32_e32 v92, 50, v26
	v_or_b32_e32 v94, 52, v26
	v_or_b32_e32 v96, 54, v26
	v_or_b32_e32 v98, 56, v26
	v_or_b32_e32 v100, 58, v26
	v_or_b32_e32 v102, 60, v26
	v_or_b32_e32 v104, 62, v26
	v_ashrrev_i32_e32 v29, 31, v28
	v_ashrrev_i32_e32 v39, 31, v38
	v_ashrrev_i32_e32 v41, 31, v40
	v_ashrrev_i32_e32 v43, 31, v42
	v_ashrrev_i32_e32 v61, 31, v60
	v_ashrrev_i32_e32 v63, 31, v62
	v_ashrrev_i32_e32 v65, 31, v64
	v_ashrrev_i32_e32 v67, 31, v66
	v_ashrrev_i32_e32 v69, 31, v68
	v_ashrrev_i32_e32 v71, 31, v70
	v_ashrrev_i32_e32 v73, 31, v72
	v_ashrrev_i32_e32 v75, 31, v74
	v_lshl_add_u64 v[106:107], s[14:15], 2, v[24:25]
	v_lshlrev_b64 v[26:27], 12, v[26:27]
	v_ashrrev_i32_e32 v31, 31, v30
	v_ashrrev_i32_e32 v33, 31, v32
	v_ashrrev_i32_e32 v35, 31, v34
	v_ashrrev_i32_e32 v37, 31, v36
	v_ashrrev_i32_e32 v77, 31, v76
	v_ashrrev_i32_e32 v79, 31, v78
	v_ashrrev_i32_e32 v81, 31, v80
	v_ashrrev_i32_e32 v83, 31, v82
	v_ashrrev_i32_e32 v85, 31, v84
	v_ashrrev_i32_e32 v87, 31, v86
	v_ashrrev_i32_e32 v89, 31, v88
	v_ashrrev_i32_e32 v91, 31, v90
	v_ashrrev_i32_e32 v93, 31, v92
	v_ashrrev_i32_e32 v95, 31, v94
	v_ashrrev_i32_e32 v97, 31, v96
	v_ashrrev_i32_e32 v99, 31, v98
	v_ashrrev_i32_e32 v101, 31, v100
	v_ashrrev_i32_e32 v103, 31, v102
	v_ashrrev_i32_e32 v105, 31, v104
	v_lshlrev_b64 v[28:29], 12, v[28:29]
	v_lshlrev_b64 v[38:39], 12, v[38:39]
	v_lshlrev_b64 v[40:41], 12, v[40:41]
	v_lshlrev_b64 v[42:43], 12, v[42:43]
	v_lshlrev_b64 v[60:61], 12, v[60:61]
	v_lshlrev_b64 v[62:63], 12, v[62:63]
	v_lshlrev_b64 v[64:65], 12, v[64:65]
	v_lshlrev_b64 v[66:67], 12, v[66:67]
	v_lshlrev_b64 v[68:69], 12, v[68:69]
	v_lshlrev_b64 v[70:71], 12, v[70:71]
	v_lshlrev_b64 v[72:73], 12, v[72:73]
	v_lshlrev_b64 v[74:75], 12, v[74:75]
	v_lshl_add_u64 v[26:27], v[106:107], 0, v[26:27]
	v_lshlrev_b64 v[30:31], 12, v[30:31]
	v_lshlrev_b64 v[32:33], 12, v[32:33]
; #define LAS __attribute__((address_space(3)))
; DI unsigned pk2(float lo, float hi) { typedef float v2f __attribute__((ext_vector_type(2))); typedef __bf16 v2b __attribute__((ext_vector_type(2))); v2f v = {lo, hi}; v2b b = __builtin_convertvector(v, v2b); return __builtin_bit_cast(unsigned, b); }
;     ...
;     for (int item = gw; item < nitems; item += ngw) {
;         const int kb = item / nblk, nb = nb0 + item % nblk, k0 = 64 * kb, n0 = 32 * nb;
;         float tv[32];
; #pragma unroll
;         for (int i = 0; i < 32; ++i) { const int kk = 2 * i + (lane >> 5); tv[i] = W[(size_t)(k0 + kk) * N + n0 + (lane & 31)]; }
; #pragma unroll
;         for (int i = 0; i < 32; ++i) { const int kk = 2 * i + (lane >> 5); float v = tv[i]; if (gk) v *= gk[k0 + kk]; scr[kk * 33 + (lane & 31)] = v; }
;         asm volatile("s_waitcnt lgkmcnt(0)" ::: "memory");
;         bf16_t* dst = dest_rows(mode, n0, K, d0, d1);
;         const int c = lane & 7;
; #pragma unroll
;         for (int jj = 0; jj < 4; ++jj) { const int n = (lane >> 3) + 8 * jj; const LAS float* s = scr + (8 * c) * 33 + n;
;             u32x4 o; o.x = pk2(s[0 * 33], s[1 * 33]); o.y = pk2(s[2 * 33], s[3 * 33]); o.z = pk2(s[4 * 33], s[5 * 33]); o.w = pk2(s[6 * 33], s[7 * 33]);
;             *(u32x4*)(dst + (size_t)n * K + k0 + 8 * c) = o; }
;         asm volatile("s_waitcnt lgkmcnt(0)" ::: "memory");
;     }
	v_lshlrev_b64 v[34:35], 12, v[34:35]
	v_lshlrev_b64 v[36:37], 12, v[36:37]
	v_lshlrev_b64 v[76:77], 12, v[76:77]
	v_lshlrev_b64 v[78:79], 12, v[78:79]
	v_lshlrev_b64 v[80:81], 12, v[80:81]
	v_lshlrev_b64 v[82:83], 12, v[82:83]
	v_lshlrev_b64 v[84:85], 12, v[84:85]
	v_lshlrev_b64 v[86:87], 12, v[86:87]
	v_lshlrev_b64 v[88:89], 12, v[88:89]
	v_lshlrev_b64 v[90:91], 12, v[90:91]
	v_lshlrev_b64 v[92:93], 12, v[92:93]
	v_lshlrev_b64 v[94:95], 12, v[94:95]
	v_lshlrev_b64 v[96:97], 12, v[96:97]
	v_lshlrev_b64 v[98:99], 12, v[98:99]
	v_lshlrev_b64 v[100:101], 12, v[100:101]
	v_lshlrev_b64 v[102:103], 12, v[102:103]
	v_lshlrev_b64 v[104:105], 12, v[104:105]
	v_lshl_add_u64 v[28:29], v[106:107], 0, v[28:29]
	v_lshl_add_u64 v[38:39], v[106:107], 0, v[38:39]
	v_lshl_add_u64 v[40:41], v[106:107], 0, v[40:41]
	v_lshl_add_u64 v[42:43], v[106:107], 0, v[42:43]
	v_lshl_add_u64 v[60:61], v[106:107], 0, v[60:61]
	v_lshl_add_u64 v[62:63], v[106:107], 0, v[62:63]
	v_lshl_add_u64 v[64:65], v[106:107], 0, v[64:65]
	v_lshl_add_u64 v[66:67], v[106:107], 0, v[66:67]
	v_lshl_add_u64 v[68:69], v[106:107], 0, v[68:69]
	v_lshl_add_u64 v[70:71], v[106:107], 0, v[70:71]
	v_lshl_add_u64 v[72:73], v[106:107], 0, v[72:73]
	v_lshl_add_u64 v[74:75], v[106:107], 0, v[74:75]
	v_lshl_add_u64 v[30:31], v[106:107], 0, v[30:31]
	v_lshl_add_u64 v[32:33], v[106:107], 0, v[32:33]
	v_lshl_add_u64 v[34:35], v[106:107], 0, v[34:35]
	v_lshl_add_u64 v[36:37], v[106:107], 0, v[36:37]
	v_lshl_add_u64 v[76:77], v[106:107], 0, v[76:77]
	v_lshl_add_u64 v[78:79], v[106:107], 0, v[78:79]
	v_lshl_add_u64 v[80:81], v[106:107], 0, v[80:81]
	v_lshl_add_u64 v[82:83], v[106:107], 0, v[82:83]
	v_lshl_add_u64 v[84:85], v[106:107], 0, v[84:85]
	v_lshl_add_u64 v[86:87], v[106:107], 0, v[86:87]
	v_lshl_add_u64 v[88:89], v[106:107], 0, v[88:89]
	v_lshl_add_u64 v[90:91], v[106:107], 0, v[90:91]
	v_lshl_add_u64 v[92:93], v[106:107], 0, v[92:93]
	v_lshl_add_u64 v[94:95], v[106:107], 0, v[94:95]
	v_lshl_add_u64 v[96:97], v[106:107], 0, v[96:97]
	v_lshl_add_u64 v[98:99], v[106:107], 0, v[98:99]
	v_lshl_add_u64 v[100:101], v[106:107], 0, v[100:101]
	v_lshl_add_u64 v[102:103], v[106:107], 0, v[102:103]
	v_lshl_add_u64 v[104:105], v[106:107], 0, v[104:105]
	global_load_dword v1, v[26:27], off
	global_load_dword v5, v[28:29], off
	global_load_dword v7, v[30:31], off
	global_load_dword v9, v[32:33], off
	global_load_dword v11, v[34:35], off
	global_load_dword v13, v[36:37], off
	global_load_dword v26, v[38:39], off
	global_load_dword v27, v[40:41], off
	global_load_dword v28, v[42:43], off
	global_load_dword v29, v[60:61], off
	s_nop 0
	global_load_dword v38, v[62:63], off
	global_load_dword v39, v[64:65], off
	global_load_dword v40, v[66:67], off
	global_load_dword v41, v[68:69], off
	global_load_dword v42, v[70:71], off
	global_load_dword v43, v[72:73], off
	global_load_dword v60, v[74:75], off
	global_load_dword v61, v[76:77], off
	global_load_dword v62, v[78:79], off
	global_load_dword v63, v[80:81], off
	global_load_dword v64, v[82:83], off
	global_load_dword v65, v[84:85], off
	global_load_dword v66, v[86:87], off
	global_load_dword v67, v[88:89], off
	global_load_dword v68, v[90:91], off
	global_load_dword v69, v[92:93], off
	global_load_dword v70, v[94:95], off
	global_load_dword v71, v[96:97], off
	global_load_dword v72, v[98:99], off
	global_load_dword v73, v[100:101], off
	global_load_dword v74, v[102:103], off
	global_load_dword v75, v[104:105], off
	s_lshl_b64 s[14:15], s[14:15], 10
	s_add_u32 s14, s33, s14
	s_addc_u32 s15, s34, s15
	s_ashr_i32 s3, s2, 31
	s_lshl_b64 s[2:3], s[2:3], 1
	s_add_u32 s2, s14, s2
	v_add_u32_e32 v76, 0x400, v45
	v_add_u32_e32 v77, 0x800, v45
	v_add_u32_e32 v78, 0xc00, v45
	v_add_u32_e32 v79, 0x1000, v45
	v_add_u32_e32 v80, 0x1400, v45
	v_add_u32_e32 v81, 0x1800, v45
	v_add_u32_e32 v82, 0x1c00, v45
	s_addc_u32 s3, s15, s3
	s_waitcnt vmcnt(0)
	ds_write2_b32 v45, v1, v5 offset1:66
	ds_write2_b32 v45, v7, v9 offset0:132 offset1:198
	ds_write2_b32 v76, v11, v13 offset0:8 offset1:74
	ds_write2_b32 v76, v26, v27 offset0:140 offset1:206
	ds_write2_b32 v77, v28, v29 offset0:16 offset1:82
	ds_write2_b32 v77, v38, v39 offset0:148 offset1:214
	ds_write2_b32 v78, v40, v41 offset0:24 offset1:90
	ds_write2_b32 v78, v42, v43 offset0:156 offset1:222
	ds_write2_b32 v79, v60, v61 offset0:32 offset1:98
	ds_write2_b32 v79, v62, v63 offset0:164 offset1:230
	ds_write2_b32 v80, v64, v65 offset0:40 offset1:106
	ds_write2_b32 v80, v66, v67 offset0:172 offset1:238
	ds_write2_b32 v81, v68, v69 offset0:48 offset1:114
	ds_write2_b32 v81, v70, v71 offset0:180 offset1:246
	ds_write2_b32 v82, v72, v73 offset0:56 offset1:122
	ds_write2_b32 v82, v74, v75 offset0:188 offset1:254
	v_mov_b32_e32 v17, v3
	v_mov_b32_e32 v19, v3
	v_lshl_add_u64 v[30:31], s[2:3], 0, v[2:3]
	s_waitcnt lgkmcnt(0)
	v_lshl_add_u64 v[32:33], v[30:31], 0, v[16:17]
	v_lshl_add_u64 v[34:35], v[30:31], 0, v[18:19]
	ds_read_b32 v1, v44
	ds_read_b32 v5, v44 offset:132
	ds_read_b32 v7, v44 offset:264
	ds_read_b32 v9, v44 offset:396
	ds_read_b32 v11, v44 offset:528
	ds_read_b32 v13, v44 offset:660
	ds_read_b32 v17, v44 offset:792
	ds_read_b32 v19, v44 offset:924
	s_waitcnt lgkmcnt(0)
	v_cvt_pk_bf16_f32 v26, v1, v5
	v_cvt_pk_bf16_f32 v27, v7, v9
	v_cvt_pk_bf16_f32 v28, v11, v13
	v_mov_b32_e32 v21, v3
	v_cvt_pk_bf16_f32 v29, v17, v19
	global_store_dwordx4 v[32:33], v[26:29], off
	ds_read_b32 v1, v44 offset:32
	ds_read_b32 v5, v44 offset:164
	ds_read_b32 v7, v44 offset:296
	ds_read_b32 v9, v44 offset:428
	ds_read_b32 v11, v44 offset:560
	ds_read_b32 v13, v44 offset:692
	ds_read_b32 v17, v44 offset:824
	ds_read_b32 v19, v44 offset:956
	s_waitcnt lgkmcnt(0)
	v_cvt_pk_bf16_f32 v26, v1, v5
	v_cvt_pk_bf16_f32 v27, v7, v9
	v_cvt_pk_bf16_f32 v28, v11, v13
	v_lshl_add_u64 v[36:37], v[30:31], 0, v[20:21]
	v_cvt_pk_bf16_f32 v29, v17, v19
	global_store_dwordx4 v[34:35], v[26:29], off
	ds_read_b32 v1, v44 offset:64
	ds_read_b32 v5, v44 offset:196
	ds_read_b32 v7, v44 offset:328
	ds_read_b32 v9, v44 offset:460
	ds_read_b32 v11, v44 offset:592
	ds_read_b32 v13, v44 offset:724
	ds_read_b32 v17, v44 offset:856
	ds_read_b32 v19, v44 offset:988
	s_waitcnt lgkmcnt(0)
	v_cvt_pk_bf16_f32 v26, v1, v5
	v_cvt_pk_bf16_f32 v27, v7, v9
	v_cvt_pk_bf16_f32 v28, v11, v13
	v_mov_b32_e32 v23, v3
	v_cvt_pk_bf16_f32 v29, v17, v19
	global_store_dwordx4 v[36:37], v[26:29], off
	ds_read_b32 v1, v44 offset:96
	ds_read_b32 v5, v44 offset:228
	ds_read_b32 v7, v44 offset:360
	ds_read_b32 v9, v44 offset:492
	ds_read_b32 v11, v44 offset:624
	ds_read_b32 v13, v44 offset:756
	ds_read_b32 v17, v44 offset:888
	ds_read_b32 v19, v44 offset:1020
	v_lshl_add_u64 v[30:31], v[30:31], 0, v[22:23]
	s_waitcnt lgkmcnt(0)
	v_cvt_pk_bf16_f32 v26, v1, v5
	v_cvt_pk_bf16_f32 v27, v7, v9
	v_cvt_pk_bf16_f32 v28, v11, v13
	v_cvt_pk_bf16_f32 v29, v17, v19
	global_store_dwordx4 v[30:31], v[26:29], off
	s_waitcnt lgkmcnt(0)
	s_add_i32 s35, s35, s88
	s_add_i32 s12, s12, s13
	s_cmpk_lt_i32 s35, 0x100
	s_cbranch_scc1 .LBB0_186

;     ...
;     for (int item = gw; item < nitems; item += ngw) {
;         const int kb = item / nblk, nb = nb0 + item % nblk, k0 = 64 * kb, n0 = 32 * nb;
;         float tv[32];
; #pragma unroll
;         for (int i = 0; i < 32; ++i) { const int kk = 2 * i + (lane >> 5); tv[i] = W[(size_t)(k0 + kk) * N + n0 + (lane & 31)]; }
.LBB0_189:
	s_ashr_i32 s2, s35, 31
	s_lshr_b32 s2, s2, 27
	s_add_i32 s2, s35, s2
	s_ashr_i32 s3, s2, 5
	s_lshl_b32 s2, s3, 6
	s_lshl_b32 s3, s3, 10
	v_or_b32_e32 v24, s2, v0
	s_sub_i32 s14, s33, s3
	v_or_b32_e32 v26, 2, v24
	v_or_b32_e32 v36, 12, v24
	v_or_b32_e32 v38, 14, v24
	v_or_b32_e32 v40, 16, v24
	v_or_b32_e32 v42, 18, v24
	v_or_b32_e32 v60, 20, v24
	v_or_b32_e32 v62, 22, v24
	v_or_b32_e32 v64, 24, v24
	v_or_b32_e32 v66, 26, v24
	v_or_b32_e32 v68, 28, v24
	v_or_b32_e32 v70, 30, v24
	v_or_b32_e32 v72, 32, v24
	v_or_b32_e32 v74, 34, v24
	v_or_b32_e32 v76, 36, v24
	s_ashr_i32 s15, s14, 31
	v_ashrrev_i32_e32 v25, 31, v24
	v_or_b32_e32 v28, 4, v24
	v_or_b32_e32 v30, 6, v24
	v_or_b32_e32 v32, 8, v24
	v_or_b32_e32 v34, 10, v24
	v_or_b32_e32 v78, 38, v24
	v_or_b32_e32 v80, 40, v24
	v_or_b32_e32 v82, 42, v24
	v_or_b32_e32 v84, 44, v24
	v_or_b32_e32 v86, 46, v24
	v_or_b32_e32 v88, 48, v24
	v_or_b32_e32 v90, 50, v24
	v_or_b32_e32 v92, 52, v24
	v_or_b32_e32 v94, 54, v24
	v_or_b32_e32 v96, 56, v24
	v_or_b32_e32 v98, 58, v24
	v_or_b32_e32 v100, 60, v24
	v_or_b32_e32 v102, 62, v24
	v_ashrrev_i32_e32 v27, 31, v26
	v_ashrrev_i32_e32 v37, 31, v36
	v_ashrrev_i32_e32 v39, 31, v38
	v_ashrrev_i32_e32 v41, 31, v40
	v_ashrrev_i32_e32 v43, 31, v42
	v_ashrrev_i32_e32 v61, 31, v60
	v_ashrrev_i32_e32 v63, 31, v62
	v_ashrrev_i32_e32 v65, 31, v64
	v_ashrrev_i32_e32 v67, 31, v66
	v_ashrrev_i32_e32 v69, 31, v68
	v_ashrrev_i32_e32 v71, 31, v70
	v_ashrrev_i32_e32 v73, 31, v72
	v_ashrrev_i32_e32 v75, 31, v74
	v_ashrrev_i32_e32 v77, 31, v76
	v_lshl_add_u64 v[104:105], s[14:15], 2, v[16:17]
	v_lshlrev_b64 v[24:25], 12, v[24:25]
	v_ashrrev_i32_e32 v29, 31, v28
	v_ashrrev_i32_e32 v31, 31, v30
	v_ashrrev_i32_e32 v33, 31, v32
	v_ashrrev_i32_e32 v35, 31, v34
	v_ashrrev_i32_e32 v79, 31, v78
	v_ashrrev_i32_e32 v81, 31, v80
	v_ashrrev_i32_e32 v83, 31, v82
	v_ashrrev_i32_e32 v85, 31, v84
	v_ashrrev_i32_e32 v87, 31, v86
	v_ashrrev_i32_e32 v89, 31, v88
	v_ashrrev_i32_e32 v91, 31, v90
	v_ashrrev_i32_e32 v93, 31, v92
	v_ashrrev_i32_e32 v95, 31, v94
	v_ashrrev_i32_e32 v97, 31, v96
	v_ashrrev_i32_e32 v99, 31, v98
	v_ashrrev_i32_e32 v101, 31, v100
	v_ashrrev_i32_e32 v103, 31, v102
	v_lshlrev_b64 v[26:27], 12, v[26:27]
	v_lshlrev_b64 v[36:37], 12, v[36:37]
	v_lshlrev_b64 v[38:39], 12, v[38:39]
	v_lshlrev_b64 v[40:41], 12, v[40:41]
	v_lshlrev_b64 v[42:43], 12, v[42:43]
	v_lshlrev_b64 v[60:61], 12, v[60:61]
	v_lshlrev_b64 v[62:63], 12, v[62:63]
	v_lshlrev_b64 v[64:65], 12, v[64:65]
	v_lshlrev_b64 v[66:67], 12, v[66:67]
	v_lshlrev_b64 v[68:69], 12, v[68:69]
	v_lshlrev_b64 v[70:71], 12, v[70:71]
	v_lshlrev_b64 v[72:73], 12, v[72:73]
	v_lshlrev_b64 v[74:75], 12, v[74:75]
	v_lshlrev_b64 v[76:77], 12, v[76:77]
	v_lshl_add_u64 v[24:25], v[104:105], 0, v[24:25]
	v_lshlrev_b64 v[28:29], 12, v[28:29]
	v_lshlrev_b64 v[30:31], 12, v[30:31]
	v_lshlrev_b64 v[32:33], 12, v[32:33]
	v_lshlrev_b64 v[34:35], 12, v[34:35]
	v_lshlrev_b64 v[78:79], 12, v[78:79]
	v_lshlrev_b64 v[80:81], 12, v[80:81]
	v_lshlrev_b64 v[82:83], 12, v[82:83]
	v_lshlrev_b64 v[84:85], 12, v[84:85]
	v_lshlrev_b64 v[86:87], 12, v[86:87]
	v_lshlrev_b64 v[88:89], 12, v[88:89]
	v_lshlrev_b64 v[90:91], 12, v[90:91]
	v_lshlrev_b64 v[92:93], 12, v[92:93]
	v_lshlrev_b64 v[94:95], 12, v[94:95]
	v_lshlrev_b64 v[96:97], 12, v[96:97]
	v_lshlrev_b64 v[98:99], 12, v[98:99]
	v_lshlrev_b64 v[100:101], 12, v[100:101]
	v_lshlrev_b64 v[102:103], 12, v[102:103]
	v_lshl_add_u64 v[26:27], v[104:105], 0, v[26:27]
	v_lshl_add_u64 v[36:37], v[104:105], 0, v[36:37]
	v_lshl_add_u64 v[38:39], v[104:105], 0, v[38:39]
	v_lshl_add_u64 v[40:41], v[104:105], 0, v[40:41]
	v_lshl_add_u64 v[42:43], v[104:105], 0, v[42:43]
	v_lshl_add_u64 v[60:61], v[104:105], 0, v[60:61]
	v_lshl_add_u64 v[62:63], v[104:105], 0, v[62:63]
	v_lshl_add_u64 v[64:65], v[104:105], 0, v[64:65]
	v_lshl_add_u64 v[66:67], v[104:105], 0, v[66:67]
	v_lshl_add_u64 v[68:69], v[104:105], 0, v[68:69]
	v_lshl_add_u64 v[70:71], v[104:105], 0, v[70:71]
	v_lshl_add_u64 v[72:73], v[104:105], 0, v[72:73]
	v_lshl_add_u64 v[74:75], v[104:105], 0, v[74:75]
	v_lshl_add_u64 v[76:77], v[104:105], 0, v[76:77]
	v_lshl_add_u64 v[28:29], v[104:105], 0, v[28:29]
	v_lshl_add_u64 v[30:31], v[104:105], 0, v[30:31]
	v_lshl_add_u64 v[32:33], v[104:105], 0, v[32:33]
	v_lshl_add_u64 v[34:35], v[104:105], 0, v[34:35]
	v_lshl_add_u64 v[78:79], v[104:105], 0, v[78:79]
	v_lshl_add_u64 v[80:81], v[104:105], 0, v[80:81]
	v_lshl_add_u64 v[82:83], v[104:105], 0, v[82:83]
	v_lshl_add_u64 v[84:85], v[104:105], 0, v[84:85]
	v_lshl_add_u64 v[86:87], v[104:105], 0, v[86:87]
	v_lshl_add_u64 v[88:89], v[104:105], 0, v[88:89]
	v_lshl_add_u64 v[90:91], v[104:105], 0, v[90:91]
	v_lshl_add_u64 v[92:93], v[104:105], 0, v[92:93]
	v_lshl_add_u64 v[94:95], v[104:105], 0, v[94:95]
	v_lshl_add_u64 v[96:97], v[104:105], 0, v[96:97]
	v_lshl_add_u64 v[98:99], v[104:105], 0, v[98:99]
	v_lshl_add_u64 v[100:101], v[104:105], 0, v[100:101]
	v_lshl_add_u64 v[102:103], v[104:105], 0, v[102:103]
	global_load_dword v23, v[24:25], off
	s_nop 0
	global_load_dword v24, v[26:27], off
	global_load_dword v25, v[28:29], off
	s_nop 0
	global_load_dword v26, v[30:31], off
	global_load_dword v27, v[32:33], off
	global_load_dword v104, v[34:35], off
	s_nop 0
	global_load_dword v36, v[36:37], off
	s_nop 0
	global_load_dword v37, v[38:39], off
	s_nop 0
	global_load_dword v38, v[40:41], off
	global_load_dword v39, v[42:43], off
	s_nop 0
	global_load_dword v40, v[60:61], off
	global_load_dword v41, v[62:63], off
	global_load_dword v42, v[64:65], off
	global_load_dword v43, v[66:67], off
	s_nop 0
	global_load_dword v60, v[68:69], off
	global_load_dword v61, v[70:71], off
	global_load_dword v62, v[72:73], off
	global_load_dword v63, v[74:75], off
	global_load_dword v64, v[76:77], off
	global_load_dword v65, v[78:79], off
	global_load_dword v66, v[80:81], off
	global_load_dword v67, v[82:83], off
	global_load_dword v68, v[84:85], off
	global_load_dword v69, v[86:87], off
	global_load_dword v70, v[88:89], off
	global_load_dword v71, v[90:91], off
	global_load_dword v72, v[92:93], off
	global_load_dword v73, v[94:95], off
	global_load_dword v74, v[96:97], off
	global_load_dword v75, v[98:99], off
	global_load_dword v76, v[100:101], off
	global_load_dword v77, v[102:103], off
	s_lshl_b64 s[14:15], s[14:15], 11
	s_waitcnt vmcnt(0)
; #define LAS __attribute__((address_space(3)))
; DI unsigned pk2(float lo, float hi) { typedef float v2f __attribute__((ext_vector_type(2))); typedef __bf16 v2b __attribute__((ext_vector_type(2))); v2f v = {lo, hi}; v2b b = __builtin_convertvector(v, v2b); return __builtin_bit_cast(unsigned, b); }
;     ...
;         for (int i = 0; i < 32; ++i) { const int kk = 2 * i + (lane >> 5); float v = tv[i]; if (gk) v *= gk[k0 + kk]; scr[kk * 33 + (lane & 31)] = v; }
;         asm volatile("s_waitcnt lgkmcnt(0)" ::: "memory");
;         bf16_t* dst = dest_rows(mode, n0, K, d0, d1);
;         const int c = lane & 7;
; #pragma unroll
;         for (int jj = 0; jj < 4; ++jj) { const int n = (lane >> 3) + 8 * jj; const LAS float* s = scr + (8 * c) * 33 + n;
;             u32x4 o; o.x = pk2(s[0 * 33], s[1 * 33]); o.y = pk2(s[2 * 33], s[3 * 33]); o.z = pk2(s[4 * 33], s[5 * 33]); o.w = pk2(s[6 * 33], s[7 * 33]);
;             *(u32x4*)(dst + (size_t)n * K + k0 + 8 * c) = o; }
;         asm volatile("s_waitcnt lgkmcnt(0)" ::: "memory");
;     }
	ds_write2_b32 v45, v23, v24 offset1:66
	ds_write2_b32 v45, v25, v26 offset0:132 offset1:198
	ds_write2_b32 v1, v27, v104 offset0:8 offset1:74
	ds_write2_b32 v1, v36, v37 offset0:140 offset1:206
	ds_write2_b32 v5, v38, v39 offset0:16 offset1:82
	ds_write2_b32 v5, v40, v41 offset0:148 offset1:214
	ds_write2_b32 v18, v42, v43 offset0:24 offset1:90
	ds_write2_b32 v18, v60, v61 offset0:156 offset1:222
	ds_write2_b32 v19, v62, v63 offset0:32 offset1:98
	ds_write2_b32 v19, v64, v65 offset0:164 offset1:230
	ds_write2_b32 v20, v66, v67 offset0:40 offset1:106
	ds_write2_b32 v20, v68, v69 offset0:172 offset1:238
	ds_write2_b32 v21, v70, v71 offset0:48 offset1:114
	ds_write2_b32 v21, v72, v73 offset0:180 offset1:246
	ds_write2_b32 v22, v74, v75 offset0:56 offset1:122
	ds_write2_b32 v22, v76, v77 offset0:188 offset1:254
	s_add_u32 s14, s12, s14
	s_waitcnt lgkmcnt(0)
	s_addc_u32 s15, s13, s15
	s_ashr_i32 s3, s2, 31
	ds_read_b32 v23, v44
	ds_read_b32 v24, v44 offset:132
	ds_read_b32 v25, v44 offset:264
	ds_read_b32 v26, v44 offset:396
	ds_read_b32 v27, v44 offset:528
	ds_read_b32 v36, v44 offset:660
	ds_read_b32 v37, v44 offset:792
	ds_read_b32 v38, v44 offset:924
	s_lshl_b64 s[2:3], s[2:3], 1
	s_add_u32 s2, s14, s2
	s_addc_u32 s3, s15, s3
	v_lshl_add_u64 v[28:29], s[2:3], 0, v[2:3]
	v_lshl_add_u64 v[30:31], v[28:29], 0, v[6:7]
	s_waitcnt lgkmcnt(0)
	v_cvt_pk_bf16_f32 v24, v23, v24
	v_cvt_pk_bf16_f32 v25, v25, v26
	v_cvt_pk_bf16_f32 v26, v27, v36
	v_cvt_pk_bf16_f32 v27, v37, v38
	global_store_dwordx4 v[30:31], v[24:27], off
	ds_read_b32 v23, v44 offset:32
	ds_read_b32 v24, v44 offset:164
	ds_read_b32 v25, v44 offset:296
	ds_read_b32 v26, v44 offset:428
	ds_read_b32 v27, v44 offset:560
	ds_read_b32 v30, v44 offset:692
	ds_read_b32 v31, v44 offset:824
	ds_read_b32 v36, v44 offset:956
	v_lshl_add_u64 v[32:33], v[28:29], 0, v[8:9]
	s_waitcnt lgkmcnt(0)
	v_cvt_pk_bf16_f32 v24, v23, v24
	v_cvt_pk_bf16_f32 v25, v25, v26
	v_cvt_pk_bf16_f32 v26, v27, v30
	v_cvt_pk_bf16_f32 v27, v31, v36
	global_store_dwordx4 v[32:33], v[24:27], off
	ds_read_b32 v23, v44 offset:64
	ds_read_b32 v24, v44 offset:196
	ds_read_b32 v25, v44 offset:328
	ds_read_b32 v26, v44 offset:460
	ds_read_b32 v27, v44 offset:592
	ds_read_b32 v30, v44 offset:724
	ds_read_b32 v31, v44 offset:856
	ds_read_b32 v32, v44 offset:988
	v_lshl_add_u64 v[34:35], v[28:29], 0, v[10:11]
	s_waitcnt lgkmcnt(0)
	v_cvt_pk_bf16_f32 v24, v23, v24
	v_cvt_pk_bf16_f32 v25, v25, v26
	v_cvt_pk_bf16_f32 v26, v27, v30
	v_cvt_pk_bf16_f32 v27, v31, v32
	global_store_dwordx4 v[34:35], v[24:27], off
	ds_read_b32 v23, v44 offset:96
	ds_read_b32 v24, v44 offset:228
	ds_read_b32 v25, v44 offset:360
	ds_read_b32 v26, v44 offset:492
	ds_read_b32 v27, v44 offset:624
	ds_read_b32 v30, v44 offset:756
	ds_read_b32 v31, v44 offset:888
	ds_read_b32 v32, v44 offset:1020
	v_lshl_add_u64 v[28:29], v[28:29], 0, v[12:13]
	s_waitcnt lgkmcnt(0)
	v_cvt_pk_bf16_f32 v24, v23, v24
	v_cvt_pk_bf16_f32 v25, v25, v26
	v_cvt_pk_bf16_f32 v26, v27, v30
	v_cvt_pk_bf16_f32 v27, v31, v32
	global_store_dwordx4 v[28:29], v[24:27], off
	s_waitcnt lgkmcnt(0)
	s_add_i32 s35, s35, s88
	s_add_i32 s33, s33, s34
	s_cmpk_lt_i32 s35, 0x200
	s_cbranch_scc1 .LBB0_189

; #define LAS __attribute__((address_space(3)))
; DI unsigned pk2(float lo, float hi) { typedef float v2f __attribute__((ext_vector_type(2))); typedef __bf16 v2b __attribute__((ext_vector_type(2))); v2f v = {lo, hi}; v2b b = __builtin_convertvector(v, v2b); return __builtin_bit_cast(unsigned, b); }
; DI bf16_t* dest_rows(int mode, int n0, int K, bf16_t* d0, bf16_t* d1) {
;     if (mode == 1) { const int isu = n0 >= FF ? 1 : 0, c = n0 - isu * FF; return d0 + (size_t)((c >> 7) * 256 + isu * 128 + (c & 127)) * K; }
;     if (mode == 2) {
;         if (n0 < 1664) return d0 + (size_t)n0 * K;
;         if (n0 < 1696) return d0 + (size_t)(2176 + n0 - 1664) * K;
;         if (n0 < 2208) return d0 + (size_t)(1664 + n0 - 1696) * K;
;         return d1 + (size_t)(n0 - 2208) * K;
;     }
;     return d0 + (size_t)n0 * K;
; }
;     if (nb1 < 0) nb1 = N / 32;
;     const int nblk = nb1 - nb0, nitems = (K / 64) * nblk;
;     for (int item = gw; item < nitems; item += ngw) {
;         const int kb = item / nblk, nb = nb0 + item % nblk, k0 = 64 * kb, n0 = 32 * nb;
;         float tv[32];
; #pragma unroll
;         for (int i = 0; i < 32; ++i) { const int kk = 2 * i + (lane >> 5); tv[i] = W[(size_t)(k0 + kk) * N + n0 + (lane & 31)]; }
; #pragma unroll
;         for (int i = 0; i < 32; ++i) { const int kk = 2 * i + (lane >> 5); float v = tv[i]; if (gk) v *= gk[k0 + kk]; scr[kk * 33 + (lane & 31)] = v; }
;         asm volatile("s_waitcnt lgkmcnt(0)" ::: "memory");
;         bf16_t* dst = dest_rows(mode, n0, K, d0, d1);
;         const int c = lane & 7;
; #pragma unroll
;         for (int jj = 0; jj < 4; ++jj) { const int n = (lane >> 3) + 8 * jj; const LAS float* s = scr + (8 * c) * 33 + n;
;             u32x4 o; o.x = pk2(s[0 * 33], s[1 * 33]); o.y = pk2(s[2 * 33], s[3 * 33]); o.z = pk2(s[4 * 33], s[5 * 33]); o.w = pk2(s[6 * 33], s[7 * 33]);
;             *(u32x4*)(dst + (size_t)n * K + k0 + 8 * c) = o; }
;         asm volatile("s_waitcnt lgkmcnt(0)" ::: "memory");
;     }
.LBB0_192:
	s_mulk_i32 s40, 0xff50
	s_add_i32 s12, s38, s40
	s_cmpk_gt_i32 s12, 0x57
	s_cselect_b32 s12, 0xfffff500, 0
	s_cselect_b32 s13, 0x80, 0
	s_add_i32 s12, s12, s35
	s_add_i32 s12, s12, s39
	s_lshl_b32 s12, s12, 1
	s_and_b32 s14, s14, 0x60
	s_and_b32 s12, s12, 0xffffff00
	s_or_b32 s13, s13, s14
	v_add_u32_e32 v5, 0x400, v9
	s_or_b32 s12, s13, s12
	ds_write2_b32 v5, v20, v21 offset0:8 offset1:74
	s_ashr_i32 s13, s12, 31
	s_waitcnt lgkmcnt(0)
	s_lshl_b64 s[12:13], s[12:13], 11
	s_add_u32 s12, s33, s12
	ds_read_b32 v5, v44
	ds_read_b32 v7, v44 offset:132
	ds_read_b32 v9, v44 offset:264
	ds_read_b32 v11, v44 offset:396
	ds_read_b32 v13, v44 offset:528
	ds_read_b32 v20, v44 offset:660
	ds_read_b32 v21, v44 offset:792
	ds_read_b32 v24, v44 offset:924
	s_addc_u32 s13, s34, s13
	s_lshl_b64 s[4:5], s[4:5], 1
	s_add_u32 s4, s12, s4
	s_addc_u32 s5, s13, s5
	v_lshl_add_u64 v[22:23], s[4:5], 0, v[2:3]
	s_waitcnt lgkmcnt(0)
	v_cvt_pk_bf16_f32 v18, v5, v7
	v_mov_b32_e32 v7, v3
	v_cvt_pk_bf16_f32 v19, v9, v11
	v_cvt_pk_bf16_f32 v20, v13, v20
	v_cvt_pk_bf16_f32 v21, v21, v24
	v_lshl_add_u64 v[24:25], v[22:23], 0, v[6:7]
	global_store_dwordx4 v[24:25], v[18:21], off
	ds_read_b32 v5, v44 offset:32
	ds_read_b32 v7, v44 offset:164
	ds_read_b32 v9, v44 offset:296
	ds_read_b32 v11, v44 offset:428
	ds_read_b32 v13, v44 offset:560
	ds_read_b32 v20, v44 offset:692
	ds_read_b32 v21, v44 offset:824
	ds_read_b32 v24, v44 offset:956
	s_waitcnt lgkmcnt(0)
	v_cvt_pk_bf16_f32 v19, v9, v11
	v_mov_b32_e32 v9, v3
	v_cvt_pk_bf16_f32 v18, v5, v7
	v_cvt_pk_bf16_f32 v20, v13, v20
	v_cvt_pk_bf16_f32 v21, v21, v24
	v_lshl_add_u64 v[24:25], v[22:23], 0, v[8:9]
	global_store_dwordx4 v[24:25], v[18:21], off
	ds_read_b32 v5, v44 offset:64
	ds_read_b32 v7, v44 offset:196
	ds_read_b32 v9, v44 offset:328
	ds_read_b32 v11, v44 offset:460
	ds_read_b32 v13, v44 offset:592
	ds_read_b32 v20, v44 offset:724
	ds_read_b32 v21, v44 offset:856
	ds_read_b32 v24, v44 offset:988
	s_waitcnt lgkmcnt(0)
	v_cvt_pk_bf16_f32 v19, v9, v11
	v_mov_b32_e32 v11, v3
	v_cvt_pk_bf16_f32 v18, v5, v7
	v_cvt_pk_bf16_f32 v20, v13, v20
	v_cvt_pk_bf16_f32 v21, v21, v24
	v_lshl_add_u64 v[24:25], v[22:23], 0, v[10:11]
	global_store_dwordx4 v[24:25], v[18:21], off
	ds_read_b32 v5, v44 offset:96
	ds_read_b32 v7, v44 offset:228
	ds_read_b32 v9, v44 offset:360
	ds_read_b32 v11, v44 offset:492
	ds_read_b32 v13, v44 offset:624
	ds_read_b32 v20, v44 offset:756
	ds_read_b32 v21, v44 offset:888
	ds_read_b32 v24, v44 offset:1020
	s_waitcnt lgkmcnt(0)
	v_cvt_pk_bf16_f32 v18, v5, v7
	v_cvt_pk_bf16_f32 v19, v9, v11
	v_cvt_pk_bf16_f32 v20, v13, v20
	v_mov_b32_e32 v13, v3
	v_cvt_pk_bf16_f32 v21, v21, v24
	v_lshl_add_u64 v[22:23], v[22:23], 0, v[12:13]
	global_store_dwordx4 v[22:23], v[18:21], off
	s_waitcnt lgkmcnt(0)
	s_add_i32 s38, s38, s88
	s_add_i32 s35, s35, s36
	s_cmpk_lt_i32 s38, 0xb00
	s_cbranch_scc0 .LBB0_225

;     ...
;     for (int item = gw; item < nitems; item += ngw) {
;         const int kb = item / nblk, nb = nb0 + item % nblk, k0 = 64 * kb, n0 = 32 * nb;
;         float tv[32];
; #pragma unroll
;         for (int i = 0; i < 32; ++i) { const int kk = 2 * i + (lane >> 5); tv[i] = W[(size_t)(k0 + kk) * N + n0 + (lane & 31)]; }
.LBB0_227:
	s_ashr_i32 s2, s33, 31
	s_lshr_b32 s2, s2, 27
	s_add_i32 s2, s33, s2
	s_ashr_i32 s3, s2, 5
	s_lshl_b32 s2, s3, 6
	s_lshl_b32 s3, s3, 10
	v_or_b32_e32 v12, s2, v0
	s_sub_i32 s4, s12, s3
	v_or_b32_e32 v16, 2, v12
	v_or_b32_e32 v18, 4, v12
	v_or_b32_e32 v24, 10, v12
	v_or_b32_e32 v26, 12, v12
	v_or_b32_e32 v28, 14, v12
	v_or_b32_e32 v30, 16, v12
	v_or_b32_e32 v32, 18, v12
	v_or_b32_e32 v34, 20, v12
	v_or_b32_e32 v36, 22, v12
	v_or_b32_e32 v38, 24, v12
	v_or_b32_e32 v40, 26, v12
	v_or_b32_e32 v42, 28, v12
	v_or_b32_e32 v46, 30, v12
	v_or_b32_e32 v48, 32, v12
	v_or_b32_e32 v50, 34, v12
	v_or_b32_e32 v52, 36, v12
	s_ashr_i32 s5, s4, 31
	v_ashrrev_i32_e32 v13, 31, v12
	v_or_b32_e32 v20, 6, v12
	v_or_b32_e32 v22, 8, v12
	v_or_b32_e32 v54, 38, v12
	v_or_b32_e32 v56, 40, v12
	v_or_b32_e32 v58, 42, v12
	v_or_b32_e32 v60, 44, v12
	v_or_b32_e32 v62, 46, v12
	v_or_b32_e32 v64, 48, v12
	v_or_b32_e32 v66, 50, v12
	v_or_b32_e32 v68, 52, v12
	v_or_b32_e32 v70, 54, v12
	v_or_b32_e32 v72, 56, v12
	v_or_b32_e32 v74, 58, v12
	v_or_b32_e32 v76, 60, v12
	v_or_b32_e32 v78, 62, v12
	v_ashrrev_i32_e32 v17, 31, v16
	v_ashrrev_i32_e32 v19, 31, v18
	v_ashrrev_i32_e32 v25, 31, v24
	v_ashrrev_i32_e32 v27, 31, v26
	v_ashrrev_i32_e32 v29, 31, v28
	v_ashrrev_i32_e32 v31, 31, v30
	v_ashrrev_i32_e32 v33, 31, v32
	v_ashrrev_i32_e32 v35, 31, v34
	v_ashrrev_i32_e32 v37, 31, v36
	v_ashrrev_i32_e32 v39, 31, v38
	v_ashrrev_i32_e32 v41, 31, v40
	v_ashrrev_i32_e32 v43, 31, v42
	v_ashrrev_i32_e32 v47, 31, v46
	v_ashrrev_i32_e32 v49, 31, v48
	v_ashrrev_i32_e32 v51, 31, v50
	v_ashrrev_i32_e32 v53, 31, v52
	v_lshl_add_u64 v[80:81], s[4:5], 2, v[6:7]
	v_lshlrev_b64 v[12:13], 12, v[12:13]
	v_ashrrev_i32_e32 v21, 31, v20
	v_ashrrev_i32_e32 v23, 31, v22
	v_ashrrev_i32_e32 v55, 31, v54
	v_ashrrev_i32_e32 v57, 31, v56
	v_ashrrev_i32_e32 v59, 31, v58
	v_ashrrev_i32_e32 v61, 31, v60
	v_ashrrev_i32_e32 v63, 31, v62
	v_ashrrev_i32_e32 v65, 31, v64
	v_ashrrev_i32_e32 v67, 31, v66
	v_ashrrev_i32_e32 v69, 31, v68
	v_ashrrev_i32_e32 v71, 31, v70
	v_ashrrev_i32_e32 v73, 31, v72
	v_ashrrev_i32_e32 v75, 31, v74
	v_ashrrev_i32_e32 v77, 31, v76
	v_ashrrev_i32_e32 v79, 31, v78
	v_lshlrev_b64 v[16:17], 12, v[16:17]
	v_lshlrev_b64 v[18:19], 12, v[18:19]
	v_lshlrev_b64 v[24:25], 12, v[24:25]
	v_lshlrev_b64 v[26:27], 12, v[26:27]
	v_lshlrev_b64 v[28:29], 12, v[28:29]
	v_lshlrev_b64 v[30:31], 12, v[30:31]
	v_lshlrev_b64 v[32:33], 12, v[32:33]
	v_lshlrev_b64 v[34:35], 12, v[34:35]
	v_lshlrev_b64 v[36:37], 12, v[36:37]
	v_lshlrev_b64 v[38:39], 12, v[38:39]
	v_lshlrev_b64 v[40:41], 12, v[40:41]
	v_lshlrev_b64 v[42:43], 12, v[42:43]
	v_lshlrev_b64 v[46:47], 12, v[46:47]
	v_lshlrev_b64 v[48:49], 12, v[48:49]
	v_lshlrev_b64 v[50:51], 12, v[50:51]
	v_lshlrev_b64 v[52:53], 12, v[52:53]
	v_lshl_add_u64 v[12:13], v[80:81], 0, v[12:13]
	v_lshlrev_b64 v[20:21], 12, v[20:21]
	v_lshlrev_b64 v[22:23], 12, v[22:23]
	v_lshlrev_b64 v[54:55], 12, v[54:55]
	v_lshlrev_b64 v[56:57], 12, v[56:57]
	v_lshlrev_b64 v[58:59], 12, v[58:59]
	v_lshlrev_b64 v[60:61], 12, v[60:61]
	v_lshlrev_b64 v[62:63], 12, v[62:63]
	v_lshlrev_b64 v[64:65], 12, v[64:65]
	v_lshlrev_b64 v[66:67], 12, v[66:67]
	v_lshlrev_b64 v[68:69], 12, v[68:69]
	v_lshlrev_b64 v[70:71], 12, v[70:71]
	v_lshlrev_b64 v[72:73], 12, v[72:73]
	v_lshlrev_b64 v[74:75], 12, v[74:75]
	v_lshlrev_b64 v[76:77], 12, v[76:77]
	v_lshlrev_b64 v[78:79], 12, v[78:79]
	v_lshl_add_u64 v[16:17], v[80:81], 0, v[16:17]
	v_lshl_add_u64 v[18:19], v[80:81], 0, v[18:19]
	v_lshl_add_u64 v[24:25], v[80:81], 0, v[24:25]
	v_lshl_add_u64 v[26:27], v[80:81], 0, v[26:27]
	v_lshl_add_u64 v[28:29], v[80:81], 0, v[28:29]
	v_lshl_add_u64 v[30:31], v[80:81], 0, v[30:31]
	v_lshl_add_u64 v[32:33], v[80:81], 0, v[32:33]
	v_lshl_add_u64 v[34:35], v[80:81], 0, v[34:35]
	v_lshl_add_u64 v[36:37], v[80:81], 0, v[36:37]
	v_lshl_add_u64 v[38:39], v[80:81], 0, v[38:39]
	v_lshl_add_u64 v[40:41], v[80:81], 0, v[40:41]
	v_lshl_add_u64 v[42:43], v[80:81], 0, v[42:43]
	v_lshl_add_u64 v[46:47], v[80:81], 0, v[46:47]
	v_lshl_add_u64 v[48:49], v[80:81], 0, v[48:49]
	v_lshl_add_u64 v[50:51], v[80:81], 0, v[50:51]
	v_lshl_add_u64 v[52:53], v[80:81], 0, v[52:53]
	v_lshl_add_u64 v[20:21], v[80:81], 0, v[20:21]
	v_lshl_add_u64 v[22:23], v[80:81], 0, v[22:23]
	v_lshl_add_u64 v[54:55], v[80:81], 0, v[54:55]
	v_lshl_add_u64 v[56:57], v[80:81], 0, v[56:57]
	v_lshl_add_u64 v[58:59], v[80:81], 0, v[58:59]
	v_lshl_add_u64 v[60:61], v[80:81], 0, v[60:61]
	v_lshl_add_u64 v[62:63], v[80:81], 0, v[62:63]
	v_lshl_add_u64 v[64:65], v[80:81], 0, v[64:65]
	v_lshl_add_u64 v[66:67], v[80:81], 0, v[66:67]
	v_lshl_add_u64 v[68:69], v[80:81], 0, v[68:69]
	v_lshl_add_u64 v[70:71], v[80:81], 0, v[70:71]
	v_lshl_add_u64 v[72:73], v[80:81], 0, v[72:73]
	v_lshl_add_u64 v[74:75], v[80:81], 0, v[74:75]
	v_lshl_add_u64 v[76:77], v[80:81], 0, v[76:77]
	v_lshl_add_u64 v[78:79], v[80:81], 0, v[78:79]
	global_load_dword v80, v[12:13], off
	s_nop 0
	global_load_dword v16, v[16:17], off
	s_nop 0
	global_load_dword v17, v[18:19], off
	s_nop 0
	global_load_dword v18, v[20:21], off
	global_load_dword v19, v[22:23], off
	s_nop 0
	global_load_dword v25, v[24:25], off
	s_nop 0
	global_load_dword v26, v[26:27], off
	s_nop 0
	global_load_dword v27, v[28:29], off
	s_nop 0
	global_load_dword v28, v[30:31], off
	global_load_dword v29, v[32:33], off
	s_nop 0
	global_load_dword v30, v[34:35], off
	global_load_dword v31, v[36:37], off
	global_load_dword v32, v[38:39], off
	global_load_dword v33, v[40:41], off
	s_nop 0
	global_load_dword v34, v[42:43], off
	global_load_dword v35, v[46:47], off
	global_load_dword v36, v[48:49], off
	global_load_dword v37, v[50:51], off
	global_load_dword v38, v[52:53], off
	global_load_dword v39, v[54:55], off
	global_load_dword v40, v[56:57], off
	global_load_dword v41, v[58:59], off
	global_load_dword v42, v[60:61], off
	global_load_dword v43, v[62:63], off
	global_load_dword v46, v[64:65], off
	global_load_dword v47, v[66:67], off
	global_load_dword v48, v[68:69], off
	global_load_dword v49, v[70:71], off
	global_load_dword v50, v[72:73], off
	global_load_dword v51, v[74:75], off
	global_load_dword v52, v[76:77], off
	global_load_dword v53, v[78:79], off
	s_mul_hi_i32 s3, s4, 0x1600
	s_mulk_i32 s4, 0x1600
	s_add_u32 s4, s6, s4
	s_addc_u32 s5, s7, s3
	s_ashr_i32 s3, s2, 31
	s_lshl_b64 s[2:3], s[2:3], 1
	s_waitcnt vmcnt(0)
; #define LAS __attribute__((address_space(3)))
; DI unsigned pk2(float lo, float hi) { typedef float v2f __attribute__((ext_vector_type(2))); typedef __bf16 v2b __attribute__((ext_vector_type(2))); v2f v = {lo, hi}; v2b b = __builtin_convertvector(v, v2b); return __builtin_bit_cast(unsigned, b); }
;     ...
;         for (int i = 0; i < 32; ++i) { const int kk = 2 * i + (lane >> 5); float v = tv[i]; if (gk) v *= gk[k0 + kk]; scr[kk * 33 + (lane & 31)] = v; }
;         asm volatile("s_waitcnt lgkmcnt(0)" ::: "memory");
;         bf16_t* dst = dest_rows(mode, n0, K, d0, d1);
;         const int c = lane & 7;
; #pragma unroll
;         for (int jj = 0; jj < 4; ++jj) { const int n = (lane >> 3) + 8 * jj; const LAS float* s = scr + (8 * c) * 33 + n;
;             u32x4 o; o.x = pk2(s[0 * 33], s[1 * 33]); o.y = pk2(s[2 * 33], s[3 * 33]); o.z = pk2(s[4 * 33], s[5 * 33]); o.w = pk2(s[6 * 33], s[7 * 33]);
;             *(u32x4*)(dst + (size_t)n * K + k0 + 8 * c) = o; }
;         asm volatile("s_waitcnt lgkmcnt(0)" ::: "memory");
;     }
	ds_write2_b32 v45, v80, v16 offset1:66
	ds_write2_b32 v45, v17, v18 offset0:132 offset1:198
	ds_write2_b32 v1, v19, v25 offset0:8 offset1:74
	ds_write2_b32 v1, v26, v27 offset0:140 offset1:206
	ds_write2_b32 v4, v28, v29 offset0:16 offset1:82
	ds_write2_b32 v4, v30, v31 offset0:148 offset1:214
	ds_write2_b32 v5, v32, v33 offset0:24 offset1:90
	ds_write2_b32 v5, v34, v35 offset0:156 offset1:222
	ds_write2_b32 v8, v36, v37 offset0:32 offset1:98
	ds_write2_b32 v8, v38, v39 offset0:164 offset1:230
	ds_write2_b32 v9, v40, v41 offset0:40 offset1:106
	ds_write2_b32 v9, v42, v43 offset0:172 offset1:238
	ds_write2_b32 v10, v46, v47 offset0:48 offset1:114
	ds_write2_b32 v10, v48, v49 offset0:180 offset1:246
	ds_write2_b32 v11, v50, v51 offset0:56 offset1:122
	ds_write2_b32 v11, v52, v53 offset0:188 offset1:254
	s_add_u32 s2, s4, s2
	s_waitcnt lgkmcnt(0)
	s_addc_u32 s3, s5, s3
	ds_read_b32 v16, v44
	ds_read_b32 v17, v44 offset:132
	ds_read_b32 v18, v44 offset:264
	ds_read_b32 v19, v44 offset:396
	ds_read_b32 v25, v44 offset:528
	ds_read_b32 v26, v44 offset:660
	ds_read_b32 v27, v44 offset:792
	ds_read_b32 v28, v44 offset:924
	v_lshl_add_u64 v[12:13], s[2:3], 0, v[2:3]
	v_lshl_add_u64 v[12:13], v[12:13], 0, v[14:15]
	v_add_co_u32_e32 v20, vcc, s14, v12
	s_waitcnt lgkmcnt(0)
	v_cvt_pk_bf16_f32 v16, v16, v17
	v_addc_co_u32_e32 v21, vcc, 0, v13, vcc
	v_add_co_u32_e32 v22, vcc, s15, v12
	v_cvt_pk_bf16_f32 v17, v18, v19
	v_cvt_pk_bf16_f32 v18, v25, v26
	v_cvt_pk_bf16_f32 v19, v27, v28
	v_addc_co_u32_e32 v23, vcc, 0, v13, vcc
	global_store_dwordx4 v[12:13], v[16:19], off
	v_add_co_u32_e32 v24, vcc, 0x21000, v12
	ds_read_b32 v12, v44 offset:32
	ds_read_b32 v16, v44 offset:164
	ds_read_b32 v17, v44 offset:296
	ds_read_b32 v18, v44 offset:428
	ds_read_b32 v19, v44 offset:560
	ds_read_b32 v25, v44 offset:692
	ds_read_b32 v26, v44 offset:824
	ds_read_b32 v27, v44 offset:956
	s_waitcnt lgkmcnt(0)
	v_cvt_pk_bf16_f32 v16, v12, v16
	v_cvt_pk_bf16_f32 v17, v17, v18
	v_cvt_pk_bf16_f32 v18, v19, v25
	s_add_i32 s33, s33, s88
	v_cvt_pk_bf16_f32 v19, v26, v27
	global_store_dwordx4 v[20:21], v[16:19], off
	ds_read_b32 v12, v44 offset:64
	ds_read_b32 v16, v44 offset:196
	ds_read_b32 v17, v44 offset:328
	ds_read_b32 v18, v44 offset:460
	ds_read_b32 v19, v44 offset:592
	ds_read_b32 v20, v44 offset:724
	ds_read_b32 v21, v44 offset:856
	ds_read_b32 v25, v44 offset:988
	s_waitcnt lgkmcnt(0)
	v_cvt_pk_bf16_f32 v16, v12, v16
	v_cvt_pk_bf16_f32 v17, v17, v18
	v_cvt_pk_bf16_f32 v18, v19, v20
	s_add_i32 s12, s12, s13
	v_cvt_pk_bf16_f32 v19, v21, v25
	global_store_dwordx4 v[22:23], v[16:19], off
	ds_read_b32 v12, v44 offset:96
	ds_read_b32 v16, v44 offset:228
	ds_read_b32 v17, v44 offset:360
	ds_read_b32 v18, v44 offset:492
	ds_read_b32 v19, v44 offset:624
	ds_read_b32 v20, v44 offset:756
	ds_read_b32 v21, v44 offset:888
	ds_read_b32 v22, v44 offset:1020
	v_addc_co_u32_e32 v25, vcc, 0, v13, vcc
	s_waitcnt lgkmcnt(0)
	v_cvt_pk_bf16_f32 v16, v12, v16
	v_cvt_pk_bf16_f32 v17, v17, v18
	v_cvt_pk_bf16_f32 v18, v19, v20
	v_cvt_pk_bf16_f32 v19, v21, v22
	global_store_dwordx4 v[24:25], v[16:19], off
	s_waitcnt lgkmcnt(0)
	s_cmpk_lt_i32 s33, 0x580
	s_cbranch_scc1 .LBB0_227

; __global__ void __launch_bounds__(512, 2) fwd_mega(Args args) {
;     ...
;         for (int i = gt; i < 96 * 1024 / 8; i += ngt) ((u32x4*)(wIN + (size_t)2208 * 1024))[i] = (u32x4){0u, 0u, 0u, 0u};
.LBB0_230:
	v_add_u32_e32 v6, s72, v6
	v_cmp_lt_i32_e32 vcc, s12, v6
	global_store_dwordx4 v[4:5], v[0:3], off
	s_or_b64 s[6:7], vcc, s[6:7]
	v_lshl_add_u64 v[4:5], v[4:5], 0, s[4:5]
	s_andn2_b64 exec, exec, s[6:7]
	s_cbranch_execnz .LBB0_230

; __global__ void __launch_bounds__(512, 2) fwd_mega(Args args) {
;     ...
;         for (int i = gt; i < T; i += ngt) { SS1[i] = 0.f; SS2[i] = 0.f; CQP[i] = 0.f; CKVP[i] = 0.f; }
.LBB0_233:
	v_add_co_u32_e32 v4, vcc, 0xffb00000, v0
	v_add_u32_e32 v3, s72, v3
	s_nop 0
	v_addc_co_u32_e32 v5, vcc, -1, v1, vcc
	global_store_dword v[4:5], v2, off
	v_add_co_u32_e32 v4, vcc, 0xffc00000, v0
	s_nop 1
	v_addc_co_u32_e32 v5, vcc, -1, v1, vcc
	global_store_dword v[4:5], v2, off
	v_add_co_u32_e32 v4, vcc, 0xfff00000, v0
	s_nop 1
	v_addc_co_u32_e32 v5, vcc, -1, v1, vcc
	v_cmp_lt_i32_e32 vcc, s12, v3
	global_store_dword v[4:5], v2, off
	global_store_dword v[0:1], v2, off
	s_or_b64 s[6:7], vcc, s[6:7]
	v_lshl_add_u64 v[0:1], v[0:1], 0, s[4:5]
	s_andn2_b64 exec, exec, s[6:7]
	s_cbranch_execnz .LBB0_233

; DI unsigned pk2(float lo, float hi) { typedef float v2f __attribute__((ext_vector_type(2))); typedef __bf16 v2b __attribute__((ext_vector_type(2))); v2f v = {lo, hi}; v2b b = __builtin_convertvector(v, v2b); return __builtin_bit_cast(unsigned, b); }
; __global__ void __launch_bounds__(512, 2) fwd_mega(Args args) {
;     ...
;             const float q0_ = sqrtf(wave_sum(s0) * (1.0f / 1024.0f) + EPS), q1_ = sqrtf(wave_sum(s1) * (1.0f / 1024.0f) + EPS), r0 = 1.0f / q0_, r1 = 1.0f / q1_;
;             if (lane == 0) { ((float*)(ws + S_R0))[m] = q0_; ((float*)(ws + S_R0))[m + 1] = q1_; }
;             u32x2* o0 = (u32x2*)(XB + (size_t)m * DM) + lane; u32x2* o1 = o0 + DM / 4;
; #pragma unroll
;             for (int jj = 0; jj < 4; ++jj) { u32x2 w0, w1; w0.x = pk2(v0[jj][0] * r0, v0[jj][1] * r0); w0.y = pk2(v0[jj][2] * r0, v0[jj][3] * r0); w1.x = pk2(v1[jj][0] * r1, v1[jj][1] * r1); w1.y = pk2(v1[jj][2] * r1, v1[jj][3] * r1);
;                 o0[64 * jj] = w0; o1[64 * jj] = w1; }
.LBB0_236:
	s_or_b64 exec, exec, s[4:5]
	v_div_scale_f32 v47, s[4:5], v38, v38, 1.0
	v_rcp_f32_e32 v48, v47
	v_div_scale_f32 v49, vcc, 1.0, v38, 1.0
	s_add_i32 s14, s14, s34
	v_fma_f32 v50, -v47, v48, 1.0
	v_fmac_f32_e32 v48, v50, v48
	v_mul_f32_e32 v50, v49, v48
	v_fma_f32 v51, -v47, v50, v49
	v_fmac_f32_e32 v50, v51, v48
	v_fma_f32 v47, -v47, v50, v49
	v_div_scale_f32 v49, s[4:5], v39, v39, 1.0
	v_rcp_f32_e32 v51, v49
	v_div_fmas_f32 v47, v47, v48, v50
	v_div_fixup_f32 v38, v47, v38, 1.0
	v_pk_mul_f32 v[28:29], v[38:39], v[28:29] op_sel_hi:[0,1]
	v_fma_f32 v47, -v49, v51, 1.0
	v_fmac_f32_e32 v51, v47, v51
	v_div_scale_f32 v47, vcc, 1.0, v39, 1.0
	v_mul_f32_e32 v48, v47, v51
	v_fma_f32 v50, -v49, v48, v47
	v_fmac_f32_e32 v48, v50, v51
	v_fma_f32 v47, -v49, v48, v47
	v_div_fmas_f32 v47, v47, v51, v48
	v_div_fixup_f32 v48, v47, v39, 1.0
	v_lshl_add_u64 v[50:51], s[8:9], 0, v[34:35]
	v_pk_mul_f32 v[24:25], v[48:49], v[24:25] op_sel_hi:[0,1]
	v_pk_mul_f32 v[26:27], v[48:49], v[26:27] op_sel_hi:[0,1]
	v_pk_mul_f32 v[30:31], v[38:39], v[30:31] op_sel_hi:[0,1]
	v_cvt_pk_bf16_f32 v24, v24, v25
	v_cvt_pk_bf16_f32 v25, v26, v27
	v_add_co_u32_e32 v26, vcc, s13, v50
	v_pk_mul_f32 v[20:21], v[38:39], v[20:21] op_sel_hi:[0,1]
	v_pk_mul_f32 v[22:23], v[38:39], v[22:23] op_sel_hi:[0,1]
	v_pk_mul_f32 v[12:13], v[48:49], v[12:13] op_sel_hi:[0,1]
	v_pk_mul_f32 v[14:15], v[48:49], v[14:15] op_sel_hi:[0,1]
	v_cvt_pk_bf16_f32 v28, v28, v29
	v_cvt_pk_bf16_f32 v29, v30, v31
	v_addc_co_u32_e32 v27, vcc, 0, v51, vcc
	v_cvt_pk_bf16_f32 v20, v20, v21
	v_cvt_pk_bf16_f32 v21, v22, v23
	v_cvt_pk_bf16_f32 v12, v12, v13
	v_cvt_pk_bf16_f32 v13, v14, v15
	global_store_dwordx2 v[26:27], v[28:29], off
	global_store_dwordx2 v[26:27], v[24:25], off offset:2048
	global_store_dwordx2 v[26:27], v[20:21], off offset:512
	global_store_dwordx2 v[26:27], v[12:13], off offset:2560
	v_pk_mul_f32 v[12:13], v[38:39], v[16:17] op_sel_hi:[0,1]
	v_pk_mul_f32 v[14:15], v[38:39], v[18:19] op_sel_hi:[0,1]
	v_pk_mul_f32 v[4:5], v[48:49], v[4:5] op_sel_hi:[0,1]
	v_pk_mul_f32 v[6:7], v[48:49], v[6:7] op_sel_hi:[0,1]
	v_cvt_pk_bf16_f32 v12, v12, v13
	v_cvt_pk_bf16_f32 v13, v14, v15
	v_cvt_pk_bf16_f32 v4, v4, v5
	v_cvt_pk_bf16_f32 v5, v6, v7
	s_add_u32 s74, s74, s76
	global_store_dwordx2 v[26:27], v[12:13], off offset:1024
	global_store_dwordx2 v[26:27], v[4:5], off offset:3072
	v_pk_mul_f32 v[4:5], v[38:39], v[8:9] op_sel_hi:[0,1]
	v_pk_mul_f32 v[6:7], v[38:39], v[10:11] op_sel_hi:[0,1]
	s_addc_u32 s75, s75, s77
	v_cvt_pk_bf16_f32 v4, v4, v5
	v_cvt_pk_bf16_f32 v5, v6, v7
	v_pk_mul_f32 v[0:1], v[48:49], v[0:1] op_sel_hi:[0,1]
	v_pk_mul_f32 v[2:3], v[48:49], v[2:3] op_sel_hi:[0,1]
	v_lshl_add_u64 v[34:35], v[34:35], 0, s[60:61]
	s_cmpk_gt_i32 s14, 0x3fff
	v_lshl_add_u64 v[36:37], v[36:37], 0, s[68:69]
	v_cvt_pk_bf16_f32 v0, v0, v1
	v_cvt_pk_bf16_f32 v1, v2, v3
	global_store_dwordx2 v[26:27], v[4:5], off offset:1536
	global_store_dwordx2 v[26:27], v[0:1], off offset:3584
	s_cbranch_scc1 .LBB0_239
; __global__ void __launch_bounds__(512, 2) fwd_mega(Args args) {
;     ...
;             const f32x4* x0 = (const f32x4*)(x + (size_t)m * DM) + lane; const f32x4* x1 = x0 + DM / 4;
;             f32x4 v0[4], v1[4]; float s0 = 0.f, s1 = 0.f;
; #pragma unroll
;             for (int jj = 0; jj < 4; ++jj) { v0[jj] = x0[64 * jj]; v1[jj] = x1[64 * jj]; }
; #pragma unroll
;             for (int jj = 0; jj < 4; ++jj) { s0 += (v0[jj][0] * v0[jj][0] + v0[jj][1] * v0[jj][1]) + (v0[jj][2] * v0[jj][2] + v0[jj][3] * v0[jj][3]);
;                                              s1 += (v1[jj][0] * v1[jj][0] + v1[jj][1] * v1[jj][1]) + (v1[jj][2] * v1[jj][2] + v1[jj][3] * v1[jj][3]); }
;             const float q0_ = sqrtf(wave_sum(s0) * (1.0f / 1024.0f) + EPS), q1_ = sqrtf(wave_sum(s1) * (1.0f / 1024.0f) + EPS), r0 = 1.0f / q0_, r1 = 1.0f / q1_;
;             if (lane == 0) { ((float*)(ws + S_R0))[m] = q0_; ((float*)(ws + S_R0))[m + 1] = q1_; }
.LBB0_237:
	global_load_dwordx4 v[24:27], v[36:37], off offset:-3072
	global_load_dwordx4 v[12:15], v[36:37], off offset:-2048
	global_load_dwordx4 v[4:7], v[36:37], off offset:-1024
	global_load_dwordx4 v[0:3], v[36:37], off
	v_add_co_u32_e32 v8, vcc, 0xfffff000, v36
	s_waitcnt vmcnt(0)
	v_mul_f32_e32 v38, v25, v25
	v_addc_co_u32_e32 v9, vcc, -1, v37, vcc
	global_load_dwordx4 v[28:31], v[8:9], off offset:-3072
	global_load_dwordx4 v[20:23], v[8:9], off offset:-2048
	global_load_dwordx4 v[16:19], v[8:9], off offset:-1024
	s_nop 0
	global_load_dwordx4 v[8:11], v[36:37], off offset:-4096
	v_mul_f32_e32 v39, v27, v27
	v_mul_f32_e32 v47, v13, v13
	v_mul_f32_e32 v48, v15, v15
	v_mul_f32_e32 v49, v5, v5
	v_mul_f32_e32 v50, v7, v7
	v_fmac_f32_e32 v38, v24, v24
	v_fmac_f32_e32 v39, v26, v26
	v_fmac_f32_e32 v47, v12, v12
	v_fmac_f32_e32 v48, v14, v14
	v_mul_f32_e32 v51, v1, v1
	v_mul_f32_e32 v52, v3, v3
	v_fmac_f32_e32 v49, v4, v4
	v_fmac_f32_e32 v50, v6, v6
	v_add_f32_e32 v38, v38, v39
	v_add_f32_e32 v47, v47, v48
	v_fmac_f32_e32 v51, v0, v0
	v_fmac_f32_e32 v52, v2, v2
	v_add_f32_e32 v49, v49, v50
	v_add_f32_e32 v38, v38, v47
	v_add_f32_e32 v51, v51, v52
	v_add_f32_e32 v38, v38, v49
	v_add_f32_e32 v38, v38, v51
	s_waitcnt vmcnt(0)
	v_mul_f32_e32 v53, v29, v29
	v_mul_f32_e32 v54, v31, v31
	v_mul_f32_e32 v39, v21, v21
	v_mul_f32_e32 v55, v23, v23
	v_mul_f32_e32 v48, v17, v17
	v_mul_f32_e32 v56, v19, v19
	v_fmac_f32_e32 v53, v28, v28
	v_fmac_f32_e32 v54, v30, v30
	v_fmac_f32_e32 v39, v20, v20
	v_fmac_f32_e32 v55, v22, v22
	v_mul_f32_e32 v50, v9, v9
	v_mul_f32_e32 v57, v11, v11
	v_fmac_f32_e32 v48, v16, v16
	v_fmac_f32_e32 v56, v18, v18
	v_add_f32_e32 v47, v53, v54
	v_add_f32_e32 v39, v39, v55
	v_fmac_f32_e32 v50, v8, v8
	v_fmac_f32_e32 v57, v10, v10
	v_add_f32_e32 v48, v48, v56
	v_add_f32_e32 v39, v47, v39
	v_add_f32_e32 v49, v50, v57
	v_add_f32_e32 v39, v39, v48
	ds_bpermute_b32 v47, v40, v38
	v_add_f32_e32 v39, v39, v49
	ds_bpermute_b32 v48, v40, v39
	s_waitcnt lgkmcnt(0)
	v_add_f32_e32 v38, v38, v47
	ds_bpermute_b32 v47, v41, v38
	v_add_f32_e32 v39, v39, v48
	ds_bpermute_b32 v48, v41, v39
	s_waitcnt lgkmcnt(1)
	v_add_f32_e32 v38, v38, v47
	ds_bpermute_b32 v47, v42, v38
	s_waitcnt lgkmcnt(1)
	v_add_f32_e32 v39, v39, v48
	ds_bpermute_b32 v48, v42, v39
	s_waitcnt lgkmcnt(1)
	v_add_f32_e32 v38, v38, v47
	ds_bpermute_b32 v47, v43, v38
	s_waitcnt lgkmcnt(1)
	v_add_f32_e32 v39, v39, v48
	ds_bpermute_b32 v48, v43, v39
	s_waitcnt lgkmcnt(1)
	v_add_f32_e32 v38, v38, v47
	ds_bpermute_b32 v47, v44, v38
	s_waitcnt lgkmcnt(1)
	v_add_f32_e32 v39, v39, v48
	ds_bpermute_b32 v48, v44, v39
	s_waitcnt lgkmcnt(1)
	v_add_f32_e32 v38, v38, v47
	ds_bpermute_b32 v47, v45, v38
	s_waitcnt lgkmcnt(1)
	v_add_f32_e32 v39, v39, v48
	ds_bpermute_b32 v48, v45, v39
	s_waitcnt lgkmcnt(1)
	v_add_f32_e32 v38, v38, v47
	v_fmamk_f32 v38, v38, 0x3a800000, v33
	s_waitcnt lgkmcnt(0)
	v_add_f32_e32 v39, v39, v48
	v_mul_f32_e32 v47, 0x4f800000, v38
	v_cmp_gt_f32_e32 vcc, s12, v38
	v_fmamk_f32 v39, v39, 0x3a800000, v33
	v_cmp_gt_f32_e64 s[4:5], s12, v39
	v_cndmask_b32_e32 v47, v38, v47, vcc
	v_mul_f32_e32 v38, 0x4f800000, v39
	v_sqrt_f32_e32 v48, v47
	v_cndmask_b32_e64 v38, v39, v38, s[4:5]
	v_sqrt_f32_e32 v39, v38
	v_add_u32_e32 v49, -1, v48
	v_add_u32_e32 v50, 1, v48
	v_fma_f32 v51, -v49, v48, v47
	v_fma_f32 v52, -v50, v48, v47
	v_add_u32_e32 v53, -1, v39
	v_cmp_ge_f32_e64 s[6:7], 0, v51
	v_add_u32_e32 v54, 1, v39
	v_fma_f32 v51, -v54, v39, v38
	v_cndmask_b32_e64 v48, v48, v49, s[6:7]
	v_fma_f32 v49, -v53, v39, v38
	v_cmp_lt_f32_e64 s[6:7], 0, v52
	s_nop 1
	v_cndmask_b32_e64 v48, v48, v50, s[6:7]
	v_cmp_ge_f32_e64 s[6:7], 0, v49
	v_mul_f32_e32 v49, 0x37800000, v48
	v_cndmask_b32_e32 v48, v48, v49, vcc
	v_cndmask_b32_e64 v39, v39, v53, s[6:7]
	v_cmp_lt_f32_e64 s[6:7], 0, v51
	v_cmp_class_f32_e32 vcc, v38, v46
	s_nop 0
	v_cndmask_b32_e64 v39, v39, v54, s[6:7]
	v_mul_f32_e32 v49, 0x37800000, v39
	v_cndmask_b32_e64 v39, v39, v49, s[4:5]
	v_cndmask_b32_e32 v38, v39, v38, vcc
	v_cmp_class_f32_e32 vcc, v47, v46
	s_nop 1
	v_cndmask_b32_e32 v39, v48, v47, vcc
	s_and_saveexec_b64 s[4:5], s[2:3]
	s_cbranch_execz .LBB0_236
	s_add_u32 s6, s8, s74
	s_addc_u32 s7, s9, s75
	v_mov_b32_e32 v47, s6
	v_add_co_u32_e32 v48, vcc, 0x3560000, v47
	v_mov_b32_e32 v47, s7
	s_nop 0
	v_addc_co_u32_e32 v49, vcc, 0, v47, vcc
	global_store_dwordx2 v[48:49], v[38:39], off
	s_branch .LBB0_236

; DI unsigned pk2(float lo, float hi) { typedef float v2f __attribute__((ext_vector_type(2))); typedef __bf16 v2b __attribute__((ext_vector_type(2))); v2f v = {lo, hi}; v2b b = __builtin_convertvector(v, v2b); return __builtin_bit_cast(unsigned, b); }
; DI void rms_row_to_bf16(const float* xrow, const float* gain, bf16_t* orow, int lane) {
;     ...
;     for (int jj = 0; jj < 4; ++jj) {
;         f32x4 gg = (f32x4){1.f, 1.f, 1.f, 1.f}; if (gain) gg = ((const f32x4*)gain)[lane + 64 * jj];
;         u32x2 wv; wv.x = pk2(v[jj][0] * rstd * gg[0], v[jj][1] * rstd * gg[1]); wv.y = pk2(v[jj][2] * rstd * gg[2], v[jj][3] * rstd * gg[3]); o8[64 * jj] = wv;
.LBB0_241:
	v_pk_mul_f32 v[0:1], v[0:1], v[28:29]
	v_pk_mul_f32 v[2:3], v[2:3], v[28:29]
	s_waitcnt vmcnt(0)
	v_pk_mul_f32 v[0:1], v[0:1], v[8:9]
	v_pk_mul_f32 v[2:3], v[2:3], v[10:11]
	v_cvt_pk_bf16_f32 v0, v0, v1
	v_cvt_pk_bf16_f32 v1, v2, v3
	s_add_i32 s13, s13, s88
	global_store_dwordx2 v[24:25], v[0:1], off offset:1536
	v_lshl_add_u64 v[24:25], v[24:25], 0, s[6:7]
	s_cmpk_gt_i32 s13, 0x1ff
	v_lshl_add_u64 v[26:27], v[26:27], 0, s[10:11]
	s_cbranch_scc1 .LBB0_250

; DI unsigned pk2(float lo, float hi) { typedef float v2f __attribute__((ext_vector_type(2))); typedef __bf16 v2b __attribute__((ext_vector_type(2))); v2f v = {lo, hi}; v2b b = __builtin_convertvector(v, v2b); return __builtin_bit_cast(unsigned, b); }
; DI void rms_row_to_bf16(const float* xrow, const float* gain, bf16_t* orow, int lane) {
;     ...
;     const float rstd = 1.0f / sqrtf(wave_sum(s) * (1.0f / 1024.0f) + EPS);
;     u32x2* o8 = (u32x2*)orow + lane;
; #pragma unroll
;     for (int jj = 0; jj < 4; ++jj) {
;         f32x4 gg = (f32x4){1.f, 1.f, 1.f, 1.f}; if (gain) gg = ((const f32x4*)gain)[lane + 64 * jj];
;         u32x2 wv; wv.x = pk2(v[jj][0] * rstd * gg[0], v[jj][1] * rstd * gg[1]); wv.y = pk2(v[jj][2] * rstd * gg[2], v[jj][3] * rstd * gg[3]); o8[64 * jj] = wv;
.LBB0_244:
	s_waitcnt lgkmcnt(0)
	v_add_f32_e32 v17, v17, v28
	v_fmamk_f32 v17, v17, 0x3a800000, v32
	v_mul_f32_e32 v28, 0x4f800000, v17
	v_cmp_gt_f32_e32 vcc, s12, v17
	s_nop 1
	v_cndmask_b32_e32 v17, v17, v28, vcc
	v_sqrt_f32_e32 v28, v17
	s_nop 0
	v_add_u32_e32 v29, -1, v28
	v_fma_f32 v39, -v29, v28, v17
	v_add_u32_e32 v38, 1, v28
	v_cmp_ge_f32_e64 s[4:5], 0, v39
	s_nop 1
	v_cndmask_b32_e64 v29, v28, v29, s[4:5]
	v_fma_f32 v28, -v38, v28, v17
	v_cmp_lt_f32_e64 s[4:5], 0, v28
	s_nop 1
	v_cndmask_b32_e64 v28, v29, v38, s[4:5]
	v_mul_f32_e32 v29, 0x37800000, v28
	v_cndmask_b32_e32 v28, v28, v29, vcc
	v_cmp_class_f32_e32 vcc, v17, v33
	s_nop 1
	v_cndmask_b32_e32 v17, v28, v17, vcc
	v_div_scale_f32 v28, s[4:5], v17, v17, 1.0
	v_rcp_f32_e32 v29, v28
	s_nop 0
	v_fma_f32 v38, -v28, v29, 1.0
	v_fmac_f32_e32 v29, v38, v29
	v_div_scale_f32 v38, vcc, 1.0, v17, 1.0
	v_mul_f32_e32 v39, v38, v29
	v_fma_f32 v40, -v28, v39, v38
	v_fmac_f32_e32 v39, v40, v29
	v_fma_f32 v28, -v28, v39, v38
	v_div_fmas_f32 v28, v28, v29, v39
	v_div_fixup_f32 v28, v28, v17, 1.0
	v_pk_mul_f32 v[12:13], v[12:13], v[28:29] op_sel_hi:[1,0]
	v_pk_mul_f32 v[14:15], v[14:15], v[28:29] op_sel_hi:[1,0]
	s_waitcnt vmcnt(0)
	v_pk_mul_f32 v[12:13], v[12:13], v[18:19]
	v_pk_mul_f32 v[14:15], v[14:15], v[20:21]
	v_cvt_pk_bf16_f32 v12, v12, v13
	v_cvt_pk_bf16_f32 v13, v14, v15
	s_and_b64 vcc, exec, s[2:3]
	v_mov_b32_e32 v17, 1.0
	v_mov_b32_e32 v18, 1.0
	v_mov_b32_e32 v19, 1.0
	global_store_dwordx2 v[24:25], v[12:13], off
	s_cbranch_vccnz .LBB0_246
	global_load_dwordx4 v[16:19], v[22:23], off offset:1024
.LBB0_246:
	v_mov_b32_e32 v29, v28
	v_pk_mul_f32 v[8:9], v[8:9], v[28:29]
	v_pk_mul_f32 v[10:11], v[10:11], v[28:29]
	s_waitcnt vmcnt(0)
	v_pk_mul_f32 v[8:9], v[8:9], v[16:17]
	v_pk_mul_f32 v[10:11], v[10:11], v[18:19]
	v_cvt_pk_bf16_f32 v8, v8, v9
	v_cvt_pk_bf16_f32 v9, v10, v11
	global_store_dwordx2 v[24:25], v[8:9], off offset:512
	v_mov_b32_e32 v8, 1.0
	s_and_b64 vcc, exec, s[2:3]
	v_mov_b32_e32 v10, 1.0
	v_mov_b32_e32 v11, 1.0
	v_mov_b32_e32 v12, 1.0
	v_mov_b32_e32 v13, 1.0
	s_cbranch_vccnz .LBB0_248
	global_load_dwordx4 v[10:13], v[22:23], off offset:2048
.LBB0_248:
	v_pk_mul_f32 v[4:5], v[4:5], v[28:29]
	v_pk_mul_f32 v[6:7], v[6:7], v[28:29]
	s_waitcnt vmcnt(0)
	v_pk_mul_f32 v[4:5], v[4:5], v[10:11]
	v_pk_mul_f32 v[6:7], v[6:7], v[12:13]
	v_cvt_pk_bf16_f32 v4, v4, v5
	v_cvt_pk_bf16_f32 v5, v6, v7
	s_and_b64 vcc, exec, s[2:3]
	v_mov_b32_e32 v9, 1.0
	v_mov_b32_e32 v10, 1.0
	v_mov_b32_e32 v11, 1.0
	global_store_dwordx2 v[24:25], v[4:5], off offset:1024
	s_cbranch_vccnz .LBB0_241
	global_load_dwordx4 v[8:11], v[22:23], off offset:3072
	s_branch .LBB0_241

; DI unsigned pk2(float lo, float hi) { typedef float v2f __attribute__((ext_vector_type(2))); typedef __bf16 v2b __attribute__((ext_vector_type(2))); v2f v = {lo, hi}; v2b b = __builtin_convertvector(v, v2b); return __builtin_bit_cast(unsigned, b); }
; __global__ void __launch_bounds__(512, 2) fwd_mega(Args args) {
;     ...
;           for (int i = gt; i < 8 * 128 * 128 / 2; i += ngt) { const int e = 2 * i, s = e & 127, t = (e >> 7) & 127; const float a = s <= t ? sgw[e] : 0.f, b = (s + 1) <= t ? sgw[e + 1] : 0.f; ((unsigned*)wSG)[i] = pk2(a, b); } }
.LBB0_252:
	s_or_b64 exec, exec, s[8:9]
	v_add_u32_e32 v4, s72, v4
	s_waitcnt vmcnt(0)
	v_cvt_pk_bf16_f32 v3, v6, v5
	v_cmp_lt_i32_e32 vcc, s11, v4
	global_store_dword v[0:1], v3, off
	v_lshl_add_u64 v[0:1], v[0:1], 0, s[4:5]
	s_or_b64 s[6:7], vcc, s[6:7]
	v_add_u32_e32 v2, s10, v2
	s_andn2_b64 exec, exec, s[6:7]
	s_cbranch_execz .LBB0_257

; DI unsigned pk2(float lo, float hi) { typedef float v2f __attribute__((ext_vector_type(2))); typedef __bf16 v2b __attribute__((ext_vector_type(2))); v2f v = {lo, hi}; v2b b = __builtin_convertvector(v, v2b); return __builtin_bit_cast(unsigned, b); }
; DI float siluf_(float v) { return v * sigmoidf_(v); }
;     DI void operator()(const f32x4 (&acc)[2][2][4][2], const Unit& u, int wr, int wc, int fr, int fq) const {
;         const int row0 = u.pm * 256 + wr * 64 + fr, col0 = u.pn * 128 + wc * 32 + 8 * fq;
; #pragma unroll
;         for (int ai = 0; ai < 2; ++ai)
; #pragma unroll
;             for (int m = 0; m < 4; ++m) {
;                 const int row = row0 + ai * 128 + m * 16; const float rs = row_rstd<NP>(P, row, 1.0f / 1024.0f);
;                 float a[8];
; #pragma unroll
;                 for (int n = 0; n < 2; ++n)
; #pragma unroll
;                     for (int i = 0; i < 4; ++i) { const float g = acc[ai][0][m][n][i] * rs, uu = acc[ai][1][m][n][i] * rs; a[4 * n + i] = siluf_(g) * uu; }
;                 u32x4 w; w.x = pk2(a[0], a[1]); w.y = pk2(a[2], a[3]); w.z = pk2(a[4], a[5]); w.w = pk2(a[6], a[7]);
;                 *(u32x4*)(O + (size_t)row * FF + col0) = w;
.LBB0_325:
	v_mul_f32_e32 v160, 0xbfb8aa3b, v124
	v_mul_f32_e32 v161, 0xbfb8aa3b, v125
	v_exp_f32_e32 v160, v160
	v_exp_f32_e32 v161, v161
	v_lshl_or_b32 v164, s88, 7, v156
	v_ashrrev_i32_e32 v165, 31, v164
	v_add_f32_e32 v160, 1.0, v160
	v_add_f32_e32 v161, 1.0, v161
	v_rcp_f32_e32 v162, v160
	v_rcp_f32_e32 v163, v161
	v_mul_f32_e32 v161, 0xbfb8aa3b, v126
	v_exp_f32_e32 v161, v161
	v_lshl_add_u32 v160, s68, 8, v154
	v_pk_mul_f32 v[124:125], v[124:125], v[162:163]
	v_mul_f32_e32 v162, 0xbfb8aa3b, v127
	v_exp_f32_e32 v162, v162
	v_pk_mul_f32 v[116:117], v[124:125], v[116:117]
	v_add_f32_e32 v124, 1.0, v161
	v_mul_f32_e32 v161, 0xbfb8aa3b, v120
	v_add_f32_e32 v125, 1.0, v162
	v_rcp_f32_e32 v124, v124
	v_rcp_f32_e32 v125, v125
	v_exp_f32_e32 v161, v161
	v_mul_f32_e32 v162, 0xbfb8aa3b, v121
	v_exp_f32_e32 v162, v162
	v_pk_mul_f32 v[124:125], v[126:127], v[124:125]
	v_add_f32_e32 v126, 1.0, v161
	v_mul_f32_e32 v161, 0xbfb8aa3b, v122
	v_add_f32_e32 v127, 1.0, v162
	v_exp_f32_e32 v161, v161
	v_mul_f32_e32 v162, 0xbfb8aa3b, v123
	v_exp_f32_e32 v163, v162
	v_rcp_f32_e32 v126, v126
	v_add_f32_e32 v161, 1.0, v161
	v_rcp_f32_e32 v127, v127
	v_rcp_f32_e32 v162, v161
	v_add_f32_e32 v161, 1.0, v163
	v_rcp_f32_e32 v163, v161
	v_pk_mul_f32 v[120:121], v[120:121], v[126:127]
	v_pk_mul_f32 v[118:119], v[124:125], v[118:119]
	v_pk_mul_f32 v[112:113], v[120:121], v[112:113]
	v_pk_mul_f32 v[120:121], v[122:123], v[162:163]
	v_cvt_pk_bf16_f32 v116, v116, v117
	v_pk_mul_f32 v[114:115], v[120:121], v[114:115]
	v_cvt_pk_bf16_f32 v117, v118, v119
	v_cvt_pk_bf16_f32 v119, v114, v115
	v_mul_f32_e32 v114, 0xbfb8aa3b, v108
	v_exp_f32_e32 v114, v114
	v_mul_f32_e32 v115, 0xbfb8aa3b, v109
	v_exp_f32_e32 v115, v115
	v_cvt_pk_bf16_f32 v118, v112, v113
	v_add_f32_e32 v114, 1.0, v114
	v_mov_b64_e32 v[112:113], s[8:9]
	v_rcp_f32_e32 v122, v114
	v_add_f32_e32 v114, 1.0, v115
	v_mad_i64_i32 v[120:121], s[12:13], v160, s69, v[112:113]
	v_rcp_f32_e32 v123, v114
	v_lshlrev_b64 v[114:115], 1, v[164:165]
	v_lshl_add_u64 v[120:121], v[120:121], 0, v[114:115]
	global_store_dwordx4 v[120:121], v[116:119], off
	v_pk_mul_f32 v[108:109], v[108:109], v[122:123]
	s_andn2_b64 vcc, exec, s[2:3]
	v_mul_f32_e32 v116, 0xbfb8aa3b, v110
	v_mul_f32_e32 v117, 0xbfb8aa3b, v111
	v_exp_f32_e32 v116, v116
	v_exp_f32_e32 v117, v117
	v_pk_mul_f32 v[100:101], v[108:109], v[100:101]
	s_mov_b64 s[2:3], -1
	v_add_f32_e32 v108, 1.0, v116
	v_add_f32_e32 v109, 1.0, v117
	v_mul_f32_e32 v116, 0xbfb8aa3b, v104
	v_mul_f32_e32 v117, 0xbfb8aa3b, v105
	v_rcp_f32_e32 v108, v108
	v_rcp_f32_e32 v109, v109
	v_exp_f32_e32 v116, v116
	v_exp_f32_e32 v117, v117
	v_pk_mul_f32 v[108:109], v[110:111], v[108:109]
	v_add_f32_e32 v110, 1.0, v116
	v_add_f32_e32 v111, 1.0, v117
	v_mul_f32_e32 v116, 0xbfb8aa3b, v106
	v_mul_f32_e32 v117, 0xbfb8aa3b, v107
	v_exp_f32_e32 v116, v116
	v_exp_f32_e32 v117, v117
	v_rcp_f32_e32 v110, v110
	v_rcp_f32_e32 v111, v111
	v_add_f32_e32 v116, 1.0, v116
	v_add_f32_e32 v117, 1.0, v117
	v_rcp_f32_e32 v116, v116
	v_rcp_f32_e32 v117, v117
	v_pk_mul_f32 v[104:105], v[104:105], v[110:111]
	v_pk_mul_f32 v[102:103], v[108:109], v[102:103]
	v_pk_mul_f32 v[104:105], v[104:105], v[96:97]
	v_pk_mul_f32 v[96:97], v[106:107], v[116:117]
	v_or_b32_e32 v108, 16, v160
	v_pk_mul_f32 v[106:107], v[96:97], v[98:99]
	v_mul_f32_e32 v99, 0xbfb8aa3b, v92
	v_cvt_pk_bf16_f32 v96, v100, v101
	v_exp_f32_e32 v100, v99
	v_mul_f32_e32 v99, 0xbfb8aa3b, v93
	v_exp_f32_e32 v101, v99
	v_cvt_pk_bf16_f32 v97, v102, v103
	v_mad_i64_i32 v[102:103], s[12:13], v108, s69, v[112:113]
	v_cvt_pk_bf16_f32 v98, v104, v105
	v_cvt_pk_bf16_f32 v99, v106, v107
	v_add_f32_e32 v100, 1.0, v100
	v_add_f32_e32 v101, 1.0, v101
	v_lshl_add_u64 v[102:103], v[102:103], 0, v[114:115]
	v_rcp_f32_e32 v100, v100
	v_rcp_f32_e32 v101, v101
	global_store_dwordx4 v[102:103], v[96:99], off
	v_pk_mul_f32 v[92:93], v[92:93], v[100:101]
	s_nop 0
	v_mul_f32_e32 v96, 0xbfb8aa3b, v94
	v_mul_f32_e32 v97, 0xbfb8aa3b, v95
	v_exp_f32_e32 v96, v96
	v_exp_f32_e32 v97, v97
	v_pk_mul_f32 v[84:85], v[92:93], v[84:85]
	v_add_f32_e32 v92, 1.0, v96
	v_add_f32_e32 v93, 1.0, v97
	v_mul_f32_e32 v96, 0xbfb8aa3b, v88
	v_mul_f32_e32 v97, 0xbfb8aa3b, v89
	v_rcp_f32_e32 v92, v92
	v_rcp_f32_e32 v93, v93
	v_exp_f32_e32 v96, v96
	v_exp_f32_e32 v97, v97
	v_pk_mul_f32 v[92:93], v[94:95], v[92:93]
	v_add_f32_e32 v94, 1.0, v96
	v_add_f32_e32 v95, 1.0, v97
	v_mul_f32_e32 v96, 0xbfb8aa3b, v90
	v_mul_f32_e32 v97, 0xbfb8aa3b, v91
	v_exp_f32_e32 v96, v96
	v_exp_f32_e32 v97, v97
	v_rcp_f32_e32 v94, v94
	v_rcp_f32_e32 v95, v95
	v_add_f32_e32 v96, 1.0, v96
	v_add_f32_e32 v97, 1.0, v97
	v_rcp_f32_e32 v96, v96
	v_rcp_f32_e32 v97, v97
	v_pk_mul_f32 v[88:89], v[88:89], v[94:95]
	v_pk_mul_f32 v[86:87], v[92:93], v[86:87]
	v_pk_mul_f32 v[88:89], v[88:89], v[80:81]
	v_pk_mul_f32 v[80:81], v[90:91], v[96:97]
	v_or_b32_e32 v92, 32, v160
	v_pk_mul_f32 v[90:91], v[80:81], v[82:83]
	v_mul_f32_e32 v83, 0xbfb8aa3b, v76
	v_cvt_pk_bf16_f32 v80, v84, v85
	v_exp_f32_e32 v84, v83
	v_mul_f32_e32 v83, 0xbfb8aa3b, v77
	v_exp_f32_e32 v85, v83
	v_cvt_pk_bf16_f32 v81, v86, v87
	v_mad_i64_i32 v[86:87], s[12:13], v92, s69, v[112:113]
	v_cvt_pk_bf16_f32 v82, v88, v89
	v_cvt_pk_bf16_f32 v83, v90, v91
	v_add_f32_e32 v84, 1.0, v84
	v_add_f32_e32 v85, 1.0, v85
	v_lshl_add_u64 v[86:87], v[86:87], 0, v[114:115]
	v_rcp_f32_e32 v84, v84
	v_rcp_f32_e32 v85, v85
	global_store_dwordx4 v[86:87], v[80:83], off
	v_pk_mul_f32 v[76:77], v[76:77], v[84:85]
	s_nop 0
	v_mul_f32_e32 v80, 0xbfb8aa3b, v78
	v_mul_f32_e32 v81, 0xbfb8aa3b, v79
	v_exp_f32_e32 v80, v80
	v_exp_f32_e32 v81, v81
	v_pk_mul_f32 v[68:69], v[76:77], v[68:69]
	v_add_f32_e32 v76, 1.0, v80
; DI unsigned pk2(float lo, float hi) { typedef float v2f __attribute__((ext_vector_type(2))); typedef __bf16 v2b __attribute__((ext_vector_type(2))); v2f v = {lo, hi}; v2b b = __builtin_convertvector(v, v2b); return __builtin_bit_cast(unsigned, b); }
; DI float siluf_(float v) { return v * sigmoidf_(v); }
;     DI void operator()(const f32x4 (&acc)[2][2][4][2], const Unit& u, int wr, int wc, int fr, int fq) const {
;     ...
;                 float a[8];
; #pragma unroll
;                 for (int n = 0; n < 2; ++n)
; #pragma unroll
;                     for (int i = 0; i < 4; ++i) { const float g = acc[ai][0][m][n][i] * rs, uu = acc[ai][1][m][n][i] * rs; a[4 * n + i] = siluf_(g) * uu; }
;                 u32x4 w; w.x = pk2(a[0], a[1]); w.y = pk2(a[2], a[3]); w.z = pk2(a[4], a[5]); w.w = pk2(a[6], a[7]);
;                 *(u32x4*)(O + (size_t)row * FF + col0) = w;
	v_add_f32_e32 v77, 1.0, v81
	v_mul_f32_e32 v80, 0xbfb8aa3b, v72
	v_mul_f32_e32 v81, 0xbfb8aa3b, v73
	v_rcp_f32_e32 v76, v76
	v_rcp_f32_e32 v77, v77
	v_exp_f32_e32 v80, v80
	v_exp_f32_e32 v81, v81
	v_pk_mul_f32 v[76:77], v[78:79], v[76:77]
	v_add_f32_e32 v78, 1.0, v80
	v_add_f32_e32 v79, 1.0, v81
	v_mul_f32_e32 v80, 0xbfb8aa3b, v74
	v_mul_f32_e32 v81, 0xbfb8aa3b, v75
	v_exp_f32_e32 v80, v80
	v_exp_f32_e32 v81, v81
	v_rcp_f32_e32 v78, v78
	v_rcp_f32_e32 v79, v79
	v_add_f32_e32 v80, 1.0, v80
	v_add_f32_e32 v81, 1.0, v81
	v_rcp_f32_e32 v80, v80
	v_rcp_f32_e32 v81, v81
	v_pk_mul_f32 v[72:73], v[72:73], v[78:79]
	v_pk_mul_f32 v[70:71], v[76:77], v[70:71]
	v_pk_mul_f32 v[72:73], v[72:73], v[64:65]
	v_pk_mul_f32 v[64:65], v[74:75], v[80:81]
	v_or_b32_e32 v76, 48, v160
	v_pk_mul_f32 v[74:75], v[64:65], v[66:67]
	v_cvt_pk_bf16_f32 v64, v68, v69
	v_mul_f32_e32 v68, 0xbfb8aa3b, v60
	v_cvt_pk_bf16_f32 v65, v70, v71
	v_exp_f32_e32 v70, v68
	v_mul_f32_e32 v68, 0xbfb8aa3b, v61
	v_exp_f32_e32 v71, v68
	v_mad_i64_i32 v[68:69], s[12:13], v76, s69, v[112:113]
	v_cvt_pk_bf16_f32 v66, v72, v73
	v_cvt_pk_bf16_f32 v67, v74, v75
	v_add_f32_e32 v70, 1.0, v70
	v_add_f32_e32 v71, 1.0, v71
	v_lshl_add_u64 v[68:69], v[68:69], 0, v[114:115]
	v_rcp_f32_e32 v70, v70
	v_rcp_f32_e32 v71, v71
	global_store_dwordx4 v[68:69], v[64:67], off
	v_pk_mul_f32 v[60:61], v[60:61], v[70:71]
	s_nop 0
	v_mul_f32_e32 v64, 0xbfb8aa3b, v62
	v_mul_f32_e32 v65, 0xbfb8aa3b, v63
	v_exp_f32_e32 v64, v64
	v_exp_f32_e32 v65, v65
	v_pk_mul_f32 v[52:53], v[60:61], v[52:53]
	v_add_u32_e32 v66, 0x80, v160
	v_add_f32_e32 v60, 1.0, v64
	v_add_f32_e32 v61, 1.0, v65
	v_mul_f32_e32 v64, 0xbfb8aa3b, v56
	v_mul_f32_e32 v65, 0xbfb8aa3b, v57
	v_rcp_f32_e32 v60, v60
	v_rcp_f32_e32 v61, v61
	v_exp_f32_e32 v64, v64
	v_exp_f32_e32 v65, v65
	v_pk_mul_f32 v[60:61], v[62:63], v[60:61]
	v_add_f32_e32 v62, 1.0, v64
	v_add_f32_e32 v63, 1.0, v65
	v_mul_f32_e32 v64, 0xbfb8aa3b, v58
	v_mul_f32_e32 v65, 0xbfb8aa3b, v59
	v_exp_f32_e32 v64, v64
	v_exp_f32_e32 v65, v65
	v_rcp_f32_e32 v62, v62
	v_rcp_f32_e32 v63, v63
	v_add_f32_e32 v64, 1.0, v64
	v_add_f32_e32 v65, 1.0, v65
	v_rcp_f32_e32 v64, v64
	v_rcp_f32_e32 v65, v65
	v_pk_mul_f32 v[56:57], v[56:57], v[62:63]
	v_pk_mul_f32 v[54:55], v[60:61], v[54:55]
	v_pk_mul_f32 v[56:57], v[56:57], v[48:49]
	v_pk_mul_f32 v[48:49], v[58:59], v[64:65]
	s_nop 0
	v_pk_mul_f32 v[58:59], v[48:49], v[50:51]
	v_mul_f32_e32 v51, 0xbfb8aa3b, v44
	v_cvt_pk_bf16_f32 v48, v52, v53
	v_exp_f32_e32 v52, v51
	v_mul_f32_e32 v51, 0xbfb8aa3b, v45
	v_exp_f32_e32 v53, v51
	v_cvt_pk_bf16_f32 v49, v54, v55
	v_mad_i64_i32 v[54:55], s[12:13], v66, s69, v[112:113]
	v_cvt_pk_bf16_f32 v50, v56, v57
	v_cvt_pk_bf16_f32 v51, v58, v59
	v_add_f32_e32 v52, 1.0, v52
	v_add_f32_e32 v53, 1.0, v53
	v_lshl_add_u64 v[54:55], v[54:55], 0, v[114:115]
	v_rcp_f32_e32 v52, v52
	v_rcp_f32_e32 v53, v53
	global_store_dwordx4 v[54:55], v[48:51], off
	v_pk_mul_f32 v[44:45], v[44:45], v[52:53]
	s_nop 0
	v_mul_f32_e32 v48, 0xbfb8aa3b, v46
	v_mul_f32_e32 v49, 0xbfb8aa3b, v47
	v_exp_f32_e32 v48, v48
	v_exp_f32_e32 v49, v49
	v_pk_mul_f32 v[36:37], v[44:45], v[36:37]
	v_add_f32_e32 v44, 1.0, v48
	v_add_f32_e32 v45, 1.0, v49
	v_mul_f32_e32 v48, 0xbfb8aa3b, v40
	v_mul_f32_e32 v49, 0xbfb8aa3b, v41
	v_rcp_f32_e32 v44, v44
	v_rcp_f32_e32 v45, v45
	v_exp_f32_e32 v48, v48
	v_exp_f32_e32 v49, v49
	v_pk_mul_f32 v[44:45], v[46:47], v[44:45]
	v_add_f32_e32 v46, 1.0, v48
	v_add_f32_e32 v47, 1.0, v49
	v_mul_f32_e32 v48, 0xbfb8aa3b, v42
	v_mul_f32_e32 v49, 0xbfb8aa3b, v43
	v_exp_f32_e32 v48, v48
	v_exp_f32_e32 v49, v49
	v_rcp_f32_e32 v46, v46
	v_rcp_f32_e32 v47, v47
	v_add_f32_e32 v48, 1.0, v48
	v_add_f32_e32 v49, 1.0, v49
	v_rcp_f32_e32 v48, v48
	v_rcp_f32_e32 v49, v49
; #define PG8_BAR __builtin_amdgcn_s_barrier()
; DI unsigned pk2(float lo, float hi) { typedef float v2f __attribute__((ext_vector_type(2))); typedef __bf16 v2b __attribute__((ext_vector_type(2))); v2f v = {lo, hi}; v2b b = __builtin_convertvector(v, v2b); return __builtin_bit_cast(unsigned, b); }
; DI float siluf_(float v) { return v * sigmoidf_(v); }
; template <class Epi, class Sched, bool ALIGN_EPI = false, bool SP2 = false>
; __device__ __forceinline__ void gemm_phase(PG8_LAS unsigned char* lds, const Gemm g, const Sched& S, const Epi& E) {
;     ...
;         if constexpr (ALIGN_EPI) { if (wr == 0) PG8_BAR; }
;         if constexpr (!Epi::AFTER_DRAIN) { E(acc, cur, wr, wc, fr, fq); S.done(cur); }
;         if (!has_next) break;
; #pragma unroll
;         for (int a = 0; a < 2; ++a)
; #pragma unroll
;             for (int b = 0; b < 2; ++b)
; #pragma unroll
;                 for (int m = 0; m < 4; ++m)
; #pragma unroll
;                     for (int n = 0; n < 2; ++n) acc[a][b][m][n] = (f32x4){0.f, 0.f, 0.f, 0.f};
;         cur = nxt; cA = nA; cB = nB; ++ui;
;         if constexpr (ALIGN_EPI) { if (wr == 1) PG8_BAR; }
;     DI void operator()(const f32x4 (&acc)[2][2][4][2], const Unit& u, int wr, int wc, int fr, int fq) const {
;     ...
;                 float a[8];
; #pragma unroll
;                 for (int n = 0; n < 2; ++n)
; #pragma unroll
;                     for (int i = 0; i < 4; ++i) { const float g = acc[ai][0][m][n][i] * rs, uu = acc[ai][1][m][n][i] * rs; a[4 * n + i] = siluf_(g) * uu; }
;                 u32x4 w; w.x = pk2(a[0], a[1]); w.y = pk2(a[2], a[3]); w.z = pk2(a[4], a[5]); w.w = pk2(a[6], a[7]);
;                 *(u32x4*)(O + (size_t)row * FF + col0) = w;
	v_pk_mul_f32 v[40:41], v[40:41], v[46:47]
	v_pk_mul_f32 v[38:39], v[44:45], v[38:39]
	v_pk_mul_f32 v[40:41], v[40:41], v[32:33]
	v_pk_mul_f32 v[32:33], v[42:43], v[48:49]
	v_add_u32_e32 v44, 0x90, v160
	v_pk_mul_f32 v[42:43], v[32:33], v[34:35]
	v_mul_f32_e32 v35, 0xbfb8aa3b, v28
	v_cvt_pk_bf16_f32 v32, v36, v37
	v_exp_f32_e32 v36, v35
	v_mul_f32_e32 v35, 0xbfb8aa3b, v29
	v_exp_f32_e32 v37, v35
	v_cvt_pk_bf16_f32 v33, v38, v39
	v_mad_i64_i32 v[38:39], s[12:13], v44, s69, v[112:113]
	v_cvt_pk_bf16_f32 v34, v40, v41
	v_cvt_pk_bf16_f32 v35, v42, v43
	v_add_f32_e32 v36, 1.0, v36
	v_add_f32_e32 v37, 1.0, v37
	v_lshl_add_u64 v[38:39], v[38:39], 0, v[114:115]
	v_rcp_f32_e32 v36, v36
	v_rcp_f32_e32 v37, v37
	global_store_dwordx4 v[38:39], v[32:35], off
	v_pk_mul_f32 v[28:29], v[28:29], v[36:37]
	s_nop 0
	v_mul_f32_e32 v32, 0xbfb8aa3b, v30
	v_mul_f32_e32 v33, 0xbfb8aa3b, v31
	v_exp_f32_e32 v32, v32
	v_exp_f32_e32 v33, v33
	v_pk_mul_f32 v[20:21], v[28:29], v[20:21]
	v_add_f32_e32 v28, 1.0, v32
	v_add_f32_e32 v29, 1.0, v33
	v_mul_f32_e32 v32, 0xbfb8aa3b, v24
	v_mul_f32_e32 v33, 0xbfb8aa3b, v25
	v_rcp_f32_e32 v28, v28
	v_rcp_f32_e32 v29, v29
	v_exp_f32_e32 v32, v32
	v_exp_f32_e32 v33, v33
	v_pk_mul_f32 v[28:29], v[30:31], v[28:29]
	v_add_f32_e32 v30, 1.0, v32
	v_add_f32_e32 v31, 1.0, v33
	v_mul_f32_e32 v32, 0xbfb8aa3b, v26
	v_mul_f32_e32 v33, 0xbfb8aa3b, v27
	v_exp_f32_e32 v32, v32
	v_exp_f32_e32 v33, v33
	v_rcp_f32_e32 v30, v30
	v_rcp_f32_e32 v31, v31
	v_add_f32_e32 v32, 1.0, v32
	v_add_f32_e32 v33, 1.0, v33
	v_rcp_f32_e32 v32, v32
	v_rcp_f32_e32 v33, v33
	v_pk_mul_f32 v[24:25], v[24:25], v[30:31]
	v_pk_mul_f32 v[22:23], v[28:29], v[22:23]
	v_pk_mul_f32 v[24:25], v[24:25], v[16:17]
	v_pk_mul_f32 v[16:17], v[26:27], v[32:33]
	v_add_u32_e32 v28, 0xa0, v160
	v_pk_mul_f32 v[26:27], v[16:17], v[18:19]
	v_mul_f32_e32 v19, 0xbfb8aa3b, v12
	v_cvt_pk_bf16_f32 v16, v20, v21
	v_exp_f32_e32 v20, v19
	v_mul_f32_e32 v19, 0xbfb8aa3b, v13
	v_exp_f32_e32 v21, v19
	v_cvt_pk_bf16_f32 v17, v22, v23
	v_mad_i64_i32 v[22:23], s[12:13], v28, s69, v[112:113]
	v_cvt_pk_bf16_f32 v18, v24, v25
	v_cvt_pk_bf16_f32 v19, v26, v27
	v_add_f32_e32 v20, 1.0, v20
	v_add_f32_e32 v21, 1.0, v21
	v_lshl_add_u64 v[22:23], v[22:23], 0, v[114:115]
	v_rcp_f32_e32 v20, v20
	v_rcp_f32_e32 v21, v21
	global_store_dwordx4 v[22:23], v[16:19], off
	v_pk_mul_f32 v[12:13], v[12:13], v[20:21]
	s_nop 0
	v_mul_f32_e32 v16, 0xbfb8aa3b, v14
	v_mul_f32_e32 v17, 0xbfb8aa3b, v15
	v_exp_f32_e32 v16, v16
	v_exp_f32_e32 v17, v17
	v_pk_mul_f32 v[4:5], v[12:13], v[4:5]
	v_add_f32_e32 v12, 1.0, v16
	v_add_f32_e32 v13, 1.0, v17
	v_mul_f32_e32 v16, 0xbfb8aa3b, v8
	v_mul_f32_e32 v17, 0xbfb8aa3b, v9
	v_rcp_f32_e32 v12, v12
	v_rcp_f32_e32 v13, v13
	v_exp_f32_e32 v16, v16
	v_exp_f32_e32 v17, v17
	v_pk_mul_f32 v[12:13], v[14:15], v[12:13]
	v_add_f32_e32 v14, 1.0, v16
	v_add_f32_e32 v15, 1.0, v17
	v_mul_f32_e32 v16, 0xbfb8aa3b, v10
	v_mul_f32_e32 v17, 0xbfb8aa3b, v11
	v_exp_f32_e32 v16, v16
	v_exp_f32_e32 v17, v17
	v_rcp_f32_e32 v14, v14
	v_rcp_f32_e32 v15, v15
	v_add_f32_e32 v16, 1.0, v16
	v_add_f32_e32 v17, 1.0, v17
	v_rcp_f32_e32 v16, v16
	v_rcp_f32_e32 v17, v17
	v_pk_mul_f32 v[8:9], v[8:9], v[14:15]
	v_pk_mul_f32 v[6:7], v[12:13], v[6:7]
	v_pk_mul_f32 v[8:9], v[8:9], v[0:1]
	v_pk_mul_f32 v[0:1], v[10:11], v[16:17]
	v_add_u32_e32 v12, 0xb0, v160
	v_pk_mul_f32 v[10:11], v[0:1], v[2:3]
	v_cvt_pk_bf16_f32 v0, v4, v5
	v_mad_i64_i32 v[4:5], s[12:13], v12, s69, v[112:113]
	v_cvt_pk_bf16_f32 v1, v6, v7
	v_cvt_pk_bf16_f32 v2, v8, v9
	v_cvt_pk_bf16_f32 v3, v10, v11
	v_lshl_add_u64 v[4:5], v[4:5], 0, v[114:115]
	global_store_dwordx4 v[4:5], v[0:3], off
	s_cbranch_vccnz .LBB0_318
	s_andn2_b64 vcc, exec, s[6:7]
	s_cbranch_vccnz .LBB0_317
	s_barrier
	s_branch .LBB0_317

; #define PG8_BAR __builtin_amdgcn_s_barrier()
; template <class Epi, class Sched, bool ALIGN_EPI = false, bool SP2 = false>
; __device__ __forceinline__ void gemm_phase(PG8_LAS unsigned char* lds, const Gemm g, const Sched& S, const Epi& E) {
;     ...
;         if constexpr (ALIGN_EPI) { if (wr == 0) PG8_BAR; }
;         if constexpr (!Epi::AFTER_DRAIN) { E(acc, cur, wr, wc, fr, fq); S.done(cur); }
;         if (!has_next) break;
; #pragma unroll
;         for (int a = 0; a < 2; ++a)
; #pragma unroll
;             for (int b = 0; b < 2; ++b)
; #pragma unroll
;                 for (int m = 0; m < 4; ++m)
; #pragma unroll
;                     for (int n = 0; n < 2; ++n) acc[a][b][m][n] = (f32x4){0.f, 0.f, 0.f, 0.f};
;         cur = nxt; cA = nA; cB = nB; ++ui;
;         if constexpr (ALIGN_EPI) { if (wr == 1) PG8_BAR; }
;     DI void operator()(const f32x4 (&acc)[2][2][4][2], const Unit& u, int wr, int wc, int fr, int fq) const {
;         const int row0 = u.pm * 256 + wr * 64 + fr, col0 = u.pn * 256 + wc * 32 + 8 * fq;
; #pragma unroll
;         for (int ai = 0; ai < 2; ++ai)
; #pragma unroll
;             for (int m = 0; m < 4; ++m)
; #pragma unroll
;                 for (int bj = 0; bj < 2; ++bj)
; #pragma unroll
;                     for (int n = 0; n < 2; ++n) *(f32x4*)(O + (size_t)(row0 + ai * 128 + m * 16) * ldc + col0 + bj * 128 + n * 4) = acc[ai][bj][m][n];
.LBB0_341:
	v_lshl_add_u32 v148, s14, 8, v144
	v_lshl_or_b32 v150, s89, 8, v146
	v_ashrrev_i32_e32 v149, 31, v148
	v_ashrrev_i32_e32 v151, 31, v150
	v_lshlrev_b64 v[152:153], 12, v[148:149]
	v_lshl_add_u64 v[152:153], s[6:7], 0, v[152:153]
	v_lshlrev_b64 v[150:151], 2, v[150:151]
	v_lshl_add_u64 v[152:153], v[152:153], 0, v[150:151]
	global_store_dwordx4 v[152:153], v[124:127], off
	global_store_dwordx4 v[152:153], v[120:123], off offset:16
	global_store_dwordx4 v[152:153], v[108:111], off offset:512
	global_store_dwordx4 v[152:153], v[100:103], off offset:528
	s_mov_b64 s[12:13], 0x80000
	s_nop 0
	v_or_b32_e32 v100, 16, v148
	v_ashrrev_i32_e32 v101, 31, v100
	v_lshlrev_b64 v[100:101], 12, v[100:101]
	v_lshl_add_u64 v[100:101], s[6:7], 0, v[100:101]
	v_lshl_add_u64 v[100:101], v[100:101], 0, v[150:151]
	global_store_dwordx4 v[100:101], v[116:119], off
	global_store_dwordx4 v[100:101], v[112:115], off offset:16
	global_store_dwordx4 v[100:101], v[92:95], off offset:512
	global_store_dwordx4 v[100:101], v[84:87], off offset:528
	s_nop 1
	v_or_b32_e32 v84, 32, v148
	v_ashrrev_i32_e32 v85, 31, v84
	v_lshlrev_b64 v[84:85], 12, v[84:85]
	v_lshl_add_u64 v[84:85], s[6:7], 0, v[84:85]
	v_lshl_add_u64 v[84:85], v[84:85], 0, v[150:151]
	global_store_dwordx4 v[84:85], v[104:107], off
	global_store_dwordx4 v[84:85], v[96:99], off offset:16
	global_store_dwordx4 v[84:85], v[76:79], off offset:512
	global_store_dwordx4 v[84:85], v[72:75], off offset:528
	s_nop 1
	v_or_b32_e32 v72, 48, v148
	v_ashrrev_i32_e32 v73, 31, v72
	v_lshlrev_b64 v[72:73], 12, v[72:73]
	v_lshl_add_u64 v[72:73], s[6:7], 0, v[72:73]
	v_lshl_add_u64 v[72:73], v[72:73], 0, v[150:151]
	global_store_dwordx4 v[72:73], v[88:91], off
	global_store_dwordx4 v[72:73], v[80:83], off offset:16
	global_store_dwordx4 v[72:73], v[68:71], off offset:512
	global_store_dwordx4 v[72:73], v[64:67], off offset:528
	s_nop 1
	v_lshl_add_u64 v[64:65], v[152:153], 0, s[12:13]
	s_mov_b32 s12, 0x80000
	v_add_co_u32_e32 v66, vcc, s12, v152
	s_mov_b64 s[12:13], 0x90000
	s_nop 0
	v_addc_co_u32_e32 v67, vcc, 0, v153, vcc
	global_store_dwordx4 v[66:67], v[60:63], off
	global_store_dwordx4 v[64:65], v[56:59], off offset:16
	global_store_dwordx4 v[64:65], v[44:47], off offset:512
	global_store_dwordx4 v[64:65], v[40:43], off offset:528
	s_nop 1
	v_lshl_add_u64 v[40:41], v[152:153], 0, s[12:13]
	s_mov_b32 s12, 0x90000
	v_add_co_u32_e32 v42, vcc, s12, v152
	s_mov_b64 s[12:13], 0xa0000
	s_nop 0
	v_addc_co_u32_e32 v43, vcc, 0, v153, vcc
	global_store_dwordx4 v[42:43], v[52:55], off
	global_store_dwordx4 v[40:41], v[48:51], off offset:16
	global_store_dwordx4 v[40:41], v[28:31], off offset:512
	global_store_dwordx4 v[40:41], v[24:27], off offset:528
	s_nop 1
	v_lshl_add_u64 v[24:25], v[152:153], 0, s[12:13]
	s_mov_b32 s12, 0xa0000
	v_add_co_u32_e32 v26, vcc, s12, v152
	s_mov_b64 s[12:13], 0xb0000
	s_nop 0
	v_addc_co_u32_e32 v27, vcc, 0, v153, vcc
	global_store_dwordx4 v[26:27], v[36:39], off
	global_store_dwordx4 v[24:25], v[32:35], off offset:16
	global_store_dwordx4 v[24:25], v[12:15], off offset:512
	global_store_dwordx4 v[24:25], v[8:11], off offset:528
	s_nop 1
	v_add_co_u32_e32 v10, vcc, 0xb0000, v152
	v_lshl_add_u64 v[8:9], v[152:153], 0, s[12:13]
	s_nop 0
	v_addc_co_u32_e32 v11, vcc, 0, v153, vcc
	s_andn2_b64 vcc, exec, s[58:59]
	s_mov_b64 s[12:13], -1
	global_store_dwordx4 v[10:11], v[20:23], off
	global_store_dwordx4 v[8:9], v[16:19], off offset:16
	global_store_dwordx4 v[8:9], v[4:7], off offset:512
	global_store_dwordx4 v[8:9], v[0:3], off offset:528
	s_cbranch_vccnz .LBB0_334
	s_andn2_b64 vcc, exec, s[2:3]
	s_cbranch_vccnz .LBB0_333
	s_barrier
	s_branch .LBB0_333

;     ...
;     for (int item = gw; item < nitems; item += ngw) {
;         const int kb = item / nblk, nb = nb0 + item % nblk, k0 = 64 * kb, n0 = 32 * nb;
;         float tv[32];
; #pragma unroll
;         for (int i = 0; i < 32; ++i) { const int kk = 2 * i + (lane >> 5); tv[i] = W[(size_t)(k0 + kk) * N + n0 + (lane & 31)]; }
; #pragma unroll
;         for (int i = 0; i < 32; ++i) { const int kk = 2 * i + (lane >> 5); float v = tv[i]; if (gk) v *= gk[k0 + kk]; scr[kk * 33 + (lane & 31)] = v; }
;         asm volatile("s_waitcnt lgkmcnt(0)" ::: "memory");
;         bf16_t* dst = dest_rows(mode, n0, K, d0, d1);
.LBB0_348:
	s_ashr_i32 s2, s14, 31
	s_lshr_b32 s2, s2, 27
	s_add_i32 s2, s14, s2
	s_ashr_i32 s3, s2, 5
	s_lshl_b32 s2, s3, 6
	s_lshl_b32 s3, s3, 10
	v_or_b32_e32 v16, s2, v0
	s_sub_i32 s6, s11, s3
	v_or_b32_e32 v18, 2, v16
	v_or_b32_e32 v26, 10, v16
	v_or_b32_e32 v28, 12, v16
	v_or_b32_e32 v30, 14, v16
	v_or_b32_e32 v32, 16, v16
	v_or_b32_e32 v38, 18, v16
	v_or_b32_e32 v40, 20, v16
	v_or_b32_e32 v42, 22, v16
	v_or_b32_e32 v44, 24, v16
	v_or_b32_e32 v48, 26, v16
	v_or_b32_e32 v50, 28, v16
	v_or_b32_e32 v52, 30, v16
	v_or_b32_e32 v54, 32, v16
	v_or_b32_e32 v56, 34, v16
	v_or_b32_e32 v58, 36, v16
	s_ashr_i32 s7, s6, 31
	v_ashrrev_i32_e32 v17, 31, v16
	v_or_b32_e32 v20, 4, v16
	v_or_b32_e32 v22, 6, v16
	v_or_b32_e32 v24, 8, v16
	v_or_b32_e32 v60, 38, v16
	v_or_b32_e32 v62, 40, v16
	v_or_b32_e32 v64, 42, v16
	v_or_b32_e32 v66, 44, v16
	v_or_b32_e32 v68, 46, v16
	v_or_b32_e32 v70, 48, v16
	v_or_b32_e32 v72, 50, v16
	v_or_b32_e32 v74, 52, v16
	v_or_b32_e32 v76, 54, v16
	v_or_b32_e32 v78, 56, v16
	v_or_b32_e32 v80, 58, v16
	v_or_b32_e32 v82, 60, v16
	v_or_b32_e32 v84, 62, v16
	v_ashrrev_i32_e32 v19, 31, v18
	v_ashrrev_i32_e32 v27, 31, v26
	v_ashrrev_i32_e32 v29, 31, v28
	v_ashrrev_i32_e32 v31, 31, v30
	v_ashrrev_i32_e32 v33, 31, v32
	v_ashrrev_i32_e32 v39, 31, v38
	v_ashrrev_i32_e32 v41, 31, v40
	v_ashrrev_i32_e32 v43, 31, v42
	v_ashrrev_i32_e32 v45, 31, v44
	v_ashrrev_i32_e32 v49, 31, v48
	v_ashrrev_i32_e32 v51, 31, v50
	v_ashrrev_i32_e32 v53, 31, v52
	v_ashrrev_i32_e32 v55, 31, v54
	v_ashrrev_i32_e32 v57, 31, v56
	v_ashrrev_i32_e32 v59, 31, v58
	v_lshl_add_u64 v[86:87], s[6:7], 2, v[6:7]
	v_lshlrev_b64 v[16:17], 12, v[16:17]
	v_ashrrev_i32_e32 v21, 31, v20
	v_ashrrev_i32_e32 v23, 31, v22
	v_ashrrev_i32_e32 v25, 31, v24
	v_ashrrev_i32_e32 v61, 31, v60
	v_ashrrev_i32_e32 v63, 31, v62
	v_ashrrev_i32_e32 v65, 31, v64
	v_ashrrev_i32_e32 v67, 31, v66
	v_ashrrev_i32_e32 v69, 31, v68
	v_ashrrev_i32_e32 v71, 31, v70
	v_ashrrev_i32_e32 v73, 31, v72
	v_ashrrev_i32_e32 v75, 31, v74
	v_ashrrev_i32_e32 v77, 31, v76
	v_ashrrev_i32_e32 v79, 31, v78
	v_ashrrev_i32_e32 v81, 31, v80
	v_ashrrev_i32_e32 v83, 31, v82
	v_ashrrev_i32_e32 v85, 31, v84
	v_lshlrev_b64 v[18:19], 12, v[18:19]
	v_lshlrev_b64 v[26:27], 12, v[26:27]
	v_lshlrev_b64 v[28:29], 12, v[28:29]
	v_lshlrev_b64 v[30:31], 12, v[30:31]
	v_lshlrev_b64 v[32:33], 12, v[32:33]
	v_lshlrev_b64 v[38:39], 12, v[38:39]
	v_lshlrev_b64 v[40:41], 12, v[40:41]
	v_lshlrev_b64 v[42:43], 12, v[42:43]
	v_lshlrev_b64 v[44:45], 12, v[44:45]
	v_lshlrev_b64 v[48:49], 12, v[48:49]
	v_lshlrev_b64 v[50:51], 12, v[50:51]
	v_lshlrev_b64 v[52:53], 12, v[52:53]
	v_lshlrev_b64 v[54:55], 12, v[54:55]
	v_lshlrev_b64 v[56:57], 12, v[56:57]
	v_lshlrev_b64 v[58:59], 12, v[58:59]
	v_lshl_add_u64 v[16:17], v[86:87], 0, v[16:17]
	v_lshlrev_b64 v[20:21], 12, v[20:21]
	v_lshlrev_b64 v[22:23], 12, v[22:23]
	v_lshlrev_b64 v[24:25], 12, v[24:25]
	v_lshlrev_b64 v[60:61], 12, v[60:61]
	v_lshlrev_b64 v[62:63], 12, v[62:63]
	v_lshlrev_b64 v[64:65], 12, v[64:65]
	v_lshlrev_b64 v[66:67], 12, v[66:67]
	v_lshlrev_b64 v[68:69], 12, v[68:69]
	v_lshlrev_b64 v[70:71], 12, v[70:71]
	v_lshlrev_b64 v[72:73], 12, v[72:73]
	v_lshlrev_b64 v[74:75], 12, v[74:75]
	v_lshlrev_b64 v[76:77], 12, v[76:77]
	v_lshlrev_b64 v[78:79], 12, v[78:79]
	v_lshlrev_b64 v[80:81], 12, v[80:81]
	v_lshlrev_b64 v[82:83], 12, v[82:83]
	v_lshlrev_b64 v[84:85], 12, v[84:85]
	v_lshl_add_u64 v[18:19], v[86:87], 0, v[18:19]
	v_lshl_add_u64 v[26:27], v[86:87], 0, v[26:27]
	v_lshl_add_u64 v[28:29], v[86:87], 0, v[28:29]
	v_lshl_add_u64 v[30:31], v[86:87], 0, v[30:31]
	v_lshl_add_u64 v[32:33], v[86:87], 0, v[32:33]
	v_lshl_add_u64 v[38:39], v[86:87], 0, v[38:39]
	v_lshl_add_u64 v[40:41], v[86:87], 0, v[40:41]
	v_lshl_add_u64 v[42:43], v[86:87], 0, v[42:43]
	v_lshl_add_u64 v[44:45], v[86:87], 0, v[44:45]
	v_lshl_add_u64 v[48:49], v[86:87], 0, v[48:49]
	v_lshl_add_u64 v[50:51], v[86:87], 0, v[50:51]
	v_lshl_add_u64 v[52:53], v[86:87], 0, v[52:53]
	v_lshl_add_u64 v[54:55], v[86:87], 0, v[54:55]
	v_lshl_add_u64 v[56:57], v[86:87], 0, v[56:57]
	v_lshl_add_u64 v[58:59], v[86:87], 0, v[58:59]
	v_lshl_add_u64 v[20:21], v[86:87], 0, v[20:21]
	v_lshl_add_u64 v[22:23], v[86:87], 0, v[22:23]
	v_lshl_add_u64 v[24:25], v[86:87], 0, v[24:25]
	v_lshl_add_u64 v[60:61], v[86:87], 0, v[60:61]
	v_lshl_add_u64 v[62:63], v[86:87], 0, v[62:63]
	v_lshl_add_u64 v[64:65], v[86:87], 0, v[64:65]
	v_lshl_add_u64 v[66:67], v[86:87], 0, v[66:67]
	v_lshl_add_u64 v[68:69], v[86:87], 0, v[68:69]
	v_lshl_add_u64 v[70:71], v[86:87], 0, v[70:71]
	v_lshl_add_u64 v[72:73], v[86:87], 0, v[72:73]
	v_lshl_add_u64 v[74:75], v[86:87], 0, v[74:75]
	v_lshl_add_u64 v[76:77], v[86:87], 0, v[76:77]
	v_lshl_add_u64 v[78:79], v[86:87], 0, v[78:79]
	v_lshl_add_u64 v[80:81], v[86:87], 0, v[80:81]
	v_lshl_add_u64 v[82:83], v[86:87], 0, v[82:83]
	v_lshl_add_u64 v[84:85], v[86:87], 0, v[84:85]
	global_load_dword v15, v[16:17], off
	s_nop 0
	global_load_dword v18, v[18:19], off
	s_nop 0
	global_load_dword v19, v[20:21], off
	global_load_dword v37, v[22:23], off
	global_load_dword v46, v[24:25], off
	s_nop 0
	global_load_dword v27, v[26:27], off
	s_nop 0
	global_load_dword v28, v[28:29], off
	s_nop 0
	global_load_dword v29, v[30:31], off
	s_nop 0
	global_load_dword v30, v[32:33], off
	global_load_dword v31, v[38:39], off
	s_nop 0
	global_load_dword v32, v[40:41], off
	global_load_dword v33, v[42:43], off
	global_load_dword v38, v[44:45], off
	global_load_dword v39, v[48:49], off
	s_nop 0
	global_load_dword v40, v[50:51], off
	global_load_dword v41, v[52:53], off
	global_load_dword v42, v[54:55], off
	global_load_dword v43, v[56:57], off
	global_load_dword v44, v[58:59], off
	global_load_dword v45, v[60:61], off
	global_load_dword v48, v[62:63], off
	global_load_dword v49, v[64:65], off
	global_load_dword v50, v[66:67], off
	global_load_dword v51, v[68:69], off
	global_load_dword v52, v[70:71], off
	global_load_dword v53, v[72:73], off
	global_load_dword v54, v[74:75], off
	global_load_dword v55, v[76:77], off
	global_load_dword v56, v[78:79], off
	global_load_dword v57, v[80:81], off
	global_load_dword v58, v[82:83], off
	global_load_dword v59, v[84:85], off
	s_mul_hi_i32 s3, s6, 0x1600
	s_mulk_i32 s6, 0x1600
	s_add_u32 s6, s9, s6
	s_addc_u32 s7, s10, s3
	s_ashr_i32 s3, s2, 31
	s_lshl_b64 s[2:3], s[2:3], 1
	s_add_u32 s2, s6, s2
	s_addc_u32 s3, s7, s3
	s_waitcnt vmcnt(0)
; #define LAS __attribute__((address_space(3)))
; DI unsigned pk2(float lo, float hi) { typedef float v2f __attribute__((ext_vector_type(2))); typedef __bf16 v2b __attribute__((ext_vector_type(2))); v2f v = {lo, hi}; v2b b = __builtin_convertvector(v, v2b); return __builtin_bit_cast(unsigned, b); }
;     ...
;         for (int i = 0; i < 32; ++i) { const int kk = 2 * i + (lane >> 5); float v = tv[i]; if (gk) v *= gk[k0 + kk]; scr[kk * 33 + (lane & 31)] = v; }
;         asm volatile("s_waitcnt lgkmcnt(0)" ::: "memory");
;         bf16_t* dst = dest_rows(mode, n0, K, d0, d1);
;         const int c = lane & 7;
; #pragma unroll
;         for (int jj = 0; jj < 4; ++jj) { const int n = (lane >> 3) + 8 * jj; const LAS float* s = scr + (8 * c) * 33 + n;
;             u32x4 o; o.x = pk2(s[0 * 33], s[1 * 33]); o.y = pk2(s[2 * 33], s[3 * 33]); o.z = pk2(s[4 * 33], s[5 * 33]); o.w = pk2(s[6 * 33], s[7 * 33]);
;             *(u32x4*)(dst + (size_t)n * K + k0 + 8 * c) = o; }
;         asm volatile("s_waitcnt lgkmcnt(0)" ::: "memory");
	ds_write2_b32 v36, v15, v18 offset1:66
	ds_write2_b32 v36, v19, v37 offset0:132 offset1:198
	ds_write2_b32 v1, v46, v27 offset0:8 offset1:74
	ds_write2_b32 v1, v28, v29 offset0:140 offset1:206
	ds_write2_b32 v5, v30, v31 offset0:16 offset1:82
	ds_write2_b32 v5, v32, v33 offset0:148 offset1:214
	ds_write2_b32 v10, v38, v39 offset0:24 offset1:90
	ds_write2_b32 v10, v40, v41 offset0:156 offset1:222
	ds_write2_b32 v11, v42, v43 offset0:32 offset1:98
	ds_write2_b32 v11, v44, v45 offset0:164 offset1:230
	ds_write2_b32 v12, v48, v49 offset0:40 offset1:106
	ds_write2_b32 v12, v50, v51 offset0:172 offset1:238
	ds_write2_b32 v13, v52, v53 offset0:48 offset1:114
	ds_write2_b32 v13, v54, v55 offset0:180 offset1:246
	ds_write2_b32 v14, v56, v57 offset0:56 offset1:122
	ds_write2_b32 v14, v58, v59 offset0:188 offset1:254
	v_lshl_add_u64 v[16:17], s[2:3], 0, v[2:3]
	s_waitcnt lgkmcnt(0)
	v_lshl_add_u64 v[20:21], v[16:17], 0, v[8:9]
	ds_read_b32 v15, v35
	ds_read_b32 v16, v35 offset:132
	ds_read_b32 v17, v35 offset:264
	ds_read_b32 v18, v35 offset:396
	ds_read_b32 v19, v35 offset:528
	ds_read_b32 v27, v35 offset:660
	ds_read_b32 v28, v35 offset:792
	ds_read_b32 v29, v35 offset:924
	v_add_co_u32_e32 v22, vcc, s12, v20
	s_waitcnt lgkmcnt(0)
	v_cvt_pk_bf16_f32 v16, v15, v16
	v_addc_co_u32_e32 v23, vcc, 0, v21, vcc
	v_add_co_u32_e32 v24, vcc, s13, v20
	v_cvt_pk_bf16_f32 v17, v17, v18
	v_cvt_pk_bf16_f32 v18, v19, v27
	v_cvt_pk_bf16_f32 v19, v28, v29
	v_addc_co_u32_e32 v25, vcc, 0, v21, vcc
	global_store_dwordx4 v[20:21], v[16:19], off
	v_add_co_u32_e32 v26, vcc, 0x21000, v20
	ds_read_b32 v15, v35 offset:32
	ds_read_b32 v16, v35 offset:164
	ds_read_b32 v17, v35 offset:296
	ds_read_b32 v18, v35 offset:428
	ds_read_b32 v19, v35 offset:560
	ds_read_b32 v20, v35 offset:692
	ds_read_b32 v27, v35 offset:824
	ds_read_b32 v28, v35 offset:956
	s_waitcnt lgkmcnt(0)
	v_cvt_pk_bf16_f32 v16, v15, v16
	v_cvt_pk_bf16_f32 v17, v17, v18
	v_cvt_pk_bf16_f32 v18, v19, v20
	s_add_i32 s6, s14, 0x3c0
	v_cvt_pk_bf16_f32 v19, v27, v28
	global_store_dwordx4 v[22:23], v[16:19], off
	ds_read_b32 v15, v35 offset:64
	ds_read_b32 v16, v35 offset:196
	ds_read_b32 v17, v35 offset:328
	ds_read_b32 v18, v35 offset:460
	ds_read_b32 v19, v35 offset:592
	ds_read_b32 v20, v35 offset:724
	ds_read_b32 v22, v35 offset:856
	ds_read_b32 v23, v35 offset:988
	s_waitcnt lgkmcnt(0)
	v_cvt_pk_bf16_f32 v16, v15, v16
	v_cvt_pk_bf16_f32 v17, v17, v18
	v_cvt_pk_bf16_f32 v18, v19, v20
	v_addc_co_u32_e32 v27, vcc, 0, v21, vcc
	v_cvt_pk_bf16_f32 v19, v22, v23
	global_store_dwordx4 v[24:25], v[16:19], off
	ds_read_b32 v15, v35 offset:96
	ds_read_b32 v16, v35 offset:228
	ds_read_b32 v17, v35 offset:360
	ds_read_b32 v18, v35 offset:492
	ds_read_b32 v19, v35 offset:624
	ds_read_b32 v20, v35 offset:756
	ds_read_b32 v22, v35 offset:888
	ds_read_b32 v23, v35 offset:1020
	s_waitcnt lgkmcnt(0)
	v_cvt_pk_bf16_f32 v16, v15, v16
	v_cvt_pk_bf16_f32 v17, v17, v18
	v_cvt_pk_bf16_f32 v18, v19, v20
	s_addk_i32 s11, 0x7800
	v_cvt_pk_bf16_f32 v19, v22, v23
	global_store_dwordx4 v[26:27], v[16:19], off
	s_waitcnt lgkmcnt(0)
	s_cmpk_lt_i32 s14, 0x1c0
	s_mov_b32 s14, s6
	s_cbranch_scc1 .LBB0_348

; #define LAS __attribute__((address_space(3)))
; DI unsigned pk2(float lo, float hi) { typedef float v2f __attribute__((ext_vector_type(2))); typedef __bf16 v2b __attribute__((ext_vector_type(2))); v2f v = {lo, hi}; v2b b = __builtin_convertvector(v, v2b); return __builtin_bit_cast(unsigned, b); }
;     ...
;         bf16_t* dst = dest_rows(mode, n0, K, d0, d1);
;         const int c = lane & 7;
; #pragma unroll
;         for (int jj = 0; jj < 4; ++jj) { const int n = (lane >> 3) + 8 * jj; const LAS float* s = scr + (8 * c) * 33 + n;
;             u32x4 o; o.x = pk2(s[0 * 33], s[1 * 33]); o.y = pk2(s[2 * 33], s[3 * 33]); o.z = pk2(s[4 * 33], s[5 * 33]); o.w = pk2(s[6 * 33], s[7 * 33]);
;             *(u32x4*)(dst + (size_t)n * K + k0 + 8 * c) = o; }
;         asm volatile("s_waitcnt lgkmcnt(0)" ::: "memory");
.LBB0_351:
	s_ashr_i32 s11, s10, 31
	ds_read_b32 v5, v35
	ds_read_b32 v9, v35 offset:132
	ds_read_b32 v11, v35 offset:264
	ds_read_b32 v13, v35 offset:396
	ds_read_b32 v15, v35 offset:528
	ds_read_b32 v18, v35 offset:660
	ds_read_b32 v19, v35 offset:792
	ds_read_b32 v22, v35 offset:924
	s_lshl_b64 s[10:11], s[10:11], 1
	s_add_u32 s2, s2, s10
	s_addc_u32 s3, s3, s11
	v_lshl_add_u64 v[20:21], s[2:3], 0, v[2:3]
	s_waitcnt lgkmcnt(0)
	v_cvt_pk_bf16_f32 v16, v5, v9
	v_mov_b32_e32 v9, v3
	v_cvt_pk_bf16_f32 v17, v11, v13
	v_cvt_pk_bf16_f32 v18, v15, v18
	v_cvt_pk_bf16_f32 v19, v19, v22
	v_lshl_add_u64 v[22:23], v[20:21], 0, v[8:9]
	global_store_dwordx4 v[22:23], v[16:19], off
	ds_read_b32 v5, v35 offset:32
	ds_read_b32 v9, v35 offset:164
	ds_read_b32 v11, v35 offset:296
	ds_read_b32 v13, v35 offset:428
	ds_read_b32 v15, v35 offset:560
	ds_read_b32 v18, v35 offset:692
	ds_read_b32 v19, v35 offset:824
	ds_read_b32 v22, v35 offset:956
	s_waitcnt lgkmcnt(0)
	v_cvt_pk_bf16_f32 v17, v11, v13
	v_mov_b32_e32 v11, v3
	v_cvt_pk_bf16_f32 v16, v5, v9
	v_cvt_pk_bf16_f32 v18, v15, v18
	v_cvt_pk_bf16_f32 v19, v19, v22
	v_lshl_add_u64 v[22:23], v[20:21], 0, v[10:11]
	global_store_dwordx4 v[22:23], v[16:19], off
	ds_read_b32 v5, v35 offset:64
	ds_read_b32 v9, v35 offset:196
	ds_read_b32 v11, v35 offset:328
	ds_read_b32 v13, v35 offset:460
	ds_read_b32 v15, v35 offset:592
	ds_read_b32 v18, v35 offset:724
	ds_read_b32 v19, v35 offset:856
	ds_read_b32 v22, v35 offset:988
	s_waitcnt lgkmcnt(0)
	v_cvt_pk_bf16_f32 v17, v11, v13
	v_mov_b32_e32 v13, v3
	v_cvt_pk_bf16_f32 v16, v5, v9
	v_cvt_pk_bf16_f32 v18, v15, v18
	v_cvt_pk_bf16_f32 v19, v19, v22
	v_lshl_add_u64 v[22:23], v[20:21], 0, v[12:13]
	global_store_dwordx4 v[22:23], v[16:19], off
	ds_read_b32 v5, v35 offset:96
	ds_read_b32 v9, v35 offset:228
	ds_read_b32 v11, v35 offset:360
	ds_read_b32 v13, v35 offset:492
	ds_read_b32 v15, v35 offset:624
	ds_read_b32 v18, v35 offset:756
	ds_read_b32 v19, v35 offset:888
	ds_read_b32 v22, v35 offset:1020
	s_waitcnt lgkmcnt(0)
	v_cvt_pk_bf16_f32 v16, v5, v9
	v_cvt_pk_bf16_f32 v17, v11, v13
	v_cvt_pk_bf16_f32 v18, v15, v18
	v_mov_b32_e32 v15, v3
	v_cvt_pk_bf16_f32 v19, v19, v22
	v_lshl_add_u64 v[20:21], v[20:21], 0, v[14:15]
	global_store_dwordx4 v[20:21], v[16:19], off
	s_waitcnt lgkmcnt(0)
	s_add_i32 s2, s41, 0x3c0
	s_addk_i32 s38, 0x7800
	s_add_i32 s39, s39, 0x1e00000
	s_cmpk_gt_i32 s41, 0x8f
	s_mov_b32 s41, s2
	s_cbranch_scc1 .LBB0_396

; #define LAS __attribute__((address_space(3)))
; DI unsigned pk2(float lo, float hi) { typedef float v2f __attribute__((ext_vector_type(2))); typedef __bf16 v2b __attribute__((ext_vector_type(2))); v2f v = {lo, hi}; v2b b = __builtin_convertvector(v, v2b); return __builtin_bit_cast(unsigned, b); }
;     ...
;         bf16_t* dst = dest_rows(mode, n0, K, d0, d1);
;         const int c = lane & 7;
; #pragma unroll
;         for (int jj = 0; jj < 4; ++jj) { const int n = (lane >> 3) + 8 * jj; const LAS float* s = scr + (8 * c) * 33 + n;
;             u32x4 o; o.x = pk2(s[0 * 33], s[1 * 33]); o.y = pk2(s[2 * 33], s[3 * 33]); o.z = pk2(s[4 * 33], s[5 * 33]); o.w = pk2(s[6 * 33], s[7 * 33]);
;             *(u32x4*)(dst + (size_t)n * K + k0 + 8 * c) = o; }
;         asm volatile("s_waitcnt lgkmcnt(0)" ::: "memory");
.LBB0_399:
	ds_write2_b32 v14, v12, v13 offset0:140 offset1:206
	s_waitcnt lgkmcnt(0)
	s_mul_hi_i32 s9, s8, 0x300
	s_mulk_i32 s8, 0x300
	s_add_u32 s8, s12, s8
	ds_read_b32 v5, v35
	ds_read_b32 v9, v35 offset:132
	ds_read_b32 v11, v35 offset:264
	ds_read_b32 v12, v35 offset:396
	ds_read_b32 v13, v35 offset:528
	ds_read_b32 v16, v35 offset:660
	ds_read_b32 v17, v35 offset:792
	ds_read_b32 v18, v35 offset:924
	s_addc_u32 s9, s13, s9
	s_lshl_b64 s[6:7], s[6:7], 1
	s_add_u32 s6, s8, s6
	s_addc_u32 s7, s9, s7
	v_lshl_add_u64 v[14:15], s[6:7], 0, v[2:3]
	s_waitcnt lgkmcnt(0)
	v_cvt_pk_bf16_f32 v10, v5, v9
	v_mov_b32_e32 v9, v3
	v_cvt_pk_bf16_f32 v11, v11, v12
	v_cvt_pk_bf16_f32 v12, v13, v16
	v_cvt_pk_bf16_f32 v13, v17, v18
	v_lshl_add_u64 v[14:15], v[14:15], 0, v[8:9]
	global_store_dwordx4 v[14:15], v[10:13], off
	ds_read_b32 v5, v35 offset:32
	ds_read_b32 v9, v35 offset:164
	ds_read_b32 v11, v35 offset:296
	ds_read_b32 v12, v35 offset:428
	ds_read_b32 v13, v35 offset:560
	ds_read_b32 v16, v35 offset:692
	ds_read_b32 v17, v35 offset:824
	ds_read_b32 v18, v35 offset:956
	s_waitcnt lgkmcnt(0)
	v_cvt_pk_bf16_f32 v11, v11, v12
	v_cvt_pk_bf16_f32 v10, v5, v9
	v_cvt_pk_bf16_f32 v12, v13, v16
	v_add_co_u32_e32 v16, vcc, s34, v14
	v_cvt_pk_bf16_f32 v13, v17, v18
	s_nop 0
	v_addc_co_u32_e32 v17, vcc, 0, v15, vcc
	global_store_dwordx4 v[16:17], v[10:13], off offset:2048
	ds_read_b32 v5, v35 offset:64
	ds_read_b32 v9, v35 offset:196
	ds_read_b32 v11, v35 offset:328
	ds_read_b32 v12, v35 offset:460
	ds_read_b32 v13, v35 offset:592
	ds_read_b32 v16, v35 offset:724
	ds_read_b32 v17, v35 offset:856
	ds_read_b32 v18, v35 offset:988
	s_waitcnt lgkmcnt(0)
	v_cvt_pk_bf16_f32 v11, v11, v12
	v_cvt_pk_bf16_f32 v10, v5, v9
	v_cvt_pk_bf16_f32 v12, v13, v16
	v_add_co_u32_e32 v16, vcc, s35, v14
	v_cvt_pk_bf16_f32 v13, v17, v18
	s_nop 0
	v_addc_co_u32_e32 v17, vcc, 0, v15, vcc
	global_store_dwordx4 v[16:17], v[10:13], off
	ds_read_b32 v5, v35 offset:96
	ds_read_b32 v9, v35 offset:228
	ds_read_b32 v11, v35 offset:360
	ds_read_b32 v12, v35 offset:492
	ds_read_b32 v13, v35 offset:624
	ds_read_b32 v16, v35 offset:756
	ds_read_b32 v17, v35 offset:888
	ds_read_b32 v18, v35 offset:1020
	v_add_co_u32_e32 v14, vcc, 0x4000, v14
	s_waitcnt lgkmcnt(0)
	v_cvt_pk_bf16_f32 v10, v5, v9
	v_cvt_pk_bf16_f32 v11, v11, v12
	v_cvt_pk_bf16_f32 v12, v13, v16
	v_cvt_pk_bf16_f32 v13, v17, v18
	v_addc_co_u32_e32 v15, vcc, 0, v15, vcc
	global_store_dwordx4 v[14:15], v[10:13], off offset:2048
	s_waitcnt lgkmcnt(0)
	s_add_i32 s6, s36, 0x3c0
	s_addk_i32 s14, 0x7800
	s_cmpk_lt_i32 s36, 0xfcd0
	s_mov_b32 s36, s6
	s_cbranch_scc0 .LBB0_432

; #define LAS __attribute__((address_space(3)))
; DI unsigned pk2(float lo, float hi) { typedef float v2f __attribute__((ext_vector_type(2))); typedef __bf16 v2b __attribute__((ext_vector_type(2))); v2f v = {lo, hi}; v2b b = __builtin_convertvector(v, v2b); return __builtin_bit_cast(unsigned, b); }
;     ...
;         bf16_t* dst = dest_rows(mode, n0, K, d0, d1);
;         const int c = lane & 7;
; #pragma unroll
;         for (int jj = 0; jj < 4; ++jj) { const int n = (lane >> 3) + 8 * jj; const LAS float* s = scr + (8 * c) * 33 + n;
;             u32x4 o; o.x = pk2(s[0 * 33], s[1 * 33]); o.y = pk2(s[2 * 33], s[3 * 33]); o.z = pk2(s[4 * 33], s[5 * 33]); o.w = pk2(s[6 * 33], s[7 * 33]);
;             *(u32x4*)(dst + (size_t)n * K + k0 + 8 * c) = o; }
;         asm volatile("s_waitcnt lgkmcnt(0)" ::: "memory");
.LBB0_434:
	ds_write2_b32 v11, v16, v17 offset0:140 offset1:206
	s_waitcnt lgkmcnt(0)
	s_lshl_b64 s[6:7], s[6:7], 9
	s_add_u32 s6, s10, s6
	ds_read_b32 v7, v35
	ds_read_b32 v9, v35 offset:132
	ds_read_b32 v11, v35 offset:264
	ds_read_b32 v13, v35 offset:396
	ds_read_b32 v16, v35 offset:528
	ds_read_b32 v17, v35 offset:660
	ds_read_b32 v20, v35 offset:792
	ds_read_b32 v21, v35 offset:924
	s_addc_u32 s7, s11, s7
	s_lshl_b64 s[4:5], s[4:5], 1
	s_add_u32 s4, s6, s4
	s_addc_u32 s5, s7, s5
	v_lshl_add_u64 v[18:19], s[4:5], 0, v[2:3]
	s_waitcnt lgkmcnt(0)
	v_cvt_pk_bf16_f32 v14, v7, v9
	v_mov_b32_e32 v7, v3
	v_cvt_pk_bf16_f32 v15, v11, v13
	v_cvt_pk_bf16_f32 v16, v16, v17
	v_cvt_pk_bf16_f32 v17, v20, v21
	v_lshl_add_u64 v[20:21], v[18:19], 0, v[6:7]
	global_store_dwordx4 v[20:21], v[14:17], off
	ds_read_b32 v7, v35 offset:32
	ds_read_b32 v9, v35 offset:164
	ds_read_b32 v11, v35 offset:296
	ds_read_b32 v13, v35 offset:428
	ds_read_b32 v16, v35 offset:560
	ds_read_b32 v17, v35 offset:692
	ds_read_b32 v20, v35 offset:824
	ds_read_b32 v21, v35 offset:956
	s_waitcnt lgkmcnt(0)
	v_cvt_pk_bf16_f32 v14, v7, v9
	v_mov_b32_e32 v9, v3
	v_cvt_pk_bf16_f32 v15, v11, v13
	v_cvt_pk_bf16_f32 v16, v16, v17
	v_cvt_pk_bf16_f32 v17, v20, v21
	v_lshl_add_u64 v[20:21], v[18:19], 0, v[8:9]
	global_store_dwordx4 v[20:21], v[14:17], off
	ds_read_b32 v7, v35 offset:64
	ds_read_b32 v9, v35 offset:196
	ds_read_b32 v11, v35 offset:328
	ds_read_b32 v13, v35 offset:460
	ds_read_b32 v16, v35 offset:592
	ds_read_b32 v17, v35 offset:724
	ds_read_b32 v20, v35 offset:856
	ds_read_b32 v21, v35 offset:988
	s_waitcnt lgkmcnt(0)
	v_cvt_pk_bf16_f32 v15, v11, v13
	v_mov_b32_e32 v11, v3
	v_cvt_pk_bf16_f32 v14, v7, v9
	v_cvt_pk_bf16_f32 v16, v16, v17
	v_cvt_pk_bf16_f32 v17, v20, v21
	v_lshl_add_u64 v[20:21], v[18:19], 0, v[10:11]
	global_store_dwordx4 v[20:21], v[14:17], off
	ds_read_b32 v7, v35 offset:96
	ds_read_b32 v9, v35 offset:228
	ds_read_b32 v11, v35 offset:360
	ds_read_b32 v13, v35 offset:492
	ds_read_b32 v16, v35 offset:624
	ds_read_b32 v17, v35 offset:756
	ds_read_b32 v20, v35 offset:888
	ds_read_b32 v21, v35 offset:1020
	s_waitcnt lgkmcnt(0)
	v_cvt_pk_bf16_f32 v15, v11, v13
	v_mov_b32_e32 v13, v3
	v_cvt_pk_bf16_f32 v14, v7, v9
	v_cvt_pk_bf16_f32 v16, v16, v17
	v_cvt_pk_bf16_f32 v17, v20, v21
	v_lshl_add_u64 v[18:19], v[18:19], 0, v[12:13]
	global_store_dwordx4 v[18:19], v[14:17], off
	s_waitcnt lgkmcnt(0)
	s_add_i32 s4, s33, 0x3c0
	s_addk_i32 s12, 0x7800
	s_cmpk_lt_i32 s33, 0xfcc0
	s_mov_b32 s33, s4
	s_cbranch_scc0 .LBB0_467

; DI unsigned pk2(float lo, float hi) { typedef float v2f __attribute__((ext_vector_type(2))); typedef __bf16 v2b __attribute__((ext_vector_type(2))); v2f v = {lo, hi}; v2b b = __builtin_convertvector(v, v2b); return __builtin_bit_cast(unsigned, b); }
; DI void atomic_addf(float* p, float v) { __builtin_amdgcn_global_atomic_fadd_f32((__attribute__((address_space(1))) float*)p, v); }
; DI float quad_sum(float s) { s += __shfl_xor(s, 16); s += __shfl_xor(s, 32); return s; }
;     DI void operator()(const f32x4 (&acc)[2][2][4][2], const Unit& u, int wr, int wc, int fr, int fq) const {
;     ...
;                         u32x4 w; w.x = pk2(v[0], v[1]); w.y = pk2(v[2], v[3]); w.z = pk2(v[4], v[5]); w.w = pk2(v[6], v[7]);
;                         *(u32x4*)(dst + cw) = w;
;                         float s2 = 0.f;
; #pragma unroll
;                         for (int i = 0; i < 8; ++i) s2 += v[i] * v[i];
;                         s2 = quad_sum(s2);
;                         if (fq == 0) { if (isqm) *pp = s2; else atomic_addf(pp, s2); }
.LBB0_645:
	v_lshlrev_b32_e32 v140, 1, v142
	v_cvt_pk_bf16_f32 v176, v168, v169
	v_cvt_pk_bf16_f32 v177, v126, v127
	v_cvt_pk_bf16_f32 v178, v124, v125
	v_cvt_pk_bf16_f32 v179, v122, v123
	v_lshl_add_u64 v[170:171], v[170:171], 0, v[140:141]
	global_store_dwordx4 v[170:171], v[176:179], off
	v_pk_mul_f32 v[170:171], v[168:169], v[168:169]
	v_xor_b32_e32 v167, 16, v175
	v_pk_mul_f32 v[176:177], v[126:127], v[126:127]
	v_add_f32_e32 v140, v170, v171
	v_add_f32_e32 v140, v176, v140
	v_pk_mul_f32 v[178:179], v[124:125], v[124:125]
	v_add_f32_e32 v140, v177, v140
	v_and_b32_e32 v170, 64, v175
	v_add_f32_e32 v140, v178, v140
	v_add_u32_e32 v170, 64, v170
	v_pk_mul_f32 v[180:181], v[122:123], v[122:123]
	v_add_f32_e32 v140, v179, v140
	v_cmp_lt_i32_e32 vcc, v167, v170
	v_add_f32_e32 v140, v180, v140
	v_add_f32_e32 v140, v181, v140
	v_cndmask_b32_e32 v167, v175, v167, vcc
	v_lshlrev_b32_e32 v167, 2, v167
	ds_bpermute_b32 v167, v167, v140
	s_waitcnt lgkmcnt(0)
	v_add_f32_e32 v140, v140, v167
	v_xor_b32_e32 v167, 32, v175
	v_cmp_lt_i32_e32 vcc, v167, v170
	s_nop 1
	v_cndmask_b32_e32 v167, v175, v167, vcc
	v_lshlrev_b32_e32 v167, 2, v167
	ds_bpermute_b32 v167, v167, v140
	s_and_saveexec_b64 s[6:7], s[2:3]
	s_cbranch_execz .LBB0_650
	s_waitcnt lgkmcnt(0)
	v_add_f32_e32 v140, v140, v167
	s_cmpk_lt_u32 s94, 0x680
	s_mov_b64 s[8:9], -1
	s_cbranch_scc0 .LBB0_648
	global_atomic_add_f32 v[120:121], v140, off
	s_mov_b64 s[8:9], 0
.LBB0_648:
	s_andn2_b64 vcc, exec, s[8:9]
	s_cbranch_vccnz .LBB0_650
	global_store_dword v[120:121], v140, off

; DI unsigned pk2(float lo, float hi) { typedef float v2f __attribute__((ext_vector_type(2))); typedef __bf16 v2b __attribute__((ext_vector_type(2))); v2f v = {lo, hi}; v2b b = __builtin_convertvector(v, v2b); return __builtin_bit_cast(unsigned, b); }
; __device__ __forceinline__ f32x2 gelu_pk(f32x2 v) {
;     const f32x2 av = __builtin_elementwise_abs(v), d = av * 0.2316418882f + 1.0f;
;     f32x2 t; t.x = __builtin_amdgcn_rcpf(d.x); t.y = __builtin_amdgcn_rcpf(d.y);
;     f32x2 q = t * 0.5307027145f + (-0.7265760135f); q = q * t + 0.7107068705f; q = q * t + (-0.142248368f); q = q * t + 0.127414796f; q = q * t;
;     const f32x2 s = (v * v) * (-0.72134752044f);
;     f32x2 e; e.x = __builtin_amdgcn_exp2f(s.x); e.y = __builtin_amdgcn_exp2f(s.y);
;     const f32x2 m = v * (q * e), r = v - m;
;     f32x2 o; o.x = v.x < 0.f ? m.x : r.x; o.y = v.y < 0.f ? m.y : r.y; return o;
; }
;     DI void operator()(const f32x4 (&acc)[2][2][4][2], const Unit& u, int wr, int wc, int fr, int fq) const {
;     ...
;                     if (c128 < 1024) {
; #pragma unroll
;                         for (int i = 0; i < 8; i += 2) { const f32x2 g = pg8::gelu_pk((f32x2){v[i], v[i + 1]}); v[i] = g.x; v[i + 1] = g.y; }
;                         const bool isv = c128 >= 512;
;                         u32x4 w; w.x = pk2(v[0], v[1]); w.y = pk2(v[2], v[3]); w.z = pk2(v[4], v[5]); w.w = pk2(v[6], v[7]);
;                         *(u32x4*)((isv ? Vg : U) + (size_t)row * 512 + (c128 & 511) + cw) = w;
.LBB0_652:
	v_lshlrev_b64 v[120:121], 4, v[154:155]
	v_or_b32_e32 v120, s97, v120
	s_andn2_b64 vcc, exec, s[6:7]
	v_lshlrev_b32_e32 v140, 1, v142
	s_cbranch_vccnz .LBB0_657
	v_and_b32_e32 v171, 0x7fffffff, v169
	v_and_b32_e32 v170, 0x7fffffff, v168
	v_pk_fma_f32 v[170:171], v[170:171], s[14:15], 1.0 op_sel_hi:[1,0,0]
	v_mov_b64_e32 v[176:177], s[96:97]
	v_rcp_f32_e32 v170, v170
	v_rcp_f32_e32 v171, v171
	v_cmp_gt_f32_e32 vcc, 0, v168
	v_cmp_gt_f32_e64 s[6:7], 0, v169
	s_cmp_gt_i32 s60, 1
	v_pk_fma_f32 v[178:179], v[170:171], s[42:43], v[176:177] op_sel_hi:[1,0,0]
	s_nop 0
	v_pk_fma_f32 v[178:179], v[170:171], v[178:179], s[0:1] op_sel_hi:[1,1,0]
	s_nop 0
	v_pk_fma_f32 v[178:179], v[170:171], v[178:179], s[50:51] op_sel_hi:[1,1,0]
	s_nop 0
	v_pk_fma_f32 v[178:179], v[170:171], v[178:179], s[34:35] op_sel_hi:[1,1,0]
	s_nop 0
	v_pk_mul_f32 v[170:171], v[170:171], v[178:179]
	v_pk_mul_f32 v[178:179], v[168:169], v[168:169]
	s_nop 0
	v_pk_mul_f32 v[178:179], v[178:179], s[46:47] op_sel_hi:[1,0]
	s_nop 0
	v_exp_f32_e32 v178, v178
	v_exp_f32_e32 v179, v179
	s_nop 0
	v_pk_mul_f32 v[170:171], v[178:179], v[170:171]
	s_nop 0
	v_pk_mul_f32 v[178:179], v[168:169], v[170:171]
	v_pk_fma_f32 v[170:171], v[168:169], v[170:171], v[168:169] neg_lo:[1,0,0] neg_hi:[1,0,0]
	s_nop 0
	v_cndmask_b32_e64 v169, v171, v179, s[6:7]
	v_cndmask_b32_e32 v168, v170, v178, vcc
	v_and_b32_e32 v171, 0x7fffffff, v127
	v_and_b32_e32 v170, 0x7fffffff, v126
	v_pk_fma_f32 v[170:171], v[170:171], s[14:15], 1.0 op_sel_hi:[1,0,0]
	v_cmp_gt_f32_e32 vcc, 0, v126
	v_rcp_f32_e32 v170, v170
	v_rcp_f32_e32 v171, v171
	v_cmp_gt_f32_e64 s[6:7], 0, v127
	v_pk_fma_f32 v[178:179], v[170:171], s[42:43], v[176:177] op_sel_hi:[1,0,0]
	s_nop 0
	v_pk_fma_f32 v[178:179], v[170:171], v[178:179], s[0:1] op_sel_hi:[1,1,0]
	s_nop 0
	v_pk_fma_f32 v[178:179], v[170:171], v[178:179], s[50:51] op_sel_hi:[1,1,0]
	s_nop 0
	v_pk_fma_f32 v[178:179], v[170:171], v[178:179], s[34:35] op_sel_hi:[1,1,0]
	s_nop 0
	v_pk_mul_f32 v[170:171], v[170:171], v[178:179]
	v_pk_mul_f32 v[178:179], v[126:127], v[126:127]
	s_nop 0
	v_pk_mul_f32 v[178:179], v[178:179], s[46:47] op_sel_hi:[1,0]
	s_nop 0
	v_exp_f32_e32 v178, v178
	v_exp_f32_e32 v179, v179
	s_nop 0
	v_pk_mul_f32 v[170:171], v[178:179], v[170:171]
	s_nop 0
	v_pk_mul_f32 v[178:179], v[126:127], v[170:171]
	v_pk_fma_f32 v[170:171], v[126:127], v[170:171], v[126:127] neg_lo:[1,0,0] neg_hi:[1,0,0]
	s_nop 0
	v_cndmask_b32_e64 v127, v171, v179, s[6:7]
	v_cndmask_b32_e32 v126, v170, v178, vcc
	v_and_b32_e32 v171, 0x7fffffff, v125
	v_and_b32_e32 v170, 0x7fffffff, v124
	v_pk_fma_f32 v[170:171], v[170:171], s[14:15], 1.0 op_sel_hi:[1,0,0]
	v_cmp_gt_f32_e32 vcc, 0, v124
	v_rcp_f32_e32 v170, v170
	v_rcp_f32_e32 v171, v171
	v_cmp_gt_f32_e64 s[6:7], 0, v125
	v_pk_fma_f32 v[178:179], v[170:171], s[42:43], v[176:177] op_sel_hi:[1,0,0]
	s_nop 0
	v_pk_fma_f32 v[178:179], v[170:171], v[178:179], s[0:1] op_sel_hi:[1,1,0]
	s_nop 0
	v_pk_fma_f32 v[178:179], v[170:171], v[178:179], s[50:51] op_sel_hi:[1,1,0]
	s_nop 0
	v_pk_fma_f32 v[178:179], v[170:171], v[178:179], s[34:35] op_sel_hi:[1,1,0]
	s_nop 0
	v_pk_mul_f32 v[170:171], v[170:171], v[178:179]
	v_pk_mul_f32 v[178:179], v[124:125], v[124:125]
	s_nop 0
	v_pk_mul_f32 v[178:179], v[178:179], s[46:47] op_sel_hi:[1,0]
	s_nop 0
	v_exp_f32_e32 v178, v178
	v_exp_f32_e32 v179, v179
	s_nop 0
	v_pk_mul_f32 v[170:171], v[178:179], v[170:171]
	s_nop 0
	v_pk_mul_f32 v[178:179], v[124:125], v[170:171]
	v_pk_fma_f32 v[170:171], v[124:125], v[170:171], v[124:125] neg_lo:[1,0,0] neg_hi:[1,0,0]
	s_nop 0
	v_cndmask_b32_e64 v125, v171, v179, s[6:7]
	v_cndmask_b32_e32 v124, v170, v178, vcc
	v_and_b32_e32 v171, 0x7fffffff, v123
	v_and_b32_e32 v170, 0x7fffffff, v122
	v_pk_fma_f32 v[170:171], v[170:171], s[14:15], 1.0 op_sel_hi:[1,0,0]
	v_cmp_gt_f32_e64 s[6:7], 0, v123
	v_rcp_f32_e32 v170, v170
	v_rcp_f32_e32 v171, v171
	v_cmp_gt_f32_e32 vcc, 0, v122
	v_cvt_pk_bf16_f32 v178, v124, v125
	v_pk_fma_f32 v[176:177], v[170:171], s[42:43], v[176:177] op_sel_hi:[1,0,0]
	s_nop 0
	v_pk_fma_f32 v[176:177], v[170:171], v[176:177], s[0:1] op_sel_hi:[1,1,0]
	s_nop 0
	v_pk_fma_f32 v[176:177], v[170:171], v[176:177], s[50:51] op_sel_hi:[1,1,0]
	s_nop 0
	v_pk_fma_f32 v[176:177], v[170:171], v[176:177], s[34:35] op_sel_hi:[1,1,0]
	s_nop 0
	v_pk_mul_f32 v[170:171], v[170:171], v[176:177]
	v_pk_mul_f32 v[176:177], v[122:123], v[122:123]
	s_nop 0
	v_pk_mul_f32 v[176:177], v[176:177], s[46:47] op_sel_hi:[1,0]
	s_nop 0
	v_exp_f32_e32 v176, v176
	v_exp_f32_e32 v177, v177
	s_nop 0
	v_pk_mul_f32 v[170:171], v[176:177], v[170:171]
	s_nop 0
	v_pk_mul_f32 v[176:177], v[122:123], v[170:171]
	v_pk_fma_f32 v[170:171], v[122:123], v[170:171], v[122:123] neg_lo:[1,0,0] neg_hi:[1,0,0]
	s_nop 0
	v_cndmask_b32_e64 v123, v171, v177, s[6:7]
	s_cselect_b32 s6, s15, s1
	s_cselect_b32 s7, s35, s43
	s_and_b32 s8, s94, 0x100
	v_cndmask_b32_e32 v122, v170, v176, vcc
	s_lshl_b32 s48, s8, 1
	v_lshl_add_u64 v[170:171], s[6:7], 0, v[158:159]
	v_lshl_add_u64 v[170:171], v[170:171], 0, s[48:49]
	s_cmp_lt_i32 s60, 2
	v_cvt_pk_bf16_f32 v176, v168, v169
	v_cvt_pk_bf16_f32 v177, v126, v127
	v_cvt_pk_bf16_f32 v179, v122, v123
	v_lshl_add_u64 v[170:171], v[170:171], 0, v[140:141]
	global_store_dwordx4 v[170:171], v[176:179], off
	s_cbranch_scc1 .LBB0_657
; DI float quad_sum(float s) { s += __shfl_xor(s, 16); s += __shfl_xor(s, 32); return s; }
;     DI void operator()(const f32x4 (&acc)[2][2][4][2], const Unit& u, int wr, int wc, int fr, int fq) const {
;     ...
;                         if (isv) {
;                             float s1 = 0.f, s2 = 0.f;
; #pragma unroll
;                             for (int i = 0; i < 8; ++i) { s1 += v[i]; s2 += v[i] * v[i]; }
;                             s1 = quad_sum(s1); s2 = quad_sum(s2);
;                             if (fq == 0) { float* d = VST + ((size_t)row * 16 + ((c128 - 512) >> 7) * 4 + wc) * 2; d[0] = s1; d[1] = s2; }
;                         }
	v_mov_b32_e32 v170, v141
	v_mov_b32_e32 v171, v169
	v_pk_add_f32 v[170:171], v[168:169], v[170:171]
	v_pk_mul_f32 v[176:177], v[168:169], v[168:169]
	v_pk_mul_f32 v[178:179], v[126:127], v[126:127]
	v_mov_b32_e32 v171, v177
	v_pk_mov_b32 v[168:169], v[168:169], v[176:177] op_sel:[1,0]
	v_pk_mul_f32 v[180:181], v[124:125], v[124:125]
	v_pk_add_f32 v[168:169], v[168:169], v[170:171]
	v_mov_b32_e32 v170, v126
	v_mov_b32_e32 v171, v178
	v_pk_add_f32 v[168:169], v[170:171], v[168:169]
	v_mov_b32_e32 v178, v127
	v_and_b32_e32 v184, 64, v175
	v_pk_add_f32 v[126:127], v[178:179], v[168:169]
	v_mov_b32_e32 v168, v124
	v_mov_b32_e32 v169, v180
	v_pk_mul_f32 v[182:183], v[122:123], v[122:123]
	s_waitcnt lgkmcnt(0)
	v_xor_b32_e32 v167, 16, v175
	v_add_u32_e32 v184, 64, v184
	v_pk_add_f32 v[126:127], v[168:169], v[126:127]
	v_mov_b32_e32 v180, v125
	v_cmp_lt_i32_e32 vcc, v167, v184
	v_pk_add_f32 v[124:125], v[180:181], v[126:127]
	v_mov_b32_e32 v126, v122
	v_mov_b32_e32 v127, v182
	v_cndmask_b32_e32 v167, v175, v167, vcc
	v_pk_add_f32 v[124:125], v[126:127], v[124:125]
	v_mov_b32_e32 v182, v123
	v_lshlrev_b32_e32 v167, 2, v167
	v_pk_add_f32 v[122:123], v[182:183], v[124:125]
	ds_bpermute_b32 v124, v167, v122
	ds_bpermute_b32 v125, v167, v123
	v_xor_b32_e32 v126, 32, v175
	v_cmp_lt_i32_e32 vcc, v126, v184
	s_waitcnt lgkmcnt(0)
	v_pk_add_f32 v[122:123], v[122:123], v[124:125]
	v_cndmask_b32_e32 v126, v175, v126, vcc
	v_lshlrev_b32_e32 v126, 2, v126
	ds_bpermute_b32 v124, v126, v122
	ds_bpermute_b32 v125, v126, v123
	s_and_saveexec_b64 s[6:7], s[2:3]
	s_cbranch_execz .LBB0_656
	s_add_i32 s8, s94, 0xfffffe00
	s_lshr_b32 s48, s8, 5
	v_lshl_add_u64 v[126:127], v[120:121], 0, s[48:49]
	v_lshl_add_u64 v[126:127], v[126:127], 3, s[80:81]
	s_waitcnt lgkmcnt(0)
	v_pk_add_f32 v[122:123], v[122:123], v[124:125]
	global_store_dwordx2 v[126:127], v[122:123], off

; DI float quad_sum(float s) { s += __shfl_xor(s, 16); s += __shfl_xor(s, 32); return s; }
;     DI void operator()(const f32x4 (&acc)[2][2][4][2], const Unit& u, int wr, int wc, int fr, int fq) const {
;     ...
;                         for (int i = 0; i < 4; ++i) v[4 * n + i] = acc[ai][bj][m][n][i] * rs;
;                     if (c128 < 1024) {
; #pragma unroll
;                         for (int i = 0; i < 8; i += 2) { const f32x2 g = pg8::gelu_pk((f32x2){v[i], v[i + 1]}); v[i] = g.x; v[i + 1] = g.y; }
;                         const bool isv = c128 >= 512;
;                         u32x4 w; w.x = pk2(v[0], v[1]); w.y = pk2(v[2], v[3]); w.z = pk2(v[4], v[5]); w.w = pk2(v[6], v[7]);
;                         *(u32x4*)((isv ? Vg : U) + (size_t)row * 512 + (c128 & 511) + cw) = w;
;                         if (isv) {
;                             float s1 = 0.f, s2 = 0.f;
; #pragma unroll
;                             for (int i = 0; i < 8; ++i) { s1 += v[i]; s2 += v[i] * v[i]; }
;                             s1 = quad_sum(s1); s2 = quad_sum(s2);
;                             if (fq == 0) { float* d = VST + ((size_t)row * 16 + ((c128 - 512) >> 7) * 4 + wc) * 2; d[0] = s1; d[1] = s2; }
;                         }
;                     } else if (c128 < 2176) {
;                         bf16_t* dst; float* pp; const bool isqm = c128 >= 1664;
;                         if (c128 < 1408) { dst = CQ + (size_t)row * 384 + (c128 - 1024); pp = CQP + row; }
;                         else if (c128 < 1664) { dst = CKV + (size_t)row * 256 + (c128 - 1408); pp = CKVP + row; }
;                         else { dst = QM + (size_t)row * 512 + (c128 - 1664); pp = QMP + (size_t)row * 16 + ((c128 - 1664) >> 7) * 4 + wc; }
;                         u32x4 w; w.x = pk2(v[0], v[1]); w.y = pk2(v[2], v[3]); w.z = pk2(v[4], v[5]); w.w = pk2(v[6], v[7]);
;                         *(u32x4*)(dst + cw) = w;
;                         float s2 = 0.f;
; #pragma unroll
;                         for (int i = 0; i < 8; ++i) s2 += v[i] * v[i];
;                         s2 = quad_sum(s2);
;                         if (fq == 0) { if (isqm) *pp = s2; else atomic_addf(pp, s2); }
;                     } else if (c128 == 2176) {
;                         if (wc == 0) { float* d = KR + (size_t)row * 32 + 8 * fq; *(f32x4*)d = (f32x4){v[0], v[1], v[2], v[3]}; *(f32x4*)(d + 4) = (f32x4){v[4], v[5], v[6], v[7]}; }
.LBB0_657:
	s_or_b32 s37, s94, 0x80
	s_waitcnt lgkmcnt(0)
	v_mov_b32_e32 v167, v166
	s_cmpk_gt_i32 s37, 0x3ff
	v_pk_mul_f32 v[116:117], v[116:117], v[166:167]
	v_pk_mul_f32 v[118:119], v[118:119], v[166:167]
	v_pk_mul_f32 v[112:113], v[112:113], v[166:167]
	v_pk_mul_f32 v[114:115], v[114:115], v[166:167]
	s_cselect_b64 s[58:59], -1, 0
	s_cmpk_lt_i32 s37, 0x400
	s_mov_b64 s[6:7], -1
	s_cbranch_scc1 .LBB0_678
	s_cmpk_lt_u32 s37, 0x880
	s_cbranch_scc1 .LBB0_662
	s_cmp_lg_u32 s60, 8
	s_cselect_b64 s[6:7], -1, 0
	s_or_b64 s[6:7], s[72:73], s[6:7]
	s_and_b64 vcc, exec, s[6:7]
	s_cbranch_vccnz .LBB0_661
	v_lshlrev_b64 v[122:123], 7, v[154:155]
	v_lshl_add_u64 v[122:123], v[144:145], 0, v[122:123]
	global_store_dwordx4 v[122:123], v[116:119], off
	global_store_dwordx4 v[122:123], v[112:115], off offset:16

; DI unsigned pk2(float lo, float hi) { typedef float v2f __attribute__((ext_vector_type(2))); typedef __bf16 v2b __attribute__((ext_vector_type(2))); v2f v = {lo, hi}; v2b b = __builtin_convertvector(v, v2b); return __builtin_bit_cast(unsigned, b); }
; DI void atomic_addf(float* p, float v) { __builtin_amdgcn_global_atomic_fadd_f32((__attribute__((address_space(1))) float*)p, v); }
; DI float quad_sum(float s) { s += __shfl_xor(s, 16); s += __shfl_xor(s, 32); return s; }
;     DI void operator()(const f32x4 (&acc)[2][2][4][2], const Unit& u, int wr, int wc, int fr, int fq) const {
;     ...
;                         u32x4 w; w.x = pk2(v[0], v[1]); w.y = pk2(v[2], v[3]); w.z = pk2(v[4], v[5]); w.w = pk2(v[6], v[7]);
;                         *(u32x4*)(dst + cw) = w;
;                         float s2 = 0.f;
; #pragma unroll
;                         for (int i = 0; i < 8; ++i) s2 += v[i] * v[i];
;                         s2 = quad_sum(s2);
;                         if (fq == 0) { if (isqm) *pp = s2; else atomic_addf(pp, s2); }
.LBB0_671:
	v_cvt_pk_bf16_f32 v160, v116, v117
	v_cvt_pk_bf16_f32 v161, v118, v119
	v_cvt_pk_bf16_f32 v162, v112, v113
	v_cvt_pk_bf16_f32 v163, v114, v115
	v_lshl_add_u64 v[124:125], v[124:125], 0, v[140:141]
	global_store_dwordx4 v[124:125], v[160:163], off
	v_pk_mul_f32 v[124:125], v[116:117], v[116:117]
	v_pk_mul_f32 v[126:127], v[118:119], v[118:119]
	v_add_f32_e32 v124, v124, v125
	v_add_f32_e32 v124, v126, v124
	v_pk_mul_f32 v[160:161], v[112:113], v[112:113]
	v_add_f32_e32 v124, v127, v124
	v_and_b32_e32 v126, 64, v175
	v_add_f32_e32 v124, v160, v124
	v_xor_b32_e32 v125, 16, v175
	v_add_u32_e32 v126, 64, v126
	v_pk_mul_f32 v[162:163], v[114:115], v[114:115]
	v_add_f32_e32 v124, v161, v124
	v_cmp_lt_i32_e32 vcc, v125, v126
	v_add_f32_e32 v124, v162, v124
	v_add_f32_e32 v124, v163, v124
	v_cndmask_b32_e32 v125, v175, v125, vcc
	v_lshlrev_b32_e32 v125, 2, v125
	ds_bpermute_b32 v125, v125, v124
	s_waitcnt lgkmcnt(0)
	v_add_f32_e32 v124, v124, v125
	v_xor_b32_e32 v125, 32, v175
	v_cmp_lt_i32_e32 vcc, v125, v126
	s_nop 1
	v_cndmask_b32_e32 v125, v175, v125, vcc
	v_lshlrev_b32_e32 v125, 2, v125
	ds_bpermute_b32 v125, v125, v124
	s_and_saveexec_b64 s[6:7], s[2:3]
	s_cbranch_execz .LBB0_676
	s_waitcnt lgkmcnt(0)
	v_add_f32_e32 v124, v124, v125
	s_cmpk_gt_u32 s37, 0x67f
	s_mov_b64 s[8:9], -1
	s_cbranch_scc1 .LBB0_674
	global_atomic_add_f32 v[122:123], v124, off
	s_mov_b64 s[8:9], 0
.LBB0_674:
	s_andn2_b64 vcc, exec, s[8:9]
	s_cbranch_vccnz .LBB0_676
	global_store_dword v[122:123], v124, off

; DI unsigned pk2(float lo, float hi) { typedef float v2f __attribute__((ext_vector_type(2))); typedef __bf16 v2b __attribute__((ext_vector_type(2))); v2f v = {lo, hi}; v2b b = __builtin_convertvector(v, v2b); return __builtin_bit_cast(unsigned, b); }
; __device__ __forceinline__ f32x2 gelu_pk(f32x2 v) {
;     const f32x2 av = __builtin_elementwise_abs(v), d = av * 0.2316418882f + 1.0f;
;     f32x2 t; t.x = __builtin_amdgcn_rcpf(d.x); t.y = __builtin_amdgcn_rcpf(d.y);
;     f32x2 q = t * 0.5307027145f + (-0.7265760135f); q = q * t + 0.7107068705f; q = q * t + (-0.142248368f); q = q * t + 0.127414796f; q = q * t;
;     const f32x2 s = (v * v) * (-0.72134752044f);
;     f32x2 e; e.x = __builtin_amdgcn_exp2f(s.x); e.y = __builtin_amdgcn_exp2f(s.y);
;     const f32x2 m = v * (q * e), r = v - m;
;     f32x2 o; o.x = v.x < 0.f ? m.x : r.x; o.y = v.y < 0.f ? m.y : r.y; return o;
; }
;     DI void operator()(const f32x4 (&acc)[2][2][4][2], const Unit& u, int wr, int wc, int fr, int fq) const {
;     ...
;                     if (c128 < 1024) {
; #pragma unroll
;                         for (int i = 0; i < 8; i += 2) { const f32x2 g = pg8::gelu_pk((f32x2){v[i], v[i + 1]}); v[i] = g.x; v[i + 1] = g.y; }
;                         const bool isv = c128 >= 512;
;                         u32x4 w; w.x = pk2(v[0], v[1]); w.y = pk2(v[2], v[3]); w.z = pk2(v[4], v[5]); w.w = pk2(v[6], v[7]);
;                         *(u32x4*)((isv ? Vg : U) + (size_t)row * 512 + (c128 & 511) + cw) = w;
.LBB0_678:
	s_andn2_b64 vcc, exec, s[6:7]
	s_cbranch_vccnz .LBB0_683
	v_and_b32_e32 v123, 0x7fffffff, v117
	v_and_b32_e32 v122, 0x7fffffff, v116
	v_pk_fma_f32 v[122:123], v[122:123], s[14:15], 1.0 op_sel_hi:[1,0,0]
	s_waitcnt lgkmcnt(0)
	v_mov_b64_e32 v[124:125], s[96:97]
	v_rcp_f32_e32 v122, v122
	v_rcp_f32_e32 v123, v123
	v_cmp_gt_f32_e32 vcc, 0, v116
	v_cmp_gt_f32_e64 s[6:7], 0, v117
	s_cmpk_gt_i32 s37, 0x1ff
	v_pk_fma_f32 v[126:127], v[122:123], s[42:43], v[124:125] op_sel_hi:[1,0,0]
	s_nop 0
	v_pk_fma_f32 v[126:127], v[122:123], v[126:127], s[0:1] op_sel_hi:[1,1,0]
	s_nop 0
	v_pk_fma_f32 v[126:127], v[122:123], v[126:127], s[50:51] op_sel_hi:[1,1,0]
	s_nop 0
	v_pk_fma_f32 v[126:127], v[122:123], v[126:127], s[34:35] op_sel_hi:[1,1,0]
	s_nop 0
	v_pk_mul_f32 v[122:123], v[122:123], v[126:127]
	v_pk_mul_f32 v[126:127], v[116:117], v[116:117]
	s_nop 0
	v_pk_mul_f32 v[126:127], v[126:127], s[46:47] op_sel_hi:[1,0]
	s_nop 0
	v_exp_f32_e32 v126, v126
	v_exp_f32_e32 v127, v127
	s_nop 0
	v_pk_mul_f32 v[122:123], v[126:127], v[122:123]
	s_nop 0
	v_pk_mul_f32 v[126:127], v[116:117], v[122:123]
	v_pk_fma_f32 v[122:123], v[116:117], v[122:123], v[116:117] neg_lo:[1,0,0] neg_hi:[1,0,0]
	s_nop 0
	v_cndmask_b32_e64 v117, v123, v127, s[6:7]
	v_cndmask_b32_e32 v116, v122, v126, vcc
	v_and_b32_e32 v123, 0x7fffffff, v119
	v_and_b32_e32 v122, 0x7fffffff, v118
	v_pk_fma_f32 v[122:123], v[122:123], s[14:15], 1.0 op_sel_hi:[1,0,0]
	v_cmp_gt_f32_e32 vcc, 0, v118
	v_rcp_f32_e32 v122, v122
	v_rcp_f32_e32 v123, v123
	v_cmp_gt_f32_e64 s[6:7], 0, v119
	v_pk_fma_f32 v[126:127], v[122:123], s[42:43], v[124:125] op_sel_hi:[1,0,0]
	s_nop 0
	v_pk_fma_f32 v[126:127], v[122:123], v[126:127], s[0:1] op_sel_hi:[1,1,0]
	s_nop 0
	v_pk_fma_f32 v[126:127], v[122:123], v[126:127], s[50:51] op_sel_hi:[1,1,0]
	s_nop 0
	v_pk_fma_f32 v[126:127], v[122:123], v[126:127], s[34:35] op_sel_hi:[1,1,0]
	s_nop 0
	v_pk_mul_f32 v[122:123], v[122:123], v[126:127]
	v_pk_mul_f32 v[126:127], v[118:119], v[118:119]
	s_nop 0
	v_pk_mul_f32 v[126:127], v[126:127], s[46:47] op_sel_hi:[1,0]
	s_nop 0
	v_exp_f32_e32 v126, v126
	v_exp_f32_e32 v127, v127
	s_nop 0
	v_pk_mul_f32 v[122:123], v[126:127], v[122:123]
	s_nop 0
	v_pk_mul_f32 v[126:127], v[118:119], v[122:123]
	v_pk_fma_f32 v[122:123], v[118:119], v[122:123], v[118:119] neg_lo:[1,0,0] neg_hi:[1,0,0]
	s_nop 0
	v_cndmask_b32_e64 v119, v123, v127, s[6:7]
	v_cndmask_b32_e32 v118, v122, v126, vcc
	v_and_b32_e32 v123, 0x7fffffff, v113
	v_and_b32_e32 v122, 0x7fffffff, v112
	v_pk_fma_f32 v[122:123], v[122:123], s[14:15], 1.0 op_sel_hi:[1,0,0]
	v_cmp_gt_f32_e32 vcc, 0, v112
	v_rcp_f32_e32 v122, v122
	v_rcp_f32_e32 v123, v123
	v_cmp_gt_f32_e64 s[6:7], 0, v113
	v_pk_fma_f32 v[126:127], v[122:123], s[42:43], v[124:125] op_sel_hi:[1,0,0]
	s_nop 0
	v_pk_fma_f32 v[126:127], v[122:123], v[126:127], s[0:1] op_sel_hi:[1,1,0]
	s_nop 0
	v_pk_fma_f32 v[126:127], v[122:123], v[126:127], s[50:51] op_sel_hi:[1,1,0]
	s_nop 0
	v_pk_fma_f32 v[126:127], v[122:123], v[126:127], s[34:35] op_sel_hi:[1,1,0]
	s_nop 0
	v_pk_mul_f32 v[122:123], v[122:123], v[126:127]
	v_pk_mul_f32 v[126:127], v[112:113], v[112:113]
	s_nop 0
	v_pk_mul_f32 v[126:127], v[126:127], s[46:47] op_sel_hi:[1,0]
	s_nop 0
	v_exp_f32_e32 v126, v126
	v_exp_f32_e32 v127, v127
	s_nop 0
	v_pk_mul_f32 v[122:123], v[126:127], v[122:123]
	s_nop 0
	v_pk_mul_f32 v[126:127], v[112:113], v[122:123]
	v_pk_fma_f32 v[122:123], v[112:113], v[122:123], v[112:113] neg_lo:[1,0,0] neg_hi:[1,0,0]
	s_nop 0
	v_cndmask_b32_e64 v113, v123, v127, s[6:7]
	v_cndmask_b32_e32 v112, v122, v126, vcc
	v_and_b32_e32 v123, 0x7fffffff, v115
	v_and_b32_e32 v122, 0x7fffffff, v114
	v_pk_fma_f32 v[122:123], v[122:123], s[14:15], 1.0 op_sel_hi:[1,0,0]
	v_cmp_gt_f32_e64 s[6:7], 0, v115
	v_rcp_f32_e32 v122, v122
	v_rcp_f32_e32 v123, v123
	v_cmp_gt_f32_e32 vcc, 0, v114
	v_pk_fma_f32 v[124:125], v[122:123], s[42:43], v[124:125] op_sel_hi:[1,0,0]
	s_nop 0
	v_pk_fma_f32 v[124:125], v[122:123], v[124:125], s[0:1] op_sel_hi:[1,1,0]
	s_nop 0
	v_pk_fma_f32 v[124:125], v[122:123], v[124:125], s[50:51] op_sel_hi:[1,1,0]
	s_nop 0
	v_pk_fma_f32 v[124:125], v[122:123], v[124:125], s[34:35] op_sel_hi:[1,1,0]
	s_nop 0
	v_pk_mul_f32 v[122:123], v[122:123], v[124:125]
	v_pk_mul_f32 v[124:125], v[114:115], v[114:115]
	s_nop 0
	v_pk_mul_f32 v[124:125], v[124:125], s[46:47] op_sel_hi:[1,0]
	s_nop 0
	v_exp_f32_e32 v124, v124
	v_exp_f32_e32 v125, v125
	s_nop 0
	v_pk_mul_f32 v[122:123], v[124:125], v[122:123]
	s_nop 0
	v_pk_mul_f32 v[124:125], v[114:115], v[122:123]
	v_pk_fma_f32 v[122:123], v[114:115], v[122:123], v[114:115] neg_lo:[1,0,0] neg_hi:[1,0,0]
	s_nop 0
	v_cndmask_b32_e64 v115, v123, v125, s[6:7]
	s_cselect_b32 s6, s15, s1
	s_cselect_b32 s7, s35, s43
	s_and_b32 s8, s37, 0x180
	s_lshl_b32 s48, s8, 1
	v_lshl_add_u64 v[126:127], s[6:7], 0, v[158:159]
	v_cndmask_b32_e32 v114, v122, v124, vcc
	v_lshl_add_u64 v[126:127], v[126:127], 0, s[48:49]
	s_cmpk_lt_i32 s37, 0x200
	v_cvt_pk_bf16_f32 v122, v116, v117
	v_cvt_pk_bf16_f32 v123, v118, v119
	v_cvt_pk_bf16_f32 v124, v112, v113
	v_cvt_pk_bf16_f32 v125, v114, v115
	v_lshl_add_u64 v[126:127], v[126:127], 0, v[140:141]
	global_store_dwordx4 v[126:127], v[122:125], off
	s_cbranch_scc1 .LBB0_683
; DI float quad_sum(float s) { s += __shfl_xor(s, 16); s += __shfl_xor(s, 32); return s; }
;     DI void operator()(const f32x4 (&acc)[2][2][4][2], const Unit& u, int wr, int wc, int fr, int fq) const {
;     ...
;                         if (isv) {
;                             float s1 = 0.f, s2 = 0.f;
; #pragma unroll
;                             for (int i = 0; i < 8; ++i) { s1 += v[i]; s2 += v[i] * v[i]; }
;                             s1 = quad_sum(s1); s2 = quad_sum(s2);
;                             if (fq == 0) { float* d = VST + ((size_t)row * 16 + ((c128 - 512) >> 7) * 4 + wc) * 2; d[0] = s1; d[1] = s2; }
;                         }
	s_nop 0
	v_mov_b32_e32 v122, v141
	v_mov_b32_e32 v123, v117
	v_pk_add_f32 v[122:123], v[116:117], v[122:123]
	v_pk_mul_f32 v[124:125], v[116:117], v[116:117]
	v_pk_mul_f32 v[126:127], v[118:119], v[118:119]
	v_mov_b32_e32 v123, v125
	v_pk_mov_b32 v[116:117], v[116:117], v[124:125] op_sel:[1,0]
	v_pk_mul_f32 v[158:159], v[112:113], v[112:113]
	v_pk_add_f32 v[116:117], v[116:117], v[122:123]
	v_mov_b32_e32 v122, v118
	v_mov_b32_e32 v123, v126
	v_pk_add_f32 v[116:117], v[122:123], v[116:117]
	v_mov_b32_e32 v126, v119
	v_and_b32_e32 v162, 64, v175
	v_pk_add_f32 v[116:117], v[126:127], v[116:117]
	v_mov_b32_e32 v118, v112
	v_mov_b32_e32 v119, v158
	v_pk_mul_f32 v[160:161], v[114:115], v[114:115]
	v_xor_b32_e32 v155, 16, v175
	v_add_u32_e32 v162, 64, v162
	v_pk_add_f32 v[116:117], v[118:119], v[116:117]
	v_mov_b32_e32 v158, v113
	v_cmp_lt_i32_e32 vcc, v155, v162
	v_pk_add_f32 v[112:113], v[158:159], v[116:117]
	v_mov_b32_e32 v116, v114
	v_mov_b32_e32 v117, v160
	v_cndmask_b32_e32 v155, v175, v155, vcc
	v_pk_add_f32 v[112:113], v[116:117], v[112:113]
	v_mov_b32_e32 v160, v115
	v_lshlrev_b32_e32 v155, 2, v155
	v_pk_add_f32 v[112:113], v[160:161], v[112:113]
	ds_bpermute_b32 v114, v155, v112
	ds_bpermute_b32 v115, v155, v113
	v_xor_b32_e32 v116, 32, v175
	v_cmp_lt_i32_e32 vcc, v116, v162
	s_waitcnt lgkmcnt(0)
	v_pk_add_f32 v[112:113], v[112:113], v[114:115]
	v_cndmask_b32_e32 v116, v175, v116, vcc
	v_lshlrev_b32_e32 v116, 2, v116
	ds_bpermute_b32 v114, v116, v112
	ds_bpermute_b32 v115, v116, v113
	s_and_saveexec_b64 s[6:7], s[2:3]
	s_cbranch_execz .LBB0_682
	s_add_i32 s8, s94, 0xfffffe80
	s_lshr_b32 s48, s8, 5
	v_lshl_add_u64 v[116:117], v[120:121], 0, s[48:49]
	v_lshl_add_u64 v[116:117], v[116:117], 3, s[80:81]
	s_waitcnt lgkmcnt(0)
	v_pk_add_f32 v[112:113], v[112:113], v[114:115]
	global_store_dwordx2 v[116:117], v[112:113], off

; DI unsigned pk2(float lo, float hi) { typedef float v2f __attribute__((ext_vector_type(2))); typedef __bf16 v2b __attribute__((ext_vector_type(2))); v2f v = {lo, hi}; v2b b = __builtin_convertvector(v, v2b); return __builtin_bit_cast(unsigned, b); }
; DI void atomic_addf(float* p, float v) { __builtin_amdgcn_global_atomic_fadd_f32((__attribute__((address_space(1))) float*)p, v); }
; DI float quad_sum(float s) { s += __shfl_xor(s, 16); s += __shfl_xor(s, 32); return s; }
;     DI void operator()(const f32x4 (&acc)[2][2][4][2], const Unit& u, int wr, int wc, int fr, int fq) const {
;     ...
;                         u32x4 w; w.x = pk2(v[0], v[1]); w.y = pk2(v[2], v[3]); w.z = pk2(v[4], v[5]); w.w = pk2(v[6], v[7]);
;                         *(u32x4*)(dst + cw) = w;
;                         float s2 = 0.f;
; #pragma unroll
;                         for (int i = 0; i < 8; ++i) s2 += v[i] * v[i];
;                         s2 = quad_sum(s2);
;                         if (fq == 0) { if (isqm) *pp = s2; else atomic_addf(pp, s2); }
.LBB0_693:
	v_cvt_pk_bf16_f32 v158, v124, v125
	v_cvt_pk_bf16_f32 v159, v110, v111
	v_cvt_pk_bf16_f32 v160, v108, v109
	v_cvt_pk_bf16_f32 v161, v106, v107
	v_lshl_add_u64 v[126:127], v[126:127], 0, v[140:141]
	global_store_dwordx4 v[126:127], v[158:161], off
	v_pk_mul_f32 v[126:127], v[124:125], v[124:125]
	v_pk_mul_f32 v[162:163], v[106:107], v[106:107]
	v_pk_mul_f32 v[158:159], v[110:111], v[110:111]
	v_add_f32_e32 v123, v126, v127
	v_add_f32_e32 v123, v158, v123
	v_pk_mul_f32 v[160:161], v[108:109], v[108:109]
	v_add_f32_e32 v123, v159, v123
	v_and_b32_e32 v127, 64, v175
	v_add_f32_e32 v123, v160, v123
	v_xor_b32_e32 v126, 16, v175
	v_add_u32_e32 v127, 64, v127
	v_add_f32_e32 v123, v161, v123
	v_cmp_lt_i32_e32 vcc, v126, v127
	v_add_f32_e32 v123, v162, v123
	v_add_f32_e32 v123, v163, v123
	v_cndmask_b32_e32 v126, v175, v126, vcc
	v_lshlrev_b32_e32 v126, 2, v126
	ds_bpermute_b32 v126, v126, v123
	s_waitcnt lgkmcnt(0)
	v_add_f32_e32 v123, v123, v126
	v_xor_b32_e32 v126, 32, v175
	v_cmp_lt_i32_e32 vcc, v126, v127
	s_nop 1
	v_cndmask_b32_e32 v126, v175, v126, vcc
	v_lshlrev_b32_e32 v126, 2, v126
	ds_bpermute_b32 v126, v126, v123
	s_and_saveexec_b64 s[6:7], s[2:3]
	s_cbranch_execz .LBB0_698
	s_waitcnt lgkmcnt(0)
	v_add_f32_e32 v123, v123, v126
	s_cmpk_gt_u32 s94, 0x67f
	s_mov_b64 s[10:11], -1
	s_cbranch_scc1 .LBB0_696
	global_atomic_add_f32 v[104:105], v123, off
	s_mov_b64 s[10:11], 0
.LBB0_696:
	s_andn2_b64 vcc, exec, s[10:11]
	s_cbranch_vccnz .LBB0_698
	global_store_dword v[104:105], v123, off

; DI unsigned pk2(float lo, float hi) { typedef float v2f __attribute__((ext_vector_type(2))); typedef __bf16 v2b __attribute__((ext_vector_type(2))); v2f v = {lo, hi}; v2b b = __builtin_convertvector(v, v2b); return __builtin_bit_cast(unsigned, b); }
; __device__ __forceinline__ f32x2 gelu_pk(f32x2 v) {
;     const f32x2 av = __builtin_elementwise_abs(v), d = av * 0.2316418882f + 1.0f;
;     f32x2 t; t.x = __builtin_amdgcn_rcpf(d.x); t.y = __builtin_amdgcn_rcpf(d.y);
;     f32x2 q = t * 0.5307027145f + (-0.7265760135f); q = q * t + 0.7107068705f; q = q * t + (-0.142248368f); q = q * t + 0.127414796f; q = q * t;
;     const f32x2 s = (v * v) * (-0.72134752044f);
;     f32x2 e; e.x = __builtin_amdgcn_exp2f(s.x); e.y = __builtin_amdgcn_exp2f(s.y);
;     const f32x2 m = v * (q * e), r = v - m;
;     f32x2 o; o.x = v.x < 0.f ? m.x : r.x; o.y = v.y < 0.f ? m.y : r.y; return o;
; }
;     DI void operator()(const f32x4 (&acc)[2][2][4][2], const Unit& u, int wr, int wc, int fr, int fq) const {
;     ...
;                     if (c128 < 1024) {
; #pragma unroll
;                         for (int i = 0; i < 8; i += 2) { const f32x2 g = pg8::gelu_pk((f32x2){v[i], v[i + 1]}); v[i] = g.x; v[i + 1] = g.y; }
;                         const bool isv = c128 >= 512;
;                         u32x4 w; w.x = pk2(v[0], v[1]); w.y = pk2(v[2], v[3]); w.z = pk2(v[4], v[5]); w.w = pk2(v[6], v[7]);
;                         *(u32x4*)((isv ? Vg : U) + (size_t)row * 512 + (c128 & 511) + cw) = w;
.LBB0_700:
	v_lshlrev_b64 v[104:105], 4, v[114:115]
	s_andn2_b64 vcc, exec, s[6:7]
	v_or_b32_e32 v104, s97, v104
	s_cbranch_vccnz .LBB0_705
	v_and_b32_e32 v127, 0x7fffffff, v125
	s_waitcnt lgkmcnt(0)
	v_and_b32_e32 v126, 0x7fffffff, v124
	v_pk_fma_f32 v[126:127], v[126:127], s[14:15], 1.0 op_sel_hi:[1,0,0]
	v_mov_b64_e32 v[158:159], s[96:97]
	v_rcp_f32_e32 v126, v126
	v_rcp_f32_e32 v127, v127
	v_cmp_gt_f32_e32 vcc, 0, v124
	v_cmp_gt_f32_e64 s[6:7], 0, v125
	s_cmp_gt_i32 s60, 1
	v_pk_fma_f32 v[160:161], v[126:127], s[42:43], v[158:159] op_sel_hi:[1,0,0]
	s_nop 0
	v_pk_fma_f32 v[160:161], v[126:127], v[160:161], s[0:1] op_sel_hi:[1,1,0]
	s_nop 0
	v_pk_fma_f32 v[160:161], v[126:127], v[160:161], s[50:51] op_sel_hi:[1,1,0]
	s_nop 0
	v_pk_fma_f32 v[160:161], v[126:127], v[160:161], s[34:35] op_sel_hi:[1,1,0]
	s_nop 0
	v_pk_mul_f32 v[126:127], v[126:127], v[160:161]
	v_pk_mul_f32 v[160:161], v[124:125], v[124:125]
	s_nop 0
	v_pk_mul_f32 v[160:161], v[160:161], s[46:47] op_sel_hi:[1,0]
	s_nop 0
	v_exp_f32_e32 v160, v160
	v_exp_f32_e32 v161, v161
	s_nop 0
	v_pk_mul_f32 v[126:127], v[160:161], v[126:127]
	s_nop 0
	v_pk_mul_f32 v[160:161], v[124:125], v[126:127]
	v_pk_fma_f32 v[126:127], v[124:125], v[126:127], v[124:125] neg_lo:[1,0,0] neg_hi:[1,0,0]
	s_nop 0
	v_cndmask_b32_e64 v125, v127, v161, s[6:7]
	v_cndmask_b32_e32 v124, v126, v160, vcc
	v_and_b32_e32 v127, 0x7fffffff, v111
	v_and_b32_e32 v126, 0x7fffffff, v110
	v_pk_fma_f32 v[126:127], v[126:127], s[14:15], 1.0 op_sel_hi:[1,0,0]
	v_cmp_gt_f32_e32 vcc, 0, v110
	v_rcp_f32_e32 v126, v126
	v_rcp_f32_e32 v127, v127
	v_cmp_gt_f32_e64 s[6:7], 0, v111
	v_pk_fma_f32 v[160:161], v[126:127], s[42:43], v[158:159] op_sel_hi:[1,0,0]
	s_nop 0
	v_pk_fma_f32 v[160:161], v[126:127], v[160:161], s[0:1] op_sel_hi:[1,1,0]
	s_nop 0
	v_pk_fma_f32 v[160:161], v[126:127], v[160:161], s[50:51] op_sel_hi:[1,1,0]
	s_nop 0
	v_pk_fma_f32 v[160:161], v[126:127], v[160:161], s[34:35] op_sel_hi:[1,1,0]
	s_nop 0
	v_pk_mul_f32 v[126:127], v[126:127], v[160:161]
	v_pk_mul_f32 v[160:161], v[110:111], v[110:111]
	s_nop 0
	v_pk_mul_f32 v[160:161], v[160:161], s[46:47] op_sel_hi:[1,0]
	s_nop 0
	v_exp_f32_e32 v160, v160
	v_exp_f32_e32 v161, v161
	s_nop 0
	v_pk_mul_f32 v[126:127], v[160:161], v[126:127]
	s_nop 0
	v_pk_mul_f32 v[160:161], v[110:111], v[126:127]
	v_pk_fma_f32 v[126:127], v[110:111], v[126:127], v[110:111] neg_lo:[1,0,0] neg_hi:[1,0,0]
	s_nop 0
	v_cndmask_b32_e64 v111, v127, v161, s[6:7]
	v_cndmask_b32_e32 v110, v126, v160, vcc
	v_and_b32_e32 v127, 0x7fffffff, v109
	v_and_b32_e32 v126, 0x7fffffff, v108
	v_pk_fma_f32 v[126:127], v[126:127], s[14:15], 1.0 op_sel_hi:[1,0,0]
	v_cmp_gt_f32_e32 vcc, 0, v108
	v_rcp_f32_e32 v126, v126
	v_rcp_f32_e32 v127, v127
	v_cmp_gt_f32_e64 s[6:7], 0, v109
	v_pk_fma_f32 v[160:161], v[126:127], s[42:43], v[158:159] op_sel_hi:[1,0,0]
	s_nop 0
	v_pk_fma_f32 v[160:161], v[126:127], v[160:161], s[0:1] op_sel_hi:[1,1,0]
	s_nop 0
	v_pk_fma_f32 v[160:161], v[126:127], v[160:161], s[50:51] op_sel_hi:[1,1,0]
	s_nop 0
	v_pk_fma_f32 v[160:161], v[126:127], v[160:161], s[34:35] op_sel_hi:[1,1,0]
	s_nop 0
	v_pk_mul_f32 v[126:127], v[126:127], v[160:161]
	v_pk_mul_f32 v[160:161], v[108:109], v[108:109]
	s_nop 0
	v_pk_mul_f32 v[160:161], v[160:161], s[46:47] op_sel_hi:[1,0]
	s_nop 0
	v_exp_f32_e32 v160, v160
	v_exp_f32_e32 v161, v161
	s_nop 0
	v_pk_mul_f32 v[126:127], v[160:161], v[126:127]
	s_nop 0
	v_pk_mul_f32 v[160:161], v[108:109], v[126:127]
	v_pk_fma_f32 v[126:127], v[108:109], v[126:127], v[108:109] neg_lo:[1,0,0] neg_hi:[1,0,0]
	s_nop 0
	v_cndmask_b32_e64 v109, v127, v161, s[6:7]
	v_cndmask_b32_e32 v108, v126, v160, vcc
	v_and_b32_e32 v127, 0x7fffffff, v107
	v_and_b32_e32 v126, 0x7fffffff, v106
	v_pk_fma_f32 v[126:127], v[126:127], s[14:15], 1.0 op_sel_hi:[1,0,0]
	v_cmp_gt_f32_e64 s[6:7], 0, v107
	v_rcp_f32_e32 v126, v126
	v_rcp_f32_e32 v127, v127
	v_cmp_gt_f32_e32 vcc, 0, v106
	v_cvt_pk_bf16_f32 v160, v108, v109
	v_pk_fma_f32 v[158:159], v[126:127], s[42:43], v[158:159] op_sel_hi:[1,0,0]
	s_nop 0
	v_pk_fma_f32 v[158:159], v[126:127], v[158:159], s[0:1] op_sel_hi:[1,1,0]
	s_nop 0
	v_pk_fma_f32 v[158:159], v[126:127], v[158:159], s[50:51] op_sel_hi:[1,1,0]
	s_nop 0
	v_pk_fma_f32 v[158:159], v[126:127], v[158:159], s[34:35] op_sel_hi:[1,1,0]
	s_nop 0
	v_pk_mul_f32 v[126:127], v[126:127], v[158:159]
	v_pk_mul_f32 v[158:159], v[106:107], v[106:107]
	s_nop 0
	v_pk_mul_f32 v[158:159], v[158:159], s[46:47] op_sel_hi:[1,0]
	s_nop 0
	v_exp_f32_e32 v158, v158
	v_exp_f32_e32 v159, v159
	s_nop 0
	v_pk_mul_f32 v[126:127], v[158:159], v[126:127]
	s_nop 0
	v_pk_mul_f32 v[158:159], v[106:107], v[126:127]
	v_pk_fma_f32 v[126:127], v[106:107], v[126:127], v[106:107] neg_lo:[1,0,0] neg_hi:[1,0,0]
	s_nop 0
	v_cndmask_b32_e64 v107, v127, v159, s[6:7]
	s_cselect_b32 s6, s15, s1
	s_cselect_b32 s7, s35, s43
	s_and_b32 s10, s94, 0x100
	v_cndmask_b32_e32 v106, v126, v158, vcc
	s_lshl_b32 s48, s10, 1
	v_lshl_add_u64 v[126:127], s[6:7], 0, v[112:113]
	v_lshl_add_u64 v[126:127], v[126:127], 0, s[48:49]
	s_cmp_lt_i32 s60, 2
	v_cvt_pk_bf16_f32 v158, v124, v125
	v_cvt_pk_bf16_f32 v159, v110, v111
	v_cvt_pk_bf16_f32 v161, v106, v107
	v_lshl_add_u64 v[126:127], v[126:127], 0, v[140:141]
	global_store_dwordx4 v[126:127], v[158:161], off
	s_cbranch_scc1 .LBB0_705
; DI float quad_sum(float s) { s += __shfl_xor(s, 16); s += __shfl_xor(s, 32); return s; }
;     DI void operator()(const f32x4 (&acc)[2][2][4][2], const Unit& u, int wr, int wc, int fr, int fq) const {
;     ...
;                         if (isv) {
;                             float s1 = 0.f, s2 = 0.f;
; #pragma unroll
;                             for (int i = 0; i < 8; ++i) { s1 += v[i]; s2 += v[i] * v[i]; }
;                             s1 = quad_sum(s1); s2 = quad_sum(s2);
;                             if (fq == 0) { float* d = VST + ((size_t)row * 16 + ((c128 - 512) >> 7) * 4 + wc) * 2; d[0] = s1; d[1] = s2; }
;                         }
	v_mov_b32_e32 v126, v141
	v_mov_b32_e32 v127, v125
	v_pk_add_f32 v[126:127], v[124:125], v[126:127]
	v_pk_mul_f32 v[158:159], v[124:125], v[124:125]
	v_pk_mul_f32 v[160:161], v[110:111], v[110:111]
	v_mov_b32_e32 v127, v159
	v_pk_mov_b32 v[124:125], v[124:125], v[158:159] op_sel:[1,0]
	v_pk_mul_f32 v[162:163], v[108:109], v[108:109]
	v_pk_add_f32 v[124:125], v[124:125], v[126:127]
	v_mov_b32_e32 v126, v110
	v_mov_b32_e32 v127, v160
	v_pk_add_f32 v[124:125], v[126:127], v[124:125]
	v_mov_b32_e32 v160, v111
	v_and_b32_e32 v155, 64, v175
	v_pk_add_f32 v[110:111], v[160:161], v[124:125]
	v_mov_b32_e32 v124, v108
	v_mov_b32_e32 v125, v162
	v_pk_mul_f32 v[164:165], v[106:107], v[106:107]
	v_xor_b32_e32 v123, 16, v175
	v_add_u32_e32 v155, 64, v155
	v_pk_add_f32 v[110:111], v[124:125], v[110:111]
	v_mov_b32_e32 v162, v109
	v_cmp_lt_i32_e32 vcc, v123, v155
	v_pk_add_f32 v[108:109], v[162:163], v[110:111]
	v_mov_b32_e32 v110, v106
	v_mov_b32_e32 v111, v164
	v_cndmask_b32_e32 v123, v175, v123, vcc
	v_pk_add_f32 v[108:109], v[110:111], v[108:109]
	v_mov_b32_e32 v164, v107
	v_lshlrev_b32_e32 v123, 2, v123
	v_pk_add_f32 v[106:107], v[164:165], v[108:109]
	ds_bpermute_b32 v108, v123, v106
	ds_bpermute_b32 v109, v123, v107
	v_xor_b32_e32 v110, 32, v175
	v_cmp_lt_i32_e32 vcc, v110, v155
	s_waitcnt lgkmcnt(0)
	v_pk_add_f32 v[106:107], v[106:107], v[108:109]
	v_cndmask_b32_e32 v110, v175, v110, vcc
	v_lshlrev_b32_e32 v110, 2, v110
	ds_bpermute_b32 v108, v110, v106
	ds_bpermute_b32 v109, v110, v107
	s_and_saveexec_b64 s[6:7], s[2:3]
	s_cbranch_execz .LBB0_704
	s_add_i32 s10, s94, 0xfffffe00
	s_lshr_b32 s48, s10, 5
	v_lshl_add_u64 v[110:111], v[104:105], 0, s[48:49]
	v_lshl_add_u64 v[110:111], v[110:111], 3, s[80:81]
	s_waitcnt lgkmcnt(0)
	v_pk_add_f32 v[106:107], v[106:107], v[108:109]
	global_store_dwordx2 v[110:111], v[106:107], off

; DI float quad_sum(float s) { s += __shfl_xor(s, 16); s += __shfl_xor(s, 32); return s; }
;     DI void operator()(const f32x4 (&acc)[2][2][4][2], const Unit& u, int wr, int wc, int fr, int fq) const {
;     ...
;                         for (int i = 0; i < 4; ++i) v[4 * n + i] = acc[ai][bj][m][n][i] * rs;
;                     if (c128 < 1024) {
; #pragma unroll
;                         for (int i = 0; i < 8; i += 2) { const f32x2 g = pg8::gelu_pk((f32x2){v[i], v[i + 1]}); v[i] = g.x; v[i + 1] = g.y; }
;                         const bool isv = c128 >= 512;
;                         u32x4 w; w.x = pk2(v[0], v[1]); w.y = pk2(v[2], v[3]); w.z = pk2(v[4], v[5]); w.w = pk2(v[6], v[7]);
;                         *(u32x4*)((isv ? Vg : U) + (size_t)row * 512 + (c128 & 511) + cw) = w;
;                         if (isv) {
;                             float s1 = 0.f, s2 = 0.f;
; #pragma unroll
;                             for (int i = 0; i < 8; ++i) { s1 += v[i]; s2 += v[i] * v[i]; }
;                             s1 = quad_sum(s1); s2 = quad_sum(s2);
;                             if (fq == 0) { float* d = VST + ((size_t)row * 16 + ((c128 - 512) >> 7) * 4 + wc) * 2; d[0] = s1; d[1] = s2; }
;                         }
;                     } else if (c128 < 2176) {
;                         bf16_t* dst; float* pp; const bool isqm = c128 >= 1664;
;                         if (c128 < 1408) { dst = CQ + (size_t)row * 384 + (c128 - 1024); pp = CQP + row; }
;                         else if (c128 < 1664) { dst = CKV + (size_t)row * 256 + (c128 - 1408); pp = CKVP + row; }
;                         else { dst = QM + (size_t)row * 512 + (c128 - 1664); pp = QMP + (size_t)row * 16 + ((c128 - 1664) >> 7) * 4 + wc; }
;                         u32x4 w; w.x = pk2(v[0], v[1]); w.y = pk2(v[2], v[3]); w.z = pk2(v[4], v[5]); w.w = pk2(v[6], v[7]);
;                         *(u32x4*)(dst + cw) = w;
;                         float s2 = 0.f;
; #pragma unroll
;                         for (int i = 0; i < 8; ++i) s2 += v[i] * v[i];
;                         s2 = quad_sum(s2);
;                         if (fq == 0) { if (isqm) *pp = s2; else atomic_addf(pp, s2); }
;                     } else if (c128 == 2176) {
;                         if (wc == 0) { float* d = KR + (size_t)row * 32 + 8 * fq; *(f32x4*)d = (f32x4){v[0], v[1], v[2], v[3]}; *(f32x4*)(d + 4) = (f32x4){v[4], v[5], v[6], v[7]}; }
.LBB0_705:
	v_mov_b32_e32 v123, v122
	v_cndmask_b32_e64 v106, 0, 1, s[58:59]
	v_pk_mul_f32 v[100:101], v[100:101], v[122:123]
	v_pk_mul_f32 v[102:103], v[102:103], v[122:123]
	v_pk_mul_f32 v[96:97], v[96:97], v[122:123]
	v_pk_mul_f32 v[98:99], v[98:99], v[122:123]
	v_cmp_ne_u32_e64 s[6:7], 1, v106
	s_andn2_b64 vcc, exec, s[58:59]
	s_mov_b64 s[10:11], -1
	s_cbranch_vccnz .LBB0_726
	s_cmpk_lt_u32 s37, 0x880
	s_cbranch_scc1 .LBB0_710
	s_cmp_lg_u32 s60, 8
	s_cselect_b64 s[10:11], -1, 0
	s_or_b64 s[10:11], s[72:73], s[10:11]
	s_and_b64 vcc, exec, s[10:11]
	s_cbranch_vccnz .LBB0_709
	v_lshlrev_b64 v[106:107], 7, v[114:115]
	v_lshl_add_u64 v[106:107], v[144:145], 0, v[106:107]
	global_store_dwordx4 v[106:107], v[100:103], off
	global_store_dwordx4 v[106:107], v[96:99], off offset:16

; DI unsigned pk2(float lo, float hi) { typedef float v2f __attribute__((ext_vector_type(2))); typedef __bf16 v2b __attribute__((ext_vector_type(2))); v2f v = {lo, hi}; v2b b = __builtin_convertvector(v, v2b); return __builtin_bit_cast(unsigned, b); }
; DI void atomic_addf(float* p, float v) { __builtin_amdgcn_global_atomic_fadd_f32((__attribute__((address_space(1))) float*)p, v); }
; DI float quad_sum(float s) { s += __shfl_xor(s, 16); s += __shfl_xor(s, 32); return s; }
;     DI void operator()(const f32x4 (&acc)[2][2][4][2], const Unit& u, int wr, int wc, int fr, int fq) const {
;     ...
;                         u32x4 w; w.x = pk2(v[0], v[1]); w.y = pk2(v[2], v[3]); w.z = pk2(v[4], v[5]); w.w = pk2(v[6], v[7]);
;                         *(u32x4*)(dst + cw) = w;
;                         float s2 = 0.f;
; #pragma unroll
;                         for (int i = 0; i < 8; ++i) s2 += v[i] * v[i];
;                         s2 = quad_sum(s2);
;                         if (fq == 0) { if (isqm) *pp = s2; else atomic_addf(pp, s2); }
.LBB0_719:
	v_cvt_pk_bf16_f32 v114, v100, v101
	v_cvt_pk_bf16_f32 v115, v102, v103
	v_cvt_pk_bf16_f32 v116, v96, v97
	v_cvt_pk_bf16_f32 v117, v98, v99
	s_waitcnt lgkmcnt(0)
	v_lshl_add_u64 v[108:109], v[108:109], 0, v[140:141]
	global_store_dwordx4 v[108:109], v[114:117], off
	v_pk_mul_f32 v[108:109], v[100:101], v[100:101]
	v_pk_mul_f32 v[110:111], v[102:103], v[102:103]
	v_add_f32_e32 v108, v108, v109
	v_add_f32_e32 v108, v110, v108
	v_pk_mul_f32 v[114:115], v[96:97], v[96:97]
	v_add_f32_e32 v108, v111, v108
	v_and_b32_e32 v110, 64, v175
	v_add_f32_e32 v108, v114, v108
	v_xor_b32_e32 v109, 16, v175
	v_add_u32_e32 v110, 64, v110
	v_pk_mul_f32 v[116:117], v[98:99], v[98:99]
	v_add_f32_e32 v108, v115, v108
	v_cmp_lt_i32_e32 vcc, v109, v110
	v_add_f32_e32 v108, v116, v108
	v_add_f32_e32 v108, v117, v108
	v_cndmask_b32_e32 v109, v175, v109, vcc
	v_lshlrev_b32_e32 v109, 2, v109
	ds_bpermute_b32 v109, v109, v108
	s_waitcnt lgkmcnt(0)
	v_add_f32_e32 v108, v108, v109
	v_xor_b32_e32 v109, 32, v175
	v_cmp_lt_i32_e32 vcc, v109, v110
	s_nop 1
	v_cndmask_b32_e32 v109, v175, v109, vcc
	v_lshlrev_b32_e32 v109, 2, v109
	ds_bpermute_b32 v109, v109, v108
	s_and_saveexec_b64 s[10:11], s[2:3]
	s_cbranch_execz .LBB0_724
	s_waitcnt lgkmcnt(0)
	v_add_f32_e32 v108, v108, v109
	s_cmpk_gt_u32 s37, 0x67f
	s_mov_b64 s[12:13], -1
	s_cbranch_scc1 .LBB0_722
	global_atomic_add_f32 v[106:107], v108, off
	s_mov_b64 s[12:13], 0
.LBB0_722:
	s_andn2_b64 vcc, exec, s[12:13]
	s_cbranch_vccnz .LBB0_724
	global_store_dword v[106:107], v108, off

; DI unsigned pk2(float lo, float hi) { typedef float v2f __attribute__((ext_vector_type(2))); typedef __bf16 v2b __attribute__((ext_vector_type(2))); v2f v = {lo, hi}; v2b b = __builtin_convertvector(v, v2b); return __builtin_bit_cast(unsigned, b); }
; DI float quad_sum(float s) { s += __shfl_xor(s, 16); s += __shfl_xor(s, 32); return s; }
; __device__ __forceinline__ f32x2 gelu_pk(f32x2 v) {
;     const f32x2 av = __builtin_elementwise_abs(v), d = av * 0.2316418882f + 1.0f;
;     f32x2 t; t.x = __builtin_amdgcn_rcpf(d.x); t.y = __builtin_amdgcn_rcpf(d.y);
;     f32x2 q = t * 0.5307027145f + (-0.7265760135f); q = q * t + 0.7107068705f; q = q * t + (-0.142248368f); q = q * t + 0.127414796f; q = q * t;
;     const f32x2 s = (v * v) * (-0.72134752044f);
;     f32x2 e; e.x = __builtin_amdgcn_exp2f(s.x); e.y = __builtin_amdgcn_exp2f(s.y);
;     const f32x2 m = v * (q * e), r = v - m;
;     f32x2 o; o.x = v.x < 0.f ? m.x : r.x; o.y = v.y < 0.f ? m.y : r.y; return o;
; }
;     DI void operator()(const f32x4 (&acc)[2][2][4][2], const Unit& u, int wr, int wc, int fr, int fq) const {
;     ...
;                     if (c128 < 1024) {
; #pragma unroll
;                         for (int i = 0; i < 8; i += 2) { const f32x2 g = pg8::gelu_pk((f32x2){v[i], v[i + 1]}); v[i] = g.x; v[i + 1] = g.y; }
;                         const bool isv = c128 >= 512;
;                         u32x4 w; w.x = pk2(v[0], v[1]); w.y = pk2(v[2], v[3]); w.z = pk2(v[4], v[5]); w.w = pk2(v[6], v[7]);
;                         *(u32x4*)((isv ? Vg : U) + (size_t)row * 512 + (c128 & 511) + cw) = w;
;                         if (isv) {
;                             float s1 = 0.f, s2 = 0.f;
; #pragma unroll
;                             for (int i = 0; i < 8; ++i) { s1 += v[i]; s2 += v[i] * v[i]; }
;                             s1 = quad_sum(s1); s2 = quad_sum(s2);
;                             if (fq == 0) { float* d = VST + ((size_t)row * 16 + ((c128 - 512) >> 7) * 4 + wc) * 2; d[0] = s1; d[1] = s2; }
;                         }
.LBB0_726:
	s_andn2_b64 vcc, exec, s[10:11]
	s_cbranch_vccnz .LBB0_731
	v_and_b32_e32 v107, 0x7fffffff, v101
	v_and_b32_e32 v106, 0x7fffffff, v100
	v_pk_fma_f32 v[106:107], v[106:107], s[14:15], 1.0 op_sel_hi:[1,0,0]
	s_waitcnt lgkmcnt(0)
	v_mov_b64_e32 v[108:109], s[96:97]
	v_rcp_f32_e32 v106, v106
	v_rcp_f32_e32 v107, v107
	v_cmp_gt_f32_e32 vcc, 0, v100
	v_cmp_gt_f32_e64 s[10:11], 0, v101
	s_cmpk_gt_i32 s37, 0x1ff
	v_pk_fma_f32 v[110:111], v[106:107], s[42:43], v[108:109] op_sel_hi:[1,0,0]
	s_nop 0
	v_pk_fma_f32 v[110:111], v[106:107], v[110:111], s[0:1] op_sel_hi:[1,1,0]
	s_nop 0
	v_pk_fma_f32 v[110:111], v[106:107], v[110:111], s[50:51] op_sel_hi:[1,1,0]
	s_nop 0
	v_pk_fma_f32 v[110:111], v[106:107], v[110:111], s[34:35] op_sel_hi:[1,1,0]
	s_nop 0
	v_pk_mul_f32 v[106:107], v[106:107], v[110:111]
	v_pk_mul_f32 v[110:111], v[100:101], v[100:101]
	s_nop 0
	v_pk_mul_f32 v[110:111], v[110:111], s[46:47] op_sel_hi:[1,0]
	s_nop 0
	v_exp_f32_e32 v110, v110
	v_exp_f32_e32 v111, v111
	s_nop 0
	v_pk_mul_f32 v[106:107], v[110:111], v[106:107]
	s_nop 0
	v_pk_mul_f32 v[110:111], v[100:101], v[106:107]
	v_pk_fma_f32 v[106:107], v[100:101], v[106:107], v[100:101] neg_lo:[1,0,0] neg_hi:[1,0,0]
	s_nop 0
	v_cndmask_b32_e64 v101, v107, v111, s[10:11]
	v_cndmask_b32_e32 v100, v106, v110, vcc
	v_and_b32_e32 v107, 0x7fffffff, v103
	v_and_b32_e32 v106, 0x7fffffff, v102
	v_pk_fma_f32 v[106:107], v[106:107], s[14:15], 1.0 op_sel_hi:[1,0,0]
	v_cmp_gt_f32_e32 vcc, 0, v102
	v_rcp_f32_e32 v106, v106
	v_rcp_f32_e32 v107, v107
	v_cmp_gt_f32_e64 s[10:11], 0, v103
	v_pk_fma_f32 v[110:111], v[106:107], s[42:43], v[108:109] op_sel_hi:[1,0,0]
	s_nop 0
	v_pk_fma_f32 v[110:111], v[106:107], v[110:111], s[0:1] op_sel_hi:[1,1,0]
	s_nop 0
	v_pk_fma_f32 v[110:111], v[106:107], v[110:111], s[50:51] op_sel_hi:[1,1,0]
	s_nop 0
	v_pk_fma_f32 v[110:111], v[106:107], v[110:111], s[34:35] op_sel_hi:[1,1,0]
	s_nop 0
	v_pk_mul_f32 v[106:107], v[106:107], v[110:111]
	v_pk_mul_f32 v[110:111], v[102:103], v[102:103]
	s_nop 0
	v_pk_mul_f32 v[110:111], v[110:111], s[46:47] op_sel_hi:[1,0]
	s_nop 0
	v_exp_f32_e32 v110, v110
	v_exp_f32_e32 v111, v111
	s_nop 0
	v_pk_mul_f32 v[106:107], v[110:111], v[106:107]
	s_nop 0
	v_pk_mul_f32 v[110:111], v[102:103], v[106:107]
	v_pk_fma_f32 v[106:107], v[102:103], v[106:107], v[102:103] neg_lo:[1,0,0] neg_hi:[1,0,0]
	s_nop 0
	v_cndmask_b32_e64 v103, v107, v111, s[10:11]
	v_cndmask_b32_e32 v102, v106, v110, vcc
	v_and_b32_e32 v107, 0x7fffffff, v97
	v_and_b32_e32 v106, 0x7fffffff, v96
	v_pk_fma_f32 v[106:107], v[106:107], s[14:15], 1.0 op_sel_hi:[1,0,0]
	v_cmp_gt_f32_e32 vcc, 0, v96
	v_rcp_f32_e32 v106, v106
	v_rcp_f32_e32 v107, v107
	v_cmp_gt_f32_e64 s[10:11], 0, v97
	v_pk_fma_f32 v[110:111], v[106:107], s[42:43], v[108:109] op_sel_hi:[1,0,0]
	s_nop 0
	v_pk_fma_f32 v[110:111], v[106:107], v[110:111], s[0:1] op_sel_hi:[1,1,0]
	s_nop 0
	v_pk_fma_f32 v[110:111], v[106:107], v[110:111], s[50:51] op_sel_hi:[1,1,0]
	s_nop 0
	v_pk_fma_f32 v[110:111], v[106:107], v[110:111], s[34:35] op_sel_hi:[1,1,0]
	s_nop 0
	v_pk_mul_f32 v[106:107], v[106:107], v[110:111]
	v_pk_mul_f32 v[110:111], v[96:97], v[96:97]
	s_nop 0
	v_pk_mul_f32 v[110:111], v[110:111], s[46:47] op_sel_hi:[1,0]
	s_nop 0
	v_exp_f32_e32 v110, v110
	v_exp_f32_e32 v111, v111
	s_nop 0
	v_pk_mul_f32 v[106:107], v[110:111], v[106:107]
	s_nop 0
	v_pk_mul_f32 v[110:111], v[96:97], v[106:107]
	v_pk_fma_f32 v[106:107], v[96:97], v[106:107], v[96:97] neg_lo:[1,0,0] neg_hi:[1,0,0]
	s_nop 0
	v_cndmask_b32_e64 v97, v107, v111, s[10:11]
	v_cndmask_b32_e32 v96, v106, v110, vcc
	v_and_b32_e32 v107, 0x7fffffff, v99
	v_and_b32_e32 v106, 0x7fffffff, v98
	v_pk_fma_f32 v[106:107], v[106:107], s[14:15], 1.0 op_sel_hi:[1,0,0]
	v_cmp_gt_f32_e64 s[10:11], 0, v99
	v_rcp_f32_e32 v106, v106
	v_rcp_f32_e32 v107, v107
	v_cmp_gt_f32_e32 vcc, 0, v98
	v_pk_fma_f32 v[108:109], v[106:107], s[42:43], v[108:109] op_sel_hi:[1,0,0]
	s_nop 0
	v_pk_fma_f32 v[108:109], v[106:107], v[108:109], s[0:1] op_sel_hi:[1,1,0]
	s_nop 0
	v_pk_fma_f32 v[108:109], v[106:107], v[108:109], s[50:51] op_sel_hi:[1,1,0]
	s_nop 0
	v_pk_fma_f32 v[108:109], v[106:107], v[108:109], s[34:35] op_sel_hi:[1,1,0]
	s_nop 0
	v_pk_mul_f32 v[106:107], v[106:107], v[108:109]
	v_pk_mul_f32 v[108:109], v[98:99], v[98:99]
	s_nop 0
	v_pk_mul_f32 v[108:109], v[108:109], s[46:47] op_sel_hi:[1,0]
	s_nop 0
	v_exp_f32_e32 v108, v108
	v_exp_f32_e32 v109, v109
	s_nop 0
	v_pk_mul_f32 v[106:107], v[108:109], v[106:107]
	s_nop 0
	v_pk_mul_f32 v[108:109], v[98:99], v[106:107]
	v_pk_fma_f32 v[106:107], v[98:99], v[106:107], v[98:99] neg_lo:[1,0,0] neg_hi:[1,0,0]
	s_nop 0
	v_cndmask_b32_e64 v99, v107, v109, s[10:11]
	s_cselect_b32 s10, s15, s1
	s_cselect_b32 s11, s35, s43
	s_and_b32 s12, s37, 0x180
	s_lshl_b32 s48, s12, 1
	v_lshl_add_u64 v[110:111], s[10:11], 0, v[112:113]
	v_cndmask_b32_e32 v98, v106, v108, vcc
	v_lshl_add_u64 v[110:111], v[110:111], 0, s[48:49]
	s_cmpk_lt_i32 s37, 0x200
	v_cvt_pk_bf16_f32 v106, v100, v101
	v_cvt_pk_bf16_f32 v107, v102, v103
	v_cvt_pk_bf16_f32 v108, v96, v97
	v_cvt_pk_bf16_f32 v109, v98, v99
	v_lshl_add_u64 v[110:111], v[110:111], 0, v[140:141]
	global_store_dwordx4 v[110:111], v[106:109], off
	s_cbranch_scc1 .LBB0_731
	s_nop 0
	v_mov_b32_e32 v106, v141
	v_mov_b32_e32 v107, v101
	v_pk_add_f32 v[106:107], v[100:101], v[106:107]
	v_pk_mul_f32 v[108:109], v[100:101], v[100:101]
	v_pk_mul_f32 v[110:111], v[102:103], v[102:103]
	v_mov_b32_e32 v107, v109
	v_pk_mov_b32 v[100:101], v[100:101], v[108:109] op_sel:[1,0]
	v_pk_mul_f32 v[112:113], v[96:97], v[96:97]
	v_pk_add_f32 v[100:101], v[100:101], v[106:107]
	v_mov_b32_e32 v106, v102
	v_mov_b32_e32 v107, v110
	v_pk_add_f32 v[100:101], v[106:107], v[100:101]
	v_mov_b32_e32 v110, v103
	v_and_b32_e32 v117, 64, v175
	v_pk_add_f32 v[100:101], v[110:111], v[100:101]
	v_mov_b32_e32 v102, v96
	v_mov_b32_e32 v103, v112
	v_pk_mul_f32 v[114:115], v[98:99], v[98:99]
	v_xor_b32_e32 v116, 16, v175
	v_add_u32_e32 v117, 64, v117
	v_pk_add_f32 v[100:101], v[102:103], v[100:101]
	v_mov_b32_e32 v112, v97
	v_cmp_lt_i32_e32 vcc, v116, v117
	v_pk_add_f32 v[96:97], v[112:113], v[100:101]
	v_mov_b32_e32 v100, v98
	v_mov_b32_e32 v101, v114
	v_cndmask_b32_e32 v116, v175, v116, vcc
	v_pk_add_f32 v[96:97], v[100:101], v[96:97]
	v_mov_b32_e32 v114, v99
	v_lshlrev_b32_e32 v116, 2, v116
	v_pk_add_f32 v[96:97], v[114:115], v[96:97]
	ds_bpermute_b32 v98, v116, v96
	ds_bpermute_b32 v99, v116, v97
	v_xor_b32_e32 v100, 32, v175
	v_cmp_lt_i32_e32 vcc, v100, v117
	s_waitcnt lgkmcnt(0)
	v_pk_add_f32 v[96:97], v[96:97], v[98:99]
	v_cndmask_b32_e32 v100, v175, v100, vcc
	v_lshlrev_b32_e32 v100, 2, v100
	ds_bpermute_b32 v98, v100, v96
	ds_bpermute_b32 v99, v100, v97
	s_and_saveexec_b64 s[10:11], s[2:3]
	s_cbranch_execz .LBB0_730
	s_add_i32 s12, s94, 0xfffffe80
	s_lshr_b32 s48, s12, 5
	v_lshl_add_u64 v[100:101], v[104:105], 0, s[48:49]
	v_lshl_add_u64 v[100:101], v[100:101], 3, s[80:81]
	s_waitcnt lgkmcnt(0)
	v_pk_add_f32 v[96:97], v[96:97], v[98:99]
	global_store_dwordx2 v[100:101], v[96:97], off

; DI unsigned pk2(float lo, float hi) { typedef float v2f __attribute__((ext_vector_type(2))); typedef __bf16 v2b __attribute__((ext_vector_type(2))); v2f v = {lo, hi}; v2b b = __builtin_convertvector(v, v2b); return __builtin_bit_cast(unsigned, b); }
; DI void atomic_addf(float* p, float v) { __builtin_amdgcn_global_atomic_fadd_f32((__attribute__((address_space(1))) float*)p, v); }
; DI float quad_sum(float s) { s += __shfl_xor(s, 16); s += __shfl_xor(s, 32); return s; }
;     DI void operator()(const f32x4 (&acc)[2][2][4][2], const Unit& u, int wr, int wc, int fr, int fq) const {
;     ...
;                         u32x4 w; w.x = pk2(v[0], v[1]); w.y = pk2(v[2], v[3]); w.z = pk2(v[4], v[5]); w.w = pk2(v[6], v[7]);
;                         *(u32x4*)(dst + cw) = w;
;                         float s2 = 0.f;
; #pragma unroll
;                         for (int i = 0; i < 8; ++i) s2 += v[i] * v[i];
;                         s2 = quad_sum(s2);
;                         if (fq == 0) { if (isqm) *pp = s2; else atomic_addf(pp, s2); }
.LBB0_741:
	v_cvt_pk_bf16_f32 v112, v108, v109
	v_cvt_pk_bf16_f32 v113, v94, v95
	v_cvt_pk_bf16_f32 v114, v92, v93
	v_cvt_pk_bf16_f32 v115, v90, v91
	v_lshl_add_u64 v[110:111], v[110:111], 0, v[140:141]
	global_store_dwordx4 v[110:111], v[112:115], off
	v_pk_mul_f32 v[110:111], v[108:109], v[108:109]
	v_pk_mul_f32 v[116:117], v[90:91], v[90:91]
	v_pk_mul_f32 v[112:113], v[94:95], v[94:95]
	v_add_f32_e32 v107, v110, v111
	v_add_f32_e32 v107, v112, v107
	v_pk_mul_f32 v[114:115], v[92:93], v[92:93]
	v_add_f32_e32 v107, v113, v107
	v_and_b32_e32 v111, 64, v175
	v_add_f32_e32 v107, v114, v107
	v_xor_b32_e32 v110, 16, v175
	v_add_u32_e32 v111, 64, v111
	v_add_f32_e32 v107, v115, v107
	v_cmp_lt_i32_e32 vcc, v110, v111
	v_add_f32_e32 v107, v116, v107
	v_add_f32_e32 v107, v117, v107
	v_cndmask_b32_e32 v110, v175, v110, vcc
	v_lshlrev_b32_e32 v110, 2, v110
	ds_bpermute_b32 v110, v110, v107
	s_waitcnt lgkmcnt(0)
	v_add_f32_e32 v107, v107, v110
	v_xor_b32_e32 v110, 32, v175
	v_cmp_lt_i32_e32 vcc, v110, v111
	s_nop 1
	v_cndmask_b32_e32 v110, v175, v110, vcc
	v_lshlrev_b32_e32 v110, 2, v110
	ds_bpermute_b32 v110, v110, v107
	s_and_saveexec_b64 s[10:11], s[2:3]
	s_cbranch_execz .LBB0_746
	s_waitcnt lgkmcnt(0)
	v_add_f32_e32 v107, v107, v110
	s_cmpk_gt_u32 s94, 0x67f
	s_mov_b64 s[12:13], -1
	s_cbranch_scc1 .LBB0_744
	global_atomic_add_f32 v[88:89], v107, off
	s_mov_b64 s[12:13], 0
.LBB0_744:
	s_andn2_b64 vcc, exec, s[12:13]
	s_cbranch_vccnz .LBB0_746
	global_store_dword v[88:89], v107, off

; DI unsigned pk2(float lo, float hi) { typedef float v2f __attribute__((ext_vector_type(2))); typedef __bf16 v2b __attribute__((ext_vector_type(2))); v2f v = {lo, hi}; v2b b = __builtin_convertvector(v, v2b); return __builtin_bit_cast(unsigned, b); }
; DI float quad_sum(float s) { s += __shfl_xor(s, 16); s += __shfl_xor(s, 32); return s; }
; __device__ __forceinline__ f32x2 gelu_pk(f32x2 v) {
;     const f32x2 av = __builtin_elementwise_abs(v), d = av * 0.2316418882f + 1.0f;
;     f32x2 t; t.x = __builtin_amdgcn_rcpf(d.x); t.y = __builtin_amdgcn_rcpf(d.y);
;     f32x2 q = t * 0.5307027145f + (-0.7265760135f); q = q * t + 0.7107068705f; q = q * t + (-0.142248368f); q = q * t + 0.127414796f; q = q * t;
;     const f32x2 s = (v * v) * (-0.72134752044f);
;     f32x2 e; e.x = __builtin_amdgcn_exp2f(s.x); e.y = __builtin_amdgcn_exp2f(s.y);
;     const f32x2 m = v * (q * e), r = v - m;
;     f32x2 o; o.x = v.x < 0.f ? m.x : r.x; o.y = v.y < 0.f ? m.y : r.y; return o;
; }
;     DI void operator()(const f32x4 (&acc)[2][2][4][2], const Unit& u, int wr, int wc, int fr, int fq) const {
;     ...
;                     if (c128 < 1024) {
; #pragma unroll
;                         for (int i = 0; i < 8; i += 2) { const f32x2 g = pg8::gelu_pk((f32x2){v[i], v[i + 1]}); v[i] = g.x; v[i + 1] = g.y; }
;                         const bool isv = c128 >= 512;
;                         u32x4 w; w.x = pk2(v[0], v[1]); w.y = pk2(v[2], v[3]); w.z = pk2(v[4], v[5]); w.w = pk2(v[6], v[7]);
;                         *(u32x4*)((isv ? Vg : U) + (size_t)row * 512 + (c128 & 511) + cw) = w;
;                         if (isv) {
;                             float s1 = 0.f, s2 = 0.f;
; #pragma unroll
;                             for (int i = 0; i < 8; ++i) { s1 += v[i]; s2 += v[i] * v[i]; }
;                             s1 = quad_sum(s1); s2 = quad_sum(s2);
;                             if (fq == 0) { float* d = VST + ((size_t)row * 16 + ((c128 - 512) >> 7) * 4 + wc) * 2; d[0] = s1; d[1] = s2; }
;                         }
.LBB0_748:
	v_lshlrev_b64 v[88:89], 4, v[98:99]
	s_andn2_b64 vcc, exec, s[10:11]
	v_or_b32_e32 v88, s97, v88
	s_cbranch_vccnz .LBB0_753
	v_and_b32_e32 v111, 0x7fffffff, v109
	s_waitcnt lgkmcnt(0)
	v_and_b32_e32 v110, 0x7fffffff, v108
	v_pk_fma_f32 v[110:111], v[110:111], s[14:15], 1.0 op_sel_hi:[1,0,0]
	v_mov_b64_e32 v[112:113], s[96:97]
	v_rcp_f32_e32 v110, v110
	v_rcp_f32_e32 v111, v111
	v_cmp_gt_f32_e32 vcc, 0, v108
	v_cmp_gt_f32_e64 s[10:11], 0, v109
	s_cmp_gt_i32 s60, 1
	v_pk_fma_f32 v[114:115], v[110:111], s[42:43], v[112:113] op_sel_hi:[1,0,0]
	s_nop 0
	v_pk_fma_f32 v[114:115], v[110:111], v[114:115], s[0:1] op_sel_hi:[1,1,0]
	s_nop 0
	v_pk_fma_f32 v[114:115], v[110:111], v[114:115], s[50:51] op_sel_hi:[1,1,0]
	s_nop 0
	v_pk_fma_f32 v[114:115], v[110:111], v[114:115], s[34:35] op_sel_hi:[1,1,0]
	s_nop 0
	v_pk_mul_f32 v[110:111], v[110:111], v[114:115]
	v_pk_mul_f32 v[114:115], v[108:109], v[108:109]
	s_nop 0
	v_pk_mul_f32 v[114:115], v[114:115], s[46:47] op_sel_hi:[1,0]
	s_nop 0
	v_exp_f32_e32 v114, v114
	v_exp_f32_e32 v115, v115
	s_nop 0
	v_pk_mul_f32 v[110:111], v[114:115], v[110:111]
	s_nop 0
	v_pk_mul_f32 v[114:115], v[108:109], v[110:111]
	v_pk_fma_f32 v[110:111], v[108:109], v[110:111], v[108:109] neg_lo:[1,0,0] neg_hi:[1,0,0]
	s_nop 0
	v_cndmask_b32_e64 v109, v111, v115, s[10:11]
	v_cndmask_b32_e32 v108, v110, v114, vcc
	v_and_b32_e32 v111, 0x7fffffff, v95
	v_and_b32_e32 v110, 0x7fffffff, v94
	v_pk_fma_f32 v[110:111], v[110:111], s[14:15], 1.0 op_sel_hi:[1,0,0]
	v_cmp_gt_f32_e32 vcc, 0, v94
	v_rcp_f32_e32 v110, v110
	v_rcp_f32_e32 v111, v111
	v_cmp_gt_f32_e64 s[10:11], 0, v95
	v_pk_fma_f32 v[114:115], v[110:111], s[42:43], v[112:113] op_sel_hi:[1,0,0]
	s_nop 0
	v_pk_fma_f32 v[114:115], v[110:111], v[114:115], s[0:1] op_sel_hi:[1,1,0]
	s_nop 0
	v_pk_fma_f32 v[114:115], v[110:111], v[114:115], s[50:51] op_sel_hi:[1,1,0]
	s_nop 0
	v_pk_fma_f32 v[114:115], v[110:111], v[114:115], s[34:35] op_sel_hi:[1,1,0]
	s_nop 0
	v_pk_mul_f32 v[110:111], v[110:111], v[114:115]
	v_pk_mul_f32 v[114:115], v[94:95], v[94:95]
	s_nop 0
	v_pk_mul_f32 v[114:115], v[114:115], s[46:47] op_sel_hi:[1,0]
	s_nop 0
	v_exp_f32_e32 v114, v114
	v_exp_f32_e32 v115, v115
	s_nop 0
	v_pk_mul_f32 v[110:111], v[114:115], v[110:111]
	s_nop 0
	v_pk_mul_f32 v[114:115], v[94:95], v[110:111]
	v_pk_fma_f32 v[110:111], v[94:95], v[110:111], v[94:95] neg_lo:[1,0,0] neg_hi:[1,0,0]
	s_nop 0
	v_cndmask_b32_e64 v95, v111, v115, s[10:11]
	v_cndmask_b32_e32 v94, v110, v114, vcc
	v_and_b32_e32 v111, 0x7fffffff, v93
	v_and_b32_e32 v110, 0x7fffffff, v92
	v_pk_fma_f32 v[110:111], v[110:111], s[14:15], 1.0 op_sel_hi:[1,0,0]
	v_cmp_gt_f32_e32 vcc, 0, v92
	v_rcp_f32_e32 v110, v110
	v_rcp_f32_e32 v111, v111
	v_cmp_gt_f32_e64 s[10:11], 0, v93
	v_pk_fma_f32 v[114:115], v[110:111], s[42:43], v[112:113] op_sel_hi:[1,0,0]
	s_nop 0
	v_pk_fma_f32 v[114:115], v[110:111], v[114:115], s[0:1] op_sel_hi:[1,1,0]
	s_nop 0
	v_pk_fma_f32 v[114:115], v[110:111], v[114:115], s[50:51] op_sel_hi:[1,1,0]
	s_nop 0
	v_pk_fma_f32 v[114:115], v[110:111], v[114:115], s[34:35] op_sel_hi:[1,1,0]
	s_nop 0
	v_pk_mul_f32 v[110:111], v[110:111], v[114:115]
	v_pk_mul_f32 v[114:115], v[92:93], v[92:93]
	s_nop 0
	v_pk_mul_f32 v[114:115], v[114:115], s[46:47] op_sel_hi:[1,0]
	s_nop 0
	v_exp_f32_e32 v114, v114
	v_exp_f32_e32 v115, v115
	s_nop 0
	v_pk_mul_f32 v[110:111], v[114:115], v[110:111]
	s_nop 0
	v_pk_mul_f32 v[114:115], v[92:93], v[110:111]
	v_pk_fma_f32 v[110:111], v[92:93], v[110:111], v[92:93] neg_lo:[1,0,0] neg_hi:[1,0,0]
	s_nop 0
	v_cndmask_b32_e64 v93, v111, v115, s[10:11]
	v_cndmask_b32_e32 v92, v110, v114, vcc
	v_and_b32_e32 v111, 0x7fffffff, v91
	v_and_b32_e32 v110, 0x7fffffff, v90
	v_pk_fma_f32 v[110:111], v[110:111], s[14:15], 1.0 op_sel_hi:[1,0,0]
	v_cmp_gt_f32_e64 s[10:11], 0, v91
	v_rcp_f32_e32 v110, v110
	v_rcp_f32_e32 v111, v111
	v_cmp_gt_f32_e32 vcc, 0, v90
	v_pk_fma_f32 v[112:113], v[110:111], s[42:43], v[112:113] op_sel_hi:[1,0,0]
	s_nop 0
	v_pk_fma_f32 v[112:113], v[110:111], v[112:113], s[0:1] op_sel_hi:[1,1,0]
	s_nop 0
	v_pk_fma_f32 v[112:113], v[110:111], v[112:113], s[50:51] op_sel_hi:[1,1,0]
	s_nop 0
	v_pk_fma_f32 v[112:113], v[110:111], v[112:113], s[34:35] op_sel_hi:[1,1,0]
	s_nop 0
	v_pk_mul_f32 v[110:111], v[110:111], v[112:113]
	v_pk_mul_f32 v[112:113], v[90:91], v[90:91]
	s_nop 0
	v_pk_mul_f32 v[112:113], v[112:113], s[46:47] op_sel_hi:[1,0]
	s_nop 0
	v_exp_f32_e32 v112, v112
	v_exp_f32_e32 v113, v113
	s_nop 0
	v_pk_mul_f32 v[110:111], v[112:113], v[110:111]
	s_nop 0
	v_pk_mul_f32 v[112:113], v[90:91], v[110:111]
	v_pk_fma_f32 v[110:111], v[90:91], v[110:111], v[90:91] neg_lo:[1,0,0] neg_hi:[1,0,0]
	s_nop 0
	v_cndmask_b32_e64 v91, v111, v113, s[10:11]
	s_cselect_b32 s10, s15, s1
	s_cselect_b32 s11, s35, s43
	s_and_b32 s12, s94, 0x100
	s_lshl_b32 s48, s12, 1
	v_lshl_add_u64 v[114:115], s[10:11], 0, v[96:97]
	v_cndmask_b32_e32 v90, v110, v112, vcc
	v_lshl_add_u64 v[114:115], v[114:115], 0, s[48:49]
	s_cmp_lt_i32 s60, 2
	v_cvt_pk_bf16_f32 v110, v108, v109
	v_cvt_pk_bf16_f32 v111, v94, v95
	v_cvt_pk_bf16_f32 v112, v92, v93
	v_cvt_pk_bf16_f32 v113, v90, v91
	v_lshl_add_u64 v[114:115], v[114:115], 0, v[140:141]
	global_store_dwordx4 v[114:115], v[110:113], off
	s_cbranch_scc1 .LBB0_753
	s_nop 0
	v_mov_b32_e32 v110, v141
	v_mov_b32_e32 v111, v109
	v_pk_add_f32 v[110:111], v[108:109], v[110:111]
	v_pk_mul_f32 v[112:113], v[108:109], v[108:109]
	v_pk_mul_f32 v[114:115], v[94:95], v[94:95]
	v_mov_b32_e32 v111, v113
	v_pk_mov_b32 v[108:109], v[108:109], v[112:113] op_sel:[1,0]
	v_pk_mul_f32 v[116:117], v[92:93], v[92:93]
	v_pk_add_f32 v[108:109], v[108:109], v[110:111]
	v_mov_b32_e32 v110, v94
	v_mov_b32_e32 v111, v114
	v_pk_add_f32 v[108:109], v[110:111], v[108:109]
	v_mov_b32_e32 v114, v95
	v_and_b32_e32 v120, 64, v175
	v_pk_add_f32 v[94:95], v[114:115], v[108:109]
	v_mov_b32_e32 v108, v92
	v_mov_b32_e32 v109, v116
	v_pk_mul_f32 v[118:119], v[90:91], v[90:91]
	v_xor_b32_e32 v107, 16, v175
	v_add_u32_e32 v120, 64, v120
	v_pk_add_f32 v[94:95], v[108:109], v[94:95]
	v_mov_b32_e32 v116, v93
	v_cmp_lt_i32_e32 vcc, v107, v120
	v_pk_add_f32 v[92:93], v[116:117], v[94:95]
	v_mov_b32_e32 v94, v90
	v_mov_b32_e32 v95, v118
	v_cndmask_b32_e32 v107, v175, v107, vcc
	v_pk_add_f32 v[92:93], v[94:95], v[92:93]
	v_mov_b32_e32 v118, v91
	v_lshlrev_b32_e32 v107, 2, v107
	v_pk_add_f32 v[90:91], v[118:119], v[92:93]
	ds_bpermute_b32 v92, v107, v90
	ds_bpermute_b32 v93, v107, v91
	v_xor_b32_e32 v94, 32, v175
	v_cmp_lt_i32_e32 vcc, v94, v120
	s_waitcnt lgkmcnt(0)
	v_pk_add_f32 v[90:91], v[90:91], v[92:93]
	v_cndmask_b32_e32 v94, v175, v94, vcc
	v_lshlrev_b32_e32 v94, 2, v94
	ds_bpermute_b32 v92, v94, v90
	ds_bpermute_b32 v93, v94, v91
	s_and_saveexec_b64 s[10:11], s[2:3]
	s_cbranch_execz .LBB0_752
	s_add_i32 s12, s94, 0xfffffe00
	s_lshr_b32 s48, s12, 5
	v_lshl_add_u64 v[94:95], v[88:89], 0, s[48:49]
	v_lshl_add_u64 v[94:95], v[94:95], 3, s[80:81]
	s_waitcnt lgkmcnt(0)
	v_pk_add_f32 v[90:91], v[90:91], v[92:93]
	global_store_dwordx2 v[94:95], v[90:91], off

; DI float quad_sum(float s) { s += __shfl_xor(s, 16); s += __shfl_xor(s, 32); return s; }
;     DI void operator()(const f32x4 (&acc)[2][2][4][2], const Unit& u, int wr, int wc, int fr, int fq) const {
;     ...
;                         for (int i = 0; i < 4; ++i) v[4 * n + i] = acc[ai][bj][m][n][i] * rs;
;                     if (c128 < 1024) {
; #pragma unroll
;                         for (int i = 0; i < 8; i += 2) { const f32x2 g = pg8::gelu_pk((f32x2){v[i], v[i + 1]}); v[i] = g.x; v[i + 1] = g.y; }
;                         const bool isv = c128 >= 512;
;                         u32x4 w; w.x = pk2(v[0], v[1]); w.y = pk2(v[2], v[3]); w.z = pk2(v[4], v[5]); w.w = pk2(v[6], v[7]);
;                         *(u32x4*)((isv ? Vg : U) + (size_t)row * 512 + (c128 & 511) + cw) = w;
;                         if (isv) {
;                             float s1 = 0.f, s2 = 0.f;
; #pragma unroll
;                             for (int i = 0; i < 8; ++i) { s1 += v[i]; s2 += v[i] * v[i]; }
;                             s1 = quad_sum(s1); s2 = quad_sum(s2);
;                             if (fq == 0) { float* d = VST + ((size_t)row * 16 + ((c128 - 512) >> 7) * 4 + wc) * 2; d[0] = s1; d[1] = s2; }
;                         }
;                     } else if (c128 < 2176) {
;                         bf16_t* dst; float* pp; const bool isqm = c128 >= 1664;
;                         if (c128 < 1408) { dst = CQ + (size_t)row * 384 + (c128 - 1024); pp = CQP + row; }
;                         else if (c128 < 1664) { dst = CKV + (size_t)row * 256 + (c128 - 1408); pp = CKVP + row; }
;                         else { dst = QM + (size_t)row * 512 + (c128 - 1664); pp = QMP + (size_t)row * 16 + ((c128 - 1664) >> 7) * 4 + wc; }
;                         u32x4 w; w.x = pk2(v[0], v[1]); w.y = pk2(v[2], v[3]); w.z = pk2(v[4], v[5]); w.w = pk2(v[6], v[7]);
;                         *(u32x4*)(dst + cw) = w;
;                         float s2 = 0.f;
; #pragma unroll
;                         for (int i = 0; i < 8; ++i) s2 += v[i] * v[i];
;                         s2 = quad_sum(s2);
;                         if (fq == 0) { if (isqm) *pp = s2; else atomic_addf(pp, s2); }
;                     } else if (c128 == 2176) {
;                         if (wc == 0) { float* d = KR + (size_t)row * 32 + 8 * fq; *(f32x4*)d = (f32x4){v[0], v[1], v[2], v[3]}; *(f32x4*)(d + 4) = (f32x4){v[4], v[5], v[6], v[7]}; }
.LBB0_753:
	v_mov_b32_e32 v107, v106
	v_pk_mul_f32 v[84:85], v[84:85], v[106:107]
	v_pk_mul_f32 v[86:87], v[86:87], v[106:107]
	v_pk_mul_f32 v[80:81], v[80:81], v[106:107]
	v_pk_mul_f32 v[82:83], v[82:83], v[106:107]
	s_and_b64 vcc, exec, s[6:7]
	s_mov_b64 s[10:11], -1
	s_cbranch_vccnz .LBB0_774
	s_cmpk_lt_u32 s37, 0x880
	s_cbranch_scc1 .LBB0_758
	s_cmp_lg_u32 s60, 8
	s_cselect_b64 s[10:11], -1, 0
	s_or_b64 s[10:11], s[72:73], s[10:11]
	s_and_b64 vcc, exec, s[10:11]
	s_cbranch_vccnz .LBB0_757
	v_lshlrev_b64 v[90:91], 7, v[98:99]
	v_lshl_add_u64 v[90:91], v[144:145], 0, v[90:91]
	global_store_dwordx4 v[90:91], v[84:87], off
	global_store_dwordx4 v[90:91], v[80:83], off offset:16

; DI unsigned pk2(float lo, float hi) { typedef float v2f __attribute__((ext_vector_type(2))); typedef __bf16 v2b __attribute__((ext_vector_type(2))); v2f v = {lo, hi}; v2b b = __builtin_convertvector(v, v2b); return __builtin_bit_cast(unsigned, b); }
; DI void atomic_addf(float* p, float v) { __builtin_amdgcn_global_atomic_fadd_f32((__attribute__((address_space(1))) float*)p, v); }
; DI float quad_sum(float s) { s += __shfl_xor(s, 16); s += __shfl_xor(s, 32); return s; }
;     DI void operator()(const f32x4 (&acc)[2][2][4][2], const Unit& u, int wr, int wc, int fr, int fq) const {
;     ...
;                         u32x4 w; w.x = pk2(v[0], v[1]); w.y = pk2(v[2], v[3]); w.z = pk2(v[4], v[5]); w.w = pk2(v[6], v[7]);
;                         *(u32x4*)(dst + cw) = w;
;                         float s2 = 0.f;
; #pragma unroll
;                         for (int i = 0; i < 8; ++i) s2 += v[i] * v[i];
;                         s2 = quad_sum(s2);
;                         if (fq == 0) { if (isqm) *pp = s2; else atomic_addf(pp, s2); }
.LBB0_767:
	v_cvt_pk_bf16_f32 v98, v84, v85
	v_cvt_pk_bf16_f32 v99, v86, v87
	v_cvt_pk_bf16_f32 v100, v80, v81
	v_cvt_pk_bf16_f32 v101, v82, v83
	s_waitcnt lgkmcnt(0)
	v_lshl_add_u64 v[92:93], v[92:93], 0, v[140:141]
	global_store_dwordx4 v[92:93], v[98:101], off
	v_pk_mul_f32 v[92:93], v[84:85], v[84:85]
	v_pk_mul_f32 v[94:95], v[86:87], v[86:87]
	v_add_f32_e32 v92, v92, v93
	v_add_f32_e32 v92, v94, v92
	v_pk_mul_f32 v[98:99], v[80:81], v[80:81]
	v_add_f32_e32 v92, v95, v92
	v_and_b32_e32 v94, 64, v175
	v_add_f32_e32 v92, v98, v92
	v_xor_b32_e32 v93, 16, v175
	v_add_u32_e32 v94, 64, v94
	v_pk_mul_f32 v[100:101], v[82:83], v[82:83]
	v_add_f32_e32 v92, v99, v92
	v_cmp_lt_i32_e32 vcc, v93, v94
	v_add_f32_e32 v92, v100, v92
	v_add_f32_e32 v92, v101, v92
	v_cndmask_b32_e32 v93, v175, v93, vcc
	v_lshlrev_b32_e32 v93, 2, v93
	ds_bpermute_b32 v93, v93, v92
	s_waitcnt lgkmcnt(0)
	v_add_f32_e32 v92, v92, v93
	v_xor_b32_e32 v93, 32, v175
	v_cmp_lt_i32_e32 vcc, v93, v94
	s_nop 1
	v_cndmask_b32_e32 v93, v175, v93, vcc
	v_lshlrev_b32_e32 v93, 2, v93
	ds_bpermute_b32 v93, v93, v92
	s_and_saveexec_b64 s[10:11], s[2:3]
	s_cbranch_execz .LBB0_772
	s_waitcnt lgkmcnt(0)
	v_add_f32_e32 v92, v92, v93
	s_cmpk_gt_u32 s37, 0x67f
	s_mov_b64 s[12:13], -1
	s_cbranch_scc1 .LBB0_770
	global_atomic_add_f32 v[90:91], v92, off
	s_mov_b64 s[12:13], 0
.LBB0_770:
	s_andn2_b64 vcc, exec, s[12:13]
	s_cbranch_vccnz .LBB0_772
	global_store_dword v[90:91], v92, off

; DI unsigned pk2(float lo, float hi) { typedef float v2f __attribute__((ext_vector_type(2))); typedef __bf16 v2b __attribute__((ext_vector_type(2))); v2f v = {lo, hi}; v2b b = __builtin_convertvector(v, v2b); return __builtin_bit_cast(unsigned, b); }
; DI float quad_sum(float s) { s += __shfl_xor(s, 16); s += __shfl_xor(s, 32); return s; }
; __device__ __forceinline__ f32x2 gelu_pk(f32x2 v) {
;     const f32x2 av = __builtin_elementwise_abs(v), d = av * 0.2316418882f + 1.0f;
;     f32x2 t; t.x = __builtin_amdgcn_rcpf(d.x); t.y = __builtin_amdgcn_rcpf(d.y);
;     f32x2 q = t * 0.5307027145f + (-0.7265760135f); q = q * t + 0.7107068705f; q = q * t + (-0.142248368f); q = q * t + 0.127414796f; q = q * t;
;     const f32x2 s = (v * v) * (-0.72134752044f);
;     f32x2 e; e.x = __builtin_amdgcn_exp2f(s.x); e.y = __builtin_amdgcn_exp2f(s.y);
;     const f32x2 m = v * (q * e), r = v - m;
;     f32x2 o; o.x = v.x < 0.f ? m.x : r.x; o.y = v.y < 0.f ? m.y : r.y; return o;
; }
;     DI void operator()(const f32x4 (&acc)[2][2][4][2], const Unit& u, int wr, int wc, int fr, int fq) const {
;     ...
;                     if (c128 < 1024) {
; #pragma unroll
;                         for (int i = 0; i < 8; i += 2) { const f32x2 g = pg8::gelu_pk((f32x2){v[i], v[i + 1]}); v[i] = g.x; v[i + 1] = g.y; }
;                         const bool isv = c128 >= 512;
;                         u32x4 w; w.x = pk2(v[0], v[1]); w.y = pk2(v[2], v[3]); w.z = pk2(v[4], v[5]); w.w = pk2(v[6], v[7]);
;                         *(u32x4*)((isv ? Vg : U) + (size_t)row * 512 + (c128 & 511) + cw) = w;
;                         if (isv) {
;                             float s1 = 0.f, s2 = 0.f;
; #pragma unroll
;                             for (int i = 0; i < 8; ++i) { s1 += v[i]; s2 += v[i] * v[i]; }
;                             s1 = quad_sum(s1); s2 = quad_sum(s2);
;                             if (fq == 0) { float* d = VST + ((size_t)row * 16 + ((c128 - 512) >> 7) * 4 + wc) * 2; d[0] = s1; d[1] = s2; }
;                         }
.LBB0_774:
	s_andn2_b64 vcc, exec, s[10:11]
	s_cbranch_vccnz .LBB0_779
	v_and_b32_e32 v91, 0x7fffffff, v85
	v_and_b32_e32 v90, 0x7fffffff, v84
	v_pk_fma_f32 v[90:91], v[90:91], s[14:15], 1.0 op_sel_hi:[1,0,0]
	s_waitcnt lgkmcnt(0)
	v_mov_b64_e32 v[92:93], s[96:97]
	v_rcp_f32_e32 v90, v90
	v_rcp_f32_e32 v91, v91
	v_cmp_gt_f32_e32 vcc, 0, v84
	v_cmp_gt_f32_e64 s[10:11], 0, v85
	s_cmpk_gt_i32 s37, 0x1ff
	v_pk_fma_f32 v[94:95], v[90:91], s[42:43], v[92:93] op_sel_hi:[1,0,0]
	s_nop 0
	v_pk_fma_f32 v[94:95], v[90:91], v[94:95], s[0:1] op_sel_hi:[1,1,0]
	s_nop 0
	v_pk_fma_f32 v[94:95], v[90:91], v[94:95], s[50:51] op_sel_hi:[1,1,0]
	s_nop 0
	v_pk_fma_f32 v[94:95], v[90:91], v[94:95], s[34:35] op_sel_hi:[1,1,0]
	s_nop 0
	v_pk_mul_f32 v[90:91], v[90:91], v[94:95]
	v_pk_mul_f32 v[94:95], v[84:85], v[84:85]
	s_nop 0
	v_pk_mul_f32 v[94:95], v[94:95], s[46:47] op_sel_hi:[1,0]
	s_nop 0
	v_exp_f32_e32 v94, v94
	v_exp_f32_e32 v95, v95
	s_nop 0
	v_pk_mul_f32 v[90:91], v[94:95], v[90:91]
	s_nop 0
	v_pk_mul_f32 v[94:95], v[84:85], v[90:91]
	v_pk_fma_f32 v[90:91], v[84:85], v[90:91], v[84:85] neg_lo:[1,0,0] neg_hi:[1,0,0]
	s_nop 0
	v_cndmask_b32_e64 v85, v91, v95, s[10:11]
	v_cndmask_b32_e32 v84, v90, v94, vcc
	v_and_b32_e32 v91, 0x7fffffff, v87
	v_and_b32_e32 v90, 0x7fffffff, v86
	v_pk_fma_f32 v[90:91], v[90:91], s[14:15], 1.0 op_sel_hi:[1,0,0]
	v_cmp_gt_f32_e32 vcc, 0, v86
	v_rcp_f32_e32 v90, v90
	v_rcp_f32_e32 v91, v91
	v_cmp_gt_f32_e64 s[10:11], 0, v87
	v_pk_fma_f32 v[94:95], v[90:91], s[42:43], v[92:93] op_sel_hi:[1,0,0]
	s_nop 0
	v_pk_fma_f32 v[94:95], v[90:91], v[94:95], s[0:1] op_sel_hi:[1,1,0]
	s_nop 0
	v_pk_fma_f32 v[94:95], v[90:91], v[94:95], s[50:51] op_sel_hi:[1,1,0]
	s_nop 0
	v_pk_fma_f32 v[94:95], v[90:91], v[94:95], s[34:35] op_sel_hi:[1,1,0]
	s_nop 0
	v_pk_mul_f32 v[90:91], v[90:91], v[94:95]
	v_pk_mul_f32 v[94:95], v[86:87], v[86:87]
	s_nop 0
	v_pk_mul_f32 v[94:95], v[94:95], s[46:47] op_sel_hi:[1,0]
	s_nop 0
	v_exp_f32_e32 v94, v94
	v_exp_f32_e32 v95, v95
	s_nop 0
	v_pk_mul_f32 v[90:91], v[94:95], v[90:91]
	s_nop 0
	v_pk_mul_f32 v[94:95], v[86:87], v[90:91]
	v_pk_fma_f32 v[90:91], v[86:87], v[90:91], v[86:87] neg_lo:[1,0,0] neg_hi:[1,0,0]
	s_nop 0
	v_cndmask_b32_e64 v87, v91, v95, s[10:11]
	v_cndmask_b32_e32 v86, v90, v94, vcc
	v_and_b32_e32 v91, 0x7fffffff, v81
	v_and_b32_e32 v90, 0x7fffffff, v80
	v_pk_fma_f32 v[90:91], v[90:91], s[14:15], 1.0 op_sel_hi:[1,0,0]
	v_cmp_gt_f32_e32 vcc, 0, v80
	v_rcp_f32_e32 v90, v90
	v_rcp_f32_e32 v91, v91
	v_cmp_gt_f32_e64 s[10:11], 0, v81
	v_pk_fma_f32 v[94:95], v[90:91], s[42:43], v[92:93] op_sel_hi:[1,0,0]
	s_nop 0
	v_pk_fma_f32 v[94:95], v[90:91], v[94:95], s[0:1] op_sel_hi:[1,1,0]
	s_nop 0
	v_pk_fma_f32 v[94:95], v[90:91], v[94:95], s[50:51] op_sel_hi:[1,1,0]
	s_nop 0
	v_pk_fma_f32 v[94:95], v[90:91], v[94:95], s[34:35] op_sel_hi:[1,1,0]
	s_nop 0
	v_pk_mul_f32 v[90:91], v[90:91], v[94:95]
	v_pk_mul_f32 v[94:95], v[80:81], v[80:81]
	s_nop 0
	v_pk_mul_f32 v[94:95], v[94:95], s[46:47] op_sel_hi:[1,0]
	s_nop 0
	v_exp_f32_e32 v94, v94
	v_exp_f32_e32 v95, v95
	s_nop 0
	v_pk_mul_f32 v[90:91], v[94:95], v[90:91]
	s_nop 0
	v_pk_mul_f32 v[94:95], v[80:81], v[90:91]
	v_pk_fma_f32 v[90:91], v[80:81], v[90:91], v[80:81] neg_lo:[1,0,0] neg_hi:[1,0,0]
	s_nop 0
	v_cndmask_b32_e64 v81, v91, v95, s[10:11]
	v_cndmask_b32_e32 v80, v90, v94, vcc
	v_and_b32_e32 v91, 0x7fffffff, v83
	v_and_b32_e32 v90, 0x7fffffff, v82
	v_pk_fma_f32 v[90:91], v[90:91], s[14:15], 1.0 op_sel_hi:[1,0,0]
	v_cmp_gt_f32_e64 s[10:11], 0, v83
	v_rcp_f32_e32 v90, v90
	v_rcp_f32_e32 v91, v91
	v_cmp_gt_f32_e32 vcc, 0, v82
	v_pk_fma_f32 v[92:93], v[90:91], s[42:43], v[92:93] op_sel_hi:[1,0,0]
	s_nop 0
	v_pk_fma_f32 v[92:93], v[90:91], v[92:93], s[0:1] op_sel_hi:[1,1,0]
	s_nop 0
	v_pk_fma_f32 v[92:93], v[90:91], v[92:93], s[50:51] op_sel_hi:[1,1,0]
	s_nop 0
	v_pk_fma_f32 v[92:93], v[90:91], v[92:93], s[34:35] op_sel_hi:[1,1,0]
	s_nop 0
	v_pk_mul_f32 v[90:91], v[90:91], v[92:93]
	v_pk_mul_f32 v[92:93], v[82:83], v[82:83]
	s_nop 0
	v_pk_mul_f32 v[92:93], v[92:93], s[46:47] op_sel_hi:[1,0]
	s_nop 0
	v_exp_f32_e32 v92, v92
	v_exp_f32_e32 v93, v93
	s_nop 0
	v_pk_mul_f32 v[90:91], v[92:93], v[90:91]
	s_nop 0
	v_pk_mul_f32 v[92:93], v[82:83], v[90:91]
	v_pk_fma_f32 v[90:91], v[82:83], v[90:91], v[82:83] neg_lo:[1,0,0] neg_hi:[1,0,0]
	s_nop 0
	v_cndmask_b32_e64 v83, v91, v93, s[10:11]
	s_cselect_b32 s10, s15, s1
	s_cselect_b32 s11, s35, s43
	s_and_b32 s12, s37, 0x180
	s_lshl_b32 s48, s12, 1
	v_lshl_add_u64 v[94:95], s[10:11], 0, v[96:97]
	v_cndmask_b32_e32 v82, v90, v92, vcc
	v_lshl_add_u64 v[94:95], v[94:95], 0, s[48:49]
	s_cmpk_lt_i32 s37, 0x200
	v_cvt_pk_bf16_f32 v90, v84, v85
	v_cvt_pk_bf16_f32 v91, v86, v87
	v_cvt_pk_bf16_f32 v92, v80, v81
	v_cvt_pk_bf16_f32 v93, v82, v83
	v_lshl_add_u64 v[94:95], v[94:95], 0, v[140:141]
	global_store_dwordx4 v[94:95], v[90:93], off
	s_cbranch_scc1 .LBB0_779
	s_nop 0
	v_mov_b32_e32 v90, v141
	v_mov_b32_e32 v91, v85
	v_pk_add_f32 v[90:91], v[84:85], v[90:91]
	v_pk_mul_f32 v[92:93], v[84:85], v[84:85]
	v_pk_mul_f32 v[94:95], v[86:87], v[86:87]
	v_mov_b32_e32 v91, v93
	v_pk_mov_b32 v[84:85], v[84:85], v[92:93] op_sel:[1,0]
	v_pk_mul_f32 v[96:97], v[80:81], v[80:81]
	v_pk_add_f32 v[84:85], v[84:85], v[90:91]
	v_mov_b32_e32 v90, v86
	v_mov_b32_e32 v91, v94
	v_pk_add_f32 v[84:85], v[90:91], v[84:85]
	v_mov_b32_e32 v94, v87
	v_and_b32_e32 v101, 64, v175
	v_pk_add_f32 v[84:85], v[94:95], v[84:85]
	v_mov_b32_e32 v86, v80
	v_mov_b32_e32 v87, v96
	v_pk_mul_f32 v[98:99], v[82:83], v[82:83]
	v_xor_b32_e32 v100, 16, v175
	v_add_u32_e32 v101, 64, v101
	v_pk_add_f32 v[84:85], v[86:87], v[84:85]
	v_mov_b32_e32 v96, v81
	v_cmp_lt_i32_e32 vcc, v100, v101
	v_pk_add_f32 v[80:81], v[96:97], v[84:85]
	v_mov_b32_e32 v84, v82
	v_mov_b32_e32 v85, v98
	v_cndmask_b32_e32 v100, v175, v100, vcc
	v_pk_add_f32 v[80:81], v[84:85], v[80:81]
	v_mov_b32_e32 v98, v83
	v_lshlrev_b32_e32 v100, 2, v100
	v_pk_add_f32 v[80:81], v[98:99], v[80:81]
	ds_bpermute_b32 v82, v100, v80
	ds_bpermute_b32 v83, v100, v81
	v_xor_b32_e32 v84, 32, v175
	v_cmp_lt_i32_e32 vcc, v84, v101
	s_waitcnt lgkmcnt(0)
	v_pk_add_f32 v[80:81], v[80:81], v[82:83]
	v_cndmask_b32_e32 v84, v175, v84, vcc
	v_lshlrev_b32_e32 v84, 2, v84
	ds_bpermute_b32 v82, v84, v80
	ds_bpermute_b32 v83, v84, v81
	s_and_saveexec_b64 s[10:11], s[2:3]
	s_cbranch_execz .LBB0_778
	s_add_i32 s12, s94, 0xfffffe80
	s_lshr_b32 s48, s12, 5
	v_lshl_add_u64 v[84:85], v[88:89], 0, s[48:49]
	v_lshl_add_u64 v[84:85], v[84:85], 3, s[80:81]
	s_waitcnt lgkmcnt(0)
	v_pk_add_f32 v[80:81], v[80:81], v[82:83]
	global_store_dwordx2 v[84:85], v[80:81], off

; DI unsigned pk2(float lo, float hi) { typedef float v2f __attribute__((ext_vector_type(2))); typedef __bf16 v2b __attribute__((ext_vector_type(2))); v2f v = {lo, hi}; v2b b = __builtin_convertvector(v, v2b); return __builtin_bit_cast(unsigned, b); }
; DI void atomic_addf(float* p, float v) { __builtin_amdgcn_global_atomic_fadd_f32((__attribute__((address_space(1))) float*)p, v); }
; DI float quad_sum(float s) { s += __shfl_xor(s, 16); s += __shfl_xor(s, 32); return s; }
;     DI void operator()(const f32x4 (&acc)[2][2][4][2], const Unit& u, int wr, int wc, int fr, int fq) const {
;     ...
;                         u32x4 w; w.x = pk2(v[0], v[1]); w.y = pk2(v[2], v[3]); w.z = pk2(v[4], v[5]); w.w = pk2(v[6], v[7]);
;                         *(u32x4*)(dst + cw) = w;
;                         float s2 = 0.f;
; #pragma unroll
;                         for (int i = 0; i < 8; ++i) s2 += v[i] * v[i];
;                         s2 = quad_sum(s2);
;                         if (fq == 0) { if (isqm) *pp = s2; else atomic_addf(pp, s2); }
.LBB0_789:
	v_cvt_pk_bf16_f32 v96, v92, v93
	v_cvt_pk_bf16_f32 v97, v78, v79
	v_cvt_pk_bf16_f32 v98, v76, v77
	v_cvt_pk_bf16_f32 v99, v74, v75
	v_lshl_add_u64 v[94:95], v[94:95], 0, v[140:141]
	global_store_dwordx4 v[94:95], v[96:99], off
	v_pk_mul_f32 v[94:95], v[92:93], v[92:93]
	v_pk_mul_f32 v[100:101], v[74:75], v[74:75]
	v_pk_mul_f32 v[96:97], v[78:79], v[78:79]
	v_add_f32_e32 v91, v94, v95
	v_add_f32_e32 v91, v96, v91
	v_pk_mul_f32 v[98:99], v[76:77], v[76:77]
	v_add_f32_e32 v91, v97, v91
	v_and_b32_e32 v95, 64, v175
	v_add_f32_e32 v91, v98, v91
	v_xor_b32_e32 v94, 16, v175
	v_add_u32_e32 v95, 64, v95
	v_add_f32_e32 v91, v99, v91
	v_cmp_lt_i32_e32 vcc, v94, v95
	v_add_f32_e32 v91, v100, v91
	v_add_f32_e32 v91, v101, v91
	v_cndmask_b32_e32 v94, v175, v94, vcc
	v_lshlrev_b32_e32 v94, 2, v94
	ds_bpermute_b32 v94, v94, v91
	s_waitcnt lgkmcnt(0)
	v_add_f32_e32 v91, v91, v94
	v_xor_b32_e32 v94, 32, v175
	v_cmp_lt_i32_e32 vcc, v94, v95
	s_nop 1
	v_cndmask_b32_e32 v94, v175, v94, vcc
	v_lshlrev_b32_e32 v94, 2, v94
	ds_bpermute_b32 v94, v94, v91
	s_and_saveexec_b64 s[10:11], s[2:3]
	s_cbranch_execz .LBB0_794
	s_waitcnt lgkmcnt(0)
	v_add_f32_e32 v91, v91, v94
	s_cmpk_gt_u32 s94, 0x67f
	s_mov_b64 s[12:13], -1
	s_cbranch_scc1 .LBB0_792
	global_atomic_add_f32 v[72:73], v91, off
	s_mov_b64 s[12:13], 0
.LBB0_792:
	s_andn2_b64 vcc, exec, s[12:13]
	s_cbranch_vccnz .LBB0_794
	global_store_dword v[72:73], v91, off

; DI unsigned pk2(float lo, float hi) { typedef float v2f __attribute__((ext_vector_type(2))); typedef __bf16 v2b __attribute__((ext_vector_type(2))); v2f v = {lo, hi}; v2b b = __builtin_convertvector(v, v2b); return __builtin_bit_cast(unsigned, b); }
; DI float quad_sum(float s) { s += __shfl_xor(s, 16); s += __shfl_xor(s, 32); return s; }
; __device__ __forceinline__ f32x2 gelu_pk(f32x2 v) {
;     const f32x2 av = __builtin_elementwise_abs(v), d = av * 0.2316418882f + 1.0f;
;     f32x2 t; t.x = __builtin_amdgcn_rcpf(d.x); t.y = __builtin_amdgcn_rcpf(d.y);
;     f32x2 q = t * 0.5307027145f + (-0.7265760135f); q = q * t + 0.7107068705f; q = q * t + (-0.142248368f); q = q * t + 0.127414796f; q = q * t;
;     const f32x2 s = (v * v) * (-0.72134752044f);
;     f32x2 e; e.x = __builtin_amdgcn_exp2f(s.x); e.y = __builtin_amdgcn_exp2f(s.y);
;     const f32x2 m = v * (q * e), r = v - m;
;     f32x2 o; o.x = v.x < 0.f ? m.x : r.x; o.y = v.y < 0.f ? m.y : r.y; return o;
; }
;     DI void operator()(const f32x4 (&acc)[2][2][4][2], const Unit& u, int wr, int wc, int fr, int fq) const {
;     ...
;                     if (c128 < 1024) {
; #pragma unroll
;                         for (int i = 0; i < 8; i += 2) { const f32x2 g = pg8::gelu_pk((f32x2){v[i], v[i + 1]}); v[i] = g.x; v[i + 1] = g.y; }
;                         const bool isv = c128 >= 512;
;                         u32x4 w; w.x = pk2(v[0], v[1]); w.y = pk2(v[2], v[3]); w.z = pk2(v[4], v[5]); w.w = pk2(v[6], v[7]);
;                         *(u32x4*)((isv ? Vg : U) + (size_t)row * 512 + (c128 & 511) + cw) = w;
;                         if (isv) {
;                             float s1 = 0.f, s2 = 0.f;
; #pragma unroll
;                             for (int i = 0; i < 8; ++i) { s1 += v[i]; s2 += v[i] * v[i]; }
;                             s1 = quad_sum(s1); s2 = quad_sum(s2);
;                             if (fq == 0) { float* d = VST + ((size_t)row * 16 + ((c128 - 512) >> 7) * 4 + wc) * 2; d[0] = s1; d[1] = s2; }
;                         }
.LBB0_796:
	v_lshlrev_b64 v[72:73], 4, v[82:83]
	s_andn2_b64 vcc, exec, s[10:11]
	v_or_b32_e32 v72, s97, v72
	s_cbranch_vccnz .LBB0_801
	v_and_b32_e32 v95, 0x7fffffff, v93
	s_waitcnt lgkmcnt(0)
	v_and_b32_e32 v94, 0x7fffffff, v92
	v_pk_fma_f32 v[94:95], v[94:95], s[14:15], 1.0 op_sel_hi:[1,0,0]
	v_mov_b64_e32 v[96:97], s[96:97]
	v_rcp_f32_e32 v94, v94
	v_rcp_f32_e32 v95, v95
	v_cmp_gt_f32_e32 vcc, 0, v92
	v_cmp_gt_f32_e64 s[10:11], 0, v93
	s_cmp_gt_i32 s60, 1
	v_pk_fma_f32 v[98:99], v[94:95], s[42:43], v[96:97] op_sel_hi:[1,0,0]
	s_nop 0
	v_pk_fma_f32 v[98:99], v[94:95], v[98:99], s[0:1] op_sel_hi:[1,1,0]
	s_nop 0
	v_pk_fma_f32 v[98:99], v[94:95], v[98:99], s[50:51] op_sel_hi:[1,1,0]
	s_nop 0
	v_pk_fma_f32 v[98:99], v[94:95], v[98:99], s[34:35] op_sel_hi:[1,1,0]
	s_nop 0
	v_pk_mul_f32 v[94:95], v[94:95], v[98:99]
	v_pk_mul_f32 v[98:99], v[92:93], v[92:93]
	s_nop 0
	v_pk_mul_f32 v[98:99], v[98:99], s[46:47] op_sel_hi:[1,0]
	s_nop 0
	v_exp_f32_e32 v98, v98
	v_exp_f32_e32 v99, v99
	s_nop 0
	v_pk_mul_f32 v[94:95], v[98:99], v[94:95]
	s_nop 0
	v_pk_mul_f32 v[98:99], v[92:93], v[94:95]
	v_pk_fma_f32 v[94:95], v[92:93], v[94:95], v[92:93] neg_lo:[1,0,0] neg_hi:[1,0,0]
	s_nop 0
	v_cndmask_b32_e64 v93, v95, v99, s[10:11]
	v_cndmask_b32_e32 v92, v94, v98, vcc
	v_and_b32_e32 v95, 0x7fffffff, v79
	v_and_b32_e32 v94, 0x7fffffff, v78
	v_pk_fma_f32 v[94:95], v[94:95], s[14:15], 1.0 op_sel_hi:[1,0,0]
	v_cmp_gt_f32_e32 vcc, 0, v78
	v_rcp_f32_e32 v94, v94
	v_rcp_f32_e32 v95, v95
	v_cmp_gt_f32_e64 s[10:11], 0, v79
	v_pk_fma_f32 v[98:99], v[94:95], s[42:43], v[96:97] op_sel_hi:[1,0,0]
	s_nop 0
	v_pk_fma_f32 v[98:99], v[94:95], v[98:99], s[0:1] op_sel_hi:[1,1,0]
	s_nop 0
	v_pk_fma_f32 v[98:99], v[94:95], v[98:99], s[50:51] op_sel_hi:[1,1,0]
	s_nop 0
	v_pk_fma_f32 v[98:99], v[94:95], v[98:99], s[34:35] op_sel_hi:[1,1,0]
	s_nop 0
	v_pk_mul_f32 v[94:95], v[94:95], v[98:99]
	v_pk_mul_f32 v[98:99], v[78:79], v[78:79]
	s_nop 0
	v_pk_mul_f32 v[98:99], v[98:99], s[46:47] op_sel_hi:[1,0]
	s_nop 0
	v_exp_f32_e32 v98, v98
	v_exp_f32_e32 v99, v99
	s_nop 0
	v_pk_mul_f32 v[94:95], v[98:99], v[94:95]
	s_nop 0
	v_pk_mul_f32 v[98:99], v[78:79], v[94:95]
	v_pk_fma_f32 v[94:95], v[78:79], v[94:95], v[78:79] neg_lo:[1,0,0] neg_hi:[1,0,0]
	s_nop 0
	v_cndmask_b32_e64 v79, v95, v99, s[10:11]
	v_cndmask_b32_e32 v78, v94, v98, vcc
	v_and_b32_e32 v95, 0x7fffffff, v77
	v_and_b32_e32 v94, 0x7fffffff, v76
	v_pk_fma_f32 v[94:95], v[94:95], s[14:15], 1.0 op_sel_hi:[1,0,0]
	v_cmp_gt_f32_e32 vcc, 0, v76
	v_rcp_f32_e32 v94, v94
	v_rcp_f32_e32 v95, v95
	v_cmp_gt_f32_e64 s[10:11], 0, v77
	v_pk_fma_f32 v[98:99], v[94:95], s[42:43], v[96:97] op_sel_hi:[1,0,0]
	s_nop 0
	v_pk_fma_f32 v[98:99], v[94:95], v[98:99], s[0:1] op_sel_hi:[1,1,0]
	s_nop 0
	v_pk_fma_f32 v[98:99], v[94:95], v[98:99], s[50:51] op_sel_hi:[1,1,0]
	s_nop 0
	v_pk_fma_f32 v[98:99], v[94:95], v[98:99], s[34:35] op_sel_hi:[1,1,0]
	s_nop 0
	v_pk_mul_f32 v[94:95], v[94:95], v[98:99]
	v_pk_mul_f32 v[98:99], v[76:77], v[76:77]
	s_nop 0
	v_pk_mul_f32 v[98:99], v[98:99], s[46:47] op_sel_hi:[1,0]
	s_nop 0
	v_exp_f32_e32 v98, v98
	v_exp_f32_e32 v99, v99
	s_nop 0
	v_pk_mul_f32 v[94:95], v[98:99], v[94:95]
	s_nop 0
	v_pk_mul_f32 v[98:99], v[76:77], v[94:95]
	v_pk_fma_f32 v[94:95], v[76:77], v[94:95], v[76:77] neg_lo:[1,0,0] neg_hi:[1,0,0]
	s_nop 0
	v_cndmask_b32_e64 v77, v95, v99, s[10:11]
	v_cndmask_b32_e32 v76, v94, v98, vcc
	v_and_b32_e32 v95, 0x7fffffff, v75
	v_and_b32_e32 v94, 0x7fffffff, v74
	v_pk_fma_f32 v[94:95], v[94:95], s[14:15], 1.0 op_sel_hi:[1,0,0]
	v_cmp_gt_f32_e64 s[10:11], 0, v75
	v_rcp_f32_e32 v94, v94
	v_rcp_f32_e32 v95, v95
	v_cmp_gt_f32_e32 vcc, 0, v74
	v_pk_fma_f32 v[96:97], v[94:95], s[42:43], v[96:97] op_sel_hi:[1,0,0]
	s_nop 0
	v_pk_fma_f32 v[96:97], v[94:95], v[96:97], s[0:1] op_sel_hi:[1,1,0]
	s_nop 0
	v_pk_fma_f32 v[96:97], v[94:95], v[96:97], s[50:51] op_sel_hi:[1,1,0]
	s_nop 0
	v_pk_fma_f32 v[96:97], v[94:95], v[96:97], s[34:35] op_sel_hi:[1,1,0]
	s_nop 0
	v_pk_mul_f32 v[94:95], v[94:95], v[96:97]
	v_pk_mul_f32 v[96:97], v[74:75], v[74:75]
	s_nop 0
	v_pk_mul_f32 v[96:97], v[96:97], s[46:47] op_sel_hi:[1,0]
	s_nop 0
	v_exp_f32_e32 v96, v96
	v_exp_f32_e32 v97, v97
	s_nop 0
	v_pk_mul_f32 v[94:95], v[96:97], v[94:95]
	s_nop 0
	v_pk_mul_f32 v[96:97], v[74:75], v[94:95]
	v_pk_fma_f32 v[94:95], v[74:75], v[94:95], v[74:75] neg_lo:[1,0,0] neg_hi:[1,0,0]
	s_nop 0
	v_cndmask_b32_e64 v75, v95, v97, s[10:11]
	s_cselect_b32 s10, s15, s1
	s_cselect_b32 s11, s35, s43
	s_and_b32 s12, s94, 0x100
	s_lshl_b32 s48, s12, 1
	v_lshl_add_u64 v[98:99], s[10:11], 0, v[80:81]
	v_cndmask_b32_e32 v74, v94, v96, vcc
	v_lshl_add_u64 v[98:99], v[98:99], 0, s[48:49]
	s_cmp_lt_i32 s60, 2
	v_cvt_pk_bf16_f32 v94, v92, v93
	v_cvt_pk_bf16_f32 v95, v78, v79
	v_cvt_pk_bf16_f32 v96, v76, v77
	v_cvt_pk_bf16_f32 v97, v74, v75
	v_lshl_add_u64 v[98:99], v[98:99], 0, v[140:141]
	global_store_dwordx4 v[98:99], v[94:97], off
	s_cbranch_scc1 .LBB0_801
	s_nop 0
	v_mov_b32_e32 v94, v141
	v_mov_b32_e32 v95, v93
	v_pk_add_f32 v[94:95], v[92:93], v[94:95]
	v_pk_mul_f32 v[96:97], v[92:93], v[92:93]
	v_pk_mul_f32 v[98:99], v[78:79], v[78:79]
	v_mov_b32_e32 v95, v97
	v_pk_mov_b32 v[92:93], v[92:93], v[96:97] op_sel:[1,0]
	v_pk_mul_f32 v[100:101], v[76:77], v[76:77]
	v_pk_add_f32 v[92:93], v[92:93], v[94:95]
	v_mov_b32_e32 v94, v78
	v_mov_b32_e32 v95, v98
	v_pk_add_f32 v[92:93], v[94:95], v[92:93]
	v_mov_b32_e32 v98, v79
	v_and_b32_e32 v104, 64, v175
	v_pk_add_f32 v[78:79], v[98:99], v[92:93]
	v_mov_b32_e32 v92, v76
	v_mov_b32_e32 v93, v100
	v_pk_mul_f32 v[102:103], v[74:75], v[74:75]
	v_xor_b32_e32 v91, 16, v175
	v_add_u32_e32 v104, 64, v104
	v_pk_add_f32 v[78:79], v[92:93], v[78:79]
	v_mov_b32_e32 v100, v77
	v_cmp_lt_i32_e32 vcc, v91, v104
	v_pk_add_f32 v[76:77], v[100:101], v[78:79]
	v_mov_b32_e32 v78, v74
	v_mov_b32_e32 v79, v102
	v_cndmask_b32_e32 v91, v175, v91, vcc
	v_pk_add_f32 v[76:77], v[78:79], v[76:77]
	v_mov_b32_e32 v102, v75
	v_lshlrev_b32_e32 v91, 2, v91
	v_pk_add_f32 v[74:75], v[102:103], v[76:77]
	ds_bpermute_b32 v76, v91, v74
	ds_bpermute_b32 v77, v91, v75
	v_xor_b32_e32 v78, 32, v175
	v_cmp_lt_i32_e32 vcc, v78, v104
	s_waitcnt lgkmcnt(0)
	v_pk_add_f32 v[74:75], v[74:75], v[76:77]
	v_cndmask_b32_e32 v78, v175, v78, vcc
	v_lshlrev_b32_e32 v78, 2, v78
	ds_bpermute_b32 v76, v78, v74
	ds_bpermute_b32 v77, v78, v75
	s_and_saveexec_b64 s[10:11], s[2:3]
	s_cbranch_execz .LBB0_800
	s_add_i32 s12, s94, 0xfffffe00
	s_lshr_b32 s48, s12, 5
	v_lshl_add_u64 v[78:79], v[72:73], 0, s[48:49]
	v_lshl_add_u64 v[78:79], v[78:79], 3, s[80:81]
	s_waitcnt lgkmcnt(0)
	v_pk_add_f32 v[74:75], v[74:75], v[76:77]
	global_store_dwordx2 v[78:79], v[74:75], off

; DI float quad_sum(float s) { s += __shfl_xor(s, 16); s += __shfl_xor(s, 32); return s; }
;     DI void operator()(const f32x4 (&acc)[2][2][4][2], const Unit& u, int wr, int wc, int fr, int fq) const {
;     ...
;                         for (int i = 0; i < 4; ++i) v[4 * n + i] = acc[ai][bj][m][n][i] * rs;
;                     if (c128 < 1024) {
; #pragma unroll
;                         for (int i = 0; i < 8; i += 2) { const f32x2 g = pg8::gelu_pk((f32x2){v[i], v[i + 1]}); v[i] = g.x; v[i + 1] = g.y; }
;                         const bool isv = c128 >= 512;
;                         u32x4 w; w.x = pk2(v[0], v[1]); w.y = pk2(v[2], v[3]); w.z = pk2(v[4], v[5]); w.w = pk2(v[6], v[7]);
;                         *(u32x4*)((isv ? Vg : U) + (size_t)row * 512 + (c128 & 511) + cw) = w;
;                         if (isv) {
;                             float s1 = 0.f, s2 = 0.f;
; #pragma unroll
;                             for (int i = 0; i < 8; ++i) { s1 += v[i]; s2 += v[i] * v[i]; }
;                             s1 = quad_sum(s1); s2 = quad_sum(s2);
;                             if (fq == 0) { float* d = VST + ((size_t)row * 16 + ((c128 - 512) >> 7) * 4 + wc) * 2; d[0] = s1; d[1] = s2; }
;                         }
;                     } else if (c128 < 2176) {
;                         bf16_t* dst; float* pp; const bool isqm = c128 >= 1664;
;                         if (c128 < 1408) { dst = CQ + (size_t)row * 384 + (c128 - 1024); pp = CQP + row; }
;                         else if (c128 < 1664) { dst = CKV + (size_t)row * 256 + (c128 - 1408); pp = CKVP + row; }
;                         else { dst = QM + (size_t)row * 512 + (c128 - 1664); pp = QMP + (size_t)row * 16 + ((c128 - 1664) >> 7) * 4 + wc; }
;                         u32x4 w; w.x = pk2(v[0], v[1]); w.y = pk2(v[2], v[3]); w.z = pk2(v[4], v[5]); w.w = pk2(v[6], v[7]);
;                         *(u32x4*)(dst + cw) = w;
;                         float s2 = 0.f;
; #pragma unroll
;                         for (int i = 0; i < 8; ++i) s2 += v[i] * v[i];
;                         s2 = quad_sum(s2);
;                         if (fq == 0) { if (isqm) *pp = s2; else atomic_addf(pp, s2); }
;                     } else if (c128 == 2176) {
;                         if (wc == 0) { float* d = KR + (size_t)row * 32 + 8 * fq; *(f32x4*)d = (f32x4){v[0], v[1], v[2], v[3]}; *(f32x4*)(d + 4) = (f32x4){v[4], v[5], v[6], v[7]}; }
.LBB0_801:
	v_mov_b32_e32 v91, v90
	v_pk_mul_f32 v[68:69], v[68:69], v[90:91]
	v_pk_mul_f32 v[70:71], v[70:71], v[90:91]
	v_pk_mul_f32 v[64:65], v[64:65], v[90:91]
	v_pk_mul_f32 v[66:67], v[66:67], v[90:91]
	s_and_b64 vcc, exec, s[6:7]
	s_mov_b64 s[10:11], -1
	s_cbranch_vccnz .LBB0_822
	s_cmpk_lt_u32 s37, 0x880
	s_cbranch_scc1 .LBB0_806
	s_cmp_lg_u32 s60, 8
	s_cselect_b64 s[10:11], -1, 0
	s_or_b64 s[10:11], s[72:73], s[10:11]
	s_and_b64 vcc, exec, s[10:11]
	s_cbranch_vccnz .LBB0_805
	v_lshlrev_b64 v[74:75], 7, v[82:83]
	v_lshl_add_u64 v[74:75], v[144:145], 0, v[74:75]
	global_store_dwordx4 v[74:75], v[68:71], off
	global_store_dwordx4 v[74:75], v[64:67], off offset:16

; DI unsigned pk2(float lo, float hi) { typedef float v2f __attribute__((ext_vector_type(2))); typedef __bf16 v2b __attribute__((ext_vector_type(2))); v2f v = {lo, hi}; v2b b = __builtin_convertvector(v, v2b); return __builtin_bit_cast(unsigned, b); }
; DI void atomic_addf(float* p, float v) { __builtin_amdgcn_global_atomic_fadd_f32((__attribute__((address_space(1))) float*)p, v); }
; DI float quad_sum(float s) { s += __shfl_xor(s, 16); s += __shfl_xor(s, 32); return s; }
;     DI void operator()(const f32x4 (&acc)[2][2][4][2], const Unit& u, int wr, int wc, int fr, int fq) const {
;     ...
;                         u32x4 w; w.x = pk2(v[0], v[1]); w.y = pk2(v[2], v[3]); w.z = pk2(v[4], v[5]); w.w = pk2(v[6], v[7]);
;                         *(u32x4*)(dst + cw) = w;
;                         float s2 = 0.f;
; #pragma unroll
;                         for (int i = 0; i < 8; ++i) s2 += v[i] * v[i];
;                         s2 = quad_sum(s2);
;                         if (fq == 0) { if (isqm) *pp = s2; else atomic_addf(pp, s2); }
.LBB0_815:
	v_cvt_pk_bf16_f32 v82, v68, v69
	v_cvt_pk_bf16_f32 v83, v70, v71
	v_cvt_pk_bf16_f32 v84, v64, v65
	v_cvt_pk_bf16_f32 v85, v66, v67
	s_waitcnt lgkmcnt(0)
	v_lshl_add_u64 v[76:77], v[76:77], 0, v[140:141]
	global_store_dwordx4 v[76:77], v[82:85], off
	v_pk_mul_f32 v[76:77], v[68:69], v[68:69]
	v_pk_mul_f32 v[78:79], v[70:71], v[70:71]
	v_add_f32_e32 v76, v76, v77
	v_add_f32_e32 v76, v78, v76
	v_pk_mul_f32 v[82:83], v[64:65], v[64:65]
	v_add_f32_e32 v76, v79, v76
	v_and_b32_e32 v78, 64, v175
	v_add_f32_e32 v76, v82, v76
	v_xor_b32_e32 v77, 16, v175
	v_add_u32_e32 v78, 64, v78
	v_pk_mul_f32 v[84:85], v[66:67], v[66:67]
	v_add_f32_e32 v76, v83, v76
	v_cmp_lt_i32_e32 vcc, v77, v78
	v_add_f32_e32 v76, v84, v76
	v_add_f32_e32 v76, v85, v76
	v_cndmask_b32_e32 v77, v175, v77, vcc
	v_lshlrev_b32_e32 v77, 2, v77
	ds_bpermute_b32 v77, v77, v76
	s_waitcnt lgkmcnt(0)
	v_add_f32_e32 v76, v76, v77
	v_xor_b32_e32 v77, 32, v175
	v_cmp_lt_i32_e32 vcc, v77, v78
	s_nop 1
	v_cndmask_b32_e32 v77, v175, v77, vcc
	v_lshlrev_b32_e32 v77, 2, v77
	ds_bpermute_b32 v77, v77, v76
	s_and_saveexec_b64 s[10:11], s[2:3]
	s_cbranch_execz .LBB0_820
	s_waitcnt lgkmcnt(0)
	v_add_f32_e32 v76, v76, v77
	s_cmpk_gt_u32 s37, 0x67f
	s_mov_b64 s[12:13], -1
	s_cbranch_scc1 .LBB0_818
	global_atomic_add_f32 v[74:75], v76, off
	s_mov_b64 s[12:13], 0
.LBB0_818:
	s_andn2_b64 vcc, exec, s[12:13]
	s_cbranch_vccnz .LBB0_820
	global_store_dword v[74:75], v76, off

; DI unsigned pk2(float lo, float hi) { typedef float v2f __attribute__((ext_vector_type(2))); typedef __bf16 v2b __attribute__((ext_vector_type(2))); v2f v = {lo, hi}; v2b b = __builtin_convertvector(v, v2b); return __builtin_bit_cast(unsigned, b); }
; DI float quad_sum(float s) { s += __shfl_xor(s, 16); s += __shfl_xor(s, 32); return s; }
; __device__ __forceinline__ f32x2 gelu_pk(f32x2 v) {
;     const f32x2 av = __builtin_elementwise_abs(v), d = av * 0.2316418882f + 1.0f;
;     f32x2 t; t.x = __builtin_amdgcn_rcpf(d.x); t.y = __builtin_amdgcn_rcpf(d.y);
;     f32x2 q = t * 0.5307027145f + (-0.7265760135f); q = q * t + 0.7107068705f; q = q * t + (-0.142248368f); q = q * t + 0.127414796f; q = q * t;
;     const f32x2 s = (v * v) * (-0.72134752044f);
;     f32x2 e; e.x = __builtin_amdgcn_exp2f(s.x); e.y = __builtin_amdgcn_exp2f(s.y);
;     const f32x2 m = v * (q * e), r = v - m;
;     f32x2 o; o.x = v.x < 0.f ? m.x : r.x; o.y = v.y < 0.f ? m.y : r.y; return o;
; }
;     DI void operator()(const f32x4 (&acc)[2][2][4][2], const Unit& u, int wr, int wc, int fr, int fq) const {
;     ...
;                     if (c128 < 1024) {
; #pragma unroll
;                         for (int i = 0; i < 8; i += 2) { const f32x2 g = pg8::gelu_pk((f32x2){v[i], v[i + 1]}); v[i] = g.x; v[i + 1] = g.y; }
;                         const bool isv = c128 >= 512;
;                         u32x4 w; w.x = pk2(v[0], v[1]); w.y = pk2(v[2], v[3]); w.z = pk2(v[4], v[5]); w.w = pk2(v[6], v[7]);
;                         *(u32x4*)((isv ? Vg : U) + (size_t)row * 512 + (c128 & 511) + cw) = w;
;                         if (isv) {
;                             float s1 = 0.f, s2 = 0.f;
; #pragma unroll
;                             for (int i = 0; i < 8; ++i) { s1 += v[i]; s2 += v[i] * v[i]; }
;                             s1 = quad_sum(s1); s2 = quad_sum(s2);
;                             if (fq == 0) { float* d = VST + ((size_t)row * 16 + ((c128 - 512) >> 7) * 4 + wc) * 2; d[0] = s1; d[1] = s2; }
;                         }
.LBB0_822:
	s_andn2_b64 vcc, exec, s[10:11]
	s_cbranch_vccnz .LBB0_827
	v_and_b32_e32 v75, 0x7fffffff, v69
	v_and_b32_e32 v74, 0x7fffffff, v68
	v_pk_fma_f32 v[74:75], v[74:75], s[14:15], 1.0 op_sel_hi:[1,0,0]
	s_waitcnt lgkmcnt(0)
	v_mov_b64_e32 v[76:77], s[96:97]
	v_rcp_f32_e32 v74, v74
	v_rcp_f32_e32 v75, v75
	v_cmp_gt_f32_e32 vcc, 0, v68
	v_cmp_gt_f32_e64 s[10:11], 0, v69
	s_cmpk_gt_i32 s37, 0x1ff
	v_pk_fma_f32 v[78:79], v[74:75], s[42:43], v[76:77] op_sel_hi:[1,0,0]
	s_nop 0
	v_pk_fma_f32 v[78:79], v[74:75], v[78:79], s[0:1] op_sel_hi:[1,1,0]
	s_nop 0
	v_pk_fma_f32 v[78:79], v[74:75], v[78:79], s[50:51] op_sel_hi:[1,1,0]
	s_nop 0
	v_pk_fma_f32 v[78:79], v[74:75], v[78:79], s[34:35] op_sel_hi:[1,1,0]
	s_nop 0
	v_pk_mul_f32 v[74:75], v[74:75], v[78:79]
	v_pk_mul_f32 v[78:79], v[68:69], v[68:69]
	s_nop 0
	v_pk_mul_f32 v[78:79], v[78:79], s[46:47] op_sel_hi:[1,0]
	s_nop 0
	v_exp_f32_e32 v78, v78
	v_exp_f32_e32 v79, v79
	s_nop 0
	v_pk_mul_f32 v[74:75], v[78:79], v[74:75]
	s_nop 0
	v_pk_mul_f32 v[78:79], v[68:69], v[74:75]
	v_pk_fma_f32 v[74:75], v[68:69], v[74:75], v[68:69] neg_lo:[1,0,0] neg_hi:[1,0,0]
	s_nop 0
	v_cndmask_b32_e64 v69, v75, v79, s[10:11]
	v_cndmask_b32_e32 v68, v74, v78, vcc
	v_and_b32_e32 v75, 0x7fffffff, v71
	v_and_b32_e32 v74, 0x7fffffff, v70
	v_pk_fma_f32 v[74:75], v[74:75], s[14:15], 1.0 op_sel_hi:[1,0,0]
	v_cmp_gt_f32_e32 vcc, 0, v70
	v_rcp_f32_e32 v74, v74
	v_rcp_f32_e32 v75, v75
	v_cmp_gt_f32_e64 s[10:11], 0, v71
	v_pk_fma_f32 v[78:79], v[74:75], s[42:43], v[76:77] op_sel_hi:[1,0,0]
	s_nop 0
	v_pk_fma_f32 v[78:79], v[74:75], v[78:79], s[0:1] op_sel_hi:[1,1,0]
	s_nop 0
	v_pk_fma_f32 v[78:79], v[74:75], v[78:79], s[50:51] op_sel_hi:[1,1,0]
	s_nop 0
	v_pk_fma_f32 v[78:79], v[74:75], v[78:79], s[34:35] op_sel_hi:[1,1,0]
	s_nop 0
	v_pk_mul_f32 v[74:75], v[74:75], v[78:79]
	v_pk_mul_f32 v[78:79], v[70:71], v[70:71]
	s_nop 0
	v_pk_mul_f32 v[78:79], v[78:79], s[46:47] op_sel_hi:[1,0]
	s_nop 0
	v_exp_f32_e32 v78, v78
	v_exp_f32_e32 v79, v79
	s_nop 0
	v_pk_mul_f32 v[74:75], v[78:79], v[74:75]
	s_nop 0
	v_pk_mul_f32 v[78:79], v[70:71], v[74:75]
	v_pk_fma_f32 v[74:75], v[70:71], v[74:75], v[70:71] neg_lo:[1,0,0] neg_hi:[1,0,0]
	s_nop 0
	v_cndmask_b32_e64 v71, v75, v79, s[10:11]
	v_cndmask_b32_e32 v70, v74, v78, vcc
	v_and_b32_e32 v75, 0x7fffffff, v65
	v_and_b32_e32 v74, 0x7fffffff, v64
	v_pk_fma_f32 v[74:75], v[74:75], s[14:15], 1.0 op_sel_hi:[1,0,0]
	v_cmp_gt_f32_e32 vcc, 0, v64
	v_rcp_f32_e32 v74, v74
	v_rcp_f32_e32 v75, v75
	v_cmp_gt_f32_e64 s[10:11], 0, v65
	v_pk_fma_f32 v[78:79], v[74:75], s[42:43], v[76:77] op_sel_hi:[1,0,0]
	s_nop 0
	v_pk_fma_f32 v[78:79], v[74:75], v[78:79], s[0:1] op_sel_hi:[1,1,0]
	s_nop 0
	v_pk_fma_f32 v[78:79], v[74:75], v[78:79], s[50:51] op_sel_hi:[1,1,0]
	s_nop 0
	v_pk_fma_f32 v[78:79], v[74:75], v[78:79], s[34:35] op_sel_hi:[1,1,0]
	s_nop 0
	v_pk_mul_f32 v[74:75], v[74:75], v[78:79]
	v_pk_mul_f32 v[78:79], v[64:65], v[64:65]
	s_nop 0
	v_pk_mul_f32 v[78:79], v[78:79], s[46:47] op_sel_hi:[1,0]
	s_nop 0
	v_exp_f32_e32 v78, v78
	v_exp_f32_e32 v79, v79
	s_nop 0
	v_pk_mul_f32 v[74:75], v[78:79], v[74:75]
	s_nop 0
	v_pk_mul_f32 v[78:79], v[64:65], v[74:75]
	v_pk_fma_f32 v[74:75], v[64:65], v[74:75], v[64:65] neg_lo:[1,0,0] neg_hi:[1,0,0]
	s_nop 0
	v_cndmask_b32_e64 v65, v75, v79, s[10:11]
	v_cndmask_b32_e32 v64, v74, v78, vcc
	v_and_b32_e32 v75, 0x7fffffff, v67
	v_and_b32_e32 v74, 0x7fffffff, v66
	v_pk_fma_f32 v[74:75], v[74:75], s[14:15], 1.0 op_sel_hi:[1,0,0]
	v_cmp_gt_f32_e64 s[10:11], 0, v67
	v_rcp_f32_e32 v74, v74
	v_rcp_f32_e32 v75, v75
	v_cmp_gt_f32_e32 vcc, 0, v66
	v_pk_fma_f32 v[76:77], v[74:75], s[42:43], v[76:77] op_sel_hi:[1,0,0]
	s_nop 0
	v_pk_fma_f32 v[76:77], v[74:75], v[76:77], s[0:1] op_sel_hi:[1,1,0]
	s_nop 0
	v_pk_fma_f32 v[76:77], v[74:75], v[76:77], s[50:51] op_sel_hi:[1,1,0]
	s_nop 0
	v_pk_fma_f32 v[76:77], v[74:75], v[76:77], s[34:35] op_sel_hi:[1,1,0]
	s_nop 0
	v_pk_mul_f32 v[74:75], v[74:75], v[76:77]
	v_pk_mul_f32 v[76:77], v[66:67], v[66:67]
	s_nop 0
	v_pk_mul_f32 v[76:77], v[76:77], s[46:47] op_sel_hi:[1,0]
	s_nop 0
	v_exp_f32_e32 v76, v76
	v_exp_f32_e32 v77, v77
	s_nop 0
	v_pk_mul_f32 v[74:75], v[76:77], v[74:75]
	s_nop 0
	v_pk_mul_f32 v[76:77], v[66:67], v[74:75]
	v_pk_fma_f32 v[74:75], v[66:67], v[74:75], v[66:67] neg_lo:[1,0,0] neg_hi:[1,0,0]
	s_nop 0
	v_cndmask_b32_e64 v67, v75, v77, s[10:11]
	s_cselect_b32 s10, s15, s1
	s_cselect_b32 s11, s35, s43
	s_and_b32 s12, s37, 0x180
	s_lshl_b32 s48, s12, 1
	v_lshl_add_u64 v[78:79], s[10:11], 0, v[80:81]
	v_cndmask_b32_e32 v66, v74, v76, vcc
	v_lshl_add_u64 v[78:79], v[78:79], 0, s[48:49]
	s_cmpk_lt_i32 s37, 0x200
	v_cvt_pk_bf16_f32 v74, v68, v69
	v_cvt_pk_bf16_f32 v75, v70, v71
	v_cvt_pk_bf16_f32 v76, v64, v65
	v_cvt_pk_bf16_f32 v77, v66, v67
	v_lshl_add_u64 v[78:79], v[78:79], 0, v[140:141]
	global_store_dwordx4 v[78:79], v[74:77], off
	s_cbranch_scc1 .LBB0_827
	s_nop 0
	v_mov_b32_e32 v74, v141
	v_mov_b32_e32 v75, v69
	v_pk_add_f32 v[74:75], v[68:69], v[74:75]
	v_pk_mul_f32 v[76:77], v[68:69], v[68:69]
	v_pk_mul_f32 v[78:79], v[70:71], v[70:71]
	v_mov_b32_e32 v75, v77
	v_pk_mov_b32 v[68:69], v[68:69], v[76:77] op_sel:[1,0]
	v_pk_mul_f32 v[80:81], v[64:65], v[64:65]
	v_pk_add_f32 v[68:69], v[68:69], v[74:75]
	v_mov_b32_e32 v74, v70
	v_mov_b32_e32 v75, v78
	v_pk_add_f32 v[68:69], v[74:75], v[68:69]
	v_mov_b32_e32 v78, v71
	v_and_b32_e32 v85, 64, v175
	v_pk_add_f32 v[68:69], v[78:79], v[68:69]
	v_mov_b32_e32 v70, v64
	v_mov_b32_e32 v71, v80
	v_pk_mul_f32 v[82:83], v[66:67], v[66:67]
	v_xor_b32_e32 v84, 16, v175
	v_add_u32_e32 v85, 64, v85
	v_pk_add_f32 v[68:69], v[70:71], v[68:69]
	v_mov_b32_e32 v80, v65
	v_cmp_lt_i32_e32 vcc, v84, v85
	v_pk_add_f32 v[64:65], v[80:81], v[68:69]
	v_mov_b32_e32 v68, v66
	v_mov_b32_e32 v69, v82
	v_cndmask_b32_e32 v84, v175, v84, vcc
	v_pk_add_f32 v[64:65], v[68:69], v[64:65]
	v_mov_b32_e32 v82, v67
	v_lshlrev_b32_e32 v84, 2, v84
	v_pk_add_f32 v[64:65], v[82:83], v[64:65]
	ds_bpermute_b32 v66, v84, v64
	ds_bpermute_b32 v67, v84, v65
	v_xor_b32_e32 v68, 32, v175
	v_cmp_lt_i32_e32 vcc, v68, v85
	s_waitcnt lgkmcnt(0)
	v_pk_add_f32 v[64:65], v[64:65], v[66:67]
	v_cndmask_b32_e32 v68, v175, v68, vcc
	v_lshlrev_b32_e32 v68, 2, v68
	ds_bpermute_b32 v66, v68, v64
	ds_bpermute_b32 v67, v68, v65
	s_and_saveexec_b64 s[10:11], s[2:3]
	s_cbranch_execz .LBB0_826
	s_add_i32 s12, s94, 0xfffffe80
	s_lshr_b32 s48, s12, 5
	v_lshl_add_u64 v[68:69], v[72:73], 0, s[48:49]
	v_lshl_add_u64 v[68:69], v[68:69], 3, s[80:81]
	s_waitcnt lgkmcnt(0)
	v_pk_add_f32 v[64:65], v[64:65], v[66:67]
	global_store_dwordx2 v[68:69], v[64:65], off

; DI unsigned pk2(float lo, float hi) { typedef float v2f __attribute__((ext_vector_type(2))); typedef __bf16 v2b __attribute__((ext_vector_type(2))); v2f v = {lo, hi}; v2b b = __builtin_convertvector(v, v2b); return __builtin_bit_cast(unsigned, b); }
; DI void atomic_addf(float* p, float v) { __builtin_amdgcn_global_atomic_fadd_f32((__attribute__((address_space(1))) float*)p, v); }
; DI float quad_sum(float s) { s += __shfl_xor(s, 16); s += __shfl_xor(s, 32); return s; }
;     DI void operator()(const f32x4 (&acc)[2][2][4][2], const Unit& u, int wr, int wc, int fr, int fq) const {
;     ...
;                         u32x4 w; w.x = pk2(v[0], v[1]); w.y = pk2(v[2], v[3]); w.z = pk2(v[4], v[5]); w.w = pk2(v[6], v[7]);
;                         *(u32x4*)(dst + cw) = w;
;                         float s2 = 0.f;
; #pragma unroll
;                         for (int i = 0; i < 8; ++i) s2 += v[i] * v[i];
;                         s2 = quad_sum(s2);
;                         if (fq == 0) { if (isqm) *pp = s2; else atomic_addf(pp, s2); }
.LBB0_837:
	v_cvt_pk_bf16_f32 v80, v76, v77
	v_cvt_pk_bf16_f32 v81, v62, v63
	v_cvt_pk_bf16_f32 v82, v60, v61
	v_cvt_pk_bf16_f32 v83, v58, v59
	v_lshl_add_u64 v[78:79], v[78:79], 0, v[140:141]
	global_store_dwordx4 v[78:79], v[80:83], off
	v_pk_mul_f32 v[78:79], v[76:77], v[76:77]
	v_pk_mul_f32 v[84:85], v[58:59], v[58:59]
	v_pk_mul_f32 v[80:81], v[62:63], v[62:63]
	v_add_f32_e32 v75, v78, v79
	v_add_f32_e32 v75, v80, v75
	v_pk_mul_f32 v[82:83], v[60:61], v[60:61]
	v_add_f32_e32 v75, v81, v75
	v_and_b32_e32 v79, 64, v175
	v_add_f32_e32 v75, v82, v75
	v_xor_b32_e32 v78, 16, v175
	v_add_u32_e32 v79, 64, v79
	v_add_f32_e32 v75, v83, v75
	v_cmp_lt_i32_e32 vcc, v78, v79
	v_add_f32_e32 v75, v84, v75
	v_add_f32_e32 v75, v85, v75
	v_cndmask_b32_e32 v78, v175, v78, vcc
	v_lshlrev_b32_e32 v78, 2, v78
	ds_bpermute_b32 v78, v78, v75
	s_waitcnt lgkmcnt(0)
	v_add_f32_e32 v75, v75, v78
	v_xor_b32_e32 v78, 32, v175
	v_cmp_lt_i32_e32 vcc, v78, v79
	s_nop 1
	v_cndmask_b32_e32 v78, v175, v78, vcc
	v_lshlrev_b32_e32 v78, 2, v78
	ds_bpermute_b32 v78, v78, v75
	s_and_saveexec_b64 s[10:11], s[2:3]
	s_cbranch_execz .LBB0_842
	s_waitcnt lgkmcnt(0)
	v_add_f32_e32 v75, v75, v78
	s_cmpk_gt_u32 s94, 0x67f
	s_mov_b64 s[12:13], -1
	s_cbranch_scc1 .LBB0_840
	global_atomic_add_f32 v[56:57], v75, off
	s_mov_b64 s[12:13], 0
.LBB0_840:
	s_andn2_b64 vcc, exec, s[12:13]
	s_cbranch_vccnz .LBB0_842
	global_store_dword v[56:57], v75, off

; DI unsigned pk2(float lo, float hi) { typedef float v2f __attribute__((ext_vector_type(2))); typedef __bf16 v2b __attribute__((ext_vector_type(2))); v2f v = {lo, hi}; v2b b = __builtin_convertvector(v, v2b); return __builtin_bit_cast(unsigned, b); }
; DI float quad_sum(float s) { s += __shfl_xor(s, 16); s += __shfl_xor(s, 32); return s; }
; __device__ __forceinline__ f32x2 gelu_pk(f32x2 v) {
;     const f32x2 av = __builtin_elementwise_abs(v), d = av * 0.2316418882f + 1.0f;
;     f32x2 t; t.x = __builtin_amdgcn_rcpf(d.x); t.y = __builtin_amdgcn_rcpf(d.y);
;     f32x2 q = t * 0.5307027145f + (-0.7265760135f); q = q * t + 0.7107068705f; q = q * t + (-0.142248368f); q = q * t + 0.127414796f; q = q * t;
;     const f32x2 s = (v * v) * (-0.72134752044f);
;     f32x2 e; e.x = __builtin_amdgcn_exp2f(s.x); e.y = __builtin_amdgcn_exp2f(s.y);
;     const f32x2 m = v * (q * e), r = v - m;
;     f32x2 o; o.x = v.x < 0.f ? m.x : r.x; o.y = v.y < 0.f ? m.y : r.y; return o;
; }
;     DI void operator()(const f32x4 (&acc)[2][2][4][2], const Unit& u, int wr, int wc, int fr, int fq) const {
;     ...
;                     if (c128 < 1024) {
; #pragma unroll
;                         for (int i = 0; i < 8; i += 2) { const f32x2 g = pg8::gelu_pk((f32x2){v[i], v[i + 1]}); v[i] = g.x; v[i + 1] = g.y; }
;                         const bool isv = c128 >= 512;
;                         u32x4 w; w.x = pk2(v[0], v[1]); w.y = pk2(v[2], v[3]); w.z = pk2(v[4], v[5]); w.w = pk2(v[6], v[7]);
;                         *(u32x4*)((isv ? Vg : U) + (size_t)row * 512 + (c128 & 511) + cw) = w;
;                         if (isv) {
;                             float s1 = 0.f, s2 = 0.f;
; #pragma unroll
;                             for (int i = 0; i < 8; ++i) { s1 += v[i]; s2 += v[i] * v[i]; }
;                             s1 = quad_sum(s1); s2 = quad_sum(s2);
;                             if (fq == 0) { float* d = VST + ((size_t)row * 16 + ((c128 - 512) >> 7) * 4 + wc) * 2; d[0] = s1; d[1] = s2; }
;                         }
.LBB0_844:
	v_lshlrev_b64 v[56:57], 4, v[66:67]
	s_andn2_b64 vcc, exec, s[10:11]
	v_or_b32_e32 v56, s97, v56
	s_cbranch_vccnz .LBB0_849
	v_and_b32_e32 v79, 0x7fffffff, v77
	s_waitcnt lgkmcnt(0)
	v_and_b32_e32 v78, 0x7fffffff, v76
	v_pk_fma_f32 v[78:79], v[78:79], s[14:15], 1.0 op_sel_hi:[1,0,0]
	v_mov_b64_e32 v[80:81], s[96:97]
	v_rcp_f32_e32 v78, v78
	v_rcp_f32_e32 v79, v79
	v_cmp_gt_f32_e32 vcc, 0, v76
	v_cmp_gt_f32_e64 s[10:11], 0, v77
	s_cmp_gt_i32 s60, 1
	v_pk_fma_f32 v[82:83], v[78:79], s[42:43], v[80:81] op_sel_hi:[1,0,0]
	s_nop 0
	v_pk_fma_f32 v[82:83], v[78:79], v[82:83], s[0:1] op_sel_hi:[1,1,0]
	s_nop 0
	v_pk_fma_f32 v[82:83], v[78:79], v[82:83], s[50:51] op_sel_hi:[1,1,0]
	s_nop 0
	v_pk_fma_f32 v[82:83], v[78:79], v[82:83], s[34:35] op_sel_hi:[1,1,0]
	s_nop 0
	v_pk_mul_f32 v[78:79], v[78:79], v[82:83]
	v_pk_mul_f32 v[82:83], v[76:77], v[76:77]
	s_nop 0
	v_pk_mul_f32 v[82:83], v[82:83], s[46:47] op_sel_hi:[1,0]
	s_nop 0
	v_exp_f32_e32 v82, v82
	v_exp_f32_e32 v83, v83
	s_nop 0
	v_pk_mul_f32 v[78:79], v[82:83], v[78:79]
	s_nop 0
	v_pk_mul_f32 v[82:83], v[76:77], v[78:79]
	v_pk_fma_f32 v[78:79], v[76:77], v[78:79], v[76:77] neg_lo:[1,0,0] neg_hi:[1,0,0]
	s_nop 0
	v_cndmask_b32_e64 v77, v79, v83, s[10:11]
	v_cndmask_b32_e32 v76, v78, v82, vcc
	v_and_b32_e32 v79, 0x7fffffff, v63
	v_and_b32_e32 v78, 0x7fffffff, v62
	v_pk_fma_f32 v[78:79], v[78:79], s[14:15], 1.0 op_sel_hi:[1,0,0]
	v_cmp_gt_f32_e32 vcc, 0, v62
	v_rcp_f32_e32 v78, v78
	v_rcp_f32_e32 v79, v79
	v_cmp_gt_f32_e64 s[10:11], 0, v63
	v_pk_fma_f32 v[82:83], v[78:79], s[42:43], v[80:81] op_sel_hi:[1,0,0]
	s_nop 0
	v_pk_fma_f32 v[82:83], v[78:79], v[82:83], s[0:1] op_sel_hi:[1,1,0]
	s_nop 0
	v_pk_fma_f32 v[82:83], v[78:79], v[82:83], s[50:51] op_sel_hi:[1,1,0]
	s_nop 0
	v_pk_fma_f32 v[82:83], v[78:79], v[82:83], s[34:35] op_sel_hi:[1,1,0]
	s_nop 0
	v_pk_mul_f32 v[78:79], v[78:79], v[82:83]
	v_pk_mul_f32 v[82:83], v[62:63], v[62:63]
	s_nop 0
	v_pk_mul_f32 v[82:83], v[82:83], s[46:47] op_sel_hi:[1,0]
	s_nop 0
	v_exp_f32_e32 v82, v82
	v_exp_f32_e32 v83, v83
	s_nop 0
	v_pk_mul_f32 v[78:79], v[82:83], v[78:79]
	s_nop 0
	v_pk_mul_f32 v[82:83], v[62:63], v[78:79]
	v_pk_fma_f32 v[78:79], v[62:63], v[78:79], v[62:63] neg_lo:[1,0,0] neg_hi:[1,0,0]
	s_nop 0
	v_cndmask_b32_e64 v63, v79, v83, s[10:11]
	v_cndmask_b32_e32 v62, v78, v82, vcc
	v_and_b32_e32 v79, 0x7fffffff, v61
	v_and_b32_e32 v78, 0x7fffffff, v60
	v_pk_fma_f32 v[78:79], v[78:79], s[14:15], 1.0 op_sel_hi:[1,0,0]
	v_cmp_gt_f32_e32 vcc, 0, v60
	v_rcp_f32_e32 v78, v78
	v_rcp_f32_e32 v79, v79
	v_cmp_gt_f32_e64 s[10:11], 0, v61
	v_pk_fma_f32 v[82:83], v[78:79], s[42:43], v[80:81] op_sel_hi:[1,0,0]
	s_nop 0
	v_pk_fma_f32 v[82:83], v[78:79], v[82:83], s[0:1] op_sel_hi:[1,1,0]
	s_nop 0
	v_pk_fma_f32 v[82:83], v[78:79], v[82:83], s[50:51] op_sel_hi:[1,1,0]
	s_nop 0
	v_pk_fma_f32 v[82:83], v[78:79], v[82:83], s[34:35] op_sel_hi:[1,1,0]
	s_nop 0
	v_pk_mul_f32 v[78:79], v[78:79], v[82:83]
	v_pk_mul_f32 v[82:83], v[60:61], v[60:61]
	s_nop 0
	v_pk_mul_f32 v[82:83], v[82:83], s[46:47] op_sel_hi:[1,0]
	s_nop 0
	v_exp_f32_e32 v82, v82
	v_exp_f32_e32 v83, v83
	s_nop 0
	v_pk_mul_f32 v[78:79], v[82:83], v[78:79]
	s_nop 0
	v_pk_mul_f32 v[82:83], v[60:61], v[78:79]
	v_pk_fma_f32 v[78:79], v[60:61], v[78:79], v[60:61] neg_lo:[1,0,0] neg_hi:[1,0,0]
	s_nop 0
	v_cndmask_b32_e64 v61, v79, v83, s[10:11]
	v_cndmask_b32_e32 v60, v78, v82, vcc
	v_and_b32_e32 v79, 0x7fffffff, v59
	v_and_b32_e32 v78, 0x7fffffff, v58
	v_pk_fma_f32 v[78:79], v[78:79], s[14:15], 1.0 op_sel_hi:[1,0,0]
	v_cmp_gt_f32_e64 s[10:11], 0, v59
	v_rcp_f32_e32 v78, v78
	v_rcp_f32_e32 v79, v79
	v_cmp_gt_f32_e32 vcc, 0, v58
	v_pk_fma_f32 v[80:81], v[78:79], s[42:43], v[80:81] op_sel_hi:[1,0,0]
	s_nop 0
	v_pk_fma_f32 v[80:81], v[78:79], v[80:81], s[0:1] op_sel_hi:[1,1,0]
	s_nop 0
	v_pk_fma_f32 v[80:81], v[78:79], v[80:81], s[50:51] op_sel_hi:[1,1,0]
	s_nop 0
	v_pk_fma_f32 v[80:81], v[78:79], v[80:81], s[34:35] op_sel_hi:[1,1,0]
	s_nop 0
	v_pk_mul_f32 v[78:79], v[78:79], v[80:81]
	v_pk_mul_f32 v[80:81], v[58:59], v[58:59]
	s_nop 0
	v_pk_mul_f32 v[80:81], v[80:81], s[46:47] op_sel_hi:[1,0]
	s_nop 0
	v_exp_f32_e32 v80, v80
	v_exp_f32_e32 v81, v81
	s_nop 0
	v_pk_mul_f32 v[78:79], v[80:81], v[78:79]
	s_nop 0
	v_pk_mul_f32 v[80:81], v[58:59], v[78:79]
	v_pk_fma_f32 v[78:79], v[58:59], v[78:79], v[58:59] neg_lo:[1,0,0] neg_hi:[1,0,0]
	s_nop 0
	v_cndmask_b32_e64 v59, v79, v81, s[10:11]
	s_cselect_b32 s10, s15, s1
	s_cselect_b32 s11, s35, s43
	s_and_b32 s12, s94, 0x100
	s_lshl_b32 s48, s12, 1
	v_lshl_add_u64 v[82:83], s[10:11], 0, v[64:65]
	v_cndmask_b32_e32 v58, v78, v80, vcc
	v_lshl_add_u64 v[82:83], v[82:83], 0, s[48:49]
	s_cmp_lt_i32 s60, 2
	v_cvt_pk_bf16_f32 v78, v76, v77
	v_cvt_pk_bf16_f32 v79, v62, v63
	v_cvt_pk_bf16_f32 v80, v60, v61
	v_cvt_pk_bf16_f32 v81, v58, v59
	v_lshl_add_u64 v[82:83], v[82:83], 0, v[140:141]
	global_store_dwordx4 v[82:83], v[78:81], off
	s_cbranch_scc1 .LBB0_849
	s_nop 0
	v_mov_b32_e32 v78, v141
	v_mov_b32_e32 v79, v77
	v_pk_add_f32 v[78:79], v[76:77], v[78:79]
	v_pk_mul_f32 v[80:81], v[76:77], v[76:77]
	v_pk_mul_f32 v[82:83], v[62:63], v[62:63]
	v_mov_b32_e32 v79, v81
	v_pk_mov_b32 v[76:77], v[76:77], v[80:81] op_sel:[1,0]
	v_pk_mul_f32 v[84:85], v[60:61], v[60:61]
	v_pk_add_f32 v[76:77], v[76:77], v[78:79]
	v_mov_b32_e32 v78, v62
	v_mov_b32_e32 v79, v82
	v_pk_add_f32 v[76:77], v[78:79], v[76:77]
	v_mov_b32_e32 v82, v63
	v_and_b32_e32 v88, 64, v175
	v_pk_add_f32 v[62:63], v[82:83], v[76:77]
	v_mov_b32_e32 v76, v60
	v_mov_b32_e32 v77, v84
	v_pk_mul_f32 v[86:87], v[58:59], v[58:59]
	v_xor_b32_e32 v75, 16, v175
	v_add_u32_e32 v88, 64, v88
	v_pk_add_f32 v[62:63], v[76:77], v[62:63]
	v_mov_b32_e32 v84, v61
	v_cmp_lt_i32_e32 vcc, v75, v88
	v_pk_add_f32 v[60:61], v[84:85], v[62:63]
	v_mov_b32_e32 v62, v58
	v_mov_b32_e32 v63, v86
	v_cndmask_b32_e32 v75, v175, v75, vcc
	v_pk_add_f32 v[60:61], v[62:63], v[60:61]
	v_mov_b32_e32 v86, v59
	v_lshlrev_b32_e32 v75, 2, v75
	v_pk_add_f32 v[58:59], v[86:87], v[60:61]
	ds_bpermute_b32 v60, v75, v58
	ds_bpermute_b32 v61, v75, v59
	v_xor_b32_e32 v62, 32, v175
	v_cmp_lt_i32_e32 vcc, v62, v88
	s_waitcnt lgkmcnt(0)
	v_pk_add_f32 v[58:59], v[58:59], v[60:61]
	v_cndmask_b32_e32 v62, v175, v62, vcc
	v_lshlrev_b32_e32 v62, 2, v62
	ds_bpermute_b32 v60, v62, v58
	ds_bpermute_b32 v61, v62, v59
	s_and_saveexec_b64 s[10:11], s[2:3]
	s_cbranch_execz .LBB0_848
	s_add_i32 s12, s94, 0xfffffe00
	s_lshr_b32 s48, s12, 5
	v_lshl_add_u64 v[62:63], v[56:57], 0, s[48:49]
	v_lshl_add_u64 v[62:63], v[62:63], 3, s[80:81]
	s_waitcnt lgkmcnt(0)
	v_pk_add_f32 v[58:59], v[58:59], v[60:61]
	global_store_dwordx2 v[62:63], v[58:59], off

; DI float quad_sum(float s) { s += __shfl_xor(s, 16); s += __shfl_xor(s, 32); return s; }
;     DI void operator()(const f32x4 (&acc)[2][2][4][2], const Unit& u, int wr, int wc, int fr, int fq) const {
;     ...
;                         for (int i = 0; i < 4; ++i) v[4 * n + i] = acc[ai][bj][m][n][i] * rs;
;                     if (c128 < 1024) {
; #pragma unroll
;                         for (int i = 0; i < 8; i += 2) { const f32x2 g = pg8::gelu_pk((f32x2){v[i], v[i + 1]}); v[i] = g.x; v[i + 1] = g.y; }
;                         const bool isv = c128 >= 512;
;                         u32x4 w; w.x = pk2(v[0], v[1]); w.y = pk2(v[2], v[3]); w.z = pk2(v[4], v[5]); w.w = pk2(v[6], v[7]);
;                         *(u32x4*)((isv ? Vg : U) + (size_t)row * 512 + (c128 & 511) + cw) = w;
;                         if (isv) {
;                             float s1 = 0.f, s2 = 0.f;
; #pragma unroll
;                             for (int i = 0; i < 8; ++i) { s1 += v[i]; s2 += v[i] * v[i]; }
;                             s1 = quad_sum(s1); s2 = quad_sum(s2);
;                             if (fq == 0) { float* d = VST + ((size_t)row * 16 + ((c128 - 512) >> 7) * 4 + wc) * 2; d[0] = s1; d[1] = s2; }
;                         }
;                     } else if (c128 < 2176) {
;                         bf16_t* dst; float* pp; const bool isqm = c128 >= 1664;
;                         if (c128 < 1408) { dst = CQ + (size_t)row * 384 + (c128 - 1024); pp = CQP + row; }
;                         else if (c128 < 1664) { dst = CKV + (size_t)row * 256 + (c128 - 1408); pp = CKVP + row; }
;                         else { dst = QM + (size_t)row * 512 + (c128 - 1664); pp = QMP + (size_t)row * 16 + ((c128 - 1664) >> 7) * 4 + wc; }
;                         u32x4 w; w.x = pk2(v[0], v[1]); w.y = pk2(v[2], v[3]); w.z = pk2(v[4], v[5]); w.w = pk2(v[6], v[7]);
;                         *(u32x4*)(dst + cw) = w;
;                         float s2 = 0.f;
; #pragma unroll
;                         for (int i = 0; i < 8; ++i) s2 += v[i] * v[i];
;                         s2 = quad_sum(s2);
;                         if (fq == 0) { if (isqm) *pp = s2; else atomic_addf(pp, s2); }
;                     } else if (c128 == 2176) {
;                         if (wc == 0) { float* d = KR + (size_t)row * 32 + 8 * fq; *(f32x4*)d = (f32x4){v[0], v[1], v[2], v[3]}; *(f32x4*)(d + 4) = (f32x4){v[4], v[5], v[6], v[7]}; }
.LBB0_849:
	v_mov_b32_e32 v75, v74
	v_pk_mul_f32 v[52:53], v[52:53], v[74:75]
	v_pk_mul_f32 v[54:55], v[54:55], v[74:75]
	v_pk_mul_f32 v[48:49], v[48:49], v[74:75]
	v_pk_mul_f32 v[50:51], v[50:51], v[74:75]
	s_and_b64 vcc, exec, s[6:7]
	s_mov_b64 s[10:11], -1
	s_cbranch_vccnz .LBB0_870
	s_cmpk_lt_u32 s37, 0x880
	s_cbranch_scc1 .LBB0_854
	s_cmp_lg_u32 s60, 8
	s_cselect_b64 s[10:11], -1, 0
	s_or_b64 s[10:11], s[72:73], s[10:11]
	s_and_b64 vcc, exec, s[10:11]
	s_cbranch_vccnz .LBB0_853
	v_lshlrev_b64 v[58:59], 7, v[66:67]
	v_lshl_add_u64 v[58:59], v[144:145], 0, v[58:59]
	global_store_dwordx4 v[58:59], v[52:55], off
	global_store_dwordx4 v[58:59], v[48:51], off offset:16

; DI unsigned pk2(float lo, float hi) { typedef float v2f __attribute__((ext_vector_type(2))); typedef __bf16 v2b __attribute__((ext_vector_type(2))); v2f v = {lo, hi}; v2b b = __builtin_convertvector(v, v2b); return __builtin_bit_cast(unsigned, b); }
; DI void atomic_addf(float* p, float v) { __builtin_amdgcn_global_atomic_fadd_f32((__attribute__((address_space(1))) float*)p, v); }
; DI float quad_sum(float s) { s += __shfl_xor(s, 16); s += __shfl_xor(s, 32); return s; }
;     DI void operator()(const f32x4 (&acc)[2][2][4][2], const Unit& u, int wr, int wc, int fr, int fq) const {
;     ...
;                         u32x4 w; w.x = pk2(v[0], v[1]); w.y = pk2(v[2], v[3]); w.z = pk2(v[4], v[5]); w.w = pk2(v[6], v[7]);
;                         *(u32x4*)(dst + cw) = w;
;                         float s2 = 0.f;
; #pragma unroll
;                         for (int i = 0; i < 8; ++i) s2 += v[i] * v[i];
;                         s2 = quad_sum(s2);
;                         if (fq == 0) { if (isqm) *pp = s2; else atomic_addf(pp, s2); }
.LBB0_863:
	v_cvt_pk_bf16_f32 v66, v52, v53
	v_cvt_pk_bf16_f32 v67, v54, v55
	v_cvt_pk_bf16_f32 v68, v48, v49
	v_cvt_pk_bf16_f32 v69, v50, v51
	s_waitcnt lgkmcnt(0)
	v_lshl_add_u64 v[60:61], v[60:61], 0, v[140:141]
	global_store_dwordx4 v[60:61], v[66:69], off
	v_pk_mul_f32 v[60:61], v[52:53], v[52:53]
	v_pk_mul_f32 v[62:63], v[54:55], v[54:55]
	v_add_f32_e32 v60, v60, v61
	v_add_f32_e32 v60, v62, v60
	v_pk_mul_f32 v[66:67], v[48:49], v[48:49]
	v_add_f32_e32 v60, v63, v60
	v_and_b32_e32 v62, 64, v175
	v_add_f32_e32 v60, v66, v60
	v_xor_b32_e32 v61, 16, v175
	v_add_u32_e32 v62, 64, v62
	v_pk_mul_f32 v[68:69], v[50:51], v[50:51]
	v_add_f32_e32 v60, v67, v60
	v_cmp_lt_i32_e32 vcc, v61, v62
	v_add_f32_e32 v60, v68, v60
	v_add_f32_e32 v60, v69, v60
	v_cndmask_b32_e32 v61, v175, v61, vcc
	v_lshlrev_b32_e32 v61, 2, v61
	ds_bpermute_b32 v61, v61, v60
	s_waitcnt lgkmcnt(0)
	v_add_f32_e32 v60, v60, v61
	v_xor_b32_e32 v61, 32, v175
	v_cmp_lt_i32_e32 vcc, v61, v62
	s_nop 1
	v_cndmask_b32_e32 v61, v175, v61, vcc
	v_lshlrev_b32_e32 v61, 2, v61
	ds_bpermute_b32 v61, v61, v60
	s_and_saveexec_b64 s[10:11], s[2:3]
	s_cbranch_execz .LBB0_868
	s_waitcnt lgkmcnt(0)
	v_add_f32_e32 v60, v60, v61
	s_cmpk_gt_u32 s37, 0x67f
	s_mov_b64 s[12:13], -1
	s_cbranch_scc1 .LBB0_866
	global_atomic_add_f32 v[58:59], v60, off
	s_mov_b64 s[12:13], 0
.LBB0_866:
	s_andn2_b64 vcc, exec, s[12:13]
	s_cbranch_vccnz .LBB0_868
	global_store_dword v[58:59], v60, off

; DI unsigned pk2(float lo, float hi) { typedef float v2f __attribute__((ext_vector_type(2))); typedef __bf16 v2b __attribute__((ext_vector_type(2))); v2f v = {lo, hi}; v2b b = __builtin_convertvector(v, v2b); return __builtin_bit_cast(unsigned, b); }
; DI float quad_sum(float s) { s += __shfl_xor(s, 16); s += __shfl_xor(s, 32); return s; }
; __device__ __forceinline__ f32x2 gelu_pk(f32x2 v) {
;     const f32x2 av = __builtin_elementwise_abs(v), d = av * 0.2316418882f + 1.0f;
;     f32x2 t; t.x = __builtin_amdgcn_rcpf(d.x); t.y = __builtin_amdgcn_rcpf(d.y);
;     f32x2 q = t * 0.5307027145f + (-0.7265760135f); q = q * t + 0.7107068705f; q = q * t + (-0.142248368f); q = q * t + 0.127414796f; q = q * t;
;     const f32x2 s = (v * v) * (-0.72134752044f);
;     f32x2 e; e.x = __builtin_amdgcn_exp2f(s.x); e.y = __builtin_amdgcn_exp2f(s.y);
;     const f32x2 m = v * (q * e), r = v - m;
;     f32x2 o; o.x = v.x < 0.f ? m.x : r.x; o.y = v.y < 0.f ? m.y : r.y; return o;
; }
;     DI void operator()(const f32x4 (&acc)[2][2][4][2], const Unit& u, int wr, int wc, int fr, int fq) const {
;     ...
;                     if (c128 < 1024) {
; #pragma unroll
;                         for (int i = 0; i < 8; i += 2) { const f32x2 g = pg8::gelu_pk((f32x2){v[i], v[i + 1]}); v[i] = g.x; v[i + 1] = g.y; }
;                         const bool isv = c128 >= 512;
;                         u32x4 w; w.x = pk2(v[0], v[1]); w.y = pk2(v[2], v[3]); w.z = pk2(v[4], v[5]); w.w = pk2(v[6], v[7]);
;                         *(u32x4*)((isv ? Vg : U) + (size_t)row * 512 + (c128 & 511) + cw) = w;
;                         if (isv) {
;                             float s1 = 0.f, s2 = 0.f;
; #pragma unroll
;                             for (int i = 0; i < 8; ++i) { s1 += v[i]; s2 += v[i] * v[i]; }
;                             s1 = quad_sum(s1); s2 = quad_sum(s2);
;                             if (fq == 0) { float* d = VST + ((size_t)row * 16 + ((c128 - 512) >> 7) * 4 + wc) * 2; d[0] = s1; d[1] = s2; }
;                         }
.LBB0_870:
	s_andn2_b64 vcc, exec, s[10:11]
	s_cbranch_vccnz .LBB0_875
	v_and_b32_e32 v59, 0x7fffffff, v53
	v_and_b32_e32 v58, 0x7fffffff, v52
	v_pk_fma_f32 v[58:59], v[58:59], s[14:15], 1.0 op_sel_hi:[1,0,0]
	s_waitcnt lgkmcnt(0)
	v_mov_b64_e32 v[60:61], s[96:97]
	v_rcp_f32_e32 v58, v58
	v_rcp_f32_e32 v59, v59
	v_cmp_gt_f32_e32 vcc, 0, v52
	v_cmp_gt_f32_e64 s[10:11], 0, v53
	s_cmpk_gt_i32 s37, 0x1ff
	v_pk_fma_f32 v[62:63], v[58:59], s[42:43], v[60:61] op_sel_hi:[1,0,0]
	s_nop 0
	v_pk_fma_f32 v[62:63], v[58:59], v[62:63], s[0:1] op_sel_hi:[1,1,0]
	s_nop 0
	v_pk_fma_f32 v[62:63], v[58:59], v[62:63], s[50:51] op_sel_hi:[1,1,0]
	s_nop 0
	v_pk_fma_f32 v[62:63], v[58:59], v[62:63], s[34:35] op_sel_hi:[1,1,0]
	s_nop 0
	v_pk_mul_f32 v[58:59], v[58:59], v[62:63]
	v_pk_mul_f32 v[62:63], v[52:53], v[52:53]
	s_nop 0
	v_pk_mul_f32 v[62:63], v[62:63], s[46:47] op_sel_hi:[1,0]
	s_nop 0
	v_exp_f32_e32 v62, v62
	v_exp_f32_e32 v63, v63
	s_nop 0
	v_pk_mul_f32 v[58:59], v[62:63], v[58:59]
	s_nop 0
	v_pk_mul_f32 v[62:63], v[52:53], v[58:59]
	v_pk_fma_f32 v[58:59], v[52:53], v[58:59], v[52:53] neg_lo:[1,0,0] neg_hi:[1,0,0]
	s_nop 0
	v_cndmask_b32_e64 v53, v59, v63, s[10:11]
	v_cndmask_b32_e32 v52, v58, v62, vcc
	v_and_b32_e32 v59, 0x7fffffff, v55
	v_and_b32_e32 v58, 0x7fffffff, v54
	v_pk_fma_f32 v[58:59], v[58:59], s[14:15], 1.0 op_sel_hi:[1,0,0]
	v_cmp_gt_f32_e32 vcc, 0, v54
	v_rcp_f32_e32 v58, v58
	v_rcp_f32_e32 v59, v59
	v_cmp_gt_f32_e64 s[10:11], 0, v55
	v_pk_fma_f32 v[62:63], v[58:59], s[42:43], v[60:61] op_sel_hi:[1,0,0]
	s_nop 0
	v_pk_fma_f32 v[62:63], v[58:59], v[62:63], s[0:1] op_sel_hi:[1,1,0]
	s_nop 0
	v_pk_fma_f32 v[62:63], v[58:59], v[62:63], s[50:51] op_sel_hi:[1,1,0]
	s_nop 0
	v_pk_fma_f32 v[62:63], v[58:59], v[62:63], s[34:35] op_sel_hi:[1,1,0]
	s_nop 0
	v_pk_mul_f32 v[58:59], v[58:59], v[62:63]
	v_pk_mul_f32 v[62:63], v[54:55], v[54:55]
	s_nop 0
	v_pk_mul_f32 v[62:63], v[62:63], s[46:47] op_sel_hi:[1,0]
	s_nop 0
	v_exp_f32_e32 v62, v62
	v_exp_f32_e32 v63, v63
	s_nop 0
	v_pk_mul_f32 v[58:59], v[62:63], v[58:59]
	s_nop 0
	v_pk_mul_f32 v[62:63], v[54:55], v[58:59]
	v_pk_fma_f32 v[58:59], v[54:55], v[58:59], v[54:55] neg_lo:[1,0,0] neg_hi:[1,0,0]
	s_nop 0
	v_cndmask_b32_e64 v55, v59, v63, s[10:11]
	v_cndmask_b32_e32 v54, v58, v62, vcc
	v_and_b32_e32 v59, 0x7fffffff, v49
	v_and_b32_e32 v58, 0x7fffffff, v48
	v_pk_fma_f32 v[58:59], v[58:59], s[14:15], 1.0 op_sel_hi:[1,0,0]
	v_cmp_gt_f32_e32 vcc, 0, v48
	v_rcp_f32_e32 v58, v58
	v_rcp_f32_e32 v59, v59
	v_cmp_gt_f32_e64 s[10:11], 0, v49
	v_pk_fma_f32 v[62:63], v[58:59], s[42:43], v[60:61] op_sel_hi:[1,0,0]
	s_nop 0
	v_pk_fma_f32 v[62:63], v[58:59], v[62:63], s[0:1] op_sel_hi:[1,1,0]
	s_nop 0
	v_pk_fma_f32 v[62:63], v[58:59], v[62:63], s[50:51] op_sel_hi:[1,1,0]
	s_nop 0
	v_pk_fma_f32 v[62:63], v[58:59], v[62:63], s[34:35] op_sel_hi:[1,1,0]
	s_nop 0
	v_pk_mul_f32 v[58:59], v[58:59], v[62:63]
	v_pk_mul_f32 v[62:63], v[48:49], v[48:49]
	s_nop 0
	v_pk_mul_f32 v[62:63], v[62:63], s[46:47] op_sel_hi:[1,0]
	s_nop 0
	v_exp_f32_e32 v62, v62
	v_exp_f32_e32 v63, v63
	s_nop 0
	v_pk_mul_f32 v[58:59], v[62:63], v[58:59]
	s_nop 0
	v_pk_mul_f32 v[62:63], v[48:49], v[58:59]
	v_pk_fma_f32 v[58:59], v[48:49], v[58:59], v[48:49] neg_lo:[1,0,0] neg_hi:[1,0,0]
	s_nop 0
	v_cndmask_b32_e64 v49, v59, v63, s[10:11]
	v_cndmask_b32_e32 v48, v58, v62, vcc
	v_and_b32_e32 v59, 0x7fffffff, v51
	v_and_b32_e32 v58, 0x7fffffff, v50
	v_pk_fma_f32 v[58:59], v[58:59], s[14:15], 1.0 op_sel_hi:[1,0,0]
	v_cmp_gt_f32_e64 s[10:11], 0, v51
	v_rcp_f32_e32 v58, v58
	v_rcp_f32_e32 v59, v59
	v_cmp_gt_f32_e32 vcc, 0, v50
	v_pk_fma_f32 v[60:61], v[58:59], s[42:43], v[60:61] op_sel_hi:[1,0,0]
	s_nop 0
	v_pk_fma_f32 v[60:61], v[58:59], v[60:61], s[0:1] op_sel_hi:[1,1,0]
	s_nop 0
	v_pk_fma_f32 v[60:61], v[58:59], v[60:61], s[50:51] op_sel_hi:[1,1,0]
	s_nop 0
	v_pk_fma_f32 v[60:61], v[58:59], v[60:61], s[34:35] op_sel_hi:[1,1,0]
	s_nop 0
	v_pk_mul_f32 v[58:59], v[58:59], v[60:61]
	v_pk_mul_f32 v[60:61], v[50:51], v[50:51]
	s_nop 0
	v_pk_mul_f32 v[60:61], v[60:61], s[46:47] op_sel_hi:[1,0]
	s_nop 0
	v_exp_f32_e32 v60, v60
	v_exp_f32_e32 v61, v61
	s_nop 0
	v_pk_mul_f32 v[58:59], v[60:61], v[58:59]
	s_nop 0
	v_pk_mul_f32 v[60:61], v[50:51], v[58:59]
	v_pk_fma_f32 v[58:59], v[50:51], v[58:59], v[50:51] neg_lo:[1,0,0] neg_hi:[1,0,0]
	s_nop 0
	v_cndmask_b32_e64 v51, v59, v61, s[10:11]
	s_cselect_b32 s10, s15, s1
	s_cselect_b32 s11, s35, s43
	s_and_b32 s12, s37, 0x180
	s_lshl_b32 s48, s12, 1
	v_lshl_add_u64 v[62:63], s[10:11], 0, v[64:65]
	v_cndmask_b32_e32 v50, v58, v60, vcc
	v_lshl_add_u64 v[62:63], v[62:63], 0, s[48:49]
	s_cmpk_lt_i32 s37, 0x200
	v_cvt_pk_bf16_f32 v58, v52, v53
	v_cvt_pk_bf16_f32 v59, v54, v55
	v_cvt_pk_bf16_f32 v60, v48, v49
	v_cvt_pk_bf16_f32 v61, v50, v51
	v_lshl_add_u64 v[62:63], v[62:63], 0, v[140:141]
	global_store_dwordx4 v[62:63], v[58:61], off
	s_cbranch_scc1 .LBB0_875
	s_nop 0
	v_mov_b32_e32 v58, v141
	v_mov_b32_e32 v59, v53
	v_pk_add_f32 v[58:59], v[52:53], v[58:59]
	v_pk_mul_f32 v[60:61], v[52:53], v[52:53]
	v_pk_mul_f32 v[62:63], v[54:55], v[54:55]
	v_mov_b32_e32 v59, v61
	v_pk_mov_b32 v[52:53], v[52:53], v[60:61] op_sel:[1,0]
	v_pk_mul_f32 v[64:65], v[48:49], v[48:49]
	v_pk_add_f32 v[52:53], v[52:53], v[58:59]
	v_mov_b32_e32 v58, v54
	v_mov_b32_e32 v59, v62
	v_pk_add_f32 v[52:53], v[58:59], v[52:53]
	v_mov_b32_e32 v62, v55
	v_and_b32_e32 v69, 64, v175
	v_pk_add_f32 v[52:53], v[62:63], v[52:53]
	v_mov_b32_e32 v54, v48
	v_mov_b32_e32 v55, v64
	v_pk_mul_f32 v[66:67], v[50:51], v[50:51]
	v_xor_b32_e32 v68, 16, v175
	v_add_u32_e32 v69, 64, v69
	v_pk_add_f32 v[52:53], v[54:55], v[52:53]
	v_mov_b32_e32 v64, v49
	v_cmp_lt_i32_e32 vcc, v68, v69
	v_pk_add_f32 v[48:49], v[64:65], v[52:53]
	v_mov_b32_e32 v52, v50
	v_mov_b32_e32 v53, v66
	v_cndmask_b32_e32 v68, v175, v68, vcc
	v_pk_add_f32 v[48:49], v[52:53], v[48:49]
	v_mov_b32_e32 v66, v51
	v_lshlrev_b32_e32 v68, 2, v68
	v_pk_add_f32 v[48:49], v[66:67], v[48:49]
	ds_bpermute_b32 v50, v68, v48
	ds_bpermute_b32 v51, v68, v49
	v_xor_b32_e32 v52, 32, v175
	v_cmp_lt_i32_e32 vcc, v52, v69
	s_waitcnt lgkmcnt(0)
	v_pk_add_f32 v[48:49], v[48:49], v[50:51]
	v_cndmask_b32_e32 v52, v175, v52, vcc
	v_lshlrev_b32_e32 v52, 2, v52
	ds_bpermute_b32 v50, v52, v48
	ds_bpermute_b32 v51, v52, v49
	s_and_saveexec_b64 s[10:11], s[2:3]
	s_cbranch_execz .LBB0_874
	s_add_i32 s12, s94, 0xfffffe80
	s_lshr_b32 s48, s12, 5
	v_lshl_add_u64 v[52:53], v[56:57], 0, s[48:49]
	v_lshl_add_u64 v[52:53], v[52:53], 3, s[80:81]
	s_waitcnt lgkmcnt(0)
	v_pk_add_f32 v[48:49], v[48:49], v[50:51]
	global_store_dwordx2 v[52:53], v[48:49], off

; DI unsigned pk2(float lo, float hi) { typedef float v2f __attribute__((ext_vector_type(2))); typedef __bf16 v2b __attribute__((ext_vector_type(2))); v2f v = {lo, hi}; v2b b = __builtin_convertvector(v, v2b); return __builtin_bit_cast(unsigned, b); }
; DI void atomic_addf(float* p, float v) { __builtin_amdgcn_global_atomic_fadd_f32((__attribute__((address_space(1))) float*)p, v); }
; DI float quad_sum(float s) { s += __shfl_xor(s, 16); s += __shfl_xor(s, 32); return s; }
;     DI void operator()(const f32x4 (&acc)[2][2][4][2], const Unit& u, int wr, int wc, int fr, int fq) const {
;     ...
;                         u32x4 w; w.x = pk2(v[0], v[1]); w.y = pk2(v[2], v[3]); w.z = pk2(v[4], v[5]); w.w = pk2(v[6], v[7]);
;                         *(u32x4*)(dst + cw) = w;
;                         float s2 = 0.f;
; #pragma unroll
;                         for (int i = 0; i < 8; ++i) s2 += v[i] * v[i];
;                         s2 = quad_sum(s2);
;                         if (fq == 0) { if (isqm) *pp = s2; else atomic_addf(pp, s2); }
.LBB0_885:
	v_cvt_pk_bf16_f32 v64, v60, v61
	v_cvt_pk_bf16_f32 v65, v46, v47
	v_cvt_pk_bf16_f32 v66, v44, v45
	v_cvt_pk_bf16_f32 v67, v42, v43
	v_lshl_add_u64 v[62:63], v[62:63], 0, v[140:141]
	global_store_dwordx4 v[62:63], v[64:67], off
	v_pk_mul_f32 v[62:63], v[60:61], v[60:61]
	v_pk_mul_f32 v[68:69], v[42:43], v[42:43]
	v_pk_mul_f32 v[64:65], v[46:47], v[46:47]
	v_add_f32_e32 v59, v62, v63
	v_add_f32_e32 v59, v64, v59
	v_pk_mul_f32 v[66:67], v[44:45], v[44:45]
	v_add_f32_e32 v59, v65, v59
	v_and_b32_e32 v63, 64, v175
	v_add_f32_e32 v59, v66, v59
	v_xor_b32_e32 v62, 16, v175
	v_add_u32_e32 v63, 64, v63
	v_add_f32_e32 v59, v67, v59
	v_cmp_lt_i32_e32 vcc, v62, v63
	v_add_f32_e32 v59, v68, v59
	v_add_f32_e32 v59, v69, v59
	v_cndmask_b32_e32 v62, v175, v62, vcc
	v_lshlrev_b32_e32 v62, 2, v62
	ds_bpermute_b32 v62, v62, v59
	s_waitcnt lgkmcnt(0)
	v_add_f32_e32 v59, v59, v62
	v_xor_b32_e32 v62, 32, v175
	v_cmp_lt_i32_e32 vcc, v62, v63
	s_nop 1
	v_cndmask_b32_e32 v62, v175, v62, vcc
	v_lshlrev_b32_e32 v62, 2, v62
	ds_bpermute_b32 v62, v62, v59
	s_and_saveexec_b64 s[10:11], s[2:3]
	s_cbranch_execz .LBB0_890
	s_waitcnt lgkmcnt(0)
	v_add_f32_e32 v59, v59, v62
	s_cmpk_gt_u32 s94, 0x67f
	s_mov_b64 s[12:13], -1
	s_cbranch_scc1 .LBB0_888
	global_atomic_add_f32 v[40:41], v59, off
	s_mov_b64 s[12:13], 0
.LBB0_888:
	s_andn2_b64 vcc, exec, s[12:13]
	s_cbranch_vccnz .LBB0_890
	global_store_dword v[40:41], v59, off

; DI unsigned pk2(float lo, float hi) { typedef float v2f __attribute__((ext_vector_type(2))); typedef __bf16 v2b __attribute__((ext_vector_type(2))); v2f v = {lo, hi}; v2b b = __builtin_convertvector(v, v2b); return __builtin_bit_cast(unsigned, b); }
; DI float quad_sum(float s) { s += __shfl_xor(s, 16); s += __shfl_xor(s, 32); return s; }
; __device__ __forceinline__ f32x2 gelu_pk(f32x2 v) {
;     const f32x2 av = __builtin_elementwise_abs(v), d = av * 0.2316418882f + 1.0f;
;     f32x2 t; t.x = __builtin_amdgcn_rcpf(d.x); t.y = __builtin_amdgcn_rcpf(d.y);
;     f32x2 q = t * 0.5307027145f + (-0.7265760135f); q = q * t + 0.7107068705f; q = q * t + (-0.142248368f); q = q * t + 0.127414796f; q = q * t;
;     const f32x2 s = (v * v) * (-0.72134752044f);
;     f32x2 e; e.x = __builtin_amdgcn_exp2f(s.x); e.y = __builtin_amdgcn_exp2f(s.y);
;     const f32x2 m = v * (q * e), r = v - m;
;     f32x2 o; o.x = v.x < 0.f ? m.x : r.x; o.y = v.y < 0.f ? m.y : r.y; return o;
; }
;     DI void operator()(const f32x4 (&acc)[2][2][4][2], const Unit& u, int wr, int wc, int fr, int fq) const {
;     ...
;                     if (c128 < 1024) {
; #pragma unroll
;                         for (int i = 0; i < 8; i += 2) { const f32x2 g = pg8::gelu_pk((f32x2){v[i], v[i + 1]}); v[i] = g.x; v[i + 1] = g.y; }
;                         const bool isv = c128 >= 512;
;                         u32x4 w; w.x = pk2(v[0], v[1]); w.y = pk2(v[2], v[3]); w.z = pk2(v[4], v[5]); w.w = pk2(v[6], v[7]);
;                         *(u32x4*)((isv ? Vg : U) + (size_t)row * 512 + (c128 & 511) + cw) = w;
;                         if (isv) {
;                             float s1 = 0.f, s2 = 0.f;
; #pragma unroll
;                             for (int i = 0; i < 8; ++i) { s1 += v[i]; s2 += v[i] * v[i]; }
;                             s1 = quad_sum(s1); s2 = quad_sum(s2);
;                             if (fq == 0) { float* d = VST + ((size_t)row * 16 + ((c128 - 512) >> 7) * 4 + wc) * 2; d[0] = s1; d[1] = s2; }
;                         }
.LBB0_892:
	v_lshlrev_b64 v[40:41], 4, v[50:51]
	s_andn2_b64 vcc, exec, s[10:11]
	v_or_b32_e32 v40, s97, v40
	s_cbranch_vccnz .LBB0_897
	v_and_b32_e32 v63, 0x7fffffff, v61
	s_waitcnt lgkmcnt(0)
	v_and_b32_e32 v62, 0x7fffffff, v60
	v_pk_fma_f32 v[62:63], v[62:63], s[14:15], 1.0 op_sel_hi:[1,0,0]
	v_mov_b64_e32 v[64:65], s[96:97]
	v_rcp_f32_e32 v62, v62
	v_rcp_f32_e32 v63, v63
	v_cmp_gt_f32_e32 vcc, 0, v60
	v_cmp_gt_f32_e64 s[10:11], 0, v61
	s_cmp_gt_i32 s60, 1
	v_pk_fma_f32 v[66:67], v[62:63], s[42:43], v[64:65] op_sel_hi:[1,0,0]
	s_nop 0
	v_pk_fma_f32 v[66:67], v[62:63], v[66:67], s[0:1] op_sel_hi:[1,1,0]
	s_nop 0
	v_pk_fma_f32 v[66:67], v[62:63], v[66:67], s[50:51] op_sel_hi:[1,1,0]
	s_nop 0
	v_pk_fma_f32 v[66:67], v[62:63], v[66:67], s[34:35] op_sel_hi:[1,1,0]
	s_nop 0
	v_pk_mul_f32 v[62:63], v[62:63], v[66:67]
	v_pk_mul_f32 v[66:67], v[60:61], v[60:61]
	s_nop 0
	v_pk_mul_f32 v[66:67], v[66:67], s[46:47] op_sel_hi:[1,0]
	s_nop 0
	v_exp_f32_e32 v66, v66
	v_exp_f32_e32 v67, v67
	s_nop 0
	v_pk_mul_f32 v[62:63], v[66:67], v[62:63]
	s_nop 0
	v_pk_mul_f32 v[66:67], v[60:61], v[62:63]
	v_pk_fma_f32 v[62:63], v[60:61], v[62:63], v[60:61] neg_lo:[1,0,0] neg_hi:[1,0,0]
	s_nop 0
	v_cndmask_b32_e64 v61, v63, v67, s[10:11]
	v_cndmask_b32_e32 v60, v62, v66, vcc
	v_and_b32_e32 v63, 0x7fffffff, v47
	v_and_b32_e32 v62, 0x7fffffff, v46
	v_pk_fma_f32 v[62:63], v[62:63], s[14:15], 1.0 op_sel_hi:[1,0,0]
	v_cmp_gt_f32_e32 vcc, 0, v46
	v_rcp_f32_e32 v62, v62
	v_rcp_f32_e32 v63, v63
	v_cmp_gt_f32_e64 s[10:11], 0, v47
	v_pk_fma_f32 v[66:67], v[62:63], s[42:43], v[64:65] op_sel_hi:[1,0,0]
	s_nop 0
	v_pk_fma_f32 v[66:67], v[62:63], v[66:67], s[0:1] op_sel_hi:[1,1,0]
	s_nop 0
	v_pk_fma_f32 v[66:67], v[62:63], v[66:67], s[50:51] op_sel_hi:[1,1,0]
	s_nop 0
	v_pk_fma_f32 v[66:67], v[62:63], v[66:67], s[34:35] op_sel_hi:[1,1,0]
	s_nop 0
	v_pk_mul_f32 v[62:63], v[62:63], v[66:67]
	v_pk_mul_f32 v[66:67], v[46:47], v[46:47]
	s_nop 0
	v_pk_mul_f32 v[66:67], v[66:67], s[46:47] op_sel_hi:[1,0]
	s_nop 0
	v_exp_f32_e32 v66, v66
	v_exp_f32_e32 v67, v67
	s_nop 0
	v_pk_mul_f32 v[62:63], v[66:67], v[62:63]
	s_nop 0
	v_pk_mul_f32 v[66:67], v[46:47], v[62:63]
	v_pk_fma_f32 v[62:63], v[46:47], v[62:63], v[46:47] neg_lo:[1,0,0] neg_hi:[1,0,0]
	s_nop 0
	v_cndmask_b32_e64 v47, v63, v67, s[10:11]
	v_cndmask_b32_e32 v46, v62, v66, vcc
	v_and_b32_e32 v63, 0x7fffffff, v45
	v_and_b32_e32 v62, 0x7fffffff, v44
	v_pk_fma_f32 v[62:63], v[62:63], s[14:15], 1.0 op_sel_hi:[1,0,0]
	v_cmp_gt_f32_e32 vcc, 0, v44
	v_rcp_f32_e32 v62, v62
	v_rcp_f32_e32 v63, v63
	v_cmp_gt_f32_e64 s[10:11], 0, v45
	v_pk_fma_f32 v[66:67], v[62:63], s[42:43], v[64:65] op_sel_hi:[1,0,0]
	s_nop 0
	v_pk_fma_f32 v[66:67], v[62:63], v[66:67], s[0:1] op_sel_hi:[1,1,0]
	s_nop 0
	v_pk_fma_f32 v[66:67], v[62:63], v[66:67], s[50:51] op_sel_hi:[1,1,0]
	s_nop 0
	v_pk_fma_f32 v[66:67], v[62:63], v[66:67], s[34:35] op_sel_hi:[1,1,0]
	s_nop 0
	v_pk_mul_f32 v[62:63], v[62:63], v[66:67]
	v_pk_mul_f32 v[66:67], v[44:45], v[44:45]
	s_nop 0
	v_pk_mul_f32 v[66:67], v[66:67], s[46:47] op_sel_hi:[1,0]
	s_nop 0
	v_exp_f32_e32 v66, v66
	v_exp_f32_e32 v67, v67
	s_nop 0
	v_pk_mul_f32 v[62:63], v[66:67], v[62:63]
	s_nop 0
	v_pk_mul_f32 v[66:67], v[44:45], v[62:63]
	v_pk_fma_f32 v[62:63], v[44:45], v[62:63], v[44:45] neg_lo:[1,0,0] neg_hi:[1,0,0]
	s_nop 0
	v_cndmask_b32_e64 v45, v63, v67, s[10:11]
	v_cndmask_b32_e32 v44, v62, v66, vcc
	v_and_b32_e32 v63, 0x7fffffff, v43
	v_and_b32_e32 v62, 0x7fffffff, v42
	v_pk_fma_f32 v[62:63], v[62:63], s[14:15], 1.0 op_sel_hi:[1,0,0]
	v_cmp_gt_f32_e64 s[10:11], 0, v43
	v_rcp_f32_e32 v62, v62
	v_rcp_f32_e32 v63, v63
	v_cmp_gt_f32_e32 vcc, 0, v42
	v_pk_fma_f32 v[64:65], v[62:63], s[42:43], v[64:65] op_sel_hi:[1,0,0]
	s_nop 0
	v_pk_fma_f32 v[64:65], v[62:63], v[64:65], s[0:1] op_sel_hi:[1,1,0]
	s_nop 0
	v_pk_fma_f32 v[64:65], v[62:63], v[64:65], s[50:51] op_sel_hi:[1,1,0]
	s_nop 0
	v_pk_fma_f32 v[64:65], v[62:63], v[64:65], s[34:35] op_sel_hi:[1,1,0]
	s_nop 0
	v_pk_mul_f32 v[62:63], v[62:63], v[64:65]
	v_pk_mul_f32 v[64:65], v[42:43], v[42:43]
	s_nop 0
	v_pk_mul_f32 v[64:65], v[64:65], s[46:47] op_sel_hi:[1,0]
	s_nop 0
	v_exp_f32_e32 v64, v64
	v_exp_f32_e32 v65, v65
	s_nop 0
	v_pk_mul_f32 v[62:63], v[64:65], v[62:63]
	s_nop 0
	v_pk_mul_f32 v[64:65], v[42:43], v[62:63]
	v_pk_fma_f32 v[62:63], v[42:43], v[62:63], v[42:43] neg_lo:[1,0,0] neg_hi:[1,0,0]
	s_nop 0
	v_cndmask_b32_e64 v43, v63, v65, s[10:11]
	s_cselect_b32 s10, s15, s1
	s_cselect_b32 s11, s35, s43
	s_and_b32 s12, s94, 0x100
	s_lshl_b32 s48, s12, 1
	v_lshl_add_u64 v[66:67], s[10:11], 0, v[48:49]
	v_cndmask_b32_e32 v42, v62, v64, vcc
	v_lshl_add_u64 v[66:67], v[66:67], 0, s[48:49]
	s_cmp_lt_i32 s60, 2
	v_cvt_pk_bf16_f32 v62, v60, v61
	v_cvt_pk_bf16_f32 v63, v46, v47
	v_cvt_pk_bf16_f32 v64, v44, v45
	v_cvt_pk_bf16_f32 v65, v42, v43
	v_lshl_add_u64 v[66:67], v[66:67], 0, v[140:141]
	global_store_dwordx4 v[66:67], v[62:65], off
	s_cbranch_scc1 .LBB0_897
	s_nop 0
	v_mov_b32_e32 v62, v141
	v_mov_b32_e32 v63, v61
	v_pk_add_f32 v[62:63], v[60:61], v[62:63]
	v_pk_mul_f32 v[64:65], v[60:61], v[60:61]
	v_pk_mul_f32 v[66:67], v[46:47], v[46:47]
	v_mov_b32_e32 v63, v65
	v_pk_mov_b32 v[60:61], v[60:61], v[64:65] op_sel:[1,0]
	v_pk_mul_f32 v[68:69], v[44:45], v[44:45]
	v_pk_add_f32 v[60:61], v[60:61], v[62:63]
	v_mov_b32_e32 v62, v46
	v_mov_b32_e32 v63, v66
	v_pk_add_f32 v[60:61], v[62:63], v[60:61]
	v_mov_b32_e32 v66, v47
	v_and_b32_e32 v72, 64, v175
	v_pk_add_f32 v[46:47], v[66:67], v[60:61]
	v_mov_b32_e32 v60, v44
	v_mov_b32_e32 v61, v68
	v_pk_mul_f32 v[70:71], v[42:43], v[42:43]
	v_xor_b32_e32 v59, 16, v175
	v_add_u32_e32 v72, 64, v72
	v_pk_add_f32 v[46:47], v[60:61], v[46:47]
	v_mov_b32_e32 v68, v45
	v_cmp_lt_i32_e32 vcc, v59, v72
	v_pk_add_f32 v[44:45], v[68:69], v[46:47]
	v_mov_b32_e32 v46, v42
	v_mov_b32_e32 v47, v70
	v_cndmask_b32_e32 v59, v175, v59, vcc
	v_pk_add_f32 v[44:45], v[46:47], v[44:45]
	v_mov_b32_e32 v70, v43
	v_lshlrev_b32_e32 v59, 2, v59
	v_pk_add_f32 v[42:43], v[70:71], v[44:45]
	ds_bpermute_b32 v44, v59, v42
	ds_bpermute_b32 v45, v59, v43
	v_xor_b32_e32 v46, 32, v175
	v_cmp_lt_i32_e32 vcc, v46, v72
	s_waitcnt lgkmcnt(0)
	v_pk_add_f32 v[42:43], v[42:43], v[44:45]
	v_cndmask_b32_e32 v46, v175, v46, vcc
	v_lshlrev_b32_e32 v46, 2, v46
	ds_bpermute_b32 v44, v46, v42
	ds_bpermute_b32 v45, v46, v43
	s_and_saveexec_b64 s[10:11], s[2:3]
	s_cbranch_execz .LBB0_896
	s_add_i32 s12, s94, 0xfffffe00
	s_lshr_b32 s48, s12, 5
	v_lshl_add_u64 v[46:47], v[40:41], 0, s[48:49]
	v_lshl_add_u64 v[46:47], v[46:47], 3, s[80:81]
	s_waitcnt lgkmcnt(0)
	v_pk_add_f32 v[42:43], v[42:43], v[44:45]
	global_store_dwordx2 v[46:47], v[42:43], off

; DI float quad_sum(float s) { s += __shfl_xor(s, 16); s += __shfl_xor(s, 32); return s; }
;     DI void operator()(const f32x4 (&acc)[2][2][4][2], const Unit& u, int wr, int wc, int fr, int fq) const {
;     ...
;                         for (int i = 0; i < 4; ++i) v[4 * n + i] = acc[ai][bj][m][n][i] * rs;
;                     if (c128 < 1024) {
; #pragma unroll
;                         for (int i = 0; i < 8; i += 2) { const f32x2 g = pg8::gelu_pk((f32x2){v[i], v[i + 1]}); v[i] = g.x; v[i + 1] = g.y; }
;                         const bool isv = c128 >= 512;
;                         u32x4 w; w.x = pk2(v[0], v[1]); w.y = pk2(v[2], v[3]); w.z = pk2(v[4], v[5]); w.w = pk2(v[6], v[7]);
;                         *(u32x4*)((isv ? Vg : U) + (size_t)row * 512 + (c128 & 511) + cw) = w;
;                         if (isv) {
;                             float s1 = 0.f, s2 = 0.f;
; #pragma unroll
;                             for (int i = 0; i < 8; ++i) { s1 += v[i]; s2 += v[i] * v[i]; }
;                             s1 = quad_sum(s1); s2 = quad_sum(s2);
;                             if (fq == 0) { float* d = VST + ((size_t)row * 16 + ((c128 - 512) >> 7) * 4 + wc) * 2; d[0] = s1; d[1] = s2; }
;                         }
;                     } else if (c128 < 2176) {
;                         bf16_t* dst; float* pp; const bool isqm = c128 >= 1664;
;                         if (c128 < 1408) { dst = CQ + (size_t)row * 384 + (c128 - 1024); pp = CQP + row; }
;                         else if (c128 < 1664) { dst = CKV + (size_t)row * 256 + (c128 - 1408); pp = CKVP + row; }
;                         else { dst = QM + (size_t)row * 512 + (c128 - 1664); pp = QMP + (size_t)row * 16 + ((c128 - 1664) >> 7) * 4 + wc; }
;                         u32x4 w; w.x = pk2(v[0], v[1]); w.y = pk2(v[2], v[3]); w.z = pk2(v[4], v[5]); w.w = pk2(v[6], v[7]);
;                         *(u32x4*)(dst + cw) = w;
;                         float s2 = 0.f;
; #pragma unroll
;                         for (int i = 0; i < 8; ++i) s2 += v[i] * v[i];
;                         s2 = quad_sum(s2);
;                         if (fq == 0) { if (isqm) *pp = s2; else atomic_addf(pp, s2); }
;                     } else if (c128 == 2176) {
;                         if (wc == 0) { float* d = KR + (size_t)row * 32 + 8 * fq; *(f32x4*)d = (f32x4){v[0], v[1], v[2], v[3]}; *(f32x4*)(d + 4) = (f32x4){v[4], v[5], v[6], v[7]}; }
.LBB0_897:
	v_mov_b32_e32 v59, v58
	v_pk_mul_f32 v[36:37], v[36:37], v[58:59]
	v_pk_mul_f32 v[38:39], v[38:39], v[58:59]
	v_pk_mul_f32 v[32:33], v[32:33], v[58:59]
	v_pk_mul_f32 v[34:35], v[34:35], v[58:59]
	s_and_b64 vcc, exec, s[6:7]
	s_mov_b64 s[10:11], -1
	s_cbranch_vccnz .LBB0_918
	s_cmpk_lt_u32 s37, 0x880
	s_cbranch_scc1 .LBB0_902
	s_cmp_lg_u32 s60, 8
	s_cselect_b64 s[10:11], -1, 0
	s_or_b64 s[10:11], s[72:73], s[10:11]
	s_and_b64 vcc, exec, s[10:11]
	s_cbranch_vccnz .LBB0_901
	v_lshlrev_b64 v[42:43], 7, v[50:51]
	v_lshl_add_u64 v[42:43], v[144:145], 0, v[42:43]
	global_store_dwordx4 v[42:43], v[36:39], off
	global_store_dwordx4 v[42:43], v[32:35], off offset:16

; DI unsigned pk2(float lo, float hi) { typedef float v2f __attribute__((ext_vector_type(2))); typedef __bf16 v2b __attribute__((ext_vector_type(2))); v2f v = {lo, hi}; v2b b = __builtin_convertvector(v, v2b); return __builtin_bit_cast(unsigned, b); }
; DI void atomic_addf(float* p, float v) { __builtin_amdgcn_global_atomic_fadd_f32((__attribute__((address_space(1))) float*)p, v); }
; DI float quad_sum(float s) { s += __shfl_xor(s, 16); s += __shfl_xor(s, 32); return s; }
;     DI void operator()(const f32x4 (&acc)[2][2][4][2], const Unit& u, int wr, int wc, int fr, int fq) const {
;     ...
;                         u32x4 w; w.x = pk2(v[0], v[1]); w.y = pk2(v[2], v[3]); w.z = pk2(v[4], v[5]); w.w = pk2(v[6], v[7]);
;                         *(u32x4*)(dst + cw) = w;
;                         float s2 = 0.f;
; #pragma unroll
;                         for (int i = 0; i < 8; ++i) s2 += v[i] * v[i];
;                         s2 = quad_sum(s2);
;                         if (fq == 0) { if (isqm) *pp = s2; else atomic_addf(pp, s2); }
.LBB0_911:
	v_cvt_pk_bf16_f32 v50, v36, v37
	v_cvt_pk_bf16_f32 v51, v38, v39
	v_cvt_pk_bf16_f32 v52, v32, v33
	v_cvt_pk_bf16_f32 v53, v34, v35
	s_waitcnt lgkmcnt(0)
	v_lshl_add_u64 v[44:45], v[44:45], 0, v[140:141]
	global_store_dwordx4 v[44:45], v[50:53], off
	v_pk_mul_f32 v[44:45], v[36:37], v[36:37]
	v_pk_mul_f32 v[46:47], v[38:39], v[38:39]
	v_add_f32_e32 v44, v44, v45
	v_add_f32_e32 v44, v46, v44
	v_pk_mul_f32 v[50:51], v[32:33], v[32:33]
	v_add_f32_e32 v44, v47, v44
	v_and_b32_e32 v46, 64, v175
	v_add_f32_e32 v44, v50, v44
	v_xor_b32_e32 v45, 16, v175
	v_add_u32_e32 v46, 64, v46
	v_pk_mul_f32 v[52:53], v[34:35], v[34:35]
	v_add_f32_e32 v44, v51, v44
	v_cmp_lt_i32_e32 vcc, v45, v46
	v_add_f32_e32 v44, v52, v44
	v_add_f32_e32 v44, v53, v44
	v_cndmask_b32_e32 v45, v175, v45, vcc
	v_lshlrev_b32_e32 v45, 2, v45
	ds_bpermute_b32 v45, v45, v44
	s_waitcnt lgkmcnt(0)
	v_add_f32_e32 v44, v44, v45
	v_xor_b32_e32 v45, 32, v175
	v_cmp_lt_i32_e32 vcc, v45, v46
	s_nop 1
	v_cndmask_b32_e32 v45, v175, v45, vcc
	v_lshlrev_b32_e32 v45, 2, v45
	ds_bpermute_b32 v45, v45, v44
	s_and_saveexec_b64 s[10:11], s[2:3]
	s_cbranch_execz .LBB0_916
	s_waitcnt lgkmcnt(0)
	v_add_f32_e32 v44, v44, v45
	s_cmpk_gt_u32 s37, 0x67f
	s_mov_b64 s[12:13], -1
	s_cbranch_scc1 .LBB0_914
	global_atomic_add_f32 v[42:43], v44, off
	s_mov_b64 s[12:13], 0
.LBB0_914:
	s_andn2_b64 vcc, exec, s[12:13]
	s_cbranch_vccnz .LBB0_916
	global_store_dword v[42:43], v44, off

; DI unsigned pk2(float lo, float hi) { typedef float v2f __attribute__((ext_vector_type(2))); typedef __bf16 v2b __attribute__((ext_vector_type(2))); v2f v = {lo, hi}; v2b b = __builtin_convertvector(v, v2b); return __builtin_bit_cast(unsigned, b); }
; DI float quad_sum(float s) { s += __shfl_xor(s, 16); s += __shfl_xor(s, 32); return s; }
; __device__ __forceinline__ f32x2 gelu_pk(f32x2 v) {
;     const f32x2 av = __builtin_elementwise_abs(v), d = av * 0.2316418882f + 1.0f;
;     f32x2 t; t.x = __builtin_amdgcn_rcpf(d.x); t.y = __builtin_amdgcn_rcpf(d.y);
;     f32x2 q = t * 0.5307027145f + (-0.7265760135f); q = q * t + 0.7107068705f; q = q * t + (-0.142248368f); q = q * t + 0.127414796f; q = q * t;
;     const f32x2 s = (v * v) * (-0.72134752044f);
;     f32x2 e; e.x = __builtin_amdgcn_exp2f(s.x); e.y = __builtin_amdgcn_exp2f(s.y);
;     const f32x2 m = v * (q * e), r = v - m;
;     f32x2 o; o.x = v.x < 0.f ? m.x : r.x; o.y = v.y < 0.f ? m.y : r.y; return o;
; }
;     DI void operator()(const f32x4 (&acc)[2][2][4][2], const Unit& u, int wr, int wc, int fr, int fq) const {
;     ...
;                     if (c128 < 1024) {
; #pragma unroll
;                         for (int i = 0; i < 8; i += 2) { const f32x2 g = pg8::gelu_pk((f32x2){v[i], v[i + 1]}); v[i] = g.x; v[i + 1] = g.y; }
;                         const bool isv = c128 >= 512;
;                         u32x4 w; w.x = pk2(v[0], v[1]); w.y = pk2(v[2], v[3]); w.z = pk2(v[4], v[5]); w.w = pk2(v[6], v[7]);
;                         *(u32x4*)((isv ? Vg : U) + (size_t)row * 512 + (c128 & 511) + cw) = w;
;                         if (isv) {
;                             float s1 = 0.f, s2 = 0.f;
; #pragma unroll
;                             for (int i = 0; i < 8; ++i) { s1 += v[i]; s2 += v[i] * v[i]; }
;                             s1 = quad_sum(s1); s2 = quad_sum(s2);
;                             if (fq == 0) { float* d = VST + ((size_t)row * 16 + ((c128 - 512) >> 7) * 4 + wc) * 2; d[0] = s1; d[1] = s2; }
;                         }
.LBB0_918:
	s_andn2_b64 vcc, exec, s[10:11]
	s_cbranch_vccnz .LBB0_923
	v_and_b32_e32 v43, 0x7fffffff, v37
	v_and_b32_e32 v42, 0x7fffffff, v36
	v_pk_fma_f32 v[42:43], v[42:43], s[14:15], 1.0 op_sel_hi:[1,0,0]
	s_waitcnt lgkmcnt(0)
	v_mov_b64_e32 v[44:45], s[96:97]
	v_rcp_f32_e32 v42, v42
	v_rcp_f32_e32 v43, v43
	v_cmp_gt_f32_e32 vcc, 0, v36
	v_cmp_gt_f32_e64 s[10:11], 0, v37
	s_cmpk_gt_i32 s37, 0x1ff
	v_pk_fma_f32 v[46:47], v[42:43], s[42:43], v[44:45] op_sel_hi:[1,0,0]
	s_nop 0
	v_pk_fma_f32 v[46:47], v[42:43], v[46:47], s[0:1] op_sel_hi:[1,1,0]
	s_nop 0
	v_pk_fma_f32 v[46:47], v[42:43], v[46:47], s[50:51] op_sel_hi:[1,1,0]
	s_nop 0
	v_pk_fma_f32 v[46:47], v[42:43], v[46:47], s[34:35] op_sel_hi:[1,1,0]
	s_nop 0
	v_pk_mul_f32 v[42:43], v[42:43], v[46:47]
	v_pk_mul_f32 v[46:47], v[36:37], v[36:37]
	s_nop 0
	v_pk_mul_f32 v[46:47], v[46:47], s[46:47] op_sel_hi:[1,0]
	s_nop 0
	v_exp_f32_e32 v46, v46
	v_exp_f32_e32 v47, v47
	s_nop 0
	v_pk_mul_f32 v[42:43], v[46:47], v[42:43]
	s_nop 0
	v_pk_mul_f32 v[46:47], v[36:37], v[42:43]
	v_pk_fma_f32 v[42:43], v[36:37], v[42:43], v[36:37] neg_lo:[1,0,0] neg_hi:[1,0,0]
	s_nop 0
	v_cndmask_b32_e64 v37, v43, v47, s[10:11]
	v_cndmask_b32_e32 v36, v42, v46, vcc
	v_and_b32_e32 v43, 0x7fffffff, v39
	v_and_b32_e32 v42, 0x7fffffff, v38
	v_pk_fma_f32 v[42:43], v[42:43], s[14:15], 1.0 op_sel_hi:[1,0,0]
	v_cmp_gt_f32_e32 vcc, 0, v38
	v_rcp_f32_e32 v42, v42
	v_rcp_f32_e32 v43, v43
	v_cmp_gt_f32_e64 s[10:11], 0, v39
	v_pk_fma_f32 v[46:47], v[42:43], s[42:43], v[44:45] op_sel_hi:[1,0,0]
	s_nop 0
	v_pk_fma_f32 v[46:47], v[42:43], v[46:47], s[0:1] op_sel_hi:[1,1,0]
	s_nop 0
	v_pk_fma_f32 v[46:47], v[42:43], v[46:47], s[50:51] op_sel_hi:[1,1,0]
	s_nop 0
	v_pk_fma_f32 v[46:47], v[42:43], v[46:47], s[34:35] op_sel_hi:[1,1,0]
	s_nop 0
	v_pk_mul_f32 v[42:43], v[42:43], v[46:47]
	v_pk_mul_f32 v[46:47], v[38:39], v[38:39]
	s_nop 0
	v_pk_mul_f32 v[46:47], v[46:47], s[46:47] op_sel_hi:[1,0]
	s_nop 0
	v_exp_f32_e32 v46, v46
	v_exp_f32_e32 v47, v47
	s_nop 0
	v_pk_mul_f32 v[42:43], v[46:47], v[42:43]
	s_nop 0
	v_pk_mul_f32 v[46:47], v[38:39], v[42:43]
	v_pk_fma_f32 v[42:43], v[38:39], v[42:43], v[38:39] neg_lo:[1,0,0] neg_hi:[1,0,0]
	s_nop 0
	v_cndmask_b32_e64 v39, v43, v47, s[10:11]
	v_cndmask_b32_e32 v38, v42, v46, vcc
	v_and_b32_e32 v43, 0x7fffffff, v33
	v_and_b32_e32 v42, 0x7fffffff, v32
	v_pk_fma_f32 v[42:43], v[42:43], s[14:15], 1.0 op_sel_hi:[1,0,0]
	v_cmp_gt_f32_e32 vcc, 0, v32
	v_rcp_f32_e32 v42, v42
	v_rcp_f32_e32 v43, v43
	v_cmp_gt_f32_e64 s[10:11], 0, v33
	v_pk_fma_f32 v[46:47], v[42:43], s[42:43], v[44:45] op_sel_hi:[1,0,0]
	s_nop 0
	v_pk_fma_f32 v[46:47], v[42:43], v[46:47], s[0:1] op_sel_hi:[1,1,0]
	s_nop 0
	v_pk_fma_f32 v[46:47], v[42:43], v[46:47], s[50:51] op_sel_hi:[1,1,0]
	s_nop 0
	v_pk_fma_f32 v[46:47], v[42:43], v[46:47], s[34:35] op_sel_hi:[1,1,0]
	s_nop 0
	v_pk_mul_f32 v[42:43], v[42:43], v[46:47]
	v_pk_mul_f32 v[46:47], v[32:33], v[32:33]
	s_nop 0
	v_pk_mul_f32 v[46:47], v[46:47], s[46:47] op_sel_hi:[1,0]
	s_nop 0
	v_exp_f32_e32 v46, v46
	v_exp_f32_e32 v47, v47
	s_nop 0
	v_pk_mul_f32 v[42:43], v[46:47], v[42:43]
	s_nop 0
	v_pk_mul_f32 v[46:47], v[32:33], v[42:43]
	v_pk_fma_f32 v[42:43], v[32:33], v[42:43], v[32:33] neg_lo:[1,0,0] neg_hi:[1,0,0]
	s_nop 0
	v_cndmask_b32_e64 v33, v43, v47, s[10:11]
	v_cndmask_b32_e32 v32, v42, v46, vcc
	v_and_b32_e32 v43, 0x7fffffff, v35
	v_and_b32_e32 v42, 0x7fffffff, v34
	v_pk_fma_f32 v[42:43], v[42:43], s[14:15], 1.0 op_sel_hi:[1,0,0]
	v_cmp_gt_f32_e64 s[10:11], 0, v35
	v_rcp_f32_e32 v42, v42
	v_rcp_f32_e32 v43, v43
	v_cmp_gt_f32_e32 vcc, 0, v34
	v_pk_fma_f32 v[44:45], v[42:43], s[42:43], v[44:45] op_sel_hi:[1,0,0]
	s_nop 0
	v_pk_fma_f32 v[44:45], v[42:43], v[44:45], s[0:1] op_sel_hi:[1,1,0]
	s_nop 0
	v_pk_fma_f32 v[44:45], v[42:43], v[44:45], s[50:51] op_sel_hi:[1,1,0]
	s_nop 0
	v_pk_fma_f32 v[44:45], v[42:43], v[44:45], s[34:35] op_sel_hi:[1,1,0]
	s_nop 0
	v_pk_mul_f32 v[42:43], v[42:43], v[44:45]
	v_pk_mul_f32 v[44:45], v[34:35], v[34:35]
	s_nop 0
	v_pk_mul_f32 v[44:45], v[44:45], s[46:47] op_sel_hi:[1,0]
	s_nop 0
	v_exp_f32_e32 v44, v44
	v_exp_f32_e32 v45, v45
	s_nop 0
	v_pk_mul_f32 v[42:43], v[44:45], v[42:43]
	s_nop 0
	v_pk_mul_f32 v[44:45], v[34:35], v[42:43]
	v_pk_fma_f32 v[42:43], v[34:35], v[42:43], v[34:35] neg_lo:[1,0,0] neg_hi:[1,0,0]
	s_nop 0
	v_cndmask_b32_e64 v35, v43, v45, s[10:11]
	s_cselect_b32 s10, s15, s1
	s_cselect_b32 s11, s35, s43
	s_and_b32 s12, s37, 0x180
	s_lshl_b32 s48, s12, 1
	v_lshl_add_u64 v[46:47], s[10:11], 0, v[48:49]
	v_cndmask_b32_e32 v34, v42, v44, vcc
	v_lshl_add_u64 v[46:47], v[46:47], 0, s[48:49]
	s_cmpk_lt_i32 s37, 0x200
	v_cvt_pk_bf16_f32 v42, v36, v37
	v_cvt_pk_bf16_f32 v43, v38, v39
	v_cvt_pk_bf16_f32 v44, v32, v33
	v_cvt_pk_bf16_f32 v45, v34, v35
	v_lshl_add_u64 v[46:47], v[46:47], 0, v[140:141]
	global_store_dwordx4 v[46:47], v[42:45], off
	s_cbranch_scc1 .LBB0_923
	s_nop 0
	v_mov_b32_e32 v42, v141
	v_mov_b32_e32 v43, v37
	v_pk_add_f32 v[42:43], v[36:37], v[42:43]
	v_pk_mul_f32 v[44:45], v[36:37], v[36:37]
	v_pk_mul_f32 v[46:47], v[38:39], v[38:39]
	v_mov_b32_e32 v43, v45
	v_pk_mov_b32 v[36:37], v[36:37], v[44:45] op_sel:[1,0]
	v_pk_mul_f32 v[48:49], v[32:33], v[32:33]
	v_pk_add_f32 v[36:37], v[36:37], v[42:43]
	v_mov_b32_e32 v42, v38
	v_mov_b32_e32 v43, v46
	v_pk_add_f32 v[36:37], v[42:43], v[36:37]
	v_mov_b32_e32 v46, v39
	v_and_b32_e32 v53, 64, v175
	v_pk_add_f32 v[36:37], v[46:47], v[36:37]
	v_mov_b32_e32 v38, v32
	v_mov_b32_e32 v39, v48
	v_pk_mul_f32 v[50:51], v[34:35], v[34:35]
	v_xor_b32_e32 v52, 16, v175
	v_add_u32_e32 v53, 64, v53
	v_pk_add_f32 v[36:37], v[38:39], v[36:37]
	v_mov_b32_e32 v48, v33
	v_cmp_lt_i32_e32 vcc, v52, v53
	v_pk_add_f32 v[32:33], v[48:49], v[36:37]
	v_mov_b32_e32 v36, v34
	v_mov_b32_e32 v37, v50
	v_cndmask_b32_e32 v52, v175, v52, vcc
	v_pk_add_f32 v[32:33], v[36:37], v[32:33]
	v_mov_b32_e32 v50, v35
	v_lshlrev_b32_e32 v52, 2, v52
	v_pk_add_f32 v[32:33], v[50:51], v[32:33]
	ds_bpermute_b32 v34, v52, v32
	ds_bpermute_b32 v35, v52, v33
	v_xor_b32_e32 v36, 32, v175
	v_cmp_lt_i32_e32 vcc, v36, v53
	s_waitcnt lgkmcnt(0)
	v_pk_add_f32 v[32:33], v[32:33], v[34:35]
	v_cndmask_b32_e32 v36, v175, v36, vcc
	v_lshlrev_b32_e32 v36, 2, v36
	ds_bpermute_b32 v34, v36, v32
	ds_bpermute_b32 v35, v36, v33
	s_and_saveexec_b64 s[10:11], s[2:3]
	s_cbranch_execz .LBB0_922
	s_add_i32 s12, s94, 0xfffffe80
	s_lshr_b32 s48, s12, 5
	v_lshl_add_u64 v[36:37], v[40:41], 0, s[48:49]
	v_lshl_add_u64 v[36:37], v[36:37], 3, s[80:81]
	s_waitcnt lgkmcnt(0)
	v_pk_add_f32 v[32:33], v[32:33], v[34:35]
	global_store_dwordx2 v[36:37], v[32:33], off

; DI unsigned pk2(float lo, float hi) { typedef float v2f __attribute__((ext_vector_type(2))); typedef __bf16 v2b __attribute__((ext_vector_type(2))); v2f v = {lo, hi}; v2b b = __builtin_convertvector(v, v2b); return __builtin_bit_cast(unsigned, b); }
; DI void atomic_addf(float* p, float v) { __builtin_amdgcn_global_atomic_fadd_f32((__attribute__((address_space(1))) float*)p, v); }
; DI float quad_sum(float s) { s += __shfl_xor(s, 16); s += __shfl_xor(s, 32); return s; }
;     DI void operator()(const f32x4 (&acc)[2][2][4][2], const Unit& u, int wr, int wc, int fr, int fq) const {
;     ...
;                         u32x4 w; w.x = pk2(v[0], v[1]); w.y = pk2(v[2], v[3]); w.z = pk2(v[4], v[5]); w.w = pk2(v[6], v[7]);
;                         *(u32x4*)(dst + cw) = w;
;                         float s2 = 0.f;
; #pragma unroll
;                         for (int i = 0; i < 8; ++i) s2 += v[i] * v[i];
;                         s2 = quad_sum(s2);
;                         if (fq == 0) { if (isqm) *pp = s2; else atomic_addf(pp, s2); }
.LBB0_933:
	v_cvt_pk_bf16_f32 v48, v44, v45
	v_cvt_pk_bf16_f32 v49, v30, v31
	v_cvt_pk_bf16_f32 v50, v28, v29
	v_cvt_pk_bf16_f32 v51, v26, v27
	v_lshl_add_u64 v[46:47], v[46:47], 0, v[140:141]
	global_store_dwordx4 v[46:47], v[48:51], off
	v_pk_mul_f32 v[46:47], v[44:45], v[44:45]
	v_pk_mul_f32 v[52:53], v[26:27], v[26:27]
	v_pk_mul_f32 v[48:49], v[30:31], v[30:31]
	v_add_f32_e32 v43, v46, v47
	v_add_f32_e32 v43, v48, v43
	v_pk_mul_f32 v[50:51], v[28:29], v[28:29]
	v_add_f32_e32 v43, v49, v43
	v_and_b32_e32 v47, 64, v175
	v_add_f32_e32 v43, v50, v43
	v_xor_b32_e32 v46, 16, v175
	v_add_u32_e32 v47, 64, v47
	v_add_f32_e32 v43, v51, v43
	v_cmp_lt_i32_e32 vcc, v46, v47
	v_add_f32_e32 v43, v52, v43
	v_add_f32_e32 v43, v53, v43
	v_cndmask_b32_e32 v46, v175, v46, vcc
	v_lshlrev_b32_e32 v46, 2, v46
	ds_bpermute_b32 v46, v46, v43
	s_waitcnt lgkmcnt(0)
	v_add_f32_e32 v43, v43, v46
	v_xor_b32_e32 v46, 32, v175
	v_cmp_lt_i32_e32 vcc, v46, v47
	s_nop 1
	v_cndmask_b32_e32 v46, v175, v46, vcc
	v_lshlrev_b32_e32 v46, 2, v46
	ds_bpermute_b32 v46, v46, v43
	s_and_saveexec_b64 s[10:11], s[2:3]
	s_cbranch_execz .LBB0_938
	s_waitcnt lgkmcnt(0)
	v_add_f32_e32 v43, v43, v46
	s_cmpk_gt_u32 s94, 0x67f
	s_mov_b64 s[12:13], -1
	s_cbranch_scc1 .LBB0_936
	global_atomic_add_f32 v[24:25], v43, off
	s_mov_b64 s[12:13], 0
.LBB0_936:
	s_andn2_b64 vcc, exec, s[12:13]
	s_cbranch_vccnz .LBB0_938
	global_store_dword v[24:25], v43, off

; DI unsigned pk2(float lo, float hi) { typedef float v2f __attribute__((ext_vector_type(2))); typedef __bf16 v2b __attribute__((ext_vector_type(2))); v2f v = {lo, hi}; v2b b = __builtin_convertvector(v, v2b); return __builtin_bit_cast(unsigned, b); }
; DI float quad_sum(float s) { s += __shfl_xor(s, 16); s += __shfl_xor(s, 32); return s; }
; __device__ __forceinline__ f32x2 gelu_pk(f32x2 v) {
;     const f32x2 av = __builtin_elementwise_abs(v), d = av * 0.2316418882f + 1.0f;
;     f32x2 t; t.x = __builtin_amdgcn_rcpf(d.x); t.y = __builtin_amdgcn_rcpf(d.y);
;     f32x2 q = t * 0.5307027145f + (-0.7265760135f); q = q * t + 0.7107068705f; q = q * t + (-0.142248368f); q = q * t + 0.127414796f; q = q * t;
;     const f32x2 s = (v * v) * (-0.72134752044f);
;     f32x2 e; e.x = __builtin_amdgcn_exp2f(s.x); e.y = __builtin_amdgcn_exp2f(s.y);
;     const f32x2 m = v * (q * e), r = v - m;
;     f32x2 o; o.x = v.x < 0.f ? m.x : r.x; o.y = v.y < 0.f ? m.y : r.y; return o;
;     DI void operator()(const f32x4 (&acc)[2][2][4][2], const Unit& u, int wr, int wc, int fr, int fq) const {
;     ...
;                     if (c128 < 1024) {
; #pragma unroll
;                         for (int i = 0; i < 8; i += 2) { const f32x2 g = pg8::gelu_pk((f32x2){v[i], v[i + 1]}); v[i] = g.x; v[i + 1] = g.y; }
;                         const bool isv = c128 >= 512;
;                         u32x4 w; w.x = pk2(v[0], v[1]); w.y = pk2(v[2], v[3]); w.z = pk2(v[4], v[5]); w.w = pk2(v[6], v[7]);
;                         *(u32x4*)((isv ? Vg : U) + (size_t)row * 512 + (c128 & 511) + cw) = w;
;                         if (isv) {
;                             float s1 = 0.f, s2 = 0.f;
; #pragma unroll
;                             for (int i = 0; i < 8; ++i) { s1 += v[i]; s2 += v[i] * v[i]; }
;                             s1 = quad_sum(s1); s2 = quad_sum(s2);
;                             if (fq == 0) { float* d = VST + ((size_t)row * 16 + ((c128 - 512) >> 7) * 4 + wc) * 2; d[0] = s1; d[1] = s2; }
;                         }
.LBB0_940:
	v_lshlrev_b64 v[24:25], 4, v[34:35]
	s_andn2_b64 vcc, exec, s[10:11]
	v_or_b32_e32 v24, s97, v24
	s_cbranch_vccnz .LBB0_945
	v_and_b32_e32 v47, 0x7fffffff, v45
	s_waitcnt lgkmcnt(0)
	v_and_b32_e32 v46, 0x7fffffff, v44
	v_pk_fma_f32 v[46:47], v[46:47], s[14:15], 1.0 op_sel_hi:[1,0,0]
	v_mov_b64_e32 v[48:49], s[96:97]
	v_rcp_f32_e32 v46, v46
	v_rcp_f32_e32 v47, v47
	v_cmp_gt_f32_e32 vcc, 0, v44
	v_cmp_gt_f32_e64 s[10:11], 0, v45
	s_cmp_gt_i32 s60, 1
	v_pk_fma_f32 v[50:51], v[46:47], s[42:43], v[48:49] op_sel_hi:[1,0,0]
	s_nop 0
	v_pk_fma_f32 v[50:51], v[46:47], v[50:51], s[0:1] op_sel_hi:[1,1,0]
	s_nop 0
	v_pk_fma_f32 v[50:51], v[46:47], v[50:51], s[50:51] op_sel_hi:[1,1,0]
	s_nop 0
	v_pk_fma_f32 v[50:51], v[46:47], v[50:51], s[34:35] op_sel_hi:[1,1,0]
	s_nop 0
	v_pk_mul_f32 v[46:47], v[46:47], v[50:51]
	v_pk_mul_f32 v[50:51], v[44:45], v[44:45]
	s_nop 0
	v_pk_mul_f32 v[50:51], v[50:51], s[46:47] op_sel_hi:[1,0]
	s_nop 0
	v_exp_f32_e32 v50, v50
	v_exp_f32_e32 v51, v51
	s_nop 0
	v_pk_mul_f32 v[46:47], v[50:51], v[46:47]
	s_nop 0
	v_pk_mul_f32 v[50:51], v[44:45], v[46:47]
	v_pk_fma_f32 v[46:47], v[44:45], v[46:47], v[44:45] neg_lo:[1,0,0] neg_hi:[1,0,0]
	s_nop 0
	v_cndmask_b32_e64 v45, v47, v51, s[10:11]
	v_cndmask_b32_e32 v44, v46, v50, vcc
	v_and_b32_e32 v47, 0x7fffffff, v31
	v_and_b32_e32 v46, 0x7fffffff, v30
	v_pk_fma_f32 v[46:47], v[46:47], s[14:15], 1.0 op_sel_hi:[1,0,0]
	v_cmp_gt_f32_e32 vcc, 0, v30
	v_rcp_f32_e32 v46, v46
	v_rcp_f32_e32 v47, v47
	v_cmp_gt_f32_e64 s[10:11], 0, v31
	v_pk_fma_f32 v[50:51], v[46:47], s[42:43], v[48:49] op_sel_hi:[1,0,0]
	s_nop 0
	v_pk_fma_f32 v[50:51], v[46:47], v[50:51], s[0:1] op_sel_hi:[1,1,0]
	s_nop 0
	v_pk_fma_f32 v[50:51], v[46:47], v[50:51], s[50:51] op_sel_hi:[1,1,0]
	s_nop 0
	v_pk_fma_f32 v[50:51], v[46:47], v[50:51], s[34:35] op_sel_hi:[1,1,0]
	s_nop 0
	v_pk_mul_f32 v[46:47], v[46:47], v[50:51]
	v_pk_mul_f32 v[50:51], v[30:31], v[30:31]
	s_nop 0
	v_pk_mul_f32 v[50:51], v[50:51], s[46:47] op_sel_hi:[1,0]
	s_nop 0
	v_exp_f32_e32 v50, v50
	v_exp_f32_e32 v51, v51
	s_nop 0
	v_pk_mul_f32 v[46:47], v[50:51], v[46:47]
	s_nop 0
	v_pk_mul_f32 v[50:51], v[30:31], v[46:47]
	v_pk_fma_f32 v[46:47], v[30:31], v[46:47], v[30:31] neg_lo:[1,0,0] neg_hi:[1,0,0]
	s_nop 0
	v_cndmask_b32_e64 v31, v47, v51, s[10:11]
	v_cndmask_b32_e32 v30, v46, v50, vcc
	v_and_b32_e32 v47, 0x7fffffff, v29
	v_and_b32_e32 v46, 0x7fffffff, v28
	v_pk_fma_f32 v[46:47], v[46:47], s[14:15], 1.0 op_sel_hi:[1,0,0]
	v_cmp_gt_f32_e32 vcc, 0, v28
	v_rcp_f32_e32 v46, v46
	v_rcp_f32_e32 v47, v47
	v_cmp_gt_f32_e64 s[10:11], 0, v29
	v_pk_fma_f32 v[50:51], v[46:47], s[42:43], v[48:49] op_sel_hi:[1,0,0]
	s_nop 0
	v_pk_fma_f32 v[50:51], v[46:47], v[50:51], s[0:1] op_sel_hi:[1,1,0]
	s_nop 0
	v_pk_fma_f32 v[50:51], v[46:47], v[50:51], s[50:51] op_sel_hi:[1,1,0]
	s_nop 0
	v_pk_fma_f32 v[50:51], v[46:47], v[50:51], s[34:35] op_sel_hi:[1,1,0]
	s_nop 0
	v_pk_mul_f32 v[46:47], v[46:47], v[50:51]
	v_pk_mul_f32 v[50:51], v[28:29], v[28:29]
	s_nop 0
	v_pk_mul_f32 v[50:51], v[50:51], s[46:47] op_sel_hi:[1,0]
	s_nop 0
	v_exp_f32_e32 v50, v50
	v_exp_f32_e32 v51, v51
	s_nop 0
	v_pk_mul_f32 v[46:47], v[50:51], v[46:47]
	s_nop 0
	v_pk_mul_f32 v[50:51], v[28:29], v[46:47]
	v_pk_fma_f32 v[46:47], v[28:29], v[46:47], v[28:29] neg_lo:[1,0,0] neg_hi:[1,0,0]
	s_nop 0
	v_cndmask_b32_e64 v29, v47, v51, s[10:11]
	v_cndmask_b32_e32 v28, v46, v50, vcc
	v_and_b32_e32 v47, 0x7fffffff, v27
	v_and_b32_e32 v46, 0x7fffffff, v26
	v_pk_fma_f32 v[46:47], v[46:47], s[14:15], 1.0 op_sel_hi:[1,0,0]
	v_cmp_gt_f32_e64 s[10:11], 0, v27
	v_rcp_f32_e32 v46, v46
	v_rcp_f32_e32 v47, v47
	v_cmp_gt_f32_e32 vcc, 0, v26
	v_pk_fma_f32 v[48:49], v[46:47], s[42:43], v[48:49] op_sel_hi:[1,0,0]
	s_nop 0
	v_pk_fma_f32 v[48:49], v[46:47], v[48:49], s[0:1] op_sel_hi:[1,1,0]
	s_nop 0
	v_pk_fma_f32 v[48:49], v[46:47], v[48:49], s[50:51] op_sel_hi:[1,1,0]
	s_nop 0
	v_pk_fma_f32 v[48:49], v[46:47], v[48:49], s[34:35] op_sel_hi:[1,1,0]
	s_nop 0
	v_pk_mul_f32 v[46:47], v[46:47], v[48:49]
	v_pk_mul_f32 v[48:49], v[26:27], v[26:27]
	s_nop 0
	v_pk_mul_f32 v[48:49], v[48:49], s[46:47] op_sel_hi:[1,0]
	s_nop 0
	v_exp_f32_e32 v48, v48
	v_exp_f32_e32 v49, v49
	s_nop 0
	v_pk_mul_f32 v[46:47], v[48:49], v[46:47]
	s_nop 0
	v_pk_mul_f32 v[48:49], v[26:27], v[46:47]
	v_pk_fma_f32 v[46:47], v[26:27], v[46:47], v[26:27] neg_lo:[1,0,0] neg_hi:[1,0,0]
	s_nop 0
	v_cndmask_b32_e64 v27, v47, v49, s[10:11]
	s_cselect_b32 s10, s15, s1
	s_cselect_b32 s11, s35, s43
	s_and_b32 s12, s94, 0x100
	s_lshl_b32 s48, s12, 1
	v_lshl_add_u64 v[50:51], s[10:11], 0, v[32:33]
	v_cndmask_b32_e32 v26, v46, v48, vcc
	v_lshl_add_u64 v[50:51], v[50:51], 0, s[48:49]
	s_cmp_lt_i32 s60, 2
	v_cvt_pk_bf16_f32 v46, v44, v45
	v_cvt_pk_bf16_f32 v47, v30, v31
	v_cvt_pk_bf16_f32 v48, v28, v29
	v_cvt_pk_bf16_f32 v49, v26, v27
	v_lshl_add_u64 v[50:51], v[50:51], 0, v[140:141]
	global_store_dwordx4 v[50:51], v[46:49], off
	s_cbranch_scc1 .LBB0_945
	s_nop 0
	v_mov_b32_e32 v46, v141
	v_mov_b32_e32 v47, v45
	v_pk_add_f32 v[46:47], v[44:45], v[46:47]
	v_pk_mul_f32 v[48:49], v[44:45], v[44:45]
	v_pk_mul_f32 v[50:51], v[30:31], v[30:31]
	v_mov_b32_e32 v47, v49
	v_pk_mov_b32 v[44:45], v[44:45], v[48:49] op_sel:[1,0]
	v_pk_mul_f32 v[52:53], v[28:29], v[28:29]
	v_pk_add_f32 v[44:45], v[44:45], v[46:47]
	v_mov_b32_e32 v46, v30
	v_mov_b32_e32 v47, v50
	v_pk_add_f32 v[44:45], v[46:47], v[44:45]
	v_mov_b32_e32 v50, v31
	v_and_b32_e32 v56, 64, v175
	v_pk_add_f32 v[30:31], v[50:51], v[44:45]
	v_mov_b32_e32 v44, v28
	v_mov_b32_e32 v45, v52
	v_pk_mul_f32 v[54:55], v[26:27], v[26:27]
	v_xor_b32_e32 v43, 16, v175
	v_add_u32_e32 v56, 64, v56
	v_pk_add_f32 v[30:31], v[44:45], v[30:31]
	v_mov_b32_e32 v52, v29
	v_cmp_lt_i32_e32 vcc, v43, v56
	v_pk_add_f32 v[28:29], v[52:53], v[30:31]
	v_mov_b32_e32 v30, v26
	v_mov_b32_e32 v31, v54
	v_cndmask_b32_e32 v43, v175, v43, vcc
	v_pk_add_f32 v[28:29], v[30:31], v[28:29]
	v_mov_b32_e32 v54, v27
	v_lshlrev_b32_e32 v43, 2, v43
	v_pk_add_f32 v[26:27], v[54:55], v[28:29]
	ds_bpermute_b32 v28, v43, v26
	ds_bpermute_b32 v29, v43, v27
	v_xor_b32_e32 v30, 32, v175
	v_cmp_lt_i32_e32 vcc, v30, v56
	s_waitcnt lgkmcnt(0)
	v_pk_add_f32 v[26:27], v[26:27], v[28:29]
	v_cndmask_b32_e32 v30, v175, v30, vcc
	v_lshlrev_b32_e32 v30, 2, v30
	ds_bpermute_b32 v28, v30, v26
	ds_bpermute_b32 v29, v30, v27
	s_and_saveexec_b64 s[10:11], s[2:3]
	s_cbranch_execz .LBB0_944
	s_add_i32 s12, s94, 0xfffffe00
	s_lshr_b32 s48, s12, 5
	v_lshl_add_u64 v[30:31], v[24:25], 0, s[48:49]
	v_lshl_add_u64 v[30:31], v[30:31], 3, s[80:81]
	s_waitcnt lgkmcnt(0)
	v_pk_add_f32 v[26:27], v[26:27], v[28:29]
	global_store_dwordx2 v[30:31], v[26:27], off

;     DI void operator()(const f32x4 (&acc)[2][2][4][2], const Unit& u, int wr, int wc, int fr, int fq) const {
;     ...
;                         for (int i = 0; i < 4; ++i) v[4 * n + i] = acc[ai][bj][m][n][i] * rs;
;     ...
;                     } else if (c128 == 2176) {
;                         if (wc == 0) { float* d = KR + (size_t)row * 32 + 8 * fq; *(f32x4*)d = (f32x4){v[0], v[1], v[2], v[3]}; *(f32x4*)(d + 4) = (f32x4){v[4], v[5], v[6], v[7]}; }
.LBB0_945:
	v_mov_b32_e32 v43, v42
	v_pk_mul_f32 v[20:21], v[20:21], v[42:43]
	v_pk_mul_f32 v[22:23], v[22:23], v[42:43]
	v_pk_mul_f32 v[16:17], v[16:17], v[42:43]
	v_pk_mul_f32 v[18:19], v[18:19], v[42:43]
	s_and_b64 vcc, exec, s[6:7]
	s_mov_b64 s[10:11], -1
	s_cbranch_vccnz .LBB0_966
	s_cmpk_lt_u32 s37, 0x880
	s_cbranch_scc1 .LBB0_950
	s_cmp_lg_u32 s60, 8
	s_cselect_b64 s[10:11], -1, 0
	s_or_b64 s[10:11], s[72:73], s[10:11]
	s_and_b64 vcc, exec, s[10:11]
	s_cbranch_vccnz .LBB0_949
	v_lshlrev_b64 v[26:27], 7, v[34:35]
	v_lshl_add_u64 v[26:27], v[144:145], 0, v[26:27]
	global_store_dwordx4 v[26:27], v[20:23], off
	global_store_dwordx4 v[26:27], v[16:19], off offset:16

; DI unsigned pk2(float lo, float hi) { typedef float v2f __attribute__((ext_vector_type(2))); typedef __bf16 v2b __attribute__((ext_vector_type(2))); v2f v = {lo, hi}; v2b b = __builtin_convertvector(v, v2b); return __builtin_bit_cast(unsigned, b); }
; DI void atomic_addf(float* p, float v) { __builtin_amdgcn_global_atomic_fadd_f32((__attribute__((address_space(1))) float*)p, v); }
; DI float quad_sum(float s) { s += __shfl_xor(s, 16); s += __shfl_xor(s, 32); return s; }
;     DI void operator()(const f32x4 (&acc)[2][2][4][2], const Unit& u, int wr, int wc, int fr, int fq) const {
;     ...
;                         u32x4 w; w.x = pk2(v[0], v[1]); w.y = pk2(v[2], v[3]); w.z = pk2(v[4], v[5]); w.w = pk2(v[6], v[7]);
;                         *(u32x4*)(dst + cw) = w;
;                         float s2 = 0.f;
; #pragma unroll
;                         for (int i = 0; i < 8; ++i) s2 += v[i] * v[i];
;                         s2 = quad_sum(s2);
;                         if (fq == 0) { if (isqm) *pp = s2; else atomic_addf(pp, s2); }
.LBB0_959:
	v_cvt_pk_bf16_f32 v34, v20, v21
	v_cvt_pk_bf16_f32 v35, v22, v23
	v_cvt_pk_bf16_f32 v36, v16, v17
	v_cvt_pk_bf16_f32 v37, v18, v19
	s_waitcnt lgkmcnt(0)
	v_lshl_add_u64 v[28:29], v[28:29], 0, v[140:141]
	global_store_dwordx4 v[28:29], v[34:37], off
	v_pk_mul_f32 v[28:29], v[20:21], v[20:21]
	v_pk_mul_f32 v[30:31], v[22:23], v[22:23]
	v_add_f32_e32 v28, v28, v29
	v_add_f32_e32 v28, v30, v28
	v_pk_mul_f32 v[34:35], v[16:17], v[16:17]
	v_add_f32_e32 v28, v31, v28
	v_and_b32_e32 v30, 64, v175
	v_add_f32_e32 v28, v34, v28
	v_xor_b32_e32 v29, 16, v175
	v_add_u32_e32 v30, 64, v30
	v_pk_mul_f32 v[36:37], v[18:19], v[18:19]
	v_add_f32_e32 v28, v35, v28
	v_cmp_lt_i32_e32 vcc, v29, v30
	v_add_f32_e32 v28, v36, v28
	v_add_f32_e32 v28, v37, v28
	v_cndmask_b32_e32 v29, v175, v29, vcc
	v_lshlrev_b32_e32 v29, 2, v29
	ds_bpermute_b32 v29, v29, v28
	s_waitcnt lgkmcnt(0)
	v_add_f32_e32 v28, v28, v29
	v_xor_b32_e32 v29, 32, v175
	v_cmp_lt_i32_e32 vcc, v29, v30
	s_nop 1
	v_cndmask_b32_e32 v29, v175, v29, vcc
	v_lshlrev_b32_e32 v29, 2, v29
	ds_bpermute_b32 v29, v29, v28
	s_and_saveexec_b64 s[10:11], s[2:3]
	s_cbranch_execz .LBB0_964
	s_waitcnt lgkmcnt(0)
	v_add_f32_e32 v28, v28, v29
	s_cmpk_gt_u32 s37, 0x67f
	s_mov_b64 s[12:13], -1
	s_cbranch_scc1 .LBB0_962
	global_atomic_add_f32 v[26:27], v28, off
	s_mov_b64 s[12:13], 0
.LBB0_962:
	s_andn2_b64 vcc, exec, s[12:13]
	s_cbranch_vccnz .LBB0_964
	global_store_dword v[26:27], v28, off

; DI unsigned pk2(float lo, float hi) { typedef float v2f __attribute__((ext_vector_type(2))); typedef __bf16 v2b __attribute__((ext_vector_type(2))); v2f v = {lo, hi}; v2b b = __builtin_convertvector(v, v2b); return __builtin_bit_cast(unsigned, b); }
; DI float quad_sum(float s) { s += __shfl_xor(s, 16); s += __shfl_xor(s, 32); return s; }
; __device__ __forceinline__ f32x2 gelu_pk(f32x2 v) {
;     const f32x2 av = __builtin_elementwise_abs(v), d = av * 0.2316418882f + 1.0f;
;     f32x2 t; t.x = __builtin_amdgcn_rcpf(d.x); t.y = __builtin_amdgcn_rcpf(d.y);
;     f32x2 q = t * 0.5307027145f + (-0.7265760135f); q = q * t + 0.7107068705f; q = q * t + (-0.142248368f); q = q * t + 0.127414796f; q = q * t;
;     const f32x2 s = (v * v) * (-0.72134752044f);
;     f32x2 e; e.x = __builtin_amdgcn_exp2f(s.x); e.y = __builtin_amdgcn_exp2f(s.y);
;     const f32x2 m = v * (q * e), r = v - m;
;     f32x2 o; o.x = v.x < 0.f ? m.x : r.x; o.y = v.y < 0.f ? m.y : r.y; return o;
;     DI void operator()(const f32x4 (&acc)[2][2][4][2], const Unit& u, int wr, int wc, int fr, int fq) const {
;     ...
;                     if (c128 < 1024) {
; #pragma unroll
;                         for (int i = 0; i < 8; i += 2) { const f32x2 g = pg8::gelu_pk((f32x2){v[i], v[i + 1]}); v[i] = g.x; v[i + 1] = g.y; }
;                         const bool isv = c128 >= 512;
;                         u32x4 w; w.x = pk2(v[0], v[1]); w.y = pk2(v[2], v[3]); w.z = pk2(v[4], v[5]); w.w = pk2(v[6], v[7]);
;                         *(u32x4*)((isv ? Vg : U) + (size_t)row * 512 + (c128 & 511) + cw) = w;
;                         if (isv) {
;                             float s1 = 0.f, s2 = 0.f;
; #pragma unroll
;                             for (int i = 0; i < 8; ++i) { s1 += v[i]; s2 += v[i] * v[i]; }
;                             s1 = quad_sum(s1); s2 = quad_sum(s2);
;                             if (fq == 0) { float* d = VST + ((size_t)row * 16 + ((c128 - 512) >> 7) * 4 + wc) * 2; d[0] = s1; d[1] = s2; }
;                         }
.LBB0_966:
	s_andn2_b64 vcc, exec, s[10:11]
	s_cbranch_vccnz .LBB0_971
	v_and_b32_e32 v27, 0x7fffffff, v21
	v_and_b32_e32 v26, 0x7fffffff, v20
	v_pk_fma_f32 v[26:27], v[26:27], s[14:15], 1.0 op_sel_hi:[1,0,0]
	s_waitcnt lgkmcnt(0)
	v_mov_b64_e32 v[28:29], s[96:97]
	v_rcp_f32_e32 v26, v26
	v_rcp_f32_e32 v27, v27
	v_cmp_gt_f32_e32 vcc, 0, v20
	v_cmp_gt_f32_e64 s[10:11], 0, v21
	s_cmpk_gt_i32 s37, 0x1ff
	v_pk_fma_f32 v[30:31], v[26:27], s[42:43], v[28:29] op_sel_hi:[1,0,0]
	s_nop 0
	v_pk_fma_f32 v[30:31], v[26:27], v[30:31], s[0:1] op_sel_hi:[1,1,0]
	s_nop 0
	v_pk_fma_f32 v[30:31], v[26:27], v[30:31], s[50:51] op_sel_hi:[1,1,0]
	s_nop 0
	v_pk_fma_f32 v[30:31], v[26:27], v[30:31], s[34:35] op_sel_hi:[1,1,0]
	s_nop 0
	v_pk_mul_f32 v[26:27], v[26:27], v[30:31]
	v_pk_mul_f32 v[30:31], v[20:21], v[20:21]
	s_nop 0
	v_pk_mul_f32 v[30:31], v[30:31], s[46:47] op_sel_hi:[1,0]
	s_nop 0
	v_exp_f32_e32 v30, v30
	v_exp_f32_e32 v31, v31
	s_nop 0
	v_pk_mul_f32 v[26:27], v[30:31], v[26:27]
	s_nop 0
	v_pk_mul_f32 v[30:31], v[20:21], v[26:27]
	v_pk_fma_f32 v[26:27], v[20:21], v[26:27], v[20:21] neg_lo:[1,0,0] neg_hi:[1,0,0]
	s_nop 0
	v_cndmask_b32_e64 v21, v27, v31, s[10:11]
	v_cndmask_b32_e32 v20, v26, v30, vcc
	v_and_b32_e32 v27, 0x7fffffff, v23
	v_and_b32_e32 v26, 0x7fffffff, v22
	v_pk_fma_f32 v[26:27], v[26:27], s[14:15], 1.0 op_sel_hi:[1,0,0]
	v_cmp_gt_f32_e32 vcc, 0, v22
	v_rcp_f32_e32 v26, v26
	v_rcp_f32_e32 v27, v27
	v_cmp_gt_f32_e64 s[10:11], 0, v23
	v_pk_fma_f32 v[30:31], v[26:27], s[42:43], v[28:29] op_sel_hi:[1,0,0]
	s_nop 0
	v_pk_fma_f32 v[30:31], v[26:27], v[30:31], s[0:1] op_sel_hi:[1,1,0]
	s_nop 0
	v_pk_fma_f32 v[30:31], v[26:27], v[30:31], s[50:51] op_sel_hi:[1,1,0]
	s_nop 0
	v_pk_fma_f32 v[30:31], v[26:27], v[30:31], s[34:35] op_sel_hi:[1,1,0]
	s_nop 0
	v_pk_mul_f32 v[26:27], v[26:27], v[30:31]
	v_pk_mul_f32 v[30:31], v[22:23], v[22:23]
	s_nop 0
	v_pk_mul_f32 v[30:31], v[30:31], s[46:47] op_sel_hi:[1,0]
	s_nop 0
	v_exp_f32_e32 v30, v30
	v_exp_f32_e32 v31, v31
	s_nop 0
	v_pk_mul_f32 v[26:27], v[30:31], v[26:27]
	s_nop 0
	v_pk_mul_f32 v[30:31], v[22:23], v[26:27]
	v_pk_fma_f32 v[26:27], v[22:23], v[26:27], v[22:23] neg_lo:[1,0,0] neg_hi:[1,0,0]
	s_nop 0
	v_cndmask_b32_e64 v23, v27, v31, s[10:11]
	v_cndmask_b32_e32 v22, v26, v30, vcc
	v_and_b32_e32 v27, 0x7fffffff, v17
	v_and_b32_e32 v26, 0x7fffffff, v16
	v_pk_fma_f32 v[26:27], v[26:27], s[14:15], 1.0 op_sel_hi:[1,0,0]
	v_cmp_gt_f32_e32 vcc, 0, v16
	v_rcp_f32_e32 v26, v26
	v_rcp_f32_e32 v27, v27
	v_cmp_gt_f32_e64 s[10:11], 0, v17
	v_pk_fma_f32 v[30:31], v[26:27], s[42:43], v[28:29] op_sel_hi:[1,0,0]
	s_nop 0
	v_pk_fma_f32 v[30:31], v[26:27], v[30:31], s[0:1] op_sel_hi:[1,1,0]
	s_nop 0
	v_pk_fma_f32 v[30:31], v[26:27], v[30:31], s[50:51] op_sel_hi:[1,1,0]
	s_nop 0
	v_pk_fma_f32 v[30:31], v[26:27], v[30:31], s[34:35] op_sel_hi:[1,1,0]
	s_nop 0
	v_pk_mul_f32 v[26:27], v[26:27], v[30:31]
	v_pk_mul_f32 v[30:31], v[16:17], v[16:17]
	s_nop 0
	v_pk_mul_f32 v[30:31], v[30:31], s[46:47] op_sel_hi:[1,0]
	s_nop 0
	v_exp_f32_e32 v30, v30
	v_exp_f32_e32 v31, v31
	s_nop 0
	v_pk_mul_f32 v[26:27], v[30:31], v[26:27]
	s_nop 0
	v_pk_mul_f32 v[30:31], v[16:17], v[26:27]
	v_pk_fma_f32 v[26:27], v[16:17], v[26:27], v[16:17] neg_lo:[1,0,0] neg_hi:[1,0,0]
	s_nop 0
	v_cndmask_b32_e64 v17, v27, v31, s[10:11]
	v_cndmask_b32_e32 v16, v26, v30, vcc
	v_and_b32_e32 v27, 0x7fffffff, v19
	v_and_b32_e32 v26, 0x7fffffff, v18
	v_pk_fma_f32 v[26:27], v[26:27], s[14:15], 1.0 op_sel_hi:[1,0,0]
	v_cmp_gt_f32_e64 s[10:11], 0, v19
	v_rcp_f32_e32 v26, v26
	v_rcp_f32_e32 v27, v27
	v_cmp_gt_f32_e32 vcc, 0, v18
	v_pk_fma_f32 v[28:29], v[26:27], s[42:43], v[28:29] op_sel_hi:[1,0,0]
	s_nop 0
	v_pk_fma_f32 v[28:29], v[26:27], v[28:29], s[0:1] op_sel_hi:[1,1,0]
	s_nop 0
	v_pk_fma_f32 v[28:29], v[26:27], v[28:29], s[50:51] op_sel_hi:[1,1,0]
	s_nop 0
	v_pk_fma_f32 v[28:29], v[26:27], v[28:29], s[34:35] op_sel_hi:[1,1,0]
	s_nop 0
	v_pk_mul_f32 v[26:27], v[26:27], v[28:29]
	v_pk_mul_f32 v[28:29], v[18:19], v[18:19]
	s_nop 0
	v_pk_mul_f32 v[28:29], v[28:29], s[46:47] op_sel_hi:[1,0]
	s_nop 0
	v_exp_f32_e32 v28, v28
	v_exp_f32_e32 v29, v29
	s_nop 0
	v_pk_mul_f32 v[26:27], v[28:29], v[26:27]
	s_nop 0
	v_pk_mul_f32 v[28:29], v[18:19], v[26:27]
	v_pk_fma_f32 v[26:27], v[18:19], v[26:27], v[18:19] neg_lo:[1,0,0] neg_hi:[1,0,0]
	s_nop 0
	v_cndmask_b32_e64 v19, v27, v29, s[10:11]
	s_cselect_b32 s10, s15, s1
	s_cselect_b32 s11, s35, s43
	s_and_b32 s12, s37, 0x180
	s_lshl_b32 s48, s12, 1
	v_lshl_add_u64 v[30:31], s[10:11], 0, v[32:33]
	v_cndmask_b32_e32 v18, v26, v28, vcc
	v_lshl_add_u64 v[30:31], v[30:31], 0, s[48:49]
	s_cmpk_lt_i32 s37, 0x200
	v_cvt_pk_bf16_f32 v26, v20, v21
	v_cvt_pk_bf16_f32 v27, v22, v23
	v_cvt_pk_bf16_f32 v28, v16, v17
	v_cvt_pk_bf16_f32 v29, v18, v19
	v_lshl_add_u64 v[30:31], v[30:31], 0, v[140:141]
	global_store_dwordx4 v[30:31], v[26:29], off
	s_cbranch_scc1 .LBB0_971
	s_nop 0
	v_mov_b32_e32 v26, v141
	v_mov_b32_e32 v27, v21
	v_pk_add_f32 v[26:27], v[20:21], v[26:27]
	v_pk_mul_f32 v[28:29], v[20:21], v[20:21]
	v_pk_mul_f32 v[30:31], v[22:23], v[22:23]
	v_mov_b32_e32 v27, v29
	v_pk_mov_b32 v[20:21], v[20:21], v[28:29] op_sel:[1,0]
	v_pk_mul_f32 v[32:33], v[16:17], v[16:17]
	v_pk_add_f32 v[20:21], v[20:21], v[26:27]
	v_mov_b32_e32 v26, v22
	v_mov_b32_e32 v27, v30
	v_pk_add_f32 v[20:21], v[26:27], v[20:21]
	v_mov_b32_e32 v30, v23
	v_and_b32_e32 v37, 64, v175
	v_pk_add_f32 v[20:21], v[30:31], v[20:21]
	v_mov_b32_e32 v22, v16
	v_mov_b32_e32 v23, v32
	v_pk_mul_f32 v[34:35], v[18:19], v[18:19]
	v_xor_b32_e32 v36, 16, v175
	v_add_u32_e32 v37, 64, v37
	v_pk_add_f32 v[20:21], v[22:23], v[20:21]
	v_mov_b32_e32 v32, v17
	v_cmp_lt_i32_e32 vcc, v36, v37
	v_pk_add_f32 v[16:17], v[32:33], v[20:21]
	v_mov_b32_e32 v20, v18
	v_mov_b32_e32 v21, v34
	v_cndmask_b32_e32 v36, v175, v36, vcc
	v_pk_add_f32 v[16:17], v[20:21], v[16:17]
	v_mov_b32_e32 v34, v19
	v_lshlrev_b32_e32 v36, 2, v36
	v_pk_add_f32 v[16:17], v[34:35], v[16:17]
	ds_bpermute_b32 v18, v36, v16
	ds_bpermute_b32 v19, v36, v17
	v_xor_b32_e32 v20, 32, v175
	v_cmp_lt_i32_e32 vcc, v20, v37
	s_waitcnt lgkmcnt(0)
	v_pk_add_f32 v[16:17], v[16:17], v[18:19]
	v_cndmask_b32_e32 v20, v175, v20, vcc
	v_lshlrev_b32_e32 v20, 2, v20
	ds_bpermute_b32 v18, v20, v16
	ds_bpermute_b32 v19, v20, v17
	s_and_saveexec_b64 s[10:11], s[2:3]
	s_cbranch_execz .LBB0_970
	s_add_i32 s12, s94, 0xfffffe80
	s_lshr_b32 s48, s12, 5
	v_lshl_add_u64 v[20:21], v[24:25], 0, s[48:49]
	v_lshl_add_u64 v[20:21], v[20:21], 3, s[80:81]
	s_waitcnt lgkmcnt(0)
	v_pk_add_f32 v[16:17], v[16:17], v[18:19]
	global_store_dwordx2 v[20:21], v[16:17], off

; DI unsigned pk2(float lo, float hi) { typedef float v2f __attribute__((ext_vector_type(2))); typedef __bf16 v2b __attribute__((ext_vector_type(2))); v2f v = {lo, hi}; v2b b = __builtin_convertvector(v, v2b); return __builtin_bit_cast(unsigned, b); }
; DI void atomic_addf(float* p, float v) { __builtin_amdgcn_global_atomic_fadd_f32((__attribute__((address_space(1))) float*)p, v); }
; DI float quad_sum(float s) { s += __shfl_xor(s, 16); s += __shfl_xor(s, 32); return s; }
;     DI void operator()(const f32x4 (&acc)[2][2][4][2], const Unit& u, int wr, int wc, int fr, int fq) const {
;     ...
;                         u32x4 w; w.x = pk2(v[0], v[1]); w.y = pk2(v[2], v[3]); w.z = pk2(v[4], v[5]); w.w = pk2(v[6], v[7]);
;                         *(u32x4*)(dst + cw) = w;
;                         float s2 = 0.f;
; #pragma unroll
;                         for (int i = 0; i < 8; ++i) s2 += v[i] * v[i];
;                         s2 = quad_sum(s2);
;                         if (fq == 0) { if (isqm) *pp = s2; else atomic_addf(pp, s2); }
.LBB0_981:
	v_cvt_pk_bf16_f32 v32, v28, v29
	v_cvt_pk_bf16_f32 v33, v14, v15
	v_cvt_pk_bf16_f32 v34, v12, v13
	v_cvt_pk_bf16_f32 v35, v10, v11
	v_lshl_add_u64 v[30:31], v[30:31], 0, v[140:141]
	global_store_dwordx4 v[30:31], v[32:35], off
	v_pk_mul_f32 v[30:31], v[28:29], v[28:29]
	v_pk_mul_f32 v[36:37], v[10:11], v[10:11]
	v_pk_mul_f32 v[32:33], v[14:15], v[14:15]
	v_add_f32_e32 v27, v30, v31
	v_add_f32_e32 v27, v32, v27
	v_pk_mul_f32 v[34:35], v[12:13], v[12:13]
	v_add_f32_e32 v27, v33, v27
	v_and_b32_e32 v31, 64, v175
	v_add_f32_e32 v27, v34, v27
	v_xor_b32_e32 v30, 16, v175
	v_add_u32_e32 v31, 64, v31
	v_add_f32_e32 v27, v35, v27
	v_cmp_lt_i32_e32 vcc, v30, v31
	v_add_f32_e32 v27, v36, v27
	v_add_f32_e32 v27, v37, v27
	v_cndmask_b32_e32 v30, v175, v30, vcc
	v_lshlrev_b32_e32 v30, 2, v30
	ds_bpermute_b32 v30, v30, v27
	s_waitcnt lgkmcnt(0)
	v_add_f32_e32 v27, v27, v30
	v_xor_b32_e32 v30, 32, v175
	v_cmp_lt_i32_e32 vcc, v30, v31
	s_nop 1
	v_cndmask_b32_e32 v30, v175, v30, vcc
	v_lshlrev_b32_e32 v30, 2, v30
	ds_bpermute_b32 v30, v30, v27
	s_and_saveexec_b64 s[8:9], s[2:3]
	s_cbranch_execz .LBB0_986
	s_waitcnt lgkmcnt(0)
	v_add_f32_e32 v27, v27, v30
	s_cmpk_gt_u32 s94, 0x67f
	s_mov_b64 s[10:11], -1
	s_cbranch_scc1 .LBB0_984
	global_atomic_add_f32 v[8:9], v27, off
	s_mov_b64 s[10:11], 0
.LBB0_984:
	s_andn2_b64 vcc, exec, s[10:11]
	s_cbranch_vccnz .LBB0_986
	global_store_dword v[8:9], v27, off

; DI unsigned pk2(float lo, float hi) { typedef float v2f __attribute__((ext_vector_type(2))); typedef __bf16 v2b __attribute__((ext_vector_type(2))); v2f v = {lo, hi}; v2b b = __builtin_convertvector(v, v2b); return __builtin_bit_cast(unsigned, b); }
; DI float quad_sum(float s) { s += __shfl_xor(s, 16); s += __shfl_xor(s, 32); return s; }
; __device__ __forceinline__ f32x2 gelu_pk(f32x2 v) {
;     const f32x2 av = __builtin_elementwise_abs(v), d = av * 0.2316418882f + 1.0f;
;     f32x2 t; t.x = __builtin_amdgcn_rcpf(d.x); t.y = __builtin_amdgcn_rcpf(d.y);
;     f32x2 q = t * 0.5307027145f + (-0.7265760135f); q = q * t + 0.7107068705f; q = q * t + (-0.142248368f); q = q * t + 0.127414796f; q = q * t;
;     const f32x2 s = (v * v) * (-0.72134752044f);
;     f32x2 e; e.x = __builtin_amdgcn_exp2f(s.x); e.y = __builtin_amdgcn_exp2f(s.y);
;     const f32x2 m = v * (q * e), r = v - m;
;     f32x2 o; o.x = v.x < 0.f ? m.x : r.x; o.y = v.y < 0.f ? m.y : r.y; return o;
;     DI void operator()(const f32x4 (&acc)[2][2][4][2], const Unit& u, int wr, int wc, int fr, int fq) const {
;     ...
;                     if (c128 < 1024) {
; #pragma unroll
;                         for (int i = 0; i < 8; i += 2) { const f32x2 g = pg8::gelu_pk((f32x2){v[i], v[i + 1]}); v[i] = g.x; v[i + 1] = g.y; }
;                         const bool isv = c128 >= 512;
;                         u32x4 w; w.x = pk2(v[0], v[1]); w.y = pk2(v[2], v[3]); w.z = pk2(v[4], v[5]); w.w = pk2(v[6], v[7]);
;                         *(u32x4*)((isv ? Vg : U) + (size_t)row * 512 + (c128 & 511) + cw) = w;
;                         if (isv) {
;                             float s1 = 0.f, s2 = 0.f;
; #pragma unroll
;                             for (int i = 0; i < 8; ++i) { s1 += v[i]; s2 += v[i] * v[i]; }
;                             s1 = quad_sum(s1); s2 = quad_sum(s2);
;                             if (fq == 0) { float* d = VST + ((size_t)row * 16 + ((c128 - 512) >> 7) * 4 + wc) * 2; d[0] = s1; d[1] = s2; }
;                         }
.LBB0_988:
	v_lshlrev_b64 v[8:9], 4, v[18:19]
	s_andn2_b64 vcc, exec, s[8:9]
	v_or_b32_e32 v8, s97, v8
	s_cbranch_vccnz .LBB0_993
	v_and_b32_e32 v31, 0x7fffffff, v29
	s_waitcnt lgkmcnt(0)
	v_and_b32_e32 v30, 0x7fffffff, v28
	v_pk_fma_f32 v[30:31], v[30:31], s[14:15], 1.0 op_sel_hi:[1,0,0]
	v_mov_b64_e32 v[32:33], s[96:97]
	v_rcp_f32_e32 v30, v30
	v_rcp_f32_e32 v31, v31
	v_cmp_gt_f32_e32 vcc, 0, v28
	v_cmp_gt_f32_e64 s[8:9], 0, v29
	s_cmp_gt_i32 s60, 1
	v_pk_fma_f32 v[34:35], v[30:31], s[42:43], v[32:33] op_sel_hi:[1,0,0]
	s_nop 0
	v_pk_fma_f32 v[34:35], v[30:31], v[34:35], s[0:1] op_sel_hi:[1,1,0]
	s_nop 0
	v_pk_fma_f32 v[34:35], v[30:31], v[34:35], s[50:51] op_sel_hi:[1,1,0]
	s_nop 0
	v_pk_fma_f32 v[34:35], v[30:31], v[34:35], s[34:35] op_sel_hi:[1,1,0]
	s_nop 0
	v_pk_mul_f32 v[30:31], v[30:31], v[34:35]
	v_pk_mul_f32 v[34:35], v[28:29], v[28:29]
	s_nop 0
	v_pk_mul_f32 v[34:35], v[34:35], s[46:47] op_sel_hi:[1,0]
	s_nop 0
	v_exp_f32_e32 v34, v34
	v_exp_f32_e32 v35, v35
	s_nop 0
	v_pk_mul_f32 v[30:31], v[34:35], v[30:31]
	s_nop 0
	v_pk_mul_f32 v[34:35], v[28:29], v[30:31]
	v_pk_fma_f32 v[30:31], v[28:29], v[30:31], v[28:29] neg_lo:[1,0,0] neg_hi:[1,0,0]
	s_nop 0
	v_cndmask_b32_e64 v29, v31, v35, s[8:9]
	v_cndmask_b32_e32 v28, v30, v34, vcc
	v_and_b32_e32 v31, 0x7fffffff, v15
	v_and_b32_e32 v30, 0x7fffffff, v14
	v_pk_fma_f32 v[30:31], v[30:31], s[14:15], 1.0 op_sel_hi:[1,0,0]
	v_cmp_gt_f32_e32 vcc, 0, v14
	v_rcp_f32_e32 v30, v30
	v_rcp_f32_e32 v31, v31
	v_cmp_gt_f32_e64 s[8:9], 0, v15
	v_pk_fma_f32 v[34:35], v[30:31], s[42:43], v[32:33] op_sel_hi:[1,0,0]
	s_nop 0
	v_pk_fma_f32 v[34:35], v[30:31], v[34:35], s[0:1] op_sel_hi:[1,1,0]
	s_nop 0
	v_pk_fma_f32 v[34:35], v[30:31], v[34:35], s[50:51] op_sel_hi:[1,1,0]
	s_nop 0
	v_pk_fma_f32 v[34:35], v[30:31], v[34:35], s[34:35] op_sel_hi:[1,1,0]
	s_nop 0
	v_pk_mul_f32 v[30:31], v[30:31], v[34:35]
	v_pk_mul_f32 v[34:35], v[14:15], v[14:15]
	s_nop 0
	v_pk_mul_f32 v[34:35], v[34:35], s[46:47] op_sel_hi:[1,0]
	s_nop 0
	v_exp_f32_e32 v34, v34
	v_exp_f32_e32 v35, v35
	s_nop 0
	v_pk_mul_f32 v[30:31], v[34:35], v[30:31]
	s_nop 0
	v_pk_mul_f32 v[34:35], v[14:15], v[30:31]
	v_pk_fma_f32 v[30:31], v[14:15], v[30:31], v[14:15] neg_lo:[1,0,0] neg_hi:[1,0,0]
	s_nop 0
	v_cndmask_b32_e64 v15, v31, v35, s[8:9]
	v_cndmask_b32_e32 v14, v30, v34, vcc
	v_and_b32_e32 v31, 0x7fffffff, v13
	v_and_b32_e32 v30, 0x7fffffff, v12
	v_pk_fma_f32 v[30:31], v[30:31], s[14:15], 1.0 op_sel_hi:[1,0,0]
	v_cmp_gt_f32_e32 vcc, 0, v12
	v_rcp_f32_e32 v30, v30
	v_rcp_f32_e32 v31, v31
	v_cmp_gt_f32_e64 s[8:9], 0, v13
	v_pk_fma_f32 v[34:35], v[30:31], s[42:43], v[32:33] op_sel_hi:[1,0,0]
	s_nop 0
	v_pk_fma_f32 v[34:35], v[30:31], v[34:35], s[0:1] op_sel_hi:[1,1,0]
	s_nop 0
	v_pk_fma_f32 v[34:35], v[30:31], v[34:35], s[50:51] op_sel_hi:[1,1,0]
	s_nop 0
	v_pk_fma_f32 v[34:35], v[30:31], v[34:35], s[34:35] op_sel_hi:[1,1,0]
	s_nop 0
	v_pk_mul_f32 v[30:31], v[30:31], v[34:35]
	v_pk_mul_f32 v[34:35], v[12:13], v[12:13]
	s_nop 0
	v_pk_mul_f32 v[34:35], v[34:35], s[46:47] op_sel_hi:[1,0]
	s_nop 0
	v_exp_f32_e32 v34, v34
	v_exp_f32_e32 v35, v35
	s_nop 0
	v_pk_mul_f32 v[30:31], v[34:35], v[30:31]
	s_nop 0
	v_pk_mul_f32 v[34:35], v[12:13], v[30:31]
	v_pk_fma_f32 v[30:31], v[12:13], v[30:31], v[12:13] neg_lo:[1,0,0] neg_hi:[1,0,0]
	s_nop 0
	v_cndmask_b32_e64 v13, v31, v35, s[8:9]
	v_cndmask_b32_e32 v12, v30, v34, vcc
	v_and_b32_e32 v31, 0x7fffffff, v11
	v_and_b32_e32 v30, 0x7fffffff, v10
	v_pk_fma_f32 v[30:31], v[30:31], s[14:15], 1.0 op_sel_hi:[1,0,0]
	v_cmp_gt_f32_e64 s[8:9], 0, v11
	v_rcp_f32_e32 v30, v30
	v_rcp_f32_e32 v31, v31
	v_cmp_gt_f32_e32 vcc, 0, v10
	v_pk_fma_f32 v[32:33], v[30:31], s[42:43], v[32:33] op_sel_hi:[1,0,0]
	s_nop 0
	v_pk_fma_f32 v[32:33], v[30:31], v[32:33], s[0:1] op_sel_hi:[1,1,0]
	s_nop 0
	v_pk_fma_f32 v[32:33], v[30:31], v[32:33], s[50:51] op_sel_hi:[1,1,0]
	s_nop 0
	v_pk_fma_f32 v[32:33], v[30:31], v[32:33], s[34:35] op_sel_hi:[1,1,0]
	s_nop 0
	v_pk_mul_f32 v[30:31], v[30:31], v[32:33]
	v_pk_mul_f32 v[32:33], v[10:11], v[10:11]
	s_nop 0
	v_pk_mul_f32 v[32:33], v[32:33], s[46:47] op_sel_hi:[1,0]
	s_nop 0
	v_exp_f32_e32 v32, v32
	v_exp_f32_e32 v33, v33
	s_nop 0
	v_pk_mul_f32 v[30:31], v[32:33], v[30:31]
	s_nop 0
	v_pk_mul_f32 v[32:33], v[10:11], v[30:31]
	v_pk_fma_f32 v[30:31], v[10:11], v[30:31], v[10:11] neg_lo:[1,0,0] neg_hi:[1,0,0]
	s_nop 0
	v_cndmask_b32_e64 v11, v31, v33, s[8:9]
	s_cselect_b32 s8, s15, s1
	s_cselect_b32 s9, s35, s43
	s_and_b32 s10, s94, 0x100
	s_lshl_b32 s48, s10, 1
	v_lshl_add_u64 v[34:35], s[8:9], 0, v[16:17]
	v_cndmask_b32_e32 v10, v30, v32, vcc
	v_lshl_add_u64 v[34:35], v[34:35], 0, s[48:49]
	s_cmp_lt_i32 s60, 2
	v_cvt_pk_bf16_f32 v30, v28, v29
	v_cvt_pk_bf16_f32 v31, v14, v15
	v_cvt_pk_bf16_f32 v32, v12, v13
	v_cvt_pk_bf16_f32 v33, v10, v11
	v_lshl_add_u64 v[34:35], v[34:35], 0, v[140:141]
	global_store_dwordx4 v[34:35], v[30:33], off
	s_cbranch_scc1 .LBB0_993
	s_nop 0
	v_mov_b32_e32 v30, v141
	v_mov_b32_e32 v31, v29
	v_pk_add_f32 v[30:31], v[28:29], v[30:31]
	v_pk_mul_f32 v[32:33], v[28:29], v[28:29]
	v_pk_mul_f32 v[34:35], v[14:15], v[14:15]
	v_mov_b32_e32 v31, v33
	v_pk_mov_b32 v[28:29], v[28:29], v[32:33] op_sel:[1,0]
	v_pk_mul_f32 v[36:37], v[12:13], v[12:13]
	v_pk_add_f32 v[28:29], v[28:29], v[30:31]
	v_mov_b32_e32 v30, v14
	v_mov_b32_e32 v31, v34
	v_pk_add_f32 v[28:29], v[30:31], v[28:29]
	v_mov_b32_e32 v34, v15
	v_and_b32_e32 v40, 64, v175
	v_pk_add_f32 v[14:15], v[34:35], v[28:29]
	v_mov_b32_e32 v28, v12
	v_mov_b32_e32 v29, v36
	v_pk_mul_f32 v[38:39], v[10:11], v[10:11]
	v_xor_b32_e32 v27, 16, v175
	v_add_u32_e32 v40, 64, v40
	v_pk_add_f32 v[14:15], v[28:29], v[14:15]
	v_mov_b32_e32 v36, v13
	v_cmp_lt_i32_e32 vcc, v27, v40
	v_pk_add_f32 v[12:13], v[36:37], v[14:15]
	v_mov_b32_e32 v14, v10
	v_mov_b32_e32 v15, v38
	v_cndmask_b32_e32 v27, v175, v27, vcc
	v_pk_add_f32 v[12:13], v[14:15], v[12:13]
	v_mov_b32_e32 v38, v11
	v_lshlrev_b32_e32 v27, 2, v27
	v_pk_add_f32 v[10:11], v[38:39], v[12:13]
	ds_bpermute_b32 v12, v27, v10
	ds_bpermute_b32 v13, v27, v11
	v_xor_b32_e32 v14, 32, v175
	v_cmp_lt_i32_e32 vcc, v14, v40
	s_waitcnt lgkmcnt(0)
	v_pk_add_f32 v[10:11], v[10:11], v[12:13]
	v_cndmask_b32_e32 v14, v175, v14, vcc
	v_lshlrev_b32_e32 v14, 2, v14
	ds_bpermute_b32 v12, v14, v10
	ds_bpermute_b32 v13, v14, v11
	s_and_saveexec_b64 s[8:9], s[2:3]
	s_cbranch_execz .LBB0_992
	s_add_i32 s10, s94, 0xfffffe00
	s_lshr_b32 s48, s10, 5
	v_lshl_add_u64 v[14:15], v[8:9], 0, s[48:49]
	v_lshl_add_u64 v[14:15], v[14:15], 3, s[80:81]
	s_waitcnt lgkmcnt(0)
	v_pk_add_f32 v[10:11], v[10:11], v[12:13]
	global_store_dwordx2 v[14:15], v[10:11], off

;     DI void operator()(const f32x4 (&acc)[2][2][4][2], const Unit& u, int wr, int wc, int fr, int fq) const {
;     ...
;                         for (int i = 0; i < 4; ++i) v[4 * n + i] = acc[ai][bj][m][n][i] * rs;
;     ...
;                     } else if (c128 == 2176) {
;                         if (wc == 0) { float* d = KR + (size_t)row * 32 + 8 * fq; *(f32x4*)d = (f32x4){v[0], v[1], v[2], v[3]}; *(f32x4*)(d + 4) = (f32x4){v[4], v[5], v[6], v[7]}; }
.LBB0_993:
	v_mov_b32_e32 v27, v26
	v_pk_mul_f32 v[4:5], v[4:5], v[26:27]
	v_pk_mul_f32 v[6:7], v[6:7], v[26:27]
	v_pk_mul_f32 v[0:1], v[0:1], v[26:27]
	v_pk_mul_f32 v[2:3], v[2:3], v[26:27]
	s_and_b64 vcc, exec, s[6:7]
	s_mov_b64 s[6:7], -1
	s_cbranch_vccnz .LBB0_1014
	s_cmpk_lt_u32 s37, 0x880
	s_cbranch_scc1 .LBB0_998
	s_cmp_lg_u32 s60, 8
	s_cselect_b64 s[6:7], -1, 0
	s_or_b64 s[6:7], s[72:73], s[6:7]
	s_and_b64 vcc, exec, s[6:7]
	s_cbranch_vccnz .LBB0_997
	v_lshlrev_b64 v[10:11], 7, v[18:19]
	v_lshl_add_u64 v[10:11], v[144:145], 0, v[10:11]
	global_store_dwordx4 v[10:11], v[4:7], off
	global_store_dwordx4 v[10:11], v[0:3], off offset:16

; DI unsigned pk2(float lo, float hi) { typedef float v2f __attribute__((ext_vector_type(2))); typedef __bf16 v2b __attribute__((ext_vector_type(2))); v2f v = {lo, hi}; v2b b = __builtin_convertvector(v, v2b); return __builtin_bit_cast(unsigned, b); }
; DI void atomic_addf(float* p, float v) { __builtin_amdgcn_global_atomic_fadd_f32((__attribute__((address_space(1))) float*)p, v); }
; DI float quad_sum(float s) { s += __shfl_xor(s, 16); s += __shfl_xor(s, 32); return s; }
;     DI void operator()(const f32x4 (&acc)[2][2][4][2], const Unit& u, int wr, int wc, int fr, int fq) const {
;     ...
;                         u32x4 w; w.x = pk2(v[0], v[1]); w.y = pk2(v[2], v[3]); w.z = pk2(v[4], v[5]); w.w = pk2(v[6], v[7]);
;                         *(u32x4*)(dst + cw) = w;
;                         float s2 = 0.f;
; #pragma unroll
;                         for (int i = 0; i < 8; ++i) s2 += v[i] * v[i];
;                         s2 = quad_sum(s2);
;                         if (fq == 0) { if (isqm) *pp = s2; else atomic_addf(pp, s2); }
.LBB0_1007:
	v_cvt_pk_bf16_f32 v18, v4, v5
	v_cvt_pk_bf16_f32 v19, v6, v7
	v_cvt_pk_bf16_f32 v20, v0, v1
	v_cvt_pk_bf16_f32 v21, v2, v3
	s_waitcnt lgkmcnt(0)
	v_lshl_add_u64 v[12:13], v[12:13], 0, v[140:141]
	global_store_dwordx4 v[12:13], v[18:21], off
	v_pk_mul_f32 v[12:13], v[4:5], v[4:5]
	v_pk_mul_f32 v[14:15], v[6:7], v[6:7]
	v_add_f32_e32 v12, v12, v13
	v_add_f32_e32 v12, v14, v12
	v_pk_mul_f32 v[18:19], v[0:1], v[0:1]
	v_add_f32_e32 v12, v15, v12
	v_and_b32_e32 v14, 64, v175
	v_add_f32_e32 v12, v18, v12
	v_xor_b32_e32 v13, 16, v175
	v_add_u32_e32 v14, 64, v14
	v_pk_mul_f32 v[20:21], v[2:3], v[2:3]
	v_add_f32_e32 v12, v19, v12
	v_cmp_lt_i32_e32 vcc, v13, v14
	v_add_f32_e32 v12, v20, v12
	v_add_f32_e32 v12, v21, v12
	v_cndmask_b32_e32 v13, v175, v13, vcc
	v_lshlrev_b32_e32 v13, 2, v13
	ds_bpermute_b32 v13, v13, v12
	s_waitcnt lgkmcnt(0)
	v_add_f32_e32 v12, v12, v13
	v_xor_b32_e32 v13, 32, v175
	v_cmp_lt_i32_e32 vcc, v13, v14
	s_nop 1
	v_cndmask_b32_e32 v13, v175, v13, vcc
	v_lshlrev_b32_e32 v13, 2, v13
	ds_bpermute_b32 v13, v13, v12
	s_and_saveexec_b64 s[6:7], s[2:3]
	s_cbranch_execz .LBB0_1012
	s_waitcnt lgkmcnt(0)
	v_add_f32_e32 v12, v12, v13
	s_cmpk_gt_u32 s37, 0x67f
	s_mov_b64 s[8:9], -1
	s_cbranch_scc1 .LBB0_1010
	global_atomic_add_f32 v[10:11], v12, off
	s_mov_b64 s[8:9], 0
.LBB0_1010:
	s_andn2_b64 vcc, exec, s[8:9]
	s_cbranch_vccnz .LBB0_1012
	global_store_dword v[10:11], v12, off

; DI unsigned pk2(float lo, float hi) { typedef float v2f __attribute__((ext_vector_type(2))); typedef __bf16 v2b __attribute__((ext_vector_type(2))); v2f v = {lo, hi}; v2b b = __builtin_convertvector(v, v2b); return __builtin_bit_cast(unsigned, b); }
; DI float quad_sum(float s) { s += __shfl_xor(s, 16); s += __shfl_xor(s, 32); return s; }
; __device__ __forceinline__ f32x2 gelu_pk(f32x2 v) {
;     const f32x2 av = __builtin_elementwise_abs(v), d = av * 0.2316418882f + 1.0f;
;     f32x2 t; t.x = __builtin_amdgcn_rcpf(d.x); t.y = __builtin_amdgcn_rcpf(d.y);
;     f32x2 q = t * 0.5307027145f + (-0.7265760135f); q = q * t + 0.7107068705f; q = q * t + (-0.142248368f); q = q * t + 0.127414796f; q = q * t;
;     const f32x2 s = (v * v) * (-0.72134752044f);
;     f32x2 e; e.x = __builtin_amdgcn_exp2f(s.x); e.y = __builtin_amdgcn_exp2f(s.y);
;     const f32x2 m = v * (q * e), r = v - m;
;     f32x2 o; o.x = v.x < 0.f ? m.x : r.x; o.y = v.y < 0.f ? m.y : r.y; return o;
;     DI void operator()(const f32x4 (&acc)[2][2][4][2], const Unit& u, int wr, int wc, int fr, int fq) const {
;     ...
;                     if (c128 < 1024) {
; #pragma unroll
;                         for (int i = 0; i < 8; i += 2) { const f32x2 g = pg8::gelu_pk((f32x2){v[i], v[i + 1]}); v[i] = g.x; v[i + 1] = g.y; }
;                         const bool isv = c128 >= 512;
;                         u32x4 w; w.x = pk2(v[0], v[1]); w.y = pk2(v[2], v[3]); w.z = pk2(v[4], v[5]); w.w = pk2(v[6], v[7]);
;                         *(u32x4*)((isv ? Vg : U) + (size_t)row * 512 + (c128 & 511) + cw) = w;
;                         if (isv) {
;                             float s1 = 0.f, s2 = 0.f;
; #pragma unroll
;                             for (int i = 0; i < 8; ++i) { s1 += v[i]; s2 += v[i] * v[i]; }
;                             s1 = quad_sum(s1); s2 = quad_sum(s2);
;                             if (fq == 0) { float* d = VST + ((size_t)row * 16 + ((c128 - 512) >> 7) * 4 + wc) * 2; d[0] = s1; d[1] = s2; }
;                         }
.LBB0_1014:
	s_andn2_b64 vcc, exec, s[6:7]
	s_cbranch_vccnz .LBB0_1019
	v_and_b32_e32 v11, 0x7fffffff, v5
	v_and_b32_e32 v10, 0x7fffffff, v4
	v_pk_fma_f32 v[10:11], v[10:11], s[14:15], 1.0 op_sel_hi:[1,0,0]
	s_waitcnt lgkmcnt(0)
	v_mov_b64_e32 v[12:13], s[96:97]
	v_rcp_f32_e32 v10, v10
	v_rcp_f32_e32 v11, v11
	v_pk_mul_f32 v[18:19], v[4:5], v[4:5]
	v_cmp_gt_f32_e32 vcc, 0, v5
	v_pk_mul_f32 v[18:19], v[18:19], s[46:47] op_sel_hi:[1,0]
	v_pk_fma_f32 v[14:15], v[10:11], s[42:43], v[12:13] op_sel_hi:[1,0,0]
	v_exp_f32_e32 v18, v18
	v_pk_fma_f32 v[14:15], v[10:11], v[14:15], s[0:1] op_sel_hi:[1,1,0]
	v_exp_f32_e32 v19, v19
	v_pk_fma_f32 v[14:15], v[10:11], v[14:15], s[50:51] op_sel_hi:[1,1,0]
	s_cmpk_gt_i32 s37, 0x1ff
	v_pk_fma_f32 v[14:15], v[10:11], v[14:15], s[34:35] op_sel_hi:[1,1,0]
	s_cselect_b32 s6, s15, s1
	v_pk_mul_f32 v[10:11], v[10:11], v[14:15]
	s_cselect_b32 s7, s35, s43
	v_pk_mul_f32 v[10:11], v[18:19], v[10:11]
	v_and_b32_e32 v19, 0x7fffffff, v7
	v_and_b32_e32 v18, 0x7fffffff, v6
	v_pk_fma_f32 v[18:19], v[18:19], s[14:15], 1.0 op_sel_hi:[1,0,0]
	v_pk_mul_f32 v[14:15], v[4:5], v[10:11]
	v_rcp_f32_e32 v18, v18
	v_rcp_f32_e32 v19, v19
	v_pk_fma_f32 v[10:11], v[4:5], v[10:11], v[4:5] neg_lo:[1,0,0] neg_hi:[1,0,0]
	s_and_b32 s8, s37, 0x180
	v_cndmask_b32_e32 v5, v11, v15, vcc
	v_cmp_gt_f32_e32 vcc, 0, v4
	s_lshl_b32 s48, s8, 1
	s_cmpk_lt_i32 s37, 0x200
	v_cndmask_b32_e32 v4, v10, v14, vcc
	v_pk_fma_f32 v[10:11], v[18:19], s[42:43], v[12:13] op_sel_hi:[1,0,0]
	v_pk_mul_f32 v[14:15], v[6:7], v[6:7]
	v_pk_fma_f32 v[10:11], v[18:19], v[10:11], s[0:1] op_sel_hi:[1,1,0]
	v_pk_mul_f32 v[14:15], v[14:15], s[46:47] op_sel_hi:[1,0]
	v_pk_fma_f32 v[10:11], v[18:19], v[10:11], s[50:51] op_sel_hi:[1,1,0]
	v_exp_f32_e32 v14, v14
	v_exp_f32_e32 v15, v15
	v_pk_fma_f32 v[10:11], v[18:19], v[10:11], s[34:35] op_sel_hi:[1,1,0]
	v_cmp_gt_f32_e32 vcc, 0, v7
	v_pk_mul_f32 v[10:11], v[18:19], v[10:11]
	v_and_b32_e32 v19, 0x7fffffff, v1
	v_and_b32_e32 v18, 0x7fffffff, v0
	v_pk_fma_f32 v[18:19], v[18:19], s[14:15], 1.0 op_sel_hi:[1,0,0]
	v_pk_mul_f32 v[10:11], v[14:15], v[10:11]
	v_rcp_f32_e32 v18, v18
	v_rcp_f32_e32 v19, v19
	v_pk_mul_f32 v[14:15], v[6:7], v[10:11]
	v_pk_fma_f32 v[10:11], v[6:7], v[10:11], v[6:7] neg_lo:[1,0,0] neg_hi:[1,0,0]
	s_nop 0
	v_cndmask_b32_e32 v7, v11, v15, vcc
	v_cmp_gt_f32_e32 vcc, 0, v6
	s_nop 1
	v_cndmask_b32_e32 v6, v10, v14, vcc
	v_pk_fma_f32 v[10:11], v[18:19], s[42:43], v[12:13] op_sel_hi:[1,0,0]
	v_pk_mul_f32 v[14:15], v[0:1], v[0:1]
	v_pk_fma_f32 v[10:11], v[18:19], v[10:11], s[0:1] op_sel_hi:[1,1,0]
	v_pk_mul_f32 v[14:15], v[14:15], s[46:47] op_sel_hi:[1,0]
	v_pk_fma_f32 v[10:11], v[18:19], v[10:11], s[50:51] op_sel_hi:[1,1,0]
	v_exp_f32_e32 v14, v14
	v_exp_f32_e32 v15, v15
	v_pk_fma_f32 v[10:11], v[18:19], v[10:11], s[34:35] op_sel_hi:[1,1,0]
	v_cmp_gt_f32_e32 vcc, 0, v1
	v_pk_mul_f32 v[10:11], v[18:19], v[10:11]
	v_and_b32_e32 v19, 0x7fffffff, v3
	v_and_b32_e32 v18, 0x7fffffff, v2
	v_pk_fma_f32 v[18:19], v[18:19], s[14:15], 1.0 op_sel_hi:[1,0,0]
	v_pk_mul_f32 v[10:11], v[14:15], v[10:11]
	v_rcp_f32_e32 v18, v18
	v_rcp_f32_e32 v19, v19
	v_pk_mul_f32 v[14:15], v[0:1], v[10:11]
	v_pk_fma_f32 v[10:11], v[0:1], v[10:11], v[0:1] neg_lo:[1,0,0] neg_hi:[1,0,0]
	s_nop 0
	v_cndmask_b32_e32 v1, v11, v15, vcc
	v_cmp_gt_f32_e32 vcc, 0, v0
	s_nop 1
	v_cndmask_b32_e32 v0, v10, v14, vcc
	v_pk_fma_f32 v[10:11], v[18:19], s[42:43], v[12:13] op_sel_hi:[1,0,0]
	v_pk_mul_f32 v[12:13], v[2:3], v[2:3]
	v_pk_fma_f32 v[10:11], v[18:19], v[10:11], s[0:1] op_sel_hi:[1,1,0]
	v_pk_mul_f32 v[12:13], v[12:13], s[46:47] op_sel_hi:[1,0]
	v_pk_fma_f32 v[10:11], v[18:19], v[10:11], s[50:51] op_sel_hi:[1,1,0]
	v_exp_f32_e32 v12, v12
	v_exp_f32_e32 v13, v13
	v_pk_fma_f32 v[10:11], v[18:19], v[10:11], s[34:35] op_sel_hi:[1,1,0]
	v_cmp_gt_f32_e32 vcc, 0, v3
	v_pk_mul_f32 v[10:11], v[18:19], v[10:11]
	v_lshl_add_u64 v[14:15], s[6:7], 0, v[16:17]
	v_pk_mul_f32 v[10:11], v[12:13], v[10:11]
	v_lshl_add_u64 v[14:15], v[14:15], 0, s[48:49]
	v_pk_mul_f32 v[12:13], v[2:3], v[10:11]
	v_pk_fma_f32 v[10:11], v[2:3], v[10:11], v[2:3] neg_lo:[1,0,0] neg_hi:[1,0,0]
	v_lshl_add_u64 v[14:15], v[14:15], 0, v[140:141]
	v_cndmask_b32_e32 v3, v11, v13, vcc
	v_cmp_gt_f32_e32 vcc, 0, v2
	v_cvt_pk_bf16_f32 v11, v6, v7
	s_nop 0
	v_cndmask_b32_e32 v2, v10, v12, vcc
	v_cvt_pk_bf16_f32 v10, v4, v5
	v_cvt_pk_bf16_f32 v12, v0, v1
	v_cvt_pk_bf16_f32 v13, v2, v3
	global_store_dwordx4 v[14:15], v[10:13], off
	s_cbranch_scc1 .LBB0_1019
	s_nop 0
	v_mov_b32_e32 v10, v141
	v_mov_b32_e32 v11, v5
	v_pk_add_f32 v[10:11], v[4:5], v[10:11]
	v_pk_mul_f32 v[12:13], v[4:5], v[4:5]
	v_pk_mul_f32 v[14:15], v[6:7], v[6:7]
	v_mov_b32_e32 v11, v13
	v_pk_mov_b32 v[4:5], v[4:5], v[12:13] op_sel:[1,0]
	v_pk_mul_f32 v[16:17], v[0:1], v[0:1]
	v_pk_add_f32 v[4:5], v[4:5], v[10:11]
	v_mov_b32_e32 v10, v6
	v_mov_b32_e32 v11, v14
	v_pk_add_f32 v[4:5], v[10:11], v[4:5]
	v_mov_b32_e32 v14, v7
	v_and_b32_e32 v21, 64, v175
	v_pk_add_f32 v[4:5], v[14:15], v[4:5]
	v_mov_b32_e32 v6, v0
	v_mov_b32_e32 v7, v16
	v_pk_mul_f32 v[18:19], v[2:3], v[2:3]
	v_xor_b32_e32 v20, 16, v175
	v_add_u32_e32 v21, 64, v21
	v_pk_add_f32 v[4:5], v[6:7], v[4:5]
	v_mov_b32_e32 v16, v1
	v_cmp_lt_i32_e32 vcc, v20, v21
	v_pk_add_f32 v[0:1], v[16:17], v[4:5]
	v_mov_b32_e32 v4, v2
	v_mov_b32_e32 v5, v18
	v_cndmask_b32_e32 v20, v175, v20, vcc
	v_pk_add_f32 v[0:1], v[4:5], v[0:1]
	v_mov_b32_e32 v18, v3
	v_lshlrev_b32_e32 v20, 2, v20
	v_pk_add_f32 v[0:1], v[18:19], v[0:1]
	ds_bpermute_b32 v2, v20, v0
	ds_bpermute_b32 v3, v20, v1
	v_xor_b32_e32 v4, 32, v175
	v_cmp_lt_i32_e32 vcc, v4, v21
	s_waitcnt lgkmcnt(0)
	v_pk_add_f32 v[0:1], v[0:1], v[2:3]
	v_cndmask_b32_e32 v4, v175, v4, vcc
	v_lshlrev_b32_e32 v4, 2, v4
	ds_bpermute_b32 v2, v4, v0
	ds_bpermute_b32 v3, v4, v1
	s_and_saveexec_b64 s[6:7], s[2:3]
	s_cbranch_execz .LBB0_1018
	s_add_i32 s8, s94, 0xfffffe80
	s_lshr_b32 s48, s8, 5
	v_lshl_add_u64 v[4:5], v[8:9], 0, s[48:49]
	v_lshl_add_u64 v[4:5], v[4:5], 3, s[80:81]
	s_waitcnt lgkmcnt(0)
	v_pk_add_f32 v[0:1], v[0:1], v[2:3]
	global_store_dwordx2 v[4:5], v[0:1], off

; #define LAS __attribute__((address_space(3)))
; DI unsigned pk2(float lo, float hi) { typedef float v2f __attribute__((ext_vector_type(2))); typedef __bf16 v2b __attribute__((ext_vector_type(2))); v2f v = {lo, hi}; v2b b = __builtin_convertvector(v, v2b); return __builtin_bit_cast(unsigned, b); }
;     ...
;         bf16_t* dst = dest_rows(mode, n0, K, d0, d1);
;         const int c = lane & 7;
; #pragma unroll
;         for (int jj = 0; jj < 4; ++jj) { const int n = (lane >> 3) + 8 * jj; const LAS float* s = scr + (8 * c) * 33 + n;
;             u32x4 o; o.x = pk2(s[0 * 33], s[1 * 33]); o.y = pk2(s[2 * 33], s[3 * 33]); o.z = pk2(s[4 * 33], s[5 * 33]); o.w = pk2(s[6 * 33], s[7 * 33]);
;             *(u32x4*)(dst + (size_t)n * K + k0 + 8 * c) = o; }
;         asm volatile("s_waitcnt lgkmcnt(0)" ::: "memory");
.LBB0_1026:
	s_ashr_i32 s7, s6, 31
	ds_read_b32 v5, v34
	ds_read_b32 v7, v34 offset:132
	ds_read_b32 v9, v34 offset:264
	ds_read_b32 v11, v34 offset:396
	ds_read_b32 v13, v34 offset:528
	ds_read_b32 v18, v34 offset:660
	ds_read_b32 v19, v34 offset:792
	ds_read_b32 v22, v34 offset:924
	s_lshl_b64 s[6:7], s[6:7], 1
	s_add_u32 s2, s2, s6
	s_addc_u32 s3, s3, s7
	v_lshl_add_u64 v[20:21], s[2:3], 0, v[2:3]
	s_waitcnt lgkmcnt(0)
	v_cvt_pk_bf16_f32 v16, v5, v7
	v_mov_b32_e32 v7, v3
	s_waitcnt lgkmcnt(4)
	v_cvt_pk_bf16_f32 v17, v9, v11
	s_waitcnt lgkmcnt(2)
	v_cvt_pk_bf16_f32 v18, v13, v18
	s_waitcnt lgkmcnt(0)
	v_cvt_pk_bf16_f32 v19, v19, v22
	v_lshl_add_u64 v[22:23], v[20:21], 0, v[6:7]
	global_store_dwordx4 v[22:23], v[16:19], off
	ds_read_b32 v5, v34 offset:32
	ds_read_b32 v7, v34 offset:164
	ds_read_b32 v9, v34 offset:296
	ds_read_b32 v11, v34 offset:428
	ds_read_b32 v13, v34 offset:560
	ds_read_b32 v18, v34 offset:692
	ds_read_b32 v19, v34 offset:824
	ds_read_b32 v22, v34 offset:956
	s_waitcnt lgkmcnt(0)
	v_cvt_pk_bf16_f32 v17, v9, v11
	v_mov_b32_e32 v9, v3
	v_cvt_pk_bf16_f32 v16, v5, v7
	v_cvt_pk_bf16_f32 v18, v13, v18
	v_cvt_pk_bf16_f32 v19, v19, v22
	v_lshl_add_u64 v[22:23], v[20:21], 0, v[8:9]
	global_store_dwordx4 v[22:23], v[16:19], off
	ds_read_b32 v5, v34 offset:64
	ds_read_b32 v7, v34 offset:196
	ds_read_b32 v9, v34 offset:328
	ds_read_b32 v11, v34 offset:460
	ds_read_b32 v13, v34 offset:592
	ds_read_b32 v18, v34 offset:724
	ds_read_b32 v19, v34 offset:856
	ds_read_b32 v22, v34 offset:988
	s_waitcnt lgkmcnt(0)
	v_cvt_pk_bf16_f32 v17, v9, v11
	v_mov_b32_e32 v11, v3
	v_cvt_pk_bf16_f32 v16, v5, v7
	v_cvt_pk_bf16_f32 v18, v13, v18
	v_cvt_pk_bf16_f32 v19, v19, v22
	v_lshl_add_u64 v[22:23], v[20:21], 0, v[10:11]
	global_store_dwordx4 v[22:23], v[16:19], off
	ds_read_b32 v5, v34 offset:96
	ds_read_b32 v7, v34 offset:228
	ds_read_b32 v9, v34 offset:360
	ds_read_b32 v11, v34 offset:492
	ds_read_b32 v13, v34 offset:624
	ds_read_b32 v18, v34 offset:756
	ds_read_b32 v19, v34 offset:888
	ds_read_b32 v22, v34 offset:1020
	s_waitcnt lgkmcnt(0)
	v_cvt_pk_bf16_f32 v16, v5, v7
	v_cvt_pk_bf16_f32 v17, v9, v11
	v_cvt_pk_bf16_f32 v18, v13, v18
	v_mov_b32_e32 v13, v3
	v_cvt_pk_bf16_f32 v19, v19, v22
	v_lshl_add_u64 v[20:21], v[20:21], 0, v[12:13]
	global_store_dwordx4 v[20:21], v[16:19], off
	s_waitcnt lgkmcnt(0)
	s_add_i32 s0, s52, 0x600
	s_add_i32 s33, s33, 0xc000
	s_add_i32 s34, s34, 0x3000000
	s_cmp_gt_i32 s52, -1
	s_mov_b32 s52, s0
	s_cbranch_scc1 .LBB0_1071

;     ...
;         const int kb = item / nblk, nb = nb0 + item % nblk, k0 = 64 * kb, n0 = 32 * nb;
;         float tv[32];
; #pragma unroll
;         for (int i = 0; i < 32; ++i) { const int kk = 2 * i + (lane >> 5); tv[i] = W[(size_t)(k0 + kk) * N + n0 + (lane & 31)]; }
.LBB0_1073:
	s_ashr_i32 s0, s8, 31
	s_lshr_b32 s0, s0, 27
	s_add_i32 s0, s8, s0
	s_ashr_i32 s1, s0, 5
	s_lshl_b32 s0, s1, 6
	s_lshl_b32 s1, s1, 10
	v_or_b32_e32 v26, s0, v0
	s_sub_i32 s2, s7, s1
	v_or_b32_e32 v28, 2, v26
	v_or_b32_e32 v54, 12, v26
	v_or_b32_e32 v56, 14, v26
	v_or_b32_e32 v58, 16, v26
	v_or_b32_e32 v60, 18, v26
	v_or_b32_e32 v62, 20, v26
	v_or_b32_e32 v64, 22, v26
	v_or_b32_e32 v66, 24, v26
	v_or_b32_e32 v68, 26, v26
	v_or_b32_e32 v70, 28, v26
	v_or_b32_e32 v72, 30, v26
	v_or_b32_e32 v74, 32, v26
	v_or_b32_e32 v76, 34, v26
	v_or_b32_e32 v78, 36, v26
	s_ashr_i32 s3, s2, 31
	v_ashrrev_i32_e32 v27, 31, v26
	v_or_b32_e32 v30, 4, v26
	v_or_b32_e32 v32, 6, v26
	v_or_b32_e32 v50, 8, v26
	v_or_b32_e32 v52, 10, v26
	v_or_b32_e32 v80, 38, v26
	v_or_b32_e32 v82, 40, v26
	v_or_b32_e32 v84, 42, v26
	v_or_b32_e32 v86, 44, v26
	v_or_b32_e32 v88, 46, v26
	v_or_b32_e32 v90, 48, v26
	v_or_b32_e32 v92, 50, v26
	v_or_b32_e32 v94, 52, v26
	v_or_b32_e32 v96, 54, v26
	v_or_b32_e32 v98, 56, v26
	v_or_b32_e32 v100, 58, v26
	v_or_b32_e32 v102, 60, v26
	v_or_b32_e32 v104, 62, v26
	v_ashrrev_i32_e32 v29, 31, v28
	v_ashrrev_i32_e32 v55, 31, v54
	v_ashrrev_i32_e32 v57, 31, v56
	v_ashrrev_i32_e32 v59, 31, v58
	v_ashrrev_i32_e32 v61, 31, v60
	v_ashrrev_i32_e32 v63, 31, v62
	v_ashrrev_i32_e32 v65, 31, v64
	v_ashrrev_i32_e32 v67, 31, v66
	v_ashrrev_i32_e32 v69, 31, v68
	v_ashrrev_i32_e32 v71, 31, v70
	v_ashrrev_i32_e32 v73, 31, v72
	v_ashrrev_i32_e32 v75, 31, v74
	v_ashrrev_i32_e32 v77, 31, v76
	v_ashrrev_i32_e32 v79, 31, v78
	v_lshl_add_u64 v[106:107], s[2:3], 2, v[22:23]
	v_lshlrev_b64 v[26:27], 12, v[26:27]
	v_ashrrev_i32_e32 v31, 31, v30
	v_ashrrev_i32_e32 v33, 31, v32
	v_ashrrev_i32_e32 v51, 31, v50
	v_ashrrev_i32_e32 v53, 31, v52
	v_ashrrev_i32_e32 v81, 31, v80
	v_ashrrev_i32_e32 v83, 31, v82
	v_ashrrev_i32_e32 v85, 31, v84
	v_ashrrev_i32_e32 v87, 31, v86
	v_ashrrev_i32_e32 v89, 31, v88
	v_ashrrev_i32_e32 v91, 31, v90
	v_ashrrev_i32_e32 v93, 31, v92
	v_ashrrev_i32_e32 v95, 31, v94
	v_ashrrev_i32_e32 v97, 31, v96
	v_ashrrev_i32_e32 v99, 31, v98
	v_ashrrev_i32_e32 v101, 31, v100
	v_ashrrev_i32_e32 v103, 31, v102
	v_ashrrev_i32_e32 v105, 31, v104
	v_lshlrev_b64 v[28:29], 12, v[28:29]
	v_lshlrev_b64 v[54:55], 12, v[54:55]
	v_lshlrev_b64 v[56:57], 12, v[56:57]
	v_lshlrev_b64 v[58:59], 12, v[58:59]
	v_lshlrev_b64 v[60:61], 12, v[60:61]
	v_lshlrev_b64 v[62:63], 12, v[62:63]
	v_lshlrev_b64 v[64:65], 12, v[64:65]
	v_lshlrev_b64 v[66:67], 12, v[66:67]
	v_lshlrev_b64 v[68:69], 12, v[68:69]
	v_lshlrev_b64 v[70:71], 12, v[70:71]
	v_lshlrev_b64 v[72:73], 12, v[72:73]
	v_lshlrev_b64 v[74:75], 12, v[74:75]
	v_lshlrev_b64 v[76:77], 12, v[76:77]
	v_lshlrev_b64 v[78:79], 12, v[78:79]
	v_lshl_add_u64 v[26:27], v[106:107], 0, v[26:27]
	v_lshlrev_b64 v[30:31], 12, v[30:31]
	v_lshlrev_b64 v[32:33], 12, v[32:33]
	v_lshlrev_b64 v[50:51], 12, v[50:51]
	v_lshlrev_b64 v[52:53], 12, v[52:53]
	v_lshlrev_b64 v[80:81], 12, v[80:81]
	v_lshlrev_b64 v[82:83], 12, v[82:83]
	v_lshlrev_b64 v[84:85], 12, v[84:85]
	v_lshlrev_b64 v[86:87], 12, v[86:87]
	v_lshlrev_b64 v[88:89], 12, v[88:89]
	v_lshlrev_b64 v[90:91], 12, v[90:91]
	v_lshlrev_b64 v[92:93], 12, v[92:93]
	v_lshlrev_b64 v[94:95], 12, v[94:95]
	v_lshlrev_b64 v[96:97], 12, v[96:97]
	v_lshlrev_b64 v[98:99], 12, v[98:99]
	v_lshlrev_b64 v[100:101], 12, v[100:101]
	v_lshlrev_b64 v[102:103], 12, v[102:103]
	v_lshlrev_b64 v[104:105], 12, v[104:105]
	v_lshl_add_u64 v[28:29], v[106:107], 0, v[28:29]
	v_lshl_add_u64 v[54:55], v[106:107], 0, v[54:55]
	v_lshl_add_u64 v[56:57], v[106:107], 0, v[56:57]
	v_lshl_add_u64 v[58:59], v[106:107], 0, v[58:59]
	v_lshl_add_u64 v[60:61], v[106:107], 0, v[60:61]
	v_lshl_add_u64 v[62:63], v[106:107], 0, v[62:63]
	v_lshl_add_u64 v[64:65], v[106:107], 0, v[64:65]
	v_lshl_add_u64 v[66:67], v[106:107], 0, v[66:67]
	v_lshl_add_u64 v[68:69], v[106:107], 0, v[68:69]
	v_lshl_add_u64 v[70:71], v[106:107], 0, v[70:71]
	v_lshl_add_u64 v[72:73], v[106:107], 0, v[72:73]
	v_lshl_add_u64 v[74:75], v[106:107], 0, v[74:75]
	v_lshl_add_u64 v[76:77], v[106:107], 0, v[76:77]
	v_lshl_add_u64 v[78:79], v[106:107], 0, v[78:79]
	v_lshl_add_u64 v[30:31], v[106:107], 0, v[30:31]
	v_lshl_add_u64 v[32:33], v[106:107], 0, v[32:33]
	v_lshl_add_u64 v[50:51], v[106:107], 0, v[50:51]
	v_lshl_add_u64 v[52:53], v[106:107], 0, v[52:53]
	v_lshl_add_u64 v[80:81], v[106:107], 0, v[80:81]
	v_lshl_add_u64 v[82:83], v[106:107], 0, v[82:83]
	v_lshl_add_u64 v[84:85], v[106:107], 0, v[84:85]
	v_lshl_add_u64 v[86:87], v[106:107], 0, v[86:87]
	v_lshl_add_u64 v[88:89], v[106:107], 0, v[88:89]
	v_lshl_add_u64 v[90:91], v[106:107], 0, v[90:91]
	v_lshl_add_u64 v[92:93], v[106:107], 0, v[92:93]
	v_lshl_add_u64 v[94:95], v[106:107], 0, v[94:95]
	v_lshl_add_u64 v[96:97], v[106:107], 0, v[96:97]
	v_lshl_add_u64 v[98:99], v[106:107], 0, v[98:99]
	v_lshl_add_u64 v[100:101], v[106:107], 0, v[100:101]
	v_lshl_add_u64 v[102:103], v[106:107], 0, v[102:103]
	v_lshl_add_u64 v[104:105], v[106:107], 0, v[104:105]
	global_load_dword v25, v[26:27], off
	s_nop 0
	global_load_dword v26, v[28:29], off
	global_load_dword v27, v[30:31], off
	s_nop 0
	global_load_dword v28, v[32:33], off
	global_load_dword v29, v[50:51], off
	global_load_dword v49, v[52:53], off
	s_nop 0
	global_load_dword v54, v[54:55], off
	s_nop 0
	global_load_dword v55, v[56:57], off
	s_nop 0
	global_load_dword v56, v[58:59], off
	global_load_dword v57, v[60:61], off
	s_nop 0
	global_load_dword v58, v[62:63], off
	global_load_dword v59, v[64:65], off
	global_load_dword v60, v[66:67], off
	global_load_dword v61, v[68:69], off
	s_nop 0
	global_load_dword v62, v[70:71], off
	global_load_dword v63, v[72:73], off
	global_load_dword v64, v[74:75], off
	global_load_dword v65, v[76:77], off
	global_load_dword v66, v[78:79], off
	global_load_dword v67, v[80:81], off
	global_load_dword v68, v[82:83], off
	global_load_dword v69, v[84:85], off
	global_load_dword v70, v[86:87], off
	global_load_dword v71, v[88:89], off
	global_load_dword v72, v[90:91], off
	global_load_dword v73, v[92:93], off
	global_load_dword v74, v[94:95], off
	global_load_dword v75, v[96:97], off
	global_load_dword v76, v[98:99], off
	global_load_dword v77, v[100:101], off
	global_load_dword v78, v[102:103], off
	global_load_dword v79, v[104:105], off
	s_lshl_b64 s[2:3], s[2:3], 10
	s_waitcnt vmcnt(0)
; #define LAS __attribute__((address_space(3)))
; DI unsigned pk2(float lo, float hi) { typedef float v2f __attribute__((ext_vector_type(2))); typedef __bf16 v2b __attribute__((ext_vector_type(2))); v2f v = {lo, hi}; v2b b = __builtin_convertvector(v, v2b); return __builtin_bit_cast(unsigned, b); }
;     ...
;         const int kb = item / nblk, nb = nb0 + item % nblk, k0 = 64 * kb, n0 = 32 * nb;
;         float tv[32];
; #pragma unroll
;         for (int i = 0; i < 32; ++i) { const int kk = 2 * i + (lane >> 5); tv[i] = W[(size_t)(k0 + kk) * N + n0 + (lane & 31)]; }
;     ...
;         for (int i = 0; i < 32; ++i) { const int kk = 2 * i + (lane >> 5); float v = tv[i]; if (gk) v *= gk[k0 + kk]; scr[kk * 33 + (lane & 31)] = v; }
;         asm volatile("s_waitcnt lgkmcnt(0)" ::: "memory");
;         bf16_t* dst = dest_rows(mode, n0, K, d0, d1);
;         const int c = lane & 7;
; #pragma unroll
;         for (int jj = 0; jj < 4; ++jj) { const int n = (lane >> 3) + 8 * jj; const LAS float* s = scr + (8 * c) * 33 + n;
;             u32x4 o; o.x = pk2(s[0 * 33], s[1 * 33]); o.y = pk2(s[2 * 33], s[3 * 33]); o.z = pk2(s[4 * 33], s[5 * 33]); o.w = pk2(s[6 * 33], s[7 * 33]);
;             *(u32x4*)(dst + (size_t)n * K + k0 + 8 * c) = o; }
;         asm volatile("s_waitcnt lgkmcnt(0)" ::: "memory");
	ds_write2_b32 v35, v25, v26 offset1:66
	ds_write2_b32 v35, v27, v28 offset0:132 offset1:198
	ds_write2_b32 v1, v29, v49 offset0:8 offset1:74
	ds_write2_b32 v1, v54, v55 offset0:140 offset1:206
	ds_write2_b32 v5, v56, v57 offset0:16 offset1:82
	ds_write2_b32 v5, v58, v59 offset0:148 offset1:214
	ds_write2_b32 v7, v60, v61 offset0:24 offset1:90
	ds_write2_b32 v7, v62, v63 offset0:156 offset1:222
	ds_write2_b32 v9, v64, v65 offset0:32 offset1:98
	ds_write2_b32 v9, v66, v67 offset0:164 offset1:230
	ds_write2_b32 v11, v68, v69 offset0:40 offset1:106
	ds_write2_b32 v11, v70, v71 offset0:172 offset1:238
	ds_write2_b32 v13, v72, v73 offset0:48 offset1:114
	ds_write2_b32 v13, v74, v75 offset0:180 offset1:246
	ds_write2_b32 v24, v76, v77 offset0:56 offset1:122
	ds_write2_b32 v24, v78, v79 offset0:188 offset1:254
	s_add_u32 s2, s5, s2
	s_waitcnt lgkmcnt(0)
	s_addc_u32 s3, s6, s3
	s_ashr_i32 s1, s0, 31
	ds_read_b32 v25, v34
	ds_read_b32 v26, v34 offset:132
	ds_read_b32 v27, v34 offset:264
	ds_read_b32 v28, v34 offset:396
	ds_read_b32 v29, v34 offset:528
	ds_read_b32 v49, v34 offset:660
	ds_read_b32 v54, v34 offset:792
	ds_read_b32 v55, v34 offset:924
	s_lshl_b64 s[0:1], s[0:1], 1
	s_add_u32 s0, s2, s0
	s_addc_u32 s1, s3, s1
	v_lshl_add_u64 v[30:31], s[0:1], 0, v[2:3]
	v_lshl_add_u64 v[32:33], v[30:31], 0, v[14:15]
	s_waitcnt lgkmcnt(0)
	v_cvt_pk_bf16_f32 v26, v25, v26
	v_cvt_pk_bf16_f32 v27, v27, v28
	v_cvt_pk_bf16_f32 v28, v29, v49
	v_cvt_pk_bf16_f32 v29, v54, v55
	global_store_dwordx4 v[32:33], v[26:29], off
	ds_read_b32 v25, v34 offset:32
	ds_read_b32 v26, v34 offset:164
	ds_read_b32 v27, v34 offset:296
	ds_read_b32 v28, v34 offset:428
	ds_read_b32 v29, v34 offset:560
	ds_read_b32 v32, v34 offset:692
	ds_read_b32 v33, v34 offset:824
	ds_read_b32 v49, v34 offset:956
	v_lshl_add_u64 v[50:51], v[30:31], 0, v[16:17]
	s_waitcnt lgkmcnt(0)
	v_cvt_pk_bf16_f32 v26, v25, v26
	v_cvt_pk_bf16_f32 v27, v27, v28
	v_cvt_pk_bf16_f32 v28, v29, v32
	v_cvt_pk_bf16_f32 v29, v33, v49
	global_store_dwordx4 v[50:51], v[26:29], off
	ds_read_b32 v25, v34 offset:64
	ds_read_b32 v26, v34 offset:196
	ds_read_b32 v27, v34 offset:328
	ds_read_b32 v28, v34 offset:460
	ds_read_b32 v29, v34 offset:592
	ds_read_b32 v32, v34 offset:724
	ds_read_b32 v33, v34 offset:856
	ds_read_b32 v49, v34 offset:988
	v_lshl_add_u64 v[52:53], v[30:31], 0, v[18:19]
	s_waitcnt lgkmcnt(0)
	v_cvt_pk_bf16_f32 v26, v25, v26
	v_cvt_pk_bf16_f32 v27, v27, v28
	v_cvt_pk_bf16_f32 v28, v29, v32
	v_cvt_pk_bf16_f32 v29, v33, v49
	global_store_dwordx4 v[52:53], v[26:29], off
	ds_read_b32 v25, v34 offset:96
	ds_read_b32 v26, v34 offset:228
	ds_read_b32 v27, v34 offset:360
	ds_read_b32 v28, v34 offset:492
	ds_read_b32 v29, v34 offset:624
	ds_read_b32 v32, v34 offset:756
	ds_read_b32 v33, v34 offset:888
	ds_read_b32 v49, v34 offset:1020
	v_lshl_add_u64 v[30:31], v[30:31], 0, v[20:21]
	s_waitcnt lgkmcnt(0)
	v_cvt_pk_bf16_f32 v26, v25, v26
	v_cvt_pk_bf16_f32 v27, v27, v28
	v_cvt_pk_bf16_f32 v28, v29, v32
	v_cvt_pk_bf16_f32 v29, v33, v49
	global_store_dwordx4 v[30:31], v[26:29], off
	s_waitcnt lgkmcnt(0)
	s_add_i32 s2, s8, 0x600
	s_add_i32 s7, s7, 0xc000
	s_cmpk_lt_i32 s8, 0xfb00
	s_mov_b32 s8, s2
	s_cbranch_scc1 .LBB0_1073
	v_mov_b32_e32 v3, 0
	v_readlane_b32 s16, v249, 1
	v_mov_b32_e32 v5, v3
	v_readlane_b32 s17, v249, 2
	s_add_u32 s5, s68, 0x2000000
	s_addc_u32 s6, s69, 0
	v_lshl_add_u64 v[22:23], s[16:17], 0, v[4:5]
	s_mov_b32 s7, s4
	s_mov_b32 s8, s13
	v_readlane_b32 s18, v249, 3
	v_readlane_b32 s19, v249, 4
	v_readlane_b32 s20, v249, 5
	v_readlane_b32 s21, v249, 6
	v_readlane_b32 s22, v249, 7
	v_readlane_b32 s23, v249, 8
	v_readlane_b32 s24, v249, 9
	v_readlane_b32 s25, v249, 10
	v_readlane_b32 s26, v249, 11
	v_readlane_b32 s27, v249, 12
	v_readlane_b32 s28, v249, 13
	v_readlane_b32 s29, v249, 14
	v_readlane_b32 s30, v249, 15
	v_readlane_b32 s31, v249, 16
.LBB0_1075:
	s_ashr_i32 s0, s8, 31
	s_lshr_b32 s0, s0, 27
	s_add_i32 s0, s8, s0
	s_ashr_i32 s1, s0, 5
	s_lshl_b32 s0, s1, 6
	s_lshl_b32 s1, s1, 10
	v_or_b32_e32 v24, s0, v0
	s_sub_i32 s2, s7, s1
	v_or_b32_e32 v26, 2, v24
	v_or_b32_e32 v52, 12, v24
	v_or_b32_e32 v54, 14, v24
	v_or_b32_e32 v56, 16, v24
	v_or_b32_e32 v58, 18, v24
	v_or_b32_e32 v60, 20, v24
	v_or_b32_e32 v62, 22, v24
	v_or_b32_e32 v64, 24, v24
	v_or_b32_e32 v66, 26, v24
	v_or_b32_e32 v68, 28, v24
	v_or_b32_e32 v70, 30, v24
	v_or_b32_e32 v72, 32, v24
	s_ashr_i32 s3, s2, 31
	v_ashrrev_i32_e32 v25, 31, v24
	v_or_b32_e32 v28, 4, v24
	v_or_b32_e32 v30, 6, v24
	v_or_b32_e32 v32, 8, v24
	v_or_b32_e32 v50, 10, v24
	v_or_b32_e32 v74, 34, v24
	v_or_b32_e32 v76, 36, v24
	v_or_b32_e32 v78, 38, v24
	v_or_b32_e32 v80, 40, v24
	v_or_b32_e32 v82, 42, v24
	v_or_b32_e32 v84, 44, v24
	v_or_b32_e32 v86, 46, v24
	v_or_b32_e32 v88, 48, v24
	v_or_b32_e32 v90, 50, v24
	v_or_b32_e32 v92, 52, v24
	v_or_b32_e32 v94, 54, v24
	v_or_b32_e32 v96, 56, v24
	v_or_b32_e32 v98, 58, v24
	v_or_b32_e32 v100, 60, v24
	v_or_b32_e32 v102, 62, v24
	v_ashrrev_i32_e32 v27, 31, v26
	v_ashrrev_i32_e32 v53, 31, v52
	v_ashrrev_i32_e32 v55, 31, v54
	v_ashrrev_i32_e32 v57, 31, v56
	v_ashrrev_i32_e32 v59, 31, v58
	v_ashrrev_i32_e32 v61, 31, v60
	v_ashrrev_i32_e32 v63, 31, v62
	v_ashrrev_i32_e32 v65, 31, v64
	v_ashrrev_i32_e32 v67, 31, v66
	v_ashrrev_i32_e32 v69, 31, v68
	v_ashrrev_i32_e32 v71, 31, v70
	v_ashrrev_i32_e32 v73, 31, v72
	v_lshl_add_u64 v[104:105], s[2:3], 2, v[22:23]
	v_lshlrev_b64 v[24:25], 12, v[24:25]
	v_ashrrev_i32_e32 v29, 31, v28
	v_ashrrev_i32_e32 v31, 31, v30
	v_ashrrev_i32_e32 v33, 31, v32
	v_ashrrev_i32_e32 v51, 31, v50
	v_ashrrev_i32_e32 v75, 31, v74
	v_ashrrev_i32_e32 v77, 31, v76
	v_ashrrev_i32_e32 v79, 31, v78
;     ...
;         const int kb = item / nblk, nb = nb0 + item % nblk, k0 = 64 * kb, n0 = 32 * nb;
;         float tv[32];
; #pragma unroll
;         for (int i = 0; i < 32; ++i) { const int kk = 2 * i + (lane >> 5); tv[i] = W[(size_t)(k0 + kk) * N + n0 + (lane & 31)]; }
; #pragma unroll
;         for (int i = 0; i < 32; ++i) { const int kk = 2 * i + (lane >> 5); float v = tv[i]; if (gk) v *= gk[k0 + kk]; scr[kk * 33 + (lane & 31)] = v; }
	v_ashrrev_i32_e32 v81, 31, v80
	v_ashrrev_i32_e32 v83, 31, v82
	v_ashrrev_i32_e32 v85, 31, v84
	v_ashrrev_i32_e32 v87, 31, v86
	v_ashrrev_i32_e32 v89, 31, v88
	v_ashrrev_i32_e32 v91, 31, v90
	v_ashrrev_i32_e32 v93, 31, v92
	v_ashrrev_i32_e32 v95, 31, v94
	v_ashrrev_i32_e32 v97, 31, v96
	v_ashrrev_i32_e32 v99, 31, v98
	v_ashrrev_i32_e32 v101, 31, v100
	v_ashrrev_i32_e32 v103, 31, v102
	v_lshlrev_b64 v[26:27], 12, v[26:27]
	v_lshlrev_b64 v[52:53], 12, v[52:53]
	v_lshlrev_b64 v[54:55], 12, v[54:55]
	v_lshlrev_b64 v[56:57], 12, v[56:57]
	v_lshlrev_b64 v[58:59], 12, v[58:59]
	v_lshlrev_b64 v[60:61], 12, v[60:61]
	v_lshlrev_b64 v[62:63], 12, v[62:63]
	v_lshlrev_b64 v[64:65], 12, v[64:65]
	v_lshlrev_b64 v[66:67], 12, v[66:67]
	v_lshlrev_b64 v[68:69], 12, v[68:69]
	v_lshlrev_b64 v[70:71], 12, v[70:71]
	v_lshlrev_b64 v[72:73], 12, v[72:73]
	v_lshl_add_u64 v[24:25], v[104:105], 0, v[24:25]
	v_lshlrev_b64 v[28:29], 12, v[28:29]
	v_lshlrev_b64 v[30:31], 12, v[30:31]
	v_lshlrev_b64 v[32:33], 12, v[32:33]
	v_lshlrev_b64 v[50:51], 12, v[50:51]
	v_lshlrev_b64 v[74:75], 12, v[74:75]
	v_lshlrev_b64 v[76:77], 12, v[76:77]
	v_lshlrev_b64 v[78:79], 12, v[78:79]
	v_lshlrev_b64 v[80:81], 12, v[80:81]
	v_lshlrev_b64 v[82:83], 12, v[82:83]
	v_lshlrev_b64 v[84:85], 12, v[84:85]
	v_lshlrev_b64 v[86:87], 12, v[86:87]
	v_lshlrev_b64 v[88:89], 12, v[88:89]
	v_lshlrev_b64 v[90:91], 12, v[90:91]
	v_lshlrev_b64 v[92:93], 12, v[92:93]
	v_lshlrev_b64 v[94:95], 12, v[94:95]
	v_lshlrev_b64 v[96:97], 12, v[96:97]
	v_lshlrev_b64 v[98:99], 12, v[98:99]
	v_lshlrev_b64 v[100:101], 12, v[100:101]
	v_lshlrev_b64 v[102:103], 12, v[102:103]
	v_lshl_add_u64 v[26:27], v[104:105], 0, v[26:27]
	v_lshl_add_u64 v[52:53], v[104:105], 0, v[52:53]
	v_lshl_add_u64 v[54:55], v[104:105], 0, v[54:55]
	v_lshl_add_u64 v[56:57], v[104:105], 0, v[56:57]
	v_lshl_add_u64 v[58:59], v[104:105], 0, v[58:59]
	v_lshl_add_u64 v[60:61], v[104:105], 0, v[60:61]
	v_lshl_add_u64 v[62:63], v[104:105], 0, v[62:63]
	v_lshl_add_u64 v[64:65], v[104:105], 0, v[64:65]
	v_lshl_add_u64 v[66:67], v[104:105], 0, v[66:67]
	v_lshl_add_u64 v[68:69], v[104:105], 0, v[68:69]
	v_lshl_add_u64 v[70:71], v[104:105], 0, v[70:71]
	v_lshl_add_u64 v[72:73], v[104:105], 0, v[72:73]
	v_lshl_add_u64 v[28:29], v[104:105], 0, v[28:29]
	v_lshl_add_u64 v[30:31], v[104:105], 0, v[30:31]
	v_lshl_add_u64 v[32:33], v[104:105], 0, v[32:33]
	v_lshl_add_u64 v[50:51], v[104:105], 0, v[50:51]
	v_lshl_add_u64 v[74:75], v[104:105], 0, v[74:75]
	v_lshl_add_u64 v[76:77], v[104:105], 0, v[76:77]
	v_lshl_add_u64 v[78:79], v[104:105], 0, v[78:79]
	v_lshl_add_u64 v[80:81], v[104:105], 0, v[80:81]
	v_lshl_add_u64 v[82:83], v[104:105], 0, v[82:83]
	v_lshl_add_u64 v[84:85], v[104:105], 0, v[84:85]
	v_lshl_add_u64 v[86:87], v[104:105], 0, v[86:87]
	v_lshl_add_u64 v[88:89], v[104:105], 0, v[88:89]
	v_lshl_add_u64 v[90:91], v[104:105], 0, v[90:91]
	v_lshl_add_u64 v[92:93], v[104:105], 0, v[92:93]
	v_lshl_add_u64 v[94:95], v[104:105], 0, v[94:95]
	v_lshl_add_u64 v[96:97], v[104:105], 0, v[96:97]
	v_lshl_add_u64 v[98:99], v[104:105], 0, v[98:99]
	v_lshl_add_u64 v[100:101], v[104:105], 0, v[100:101]
	v_lshl_add_u64 v[102:103], v[104:105], 0, v[102:103]
	global_load_dword v1, v[24:25], off
	global_load_dword v5, v[26:27], off
	global_load_dword v7, v[28:29], off
	global_load_dword v9, v[30:31], off
	global_load_dword v11, v[32:33], off
	global_load_dword v13, v[50:51], off
	global_load_dword v24, v[52:53], off
	global_load_dword v25, v[54:55], off
	global_load_dword v26, v[56:57], off
	global_load_dword v27, v[58:59], off
	global_load_dword v49, v[60:61], off
	s_nop 0
	global_load_dword v52, v[62:63], off
	global_load_dword v53, v[64:65], off
	global_load_dword v54, v[66:67], off
	global_load_dword v55, v[68:69], off
	global_load_dword v56, v[70:71], off
	global_load_dword v57, v[72:73], off
	global_load_dword v58, v[74:75], off
	global_load_dword v59, v[76:77], off
	global_load_dword v60, v[78:79], off
	global_load_dword v61, v[80:81], off
	global_load_dword v62, v[82:83], off
	global_load_dword v63, v[84:85], off
	global_load_dword v64, v[86:87], off
	global_load_dword v65, v[88:89], off
	global_load_dword v66, v[90:91], off
	global_load_dword v67, v[92:93], off
	global_load_dword v68, v[94:95], off
	global_load_dword v69, v[96:97], off
	global_load_dword v70, v[98:99], off
	global_load_dword v71, v[100:101], off
	global_load_dword v72, v[102:103], off
	s_lshl_b64 s[2:3], s[2:3], 10
	s_add_u32 s2, s5, s2
	s_addc_u32 s3, s6, s3
	s_ashr_i32 s1, s0, 31
	s_lshl_b64 s[0:1], s[0:1], 1
	s_add_u32 s0, s2, s0
	v_add_u32_e32 v73, 0x400, v35
	v_add_u32_e32 v74, 0x800, v35
	v_add_u32_e32 v75, 0xc00, v35
	v_add_u32_e32 v76, 0x1000, v35
	v_add_u32_e32 v77, 0x1400, v35
	v_add_u32_e32 v78, 0x1800, v35
	v_add_u32_e32 v79, 0x1c00, v35
	s_addc_u32 s1, s3, s1
	s_waitcnt vmcnt(0)
	ds_write2_b32 v35, v1, v5 offset1:66
	ds_write2_b32 v35, v7, v9 offset0:132 offset1:198
	ds_write2_b32 v73, v11, v13 offset0:8 offset1:74
	ds_write2_b32 v73, v24, v25 offset0:140 offset1:206
	ds_write2_b32 v74, v26, v27 offset0:16 offset1:82
	ds_write2_b32 v74, v49, v52 offset0:148 offset1:214
	ds_write2_b32 v75, v53, v54 offset0:24 offset1:90
	ds_write2_b32 v75, v55, v56 offset0:156 offset1:222
	ds_write2_b32 v76, v57, v58 offset0:32 offset1:98
	ds_write2_b32 v76, v59, v60 offset0:164 offset1:230
	ds_write2_b32 v77, v61, v62 offset0:40 offset1:106
	ds_write2_b32 v77, v63, v64 offset0:172 offset1:238
	ds_write2_b32 v78, v65, v66 offset0:48 offset1:114
	ds_write2_b32 v78, v67, v68 offset0:180 offset1:246
	ds_write2_b32 v79, v69, v70 offset0:56 offset1:122
	ds_write2_b32 v79, v71, v72 offset0:188 offset1:254
	v_mov_b32_e32 v15, v3
	v_mov_b32_e32 v17, v3
	v_lshl_add_u64 v[28:29], s[0:1], 0, v[2:3]
	s_waitcnt lgkmcnt(0)
; #define LAS __attribute__((address_space(3)))
; DI unsigned pk2(float lo, float hi) { typedef float v2f __attribute__((ext_vector_type(2))); typedef __bf16 v2b __attribute__((ext_vector_type(2))); v2f v = {lo, hi}; v2b b = __builtin_convertvector(v, v2b); return __builtin_bit_cast(unsigned, b); }
;     ...
;         const int kb = item / nblk, nb = nb0 + item % nblk, k0 = 64 * kb, n0 = 32 * nb;
;         float tv[32];
; #pragma unroll
;         for (int i = 0; i < 32; ++i) { const int kk = 2 * i + (lane >> 5); tv[i] = W[(size_t)(k0 + kk) * N + n0 + (lane & 31)]; }
;     ...
;         const int c = lane & 7;
; #pragma unroll
;         for (int jj = 0; jj < 4; ++jj) { const int n = (lane >> 3) + 8 * jj; const LAS float* s = scr + (8 * c) * 33 + n;
;             u32x4 o; o.x = pk2(s[0 * 33], s[1 * 33]); o.y = pk2(s[2 * 33], s[3 * 33]); o.z = pk2(s[4 * 33], s[5 * 33]); o.w = pk2(s[6 * 33], s[7 * 33]);
;             *(u32x4*)(dst + (size_t)n * K + k0 + 8 * c) = o; }
;         asm volatile("s_waitcnt lgkmcnt(0)" ::: "memory");
	v_lshl_add_u64 v[30:31], v[28:29], 0, v[14:15]
	v_lshl_add_u64 v[32:33], v[28:29], 0, v[16:17]
	ds_read_b32 v1, v34
	ds_read_b32 v5, v34 offset:132
	ds_read_b32 v7, v34 offset:264
	ds_read_b32 v9, v34 offset:396
	ds_read_b32 v11, v34 offset:528
	ds_read_b32 v13, v34 offset:660
	ds_read_b32 v15, v34 offset:792
	ds_read_b32 v17, v34 offset:924
	s_waitcnt lgkmcnt(0)
	v_cvt_pk_bf16_f32 v24, v1, v5
	v_cvt_pk_bf16_f32 v25, v7, v9
	v_cvt_pk_bf16_f32 v26, v11, v13
	v_mov_b32_e32 v19, v3
	v_cvt_pk_bf16_f32 v27, v15, v17
	global_store_dwordx4 v[30:31], v[24:27], off
	ds_read_b32 v1, v34 offset:32
	ds_read_b32 v5, v34 offset:164
	ds_read_b32 v7, v34 offset:296
	ds_read_b32 v9, v34 offset:428
	ds_read_b32 v11, v34 offset:560
	ds_read_b32 v13, v34 offset:692
	ds_read_b32 v15, v34 offset:824
	ds_read_b32 v17, v34 offset:956
	s_waitcnt lgkmcnt(0)
	v_cvt_pk_bf16_f32 v24, v1, v5
	v_cvt_pk_bf16_f32 v25, v7, v9
	v_cvt_pk_bf16_f32 v26, v11, v13
	v_lshl_add_u64 v[50:51], v[28:29], 0, v[18:19]
	v_cvt_pk_bf16_f32 v27, v15, v17
	global_store_dwordx4 v[32:33], v[24:27], off
	ds_read_b32 v1, v34 offset:64
	ds_read_b32 v5, v34 offset:196
	ds_read_b32 v7, v34 offset:328
	ds_read_b32 v9, v34 offset:460
	ds_read_b32 v11, v34 offset:592
	ds_read_b32 v13, v34 offset:724
	ds_read_b32 v15, v34 offset:856
	ds_read_b32 v17, v34 offset:988
	s_waitcnt lgkmcnt(0)
	v_cvt_pk_bf16_f32 v24, v1, v5
	v_cvt_pk_bf16_f32 v25, v7, v9
	v_cvt_pk_bf16_f32 v26, v11, v13
	v_mov_b32_e32 v21, v3
	v_cvt_pk_bf16_f32 v27, v15, v17
	global_store_dwordx4 v[50:51], v[24:27], off
	ds_read_b32 v1, v34 offset:96
	ds_read_b32 v5, v34 offset:228
	ds_read_b32 v7, v34 offset:360
	ds_read_b32 v9, v34 offset:492
	ds_read_b32 v11, v34 offset:624
	ds_read_b32 v13, v34 offset:756
	ds_read_b32 v15, v34 offset:888
	ds_read_b32 v17, v34 offset:1020
	v_lshl_add_u64 v[28:29], v[28:29], 0, v[20:21]
	s_waitcnt lgkmcnt(0)
	v_cvt_pk_bf16_f32 v24, v1, v5
	v_cvt_pk_bf16_f32 v25, v7, v9
	v_cvt_pk_bf16_f32 v26, v11, v13
	v_cvt_pk_bf16_f32 v27, v15, v17
	global_store_dwordx4 v[28:29], v[24:27], off
	s_waitcnt lgkmcnt(0)
	s_add_i32 s2, s8, 0x600
	s_add_i32 s7, s7, 0xc000
	s_cmpk_lt_i32 s8, 0xfb00
	s_mov_b32 s8, s2
	s_cbranch_scc1 .LBB0_1075
	v_mov_b32_e32 v3, 0
	v_readlane_b32 s16, v249, 1
	v_mov_b32_e32 v5, v3
	v_readlane_b32 s18, v249, 3
	v_readlane_b32 s19, v249, 4
	s_add_u32 s5, s68, 0x2100000
	s_addc_u32 s6, s69, 0
	v_lshl_add_u64 v[22:23], s[18:19], 0, v[4:5]
	s_mov_b32 s7, s13
	v_readlane_b32 s17, v249, 2
	v_readlane_b32 s20, v249, 5
	v_readlane_b32 s21, v249, 6
	v_readlane_b32 s22, v249, 7
	v_readlane_b32 s23, v249, 8
	v_readlane_b32 s24, v249, 9
	v_readlane_b32 s25, v249, 10
	v_readlane_b32 s26, v249, 11
	v_readlane_b32 s27, v249, 12
	v_readlane_b32 s28, v249, 13
	v_readlane_b32 s29, v249, 14
	v_readlane_b32 s30, v249, 15
	v_readlane_b32 s31, v249, 16
.LBB0_1077:
	s_ashr_i32 s0, s7, 31
	s_lshr_b32 s0, s0, 27
	s_add_i32 s0, s7, s0
	s_ashr_i32 s1, s0, 5
	s_lshl_b32 s0, s1, 6
	s_lshl_b32 s1, s1, 10
	v_or_b32_e32 v24, s0, v0
	s_sub_i32 s2, s4, s1
	v_or_b32_e32 v26, 2, v24
	v_or_b32_e32 v52, 12, v24
	v_or_b32_e32 v54, 14, v24
	v_or_b32_e32 v56, 16, v24
	v_or_b32_e32 v58, 18, v24
	v_or_b32_e32 v60, 20, v24
	v_or_b32_e32 v62, 22, v24
	v_or_b32_e32 v64, 24, v24
	v_or_b32_e32 v66, 26, v24
	v_or_b32_e32 v68, 28, v24
	v_or_b32_e32 v70, 30, v24
	v_or_b32_e32 v72, 32, v24
	s_ashr_i32 s3, s2, 31
	v_ashrrev_i32_e32 v25, 31, v24
	v_or_b32_e32 v28, 4, v24
	v_or_b32_e32 v30, 6, v24
	v_or_b32_e32 v32, 8, v24
	v_or_b32_e32 v50, 10, v24
	v_or_b32_e32 v74, 34, v24
	v_or_b32_e32 v76, 36, v24
	v_or_b32_e32 v78, 38, v24
	v_or_b32_e32 v80, 40, v24
	v_or_b32_e32 v82, 42, v24
	v_or_b32_e32 v84, 44, v24
	v_or_b32_e32 v86, 46, v24
	v_or_b32_e32 v88, 48, v24
	v_or_b32_e32 v90, 50, v24
	v_or_b32_e32 v92, 52, v24
	v_or_b32_e32 v94, 54, v24
	v_or_b32_e32 v96, 56, v24
	v_or_b32_e32 v98, 58, v24
	v_or_b32_e32 v100, 60, v24
	v_or_b32_e32 v102, 62, v24
	v_ashrrev_i32_e32 v27, 31, v26
	v_ashrrev_i32_e32 v53, 31, v52
	v_ashrrev_i32_e32 v55, 31, v54
	v_ashrrev_i32_e32 v57, 31, v56
	v_ashrrev_i32_e32 v59, 31, v58
	v_ashrrev_i32_e32 v61, 31, v60
	v_ashrrev_i32_e32 v63, 31, v62
	v_ashrrev_i32_e32 v65, 31, v64
	v_ashrrev_i32_e32 v67, 31, v66
	v_ashrrev_i32_e32 v69, 31, v68
	v_ashrrev_i32_e32 v71, 31, v70
	v_ashrrev_i32_e32 v73, 31, v72
	v_lshl_add_u64 v[104:105], s[2:3], 2, v[22:23]
	v_lshlrev_b64 v[24:25], 12, v[24:25]
	v_ashrrev_i32_e32 v29, 31, v28
	v_ashrrev_i32_e32 v31, 31, v30
	v_ashrrev_i32_e32 v33, 31, v32
	v_ashrrev_i32_e32 v51, 31, v50
	v_ashrrev_i32_e32 v75, 31, v74
	v_ashrrev_i32_e32 v77, 31, v76
	v_ashrrev_i32_e32 v79, 31, v78
	v_ashrrev_i32_e32 v81, 31, v80
	v_ashrrev_i32_e32 v83, 31, v82
	v_ashrrev_i32_e32 v85, 31, v84
	v_ashrrev_i32_e32 v87, 31, v86
	v_ashrrev_i32_e32 v89, 31, v88
	v_ashrrev_i32_e32 v91, 31, v90
	v_ashrrev_i32_e32 v93, 31, v92
	v_ashrrev_i32_e32 v95, 31, v94
	v_ashrrev_i32_e32 v97, 31, v96
	v_ashrrev_i32_e32 v99, 31, v98
	v_ashrrev_i32_e32 v101, 31, v100
	v_ashrrev_i32_e32 v103, 31, v102
	v_lshlrev_b64 v[26:27], 12, v[26:27]
	v_lshlrev_b64 v[52:53], 12, v[52:53]
	v_lshlrev_b64 v[54:55], 12, v[54:55]
	v_lshlrev_b64 v[56:57], 12, v[56:57]
	v_lshlrev_b64 v[58:59], 12, v[58:59]
	v_lshlrev_b64 v[60:61], 12, v[60:61]
	v_lshlrev_b64 v[62:63], 12, v[62:63]
	v_lshlrev_b64 v[64:65], 12, v[64:65]
	v_lshlrev_b64 v[66:67], 12, v[66:67]
	v_lshlrev_b64 v[68:69], 12, v[68:69]
	v_lshlrev_b64 v[70:71], 12, v[70:71]
	v_lshlrev_b64 v[72:73], 12, v[72:73]
	v_lshl_add_u64 v[24:25], v[104:105], 0, v[24:25]
	v_lshlrev_b64 v[28:29], 12, v[28:29]
	v_lshlrev_b64 v[30:31], 12, v[30:31]
	v_lshlrev_b64 v[32:33], 12, v[32:33]
	v_lshlrev_b64 v[50:51], 12, v[50:51]
; #define LAS __attribute__((address_space(3)))
; DI unsigned pk2(float lo, float hi) { typedef float v2f __attribute__((ext_vector_type(2))); typedef __bf16 v2b __attribute__((ext_vector_type(2))); v2f v = {lo, hi}; v2b b = __builtin_convertvector(v, v2b); return __builtin_bit_cast(unsigned, b); }
;     ...
;         const int kb = item / nblk, nb = nb0 + item % nblk, k0 = 64 * kb, n0 = 32 * nb;
;         float tv[32];
; #pragma unroll
;         for (int i = 0; i < 32; ++i) { const int kk = 2 * i + (lane >> 5); tv[i] = W[(size_t)(k0 + kk) * N + n0 + (lane & 31)]; }
; #pragma unroll
;         for (int i = 0; i < 32; ++i) { const int kk = 2 * i + (lane >> 5); float v = tv[i]; if (gk) v *= gk[k0 + kk]; scr[kk * 33 + (lane & 31)] = v; }
;         asm volatile("s_waitcnt lgkmcnt(0)" ::: "memory");
;         bf16_t* dst = dest_rows(mode, n0, K, d0, d1);
;         const int c = lane & 7;
; #pragma unroll
;         for (int jj = 0; jj < 4; ++jj) { const int n = (lane >> 3) + 8 * jj; const LAS float* s = scr + (8 * c) * 33 + n;
;             u32x4 o; o.x = pk2(s[0 * 33], s[1 * 33]); o.y = pk2(s[2 * 33], s[3 * 33]); o.z = pk2(s[4 * 33], s[5 * 33]); o.w = pk2(s[6 * 33], s[7 * 33]);
;             *(u32x4*)(dst + (size_t)n * K + k0 + 8 * c) = o; }
;         asm volatile("s_waitcnt lgkmcnt(0)" ::: "memory");
	v_lshlrev_b64 v[74:75], 12, v[74:75]
	v_lshlrev_b64 v[76:77], 12, v[76:77]
	v_lshlrev_b64 v[78:79], 12, v[78:79]
	v_lshlrev_b64 v[80:81], 12, v[80:81]
	v_lshlrev_b64 v[82:83], 12, v[82:83]
	v_lshlrev_b64 v[84:85], 12, v[84:85]
	v_lshlrev_b64 v[86:87], 12, v[86:87]
	v_lshlrev_b64 v[88:89], 12, v[88:89]
	v_lshlrev_b64 v[90:91], 12, v[90:91]
	v_lshlrev_b64 v[92:93], 12, v[92:93]
	v_lshlrev_b64 v[94:95], 12, v[94:95]
	v_lshlrev_b64 v[96:97], 12, v[96:97]
	v_lshlrev_b64 v[98:99], 12, v[98:99]
	v_lshlrev_b64 v[100:101], 12, v[100:101]
	v_lshlrev_b64 v[102:103], 12, v[102:103]
	v_lshl_add_u64 v[26:27], v[104:105], 0, v[26:27]
	v_lshl_add_u64 v[52:53], v[104:105], 0, v[52:53]
	v_lshl_add_u64 v[54:55], v[104:105], 0, v[54:55]
	v_lshl_add_u64 v[56:57], v[104:105], 0, v[56:57]
	v_lshl_add_u64 v[58:59], v[104:105], 0, v[58:59]
	v_lshl_add_u64 v[60:61], v[104:105], 0, v[60:61]
	v_lshl_add_u64 v[62:63], v[104:105], 0, v[62:63]
	v_lshl_add_u64 v[64:65], v[104:105], 0, v[64:65]
	v_lshl_add_u64 v[66:67], v[104:105], 0, v[66:67]
	v_lshl_add_u64 v[68:69], v[104:105], 0, v[68:69]
	v_lshl_add_u64 v[70:71], v[104:105], 0, v[70:71]
	v_lshl_add_u64 v[72:73], v[104:105], 0, v[72:73]
	v_lshl_add_u64 v[28:29], v[104:105], 0, v[28:29]
	v_lshl_add_u64 v[30:31], v[104:105], 0, v[30:31]
	v_lshl_add_u64 v[32:33], v[104:105], 0, v[32:33]
	v_lshl_add_u64 v[50:51], v[104:105], 0, v[50:51]
	v_lshl_add_u64 v[74:75], v[104:105], 0, v[74:75]
	v_lshl_add_u64 v[76:77], v[104:105], 0, v[76:77]
	v_lshl_add_u64 v[78:79], v[104:105], 0, v[78:79]
	v_lshl_add_u64 v[80:81], v[104:105], 0, v[80:81]
	v_lshl_add_u64 v[82:83], v[104:105], 0, v[82:83]
	v_lshl_add_u64 v[84:85], v[104:105], 0, v[84:85]
	v_lshl_add_u64 v[86:87], v[104:105], 0, v[86:87]
	v_lshl_add_u64 v[88:89], v[104:105], 0, v[88:89]
	v_lshl_add_u64 v[90:91], v[104:105], 0, v[90:91]
	v_lshl_add_u64 v[92:93], v[104:105], 0, v[92:93]
	v_lshl_add_u64 v[94:95], v[104:105], 0, v[94:95]
	v_lshl_add_u64 v[96:97], v[104:105], 0, v[96:97]
	v_lshl_add_u64 v[98:99], v[104:105], 0, v[98:99]
	v_lshl_add_u64 v[100:101], v[104:105], 0, v[100:101]
	v_lshl_add_u64 v[102:103], v[104:105], 0, v[102:103]
	global_load_dword v1, v[24:25], off
	global_load_dword v5, v[26:27], off
	global_load_dword v7, v[28:29], off
	global_load_dword v9, v[30:31], off
	global_load_dword v11, v[32:33], off
	global_load_dword v13, v[50:51], off
	global_load_dword v24, v[52:53], off
	global_load_dword v25, v[54:55], off
	global_load_dword v26, v[56:57], off
	global_load_dword v27, v[58:59], off
	global_load_dword v49, v[60:61], off
	s_nop 0
	global_load_dword v52, v[62:63], off
	global_load_dword v53, v[64:65], off
	global_load_dword v54, v[66:67], off
	global_load_dword v55, v[68:69], off
	global_load_dword v56, v[70:71], off
	global_load_dword v57, v[72:73], off
	global_load_dword v58, v[74:75], off
	global_load_dword v59, v[76:77], off
	global_load_dword v60, v[78:79], off
	global_load_dword v61, v[80:81], off
	global_load_dword v62, v[82:83], off
	global_load_dword v63, v[84:85], off
	global_load_dword v64, v[86:87], off
	global_load_dword v65, v[88:89], off
	global_load_dword v66, v[90:91], off
	global_load_dword v67, v[92:93], off
	global_load_dword v68, v[94:95], off
	global_load_dword v69, v[96:97], off
	global_load_dword v70, v[98:99], off
	global_load_dword v71, v[100:101], off
	global_load_dword v72, v[102:103], off
	s_lshl_b64 s[2:3], s[2:3], 10
	s_add_u32 s2, s5, s2
	s_addc_u32 s3, s6, s3
	s_ashr_i32 s1, s0, 31
	s_lshl_b64 s[0:1], s[0:1], 1
	s_add_u32 s0, s2, s0
	v_add_u32_e32 v73, 0x400, v35
	v_add_u32_e32 v74, 0x800, v35
	v_add_u32_e32 v75, 0xc00, v35
	v_add_u32_e32 v76, 0x1000, v35
	v_add_u32_e32 v77, 0x1400, v35
	v_add_u32_e32 v78, 0x1800, v35
	v_add_u32_e32 v79, 0x1c00, v35
	s_addc_u32 s1, s3, s1
	s_waitcnt vmcnt(0)
	ds_write2_b32 v35, v1, v5 offset1:66
	ds_write2_b32 v35, v7, v9 offset0:132 offset1:198
	ds_write2_b32 v73, v11, v13 offset0:8 offset1:74
	ds_write2_b32 v73, v24, v25 offset0:140 offset1:206
	ds_write2_b32 v74, v26, v27 offset0:16 offset1:82
	ds_write2_b32 v74, v49, v52 offset0:148 offset1:214
	ds_write2_b32 v75, v53, v54 offset0:24 offset1:90
	ds_write2_b32 v75, v55, v56 offset0:156 offset1:222
	ds_write2_b32 v76, v57, v58 offset0:32 offset1:98
	ds_write2_b32 v76, v59, v60 offset0:164 offset1:230
	ds_write2_b32 v77, v61, v62 offset0:40 offset1:106
	ds_write2_b32 v77, v63, v64 offset0:172 offset1:238
	ds_write2_b32 v78, v65, v66 offset0:48 offset1:114
	ds_write2_b32 v78, v67, v68 offset0:180 offset1:246
	ds_write2_b32 v79, v69, v70 offset0:56 offset1:122
	ds_write2_b32 v79, v71, v72 offset0:188 offset1:254
	v_mov_b32_e32 v15, v3
	v_mov_b32_e32 v17, v3
	v_lshl_add_u64 v[28:29], s[0:1], 0, v[2:3]
	s_waitcnt lgkmcnt(0)
	v_lshl_add_u64 v[30:31], v[28:29], 0, v[14:15]
	v_lshl_add_u64 v[32:33], v[28:29], 0, v[16:17]
	ds_read_b32 v1, v34
	ds_read_b32 v5, v34 offset:132
	ds_read_b32 v7, v34 offset:264
	ds_read_b32 v9, v34 offset:396
	ds_read_b32 v11, v34 offset:528
	ds_read_b32 v13, v34 offset:660
	ds_read_b32 v15, v34 offset:792
	ds_read_b32 v17, v34 offset:924
	s_waitcnt lgkmcnt(0)
	v_cvt_pk_bf16_f32 v24, v1, v5
	v_cvt_pk_bf16_f32 v25, v7, v9
	v_cvt_pk_bf16_f32 v26, v11, v13
	v_mov_b32_e32 v19, v3
	v_cvt_pk_bf16_f32 v27, v15, v17
	global_store_dwordx4 v[30:31], v[24:27], off
	ds_read_b32 v1, v34 offset:32
	ds_read_b32 v5, v34 offset:164
	ds_read_b32 v7, v34 offset:296
	ds_read_b32 v9, v34 offset:428
	ds_read_b32 v11, v34 offset:560
	ds_read_b32 v13, v34 offset:692
	ds_read_b32 v15, v34 offset:824
	ds_read_b32 v17, v34 offset:956
	s_waitcnt lgkmcnt(0)
	v_cvt_pk_bf16_f32 v24, v1, v5
	v_cvt_pk_bf16_f32 v25, v7, v9
	v_cvt_pk_bf16_f32 v26, v11, v13
	v_lshl_add_u64 v[50:51], v[28:29], 0, v[18:19]
	v_cvt_pk_bf16_f32 v27, v15, v17
	global_store_dwordx4 v[32:33], v[24:27], off
	ds_read_b32 v1, v34 offset:64
	ds_read_b32 v5, v34 offset:196
	ds_read_b32 v7, v34 offset:328
	ds_read_b32 v9, v34 offset:460
	ds_read_b32 v11, v34 offset:592
	ds_read_b32 v13, v34 offset:724
	ds_read_b32 v15, v34 offset:856
	ds_read_b32 v17, v34 offset:988
	s_waitcnt lgkmcnt(0)
	v_cvt_pk_bf16_f32 v24, v1, v5
	v_cvt_pk_bf16_f32 v25, v7, v9
	v_cvt_pk_bf16_f32 v26, v11, v13
	v_mov_b32_e32 v21, v3
	v_cvt_pk_bf16_f32 v27, v15, v17
	global_store_dwordx4 v[50:51], v[24:27], off
	ds_read_b32 v1, v34 offset:96
	ds_read_b32 v5, v34 offset:228
	ds_read_b32 v7, v34 offset:360
	ds_read_b32 v9, v34 offset:492
	ds_read_b32 v11, v34 offset:624
	ds_read_b32 v13, v34 offset:756
	ds_read_b32 v15, v34 offset:888
	ds_read_b32 v17, v34 offset:1020
	v_lshl_add_u64 v[28:29], v[28:29], 0, v[20:21]
	s_waitcnt lgkmcnt(0)
	v_cvt_pk_bf16_f32 v24, v1, v5
	v_cvt_pk_bf16_f32 v25, v7, v9
	v_cvt_pk_bf16_f32 v26, v11, v13
	v_cvt_pk_bf16_f32 v27, v15, v17
	global_store_dwordx4 v[28:29], v[24:27], off
	s_waitcnt lgkmcnt(0)
	s_add_i32 s2, s7, 0x600
	s_add_i32 s4, s4, 0xc000
	s_cmpk_lt_i32 s7, 0xfb00
	s_mov_b32 s7, s2
	s_cbranch_scc1 .LBB0_1077

;     ...
;         const int kb = item / nblk, nb = nb0 + item % nblk, k0 = 64 * kb, n0 = 32 * nb;
;         float tv[32];
; #pragma unroll
;         for (int i = 0; i < 32; ++i) { const int kk = 2 * i + (lane >> 5); tv[i] = W[(size_t)(k0 + kk) * N + n0 + (lane & 31)]; }
.LBB0_1080:
	s_ashr_i32 s0, s7, 31
	s_lshr_b32 s0, s0, 27
	s_add_i32 s0, s7, s0
	s_ashr_i32 s1, s0, 5
	s_lshl_b32 s0, s1, 6
	s_lshl_b32 s1, s1, 10
	v_or_b32_e32 v22, s0, v0
	s_sub_i32 s2, s6, s1
	v_or_b32_e32 v24, 2, v22
	v_or_b32_e32 v50, 12, v22
	v_or_b32_e32 v52, 14, v22
	v_or_b32_e32 v54, 16, v22
	v_or_b32_e32 v56, 18, v22
	v_or_b32_e32 v58, 20, v22
	v_or_b32_e32 v60, 22, v22
	v_or_b32_e32 v62, 24, v22
	v_or_b32_e32 v64, 26, v22
	v_or_b32_e32 v66, 28, v22
	v_or_b32_e32 v68, 30, v22
	v_or_b32_e32 v70, 32, v22
	v_or_b32_e32 v72, 34, v22
	v_or_b32_e32 v74, 36, v22
	s_ashr_i32 s3, s2, 31
	v_ashrrev_i32_e32 v23, 31, v22
	v_or_b32_e32 v26, 4, v22
	v_or_b32_e32 v28, 6, v22
	v_or_b32_e32 v30, 8, v22
	v_or_b32_e32 v32, 10, v22
	v_or_b32_e32 v76, 38, v22
	v_or_b32_e32 v78, 40, v22
	v_or_b32_e32 v80, 42, v22
	v_or_b32_e32 v82, 44, v22
	v_or_b32_e32 v84, 46, v22
	v_or_b32_e32 v86, 48, v22
	v_or_b32_e32 v88, 50, v22
	v_or_b32_e32 v90, 52, v22
	v_or_b32_e32 v92, 54, v22
	v_or_b32_e32 v94, 56, v22
	v_or_b32_e32 v96, 58, v22
	v_or_b32_e32 v98, 60, v22
	v_or_b32_e32 v100, 62, v22
	v_ashrrev_i32_e32 v25, 31, v24
	v_ashrrev_i32_e32 v51, 31, v50
	v_ashrrev_i32_e32 v53, 31, v52
	v_ashrrev_i32_e32 v55, 31, v54
	v_ashrrev_i32_e32 v57, 31, v56
	v_ashrrev_i32_e32 v59, 31, v58
	v_ashrrev_i32_e32 v61, 31, v60
	v_ashrrev_i32_e32 v63, 31, v62
	v_ashrrev_i32_e32 v65, 31, v64
	v_ashrrev_i32_e32 v67, 31, v66
	v_ashrrev_i32_e32 v69, 31, v68
	v_ashrrev_i32_e32 v71, 31, v70
	v_ashrrev_i32_e32 v73, 31, v72
	v_ashrrev_i32_e32 v75, 31, v74
	v_lshl_add_u64 v[102:103], s[2:3], 2, v[14:15]
	v_lshlrev_b64 v[22:23], 12, v[22:23]
	v_ashrrev_i32_e32 v27, 31, v26
	v_ashrrev_i32_e32 v29, 31, v28
	v_ashrrev_i32_e32 v31, 31, v30
	v_ashrrev_i32_e32 v33, 31, v32
	v_ashrrev_i32_e32 v77, 31, v76
	v_ashrrev_i32_e32 v79, 31, v78
	v_ashrrev_i32_e32 v81, 31, v80
	v_ashrrev_i32_e32 v83, 31, v82
	v_ashrrev_i32_e32 v85, 31, v84
	v_ashrrev_i32_e32 v87, 31, v86
	v_ashrrev_i32_e32 v89, 31, v88
	v_ashrrev_i32_e32 v91, 31, v90
	v_ashrrev_i32_e32 v93, 31, v92
	v_ashrrev_i32_e32 v95, 31, v94
	v_ashrrev_i32_e32 v97, 31, v96
	v_ashrrev_i32_e32 v99, 31, v98
	v_ashrrev_i32_e32 v101, 31, v100
	v_lshlrev_b64 v[24:25], 12, v[24:25]
	v_lshlrev_b64 v[50:51], 12, v[50:51]
	v_lshlrev_b64 v[52:53], 12, v[52:53]
	v_lshlrev_b64 v[54:55], 12, v[54:55]
	v_lshlrev_b64 v[56:57], 12, v[56:57]
	v_lshlrev_b64 v[58:59], 12, v[58:59]
	v_lshlrev_b64 v[60:61], 12, v[60:61]
	v_lshlrev_b64 v[62:63], 12, v[62:63]
	v_lshlrev_b64 v[64:65], 12, v[64:65]
	v_lshlrev_b64 v[66:67], 12, v[66:67]
	v_lshlrev_b64 v[68:69], 12, v[68:69]
	v_lshlrev_b64 v[70:71], 12, v[70:71]
	v_lshlrev_b64 v[72:73], 12, v[72:73]
	v_lshlrev_b64 v[74:75], 12, v[74:75]
	v_lshl_add_u64 v[22:23], v[102:103], 0, v[22:23]
	v_lshlrev_b64 v[26:27], 12, v[26:27]
	v_lshlrev_b64 v[28:29], 12, v[28:29]
	v_lshlrev_b64 v[30:31], 12, v[30:31]
	v_lshlrev_b64 v[32:33], 12, v[32:33]
	v_lshlrev_b64 v[76:77], 12, v[76:77]
	v_lshlrev_b64 v[78:79], 12, v[78:79]
	v_lshlrev_b64 v[80:81], 12, v[80:81]
	v_lshlrev_b64 v[82:83], 12, v[82:83]
	v_lshlrev_b64 v[84:85], 12, v[84:85]
	v_lshlrev_b64 v[86:87], 12, v[86:87]
	v_lshlrev_b64 v[88:89], 12, v[88:89]
	v_lshlrev_b64 v[90:91], 12, v[90:91]
	v_lshlrev_b64 v[92:93], 12, v[92:93]
	v_lshlrev_b64 v[94:95], 12, v[94:95]
	v_lshlrev_b64 v[96:97], 12, v[96:97]
	v_lshlrev_b64 v[98:99], 12, v[98:99]
	v_lshlrev_b64 v[100:101], 12, v[100:101]
	v_lshl_add_u64 v[24:25], v[102:103], 0, v[24:25]
	v_lshl_add_u64 v[50:51], v[102:103], 0, v[50:51]
	v_lshl_add_u64 v[52:53], v[102:103], 0, v[52:53]
	v_lshl_add_u64 v[54:55], v[102:103], 0, v[54:55]
	v_lshl_add_u64 v[56:57], v[102:103], 0, v[56:57]
	v_lshl_add_u64 v[58:59], v[102:103], 0, v[58:59]
	v_lshl_add_u64 v[60:61], v[102:103], 0, v[60:61]
	v_lshl_add_u64 v[62:63], v[102:103], 0, v[62:63]
	v_lshl_add_u64 v[64:65], v[102:103], 0, v[64:65]
	v_lshl_add_u64 v[66:67], v[102:103], 0, v[66:67]
	v_lshl_add_u64 v[68:69], v[102:103], 0, v[68:69]
	v_lshl_add_u64 v[70:71], v[102:103], 0, v[70:71]
	v_lshl_add_u64 v[72:73], v[102:103], 0, v[72:73]
	v_lshl_add_u64 v[74:75], v[102:103], 0, v[74:75]
	v_lshl_add_u64 v[26:27], v[102:103], 0, v[26:27]
	v_lshl_add_u64 v[28:29], v[102:103], 0, v[28:29]
	v_lshl_add_u64 v[30:31], v[102:103], 0, v[30:31]
	v_lshl_add_u64 v[32:33], v[102:103], 0, v[32:33]
	v_lshl_add_u64 v[76:77], v[102:103], 0, v[76:77]
	v_lshl_add_u64 v[78:79], v[102:103], 0, v[78:79]
	v_lshl_add_u64 v[80:81], v[102:103], 0, v[80:81]
	v_lshl_add_u64 v[82:83], v[102:103], 0, v[82:83]
	v_lshl_add_u64 v[84:85], v[102:103], 0, v[84:85]
	v_lshl_add_u64 v[86:87], v[102:103], 0, v[86:87]
	v_lshl_add_u64 v[88:89], v[102:103], 0, v[88:89]
	v_lshl_add_u64 v[90:91], v[102:103], 0, v[90:91]
	v_lshl_add_u64 v[92:93], v[102:103], 0, v[92:93]
	v_lshl_add_u64 v[94:95], v[102:103], 0, v[94:95]
	v_lshl_add_u64 v[96:97], v[102:103], 0, v[96:97]
	v_lshl_add_u64 v[98:99], v[102:103], 0, v[98:99]
	v_lshl_add_u64 v[100:101], v[102:103], 0, v[100:101]
	global_load_dword v21, v[22:23], off
	s_nop 0
	global_load_dword v22, v[24:25], off
	global_load_dword v23, v[26:27], off
	s_nop 0
	global_load_dword v24, v[28:29], off
	global_load_dword v25, v[30:31], off
	global_load_dword v49, v[32:33], off
	s_nop 0
	global_load_dword v50, v[50:51], off
	s_nop 0
	global_load_dword v51, v[52:53], off
	s_nop 0
	global_load_dword v52, v[54:55], off
	global_load_dword v53, v[56:57], off
	s_nop 0
	global_load_dword v54, v[58:59], off
	global_load_dword v55, v[60:61], off
	global_load_dword v56, v[62:63], off
	global_load_dword v57, v[64:65], off
	s_nop 0
	global_load_dword v58, v[66:67], off
	global_load_dword v59, v[68:69], off
	global_load_dword v60, v[70:71], off
	global_load_dword v61, v[72:73], off
	global_load_dword v62, v[74:75], off
	global_load_dword v63, v[76:77], off
	global_load_dword v64, v[78:79], off
	global_load_dword v65, v[80:81], off
	global_load_dword v66, v[82:83], off
	global_load_dword v67, v[84:85], off
	global_load_dword v68, v[86:87], off
	global_load_dword v69, v[88:89], off
	global_load_dword v70, v[90:91], off
	global_load_dword v71, v[92:93], off
	global_load_dword v72, v[94:95], off
	global_load_dword v73, v[96:97], off
	global_load_dword v74, v[98:99], off
	global_load_dword v75, v[100:101], off
	s_lshl_b64 s[2:3], s[2:3], 11
	s_waitcnt vmcnt(0)
; #define LAS __attribute__((address_space(3)))
; DI unsigned pk2(float lo, float hi) { typedef float v2f __attribute__((ext_vector_type(2))); typedef __bf16 v2b __attribute__((ext_vector_type(2))); v2f v = {lo, hi}; v2b b = __builtin_convertvector(v, v2b); return __builtin_bit_cast(unsigned, b); }
;     ...
;         for (int i = 0; i < 32; ++i) { const int kk = 2 * i + (lane >> 5); float v = tv[i]; if (gk) v *= gk[k0 + kk]; scr[kk * 33 + (lane & 31)] = v; }
;         asm volatile("s_waitcnt lgkmcnt(0)" ::: "memory");
;         bf16_t* dst = dest_rows(mode, n0, K, d0, d1);
;         const int c = lane & 7;
; #pragma unroll
;         for (int jj = 0; jj < 4; ++jj) { const int n = (lane >> 3) + 8 * jj; const LAS float* s = scr + (8 * c) * 33 + n;
;             u32x4 o; o.x = pk2(s[0 * 33], s[1 * 33]); o.y = pk2(s[2 * 33], s[3 * 33]); o.z = pk2(s[4 * 33], s[5 * 33]); o.w = pk2(s[6 * 33], s[7 * 33]);
;             *(u32x4*)(dst + (size_t)n * K + k0 + 8 * c) = o; }
;         asm volatile("s_waitcnt lgkmcnt(0)" ::: "memory");
	ds_write2_b32 v35, v21, v22 offset1:66
	ds_write2_b32 v35, v23, v24 offset0:132 offset1:198
	ds_write2_b32 v1, v25, v49 offset0:8 offset1:74
	ds_write2_b32 v1, v50, v51 offset0:140 offset1:206
	ds_write2_b32 v5, v52, v53 offset0:16 offset1:82
	ds_write2_b32 v5, v54, v55 offset0:148 offset1:214
	ds_write2_b32 v16, v56, v57 offset0:24 offset1:90
	ds_write2_b32 v16, v58, v59 offset0:156 offset1:222
	ds_write2_b32 v17, v60, v61 offset0:32 offset1:98
	ds_write2_b32 v17, v62, v63 offset0:164 offset1:230
	ds_write2_b32 v18, v64, v65 offset0:40 offset1:106
	ds_write2_b32 v18, v66, v67 offset0:172 offset1:238
	ds_write2_b32 v19, v68, v69 offset0:48 offset1:114
	ds_write2_b32 v19, v70, v71 offset0:180 offset1:246
	ds_write2_b32 v20, v72, v73 offset0:56 offset1:122
	ds_write2_b32 v20, v74, v75 offset0:188 offset1:254
	s_add_u32 s2, s4, s2
	s_waitcnt lgkmcnt(0)
	s_addc_u32 s3, s5, s3
	s_ashr_i32 s1, s0, 31
	ds_read_b32 v21, v34
	ds_read_b32 v22, v34 offset:132
	ds_read_b32 v23, v34 offset:264
	ds_read_b32 v24, v34 offset:396
	ds_read_b32 v25, v34 offset:528
	ds_read_b32 v49, v34 offset:660
	ds_read_b32 v50, v34 offset:792
	ds_read_b32 v51, v34 offset:924
	s_lshl_b64 s[0:1], s[0:1], 1
	s_add_u32 s0, s2, s0
	s_addc_u32 s1, s3, s1
	v_lshl_add_u64 v[26:27], s[0:1], 0, v[2:3]
	v_lshl_add_u64 v[28:29], v[26:27], 0, v[6:7]
	s_waitcnt lgkmcnt(0)
	v_cvt_pk_bf16_f32 v22, v21, v22
	v_cvt_pk_bf16_f32 v23, v23, v24
	v_cvt_pk_bf16_f32 v24, v25, v49
	v_cvt_pk_bf16_f32 v25, v50, v51
	global_store_dwordx4 v[28:29], v[22:25], off
	ds_read_b32 v21, v34 offset:32
	ds_read_b32 v22, v34 offset:164
	ds_read_b32 v23, v34 offset:296
	ds_read_b32 v24, v34 offset:428
	ds_read_b32 v25, v34 offset:560
	ds_read_b32 v28, v34 offset:692
	ds_read_b32 v29, v34 offset:824
	ds_read_b32 v49, v34 offset:956
	v_lshl_add_u64 v[30:31], v[26:27], 0, v[8:9]
	s_waitcnt lgkmcnt(0)
	v_cvt_pk_bf16_f32 v22, v21, v22
	v_cvt_pk_bf16_f32 v23, v23, v24
	v_cvt_pk_bf16_f32 v24, v25, v28
	v_cvt_pk_bf16_f32 v25, v29, v49
	global_store_dwordx4 v[30:31], v[22:25], off
	ds_read_b32 v21, v34 offset:64
	ds_read_b32 v22, v34 offset:196
	ds_read_b32 v23, v34 offset:328
	ds_read_b32 v24, v34 offset:460
	ds_read_b32 v25, v34 offset:592
	ds_read_b32 v28, v34 offset:724
	ds_read_b32 v29, v34 offset:856
	ds_read_b32 v30, v34 offset:988
	v_lshl_add_u64 v[32:33], v[26:27], 0, v[10:11]
	s_waitcnt lgkmcnt(0)
	v_cvt_pk_bf16_f32 v22, v21, v22
	v_cvt_pk_bf16_f32 v23, v23, v24
	v_cvt_pk_bf16_f32 v24, v25, v28
	v_cvt_pk_bf16_f32 v25, v29, v30
	global_store_dwordx4 v[32:33], v[22:25], off
	ds_read_b32 v21, v34 offset:96
	ds_read_b32 v22, v34 offset:228
	ds_read_b32 v23, v34 offset:360
	ds_read_b32 v24, v34 offset:492
	ds_read_b32 v25, v34 offset:624
	ds_read_b32 v28, v34 offset:756
	ds_read_b32 v29, v34 offset:888
	ds_read_b32 v30, v34 offset:1020
	v_lshl_add_u64 v[26:27], v[26:27], 0, v[12:13]
	s_waitcnt lgkmcnt(0)
	v_cvt_pk_bf16_f32 v22, v21, v22
	v_cvt_pk_bf16_f32 v23, v23, v24
	v_cvt_pk_bf16_f32 v24, v25, v28
	v_cvt_pk_bf16_f32 v25, v29, v30
	global_store_dwordx4 v[26:27], v[22:25], off
	s_waitcnt lgkmcnt(0)
	s_add_i32 s2, s7, 0x600
	s_add_i32 s6, s6, 0xc000
	s_cmpk_lt_i32 s7, 0xfc00
	s_mov_b32 s7, s2
	s_cbranch_scc1 .LBB0_1080

; #define LAS __attribute__((address_space(3)))
; DI unsigned pk2(float lo, float hi) { typedef float v2f __attribute__((ext_vector_type(2))); typedef __bf16 v2b __attribute__((ext_vector_type(2))); v2f v = {lo, hi}; v2b b = __builtin_convertvector(v, v2b); return __builtin_bit_cast(unsigned, b); }
; DI bf16_t* dest_rows(int mode, int n0, int K, bf16_t* d0, bf16_t* d1) {
;     if (mode == 1) { const int isu = n0 >= FF ? 1 : 0, c = n0 - isu * FF; return d0 + (size_t)((c >> 7) * 256 + isu * 128 + (c & 127)) * K; }
;     ...
;         bf16_t* dst = dest_rows(mode, n0, K, d0, d1);
;         const int c = lane & 7;
; #pragma unroll
;         for (int jj = 0; jj < 4; ++jj) { const int n = (lane >> 3) + 8 * jj; const LAS float* s = scr + (8 * c) * 33 + n;
;             u32x4 o; o.x = pk2(s[0 * 33], s[1 * 33]); o.y = pk2(s[2 * 33], s[3 * 33]); o.z = pk2(s[4 * 33], s[5 * 33]); o.w = pk2(s[6 * 33], s[7 * 33]);
;             *(u32x4*)(dst + (size_t)n * K + k0 + 8 * c) = o; }
;         asm volatile("s_waitcnt lgkmcnt(0)" ::: "memory");
.LBB0_1083:
	s_mulk_i32 s16, 0xff50
	s_add_i32 s5, s14, s16
	s_cmpk_gt_i32 s5, 0x57
	s_cselect_b32 s5, 0xfffff500, 0
	s_cselect_b32 s6, 0x80, 0
	s_add_i32 s5, s5, s10
	s_add_i32 s5, s5, s15
	s_lshl_b32 s5, s5, 1
	s_and_b32 s4, s4, 0x60
	s_and_b32 s5, s5, 0xffffff00
	s_or_b32 s4, s6, s4
	s_or_b32 s4, s4, s5
	ds_write2_b32 v11, v18, v19 offset0:148 offset1:214
	s_ashr_i32 s5, s4, 31
	s_waitcnt lgkmcnt(0)
	s_lshl_b64 s[4:5], s[4:5], 11
	s_add_u32 s4, s8, s4
	ds_read_b32 v7, v34
	ds_read_b32 v9, v34 offset:132
	ds_read_b32 v11, v34 offset:264
	ds_read_b32 v13, v34 offset:396
	ds_read_b32 v18, v34 offset:528
	ds_read_b32 v19, v34 offset:660
	ds_read_b32 v22, v34 offset:792
	ds_read_b32 v23, v34 offset:924
	s_addc_u32 s5, s9, s5
	s_lshl_b64 s[0:1], s[0:1], 1
	s_add_u32 s0, s4, s0
	s_addc_u32 s1, s5, s1
	v_lshl_add_u64 v[20:21], s[0:1], 0, v[2:3]
	s_waitcnt lgkmcnt(0)
	v_cvt_pk_bf16_f32 v16, v7, v9
	v_mov_b32_e32 v7, v3
	v_cvt_pk_bf16_f32 v17, v11, v13
	v_cvt_pk_bf16_f32 v18, v18, v19
	v_cvt_pk_bf16_f32 v19, v22, v23
	v_lshl_add_u64 v[22:23], v[20:21], 0, v[6:7]
	global_store_dwordx4 v[22:23], v[16:19], off
	ds_read_b32 v7, v34 offset:32
	ds_read_b32 v9, v34 offset:164
	ds_read_b32 v11, v34 offset:296
	ds_read_b32 v13, v34 offset:428
	ds_read_b32 v18, v34 offset:560
	ds_read_b32 v19, v34 offset:692
	ds_read_b32 v22, v34 offset:824
	ds_read_b32 v23, v34 offset:956
	s_waitcnt lgkmcnt(0)
	v_cvt_pk_bf16_f32 v16, v7, v9
	v_mov_b32_e32 v9, v3
	v_cvt_pk_bf16_f32 v17, v11, v13
	v_cvt_pk_bf16_f32 v18, v18, v19
	v_cvt_pk_bf16_f32 v19, v22, v23
	v_lshl_add_u64 v[22:23], v[20:21], 0, v[8:9]
	global_store_dwordx4 v[22:23], v[16:19], off
	ds_read_b32 v7, v34 offset:64
	ds_read_b32 v9, v34 offset:196
	ds_read_b32 v11, v34 offset:328
	ds_read_b32 v13, v34 offset:460
	ds_read_b32 v18, v34 offset:592
	ds_read_b32 v19, v34 offset:724
	ds_read_b32 v22, v34 offset:856
	ds_read_b32 v23, v34 offset:988
	s_waitcnt lgkmcnt(0)
	v_cvt_pk_bf16_f32 v17, v11, v13
	v_mov_b32_e32 v11, v3
	v_cvt_pk_bf16_f32 v16, v7, v9
	v_cvt_pk_bf16_f32 v18, v18, v19
	v_cvt_pk_bf16_f32 v19, v22, v23
	v_lshl_add_u64 v[22:23], v[20:21], 0, v[10:11]
	global_store_dwordx4 v[22:23], v[16:19], off
	ds_read_b32 v7, v34 offset:96
	ds_read_b32 v9, v34 offset:228
	ds_read_b32 v11, v34 offset:360
	ds_read_b32 v13, v34 offset:492
	ds_read_b32 v18, v34 offset:624
	ds_read_b32 v19, v34 offset:756
	ds_read_b32 v22, v34 offset:888
	ds_read_b32 v23, v34 offset:1020
	s_waitcnt lgkmcnt(0)
	v_cvt_pk_bf16_f32 v17, v11, v13
	v_mov_b32_e32 v13, v3
	v_cvt_pk_bf16_f32 v16, v7, v9
	v_cvt_pk_bf16_f32 v18, v18, v19
	v_cvt_pk_bf16_f32 v19, v22, v23
	v_lshl_add_u64 v[20:21], v[20:21], 0, v[12:13]
	global_store_dwordx4 v[20:21], v[16:19], off
	s_waitcnt lgkmcnt(0)
	s_add_i32 s0, s14, 0x600
	s_add_i32 s10, s10, 0xc000
	s_cmpk_lt_i32 s14, 0x500
	s_mov_b32 s14, s0
	s_cbranch_scc0 .LBB0_1116

;     ...
;         const int kb = item / nblk, nb = nb0 + item % nblk, k0 = 64 * kb, n0 = 32 * nb;
;         float tv[32];
; #pragma unroll
;         for (int i = 0; i < 32; ++i) { const int kk = 2 * i + (lane >> 5); tv[i] = W[(size_t)(k0 + kk) * N + n0 + (lane & 31)]; }
.LBB0_1118:
	s_ashr_i32 s0, s9, 31
	s_lshr_b32 s0, s0, 27
	s_add_i32 s0, s9, s0
	s_ashr_i32 s1, s0, 5
	s_lshl_b32 s0, s1, 6
	s_lshl_b32 s1, s1, 10
	v_or_b32_e32 v14, s0, v0
	s_sub_i32 s2, s6, s1
	v_or_b32_e32 v16, 2, v14
	v_or_b32_e32 v24, 10, v14
	v_or_b32_e32 v26, 12, v14
	v_or_b32_e32 v28, 14, v14
	v_or_b32_e32 v30, 16, v14
	v_or_b32_e32 v32, 18, v14
	v_or_b32_e32 v36, 20, v14
	v_or_b32_e32 v38, 22, v14
	v_or_b32_e32 v40, 24, v14
	v_or_b32_e32 v42, 26, v14
	v_or_b32_e32 v44, 28, v14
	v_or_b32_e32 v46, 30, v14
	v_or_b32_e32 v48, 32, v14
	v_or_b32_e32 v50, 34, v14
	v_or_b32_e32 v52, 36, v14
	s_ashr_i32 s3, s2, 31
	v_ashrrev_i32_e32 v15, 31, v14
	v_or_b32_e32 v18, 4, v14
	v_or_b32_e32 v20, 6, v14
	v_or_b32_e32 v22, 8, v14
	v_or_b32_e32 v54, 38, v14
	v_or_b32_e32 v56, 40, v14
	v_or_b32_e32 v58, 42, v14
	v_or_b32_e32 v60, 44, v14
	v_or_b32_e32 v62, 46, v14
	v_or_b32_e32 v64, 48, v14
	v_or_b32_e32 v66, 50, v14
	v_or_b32_e32 v68, 52, v14
	v_or_b32_e32 v70, 54, v14
	v_or_b32_e32 v72, 56, v14
	v_or_b32_e32 v74, 58, v14
	v_or_b32_e32 v76, 60, v14
	v_or_b32_e32 v78, 62, v14
	v_ashrrev_i32_e32 v17, 31, v16
	v_ashrrev_i32_e32 v25, 31, v24
	v_ashrrev_i32_e32 v27, 31, v26
	v_ashrrev_i32_e32 v29, 31, v28
	v_ashrrev_i32_e32 v31, 31, v30
	v_ashrrev_i32_e32 v33, 31, v32
	v_ashrrev_i32_e32 v37, 31, v36
	v_ashrrev_i32_e32 v39, 31, v38
	v_ashrrev_i32_e32 v41, 31, v40
	v_ashrrev_i32_e32 v43, 31, v42
	v_ashrrev_i32_e32 v45, 31, v44
	v_ashrrev_i32_e32 v47, 31, v46
	v_ashrrev_i32_e32 v49, 31, v48
	v_ashrrev_i32_e32 v51, 31, v50
	v_ashrrev_i32_e32 v53, 31, v52
	v_lshl_add_u64 v[80:81], s[2:3], 2, v[6:7]
	v_lshlrev_b64 v[14:15], 12, v[14:15]
	v_ashrrev_i32_e32 v19, 31, v18
	v_ashrrev_i32_e32 v21, 31, v20
	v_ashrrev_i32_e32 v23, 31, v22
	v_ashrrev_i32_e32 v55, 31, v54
	v_ashrrev_i32_e32 v57, 31, v56
	v_ashrrev_i32_e32 v59, 31, v58
	v_ashrrev_i32_e32 v61, 31, v60
	v_ashrrev_i32_e32 v63, 31, v62
	v_ashrrev_i32_e32 v65, 31, v64
	v_ashrrev_i32_e32 v67, 31, v66
	v_ashrrev_i32_e32 v69, 31, v68
	v_ashrrev_i32_e32 v71, 31, v70
	v_ashrrev_i32_e32 v73, 31, v72
	v_ashrrev_i32_e32 v75, 31, v74
	v_ashrrev_i32_e32 v77, 31, v76
	v_ashrrev_i32_e32 v79, 31, v78
	v_lshlrev_b64 v[16:17], 12, v[16:17]
	v_lshlrev_b64 v[24:25], 12, v[24:25]
	v_lshlrev_b64 v[26:27], 12, v[26:27]
	v_lshlrev_b64 v[28:29], 12, v[28:29]
	v_lshlrev_b64 v[30:31], 12, v[30:31]
	v_lshlrev_b64 v[32:33], 12, v[32:33]
	v_lshlrev_b64 v[36:37], 12, v[36:37]
	v_lshlrev_b64 v[38:39], 12, v[38:39]
	v_lshlrev_b64 v[40:41], 12, v[40:41]
	v_lshlrev_b64 v[42:43], 12, v[42:43]
	v_lshlrev_b64 v[44:45], 12, v[44:45]
	v_lshlrev_b64 v[46:47], 12, v[46:47]
	v_lshlrev_b64 v[48:49], 12, v[48:49]
	v_lshlrev_b64 v[50:51], 12, v[50:51]
	v_lshlrev_b64 v[52:53], 12, v[52:53]
	v_lshl_add_u64 v[14:15], v[80:81], 0, v[14:15]
	v_lshlrev_b64 v[18:19], 12, v[18:19]
	v_lshlrev_b64 v[20:21], 12, v[20:21]
	v_lshlrev_b64 v[22:23], 12, v[22:23]
	v_lshlrev_b64 v[54:55], 12, v[54:55]
	v_lshlrev_b64 v[56:57], 12, v[56:57]
	v_lshlrev_b64 v[58:59], 12, v[58:59]
	v_lshlrev_b64 v[60:61], 12, v[60:61]
	v_lshlrev_b64 v[62:63], 12, v[62:63]
	v_lshlrev_b64 v[64:65], 12, v[64:65]
	v_lshlrev_b64 v[66:67], 12, v[66:67]
	v_lshlrev_b64 v[68:69], 12, v[68:69]
	v_lshlrev_b64 v[70:71], 12, v[70:71]
	v_lshlrev_b64 v[72:73], 12, v[72:73]
	v_lshlrev_b64 v[74:75], 12, v[74:75]
	v_lshlrev_b64 v[76:77], 12, v[76:77]
	v_lshlrev_b64 v[78:79], 12, v[78:79]
	v_lshl_add_u64 v[16:17], v[80:81], 0, v[16:17]
	v_lshl_add_u64 v[24:25], v[80:81], 0, v[24:25]
	v_lshl_add_u64 v[26:27], v[80:81], 0, v[26:27]
	v_lshl_add_u64 v[28:29], v[80:81], 0, v[28:29]
	v_lshl_add_u64 v[30:31], v[80:81], 0, v[30:31]
	v_lshl_add_u64 v[32:33], v[80:81], 0, v[32:33]
	v_lshl_add_u64 v[36:37], v[80:81], 0, v[36:37]
	v_lshl_add_u64 v[38:39], v[80:81], 0, v[38:39]
	v_lshl_add_u64 v[40:41], v[80:81], 0, v[40:41]
	v_lshl_add_u64 v[42:43], v[80:81], 0, v[42:43]
	v_lshl_add_u64 v[44:45], v[80:81], 0, v[44:45]
	v_lshl_add_u64 v[46:47], v[80:81], 0, v[46:47]
	v_lshl_add_u64 v[48:49], v[80:81], 0, v[48:49]
	v_lshl_add_u64 v[50:51], v[80:81], 0, v[50:51]
	v_lshl_add_u64 v[52:53], v[80:81], 0, v[52:53]
	v_lshl_add_u64 v[18:19], v[80:81], 0, v[18:19]
	v_lshl_add_u64 v[20:21], v[80:81], 0, v[20:21]
	v_lshl_add_u64 v[22:23], v[80:81], 0, v[22:23]
	v_lshl_add_u64 v[54:55], v[80:81], 0, v[54:55]
	v_lshl_add_u64 v[56:57], v[80:81], 0, v[56:57]
	v_lshl_add_u64 v[58:59], v[80:81], 0, v[58:59]
	v_lshl_add_u64 v[60:61], v[80:81], 0, v[60:61]
	v_lshl_add_u64 v[62:63], v[80:81], 0, v[62:63]
	v_lshl_add_u64 v[64:65], v[80:81], 0, v[64:65]
	v_lshl_add_u64 v[66:67], v[80:81], 0, v[66:67]
	v_lshl_add_u64 v[68:69], v[80:81], 0, v[68:69]
	v_lshl_add_u64 v[70:71], v[80:81], 0, v[70:71]
	v_lshl_add_u64 v[72:73], v[80:81], 0, v[72:73]
	v_lshl_add_u64 v[74:75], v[80:81], 0, v[74:75]
	v_lshl_add_u64 v[76:77], v[80:81], 0, v[76:77]
	v_lshl_add_u64 v[78:79], v[80:81], 0, v[78:79]
	global_load_dword v80, v[14:15], off
	s_nop 0
	global_load_dword v16, v[16:17], off
	s_nop 0
	global_load_dword v17, v[18:19], off
	global_load_dword v81, v[20:21], off
	global_load_dword v82, v[22:23], off
	s_nop 0
	global_load_dword v25, v[24:25], off
	s_nop 0
	global_load_dword v26, v[26:27], off
	s_nop 0
	global_load_dword v27, v[28:29], off
	s_nop 0
	global_load_dword v28, v[30:31], off
	global_load_dword v29, v[32:33], off
	s_nop 0
	global_load_dword v30, v[36:37], off
	global_load_dword v31, v[38:39], off
	global_load_dword v32, v[40:41], off
	global_load_dword v33, v[42:43], off
	s_nop 0
	global_load_dword v36, v[44:45], off
	global_load_dword v37, v[46:47], off
	global_load_dword v38, v[48:49], off
	global_load_dword v39, v[50:51], off
	global_load_dword v40, v[52:53], off
	global_load_dword v41, v[54:55], off
	global_load_dword v42, v[56:57], off
	global_load_dword v43, v[58:59], off
	global_load_dword v44, v[60:61], off
	global_load_dword v45, v[62:63], off
	global_load_dword v46, v[64:65], off
	global_load_dword v47, v[66:67], off
	global_load_dword v48, v[68:69], off
	global_load_dword v49, v[70:71], off
	global_load_dword v50, v[72:73], off
	global_load_dword v51, v[74:75], off
	global_load_dword v52, v[76:77], off
	global_load_dword v53, v[78:79], off
	s_mul_hi_i32 s1, s2, 0x1600
	s_mulk_i32 s2, 0x1600
	s_add_u32 s2, s4, s2
	s_addc_u32 s3, s5, s1
	s_ashr_i32 s1, s0, 31
	s_lshl_b64 s[0:1], s[0:1], 1
	s_add_u32 s0, s2, s0
	s_addc_u32 s1, s3, s1
	s_waitcnt vmcnt(0)
; #define LAS __attribute__((address_space(3)))
; DI unsigned pk2(float lo, float hi) { typedef float v2f __attribute__((ext_vector_type(2))); typedef __bf16 v2b __attribute__((ext_vector_type(2))); v2f v = {lo, hi}; v2b b = __builtin_convertvector(v, v2b); return __builtin_bit_cast(unsigned, b); }
;     ...
;         for (int i = 0; i < 32; ++i) { const int kk = 2 * i + (lane >> 5); float v = tv[i]; if (gk) v *= gk[k0 + kk]; scr[kk * 33 + (lane & 31)] = v; }
;         asm volatile("s_waitcnt lgkmcnt(0)" ::: "memory");
;         bf16_t* dst = dest_rows(mode, n0, K, d0, d1);
;         const int c = lane & 7;
; #pragma unroll
;         for (int jj = 0; jj < 4; ++jj) { const int n = (lane >> 3) + 8 * jj; const LAS float* s = scr + (8 * c) * 33 + n;
;             u32x4 o; o.x = pk2(s[0 * 33], s[1 * 33]); o.y = pk2(s[2 * 33], s[3 * 33]); o.z = pk2(s[4 * 33], s[5 * 33]); o.w = pk2(s[6 * 33], s[7 * 33]);
;             *(u32x4*)(dst + (size_t)n * K + k0 + 8 * c) = o; }
;         asm volatile("s_waitcnt lgkmcnt(0)" ::: "memory");
	ds_write2_b32 v35, v80, v16 offset1:66
	ds_write2_b32 v35, v17, v81 offset0:132 offset1:198
	ds_write2_b32 v1, v82, v25 offset0:8 offset1:74
	ds_write2_b32 v1, v26, v27 offset0:140 offset1:206
	ds_write2_b32 v8, v28, v29 offset0:16 offset1:82
	ds_write2_b32 v8, v30, v31 offset0:148 offset1:214
	ds_write2_b32 v9, v32, v33 offset0:24 offset1:90
	ds_write2_b32 v9, v36, v37 offset0:156 offset1:222
	ds_write2_b32 v10, v38, v39 offset0:32 offset1:98
	ds_write2_b32 v10, v40, v41 offset0:164 offset1:230
	ds_write2_b32 v11, v42, v43 offset0:40 offset1:106
	ds_write2_b32 v11, v44, v45 offset0:172 offset1:238
	ds_write2_b32 v12, v46, v47 offset0:48 offset1:114
	ds_write2_b32 v12, v48, v49 offset0:180 offset1:246
	ds_write2_b32 v13, v50, v51 offset0:56 offset1:122
	ds_write2_b32 v13, v52, v53 offset0:188 offset1:254
	v_lshl_add_u64 v[14:15], s[0:1], 0, v[2:3]
	s_waitcnt lgkmcnt(0)
	v_lshl_add_u64 v[18:19], v[14:15], 0, v[4:5]
	ds_read_b32 v14, v34
	ds_read_b32 v15, v34 offset:132
	ds_read_b32 v16, v34 offset:264
	ds_read_b32 v17, v34 offset:396
	ds_read_b32 v25, v34 offset:528
	ds_read_b32 v26, v34 offset:660
	ds_read_b32 v27, v34 offset:792
	ds_read_b32 v28, v34 offset:924
	v_add_co_u32_e32 v20, vcc, s7, v18
	s_waitcnt lgkmcnt(0)
	v_cvt_pk_bf16_f32 v14, v14, v15
	v_addc_co_u32_e32 v21, vcc, 0, v19, vcc
	v_add_co_u32_e32 v22, vcc, s8, v18
	v_cvt_pk_bf16_f32 v15, v16, v17
	v_cvt_pk_bf16_f32 v16, v25, v26
	v_cvt_pk_bf16_f32 v17, v27, v28
	v_addc_co_u32_e32 v23, vcc, 0, v19, vcc
	global_store_dwordx4 v[18:19], v[14:17], off
	v_add_co_u32_e32 v24, vcc, 0x21000, v18
	ds_read_b32 v14, v34 offset:32
	ds_read_b32 v15, v34 offset:164
	ds_read_b32 v16, v34 offset:296
	ds_read_b32 v17, v34 offset:428
	ds_read_b32 v18, v34 offset:560
	ds_read_b32 v25, v34 offset:692
	ds_read_b32 v26, v34 offset:824
	ds_read_b32 v27, v34 offset:956
	s_waitcnt lgkmcnt(0)
	v_cvt_pk_bf16_f32 v14, v14, v15
	v_cvt_pk_bf16_f32 v15, v16, v17
	v_cvt_pk_bf16_f32 v16, v18, v25
	s_add_i32 s2, s9, 0x600
	v_cvt_pk_bf16_f32 v17, v26, v27
	global_store_dwordx4 v[20:21], v[14:17], off
	ds_read_b32 v14, v34 offset:64
	ds_read_b32 v15, v34 offset:196
	ds_read_b32 v16, v34 offset:328
	ds_read_b32 v17, v34 offset:460
	ds_read_b32 v18, v34 offset:592
	ds_read_b32 v20, v34 offset:724
	ds_read_b32 v21, v34 offset:856
	ds_read_b32 v25, v34 offset:988
	s_waitcnt lgkmcnt(0)
	v_cvt_pk_bf16_f32 v14, v14, v15
	v_cvt_pk_bf16_f32 v15, v16, v17
	v_cvt_pk_bf16_f32 v16, v18, v20
	s_add_i32 s6, s6, 0xc000
	v_cvt_pk_bf16_f32 v17, v21, v25
	global_store_dwordx4 v[22:23], v[14:17], off
	ds_read_b32 v14, v34 offset:96
	ds_read_b32 v15, v34 offset:228
	ds_read_b32 v16, v34 offset:360
	ds_read_b32 v17, v34 offset:492
	ds_read_b32 v18, v34 offset:624
	ds_read_b32 v20, v34 offset:756
	ds_read_b32 v21, v34 offset:888
	ds_read_b32 v22, v34 offset:1020
	v_addc_co_u32_e32 v25, vcc, 0, v19, vcc
	s_waitcnt lgkmcnt(0)
	v_cvt_pk_bf16_f32 v14, v14, v15
	v_cvt_pk_bf16_f32 v15, v16, v17
	v_cvt_pk_bf16_f32 v16, v18, v20
	v_cvt_pk_bf16_f32 v17, v21, v22
	global_store_dwordx4 v[24:25], v[14:17], off
	s_waitcnt lgkmcnt(0)
	s_cmpk_lt_i32 s9, 0xff80
	s_mov_b32 s9, s2
	s_cbranch_scc1 .LBB0_1118

; DI unsigned pk2(float lo, float hi) { typedef float v2f __attribute__((ext_vector_type(2))); typedef __bf16 v2b __attribute__((ext_vector_type(2))); v2f v = {lo, hi}; v2b b = __builtin_convertvector(v, v2b); return __builtin_bit_cast(unsigned, b); }
; __global__ void __launch_bounds__(512, 2) fwd_mega(Args args) {
;     ...
;                 for (int idx = gw2; idx < 512 * 4; idx += ngw2) {
;                     const int row = idx >> 2, hd = idx & 3;
;                     const float a = MKV[(size_t)row * 1024 + hd * 128 + 2 * lane], b = MKV[(size_t)row * 1024 + hd * 128 + 2 * lane + 1];
;                     const float rk = __builtin_amdgcn_rsqf(wave_sum(a * a + b * b) * (1.0f / 128.0f) + EPS);
;                     ((unsigned*)(KM + (size_t)row * 512 + hd * 128))[lane] = pk2(a * rk * mkn[2 * lane], b * rk * mkn[2 * lane + 1]);
;                 }
.LBB0_1121:
	s_addk_i32 s4, 0x600
	s_ashr_i32 s6, s4, 2
	s_ashr_i32 s7, s6, 31
	s_and_b32 s10, s5, 0x180
	s_lshl_b64 s[8:9], s[6:7], 10
	s_lshl_b64 s[6:7], s[6:7], 12
	s_add_u32 s6, s0, s6
	s_addc_u32 s7, s1, s7
	s_lshl_b32 s11, s10, 2
	s_add_u32 s6, s6, s11
	s_addc_u32 s7, s7, 0
	v_lshl_add_u64 v[14:15], s[6:7], 0, v[2:3]
	global_load_dwordx2 v[14:15], v[14:15], off
	s_add_u32 s6, s2, s8
	s_addc_u32 s7, s3, s9
	s_lshl_b32 s8, s10, 1
	s_add_u32 s6, s6, s8
	s_addc_u32 s7, s7, 0
	s_add_i32 s5, s5, 0x30000
	v_lshl_add_u64 v[18:19], s[6:7], 0, v[4:5]
	s_cmpk_gt_i32 s4, 0x1ff
	s_waitcnt vmcnt(0) lgkmcnt(0)
	v_pk_mul_f32 v[16:17], v[14:15], v[14:15]
	s_nop 0
	v_add_f32_e32 v13, v16, v17
	ds_bpermute_b32 v16, v6, v13
	s_waitcnt lgkmcnt(0)
	v_add_f32_e32 v13, v13, v16
	ds_bpermute_b32 v16, v7, v13
	s_waitcnt lgkmcnt(0)
	v_add_f32_e32 v13, v13, v16
	ds_bpermute_b32 v16, v8, v13
	s_waitcnt lgkmcnt(0)
	v_add_f32_e32 v13, v13, v16
	ds_bpermute_b32 v16, v9, v13
	s_waitcnt lgkmcnt(0)
	v_add_f32_e32 v13, v13, v16
	ds_bpermute_b32 v16, v10, v13
	s_waitcnt lgkmcnt(0)
	v_add_f32_e32 v13, v13, v16
	ds_bpermute_b32 v16, v11, v13
	s_waitcnt lgkmcnt(0)
	v_add_f32_e32 v13, v13, v16
	v_fmamk_f32 v13, v13, 0x3c000000, v12
	v_rsq_f32_e32 v16, v13
	s_nop 0
	v_pk_mul_f32 v[14:15], v[14:15], v[16:17] op_sel_hi:[1,0]
	s_nop 0
	v_pk_mul_f32 v[14:15], v[0:1], v[14:15]
	s_nop 0
	v_cvt_pk_bf16_f32 v13, v14, v15
	global_store_dword v[18:19], v13, off
	s_cbranch_scc0 .LBB0_1121

; DI unsigned f2bf(float f) { unsigned u = __builtin_bit_cast(unsigned, f); return (u + 0x7fffu + ((u >> 16) & 1u)) >> 16; }
; __global__ void __launch_bounds__(512, 2) fwd_mega(Args args) {
;     ...
;                 for (int i = (bx - 64) * 512 + tid; i < 2 * 4 * 128 * 256; i += 192 * 512) { const int m = i & 255, d = (i >> 8) & 127, hd = (i >> 15) & 3, b = i >> 17;
;                     VMT[i] = (bf16_t)f2bf(MKV[(size_t)(b * 256 + m) * 1024 + 512 + hd * 128 + d]); }
.LBB0_1125:
	v_lshrrev_b32_e32 v16, 9, v8
	v_lshrrev_b32_e32 v6, 8, v8
	v_lshrrev_b32_e32 v14, 9, v9
	v_and_b32_e32 v16, 0x7fff00, v16
	v_and_b32_e32 v14, 0x7fff00, v14
	v_and_b32_e32 v18, 0x180, v6
	v_or_b32_e32 v6, v16, v2
	v_lshrrev_b32_e32 v1, 8, v9
	v_mov_b32_e32 v15, v7
	v_or_b32_e32 v14, v14, v3
	v_lshlrev_b64 v[16:17], 12, v[6:7]
	v_and_b32_e32 v1, 0x180, v1
	v_lshlrev_b64 v[14:15], 12, v[14:15]
	v_lshlrev_b32_e32 v6, 2, v18
	v_lshl_add_u64 v[16:17], s[2:3], 0, v[16:17]
	v_lshl_add_u64 v[14:15], s[2:3], 0, v[14:15]
	v_lshl_add_u64 v[16:17], v[16:17], 0, v[6:7]
	v_lshlrev_b32_e32 v6, 2, v1
	v_lshl_add_u64 v[14:15], v[14:15], 0, v[6:7]
	v_lshl_add_u64 v[16:17], v[16:17], 0, v[4:5]
	v_lshl_add_u64 v[14:15], v[14:15], 0, v[4:5]
	global_load_dword v1, v[16:17], off
	global_load_dword v18, v[14:15], off
	v_mov_b32_e32 v6, v8
	v_add_u32_e32 v13, -2, v13
	v_lshl_add_u64 v[14:15], v[6:7], 1, s[6:7]
	v_mov_b32_e32 v6, v9
	v_cmp_eq_u32_e32 vcc, 0, v13
	v_lshl_add_u64 v[16:17], v[6:7], 1, s[6:7]
	s_or_b64 s[8:9], vcc, s[8:9]
	v_add_u32_e32 v8, 0x30000, v8
	v_add_u32_e32 v9, 0x30000, v9
	s_waitcnt vmcnt(0) lgkmcnt(0)
	v_and_b32_sdwa v6, v1, v12 dst_sel:DWORD dst_unused:UNUSED_PAD src0_sel:WORD_1 src1_sel:DWORD
	v_and_b32_sdwa v19, v18, v12 dst_sel:DWORD dst_unused:UNUSED_PAD src0_sel:WORD_1 src1_sel:DWORD
	v_add3_u32 v1, v1, v6, s10
	v_add3_u32 v6, v18, v19, s10
	global_store_short_d16_hi v[14:15], v1, off
	global_store_short_d16_hi v[16:17], v6, off
	s_andn2_b64 exec, exec, s[8:9]
	s_cbranch_execnz .LBB0_1125
	s_or_b64 exec, exec, s[8:9]
	v_cmp_ne_u32_e32 vcc, v11, v10
	s_mov_b64 s[6:7], 0
	s_and_saveexec_b64 s[8:9], vcc
	s_mov_b32 s10, 0x18000
	v_mad_u32_u24 v0, v10, s10, v0
	s_mov_b64 s[6:7], exec
	v_lshrrev_b32_e32 v3, 8, v0
	s_or_b64 exec, exec, s[8:9]
	s_orn2_b64 s[6:7], s[6:7], exec

; DI unsigned f2bf(float f) { unsigned u = __builtin_bit_cast(unsigned, f); return (u + 0x7fffu + ((u >> 16) & 1u)) >> 16; }
; __global__ void __launch_bounds__(512, 2) fwd_mega(Args args) {
;     ...
;                 for (int i = (bx - 64) * 512 + tid; i < 2 * 4 * 128 * 256; i += 192 * 512) { const int m = i & 255, d = (i >> 8) & 127, hd = (i >> 15) & 3, b = i >> 17;
;                     VMT[i] = (bf16_t)f2bf(MKV[(size_t)(b * 256 + m) * 1024 + 512 + hd * 128 + d]); }
.LBB0_1131:
	v_and_or_b32 v0, v9, s8, v2
	v_and_b32_e32 v12, 0x180, v3
	v_lshlrev_b64 v[10:11], 12, v[0:1]
	v_lshlrev_b32_e32 v0, 2, v12
	v_lshl_add_u64 v[10:11], s[2:3], 0, v[10:11]
	v_lshl_add_u64 v[10:11], v[10:11], 0, v[0:1]
	v_lshl_add_u64 v[10:11], v[10:11], 0, v[4:5]
	global_load_dword v0, v[10:11], off
	v_add_u32_e32 v8, 0x18000, v8
	v_cmp_lt_i32_e32 vcc, s10, v8
	v_add_u32_e32 v3, 0x180, v3
	v_add_u32_e32 v9, 0xc0, v9
	s_or_b64 s[4:5], vcc, s[4:5]
	s_waitcnt vmcnt(0) lgkmcnt(0)
	v_bfe_u32 v10, v0, 16, 1
	v_add3_u32 v0, v0, v10, s9
	global_store_short_d16_hi v[6:7], v0, off
	v_lshl_add_u64 v[6:7], v[6:7], 0, s[6:7]
	s_andn2_b64 exec, exec, s[4:5]
	s_cbranch_execnz .LBB0_1131

; DI unsigned pk2(float lo, float hi) { typedef float v2f __attribute__((ext_vector_type(2))); typedef __bf16 v2b __attribute__((ext_vector_type(2))); v2f v = {lo, hi}; v2b b = __builtin_convertvector(v, v2b); return __builtin_bit_cast(unsigned, b); }
;     DI void operator()(const f32x4 (&acc)[2][2][4][2], const Unit& u, int wr, int wc, int fr, int fq) const {
;         const int row0 = u.pm * 256 + wr * 64 + fr, cw = u.pn * 256 + wc * 32 + 8 * fq;
; #pragma unroll
;         for (int ai = 0; ai < 2; ++ai)
; #pragma unroll
;             for (int m = 0; m < 4; ++m) {
;                 const int row = row0 + ai * 128 + m * 16; const float rs = row_rstd<1>(P, row, 1.0f / 384.0f);
; #pragma unroll
;                 for (int bj = 0; bj < 2; ++bj) {
;                     const f32x4 a = acc[ai][bj][m][0] * rs, b = acc[ai][bj][m][1] * rs;
;                     u32x4 w; w.x = pk2(a[0], a[1]); w.y = pk2(a[2], a[3]); w.z = pk2(b[0], b[1]); w.w = pk2(b[2], b[3]);
;                     *(u32x4*)(O + (size_t)row * 768 + cw + bj * 128) = w;
;                 }
.LBB0_1205:
	v_lshl_add_u32 v148, s68, 8, v161
	v_ashrrev_i32_e32 v149, 31, v148
	v_lshl_add_u64 v[152:153], v[148:149], 2, s[18:19]
	global_load_dword v198, v[152:153], off
	global_load_dword v199, v[152:153], off offset:64
	global_load_dword v200, v[152:153], off offset:128
	global_load_dword v201, v[152:153], off offset:192
	global_load_dword v202, v[152:153], off offset:512
	global_load_dword v203, v[152:153], off offset:576
	global_load_dword v204, v[152:153], off offset:640
	global_load_dword v205, v[152:153], off offset:704
	v_lshl_or_b32 v154, s69, 8, v170
	v_mov_b64_e32 v[150:151], s[20:21]
	v_ashrrev_i32_e32 v155, 31, v154
	v_mad_i64_i32 v[176:177], s[42:43], v148, s61, v[150:151]
	v_or_b32_e32 v178, 16, v148
	v_lshlrev_b64 v[154:155], 1, v[154:155]
	v_ashrrev_i32_e32 v179, 31, v178
	v_lshl_add_u64 v[176:177], v[176:177], 0, v[154:155]
	v_lshl_add_u64 v[182:183], v[178:179], 2, s[18:19]
	s_and_b64 vcc, exec, s[2:3]
	s_waitcnt vmcnt(0) lgkmcnt(0)
	v_fmamk_f32 v149, v198, 0x3b2aaaab, v174
	v_rsq_f32_e32 v180, v149
	s_nop 0
	v_pk_mul_f32 v[122:123], v[122:123], v[180:181] op_sel_hi:[1,0]
	v_pk_mul_f32 v[120:121], v[120:121], v[180:181] op_sel_hi:[1,0]
	v_pk_mul_f32 v[126:127], v[126:127], v[180:181] op_sel_hi:[1,0]
	v_pk_mul_f32 v[124:125], v[124:125], v[180:181] op_sel_hi:[1,0]
	v_pk_mul_f32 v[118:119], v[118:119], v[180:181] op_sel_hi:[1,0]
	v_pk_mul_f32 v[116:117], v[116:117], v[180:181] op_sel_hi:[1,0]
	v_pk_mul_f32 v[184:185], v[114:115], v[180:181] op_sel_hi:[1,0]
	v_pk_mul_f32 v[180:181], v[112:113], v[180:181] op_sel_hi:[1,0]
	v_cvt_pk_bf16_f32 v112, v120, v121
	v_cvt_pk_bf16_f32 v113, v122, v123
	v_cvt_pk_bf16_f32 v114, v124, v125
	v_cvt_pk_bf16_f32 v115, v126, v127
	v_cvt_pk_bf16_f32 v116, v116, v117
	v_cvt_pk_bf16_f32 v117, v118, v119
	v_cvt_pk_bf16_f32 v118, v180, v181
	v_cvt_pk_bf16_f32 v119, v184, v185
	global_store_dwordx4 v[176:177], v[112:115], off
	global_store_dwordx4 v[176:177], v[116:119], off offset:256
	s_nop 0
	v_or_b32_e32 v112, 32, v148
	v_mad_i64_i32 v[114:115], s[42:43], v178, s61, v[150:151]
	v_lshl_add_u64 v[114:115], v[114:115], 0, v[154:155]
	s_waitcnt lgkmcnt(0)
	v_fmamk_f32 v113, v199, 0x3b2aaaab, v174
	v_rsq_f32_e32 v116, v113
	v_ashrrev_i32_e32 v113, 31, v112
	v_lshl_add_u64 v[118:119], v[112:113], 2, s[18:19]
	v_pk_mul_f32 v[110:111], v[110:111], v[116:117] op_sel_hi:[1,0]
	v_pk_mul_f32 v[108:109], v[108:109], v[116:117] op_sel_hi:[1,0]
	v_pk_mul_f32 v[106:107], v[106:107], v[116:117] op_sel_hi:[1,0]
	v_pk_mul_f32 v[104:105], v[104:105], v[116:117] op_sel_hi:[1,0]
	v_pk_mul_f32 v[102:103], v[102:103], v[116:117] op_sel_hi:[1,0]
	v_pk_mul_f32 v[100:101], v[100:101], v[116:117] op_sel_hi:[1,0]
	v_pk_mul_f32 v[120:121], v[98:99], v[116:117] op_sel_hi:[1,0]
	v_pk_mul_f32 v[116:117], v[96:97], v[116:117] op_sel_hi:[1,0]
	v_cvt_pk_bf16_f32 v96, v108, v109
	v_cvt_pk_bf16_f32 v97, v110, v111
	v_cvt_pk_bf16_f32 v98, v104, v105
	v_cvt_pk_bf16_f32 v99, v106, v107
	v_cvt_pk_bf16_f32 v100, v100, v101
	v_cvt_pk_bf16_f32 v101, v102, v103
	v_cvt_pk_bf16_f32 v102, v116, v117
	v_cvt_pk_bf16_f32 v103, v120, v121
	global_store_dwordx4 v[114:115], v[96:99], off
	global_store_dwordx4 v[114:115], v[100:103], off offset:256
	s_nop 0
	v_or_b32_e32 v96, 48, v148
	v_mad_i64_i32 v[98:99], s[42:43], v112, s61, v[150:151]
	v_lshl_add_u64 v[98:99], v[98:99], 0, v[154:155]
	s_waitcnt lgkmcnt(0)
	v_fmamk_f32 v97, v200, 0x3b2aaaab, v174
	v_rsq_f32_e32 v100, v97
	v_ashrrev_i32_e32 v97, 31, v96
	v_lshl_add_u64 v[102:103], v[96:97], 2, s[18:19]
	v_pk_mul_f32 v[94:95], v[94:95], v[100:101] op_sel_hi:[1,0]
	v_pk_mul_f32 v[92:93], v[92:93], v[100:101] op_sel_hi:[1,0]
	v_pk_mul_f32 v[90:91], v[90:91], v[100:101] op_sel_hi:[1,0]
	v_pk_mul_f32 v[88:89], v[88:89], v[100:101] op_sel_hi:[1,0]
	v_pk_mul_f32 v[86:87], v[86:87], v[100:101] op_sel_hi:[1,0]
	v_pk_mul_f32 v[84:85], v[84:85], v[100:101] op_sel_hi:[1,0]
	v_pk_mul_f32 v[104:105], v[82:83], v[100:101] op_sel_hi:[1,0]
	v_pk_mul_f32 v[100:101], v[80:81], v[100:101] op_sel_hi:[1,0]
	v_cvt_pk_bf16_f32 v80, v92, v93
	v_cvt_pk_bf16_f32 v81, v94, v95
	v_cvt_pk_bf16_f32 v82, v88, v89
	v_cvt_pk_bf16_f32 v83, v90, v91
	v_cvt_pk_bf16_f32 v84, v84, v85
	v_cvt_pk_bf16_f32 v85, v86, v87
	v_cvt_pk_bf16_f32 v86, v100, v101
	v_cvt_pk_bf16_f32 v87, v104, v105
	global_store_dwordx4 v[98:99], v[80:83], off
	global_store_dwordx4 v[98:99], v[84:87], off offset:256
	s_nop 0
	v_mad_i64_i32 v[82:83], s[42:43], v96, s61, v[150:151]
	v_lshl_add_u64 v[82:83], v[82:83], 0, v[154:155]
	s_waitcnt lgkmcnt(0)
; DI unsigned pk2(float lo, float hi) { typedef float v2f __attribute__((ext_vector_type(2))); typedef __bf16 v2b __attribute__((ext_vector_type(2))); v2f v = {lo, hi}; v2b b = __builtin_convertvector(v, v2b); return __builtin_bit_cast(unsigned, b); }
;     DI void operator()(const f32x4 (&acc)[2][2][4][2], const Unit& u, int wr, int wc, int fr, int fq) const {
;         const int row0 = u.pm * 256 + wr * 64 + fr, cw = u.pn * 256 + wc * 32 + 8 * fq;
; #pragma unroll
;         for (int ai = 0; ai < 2; ++ai)
; #pragma unroll
;             for (int m = 0; m < 4; ++m) {
;                 const int row = row0 + ai * 128 + m * 16; const float rs = row_rstd<1>(P, row, 1.0f / 384.0f);
; #pragma unroll
;                 for (int bj = 0; bj < 2; ++bj) {
;                     const f32x4 a = acc[ai][bj][m][0] * rs, b = acc[ai][bj][m][1] * rs;
;                     u32x4 w; w.x = pk2(a[0], a[1]); w.y = pk2(a[2], a[3]); w.z = pk2(b[0], b[1]); w.w = pk2(b[2], b[3]);
;                     *(u32x4*)(O + (size_t)row * 768 + cw + bj * 128) = w;
;                 }
	v_fmamk_f32 v80, v201, 0x3b2aaaab, v174
	v_rsq_f32_e32 v80, v80
	s_nop 0
	v_pk_mul_f32 v[78:79], v[78:79], v[80:81] op_sel_hi:[1,0]
	v_pk_mul_f32 v[76:77], v[76:77], v[80:81] op_sel_hi:[1,0]
	v_pk_mul_f32 v[74:75], v[74:75], v[80:81] op_sel_hi:[1,0]
	v_pk_mul_f32 v[72:73], v[72:73], v[80:81] op_sel_hi:[1,0]
	v_pk_mul_f32 v[70:71], v[70:71], v[80:81] op_sel_hi:[1,0]
	v_pk_mul_f32 v[68:69], v[68:69], v[80:81] op_sel_hi:[1,0]
	v_pk_mul_f32 v[84:85], v[66:67], v[80:81] op_sel_hi:[1,0]
	v_pk_mul_f32 v[80:81], v[64:65], v[80:81] op_sel_hi:[1,0]
	v_cvt_pk_bf16_f32 v64, v76, v77
	v_cvt_pk_bf16_f32 v65, v78, v79
	v_cvt_pk_bf16_f32 v66, v72, v73
	v_cvt_pk_bf16_f32 v67, v74, v75
	v_cvt_pk_bf16_f32 v68, v68, v69
	v_cvt_pk_bf16_f32 v69, v70, v71
	v_cvt_pk_bf16_f32 v70, v80, v81
	v_cvt_pk_bf16_f32 v71, v84, v85
	global_store_dwordx4 v[82:83], v[64:67], off
	global_store_dwordx4 v[82:83], v[68:71], off offset:256
	s_nop 0
	v_add_u32_e32 v65, 0x80, v148
	v_mad_i64_i32 v[66:67], s[42:43], v65, s61, v[150:151]
	v_lshl_add_u64 v[66:67], v[66:67], 0, v[154:155]
	s_waitcnt lgkmcnt(0)
	v_fmamk_f32 v64, v202, 0x3b2aaaab, v174
	v_rsq_f32_e32 v64, v64
	s_nop 0
	v_pk_mul_f32 v[62:63], v[62:63], v[64:65] op_sel_hi:[1,0]
	v_pk_mul_f32 v[60:61], v[60:61], v[64:65] op_sel_hi:[1,0]
	v_pk_mul_f32 v[58:59], v[58:59], v[64:65] op_sel_hi:[1,0]
	v_pk_mul_f32 v[56:57], v[56:57], v[64:65] op_sel_hi:[1,0]
	v_pk_mul_f32 v[54:55], v[54:55], v[64:65] op_sel_hi:[1,0]
	v_pk_mul_f32 v[52:53], v[52:53], v[64:65] op_sel_hi:[1,0]
	v_pk_mul_f32 v[68:69], v[50:51], v[64:65] op_sel_hi:[1,0]
	v_pk_mul_f32 v[64:65], v[48:49], v[64:65] op_sel_hi:[1,0]
	v_cvt_pk_bf16_f32 v48, v60, v61
	v_cvt_pk_bf16_f32 v49, v62, v63
	v_cvt_pk_bf16_f32 v50, v56, v57
	v_cvt_pk_bf16_f32 v51, v58, v59
	v_cvt_pk_bf16_f32 v52, v52, v53
	v_cvt_pk_bf16_f32 v53, v54, v55
	v_cvt_pk_bf16_f32 v54, v64, v65
	v_cvt_pk_bf16_f32 v55, v68, v69
	global_store_dwordx4 v[66:67], v[48:51], off
	global_store_dwordx4 v[66:67], v[52:55], off offset:256
	s_nop 0
	v_add_u32_e32 v49, 0x90, v148
	v_mad_i64_i32 v[50:51], s[42:43], v49, s61, v[150:151]
	v_lshl_add_u64 v[50:51], v[50:51], 0, v[154:155]
	s_waitcnt lgkmcnt(0)
	v_fmamk_f32 v48, v203, 0x3b2aaaab, v174
	v_rsq_f32_e32 v48, v48
	s_nop 0
	v_pk_mul_f32 v[46:47], v[46:47], v[48:49] op_sel_hi:[1,0]
	v_pk_mul_f32 v[44:45], v[44:45], v[48:49] op_sel_hi:[1,0]
	v_pk_mul_f32 v[42:43], v[42:43], v[48:49] op_sel_hi:[1,0]
	v_pk_mul_f32 v[40:41], v[40:41], v[48:49] op_sel_hi:[1,0]
	v_pk_mul_f32 v[38:39], v[38:39], v[48:49] op_sel_hi:[1,0]
	v_pk_mul_f32 v[36:37], v[36:37], v[48:49] op_sel_hi:[1,0]
	v_pk_mul_f32 v[52:53], v[34:35], v[48:49] op_sel_hi:[1,0]
	v_pk_mul_f32 v[48:49], v[32:33], v[48:49] op_sel_hi:[1,0]
	v_cvt_pk_bf16_f32 v32, v44, v45
	v_cvt_pk_bf16_f32 v33, v46, v47
	v_cvt_pk_bf16_f32 v34, v40, v41
	v_cvt_pk_bf16_f32 v35, v42, v43
	v_cvt_pk_bf16_f32 v36, v36, v37
	v_cvt_pk_bf16_f32 v37, v38, v39
	v_cvt_pk_bf16_f32 v38, v48, v49
	v_cvt_pk_bf16_f32 v39, v52, v53
	global_store_dwordx4 v[50:51], v[32:35], off
	global_store_dwordx4 v[50:51], v[36:39], off offset:256
	s_nop 0
	v_add_u32_e32 v33, 0xa0, v148
	v_mad_i64_i32 v[34:35], s[42:43], v33, s61, v[150:151]
	v_lshl_add_u64 v[34:35], v[34:35], 0, v[154:155]
	s_waitcnt lgkmcnt(0)
	v_fmamk_f32 v32, v204, 0x3b2aaaab, v174
	v_rsq_f32_e32 v32, v32
	s_nop 0
	v_pk_mul_f32 v[30:31], v[30:31], v[32:33] op_sel_hi:[1,0]
	v_pk_mul_f32 v[28:29], v[28:29], v[32:33] op_sel_hi:[1,0]
	v_pk_mul_f32 v[26:27], v[26:27], v[32:33] op_sel_hi:[1,0]
	v_pk_mul_f32 v[24:25], v[24:25], v[32:33] op_sel_hi:[1,0]
	v_pk_mul_f32 v[22:23], v[22:23], v[32:33] op_sel_hi:[1,0]
	v_pk_mul_f32 v[20:21], v[20:21], v[32:33] op_sel_hi:[1,0]
	v_pk_mul_f32 v[36:37], v[18:19], v[32:33] op_sel_hi:[1,0]
	v_pk_mul_f32 v[32:33], v[16:17], v[32:33] op_sel_hi:[1,0]
	v_cvt_pk_bf16_f32 v16, v28, v29
	v_cvt_pk_bf16_f32 v17, v30, v31
	v_cvt_pk_bf16_f32 v18, v24, v25
	v_cvt_pk_bf16_f32 v19, v26, v27
	v_cvt_pk_bf16_f32 v20, v20, v21
	v_cvt_pk_bf16_f32 v21, v22, v23
	v_cvt_pk_bf16_f32 v22, v32, v33
	v_cvt_pk_bf16_f32 v23, v36, v37
	global_store_dwordx4 v[34:35], v[16:19], off
	global_store_dwordx4 v[34:35], v[20:23], off offset:256
	s_nop 0
	v_add_u32_e32 v17, 0xb0, v148
	v_mad_i64_i32 v[18:19], s[2:3], v17, s61, v[150:151]
	v_lshl_add_u64 v[18:19], v[18:19], 0, v[154:155]
	s_mov_b64 s[2:3], -1
	s_waitcnt lgkmcnt(0)
	v_fmamk_f32 v16, v205, 0x3b2aaaab, v174
	v_rsq_f32_e32 v16, v16
	s_nop 0
	v_pk_mul_f32 v[14:15], v[14:15], v[16:17] op_sel_hi:[1,0]
	v_pk_mul_f32 v[12:13], v[12:13], v[16:17] op_sel_hi:[1,0]
	v_pk_mul_f32 v[10:11], v[10:11], v[16:17] op_sel_hi:[1,0]
	v_pk_mul_f32 v[8:9], v[8:9], v[16:17] op_sel_hi:[1,0]
	v_pk_mul_f32 v[6:7], v[6:7], v[16:17] op_sel_hi:[1,0]
	v_pk_mul_f32 v[4:5], v[4:5], v[16:17] op_sel_hi:[1,0]
	v_pk_mul_f32 v[20:21], v[2:3], v[16:17] op_sel_hi:[1,0]
	v_pk_mul_f32 v[16:17], v[0:1], v[16:17] op_sel_hi:[1,0]
	v_cvt_pk_bf16_f32 v0, v12, v13
	v_cvt_pk_bf16_f32 v1, v14, v15
	v_cvt_pk_bf16_f32 v2, v8, v9
	v_cvt_pk_bf16_f32 v3, v10, v11
	v_cvt_pk_bf16_f32 v4, v4, v5
	v_cvt_pk_bf16_f32 v5, v6, v7
	v_cvt_pk_bf16_f32 v6, v16, v17
	v_cvt_pk_bf16_f32 v7, v20, v21
	global_store_dwordx4 v[18:19], v[0:3], off
	global_store_dwordx4 v[18:19], v[4:7], off offset:256
	s_cbranch_vccnz .LBB0_1193
	s_andn2_b64 vcc, exec, s[16:17]
	s_cbranch_vccnz .LBB0_1192
	s_barrier
	s_branch .LBB0_1192

; DI unsigned f2bf(float f) { unsigned u = __builtin_bit_cast(unsigned, f); return (u + 0x7fffu + ((u >> 16) & 1u)) >> 16; }
; DI unsigned pk2(float lo, float hi) { typedef float v2f __attribute__((ext_vector_type(2))); typedef __bf16 v2b __attribute__((ext_vector_type(2))); v2f v = {lo, hi}; v2b b = __builtin_convertvector(v, v2b); return __builtin_bit_cast(unsigned, b); }
;     DI void operator()(const f32x4 (&acc)[2][2][4][2], const Unit& u, int wr, int wc, int fr, int fq) const {
;         const int row0 = u.pm * 256 + wr * 64 + fr;
; #pragma unroll
;         for (int ai = 0; ai < 2; ++ai)
; #pragma unroll
;             for (int m = 0; m < 4; ++m) {
;                 const int row = row0 + ai * 128 + m * 16; const float rs = row_rstd<1>(P, row, 1.0f / 256.0f);
;                 const int b = row >> 13, s = row & 8191;
; #pragma unroll
;                 for (int bj = 0; bj < 2; ++bj) {
;                     const int h = u.pn * 2 + bj;
;                     const f32x4 a = acc[ai][bj][m][0] * rs, c = acc[ai][bj][m][1] * rs;
;                     if (wc < 2) {
;                         u32x4 w; w.x = pk2(a[0], a[1]); w.y = pk2(a[2], a[3]); w.z = pk2(c[0], c[1]); w.w = pk2(c[2], c[3]);
;                         *(u32x4*)(KN + (size_t)row * 512 + h * 64 + wc * 32 + 8 * fq) = w;
;                     } else {
;                         const unsigned vo = (unsigned)((b * 8 + h) * 64 + (wc - 2) * 32 + 8 * fq) * (unsigned)SEQ + (unsigned)s;
; #pragma unroll
;                         for (int i = 0; i < 4; ++i) { Vt[vo + (unsigned)(i * SEQ)] = (bf16_t)f2bf(a[i]); Vt[vo + (unsigned)((4 + i) * SEQ)] = (bf16_t)f2bf(c[i]); }
;                     }
.LBB0_1233:
	s_lshl_b32 s4, s14, 8
	s_add_i32 s12, s4, s68
	v_or_b32_e32 v152, s12, v129
	v_ashrrev_i32_e32 v153, 31, v152
	v_lshl_add_u64 v[154:155], v[152:153], 2, s[18:19]
	global_load_dword v198, v[154:155], off
	global_load_dword v199, v[154:155], off offset:64
	global_load_dword v200, v[154:155], off offset:128
	global_load_dword v201, v[154:155], off offset:192
	global_load_dword v202, v[154:155], off offset:512
	global_load_dword v203, v[154:155], off offset:576
	global_load_dword v204, v[154:155], off offset:640
	global_load_dword v205, v[154:155], off offset:704
	s_lshr_b32 s12, s12, 10
	s_lshl_b32 s51, s60, 1
	s_mov_b64 s[4:5], -1
	s_and_b64 vcc, exec, s[42:43]
	s_and_b32 s52, s12, 0x1ff8
	v_and_or_b32 v168, v152, s75, v163
	s_waitcnt vmcnt(0) lgkmcnt(0)
	v_fmamk_f32 v140, v198, 0x3b800000, v167
	v_rsq_f32_e32 v156, v140
	s_nop 0
	v_pk_mul_f32 v[122:123], v[122:123], v[156:157] op_sel_hi:[1,0]
	v_pk_mul_f32 v[158:159], v[120:121], v[156:157] op_sel_hi:[1,0]
	v_pk_mul_f32 v[126:127], v[126:127], v[156:157] op_sel_hi:[1,0]
	v_pk_mul_f32 v[124:125], v[124:125], v[156:157] op_sel_hi:[1,0]
	s_cbranch_vccz .LBB0_1235
	s_add_i32 s4, s52, s51
	v_lshl_add_u32 v140, s4, 19, v168
	v_bfe_u32 v120, v158, 16, 1
	v_add3_u32 v157, v158, v120, s76
	v_lshl_add_u64 v[120:121], v[140:141], 1, s[22:23]
	global_store_short_d16_hi v[120:121], v157, off
	v_bfe_u32 v120, v124, 16, 1
	v_add3_u32 v157, v124, v120, s76
	v_or_b32_e32 v120, 0x8000, v140
	v_mov_b32_e32 v121, v141
	v_lshl_add_u64 v[120:121], v[120:121], 1, s[22:23]
	global_store_short_d16_hi v[120:121], v157, off
	v_bfe_u32 v120, v159, 16, 1
	v_add3_u32 v157, v159, v120, s76
	v_or_b32_e32 v120, 0x2000, v140
	v_mov_b32_e32 v121, v141
	v_lshl_add_u64 v[120:121], v[120:121], 1, s[22:23]
	global_store_short_d16_hi v[120:121], v157, off
	v_bfe_u32 v120, v125, 16, 1
	v_add3_u32 v157, v125, v120, s76
	v_or_b32_e32 v120, 0xa000, v140
	v_mov_b32_e32 v121, v141
	v_lshl_add_u64 v[120:121], v[120:121], 1, s[22:23]
	global_store_short_d16_hi v[120:121], v157, off
	v_bfe_u32 v120, v122, 16, 1
	v_add3_u32 v157, v122, v120, s76
	v_or_b32_e32 v120, 0x4000, v140
	v_mov_b32_e32 v121, v141
	v_lshl_add_u64 v[120:121], v[120:121], 1, s[22:23]
	global_store_short_d16_hi v[120:121], v157, off
	v_bfe_u32 v120, v126, 16, 1
	v_add3_u32 v157, v126, v120, s76
	v_or_b32_e32 v120, 0xc000, v140
	v_mov_b32_e32 v121, v141
	v_lshl_add_u64 v[120:121], v[120:121], 1, s[22:23]
	global_store_short_d16_hi v[120:121], v157, off
	v_bfe_u32 v120, v123, 16, 1
	v_add3_u32 v157, v123, v120, s76
	v_or_b32_e32 v120, 0x6000, v140
	v_mov_b32_e32 v121, v141
	v_lshl_add_u64 v[120:121], v[120:121], 1, s[22:23]
	global_store_short_d16_hi v[120:121], v157, off
	v_bfe_u32 v120, v127, 16, 1
	v_or_b32_e32 v140, 0xe000, v140
	v_add3_u32 v157, v127, v120, s76
	v_lshl_add_u64 v[120:121], v[140:141], 1, s[22:23]
	global_store_short_d16_hi v[120:121], v157, off
	s_mov_b64 s[4:5], 0
.LBB0_1235:
	v_lshlrev_b64 v[120:121], 10, v[152:153]
	s_andn2_b64 vcc, exec, s[4:5]
	v_lshl_add_u64 v[120:121], s[20:21], 0, v[120:121]
	v_lshlrev_b32_e32 v140, 1, v142
	s_cbranch_vccnz .LBB0_1237
	s_lshl_b32 s4, s60, 7
	s_ashr_i32 s5, s4, 31
	v_cvt_pk_bf16_f32 v171, v122, v123
	v_lshl_add_u64 v[122:123], s[4:5], 1, v[120:121]
	s_lshl_b32 s14, s69, 1
	v_lshl_add_u64 v[122:123], v[122:123], 0, s[14:15]
	v_cvt_pk_bf16_f32 v170, v158, v159
	v_cvt_pk_bf16_f32 v172, v124, v125
	v_cvt_pk_bf16_f32 v173, v126, v127
	v_lshl_add_u64 v[122:123], v[122:123], 0, v[140:141]
	global_store_dwordx4 v[122:123], v[170:173], off
.LBB0_1237:
	v_mov_b32_e32 v122, v156
	v_mov_b32_e32 v123, v156
	v_mov_b32_e32 v157, v156
	v_pk_mul_f32 v[118:119], v[118:119], v[122:123]
	v_pk_mul_f32 v[114:115], v[114:115], v[122:123]
	v_cndmask_b32_e64 v122, 0, 1, s[42:43]
	s_or_b32 s50, s51, 1
	v_pk_mul_f32 v[116:117], v[116:117], v[156:157]
	v_pk_mul_f32 v[112:113], v[112:113], v[156:157]
	v_cmp_ne_u32_e64 s[4:5], 1, v122
	s_andn2_b64 vcc, exec, s[42:43]
	s_mov_b64 s[12:13], -1
	s_cbranch_vccnz .LBB0_1239
	s_add_i32 s12, s52, s50
	v_bfe_u32 v123, v116, 16, 1
	v_lshl_add_u32 v122, s12, 19, v168
	v_add3_u32 v126, v116, v123, s76
	v_mov_b32_e32 v123, v141
	v_lshl_add_u64 v[124:125], v[122:123], 1, s[22:23]
	global_store_short_d16_hi v[124:125], v126, off
	v_bfe_u32 v123, v112, 16, 1
	v_or_b32_e32 v124, 0x8000, v122
	v_mov_b32_e32 v125, v141
	v_add3_u32 v123, v112, v123, s76
	v_lshl_add_u64 v[124:125], v[124:125], 1, s[22:23]
	global_store_short_d16_hi v[124:125], v123, off
	v_bfe_u32 v123, v117, 16, 1
	v_or_b32_e32 v124, 0x2000, v122
	v_mov_b32_e32 v125, v141
	v_add3_u32 v123, v117, v123, s76
	v_lshl_add_u64 v[124:125], v[124:125], 1, s[22:23]
	global_store_short_d16_hi v[124:125], v123, off
	v_bfe_u32 v123, v113, 16, 1
	v_or_b32_e32 v124, 0xa000, v122
	v_mov_b32_e32 v125, v141
	v_add3_u32 v123, v113, v123, s76
	v_lshl_add_u64 v[124:125], v[124:125], 1, s[22:23]
	global_store_short_d16_hi v[124:125], v123, off
	v_bfe_u32 v123, v118, 16, 1
	v_or_b32_e32 v124, 0x4000, v122
	v_mov_b32_e32 v125, v141
	v_add3_u32 v123, v118, v123, s76
	v_lshl_add_u64 v[124:125], v[124:125], 1, s[22:23]
	global_store_short_d16_hi v[124:125], v123, off
	v_bfe_u32 v123, v114, 16, 1
	v_or_b32_e32 v124, 0xc000, v122
	v_mov_b32_e32 v125, v141
	v_add3_u32 v123, v114, v123, s76
	v_lshl_add_u64 v[124:125], v[124:125], 1, s[22:23]
	global_store_short_d16_hi v[124:125], v123, off
	v_bfe_u32 v123, v119, 16, 1
	v_or_b32_e32 v124, 0x6000, v122
	v_mov_b32_e32 v125, v141
	v_add3_u32 v123, v119, v123, s76
	v_lshl_add_u64 v[124:125], v[124:125], 1, s[22:23]
	global_store_short_d16_hi v[124:125], v123, off
	v_bfe_u32 v123, v115, 16, 1
	v_add3_u32 v124, v115, v123, s76
	v_or_b32_e32 v122, 0xe000, v122
	v_mov_b32_e32 v123, v141
	v_lshl_add_u64 v[122:123], v[122:123], 1, s[22:23]
	s_mov_b64 s[12:13], 0
	global_store_short_d16_hi v[122:123], v124, off
; DI unsigned f2bf(float f) { unsigned u = __builtin_bit_cast(unsigned, f); return (u + 0x7fffu + ((u >> 16) & 1u)) >> 16; }
; DI unsigned pk2(float lo, float hi) { typedef float v2f __attribute__((ext_vector_type(2))); typedef __bf16 v2b __attribute__((ext_vector_type(2))); v2f v = {lo, hi}; v2b b = __builtin_convertvector(v, v2b); return __builtin_bit_cast(unsigned, b); }
;     DI void operator()(const f32x4 (&acc)[2][2][4][2], const Unit& u, int wr, int wc, int fr, int fq) const {
;     ...
;                 const int row = row0 + ai * 128 + m * 16; const float rs = row_rstd<1>(P, row, 1.0f / 256.0f);
;                 const int b = row >> 13, s = row & 8191;
; #pragma unroll
;                 for (int bj = 0; bj < 2; ++bj) {
;                     const int h = u.pn * 2 + bj;
;                     const f32x4 a = acc[ai][bj][m][0] * rs, c = acc[ai][bj][m][1] * rs;
;                     if (wc < 2) {
;                         u32x4 w; w.x = pk2(a[0], a[1]); w.y = pk2(a[2], a[3]); w.z = pk2(c[0], c[1]); w.w = pk2(c[2], c[3]);
;                         *(u32x4*)(KN + (size_t)row * 512 + h * 64 + wc * 32 + 8 * fq) = w;
;                     } else {
;                         const unsigned vo = (unsigned)((b * 8 + h) * 64 + (wc - 2) * 32 + 8 * fq) * (unsigned)SEQ + (unsigned)s;
; #pragma unroll
;                         for (int i = 0; i < 4; ++i) { Vt[vo + (unsigned)(i * SEQ)] = (bf16_t)f2bf(a[i]); Vt[vo + (unsigned)((4 + i) * SEQ)] = (bf16_t)f2bf(c[i]); }
;                     }
.LBB0_1239:
	s_andn2_b64 vcc, exec, s[12:13]
	s_cbranch_vccnz .LBB0_1241
	s_lshl_b32 s12, s50, 6
	s_ashr_i32 s13, s12, 31
	v_cvt_pk_bf16_f32 v116, v116, v117
	v_cvt_pk_bf16_f32 v117, v118, v119
	v_cvt_pk_bf16_f32 v118, v112, v113
	v_lshl_add_u64 v[112:113], s[12:13], 1, v[120:121]
	s_lshl_b32 s14, s69, 1
	v_lshl_add_u64 v[112:113], v[112:113], 0, s[14:15]
	v_cvt_pk_bf16_f32 v119, v114, v115
	v_lshl_add_u64 v[112:113], v[112:113], 0, v[140:141]
	global_store_dwordx4 v[112:113], v[116:119], off
.LBB0_1241:
	v_or_b32_e32 v114, 16, v152
	v_ashrrev_i32_e32 v115, 31, v114
	v_lshl_add_u64 v[112:113], v[114:115], 2, s[18:19]
	s_nop 0
	s_and_b64 vcc, exec, s[4:5]
	v_and_or_b32 v118, v114, s77, v163
	s_mov_b64 s[12:13], -1
	s_waitcnt lgkmcnt(0)
	v_fmamk_f32 v112, v199, 0x3b800000, v167
	v_rsq_f32_e32 v112, v112
	s_nop 0
	v_pk_mul_f32 v[110:111], v[110:111], v[112:113] op_sel_hi:[1,0]
	v_pk_mul_f32 v[108:109], v[108:109], v[112:113] op_sel_hi:[1,0]
	v_pk_mul_f32 v[106:107], v[106:107], v[112:113] op_sel_hi:[1,0]
	v_pk_mul_f32 v[116:117], v[104:105], v[112:113] op_sel_hi:[1,0]
	s_cbranch_vccnz .LBB0_1243
	s_add_i32 s12, s52, s51
	v_bfe_u32 v105, v108, 16, 1
	v_lshl_add_u32 v104, s12, 19, v118
	v_add3_u32 v113, v108, v105, s76
	v_mov_b32_e32 v105, v141
	v_lshl_add_u64 v[120:121], v[104:105], 1, s[22:23]
	global_store_short_d16_hi v[120:121], v113, off
	v_bfe_u32 v105, v116, 16, 1
	v_or_b32_e32 v120, 0x8000, v104
	v_mov_b32_e32 v121, v141
	v_add3_u32 v105, v116, v105, s76
	v_lshl_add_u64 v[120:121], v[120:121], 1, s[22:23]
	global_store_short_d16_hi v[120:121], v105, off
	v_bfe_u32 v105, v109, 16, 1
	v_or_b32_e32 v120, 0x2000, v104
	v_mov_b32_e32 v121, v141
	v_add3_u32 v105, v109, v105, s76
	v_lshl_add_u64 v[120:121], v[120:121], 1, s[22:23]
	global_store_short_d16_hi v[120:121], v105, off
	v_bfe_u32 v105, v117, 16, 1
	v_or_b32_e32 v120, 0xa000, v104
	v_mov_b32_e32 v121, v141
	v_add3_u32 v105, v117, v105, s76
	v_lshl_add_u64 v[120:121], v[120:121], 1, s[22:23]
	global_store_short_d16_hi v[120:121], v105, off
	v_bfe_u32 v105, v110, 16, 1
	v_or_b32_e32 v120, 0x4000, v104
	v_mov_b32_e32 v121, v141
	v_add3_u32 v105, v110, v105, s76
	v_lshl_add_u64 v[120:121], v[120:121], 1, s[22:23]
	global_store_short_d16_hi v[120:121], v105, off
	v_bfe_u32 v105, v106, 16, 1
	v_or_b32_e32 v120, 0xc000, v104
	v_mov_b32_e32 v121, v141
	v_add3_u32 v105, v106, v105, s76
	v_lshl_add_u64 v[120:121], v[120:121], 1, s[22:23]
	global_store_short_d16_hi v[120:121], v105, off
	v_bfe_u32 v105, v111, 16, 1
	v_or_b32_e32 v120, 0x6000, v104
	v_mov_b32_e32 v121, v141
	v_add3_u32 v105, v111, v105, s76
	v_lshl_add_u64 v[120:121], v[120:121], 1, s[22:23]
	global_store_short_d16_hi v[120:121], v105, off
	v_bfe_u32 v105, v107, 16, 1
	v_add3_u32 v113, v107, v105, s76
	v_or_b32_e32 v104, 0xe000, v104
	v_mov_b32_e32 v105, v141
	v_lshl_add_u64 v[104:105], v[104:105], 1, s[22:23]
	s_mov_b64 s[12:13], 0
	global_store_short_d16_hi v[104:105], v113, off
.LBB0_1243:
	v_lshlrev_b64 v[104:105], 10, v[114:115]
	s_andn2_b64 vcc, exec, s[12:13]
	v_lshl_add_u64 v[104:105], s[20:21], 0, v[104:105]
	s_cbranch_vccnz .LBB0_1245
	s_lshl_b32 s12, s60, 7
	s_ashr_i32 s13, s12, 31
	v_cvt_pk_bf16_f32 v108, v108, v109
	v_cvt_pk_bf16_f32 v109, v110, v111
	v_cvt_pk_bf16_f32 v111, v106, v107
	v_lshl_add_u64 v[106:107], s[12:13], 1, v[104:105]
	s_lshl_b32 s14, s69, 1
	v_lshl_add_u64 v[106:107], v[106:107], 0, s[14:15]
	v_cvt_pk_bf16_f32 v110, v116, v117
	v_lshl_add_u64 v[106:107], v[106:107], 0, v[140:141]
	global_store_dwordx4 v[106:107], v[108:111], off
.LBB0_1245:
	v_mov_b32_e32 v113, v112
	v_mov_b32_e32 v106, v112
	v_mov_b32_e32 v107, v112
	v_pk_mul_f32 v[102:103], v[102:103], v[106:107]
	v_pk_mul_f32 v[100:101], v[100:101], v[112:113]
	v_pk_mul_f32 v[98:99], v[98:99], v[106:107]
	v_pk_mul_f32 v[96:97], v[96:97], v[112:113]
	s_and_b64 vcc, exec, s[4:5]
	s_mov_b64 s[12:13], -1
	s_cbranch_vccnz .LBB0_1247
	s_add_i32 s12, s52, s50
	v_bfe_u32 v107, v100, 16, 1
	v_lshl_add_u32 v106, s12, 19, v118
	v_add3_u32 v110, v100, v107, s76
	v_mov_b32_e32 v107, v141
	v_lshl_add_u64 v[108:109], v[106:107], 1, s[22:23]
	global_store_short_d16_hi v[108:109], v110, off
	v_bfe_u32 v107, v96, 16, 1
	v_or_b32_e32 v108, 0x8000, v106
	v_mov_b32_e32 v109, v141
	v_add3_u32 v107, v96, v107, s76
	v_lshl_add_u64 v[108:109], v[108:109], 1, s[22:23]
	global_store_short_d16_hi v[108:109], v107, off
	v_bfe_u32 v107, v101, 16, 1
	v_or_b32_e32 v108, 0x2000, v106
	v_mov_b32_e32 v109, v141
	v_add3_u32 v107, v101, v107, s76
	v_lshl_add_u64 v[108:109], v[108:109], 1, s[22:23]
	global_store_short_d16_hi v[108:109], v107, off
	v_bfe_u32 v107, v97, 16, 1
	v_or_b32_e32 v108, 0xa000, v106
	v_mov_b32_e32 v109, v141
	v_add3_u32 v107, v97, v107, s76
	v_lshl_add_u64 v[108:109], v[108:109], 1, s[22:23]
	global_store_short_d16_hi v[108:109], v107, off
	v_bfe_u32 v107, v102, 16, 1
	v_or_b32_e32 v108, 0x4000, v106
	v_mov_b32_e32 v109, v141
	v_add3_u32 v107, v102, v107, s76
	v_lshl_add_u64 v[108:109], v[108:109], 1, s[22:23]
	global_store_short_d16_hi v[108:109], v107, off
	v_bfe_u32 v107, v98, 16, 1
	v_or_b32_e32 v108, 0xc000, v106
	v_mov_b32_e32 v109, v141
	v_add3_u32 v107, v98, v107, s76
	v_lshl_add_u64 v[108:109], v[108:109], 1, s[22:23]
	global_store_short_d16_hi v[108:109], v107, off
	v_bfe_u32 v107, v103, 16, 1
	v_or_b32_e32 v108, 0x6000, v106
	v_mov_b32_e32 v109, v141
	v_add3_u32 v107, v103, v107, s76
	v_lshl_add_u64 v[108:109], v[108:109], 1, s[22:23]
	global_store_short_d16_hi v[108:109], v107, off
	v_bfe_u32 v107, v99, 16, 1
	v_add3_u32 v108, v99, v107, s76
	v_or_b32_e32 v106, 0xe000, v106
	v_mov_b32_e32 v107, v141
	v_lshl_add_u64 v[106:107], v[106:107], 1, s[22:23]
	s_mov_b64 s[12:13], 0
	global_store_short_d16_hi v[106:107], v108, off
; DI unsigned f2bf(float f) { unsigned u = __builtin_bit_cast(unsigned, f); return (u + 0x7fffu + ((u >> 16) & 1u)) >> 16; }
; DI unsigned pk2(float lo, float hi) { typedef float v2f __attribute__((ext_vector_type(2))); typedef __bf16 v2b __attribute__((ext_vector_type(2))); v2f v = {lo, hi}; v2b b = __builtin_convertvector(v, v2b); return __builtin_bit_cast(unsigned, b); }
;     DI void operator()(const f32x4 (&acc)[2][2][4][2], const Unit& u, int wr, int wc, int fr, int fq) const {
;     ...
;                 const int row = row0 + ai * 128 + m * 16; const float rs = row_rstd<1>(P, row, 1.0f / 256.0f);
;                 const int b = row >> 13, s = row & 8191;
; #pragma unroll
;                 for (int bj = 0; bj < 2; ++bj) {
;                     const int h = u.pn * 2 + bj;
;                     const f32x4 a = acc[ai][bj][m][0] * rs, c = acc[ai][bj][m][1] * rs;
;                     if (wc < 2) {
;                         u32x4 w; w.x = pk2(a[0], a[1]); w.y = pk2(a[2], a[3]); w.z = pk2(c[0], c[1]); w.w = pk2(c[2], c[3]);
;                         *(u32x4*)(KN + (size_t)row * 512 + h * 64 + wc * 32 + 8 * fq) = w;
;                     } else {
;                         const unsigned vo = (unsigned)((b * 8 + h) * 64 + (wc - 2) * 32 + 8 * fq) * (unsigned)SEQ + (unsigned)s;
; #pragma unroll
;                         for (int i = 0; i < 4; ++i) { Vt[vo + (unsigned)(i * SEQ)] = (bf16_t)f2bf(a[i]); Vt[vo + (unsigned)((4 + i) * SEQ)] = (bf16_t)f2bf(c[i]); }
;                     }
.LBB0_1247:
	s_andn2_b64 vcc, exec, s[12:13]
	s_cbranch_vccnz .LBB0_1249
	s_lshl_b32 s12, s50, 6
	s_ashr_i32 s13, s12, 31
	v_cvt_pk_bf16_f32 v100, v100, v101
	v_cvt_pk_bf16_f32 v101, v102, v103
	v_cvt_pk_bf16_f32 v102, v96, v97
	v_lshl_add_u64 v[96:97], s[12:13], 1, v[104:105]
	s_lshl_b32 s14, s69, 1
	v_lshl_add_u64 v[96:97], v[96:97], 0, s[14:15]
	v_cvt_pk_bf16_f32 v103, v98, v99
	v_lshl_add_u64 v[96:97], v[96:97], 0, v[140:141]
	global_store_dwordx4 v[96:97], v[100:103], off
.LBB0_1249:
	v_or_b32_e32 v98, 32, v152
	v_ashrrev_i32_e32 v99, 31, v98
	v_lshl_add_u64 v[96:97], v[98:99], 2, s[18:19]
	s_nop 0
	s_and_b64 vcc, exec, s[4:5]
	v_and_or_b32 v102, v98, s78, v163
	s_mov_b64 s[12:13], -1
	s_waitcnt lgkmcnt(0)
	v_fmamk_f32 v96, v200, 0x3b800000, v167
	v_rsq_f32_e32 v96, v96
	s_nop 0
	v_pk_mul_f32 v[94:95], v[94:95], v[96:97] op_sel_hi:[1,0]
	v_pk_mul_f32 v[92:93], v[92:93], v[96:97] op_sel_hi:[1,0]
	v_pk_mul_f32 v[90:91], v[90:91], v[96:97] op_sel_hi:[1,0]
	v_pk_mul_f32 v[100:101], v[88:89], v[96:97] op_sel_hi:[1,0]
	s_cbranch_vccnz .LBB0_1251
	s_add_i32 s12, s52, s51
	v_bfe_u32 v89, v92, 16, 1
	v_lshl_add_u32 v88, s12, 19, v102
	v_add3_u32 v97, v92, v89, s76
	v_mov_b32_e32 v89, v141
	v_lshl_add_u64 v[104:105], v[88:89], 1, s[22:23]
	global_store_short_d16_hi v[104:105], v97, off
	v_bfe_u32 v89, v100, 16, 1
	v_or_b32_e32 v104, 0x8000, v88
	v_mov_b32_e32 v105, v141
	v_add3_u32 v89, v100, v89, s76
	v_lshl_add_u64 v[104:105], v[104:105], 1, s[22:23]
	global_store_short_d16_hi v[104:105], v89, off
	v_bfe_u32 v89, v93, 16, 1
	v_or_b32_e32 v104, 0x2000, v88
	v_mov_b32_e32 v105, v141
	v_add3_u32 v89, v93, v89, s76
	v_lshl_add_u64 v[104:105], v[104:105], 1, s[22:23]
	global_store_short_d16_hi v[104:105], v89, off
	v_bfe_u32 v89, v101, 16, 1
	v_or_b32_e32 v104, 0xa000, v88
	v_mov_b32_e32 v105, v141
	v_add3_u32 v89, v101, v89, s76
	v_lshl_add_u64 v[104:105], v[104:105], 1, s[22:23]
	global_store_short_d16_hi v[104:105], v89, off
	v_bfe_u32 v89, v94, 16, 1
	v_or_b32_e32 v104, 0x4000, v88
	v_mov_b32_e32 v105, v141
	v_add3_u32 v89, v94, v89, s76
	v_lshl_add_u64 v[104:105], v[104:105], 1, s[22:23]
	global_store_short_d16_hi v[104:105], v89, off
	v_bfe_u32 v89, v90, 16, 1
	v_or_b32_e32 v104, 0xc000, v88
	v_mov_b32_e32 v105, v141
	v_add3_u32 v89, v90, v89, s76
	v_lshl_add_u64 v[104:105], v[104:105], 1, s[22:23]
	global_store_short_d16_hi v[104:105], v89, off
	v_bfe_u32 v89, v95, 16, 1
	v_or_b32_e32 v104, 0x6000, v88
	v_mov_b32_e32 v105, v141
	v_add3_u32 v89, v95, v89, s76
	v_lshl_add_u64 v[104:105], v[104:105], 1, s[22:23]
	global_store_short_d16_hi v[104:105], v89, off
	v_bfe_u32 v89, v91, 16, 1
	v_add3_u32 v97, v91, v89, s76
	v_or_b32_e32 v88, 0xe000, v88
	v_mov_b32_e32 v89, v141
	v_lshl_add_u64 v[88:89], v[88:89], 1, s[22:23]
	s_mov_b64 s[12:13], 0
	global_store_short_d16_hi v[88:89], v97, off
.LBB0_1251:
	v_lshlrev_b64 v[88:89], 10, v[98:99]
	s_andn2_b64 vcc, exec, s[12:13]
	v_lshl_add_u64 v[88:89], s[20:21], 0, v[88:89]
	s_cbranch_vccnz .LBB0_1253
	s_lshl_b32 s12, s60, 7
	s_ashr_i32 s13, s12, 31
	v_cvt_pk_bf16_f32 v92, v92, v93
	v_cvt_pk_bf16_f32 v93, v94, v95
	v_cvt_pk_bf16_f32 v95, v90, v91
	v_lshl_add_u64 v[90:91], s[12:13], 1, v[88:89]
	s_lshl_b32 s14, s69, 1
	v_lshl_add_u64 v[90:91], v[90:91], 0, s[14:15]
	v_cvt_pk_bf16_f32 v94, v100, v101
	v_lshl_add_u64 v[90:91], v[90:91], 0, v[140:141]
	global_store_dwordx4 v[90:91], v[92:95], off
.LBB0_1253:
	v_mov_b32_e32 v97, v96
	v_mov_b32_e32 v90, v96
	v_mov_b32_e32 v91, v96
	v_pk_mul_f32 v[86:87], v[86:87], v[90:91]
	v_pk_mul_f32 v[84:85], v[84:85], v[96:97]
	v_pk_mul_f32 v[82:83], v[82:83], v[90:91]
	v_pk_mul_f32 v[80:81], v[80:81], v[96:97]
	s_and_b64 vcc, exec, s[4:5]
	s_mov_b64 s[12:13], -1
	s_cbranch_vccnz .LBB0_1255
	s_add_i32 s12, s52, s50
	v_bfe_u32 v91, v84, 16, 1
	v_lshl_add_u32 v90, s12, 19, v102
	v_add3_u32 v94, v84, v91, s76
	v_mov_b32_e32 v91, v141
	v_lshl_add_u64 v[92:93], v[90:91], 1, s[22:23]
	global_store_short_d16_hi v[92:93], v94, off
	v_bfe_u32 v91, v80, 16, 1
	v_or_b32_e32 v92, 0x8000, v90
	v_mov_b32_e32 v93, v141
	v_add3_u32 v91, v80, v91, s76
	v_lshl_add_u64 v[92:93], v[92:93], 1, s[22:23]
	global_store_short_d16_hi v[92:93], v91, off
	v_bfe_u32 v91, v85, 16, 1
	v_or_b32_e32 v92, 0x2000, v90
	v_mov_b32_e32 v93, v141
	v_add3_u32 v91, v85, v91, s76
	v_lshl_add_u64 v[92:93], v[92:93], 1, s[22:23]
	global_store_short_d16_hi v[92:93], v91, off
	v_bfe_u32 v91, v81, 16, 1
	v_or_b32_e32 v92, 0xa000, v90
	v_mov_b32_e32 v93, v141
	v_add3_u32 v91, v81, v91, s76
	v_lshl_add_u64 v[92:93], v[92:93], 1, s[22:23]
	global_store_short_d16_hi v[92:93], v91, off
	v_bfe_u32 v91, v86, 16, 1
	v_or_b32_e32 v92, 0x4000, v90
	v_mov_b32_e32 v93, v141
	v_add3_u32 v91, v86, v91, s76
	v_lshl_add_u64 v[92:93], v[92:93], 1, s[22:23]
	global_store_short_d16_hi v[92:93], v91, off
	v_bfe_u32 v91, v82, 16, 1
	v_or_b32_e32 v92, 0xc000, v90
	v_mov_b32_e32 v93, v141
	v_add3_u32 v91, v82, v91, s76
	v_lshl_add_u64 v[92:93], v[92:93], 1, s[22:23]
	global_store_short_d16_hi v[92:93], v91, off
	v_bfe_u32 v91, v87, 16, 1
	v_or_b32_e32 v92, 0x6000, v90
	v_mov_b32_e32 v93, v141
	v_add3_u32 v91, v87, v91, s76
	v_lshl_add_u64 v[92:93], v[92:93], 1, s[22:23]
	global_store_short_d16_hi v[92:93], v91, off
	v_bfe_u32 v91, v83, 16, 1
	v_add3_u32 v92, v83, v91, s76
	v_or_b32_e32 v90, 0xe000, v90
	v_mov_b32_e32 v91, v141
	v_lshl_add_u64 v[90:91], v[90:91], 1, s[22:23]
	s_mov_b64 s[12:13], 0
	global_store_short_d16_hi v[90:91], v92, off
; DI unsigned f2bf(float f) { unsigned u = __builtin_bit_cast(unsigned, f); return (u + 0x7fffu + ((u >> 16) & 1u)) >> 16; }
; DI unsigned pk2(float lo, float hi) { typedef float v2f __attribute__((ext_vector_type(2))); typedef __bf16 v2b __attribute__((ext_vector_type(2))); v2f v = {lo, hi}; v2b b = __builtin_convertvector(v, v2b); return __builtin_bit_cast(unsigned, b); }
;     DI void operator()(const f32x4 (&acc)[2][2][4][2], const Unit& u, int wr, int wc, int fr, int fq) const {
;         const int row0 = u.pm * 256 + wr * 64 + fr;
; #pragma unroll
;         for (int ai = 0; ai < 2; ++ai)
; #pragma unroll
;             for (int m = 0; m < 4; ++m) {
;                 const int row = row0 + ai * 128 + m * 16; const float rs = row_rstd<1>(P, row, 1.0f / 256.0f);
;                 const int b = row >> 13, s = row & 8191;
; #pragma unroll
;                 for (int bj = 0; bj < 2; ++bj) {
;                     const int h = u.pn * 2 + bj;
;                     const f32x4 a = acc[ai][bj][m][0] * rs, c = acc[ai][bj][m][1] * rs;
;                     if (wc < 2) {
;                         u32x4 w; w.x = pk2(a[0], a[1]); w.y = pk2(a[2], a[3]); w.z = pk2(c[0], c[1]); w.w = pk2(c[2], c[3]);
;                         *(u32x4*)(KN + (size_t)row * 512 + h * 64 + wc * 32 + 8 * fq) = w;
;                     } else {
;                         const unsigned vo = (unsigned)((b * 8 + h) * 64 + (wc - 2) * 32 + 8 * fq) * (unsigned)SEQ + (unsigned)s;
; #pragma unroll
;                         for (int i = 0; i < 4; ++i) { Vt[vo + (unsigned)(i * SEQ)] = (bf16_t)f2bf(a[i]); Vt[vo + (unsigned)((4 + i) * SEQ)] = (bf16_t)f2bf(c[i]); }
;                     }
;                 }
.LBB0_1255:
	s_andn2_b64 vcc, exec, s[12:13]
	s_cbranch_vccnz .LBB0_1257
	s_lshl_b32 s12, s50, 6
	s_ashr_i32 s13, s12, 31
	v_cvt_pk_bf16_f32 v84, v84, v85
	v_cvt_pk_bf16_f32 v85, v86, v87
	v_cvt_pk_bf16_f32 v86, v80, v81
	v_lshl_add_u64 v[80:81], s[12:13], 1, v[88:89]
	s_lshl_b32 s14, s69, 1
	v_lshl_add_u64 v[80:81], v[80:81], 0, s[14:15]
	v_cvt_pk_bf16_f32 v87, v82, v83
	v_lshl_add_u64 v[80:81], v[80:81], 0, v[140:141]
	global_store_dwordx4 v[80:81], v[84:87], off
.LBB0_1257:
	v_or_b32_e32 v82, 48, v152
	v_ashrrev_i32_e32 v83, 31, v82
	v_lshl_add_u64 v[80:81], v[82:83], 2, s[18:19]
	s_nop 0
	s_and_b64 vcc, exec, s[4:5]
	v_and_or_b32 v86, v82, s79, v163
	s_mov_b64 s[12:13], -1
	s_waitcnt lgkmcnt(0)
	v_fmamk_f32 v80, v201, 0x3b800000, v167
	v_rsq_f32_e32 v80, v80
	s_nop 0
	v_pk_mul_f32 v[78:79], v[78:79], v[80:81] op_sel_hi:[1,0]
	v_pk_mul_f32 v[76:77], v[76:77], v[80:81] op_sel_hi:[1,0]
	v_pk_mul_f32 v[74:75], v[74:75], v[80:81] op_sel_hi:[1,0]
	v_pk_mul_f32 v[84:85], v[72:73], v[80:81] op_sel_hi:[1,0]
	s_cbranch_vccnz .LBB0_1259
	s_add_i32 s12, s52, s51
	v_bfe_u32 v73, v76, 16, 1
	v_lshl_add_u32 v72, s12, 19, v86
	v_add3_u32 v81, v76, v73, s76
	v_mov_b32_e32 v73, v141
	v_lshl_add_u64 v[88:89], v[72:73], 1, s[22:23]
	global_store_short_d16_hi v[88:89], v81, off
	v_bfe_u32 v73, v84, 16, 1
	v_or_b32_e32 v88, 0x8000, v72
	v_mov_b32_e32 v89, v141
	v_add3_u32 v73, v84, v73, s76
	v_lshl_add_u64 v[88:89], v[88:89], 1, s[22:23]
	global_store_short_d16_hi v[88:89], v73, off
	v_bfe_u32 v73, v77, 16, 1
	v_or_b32_e32 v88, 0x2000, v72
	v_mov_b32_e32 v89, v141
	v_add3_u32 v73, v77, v73, s76
	v_lshl_add_u64 v[88:89], v[88:89], 1, s[22:23]
	global_store_short_d16_hi v[88:89], v73, off
	v_bfe_u32 v73, v85, 16, 1
	v_or_b32_e32 v88, 0xa000, v72
	v_mov_b32_e32 v89, v141
	v_add3_u32 v73, v85, v73, s76
	v_lshl_add_u64 v[88:89], v[88:89], 1, s[22:23]
	global_store_short_d16_hi v[88:89], v73, off
	v_bfe_u32 v73, v78, 16, 1
	v_or_b32_e32 v88, 0x4000, v72
	v_mov_b32_e32 v89, v141
	v_add3_u32 v73, v78, v73, s76
	v_lshl_add_u64 v[88:89], v[88:89], 1, s[22:23]
	global_store_short_d16_hi v[88:89], v73, off
	v_bfe_u32 v73, v74, 16, 1
	v_or_b32_e32 v88, 0xc000, v72
	v_mov_b32_e32 v89, v141
	v_add3_u32 v73, v74, v73, s76
	v_lshl_add_u64 v[88:89], v[88:89], 1, s[22:23]
	global_store_short_d16_hi v[88:89], v73, off
	v_bfe_u32 v73, v79, 16, 1
	v_or_b32_e32 v88, 0x6000, v72
	v_mov_b32_e32 v89, v141
	v_add3_u32 v73, v79, v73, s76
	v_lshl_add_u64 v[88:89], v[88:89], 1, s[22:23]
	global_store_short_d16_hi v[88:89], v73, off
	v_bfe_u32 v73, v75, 16, 1
	v_add3_u32 v81, v75, v73, s76
	v_or_b32_e32 v72, 0xe000, v72
	v_mov_b32_e32 v73, v141
	v_lshl_add_u64 v[72:73], v[72:73], 1, s[22:23]
	s_mov_b64 s[12:13], 0
	global_store_short_d16_hi v[72:73], v81, off
.LBB0_1259:
	v_lshlrev_b64 v[72:73], 10, v[82:83]
	s_andn2_b64 vcc, exec, s[12:13]
	v_lshl_add_u64 v[72:73], s[20:21], 0, v[72:73]
	s_cbranch_vccnz .LBB0_1261
	s_lshl_b32 s12, s60, 7
	s_ashr_i32 s13, s12, 31
	v_cvt_pk_bf16_f32 v76, v76, v77
	v_cvt_pk_bf16_f32 v77, v78, v79
	v_cvt_pk_bf16_f32 v79, v74, v75
	v_lshl_add_u64 v[74:75], s[12:13], 1, v[72:73]
	s_lshl_b32 s14, s69, 1
	v_lshl_add_u64 v[74:75], v[74:75], 0, s[14:15]
	v_cvt_pk_bf16_f32 v78, v84, v85
	v_lshl_add_u64 v[74:75], v[74:75], 0, v[140:141]
	global_store_dwordx4 v[74:75], v[76:79], off
.LBB0_1261:
	v_mov_b32_e32 v81, v80
	v_mov_b32_e32 v74, v80
	v_mov_b32_e32 v75, v80
	v_pk_mul_f32 v[70:71], v[70:71], v[74:75]
	v_pk_mul_f32 v[68:69], v[68:69], v[80:81]
	v_pk_mul_f32 v[66:67], v[66:67], v[74:75]
	v_pk_mul_f32 v[64:65], v[64:65], v[80:81]
	s_and_b64 vcc, exec, s[4:5]
	s_mov_b64 s[12:13], -1
	s_cbranch_vccnz .LBB0_1263
	s_add_i32 s52, s52, s50
	v_bfe_u32 v75, v68, 16, 1
	v_lshl_add_u32 v74, s52, 19, v86
	v_add3_u32 v78, v68, v75, s76
	v_mov_b32_e32 v75, v141
	v_lshl_add_u64 v[76:77], v[74:75], 1, s[22:23]
	global_store_short_d16_hi v[76:77], v78, off
	v_bfe_u32 v75, v64, 16, 1
	v_or_b32_e32 v76, 0x8000, v74
	v_mov_b32_e32 v77, v141
	v_add3_u32 v75, v64, v75, s76
	v_lshl_add_u64 v[76:77], v[76:77], 1, s[22:23]
	global_store_short_d16_hi v[76:77], v75, off
	v_bfe_u32 v75, v69, 16, 1
	v_or_b32_e32 v76, 0x2000, v74
	v_mov_b32_e32 v77, v141
	v_add3_u32 v75, v69, v75, s76
	v_lshl_add_u64 v[76:77], v[76:77], 1, s[22:23]
	global_store_short_d16_hi v[76:77], v75, off
	v_bfe_u32 v75, v65, 16, 1
	v_or_b32_e32 v76, 0xa000, v74
	v_mov_b32_e32 v77, v141
	v_add3_u32 v75, v65, v75, s76
	v_lshl_add_u64 v[76:77], v[76:77], 1, s[22:23]
	global_store_short_d16_hi v[76:77], v75, off
	v_bfe_u32 v75, v70, 16, 1
	v_or_b32_e32 v76, 0x4000, v74
	v_mov_b32_e32 v77, v141
	v_add3_u32 v75, v70, v75, s76
	v_lshl_add_u64 v[76:77], v[76:77], 1, s[22:23]
	global_store_short_d16_hi v[76:77], v75, off
	v_bfe_u32 v75, v66, 16, 1
	v_or_b32_e32 v76, 0xc000, v74
	v_mov_b32_e32 v77, v141
	v_add3_u32 v75, v66, v75, s76
	v_lshl_add_u64 v[76:77], v[76:77], 1, s[22:23]
	global_store_short_d16_hi v[76:77], v75, off
	v_bfe_u32 v75, v71, 16, 1
	v_or_b32_e32 v76, 0x6000, v74
	v_mov_b32_e32 v77, v141
	v_add3_u32 v75, v71, v75, s76
	v_lshl_add_u64 v[76:77], v[76:77], 1, s[22:23]
	global_store_short_d16_hi v[76:77], v75, off
	v_bfe_u32 v75, v67, 16, 1
	v_add3_u32 v76, v67, v75, s76
	v_or_b32_e32 v74, 0xe000, v74
	v_mov_b32_e32 v75, v141
	v_lshl_add_u64 v[74:75], v[74:75], 1, s[22:23]
	s_mov_b64 s[12:13], 0
	global_store_short_d16_hi v[74:75], v76, off
.LBB0_1263:
	s_andn2_b64 vcc, exec, s[12:13]
	s_cbranch_vccnz .LBB0_1265
	s_lshl_b32 s12, s50, 6
	s_ashr_i32 s13, s12, 31
	v_cvt_pk_bf16_f32 v68, v68, v69
	v_cvt_pk_bf16_f32 v69, v70, v71
	v_cvt_pk_bf16_f32 v70, v64, v65
	v_lshl_add_u64 v[64:65], s[12:13], 1, v[72:73]
	s_lshl_b32 s14, s69, 1
	v_lshl_add_u64 v[64:65], v[64:65], 0, s[14:15]
	v_cvt_pk_bf16_f32 v71, v66, v67
	v_lshl_add_u64 v[64:65], v[64:65], 0, v[140:141]
	global_store_dwordx4 v[64:65], v[68:71], off
; DI unsigned f2bf(float f) { unsigned u = __builtin_bit_cast(unsigned, f); return (u + 0x7fffu + ((u >> 16) & 1u)) >> 16; }
; DI unsigned pk2(float lo, float hi) { typedef float v2f __attribute__((ext_vector_type(2))); typedef __bf16 v2b __attribute__((ext_vector_type(2))); v2f v = {lo, hi}; v2b b = __builtin_convertvector(v, v2b); return __builtin_bit_cast(unsigned, b); }
;     DI void operator()(const f32x4 (&acc)[2][2][4][2], const Unit& u, int wr, int wc, int fr, int fq) const {
;         const int row0 = u.pm * 256 + wr * 64 + fr;
; #pragma unroll
;         for (int ai = 0; ai < 2; ++ai)
; #pragma unroll
;             for (int m = 0; m < 4; ++m) {
;                 const int row = row0 + ai * 128 + m * 16; const float rs = row_rstd<1>(P, row, 1.0f / 256.0f);
;                 const int b = row >> 13, s = row & 8191;
; #pragma unroll
;                 for (int bj = 0; bj < 2; ++bj) {
;                     const int h = u.pn * 2 + bj;
;                     const f32x4 a = acc[ai][bj][m][0] * rs, c = acc[ai][bj][m][1] * rs;
;                     if (wc < 2) {
;                         u32x4 w; w.x = pk2(a[0], a[1]); w.y = pk2(a[2], a[3]); w.z = pk2(c[0], c[1]); w.w = pk2(c[2], c[3]);
;                         *(u32x4*)(KN + (size_t)row * 512 + h * 64 + wc * 32 + 8 * fq) = w;
;                     } else {
;                         const unsigned vo = (unsigned)((b * 8 + h) * 64 + (wc - 2) * 32 + 8 * fq) * (unsigned)SEQ + (unsigned)s;
; #pragma unroll
;                         for (int i = 0; i < 4; ++i) { Vt[vo + (unsigned)(i * SEQ)] = (bf16_t)f2bf(a[i]); Vt[vo + (unsigned)((4 + i) * SEQ)] = (bf16_t)f2bf(c[i]); }
;                     }
;                 }
.LBB0_1265:
	s_nop 0
	v_add_u32_e32 v66, 0x80, v152
	v_lshrrev_b32_e32 v65, 10, v66
	v_and_b32_e32 v72, 0x1ff8, v65
	s_mov_b64 s[12:13], -1
	s_and_b64 vcc, exec, s[4:5]
	v_and_or_b32 v71, v66, s75, v163
	v_add_u32_e32 v70, s51, v72
	s_waitcnt lgkmcnt(0)
	v_fmamk_f32 v64, v202, 0x3b800000, v167
	v_rsq_f32_e32 v64, v64
	s_nop 0
	v_pk_mul_f32 v[62:63], v[62:63], v[64:65] op_sel_hi:[1,0]
	v_pk_mul_f32 v[60:61], v[60:61], v[64:65] op_sel_hi:[1,0]
	v_pk_mul_f32 v[58:59], v[58:59], v[64:65] op_sel_hi:[1,0]
	v_pk_mul_f32 v[68:69], v[56:57], v[64:65] op_sel_hi:[1,0]
	s_cbranch_vccnz .LBB0_1267
	v_bfe_u32 v57, v60, 16, 1
	v_lshl_add_u32 v56, v70, 19, v71
	v_add3_u32 v65, v60, v57, s76
	v_mov_b32_e32 v57, v141
	v_lshl_add_u64 v[74:75], v[56:57], 1, s[22:23]
	global_store_short_d16_hi v[74:75], v65, off
	v_bfe_u32 v57, v68, 16, 1
	v_or_b32_e32 v74, 0x8000, v56
	v_mov_b32_e32 v75, v141
	v_add3_u32 v57, v68, v57, s76
	v_lshl_add_u64 v[74:75], v[74:75], 1, s[22:23]
	global_store_short_d16_hi v[74:75], v57, off
	v_bfe_u32 v57, v61, 16, 1
	v_or_b32_e32 v74, 0x2000, v56
	v_mov_b32_e32 v75, v141
	v_add3_u32 v57, v61, v57, s76
	v_lshl_add_u64 v[74:75], v[74:75], 1, s[22:23]
	global_store_short_d16_hi v[74:75], v57, off
	v_bfe_u32 v57, v69, 16, 1
	v_or_b32_e32 v74, 0xa000, v56
	v_mov_b32_e32 v75, v141
	v_add3_u32 v57, v69, v57, s76
	v_lshl_add_u64 v[74:75], v[74:75], 1, s[22:23]
	global_store_short_d16_hi v[74:75], v57, off
	v_bfe_u32 v57, v62, 16, 1
	v_or_b32_e32 v74, 0x4000, v56
	v_mov_b32_e32 v75, v141
	v_add3_u32 v57, v62, v57, s76
	v_lshl_add_u64 v[74:75], v[74:75], 1, s[22:23]
	global_store_short_d16_hi v[74:75], v57, off
	v_bfe_u32 v57, v58, 16, 1
	v_or_b32_e32 v74, 0xc000, v56
	v_mov_b32_e32 v75, v141
	v_add3_u32 v57, v58, v57, s76
	v_lshl_add_u64 v[74:75], v[74:75], 1, s[22:23]
	global_store_short_d16_hi v[74:75], v57, off
	v_bfe_u32 v57, v63, 16, 1
	v_or_b32_e32 v74, 0x6000, v56
	v_mov_b32_e32 v75, v141
	v_add3_u32 v57, v63, v57, s76
	v_lshl_add_u64 v[74:75], v[74:75], 1, s[22:23]
	global_store_short_d16_hi v[74:75], v57, off
	v_bfe_u32 v57, v59, 16, 1
	v_add3_u32 v65, v59, v57, s76
	v_or_b32_e32 v56, 0xe000, v56
	v_mov_b32_e32 v57, v141
	v_lshl_add_u64 v[56:57], v[56:57], 1, s[22:23]
	s_mov_b64 s[12:13], 0
	global_store_short_d16_hi v[56:57], v65, off
.LBB0_1267:
	v_ashrrev_i32_e32 v67, 31, v66
	v_lshlrev_b64 v[56:57], 10, v[66:67]
	s_andn2_b64 vcc, exec, s[12:13]
	v_lshl_add_u64 v[56:57], s[20:21], 0, v[56:57]
	s_cbranch_vccnz .LBB0_1269
	s_lshl_b32 s12, s60, 7
	s_ashr_i32 s13, s12, 31
	v_cvt_pk_bf16_f32 v60, v60, v61
	v_cvt_pk_bf16_f32 v61, v62, v63
	v_cvt_pk_bf16_f32 v63, v58, v59
	v_lshl_add_u64 v[58:59], s[12:13], 1, v[56:57]
	s_lshl_b32 s14, s69, 1
	v_lshl_add_u64 v[58:59], v[58:59], 0, s[14:15]
	v_cvt_pk_bf16_f32 v62, v68, v69
	v_lshl_add_u64 v[58:59], v[58:59], 0, v[140:141]
	global_store_dwordx4 v[58:59], v[60:63], off
.LBB0_1269:
	v_mov_b32_e32 v65, v64
	v_mov_b32_e32 v58, v64
	v_mov_b32_e32 v59, v64
	v_pk_mul_f32 v[54:55], v[54:55], v[58:59]
	v_pk_mul_f32 v[52:53], v[52:53], v[64:65]
	v_pk_mul_f32 v[50:51], v[50:51], v[58:59]
	v_pk_mul_f32 v[48:49], v[48:49], v[64:65]
	s_mov_b64 s[12:13], -1
	s_and_b64 vcc, exec, s[4:5]
	v_add_u32_e32 v58, s50, v72
	s_cbranch_vccnz .LBB0_1271
	v_lshl_add_u32 v60, v58, 19, v71
	v_bfe_u32 v59, v52, 16, 1
	v_mov_b32_e32 v61, v141
	v_add3_u32 v59, v52, v59, s76
	v_lshl_add_u64 v[62:63], v[60:61], 1, s[22:23]
	global_store_short_d16_hi v[62:63], v59, off
	v_bfe_u32 v59, v48, 16, 1
	v_or_b32_e32 v62, 0x8000, v60
	v_mov_b32_e32 v63, v141
	v_add3_u32 v59, v48, v59, s76
	v_lshl_add_u64 v[62:63], v[62:63], 1, s[22:23]
	global_store_short_d16_hi v[62:63], v59, off
	v_bfe_u32 v59, v53, 16, 1
	v_or_b32_e32 v62, 0x2000, v60
	v_mov_b32_e32 v63, v141
	v_add3_u32 v59, v53, v59, s76
	v_lshl_add_u64 v[62:63], v[62:63], 1, s[22:23]
	global_store_short_d16_hi v[62:63], v59, off
	v_bfe_u32 v59, v49, 16, 1
	v_or_b32_e32 v62, 0xa000, v60
	v_mov_b32_e32 v63, v141
	v_add3_u32 v59, v49, v59, s76
	v_lshl_add_u64 v[62:63], v[62:63], 1, s[22:23]
	global_store_short_d16_hi v[62:63], v59, off
	v_bfe_u32 v59, v54, 16, 1
	v_or_b32_e32 v62, 0x4000, v60
	v_mov_b32_e32 v63, v141
	v_add3_u32 v59, v54, v59, s76
	v_lshl_add_u64 v[62:63], v[62:63], 1, s[22:23]
	global_store_short_d16_hi v[62:63], v59, off
	v_bfe_u32 v59, v50, 16, 1
	v_or_b32_e32 v62, 0xc000, v60
	v_mov_b32_e32 v63, v141
	v_add3_u32 v59, v50, v59, s76
	v_lshl_add_u64 v[62:63], v[62:63], 1, s[22:23]
	global_store_short_d16_hi v[62:63], v59, off
	v_bfe_u32 v59, v55, 16, 1
	v_or_b32_e32 v62, 0x6000, v60
	v_mov_b32_e32 v63, v141
	v_add3_u32 v59, v55, v59, s76
	v_lshl_add_u64 v[62:63], v[62:63], 1, s[22:23]
	global_store_short_d16_hi v[62:63], v59, off
	v_bfe_u32 v59, v51, 16, 1
	v_or_b32_e32 v60, 0xe000, v60
	v_add3_u32 v59, v51, v59, s76
	v_lshl_add_u64 v[60:61], v[60:61], 1, s[22:23]
	s_mov_b64 s[12:13], 0
	global_store_short_d16_hi v[60:61], v59, off
.LBB0_1271:
	s_andn2_b64 vcc, exec, s[12:13]
	s_cbranch_vccnz .LBB0_1273
	s_lshl_b32 s12, s50, 6
	s_ashr_i32 s13, s12, 31
	v_cvt_pk_bf16_f32 v52, v52, v53
	v_cvt_pk_bf16_f32 v53, v54, v55
	v_cvt_pk_bf16_f32 v54, v48, v49
	v_lshl_add_u64 v[48:49], s[12:13], 1, v[56:57]
	s_lshl_b32 s14, s69, 1
	v_lshl_add_u64 v[48:49], v[48:49], 0, s[14:15]
	v_cvt_pk_bf16_f32 v55, v50, v51
	v_lshl_add_u64 v[48:49], v[48:49], 0, v[140:141]
	global_store_dwordx4 v[48:49], v[52:55], off
; DI unsigned f2bf(float f) { unsigned u = __builtin_bit_cast(unsigned, f); return (u + 0x7fffu + ((u >> 16) & 1u)) >> 16; }
; DI unsigned pk2(float lo, float hi) { typedef float v2f __attribute__((ext_vector_type(2))); typedef __bf16 v2b __attribute__((ext_vector_type(2))); v2f v = {lo, hi}; v2b b = __builtin_convertvector(v, v2b); return __builtin_bit_cast(unsigned, b); }
;     DI void operator()(const f32x4 (&acc)[2][2][4][2], const Unit& u, int wr, int wc, int fr, int fq) const {
;         const int row0 = u.pm * 256 + wr * 64 + fr;
; #pragma unroll
;         for (int ai = 0; ai < 2; ++ai)
; #pragma unroll
;             for (int m = 0; m < 4; ++m) {
;                 const int row = row0 + ai * 128 + m * 16; const float rs = row_rstd<1>(P, row, 1.0f / 256.0f);
;                 const int b = row >> 13, s = row & 8191;
; #pragma unroll
;                 for (int bj = 0; bj < 2; ++bj) {
;                     const int h = u.pn * 2 + bj;
;                     const f32x4 a = acc[ai][bj][m][0] * rs, c = acc[ai][bj][m][1] * rs;
;                     if (wc < 2) {
;                         u32x4 w; w.x = pk2(a[0], a[1]); w.y = pk2(a[2], a[3]); w.z = pk2(c[0], c[1]); w.w = pk2(c[2], c[3]);
;                         *(u32x4*)(KN + (size_t)row * 512 + h * 64 + wc * 32 + 8 * fq) = w;
;                     } else {
;                         const unsigned vo = (unsigned)((b * 8 + h) * 64 + (wc - 2) * 32 + 8 * fq) * (unsigned)SEQ + (unsigned)s;
; #pragma unroll
;                         for (int i = 0; i < 4; ++i) { Vt[vo + (unsigned)(i * SEQ)] = (bf16_t)f2bf(a[i]); Vt[vo + (unsigned)((4 + i) * SEQ)] = (bf16_t)f2bf(c[i]); }
;                     }
;                 }
.LBB0_1273:
	s_nop 0
	v_add_u32_e32 v50, 0x90, v152
	s_and_b64 vcc, exec, s[4:5]
	v_and_or_b32 v54, v50, s77, v163
	s_mov_b64 s[12:13], -1
	s_waitcnt lgkmcnt(0)
	v_fmamk_f32 v48, v203, 0x3b800000, v167
	v_rsq_f32_e32 v48, v48
	s_nop 0
	v_pk_mul_f32 v[46:47], v[46:47], v[48:49] op_sel_hi:[1,0]
	v_pk_mul_f32 v[44:45], v[44:45], v[48:49] op_sel_hi:[1,0]
	v_pk_mul_f32 v[42:43], v[42:43], v[48:49] op_sel_hi:[1,0]
	v_pk_mul_f32 v[52:53], v[40:41], v[48:49] op_sel_hi:[1,0]
	s_cbranch_vccnz .LBB0_1275
	v_bfe_u32 v41, v44, 16, 1
	v_lshl_add_u32 v40, v70, 19, v54
	v_add3_u32 v49, v44, v41, s76
	v_mov_b32_e32 v41, v141
	v_lshl_add_u64 v[56:57], v[40:41], 1, s[22:23]
	global_store_short_d16_hi v[56:57], v49, off
	v_bfe_u32 v41, v52, 16, 1
	v_or_b32_e32 v56, 0x8000, v40
	v_mov_b32_e32 v57, v141
	v_add3_u32 v41, v52, v41, s76
	v_lshl_add_u64 v[56:57], v[56:57], 1, s[22:23]
	global_store_short_d16_hi v[56:57], v41, off
	v_bfe_u32 v41, v45, 16, 1
	v_or_b32_e32 v56, 0x2000, v40
	v_mov_b32_e32 v57, v141
	v_add3_u32 v41, v45, v41, s76
	v_lshl_add_u64 v[56:57], v[56:57], 1, s[22:23]
	global_store_short_d16_hi v[56:57], v41, off
	v_bfe_u32 v41, v53, 16, 1
	v_or_b32_e32 v56, 0xa000, v40
	v_mov_b32_e32 v57, v141
	v_add3_u32 v41, v53, v41, s76
	v_lshl_add_u64 v[56:57], v[56:57], 1, s[22:23]
	global_store_short_d16_hi v[56:57], v41, off
	v_bfe_u32 v41, v46, 16, 1
	v_or_b32_e32 v56, 0x4000, v40
	v_mov_b32_e32 v57, v141
	v_add3_u32 v41, v46, v41, s76
	v_lshl_add_u64 v[56:57], v[56:57], 1, s[22:23]
	global_store_short_d16_hi v[56:57], v41, off
	v_bfe_u32 v41, v42, 16, 1
	v_or_b32_e32 v56, 0xc000, v40
	v_mov_b32_e32 v57, v141
	v_add3_u32 v41, v42, v41, s76
	v_lshl_add_u64 v[56:57], v[56:57], 1, s[22:23]
	global_store_short_d16_hi v[56:57], v41, off
	v_bfe_u32 v41, v47, 16, 1
	v_or_b32_e32 v56, 0x6000, v40
	v_mov_b32_e32 v57, v141
	v_add3_u32 v41, v47, v41, s76
	v_lshl_add_u64 v[56:57], v[56:57], 1, s[22:23]
	global_store_short_d16_hi v[56:57], v41, off
	v_bfe_u32 v41, v43, 16, 1
	v_add3_u32 v49, v43, v41, s76
	v_or_b32_e32 v40, 0xe000, v40
	v_mov_b32_e32 v41, v141
	v_lshl_add_u64 v[40:41], v[40:41], 1, s[22:23]
	s_mov_b64 s[12:13], 0
	global_store_short_d16_hi v[40:41], v49, off
.LBB0_1275:
	v_ashrrev_i32_e32 v51, 31, v50
	v_lshlrev_b64 v[40:41], 10, v[50:51]
	s_andn2_b64 vcc, exec, s[12:13]
	v_lshl_add_u64 v[40:41], s[20:21], 0, v[40:41]
	s_cbranch_vccnz .LBB0_1277
	s_lshl_b32 s12, s60, 7
	s_ashr_i32 s13, s12, 31
	v_cvt_pk_bf16_f32 v44, v44, v45
	v_cvt_pk_bf16_f32 v45, v46, v47
	v_cvt_pk_bf16_f32 v47, v42, v43
	v_lshl_add_u64 v[42:43], s[12:13], 1, v[40:41]
	s_lshl_b32 s14, s69, 1
	v_lshl_add_u64 v[42:43], v[42:43], 0, s[14:15]
	v_cvt_pk_bf16_f32 v46, v52, v53
	v_lshl_add_u64 v[42:43], v[42:43], 0, v[140:141]
	global_store_dwordx4 v[42:43], v[44:47], off
.LBB0_1277:
	v_mov_b32_e32 v49, v48
	v_mov_b32_e32 v42, v48
	v_mov_b32_e32 v43, v48
	v_pk_mul_f32 v[38:39], v[38:39], v[42:43]
	v_pk_mul_f32 v[36:37], v[36:37], v[48:49]
	v_pk_mul_f32 v[34:35], v[34:35], v[42:43]
	v_pk_mul_f32 v[32:33], v[32:33], v[48:49]
	s_and_b64 vcc, exec, s[4:5]
	s_mov_b64 s[12:13], -1
	s_cbranch_vccnz .LBB0_1279
	v_bfe_u32 v43, v36, 16, 1
	v_lshl_add_u32 v42, v58, 19, v54
	v_add3_u32 v46, v36, v43, s76
	v_mov_b32_e32 v43, v141
	v_lshl_add_u64 v[44:45], v[42:43], 1, s[22:23]
	global_store_short_d16_hi v[44:45], v46, off
	v_bfe_u32 v43, v32, 16, 1
	v_or_b32_e32 v44, 0x8000, v42
	v_mov_b32_e32 v45, v141
	v_add3_u32 v43, v32, v43, s76
	v_lshl_add_u64 v[44:45], v[44:45], 1, s[22:23]
	global_store_short_d16_hi v[44:45], v43, off
	v_bfe_u32 v43, v37, 16, 1
	v_or_b32_e32 v44, 0x2000, v42
	v_mov_b32_e32 v45, v141
	v_add3_u32 v43, v37, v43, s76
	v_lshl_add_u64 v[44:45], v[44:45], 1, s[22:23]
	global_store_short_d16_hi v[44:45], v43, off
	v_bfe_u32 v43, v33, 16, 1
	v_or_b32_e32 v44, 0xa000, v42
	v_mov_b32_e32 v45, v141
	v_add3_u32 v43, v33, v43, s76
	v_lshl_add_u64 v[44:45], v[44:45], 1, s[22:23]
	global_store_short_d16_hi v[44:45], v43, off
	v_bfe_u32 v43, v38, 16, 1
	v_or_b32_e32 v44, 0x4000, v42
	v_mov_b32_e32 v45, v141
	v_add3_u32 v43, v38, v43, s76
	v_lshl_add_u64 v[44:45], v[44:45], 1, s[22:23]
	global_store_short_d16_hi v[44:45], v43, off
	v_bfe_u32 v43, v34, 16, 1
	v_or_b32_e32 v44, 0xc000, v42
	v_mov_b32_e32 v45, v141
	v_add3_u32 v43, v34, v43, s76
	v_lshl_add_u64 v[44:45], v[44:45], 1, s[22:23]
	global_store_short_d16_hi v[44:45], v43, off
	v_bfe_u32 v43, v39, 16, 1
	v_or_b32_e32 v44, 0x6000, v42
	v_mov_b32_e32 v45, v141
	v_add3_u32 v43, v39, v43, s76
	v_lshl_add_u64 v[44:45], v[44:45], 1, s[22:23]
	global_store_short_d16_hi v[44:45], v43, off
	v_bfe_u32 v43, v35, 16, 1
	v_add3_u32 v44, v35, v43, s76
	v_or_b32_e32 v42, 0xe000, v42
	v_mov_b32_e32 v43, v141
	v_lshl_add_u64 v[42:43], v[42:43], 1, s[22:23]
	s_mov_b64 s[12:13], 0
	global_store_short_d16_hi v[42:43], v44, off
.LBB0_1279:
	s_andn2_b64 vcc, exec, s[12:13]
	s_cbranch_vccnz .LBB0_1281
	s_lshl_b32 s12, s50, 6
	s_ashr_i32 s13, s12, 31
	v_cvt_pk_bf16_f32 v36, v36, v37
	v_cvt_pk_bf16_f32 v37, v38, v39
	v_cvt_pk_bf16_f32 v38, v32, v33
	v_lshl_add_u64 v[32:33], s[12:13], 1, v[40:41]
	s_lshl_b32 s14, s69, 1
	v_lshl_add_u64 v[32:33], v[32:33], 0, s[14:15]
	v_cvt_pk_bf16_f32 v39, v34, v35
	v_lshl_add_u64 v[32:33], v[32:33], 0, v[140:141]
	global_store_dwordx4 v[32:33], v[36:39], off
; DI unsigned f2bf(float f) { unsigned u = __builtin_bit_cast(unsigned, f); return (u + 0x7fffu + ((u >> 16) & 1u)) >> 16; }
; DI unsigned pk2(float lo, float hi) { typedef float v2f __attribute__((ext_vector_type(2))); typedef __bf16 v2b __attribute__((ext_vector_type(2))); v2f v = {lo, hi}; v2b b = __builtin_convertvector(v, v2b); return __builtin_bit_cast(unsigned, b); }
;     DI void operator()(const f32x4 (&acc)[2][2][4][2], const Unit& u, int wr, int wc, int fr, int fq) const {
;         const int row0 = u.pm * 256 + wr * 64 + fr;
; #pragma unroll
;         for (int ai = 0; ai < 2; ++ai)
; #pragma unroll
;             for (int m = 0; m < 4; ++m) {
;                 const int row = row0 + ai * 128 + m * 16; const float rs = row_rstd<1>(P, row, 1.0f / 256.0f);
;                 const int b = row >> 13, s = row & 8191;
; #pragma unroll
;                 for (int bj = 0; bj < 2; ++bj) {
;                     const int h = u.pn * 2 + bj;
;                     const f32x4 a = acc[ai][bj][m][0] * rs, c = acc[ai][bj][m][1] * rs;
;                     if (wc < 2) {
;                         u32x4 w; w.x = pk2(a[0], a[1]); w.y = pk2(a[2], a[3]); w.z = pk2(c[0], c[1]); w.w = pk2(c[2], c[3]);
;                         *(u32x4*)(KN + (size_t)row * 512 + h * 64 + wc * 32 + 8 * fq) = w;
;                     } else {
;                         const unsigned vo = (unsigned)((b * 8 + h) * 64 + (wc - 2) * 32 + 8 * fq) * (unsigned)SEQ + (unsigned)s;
; #pragma unroll
;                         for (int i = 0; i < 4; ++i) { Vt[vo + (unsigned)(i * SEQ)] = (bf16_t)f2bf(a[i]); Vt[vo + (unsigned)((4 + i) * SEQ)] = (bf16_t)f2bf(c[i]); }
;                     }
;                 }
.LBB0_1281:
	s_nop 0
	v_add_u32_e32 v34, 0xa0, v152
	s_and_b64 vcc, exec, s[4:5]
	v_and_or_b32 v38, v34, s78, v163
	s_mov_b64 s[12:13], -1
	s_waitcnt lgkmcnt(0)
	v_fmamk_f32 v32, v204, 0x3b800000, v167
	v_rsq_f32_e32 v32, v32
	s_nop 0
	v_pk_mul_f32 v[30:31], v[30:31], v[32:33] op_sel_hi:[1,0]
	v_pk_mul_f32 v[28:29], v[28:29], v[32:33] op_sel_hi:[1,0]
	v_pk_mul_f32 v[26:27], v[26:27], v[32:33] op_sel_hi:[1,0]
	v_pk_mul_f32 v[36:37], v[24:25], v[32:33] op_sel_hi:[1,0]
	s_cbranch_vccnz .LBB0_1283
	v_bfe_u32 v25, v28, 16, 1
	v_lshl_add_u32 v24, v70, 19, v38
	v_add3_u32 v33, v28, v25, s76
	v_mov_b32_e32 v25, v141
	v_lshl_add_u64 v[40:41], v[24:25], 1, s[22:23]
	global_store_short_d16_hi v[40:41], v33, off
	v_bfe_u32 v25, v36, 16, 1
	v_or_b32_e32 v40, 0x8000, v24
	v_mov_b32_e32 v41, v141
	v_add3_u32 v25, v36, v25, s76
	v_lshl_add_u64 v[40:41], v[40:41], 1, s[22:23]
	global_store_short_d16_hi v[40:41], v25, off
	v_bfe_u32 v25, v29, 16, 1
	v_or_b32_e32 v40, 0x2000, v24
	v_mov_b32_e32 v41, v141
	v_add3_u32 v25, v29, v25, s76
	v_lshl_add_u64 v[40:41], v[40:41], 1, s[22:23]
	global_store_short_d16_hi v[40:41], v25, off
	v_bfe_u32 v25, v37, 16, 1
	v_or_b32_e32 v40, 0xa000, v24
	v_mov_b32_e32 v41, v141
	v_add3_u32 v25, v37, v25, s76
	v_lshl_add_u64 v[40:41], v[40:41], 1, s[22:23]
	global_store_short_d16_hi v[40:41], v25, off
	v_bfe_u32 v25, v30, 16, 1
	v_or_b32_e32 v40, 0x4000, v24
	v_mov_b32_e32 v41, v141
	v_add3_u32 v25, v30, v25, s76
	v_lshl_add_u64 v[40:41], v[40:41], 1, s[22:23]
	global_store_short_d16_hi v[40:41], v25, off
	v_bfe_u32 v25, v26, 16, 1
	v_or_b32_e32 v40, 0xc000, v24
	v_mov_b32_e32 v41, v141
	v_add3_u32 v25, v26, v25, s76
	v_lshl_add_u64 v[40:41], v[40:41], 1, s[22:23]
	global_store_short_d16_hi v[40:41], v25, off
	v_bfe_u32 v25, v31, 16, 1
	v_or_b32_e32 v40, 0x6000, v24
	v_mov_b32_e32 v41, v141
	v_add3_u32 v25, v31, v25, s76
	v_lshl_add_u64 v[40:41], v[40:41], 1, s[22:23]
	global_store_short_d16_hi v[40:41], v25, off
	v_bfe_u32 v25, v27, 16, 1
	v_add3_u32 v33, v27, v25, s76
	v_or_b32_e32 v24, 0xe000, v24
	v_mov_b32_e32 v25, v141
	v_lshl_add_u64 v[24:25], v[24:25], 1, s[22:23]
	s_mov_b64 s[12:13], 0
	global_store_short_d16_hi v[24:25], v33, off
.LBB0_1283:
	v_ashrrev_i32_e32 v35, 31, v34
	v_lshlrev_b64 v[24:25], 10, v[34:35]
	s_andn2_b64 vcc, exec, s[12:13]
	v_lshl_add_u64 v[24:25], s[20:21], 0, v[24:25]
	s_cbranch_vccnz .LBB0_1285
	s_lshl_b32 s12, s60, 7
	s_ashr_i32 s13, s12, 31
	v_cvt_pk_bf16_f32 v28, v28, v29
	v_cvt_pk_bf16_f32 v29, v30, v31
	v_cvt_pk_bf16_f32 v31, v26, v27
	v_lshl_add_u64 v[26:27], s[12:13], 1, v[24:25]
	s_lshl_b32 s14, s69, 1
	v_lshl_add_u64 v[26:27], v[26:27], 0, s[14:15]
	v_cvt_pk_bf16_f32 v30, v36, v37
	v_lshl_add_u64 v[26:27], v[26:27], 0, v[140:141]
	global_store_dwordx4 v[26:27], v[28:31], off
.LBB0_1285:
	v_mov_b32_e32 v33, v32
	v_mov_b32_e32 v26, v32
	v_mov_b32_e32 v27, v32
	v_pk_mul_f32 v[22:23], v[22:23], v[26:27]
	v_pk_mul_f32 v[20:21], v[20:21], v[32:33]
	v_pk_mul_f32 v[18:19], v[18:19], v[26:27]
	v_pk_mul_f32 v[16:17], v[16:17], v[32:33]
	s_and_b64 vcc, exec, s[4:5]
	s_mov_b64 s[12:13], -1
	s_cbranch_vccnz .LBB0_1287
	v_bfe_u32 v27, v20, 16, 1
	v_lshl_add_u32 v26, v58, 19, v38
	v_add3_u32 v30, v20, v27, s76
	v_mov_b32_e32 v27, v141
	v_lshl_add_u64 v[28:29], v[26:27], 1, s[22:23]
	global_store_short_d16_hi v[28:29], v30, off
	v_bfe_u32 v27, v16, 16, 1
	v_or_b32_e32 v28, 0x8000, v26
	v_mov_b32_e32 v29, v141
	v_add3_u32 v27, v16, v27, s76
	v_lshl_add_u64 v[28:29], v[28:29], 1, s[22:23]
	global_store_short_d16_hi v[28:29], v27, off
	v_bfe_u32 v27, v21, 16, 1
	v_or_b32_e32 v28, 0x2000, v26
	v_mov_b32_e32 v29, v141
	v_add3_u32 v27, v21, v27, s76
	v_lshl_add_u64 v[28:29], v[28:29], 1, s[22:23]
	global_store_short_d16_hi v[28:29], v27, off
	v_bfe_u32 v27, v17, 16, 1
	v_or_b32_e32 v28, 0xa000, v26
	v_mov_b32_e32 v29, v141
	v_add3_u32 v27, v17, v27, s76
	v_lshl_add_u64 v[28:29], v[28:29], 1, s[22:23]
	global_store_short_d16_hi v[28:29], v27, off
	v_bfe_u32 v27, v22, 16, 1
	v_or_b32_e32 v28, 0x4000, v26
	v_mov_b32_e32 v29, v141
	v_add3_u32 v27, v22, v27, s76
	v_lshl_add_u64 v[28:29], v[28:29], 1, s[22:23]
	global_store_short_d16_hi v[28:29], v27, off
	v_bfe_u32 v27, v18, 16, 1
	v_or_b32_e32 v28, 0xc000, v26
	v_mov_b32_e32 v29, v141
	v_add3_u32 v27, v18, v27, s76
	v_lshl_add_u64 v[28:29], v[28:29], 1, s[22:23]
	global_store_short_d16_hi v[28:29], v27, off
	v_bfe_u32 v27, v23, 16, 1
	v_or_b32_e32 v28, 0x6000, v26
	v_mov_b32_e32 v29, v141
	v_add3_u32 v27, v23, v27, s76
	v_lshl_add_u64 v[28:29], v[28:29], 1, s[22:23]
	global_store_short_d16_hi v[28:29], v27, off
	v_bfe_u32 v27, v19, 16, 1
	v_add3_u32 v28, v19, v27, s76
	v_or_b32_e32 v26, 0xe000, v26
	v_mov_b32_e32 v27, v141
	v_lshl_add_u64 v[26:27], v[26:27], 1, s[22:23]
	s_mov_b64 s[12:13], 0
	global_store_short_d16_hi v[26:27], v28, off
; DI unsigned f2bf(float f) { unsigned u = __builtin_bit_cast(unsigned, f); return (u + 0x7fffu + ((u >> 16) & 1u)) >> 16; }
; DI unsigned pk2(float lo, float hi) { typedef float v2f __attribute__((ext_vector_type(2))); typedef __bf16 v2b __attribute__((ext_vector_type(2))); v2f v = {lo, hi}; v2b b = __builtin_convertvector(v, v2b); return __builtin_bit_cast(unsigned, b); }
;     DI void operator()(const f32x4 (&acc)[2][2][4][2], const Unit& u, int wr, int wc, int fr, int fq) const {
;         const int row0 = u.pm * 256 + wr * 64 + fr;
; #pragma unroll
;         for (int ai = 0; ai < 2; ++ai)
; #pragma unroll
;             for (int m = 0; m < 4; ++m) {
;                 const int row = row0 + ai * 128 + m * 16; const float rs = row_rstd<1>(P, row, 1.0f / 256.0f);
;                 const int b = row >> 13, s = row & 8191;
; #pragma unroll
;                 for (int bj = 0; bj < 2; ++bj) {
;                     const int h = u.pn * 2 + bj;
;                     const f32x4 a = acc[ai][bj][m][0] * rs, c = acc[ai][bj][m][1] * rs;
;                     if (wc < 2) {
;                         u32x4 w; w.x = pk2(a[0], a[1]); w.y = pk2(a[2], a[3]); w.z = pk2(c[0], c[1]); w.w = pk2(c[2], c[3]);
;                         *(u32x4*)(KN + (size_t)row * 512 + h * 64 + wc * 32 + 8 * fq) = w;
;                     } else {
;                         const unsigned vo = (unsigned)((b * 8 + h) * 64 + (wc - 2) * 32 + 8 * fq) * (unsigned)SEQ + (unsigned)s;
; #pragma unroll
;                         for (int i = 0; i < 4; ++i) { Vt[vo + (unsigned)(i * SEQ)] = (bf16_t)f2bf(a[i]); Vt[vo + (unsigned)((4 + i) * SEQ)] = (bf16_t)f2bf(c[i]); }
;                     }
;                 }
.LBB0_1287:
	s_andn2_b64 vcc, exec, s[12:13]
	s_cbranch_vccnz .LBB0_1289
	s_lshl_b32 s12, s50, 6
	s_ashr_i32 s13, s12, 31
	v_cvt_pk_bf16_f32 v20, v20, v21
	v_cvt_pk_bf16_f32 v21, v22, v23
	v_cvt_pk_bf16_f32 v22, v16, v17
	v_lshl_add_u64 v[16:17], s[12:13], 1, v[24:25]
	s_lshl_b32 s14, s69, 1
	v_lshl_add_u64 v[16:17], v[16:17], 0, s[14:15]
	v_cvt_pk_bf16_f32 v23, v18, v19
	v_lshl_add_u64 v[16:17], v[16:17], 0, v[140:141]
	global_store_dwordx4 v[16:17], v[20:23], off
.LBB0_1289:
	s_nop 0
	v_add_u32_e32 v18, 0xb0, v152
	s_and_b64 vcc, exec, s[4:5]
	v_and_or_b32 v22, v18, s79, v163
	s_mov_b64 s[12:13], -1
	s_waitcnt lgkmcnt(0)
	v_fmamk_f32 v16, v205, 0x3b800000, v167
	v_rsq_f32_e32 v16, v16
	s_nop 0
	v_pk_mul_f32 v[14:15], v[14:15], v[16:17] op_sel_hi:[1,0]
	v_pk_mul_f32 v[12:13], v[12:13], v[16:17] op_sel_hi:[1,0]
	v_pk_mul_f32 v[10:11], v[10:11], v[16:17] op_sel_hi:[1,0]
	v_pk_mul_f32 v[20:21], v[8:9], v[16:17] op_sel_hi:[1,0]
	s_cbranch_vccnz .LBB0_1291
	v_bfe_u32 v9, v12, 16, 1
	v_lshl_add_u32 v8, v70, 19, v22
	v_add3_u32 v17, v12, v9, s76
	v_mov_b32_e32 v9, v141
	v_lshl_add_u64 v[24:25], v[8:9], 1, s[22:23]
	global_store_short_d16_hi v[24:25], v17, off
	v_bfe_u32 v9, v20, 16, 1
	v_or_b32_e32 v24, 0x8000, v8
	v_mov_b32_e32 v25, v141
	v_add3_u32 v9, v20, v9, s76
	v_lshl_add_u64 v[24:25], v[24:25], 1, s[22:23]
	global_store_short_d16_hi v[24:25], v9, off
	v_bfe_u32 v9, v13, 16, 1
	v_or_b32_e32 v24, 0x2000, v8
	v_mov_b32_e32 v25, v141
	v_add3_u32 v9, v13, v9, s76
	v_lshl_add_u64 v[24:25], v[24:25], 1, s[22:23]
	global_store_short_d16_hi v[24:25], v9, off
	v_bfe_u32 v9, v21, 16, 1
	v_or_b32_e32 v24, 0xa000, v8
	v_mov_b32_e32 v25, v141
	v_add3_u32 v9, v21, v9, s76
	v_lshl_add_u64 v[24:25], v[24:25], 1, s[22:23]
	global_store_short_d16_hi v[24:25], v9, off
	v_bfe_u32 v9, v14, 16, 1
	v_or_b32_e32 v24, 0x4000, v8
	v_mov_b32_e32 v25, v141
	v_add3_u32 v9, v14, v9, s76
	v_lshl_add_u64 v[24:25], v[24:25], 1, s[22:23]
	global_store_short_d16_hi v[24:25], v9, off
	v_bfe_u32 v9, v10, 16, 1
	v_or_b32_e32 v24, 0xc000, v8
	v_mov_b32_e32 v25, v141
	v_add3_u32 v9, v10, v9, s76
	v_lshl_add_u64 v[24:25], v[24:25], 1, s[22:23]
	global_store_short_d16_hi v[24:25], v9, off
	v_bfe_u32 v9, v15, 16, 1
	v_or_b32_e32 v24, 0x6000, v8
	v_mov_b32_e32 v25, v141
	v_add3_u32 v9, v15, v9, s76
	v_lshl_add_u64 v[24:25], v[24:25], 1, s[22:23]
	global_store_short_d16_hi v[24:25], v9, off
	v_bfe_u32 v9, v11, 16, 1
	v_add3_u32 v17, v11, v9, s76
	v_or_b32_e32 v8, 0xe000, v8
	v_mov_b32_e32 v9, v141
	v_lshl_add_u64 v[8:9], v[8:9], 1, s[22:23]
	s_mov_b64 s[12:13], 0
	global_store_short_d16_hi v[8:9], v17, off
.LBB0_1291:
	v_ashrrev_i32_e32 v19, 31, v18
	v_lshlrev_b64 v[8:9], 10, v[18:19]
	s_andn2_b64 vcc, exec, s[12:13]
	v_lshl_add_u64 v[8:9], s[20:21], 0, v[8:9]
	s_cbranch_vccnz .LBB0_1293
	s_lshl_b32 s12, s60, 7
	s_ashr_i32 s13, s12, 31
	v_cvt_pk_bf16_f32 v12, v12, v13
	v_cvt_pk_bf16_f32 v13, v14, v15
	v_cvt_pk_bf16_f32 v15, v10, v11
	v_lshl_add_u64 v[10:11], s[12:13], 1, v[8:9]
	s_lshl_b32 s14, s69, 1
	v_lshl_add_u64 v[10:11], v[10:11], 0, s[14:15]
	v_cvt_pk_bf16_f32 v14, v20, v21
	v_lshl_add_u64 v[10:11], v[10:11], 0, v[140:141]
	global_store_dwordx4 v[10:11], v[12:15], off

; DI unsigned f2bf(float f) { unsigned u = __builtin_bit_cast(unsigned, f); return (u + 0x7fffu + ((u >> 16) & 1u)) >> 16; }
; DI unsigned pk2(float lo, float hi) { typedef float v2f __attribute__((ext_vector_type(2))); typedef __bf16 v2b __attribute__((ext_vector_type(2))); v2f v = {lo, hi}; v2b b = __builtin_convertvector(v, v2b); return __builtin_bit_cast(unsigned, b); }
;     DI void operator()(const f32x4 (&acc)[2][2][4][2], const Unit& u, int wr, int wc, int fr, int fq) const {
;     ...
;                 const int b = row >> 13, s = row & 8191;
; #pragma unroll
;                 for (int bj = 0; bj < 2; ++bj) {
;                     const int h = u.pn * 2 + bj;
;                     const f32x4 a = acc[ai][bj][m][0] * rs, c = acc[ai][bj][m][1] * rs;
;                     if (wc < 2) {
;                         u32x4 w; w.x = pk2(a[0], a[1]); w.y = pk2(a[2], a[3]); w.z = pk2(c[0], c[1]); w.w = pk2(c[2], c[3]);
;                         *(u32x4*)(KN + (size_t)row * 512 + h * 64 + wc * 32 + 8 * fq) = w;
;                     } else {
;                         const unsigned vo = (unsigned)((b * 8 + h) * 64 + (wc - 2) * 32 + 8 * fq) * (unsigned)SEQ + (unsigned)s;
; #pragma unroll
;                         for (int i = 0; i < 4; ++i) { Vt[vo + (unsigned)(i * SEQ)] = (bf16_t)f2bf(a[i]); Vt[vo + (unsigned)((4 + i) * SEQ)] = (bf16_t)f2bf(c[i]); }
;                     }
;                 }
.LBB0_1296:
	v_bfe_u32 v11, v4, 16, 1
	v_lshl_add_u32 v10, v58, 19, v22
	v_add3_u32 v14, v4, v11, s76
	v_mov_b32_e32 v11, v141
	v_lshl_add_u64 v[12:13], v[10:11], 1, s[22:23]
	global_store_short_d16_hi v[12:13], v14, off
	v_bfe_u32 v11, v0, 16, 1
	v_or_b32_e32 v12, 0x8000, v10
	v_mov_b32_e32 v13, v141
	v_add3_u32 v11, v0, v11, s76
	v_lshl_add_u64 v[12:13], v[12:13], 1, s[22:23]
	global_store_short_d16_hi v[12:13], v11, off
	v_bfe_u32 v11, v5, 16, 1
	v_or_b32_e32 v12, 0x2000, v10
	v_mov_b32_e32 v13, v141
	v_add3_u32 v11, v5, v11, s76
	v_lshl_add_u64 v[12:13], v[12:13], 1, s[22:23]
	global_store_short_d16_hi v[12:13], v11, off
	v_bfe_u32 v11, v1, 16, 1
	v_or_b32_e32 v12, 0xa000, v10
	v_mov_b32_e32 v13, v141
	v_add3_u32 v11, v1, v11, s76
	v_lshl_add_u64 v[12:13], v[12:13], 1, s[22:23]
	global_store_short_d16_hi v[12:13], v11, off
	v_bfe_u32 v11, v6, 16, 1
	v_or_b32_e32 v12, 0x4000, v10
	v_mov_b32_e32 v13, v141
	v_add3_u32 v11, v6, v11, s76
	v_lshl_add_u64 v[12:13], v[12:13], 1, s[22:23]
	global_store_short_d16_hi v[12:13], v11, off
	v_bfe_u32 v11, v2, 16, 1
	v_or_b32_e32 v12, 0xc000, v10
	v_mov_b32_e32 v13, v141
	v_add3_u32 v11, v2, v11, s76
	v_lshl_add_u64 v[12:13], v[12:13], 1, s[22:23]
	global_store_short_d16_hi v[12:13], v11, off
	v_bfe_u32 v11, v7, 16, 1
	v_or_b32_e32 v12, 0x6000, v10
	v_mov_b32_e32 v13, v141
	v_add3_u32 v11, v7, v11, s76
	v_lshl_add_u64 v[12:13], v[12:13], 1, s[22:23]
	global_store_short_d16_hi v[12:13], v11, off
	v_bfe_u32 v11, v3, 16, 1
	v_add3_u32 v12, v3, v11, s76
	v_or_b32_e32 v10, 0xe000, v10
	v_mov_b32_e32 v11, v141
	v_lshl_add_u64 v[10:11], v[10:11], 1, s[22:23]
	global_store_short_d16_hi v[10:11], v12, off
	s_cbranch_execnz .LBB0_1295
.LBB0_1297:
	s_lshl_b32 s4, s50, 6
	s_ashr_i32 s5, s4, 31
	v_cvt_pk_bf16_f32 v4, v4, v5
	v_cvt_pk_bf16_f32 v5, v6, v7
	v_cvt_pk_bf16_f32 v6, v0, v1
	v_lshl_add_u64 v[0:1], s[4:5], 1, v[8:9]
	s_lshl_b32 s14, s69, 1
	v_lshl_add_u64 v[0:1], v[0:1], 0, s[14:15]
	v_cvt_pk_bf16_f32 v7, v2, v3
	v_lshl_add_u64 v[0:1], v[0:1], 0, v[140:141]
	global_store_dwordx4 v[0:1], v[4:7], off
	s_and_b64 vcc, exec, s[2:3]
	s_mov_b64 s[2:3], -1
	s_cbranch_vccnz .LBB0_1216

; #define LAS __attribute__((address_space(3)))
; DI float bflo(unsigned w) { return __uint_as_float(w << 16); }
; DI void sgu_item(int g, int bc, int par, const bf16_t* SGW, const bf16_t* Vg, const float* VST, const float* lng, const float* lnb, const float* sgb, bf16_t* U, LAS unsigned char* lds) {
;     constexpr int RS = 272;
;     const int tid = threadIdx.x, lane = tid & 63, w = __builtin_amdgcn_readfirstlane(tid >> 6), row0 = bc * 128;
;     LAS unsigned char* Wl = lds + par * (192 * RS); LAS unsigned char* Vl = Wl + 128 * RS;
;     const int j = lane & 15, q = lane >> 4, t0 = 16 * w, nks = (t0 + 15) / 32 + 1, t = t0 + j;
;     u32x4 wreg[4];
; #pragma unroll
;     for (int i = 0; i < 4; ++i) { const int c = tid + i * 512, rr = c >> 4, cc = c & 15; wreg[i] = *(const u32x4*)(SGW + (size_t)g * 16384 + rr * 128 + cc * 8); }
;     const int s = tid & 127, dg = tid >> 7, row = row0 + s;
;     f32x4 pst[8];
; #pragma unroll
;     for (int i = 0; i < 8; ++i) pst[i] = *(const f32x4*)(VST + (size_t)row * 32 + 4 * i);
;     const u32x4 a = *(const u32x4*)(Vg + (size_t)row * 512 + g * 64 + dg * 16), b = *(const u32x4*)(Vg + (size_t)row * 512 + g * 64 + dg * 16 + 8);
;     bf16_t* up = U + (size_t)(row0 + t) * 512 + g * 64 + 4 * q;
;     u32x2 uu[4];
; #pragma unroll
;     for (int db = 0; db < 4; ++db) uu[db] = *(const u32x2*)(up + 16 * db);
;     const float bias = sgb[g * 128 + t];
; #pragma unroll
;     for (int i = 0; i < 4; ++i) { const int c = tid + i * 512, rr = c >> 4, cc = c & 15; *(LAS u32x4*)(Wl + rr * RS + cc * 16) = wreg[i]; }
;     {
;         float s1 = 0.f, s2 = 0.f;
; #pragma unroll
;         for (int i = 0; i < 8; ++i) { s1 += pst[i][0] + pst[i][2]; s2 += pst[i][1] + pst[i][3]; }
;         const float mu = s1 * (1.0f / 512.0f), var = s2 * (1.0f / 512.0f) - mu * mu, rstd = __builtin_amdgcn_rsqf(fmaxf(var, 0.f) + EPS);
;         const unsigned wd[8] = {a.x, a.y, a.z, a.w, b.x, b.y, b.z, b.w};
; #pragma unroll
;         for (int i = 0; i < 8; ++i) {
;             const int d = dg * 16 + 2 * i, c = g * 64 + d;
;             const float v0 = (bflo(wd[i]) - mu) * rstd * lng[c] + lnb[c], v1 = (bfhi(wd[i]) - mu) * rstd * lng[c + 1] + lnb[c + 1];
;             *(LAS bf16_t*)(Vl + d * RS + s * 2) = (bf16_t)f2bf(v0); *(LAS bf16_t*)(Vl + (d + 1) * RS + s * 2) = (bf16_t)f2bf(v1);
;         }
;     }
;     __syncthreads();
.LBB0_1303:
	s_ashr_i32 s14, s12, 7
	s_ashr_i32 s15, s14, 31
	s_lshl_b64 s[16:17], s[14:15], 15
	s_lshl_b32 s13, s12, 7
	v_lshl_add_u64 v[32:33], v[20:21], 0, s[16:17]
	s_and_b32 s17, s13, 0x3f80
	v_lshl_add_u64 v[34:35], v[32:33], 0, v[22:23]
	v_lshl_add_u64 v[4:5], v[32:33], 0, v[24:25]
	v_or_b32_e32 v38, s17, v42
	global_load_dwordx4 v[0:3], v[34:35], off
	s_nop 0
	global_load_dwordx4 v[4:7], v[4:5], off
	v_lshlrev_b32_e32 v16, 7, v38
	v_lshl_add_u64 v[36:37], s[4:5], 0, v[16:17]
	global_load_dwordx4 v[8:11], v[36:37], off
	global_load_dwordx4 v[12:15], v[36:37], off offset:16
	global_load_dwordx4 v[56:59], v[36:37], off offset:32
	global_load_dwordx4 v[60:63], v[36:37], off offset:48
	v_add_co_u32_e32 v34, vcc, s7, v34
	s_lshl_b32 s14, s14, 6
	s_nop 0
	v_addc_co_u32_e32 v35, vcc, 0, v35, vcc
	global_load_dwordx4 v[64:67], v[34:35], off
	global_load_dwordx4 v[68:71], v[36:37], off offset:64
	global_load_dwordx4 v[72:75], v[36:37], off offset:80
	global_load_dwordx4 v[76:79], v[36:37], off offset:96
	global_load_dwordx4 v[80:83], v[36:37], off offset:112
	s_ashr_i32 s15, s14, 31
	v_lshl_add_u64 v[32:33], v[32:33], 0, v[26:27]
	v_lshlrev_b32_e32 v16, 10, v38
	s_lshl_b64 s[18:19], s[14:15], 1
	global_load_dwordx4 v[84:87], v[32:33], off
	v_lshl_add_u64 v[36:37], s[2:3], 0, v[16:17]
	v_lshl_add_u64 v[36:37], v[36:37], 0, s[18:19]
	v_lshl_add_u64 v[32:33], v[36:37], 0, v[28:29]
	global_load_dwordx4 v[88:91], v[32:33], off
	v_add_u32_e32 v34, s14, v131
	v_ashrrev_i32_e32 v35, 31, v34
	v_readlane_b32 s36, v249, 33
	v_lshlrev_b64 v[34:35], 2, v[34:35]
	v_readlane_b32 s40, v249, 37
	v_readlane_b32 s41, v249, 38
	v_readlane_b32 s38, v249, 35
	v_readlane_b32 s39, v249, 36
	v_lshl_add_u64 v[114:115], s[40:41], 0, v[34:35]
	v_readfirstlane_b32 s14, v196
	v_lshl_add_u64 v[112:113], s[38:39], 0, v[34:35]
	global_load_dwordx4 v[92:95], v[114:115], off
	global_load_dwordx4 v[96:99], v[112:113], off
	global_load_dwordx4 v[100:103], v[112:113], off offset:16
	global_load_dwordx4 v[104:107], v[114:115], off offset:16
	s_mul_i32 s13, s6, 0xcc00
	s_lshr_b32 s21, s14, 2
	s_add_i32 s16, s13, 0
	s_and_b32 s21, s21, 0x3ffffff0
	s_and_b32 s20, s12, 0xffffff80
	v_add_u32_e32 v16, s16, v18
	v_or_b32_e32 v35, s21, v129
	v_add_u32_e32 v116, v16, v43
	v_add_u32_e32 v117, v16, v44
	v_add_u32_e32 v118, v16, v45
	v_add_u32_e32 v34, s20, v35
	v_add_u32_e32 v16, s17, v35
	v_readlane_b32 s44, v249, 41
	v_readlane_b32 s45, v249, 42
	v_ashrrev_i32_e32 v35, 31, v34
	v_lshlrev_b64 v[36:37], 10, v[16:17]
	v_lshl_add_u64 v[34:35], v[34:35], 2, s[44:45]
	v_lshl_add_u64 v[36:37], s[8:9], 0, v[36:37]
	global_load_dword v16, v[34:35], off
	global_load_dwordx4 v[108:111], v[32:33], off offset:16
	v_lshl_add_u64 v[32:33], v[36:37], 0, s[18:19]
	v_lshl_add_u64 v[32:33], v[32:33], 0, v[30:31]
	global_load_dwordx2 v[40:41], v[32:33], off
	global_load_dwordx2 v[38:39], v[32:33], off offset:32
	global_load_dwordx2 v[36:37], v[32:33], off offset:64
	global_load_dwordx2 v[34:35], v[32:33], off offset:96
	s_lshr_b32 s15, s14, 7
	s_lshr_b32 s14, s14, 6
	s_mulk_i32 s14, 0x1100
	s_add_i32 s15, s15, 1
	v_readlane_b32 s37, v249, 34
	v_readlane_b32 s42, v249, 39
	v_readlane_b32 s43, v249, 40
	v_readlane_b32 s46, v249, 43
	v_readlane_b32 s47, v249, 44
	v_readlane_b32 s48, v249, 45
	v_readlane_b32 s49, v249, 46
	v_readlane_b32 s50, v249, 47
	v_readlane_b32 s51, v249, 48
	s_waitcnt vmcnt(0) lgkmcnt(0)
	ds_write_b128 v116, v[0:3]
	ds_write_b128 v117, v[4:7]
	v_add_f32_e32 v0, v8, v10
	v_add_f32_e32 v1, v9, v11
	v_add_f32_e32 v2, v12, v14
	v_add_f32_e32 v0, 0, v0
	v_add_f32_e32 v3, v13, v15
	v_add_f32_e32 v4, v56, v58
	v_add_f32_e32 v1, 0, v1
	v_add_f32_e32 v0, v0, v2
	v_add_f32_e32 v5, v57, v59
	v_add_f32_e32 v6, v60, v62
	v_add_f32_e32 v1, v1, v3
	v_add_f32_e32 v0, v0, v4
	v_add_f32_e32 v7, v61, v63
	v_add_f32_e32 v1, v1, v5
	v_add_f32_e32 v0, v0, v6
	v_add_f32_e32 v2, v68, v70
	v_add_f32_e32 v1, v1, v7
	v_add_f32_e32 v0, v0, v2
	v_add_f32_e32 v2, v69, v71
	ds_write_b128 v116, v[64:67] offset:17408
	v_add_f32_e32 v56, v1, v2
	v_add_f32_e32 v1, v72, v74
	v_add_f32_e32 v57, v0, v1
	global_load_dwordx4 v[0:3], v[112:113], off offset:48
	global_load_dwordx4 v[4:7], v[112:113], off offset:32
	global_load_dwordx4 v[8:11], v[114:115], off offset:48
	global_load_dwordx4 v[12:15], v[114:115], off offset:32
	v_add_f32_e32 v58, v73, v75
	v_add_f32_e32 v56, v56, v58
	v_add_f32_e32 v58, v76, v78
	v_add_f32_e32 v57, v57, v58
	v_add_f32_e32 v58, v77, v79
	v_add_f32_e32 v56, v56, v58
	v_add_f32_e32 v58, v80, v82
	v_add_f32_e32 v57, v57, v58
	v_add_f32_e32 v58, v81, v83
	v_add_f32_e32 v56, v56, v58
	v_mul_f32_e32 v58, 0x3b000000, v57
	v_mul_f32_e32 v58, v58, v58
	v_fma_f32 v56, v56, s10, -v58
	v_max_f32_e32 v56, 0, v56
	v_add_f32_e32 v56, 0x358637bd, v56
	v_rsq_f32_e32 v56, v56
	v_lshlrev_b32_e32 v58, 16, v88
	v_fmac_f32_e32 v58, 0xbb000000, v57
	v_and_b32_e32 v59, 0xffff0000, v88
	v_mul_f32_e32 v58, v58, v56
	v_fma_f32 v58, v58, v96, v92
	v_fmac_f32_e32 v59, 0xbb000000, v57
	v_mul_f32_e32 v59, v59, v56
	v_bfe_u32 v60, v58, 16, 1
	v_fma_f32 v59, v59, v97, v93
	v_add3_u32 v58, v58, v60, s11
	v_add3_u32 v60, s16, v47, v46
	ds_write_b128 v118, v[84:87]
	ds_write_b16_d16_hi v60, v58 offset:34816
	v_bfe_u32 v58, v59, 16, 1
	v_add3_u32 v58, v59, v58, s11
	ds_write_b16_d16_hi v60, v58 offset:35088
	v_lshlrev_b32_e32 v58, 16, v89
	v_fmac_f32_e32 v58, 0xbb000000, v57
	v_and_b32_e32 v59, 0xffff0000, v89
	v_mul_f32_e32 v58, v58, v56
	v_fmac_f32_e32 v59, 0xbb000000, v57
	v_fma_f32 v58, v58, v98, v94
	v_mul_f32_e32 v59, v59, v56
	v_fmac_f32_e32 v95, v59, v99
	v_bfe_u32 v59, v58, 16, 1
	v_add3_u32 v58, v58, v59, s11
	v_add3_u32 v59, s16, v48, v46
	ds_write_b16_d16_hi v59, v58 offset:34816
	v_bfe_u32 v58, v95, 16, 1
	v_add3_u32 v58, v95, v58, s11
	ds_write_b16_d16_hi v59, v58 offset:35088
	v_lshlrev_b32_e32 v58, 16, v90
	v_fmac_f32_e32 v58, 0xbb000000, v57
	v_mul_f32_e32 v58, v58, v56
	v_and_b32_e32 v59, 0xffff0000, v90
	v_fma_f32 v58, v58, v100, v104
	v_fmac_f32_e32 v59, 0xbb000000, v57
	v_mul_f32_e32 v59, v59, v56
	v_bfe_u32 v60, v58, 16, 1
	v_fma_f32 v59, v59, v101, v105
	v_add3_u32 v58, v58, v60, s11
	v_add3_u32 v60, s16, v49, v46
	ds_write_b16_d16_hi v60, v58 offset:34816
	v_bfe_u32 v58, v59, 16, 1
	v_add3_u32 v58, v59, v58, s11
	ds_write_b16_d16_hi v60, v58 offset:35088
	v_lshlrev_b32_e32 v58, 16, v91
	v_fmac_f32_e32 v58, 0xbb000000, v57
	v_and_b32_e32 v59, 0xffff0000, v91
	v_mul_f32_e32 v58, v58, v56
	v_fmac_f32_e32 v59, 0xbb000000, v57
	v_fma_f32 v58, v58, v102, v106
	v_mul_f32_e32 v59, v59, v56
	v_fmac_f32_e32 v107, v59, v103
	v_bfe_u32 v59, v58, 16, 1
	v_add3_u32 v58, v58, v59, s11
	v_add3_u32 v59, s16, v50, v46
	ds_write_b16_d16_hi v59, v58 offset:34816
	v_bfe_u32 v58, v107, 16, 1
	v_add3_u32 v58, v107, v58, s11
	ds_write_b16_d16_hi v59, v58 offset:35088
	v_lshlrev_b32_e32 v58, 16, v108
	v_fmac_f32_e32 v58, 0xbb000000, v57
	v_mul_f32_e32 v58, v58, v56
	s_waitcnt vmcnt(0)
; #define LAS __attribute__((address_space(3)))
; DI unsigned f2bf(float f) { unsigned u = __builtin_bit_cast(unsigned, f); return (u + 0x7fffu + ((u >> 16) & 1u)) >> 16; }
; DI unsigned pk2(float lo, float hi) { typedef float v2f __attribute__((ext_vector_type(2))); typedef __bf16 v2b __attribute__((ext_vector_type(2))); v2f v = {lo, hi}; v2b b = __builtin_convertvector(v, v2b); return __builtin_bit_cast(unsigned, b); }
; DI float bflo(unsigned w) { return __uint_as_float(w << 16); }
; DI float bfhi(unsigned w) { return __uint_as_float(w & 0xffff0000u); }
; #define MFMA16(a, b, c) __builtin_amdgcn_mfma_f32_16x16x32_bf16((a), (b), (c), 0, 0, 0)
; DI void sgu_item(int g, int bc, int par, const bf16_t* SGW, const bf16_t* Vg, const float* VST, const float* lng, const float* lnb, const float* sgb, bf16_t* U, LAS unsigned char* lds) {
;     ...
;         for (int i = 0; i < 8; ++i) {
;             const int d = dg * 16 + 2 * i, c = g * 64 + d;
;             const float v0 = (bflo(wd[i]) - mu) * rstd * lng[c] + lnb[c], v1 = (bfhi(wd[i]) - mu) * rstd * lng[c + 1] + lnb[c + 1];
;             *(LAS bf16_t*)(Vl + d * RS + s * 2) = (bf16_t)f2bf(v0); *(LAS bf16_t*)(Vl + (d + 1) * RS + s * 2) = (bf16_t)f2bf(v1);
;         }
;     }
;     __syncthreads();
;     f32x4 acc[4];
; #pragma unroll
;     for (int db = 0; db < 4; ++db) acc[db] = (f32x4){0.f, 0.f, 0.f, 0.f};
;     for (int ks = 0; ks < nks; ++ks) {
;         const bf16x8 bw = *(const LAS bf16x8*)(Wl + (t0 + j) * RS + (32 * ks + 8 * q) * 2);
; #pragma unroll
;         for (int db = 0; db < 4; ++db) { const bf16x8 av = *(const LAS bf16x8*)(Vl + (16 * db + j) * RS + (32 * ks + 8 * q) * 2); acc[db] = MFMA16(av, bw, acc[db]); }
;     }
; #pragma unroll
;     for (int db = 0; db < 4; ++db) {
;         u32x2 wv; wv.x = pk2(bflo(uu[db].x) * (acc[db][0] + bias), bfhi(uu[db].x) * (acc[db][1] + bias)); wv.y = pk2(bflo(uu[db].y) * (acc[db][2] + bias), bfhi(uu[db].y) * (acc[db][3] + bias));
;         *(u32x2*)(up + 16 * db) = wv;
;     }
	v_fma_f32 v4, v58, v4, v12
	v_and_b32_e32 v12, 0xffff0000, v108
	v_fmac_f32_e32 v12, 0xbb000000, v57
	v_mul_f32_e32 v12, v12, v56
	v_fma_f32 v5, v12, v5, v13
	v_bfe_u32 v12, v4, 16, 1
	v_add3_u32 v4, v4, v12, s11
	v_add3_u32 v12, s16, v51, v46
	ds_write_b16_d16_hi v12, v4 offset:34816
	v_bfe_u32 v4, v5, 16, 1
	v_add3_u32 v4, v5, v4, s11
	ds_write_b16_d16_hi v12, v4 offset:35088
	v_lshlrev_b32_e32 v4, 16, v109
	v_fmac_f32_e32 v4, 0xbb000000, v57
	v_and_b32_e32 v5, 0xffff0000, v109
	v_mul_f32_e32 v4, v4, v56
	v_fmac_f32_e32 v5, 0xbb000000, v57
	v_fma_f32 v4, v4, v6, v14
	v_mul_f32_e32 v5, v5, v56
	v_fmac_f32_e32 v15, v5, v7
	v_bfe_u32 v5, v4, 16, 1
	v_add3_u32 v4, v4, v5, s11
	v_add3_u32 v5, s16, v52, v46
	ds_write_b16_d16_hi v5, v4 offset:34816
	v_bfe_u32 v4, v15, 16, 1
	v_add3_u32 v4, v15, v4, s11
	ds_write_b16_d16_hi v5, v4 offset:35088
	v_lshlrev_b32_e32 v4, 16, v110
	v_fmac_f32_e32 v4, 0xbb000000, v57
	v_mul_f32_e32 v4, v4, v56
	v_fma_f32 v0, v4, v0, v8
	v_and_b32_e32 v4, 0xffff0000, v110
	v_fmac_f32_e32 v4, 0xbb000000, v57
	v_mul_f32_e32 v4, v4, v56
	v_fma_f32 v1, v4, v1, v9
	v_bfe_u32 v4, v0, 16, 1
	v_add3_u32 v0, v0, v4, s11
	v_add3_u32 v4, s16, v53, v46
	ds_write_b16_d16_hi v4, v0 offset:34816
	v_bfe_u32 v0, v1, 16, 1
	v_add3_u32 v0, v1, v0, s11
	ds_write_b16_d16_hi v4, v0 offset:35088
	v_lshlrev_b32_e32 v0, 16, v111
	v_fmac_f32_e32 v0, 0xbb000000, v57
	v_and_b32_e32 v1, 0xffff0000, v111
	v_mul_f32_e32 v0, v0, v56
	v_fmac_f32_e32 v1, 0xbb000000, v57
	v_fma_f32 v0, v0, v2, v10
	v_mul_f32_e32 v1, v1, v56
	v_fmac_f32_e32 v11, v1, v3
	v_bfe_u32 v1, v0, 16, 1
	v_add3_u32 v0, v0, v1, s11
	v_add3_u32 v1, s16, v54, v46
	ds_write_b16_d16_hi v1, v0 offset:34816
	v_bfe_u32 v0, v11, 16, 1
	v_add3_u32 v0, v11, v0, s11
	v_add_u32_e32 v56, s13, v55
	s_add_i32 s13, s13, s14
	ds_write_b16_d16_hi v1, v0 offset:35088
	v_add_u32_e32 v57, s13, v19
	v_mov_b32_e32 v0, 0
	v_mov_b32_e32 v1, v17
	v_mov_b32_e32 v2, v17
	v_mov_b32_e32 v3, v17
	v_mov_b32_e32 v12, 0
	v_mov_b32_e32 v13, v17
	v_mov_b32_e32 v14, v17
	v_mov_b32_e32 v15, v17
	v_mov_b32_e32 v8, 0
	v_mov_b32_e32 v9, v17
	v_mov_b32_e32 v10, v17
	v_mov_b32_e32 v11, v17
	v_mov_b32_e32 v4, 0
	v_mov_b32_e32 v5, v17
	v_mov_b32_e32 v6, v17
	v_mov_b32_e32 v7, v17
	s_waitcnt lgkmcnt(0)
	s_barrier
.LBB0_1304:
	ds_read_b128 v[58:61], v56
	ds_read_b128 v[62:65], v57
	ds_read_b128 v[66:69], v56 offset:4352
	s_add_i32 s15, s15, -1
	s_cmp_lg_u32 s15, 0
	v_add_u32_e32 v57, 64, v57
	s_waitcnt lgkmcnt(1)
	v_mfma_f32_16x16x32_bf16 v[12:15], v[58:61], v[62:65], v[12:15]
	ds_read_b128 v[58:61], v56 offset:8704
	s_waitcnt lgkmcnt(1)
	v_mfma_f32_16x16x32_bf16 v[8:11], v[66:69], v[62:65], v[8:11]
	ds_read_b128 v[66:69], v56 offset:13056
	v_add_u32_e32 v56, 64, v56
	s_waitcnt lgkmcnt(1)
	v_mfma_f32_16x16x32_bf16 v[4:7], v[58:61], v[62:65], v[4:7]
	s_waitcnt lgkmcnt(0)
	v_mfma_f32_16x16x32_bf16 v[0:3], v[66:69], v[62:65], v[0:3]
	s_cbranch_scc1 .LBB0_1304
	v_lshlrev_b32_e32 v56, 16, v40
	v_and_b32_e32 v57, 0xffff0000, v40
	v_pk_add_f32 v[12:13], v[16:17], v[12:13] op_sel_hi:[0,1]
	v_lshlrev_b32_e32 v40, 16, v41
	v_and_b32_e32 v41, 0xffff0000, v41
	v_pk_add_f32 v[14:15], v[16:17], v[14:15] op_sel_hi:[0,1]
	v_pk_mul_f32 v[12:13], v[12:13], v[56:57]
	v_pk_mul_f32 v[14:15], v[14:15], v[40:41]
	v_cvt_pk_bf16_f32 v12, v12, v13
	v_cvt_pk_bf16_f32 v13, v14, v15
	global_store_dwordx2 v[32:33], v[12:13], off
	v_lshlrev_b32_e32 v12, 16, v38
	v_and_b32_e32 v13, 0xffff0000, v38
	v_pk_add_f32 v[8:9], v[16:17], v[8:9] op_sel_hi:[0,1]
	v_pk_mul_f32 v[8:9], v[8:9], v[12:13]
	v_lshlrev_b32_e32 v12, 16, v39
	v_and_b32_e32 v13, 0xffff0000, v39
	v_pk_add_f32 v[10:11], v[16:17], v[10:11] op_sel_hi:[0,1]
	v_pk_mul_f32 v[10:11], v[10:11], v[12:13]
	v_cvt_pk_bf16_f32 v8, v8, v9
	v_cvt_pk_bf16_f32 v9, v10, v11
	global_store_dwordx2 v[32:33], v[8:9], off offset:32
	v_lshlrev_b32_e32 v8, 16, v36
	v_and_b32_e32 v9, 0xffff0000, v36
	v_pk_add_f32 v[4:5], v[16:17], v[4:5] op_sel_hi:[0,1]
	v_pk_mul_f32 v[4:5], v[4:5], v[8:9]
	v_lshlrev_b32_e32 v8, 16, v37
	v_and_b32_e32 v9, 0xffff0000, v37
	v_pk_add_f32 v[6:7], v[16:17], v[6:7] op_sel_hi:[0,1]
	v_pk_mul_f32 v[6:7], v[6:7], v[8:9]
	v_cvt_pk_bf16_f32 v4, v4, v5
	v_cvt_pk_bf16_f32 v5, v6, v7
	global_store_dwordx2 v[32:33], v[4:5], off offset:64
	v_lshlrev_b32_e32 v4, 16, v34
	v_and_b32_e32 v5, 0xffff0000, v34
	v_pk_add_f32 v[0:1], v[16:17], v[0:1] op_sel_hi:[0,1]
	v_pk_mul_f32 v[0:1], v[0:1], v[4:5]
	v_lshlrev_b32_e32 v4, 16, v35
	v_and_b32_e32 v5, 0xffff0000, v35
	v_pk_add_f32 v[2:3], v[16:17], v[2:3] op_sel_hi:[0,1]
	v_pk_mul_f32 v[2:3], v[2:3], v[4:5]
	s_add_i32 s12, s12, s86
	s_xor_b32 s6, s6, 1
	v_cvt_pk_bf16_f32 v0, v0, v1
	v_cvt_pk_bf16_f32 v1, v2, v3
	s_cmpk_gt_i32 s12, 0x3ff
	global_store_dwordx2 v[32:33], v[0:1], off offset:96
	s_cbranch_scc0 .LBB0_1303

; __global__ void __launch_bounds__(512, 2) fwd_mega(Args args) {
;     ...
;             for (int it0 = gw * NB; it0 < T * 2; it0 += ngw * NB) {
;                 u32x4 qa[NB], ka[NB]; f32x4 kb0[NB], kb1[NB]; float pos[NB];
; #pragma unroll
;                 for (int u = 0; u < NB; ++u) {
;                     const int task = (it0 + u) * 4 + grp, tok = task >> 3, hd = task & 7;
;                     pos[u] = (float)positions[tok];
;                     qa[u] = (u32x4){0u, 0u, 0u, 0u}; ka[u] = (u32x4){0u, 0u, 0u, 0u}; kb0[u] = (f32x4){0.f, 0.f, 0.f, 0.f}; kb1[u] = (f32x4){0.f, 0.f, 0.f, 0.f};
;                     if (m < 8) ka[u] = *(const u32x4*)(KN + (size_t)tok * 512 + hd * 64 + 8 * m);
;                     if (isrope) { kb0[u] = *(const f32x4*)(KR + (size_t)tok * 32 + 8 * (m - 8)); kb1[u] = *(const f32x4*)(KR + (size_t)tok * 32 + 8 * (m - 8) + 4); }
;                 }
.LBB0_1365:
	s_ashr_i32 s20, s24, 1
	s_ashr_i32 s21, s20, 31
	v_readlane_b32 s36, v249, 17
	s_lshl_b64 s[12:13], s[20:21], 2
	v_readlane_b32 s40, v249, 21
	v_readlane_b32 s41, v249, 22
	s_add_u32 s18, s40, s12
	s_addc_u32 s19, s41, s13
	global_load_dword v78, v65, s[18:19]
	v_mov_b32_e32 v56, 0
	v_mov_b32_e32 v57, 0
	v_mov_b32_e32 v58, 0
	v_mov_b32_e32 v59, 0
	v_readlane_b32 s37, v249, 18
	v_readlane_b32 s38, v249, 19
	v_readlane_b32 s39, v249, 20
	v_readlane_b32 s42, v249, 23
	v_readlane_b32 s43, v249, 24
	v_readlane_b32 s44, v249, 25
	v_readlane_b32 s45, v249, 26
	v_readlane_b32 s46, v249, 27
	v_readlane_b32 s47, v249, 28
	v_readlane_b32 s48, v249, 29
	v_readlane_b32 s49, v249, 30
	v_readlane_b32 s50, v249, 31
	v_readlane_b32 s51, v249, 32
	s_and_saveexec_b64 s[12:13], s[8:9]
	s_cbranch_execz .LBB0_1367
	s_lshl_b64 s[22:23], s[20:21], 10
	v_lshl_add_u64 v[12:13], v[68:69], 0, s[22:23]
	global_load_dwordx4 v[56:59], v[12:13], off
.LBB0_1367:
	s_or_b64 exec, exec, s[12:13]
	v_mov_b32_e32 v36, 0
	v_mov_b32_e32 v48, 0
	v_mov_b32_e32 v49, 0
	v_mov_b32_e32 v50, 0
	v_mov_b32_e32 v51, 0
	v_mov_b32_e32 v52, 0
	v_mov_b32_e32 v53, 0
	v_mov_b32_e32 v54, 0
	v_mov_b32_e32 v55, 0
	s_and_saveexec_b64 s[12:13], s[4:5]
	s_cbranch_execz .LBB0_1369
	s_lshl_b64 s[22:23], s[20:21], 7
	v_lshl_add_u64 v[12:13], v[66:67], 0, s[22:23]
	v_add_co_u32_e32 v12, vcc, 0x3cff000, v12
	s_nop 1
	v_addc_co_u32_e32 v13, vcc, 0, v13, vcc
	global_load_dwordx4 v[48:51], v[12:13], off offset:3840
	global_load_dwordx4 v[52:55], v[12:13], off offset:3856
.LBB0_1369:
	s_or_b64 exec, exec, s[12:13]
	v_mov_b32_e32 v37, 0
	v_mov_b32_e32 v38, 0
	v_mov_b32_e32 v39, 0
	s_and_saveexec_b64 s[12:13], s[8:9]
	s_cbranch_execz .LBB0_1371
	s_lshl_b64 s[22:23], s[20:21], 10
	v_lshl_add_u64 v[12:13], v[68:69], 0, s[22:23]
	global_load_dwordx4 v[36:39], v[12:13], off offset:512
.LBB0_1371:
	s_or_b64 exec, exec, s[12:13]
	v_mov_b32_e32 v32, 0
	v_mov_b32_e32 v40, 0
	v_mov_b32_e32 v41, 0
	v_mov_b32_e32 v42, 0
	v_mov_b32_e32 v43, 0
	v_mov_b32_e32 v44, 0
	v_mov_b32_e32 v45, 0
	v_mov_b32_e32 v46, 0
	v_mov_b32_e32 v47, 0
	s_and_saveexec_b64 s[12:13], s[4:5]
	s_cbranch_execz .LBB0_1373
	s_lshl_b64 s[22:23], s[20:21], 7
	v_lshl_add_u64 v[12:13], v[66:67], 0, s[22:23]
	v_add_co_u32_e32 v12, vcc, 0x3cff000, v12
	s_nop 1
	v_addc_co_u32_e32 v13, vcc, 0, v13, vcc
	global_load_dwordx4 v[40:43], v[12:13], off offset:3840
	global_load_dwordx4 v[44:47], v[12:13], off offset:3856
.LBB0_1373:
	s_or_b64 exec, exec, s[12:13]
	global_load_dword v77, v32, s[18:19] offset:4
	s_or_b32 s18, s20, 1
	s_ashr_i32 s19, s18, 31
	v_mov_b32_e32 v33, 0
	v_mov_b32_e32 v34, 0
	v_mov_b32_e32 v35, 0
	s_and_saveexec_b64 s[12:13], s[8:9]
	s_cbranch_execz .LBB0_1375
	s_lshl_b64 s[22:23], s[18:19], 10
	v_lshl_add_u64 v[12:13], v[68:69], 0, s[22:23]
	global_load_dwordx4 v[32:35], v[12:13], off
.LBB0_1375:
	s_or_b64 exec, exec, s[12:13]
	v_mov_b32_e32 v12, 0
	s_waitcnt lgkmcnt(0)
	v_mov_b32_e32 v24, 0
	v_mov_b32_e32 v25, 0
	v_mov_b32_e32 v26, 0
	v_mov_b32_e32 v27, 0
	v_mov_b32_e32 v28, 0
	v_mov_b32_e32 v29, 0
	v_mov_b32_e32 v30, 0
	v_mov_b32_e32 v31, 0
	s_and_saveexec_b64 s[12:13], s[4:5]
	s_cbranch_execz .LBB0_1377
	s_lshl_b64 s[22:23], s[18:19], 7
	v_lshl_add_u64 v[14:15], v[66:67], 0, s[22:23]
	v_add_co_u32_e32 v14, vcc, 0x3cff000, v14
	s_nop 1
	v_addc_co_u32_e32 v15, vcc, 0, v15, vcc
	global_load_dwordx4 v[24:27], v[14:15], off offset:3840
	global_load_dwordx4 v[28:31], v[14:15], off offset:3856
.LBB0_1377:
	s_or_b64 exec, exec, s[12:13]
	v_mov_b32_e32 v13, 0
	v_mov_b32_e32 v14, 0
	v_mov_b32_e32 v15, 0
	s_and_saveexec_b64 s[12:13], s[8:9]
	s_cbranch_execz .LBB0_1379
	s_lshl_b64 s[22:23], s[18:19], 10
	v_lshl_add_u64 v[12:13], v[68:69], 0, s[22:23]
	global_load_dwordx4 v[12:15], v[12:13], off offset:512

; DI unsigned pk2(float lo, float hi) { typedef float v2f __attribute__((ext_vector_type(2))); typedef __bf16 v2b __attribute__((ext_vector_type(2))); v2f v = {lo, hi}; v2b b = __builtin_convertvector(v, v2b); return __builtin_bit_cast(unsigned, b); }
; DI float bflo(unsigned w) { return __uint_as_float(w << 16); }
; DI float bfhi(unsigned w) { return __uint_as_float(w & 0xffff0000u); }
; __global__ void __launch_bounds__(512, 2) fwd_mega(Args args) {
;     ...
;                         const u32x4 a = ka[u];
;                         if (m < 8) { v[0] = bflo(a.x); v[1] = bfhi(a.x); v[2] = bflo(a.y); v[3] = bfhi(a.y); v[4] = bflo(a.z); v[5] = bfhi(a.z); v[6] = bflo(a.w); v[7] = bfhi(a.w); }
;                         else { v[0] = kb0[u][0]; v[1] = kb0[u][1]; v[2] = kb0[u][2]; v[3] = kb0[u][3]; v[4] = kb1[u][0]; v[5] = kb1[u][1]; v[6] = kb1[u][2]; v[7] = kb1[u][3]; }
;                         float ss = 0.f;
; #pragma unroll
;                         for (int e = 0; e < 8; ++e) ss += v[e] * v[e];
;                         ss += __shfl_xor(ss, 1); ss += __shfl_xor(ss, 2); ss += __shfl_xor(ss, 4); ss += __shfl_xor(ss, 8);
;                         const float rk = __builtin_amdgcn_rsqf(ss * (1.0f / 96.0f) + EPS);
; #pragma unroll
;                         for (int e = 0; e < 8; ++e) v[e] = v[e] * rk * gk[e];
; #pragma unroll
;                         for (int e = 0; e < 8; ++e) { const float o = __shfl_xor(v[e], 2); if (isrope) v[e] = isx1 ? v[e] * cs[e] - o * sn[e] : v[e] * cs[e] + o * sn[e]; }
;                         if (act) { u32x4 w; w.x = pk2(v[0], v[1]); w.y = pk2(v[2], v[3]); w.z = pk2(v[4], v[5]); w.w = pk2(v[6], v[7]); *(u32x4*)(KF + (size_t)tok * 768 + hd * 96 + 8 * m) = w; }
.LBB0_1395:
	s_or_b64 exec, exec, s[12:13]
	v_mul_f32_e32 v24, v17, v17
	v_fmac_f32_e32 v24, v16, v16
	v_fmac_f32_e32 v24, v18, v18
	v_fmac_f32_e32 v24, v19, v19
	v_pk_mul_f32 v[14:15], v[20:21], v[20:21]
	v_pk_mul_f32 v[12:13], v[22:23], v[22:23]
	v_add_f32_e32 v14, v24, v14
	v_add_f32_e32 v14, v14, v15
	v_add_f32_e32 v12, v14, v12
	v_add_f32_e32 v12, v12, v13
	ds_bpermute_b32 v13, v72, v12
	s_waitcnt lgkmcnt(0)
	v_add_f32_e32 v12, v12, v13
	ds_bpermute_b32 v13, v73, v12
	s_waitcnt lgkmcnt(0)
	v_add_f32_e32 v12, v12, v13
	ds_bpermute_b32 v13, v74, v12
	s_waitcnt lgkmcnt(0)
	v_add_f32_e32 v12, v12, v13
	ds_bpermute_b32 v13, v75, v12
	s_waitcnt lgkmcnt(0)
	v_add_f32_e32 v12, v12, v13
	v_fmamk_f32 v12, v12, 0x3c2aaaab, v64
	v_rsq_f32_e32 v12, v12
	s_nop 0
	v_pk_mul_f32 v[14:15], v[12:13], v[16:17] op_sel_hi:[0,1]
	v_pk_mul_f32 v[16:17], v[12:13], v[18:19] op_sel_hi:[0,1]
	v_pk_mul_f32 v[18:19], v[12:13], v[20:21] op_sel_hi:[0,1]
	v_pk_mul_f32 v[20:21], v[12:13], v[22:23] op_sel_hi:[0,1]
	v_pk_mul_f32 v[12:13], v[14:15], v[62:63]
	v_pk_mul_f32 v[16:17], v[16:17], v[8:9]
	v_pk_mul_f32 v[18:19], v[18:19], v[10:11]
	v_pk_mul_f32 v[14:15], v[20:21], v[60:61]
	ds_bpermute_b32 v27, v73, v12
	ds_bpermute_b32 v26, v73, v13
	ds_bpermute_b32 v25, v73, v16
	ds_bpermute_b32 v24, v73, v17
	ds_bpermute_b32 v23, v73, v18
	ds_bpermute_b32 v22, v73, v19
	ds_bpermute_b32 v21, v73, v14
	ds_bpermute_b32 v20, v73, v15
	s_and_saveexec_b64 s[20:21], s[2:3]
	s_cbranch_execz .LBB0_1364
	s_waitcnt lgkmcnt(0)
	v_mul_f32_e32 v27, v36, v27
	v_mul_f32_e32 v26, v37, v26
	v_mul_f32_e32 v25, v39, v25
	v_mul_f32_e32 v24, v41, v24
	v_mul_f32_e32 v23, v43, v23
	v_mul_f32_e32 v22, v45, v22
	v_mul_f32_e32 v21, v48, v21
	v_cndmask_b32_e64 v27, v27, -v27, s[6:7]
	v_cndmask_b32_e64 v26, v26, -v26, s[6:7]
	v_cndmask_b32_e64 v25, v25, -v25, s[6:7]
	v_cndmask_b32_e64 v24, v24, -v24, s[6:7]
	v_cndmask_b32_e64 v23, v23, -v23, s[6:7]
	v_cndmask_b32_e64 v22, v22, -v22, s[6:7]
	v_cndmask_b32_e64 v21, v21, -v21, s[6:7]
	v_mul_f32_e32 v20, v30, v20
	v_fmac_f32_e32 v27, v34, v12
	v_fmac_f32_e32 v26, v35, v13
	v_fmac_f32_e32 v25, v38, v16
	v_fmac_f32_e32 v24, v40, v17
	v_fmac_f32_e32 v23, v42, v18
	v_fmac_f32_e32 v22, v44, v19
	v_fmac_f32_e32 v21, v46, v14
	v_cndmask_b32_e64 v20, v20, -v20, s[6:7]
	v_cndmask_b32_e64 v21, v14, v21, s[4:5]
	v_cndmask_b32_e64 v22, v19, v22, s[4:5]
	v_cndmask_b32_e64 v23, v18, v23, s[4:5]
	v_cndmask_b32_e64 v24, v17, v24, s[4:5]
	v_cndmask_b32_e64 v25, v16, v25, s[4:5]
	v_cndmask_b32_e64 v26, v13, v26, s[4:5]
	v_cndmask_b32_e64 v27, v12, v27, s[4:5]
	v_fmac_f32_e32 v20, v47, v15
	v_cndmask_b32_e64 v21, v14, v21, s[4:5]
	v_cndmask_b32_e64 v14, v19, v22, s[4:5]
	v_cndmask_b32_e64 v18, v18, v23, s[4:5]
	v_cndmask_b32_e64 v17, v17, v24, s[4:5]
	v_cndmask_b32_e64 v16, v16, v25, s[4:5]
	v_cndmask_b32_e64 v13, v13, v26, s[4:5]
	v_cndmask_b32_e64 v12, v12, v27, s[4:5]
	v_cndmask_b32_e64 v15, v15, v20, s[4:5]
	v_cvt_pk_bf16_f32 v12, v12, v13
	v_cvt_pk_bf16_f32 v13, v16, v17
	v_cvt_pk_bf16_f32 v14, v18, v14
	v_cvt_pk_bf16_f32 v15, v21, v15
	v_mad_i64_i32 v[16:17], s[12:13], s18, v76, v[70:71]
	global_store_dwordx4 v[16:17], v[12:15], off offset:768
	s_branch .LBB0_1364
.LBB0_1397:
	s_lshl_b64 s[22:23], s[18:19], 7
	v_lshl_add_u64 v[16:17], v[66:67], 0, s[22:23]
	v_add_co_u32_e32 v20, vcc, 0x3cff000, v16
	s_nop 1
	v_addc_co_u32_e32 v21, vcc, 0, v17, vcc
	global_load_dwordx4 v[16:19], v[20:21], off offset:3840
	s_nop 0
	global_load_dwordx4 v[20:23], v[20:21], off offset:3856
	s_or_b64 exec, exec, s[12:13]
	s_and_saveexec_b64 s[12:13], s[10:11]
	s_xor_b64 s[12:13], exec, s[12:13]
	s_cbranch_execz .LBB0_1381

; DI unsigned pk2(float lo, float hi) { typedef float v2f __attribute__((ext_vector_type(2))); typedef __bf16 v2b __attribute__((ext_vector_type(2))); v2f v = {lo, hi}; v2b b = __builtin_convertvector(v, v2b); return __builtin_bit_cast(unsigned, b); }
; __global__ void __launch_bounds__(512, 2) fwd_mega(Args args) {
;     ...
;                         for (int e = 0; e < 8; ++e) { const float o = __shfl_xor(v[e], 2); if (isrope) v[e] = isx1 ? v[e] * cs[e] - o * sn[e] : v[e] * cs[e] + o * sn[e]; }
;                         if (act) { u32x4 w; w.x = pk2(v[0], v[1]); w.y = pk2(v[2], v[3]); w.z = pk2(v[4], v[5]); w.w = pk2(v[6], v[7]); *(u32x4*)(KF + (size_t)tok * 768 + hd * 96 + 8 * m) = w; }
.LBB0_1399:
	s_waitcnt lgkmcnt(7)
	v_mul_f32_e32 v97, v78, v97
	s_waitcnt lgkmcnt(6)
	v_mul_f32_e32 v96, v79, v96
	s_waitcnt lgkmcnt(5)
	v_mul_f32_e32 v95, v81, v95
	s_waitcnt lgkmcnt(4)
	v_mul_f32_e32 v94, v83, v94
	s_waitcnt lgkmcnt(3)
	v_mul_f32_e32 v93, v85, v93
	s_waitcnt lgkmcnt(2)
	v_mul_f32_e32 v92, v87, v92
	s_waitcnt lgkmcnt(1)
	v_mul_f32_e32 v91, v90, v91
	v_cndmask_b32_e64 v97, v97, -v97, s[6:7]
	v_cndmask_b32_e64 v96, v96, -v96, s[6:7]
	v_cndmask_b32_e64 v95, v95, -v95, s[6:7]
	v_cndmask_b32_e64 v94, v94, -v94, s[6:7]
	v_cndmask_b32_e64 v93, v93, -v93, s[6:7]
	v_cndmask_b32_e64 v92, v92, -v92, s[6:7]
	v_cndmask_b32_e64 v91, v91, -v91, s[6:7]
	s_waitcnt lgkmcnt(0)
	v_mul_f32_e32 v55, v54, v55
	v_fmac_f32_e32 v97, v58, v48
	v_fmac_f32_e32 v96, v59, v49
	v_fmac_f32_e32 v95, v80, v50
	v_fmac_f32_e32 v94, v82, v51
	v_fmac_f32_e32 v93, v84, v56
	v_fmac_f32_e32 v92, v86, v57
	v_fmac_f32_e32 v91, v88, v52
	v_cndmask_b32_e64 v55, v55, -v55, s[6:7]
	v_cndmask_b32_e64 v91, v52, v91, s[4:5]
	v_cndmask_b32_e64 v92, v57, v92, s[4:5]
	v_cndmask_b32_e64 v93, v56, v93, s[4:5]
	v_cndmask_b32_e64 v94, v51, v94, s[4:5]
	v_cndmask_b32_e64 v95, v50, v95, s[4:5]
	v_cndmask_b32_e64 v96, v49, v96, s[4:5]
	v_cndmask_b32_e64 v97, v48, v97, s[4:5]
	v_fmac_f32_e32 v55, v89, v53
	v_cndmask_b32_e64 v52, v52, v91, s[4:5]
	v_cndmask_b32_e64 v57, v57, v92, s[4:5]
	v_cndmask_b32_e64 v56, v56, v93, s[4:5]
	v_cndmask_b32_e64 v51, v51, v94, s[4:5]
	v_cndmask_b32_e64 v50, v50, v95, s[4:5]
	v_cndmask_b32_e64 v49, v49, v96, s[4:5]
	v_cndmask_b32_e64 v48, v48, v97, s[4:5]
	v_cndmask_b32_e64 v53, v53, v55, s[4:5]
	v_cvt_pk_bf16_f32 v48, v48, v49
	v_cvt_pk_bf16_f32 v49, v50, v51
	v_cvt_pk_bf16_f32 v50, v56, v57
	v_cvt_pk_bf16_f32 v51, v52, v53
	v_mad_i64_i32 v[52:53], s[12:13], s20, v76, v[70:71]
	global_store_dwordx4 v[52:53], v[48:51], off
	s_or_b64 exec, exec, s[22:23]
	s_and_saveexec_b64 s[12:13], s[10:11]
	s_xor_b64 s[12:13], exec, s[12:13]
	s_cbranch_execz .LBB0_1385

; DI unsigned pk2(float lo, float hi) { typedef float v2f __attribute__((ext_vector_type(2))); typedef __bf16 v2b __attribute__((ext_vector_type(2))); v2f v = {lo, hi}; v2b b = __builtin_convertvector(v, v2b); return __builtin_bit_cast(unsigned, b); }
; __global__ void __launch_bounds__(512, 2) fwd_mega(Args args) {
;     ...
;                         for (int e = 0; e < 8; ++e) { const float o = __shfl_xor(v[e], 2); if (isrope) v[e] = isx1 ? v[e] * cs[e] - o * sn[e] : v[e] * cs[e] + o * sn[e]; }
;                         if (act) { u32x4 w; w.x = pk2(v[0], v[1]); w.y = pk2(v[2], v[3]); w.z = pk2(v[4], v[5]); w.w = pk2(v[6], v[7]); *(u32x4*)(KF + (size_t)tok * 768 + hd * 96 + 8 * m) = w; }
.LBB0_1401:
	s_waitcnt lgkmcnt(0)
	v_mul_f32_e32 v51, v78, v51
	v_mul_f32_e32 v50, v79, v50
	v_mul_f32_e32 v49, v81, v49
	v_mul_f32_e32 v48, v83, v48
	v_mul_f32_e32 v47, v85, v47
	v_mul_f32_e32 v46, v87, v46
	v_mul_f32_e32 v45, v90, v45
	v_cndmask_b32_e64 v51, v51, -v51, s[6:7]
	v_cndmask_b32_e64 v50, v50, -v50, s[6:7]
	v_cndmask_b32_e64 v49, v49, -v49, s[6:7]
	v_cndmask_b32_e64 v48, v48, -v48, s[6:7]
	v_cndmask_b32_e64 v47, v47, -v47, s[6:7]
	v_cndmask_b32_e64 v46, v46, -v46, s[6:7]
	v_cndmask_b32_e64 v45, v45, -v45, s[6:7]
	v_mul_f32_e32 v44, v54, v44
	v_fmac_f32_e32 v51, v58, v36
	v_fmac_f32_e32 v50, v59, v37
	v_fmac_f32_e32 v49, v80, v40
	v_fmac_f32_e32 v48, v82, v41
	v_fmac_f32_e32 v47, v84, v42
	v_fmac_f32_e32 v46, v86, v43
	v_fmac_f32_e32 v45, v88, v38
	v_cndmask_b32_e64 v44, v44, -v44, s[6:7]
	v_cndmask_b32_e64 v45, v38, v45, s[4:5]
	v_cndmask_b32_e64 v46, v43, v46, s[4:5]
	v_cndmask_b32_e64 v47, v42, v47, s[4:5]
	v_cndmask_b32_e64 v48, v41, v48, s[4:5]
	v_cndmask_b32_e64 v49, v40, v49, s[4:5]
	v_cndmask_b32_e64 v50, v37, v50, s[4:5]
	v_cndmask_b32_e64 v51, v36, v51, s[4:5]
	v_fmac_f32_e32 v44, v89, v39
	v_cndmask_b32_e64 v45, v38, v45, s[4:5]
	v_cndmask_b32_e64 v38, v43, v46, s[4:5]
	v_cndmask_b32_e64 v42, v42, v47, s[4:5]
	v_cndmask_b32_e64 v41, v41, v48, s[4:5]
	v_cndmask_b32_e64 v40, v40, v49, s[4:5]
	v_cndmask_b32_e64 v37, v37, v50, s[4:5]
	v_cndmask_b32_e64 v36, v36, v51, s[4:5]
	v_cndmask_b32_e64 v39, v39, v44, s[4:5]
	v_cvt_pk_bf16_f32 v36, v36, v37
	v_cvt_pk_bf16_f32 v37, v40, v41
	v_cvt_pk_bf16_f32 v38, v42, v38
	v_cvt_pk_bf16_f32 v39, v45, v39
	v_mad_i64_i32 v[40:41], s[12:13], s20, v76, v[70:71]
	global_store_dwordx4 v[40:41], v[36:39], off offset:768
	s_or_b64 exec, exec, s[22:23]
	s_and_saveexec_b64 s[12:13], s[10:11]
	s_xor_b64 s[12:13], exec, s[12:13]
	s_cbranch_execz .LBB0_1389

; DI unsigned pk2(float lo, float hi) { typedef float v2f __attribute__((ext_vector_type(2))); typedef __bf16 v2b __attribute__((ext_vector_type(2))); v2f v = {lo, hi}; v2b b = __builtin_convertvector(v, v2b); return __builtin_bit_cast(unsigned, b); }
; __global__ void __launch_bounds__(512, 2) fwd_mega(Args args) {
;     ...
;                         for (int e = 0; e < 8; ++e) { const float o = __shfl_xor(v[e], 2); if (isrope) v[e] = isx1 ? v[e] * cs[e] - o * sn[e] : v[e] * cs[e] + o * sn[e]; }
;                         if (act) { u32x4 w; w.x = pk2(v[0], v[1]); w.y = pk2(v[2], v[3]); w.z = pk2(v[4], v[5]); w.w = pk2(v[6], v[7]); *(u32x4*)(KF + (size_t)tok * 768 + hd * 96 + 8 * m) = w; }
.LBB0_1403:
	s_waitcnt lgkmcnt(0)
	v_mul_f32_e32 v55, v36, v55
	v_mul_f32_e32 v54, v37, v54
	v_mul_f32_e32 v53, v39, v53
	v_mul_f32_e32 v52, v41, v52
	v_mul_f32_e32 v51, v43, v51
	v_mul_f32_e32 v50, v45, v50
	v_mul_f32_e32 v49, v48, v49
	v_cndmask_b32_e64 v55, v55, -v55, s[6:7]
	v_cndmask_b32_e64 v54, v54, -v54, s[6:7]
	v_cndmask_b32_e64 v53, v53, -v53, s[6:7]
	v_cndmask_b32_e64 v52, v52, -v52, s[6:7]
	v_cndmask_b32_e64 v51, v51, -v51, s[6:7]
	v_cndmask_b32_e64 v50, v50, -v50, s[6:7]
	v_cndmask_b32_e64 v49, v49, -v49, s[6:7]
	v_mul_f32_e32 v31, v30, v31
	v_fmac_f32_e32 v55, v34, v24
	v_fmac_f32_e32 v54, v35, v25
	v_fmac_f32_e32 v53, v38, v26
	v_fmac_f32_e32 v52, v40, v27
	v_fmac_f32_e32 v51, v42, v32
	v_fmac_f32_e32 v50, v44, v33
	v_fmac_f32_e32 v49, v46, v28
	v_cndmask_b32_e64 v31, v31, -v31, s[6:7]
	v_cndmask_b32_e64 v49, v28, v49, s[4:5]
	v_cndmask_b32_e64 v50, v33, v50, s[4:5]
	v_cndmask_b32_e64 v51, v32, v51, s[4:5]
	v_cndmask_b32_e64 v52, v27, v52, s[4:5]
	v_cndmask_b32_e64 v53, v26, v53, s[4:5]
	v_cndmask_b32_e64 v54, v25, v54, s[4:5]
	v_cndmask_b32_e64 v55, v24, v55, s[4:5]
	v_fmac_f32_e32 v31, v47, v29
	v_cndmask_b32_e64 v28, v28, v49, s[4:5]
	v_cndmask_b32_e64 v33, v33, v50, s[4:5]
	v_cndmask_b32_e64 v32, v32, v51, s[4:5]
	v_cndmask_b32_e64 v27, v27, v52, s[4:5]
	v_cndmask_b32_e64 v26, v26, v53, s[4:5]
	v_cndmask_b32_e64 v25, v25, v54, s[4:5]
	v_cndmask_b32_e64 v24, v24, v55, s[4:5]
	v_cndmask_b32_e64 v29, v29, v31, s[4:5]
	v_cvt_pk_bf16_f32 v24, v24, v25
	v_cvt_pk_bf16_f32 v25, v26, v27
	v_cvt_pk_bf16_f32 v26, v32, v33
	v_cvt_pk_bf16_f32 v27, v28, v29
	v_mad_i64_i32 v[28:29], s[12:13], s18, v76, v[70:71]
	global_store_dwordx4 v[28:29], v[24:27], off
	s_or_b64 exec, exec, s[20:21]
	s_and_saveexec_b64 s[12:13], s[10:11]
	s_xor_b64 s[12:13], exec, s[12:13]
	s_cbranch_execz .LBB0_1393

; DI unsigned pk2(float lo, float hi) { typedef float v2f __attribute__((ext_vector_type(2))); typedef __bf16 v2b __attribute__((ext_vector_type(2))); v2f v = {lo, hi}; v2b b = __builtin_convertvector(v, v2b); return __builtin_bit_cast(unsigned, b); }
; __global__ void __launch_bounds__(512, 2) fwd_mega(Args args) {
;     ...
;             for (int idx = gw; idx < 512 * 4; idx += ngw) {
;                 const int row = idx >> 2, hd = idx & 3;
;                 const float a = MKV[(size_t)row * 1024 + hd * 128 + 2 * lane], b = MKV[(size_t)row * 1024 + hd * 128 + 2 * lane + 1];
;                 const float rk = __builtin_amdgcn_rsqf(wave_sum(a * a + b * b) * (1.0f / 128.0f) + EPS);
;                 ((unsigned*)(KM + (size_t)row * 512 + hd * 128))[lane] = pk2(a * rk * mkn[2 * lane], b * rk * mkn[2 * lane + 1]);
;             }
.LBB0_1408:
	s_ashr_i32 s8, s52, 2
	s_ashr_i32 s9, s8, 31
	s_and_b32 s12, s6, 0x180
	s_lshl_b64 s[10:11], s[8:9], 10
	s_lshl_b64 s[8:9], s[8:9], 12
	s_add_u32 s8, s2, s8
	s_addc_u32 s9, s3, s9
	s_lshl_b32 s13, s12, 2
	s_add_u32 s8, s8, s13
	s_addc_u32 s9, s9, 0
	v_lshl_add_u64 v[14:15], s[8:9], 0, v[2:3]
	global_load_dwordx2 v[14:15], v[14:15], off
	s_add_u32 s8, s4, s10
	s_addc_u32 s9, s5, s11
	s_lshl_b32 s10, s12, 1
	s_add_u32 s8, s8, s10
	s_addc_u32 s9, s9, 0
	s_add_i32 s52, s52, s88
	s_add_i32 s6, s6, s7
	v_lshl_add_u64 v[18:19], s[8:9], 0, v[4:5]
	s_cmpk_gt_i32 s52, 0x7ff
	s_waitcnt vmcnt(0) lgkmcnt(0)
	v_pk_mul_f32 v[16:17], v[14:15], v[14:15]
	s_nop 0
	v_add_f32_e32 v13, v16, v17
	ds_bpermute_b32 v16, v6, v13
	s_waitcnt lgkmcnt(0)
	v_add_f32_e32 v13, v13, v16
	ds_bpermute_b32 v16, v7, v13
	s_waitcnt lgkmcnt(0)
	v_add_f32_e32 v13, v13, v16
	ds_bpermute_b32 v16, v8, v13
	s_waitcnt lgkmcnt(0)
	v_add_f32_e32 v13, v13, v16
	ds_bpermute_b32 v16, v9, v13
	s_waitcnt lgkmcnt(0)
	v_add_f32_e32 v13, v13, v16
	ds_bpermute_b32 v16, v10, v13
	s_waitcnt lgkmcnt(0)
	v_add_f32_e32 v13, v13, v16
	ds_bpermute_b32 v16, v11, v13
	s_waitcnt lgkmcnt(0)
	v_add_f32_e32 v13, v13, v16
	v_fmamk_f32 v13, v13, 0x3c000000, v12
	v_rsq_f32_e32 v16, v13
	s_nop 0
	v_pk_mul_f32 v[14:15], v[14:15], v[16:17] op_sel_hi:[1,0]
	s_nop 0
	v_pk_mul_f32 v[14:15], v[0:1], v[14:15]
	s_nop 0
	v_cvt_pk_bf16_f32 v13, v14, v15
	global_store_dword v[18:19], v13, off
	s_cbranch_scc0 .LBB0_1408

; DI unsigned f2bf(float f) { unsigned u = __builtin_bit_cast(unsigned, f); return (u + 0x7fffu + ((u >> 16) & 1u)) >> 16; }
; __global__ void __launch_bounds__(512, 2) fwd_mega(Args args) {
;     ...
;             for (int i = gt; i < 2 * 4 * 128 * 256; i += ngt) { const int m = i & 255, d = (i >> 8) & 127, hd = (i >> 15) & 3, b = i >> 17;
;                 VMT[i] = (bf16_t)f2bf(MKV[(size_t)(b * 256 + m) * 1024 + 512 + hd * 128 + d]); }
.LBB0_1412:
	v_ashrrev_i32_e32 v12, 9, v4
	v_ashrrev_i32_e32 v11, 9, v5
	v_and_b32_e32 v12, 0xffffff00, v12
	v_lshrrev_b32_e32 v2, 8, v5
	v_lshrrev_b32_e32 v10, 8, v4
	v_and_b32_e32 v11, 0xffffff00, v11
	v_or_b32_e32 v12, v12, v0
	v_and_b32_e32 v14, 0x7f, v2
	v_and_b32_e32 v15, 0x7f, v10
	v_and_b32_e32 v16, 0x180, v2
	v_and_b32_e32 v2, 0x180, v10
	v_or_b32_e32 v10, v11, v1
	v_ashrrev_i32_e32 v13, 31, v12
	v_ashrrev_i32_e32 v11, 31, v10
	v_lshlrev_b64 v[12:13], 12, v[12:13]
	v_lshlrev_b32_e32 v2, 2, v2
	v_lshlrev_b64 v[10:11], 12, v[10:11]
	v_lshl_add_u64 v[12:13], s[6:7], 0, v[12:13]
	v_lshl_add_u64 v[10:11], s[6:7], 0, v[10:11]
	v_lshl_add_u64 v[12:13], v[12:13], 0, v[2:3]
	v_lshlrev_b32_e32 v2, 2, v16
	v_lshl_add_u64 v[10:11], v[10:11], 0, v[2:3]
	v_lshlrev_b32_e32 v2, 2, v15
	v_lshl_add_u64 v[12:13], v[12:13], 0, v[2:3]
	v_lshlrev_b32_e32 v2, 2, v14
	v_lshl_add_u64 v[10:11], v[10:11], 0, v[2:3]
	global_load_dword v2, v[12:13], off
	global_load_dword v14, v[10:11], off
	v_add_u32_e32 v9, -2, v9
	v_ashrrev_i32_e32 v13, 31, v4
	v_mov_b32_e32 v12, v4
	v_cmp_eq_u32_e32 vcc, 0, v9
	v_ashrrev_i32_e32 v11, 31, v5
	v_mov_b32_e32 v10, v5
	v_add_u32_e32 v5, s13, v5
	v_add_u32_e32 v4, s12, v4
	v_lshl_add_u64 v[12:13], v[12:13], 1, s[8:9]
	s_or_b64 s[10:11], vcc, s[10:11]
	v_lshl_add_u64 v[10:11], v[10:11], 1, s[8:9]
	s_waitcnt vmcnt(0) lgkmcnt(0)
	v_and_b32_sdwa v15, v2, v8 dst_sel:DWORD dst_unused:UNUSED_PAD src0_sel:WORD_1 src1_sel:DWORD
	v_and_b32_sdwa v16, v14, v8 dst_sel:DWORD dst_unused:UNUSED_PAD src0_sel:WORD_1 src1_sel:DWORD
	v_add3_u32 v2, v2, v15, s16
	v_add3_u32 v14, v14, v16, s16
	global_store_short_d16_hi v[12:13], v2, off
	global_store_short_d16_hi v[10:11], v14, off
	s_andn2_b64 exec, exec, s[10:11]
	s_cbranch_execnz .LBB0_1412
	s_or_b64 exec, exec, s[10:11]
	v_readlane_b32 s8, v249, 59
	v_readlane_b32 s9, v249, 60
	v_cmp_ne_u32_e32 vcc, v6, v7
	v_mad_u64_u32 v[130:131], s[8:9], v7, s8, v[130:131]
	s_orn2_b64 s[8:9], vcc, exec

; DI unsigned f2bf(float f) { unsigned u = __builtin_bit_cast(unsigned, f); return (u + 0x7fffu + ((u >> 16) & 1u)) >> 16; }
; __global__ void __launch_bounds__(512, 2) fwd_mega(Args args) {
;     ...
;             for (int i = gt; i < 2 * 4 * 128 * 256; i += ngt) { const int m = i & 255, d = (i >> 8) & 127, hd = (i >> 15) & 3, b = i >> 17;
;                 VMT[i] = (bf16_t)f2bf(MKV[(size_t)(b * 256 + m) * 1024 + 512 + hd * 128 + d]); }
.LBB0_1416:
	v_ashrrev_i32_e32 v1, 9, v130
	v_and_or_b32 v6, v1, s10, v0
	v_ashrrev_i32_e32 v7, 31, v6
	v_lshrrev_b32_e32 v8, 6, v130
	v_lshlrev_b64 v[6:7], 12, v[6:7]
	v_and_b32_e32 v4, 0x600, v8
	v_lshl_add_u64 v[6:7], s[6:7], 0, v[6:7]
	v_lshl_add_u64 v[6:7], v[6:7], 0, v[4:5]
	v_and_b32_e32 v4, 0x1fc, v8
	v_lshl_add_u64 v[6:7], v[6:7], 0, v[4:5]
	global_load_dword v1, v[6:7], off
	v_add_u32_e32 v130, s16, v130
	v_cmp_lt_i32_e32 vcc, s12, v130
	s_or_b64 s[8:9], vcc, s[8:9]
	s_waitcnt vmcnt(0) lgkmcnt(0)
	v_bfe_u32 v4, v1, 16, 1
	v_add3_u32 v1, v1, v4, s11
	global_store_short_d16_hi v[2:3], v1, off
	v_lshl_add_u64 v[2:3], v[2:3], 0, s[2:3]
	s_andn2_b64 exec, exec, s[8:9]
	s_cbranch_execnz .LBB0_1416

; #define LAS __attribute__((address_space(3)))
; DI unsigned pk2(float lo, float hi) { typedef float v2f __attribute__((ext_vector_type(2))); typedef __bf16 v2b __attribute__((ext_vector_type(2))); v2f v = {lo, hi}; v2b b = __builtin_convertvector(v, v2b); return __builtin_bit_cast(unsigned, b); }
; DI float xhalf_sum(float m) { auto rr = __builtin_amdgcn_permlane32_swap(__float_as_uint(m), __float_as_uint(m), false, false); return __uint_as_float(rr[0]) + __uint_as_float(rr[1]); }
; template <int DQK, int DV, bool CAUSAL, int KT, bool PRIO>
; DI void attn_unit(const bf16_t* Qb, int qpitch, const bf16_t* Kb, int kpitch, const bf16_t* Vtb, int vpitch, bf16_t* Ob, int opitch, int q0, int nt, LAS unsigned char* lds, float kbound, const float* qgain, const int* qpos, float qscale) {
;     ...
;     auto gload = [&](int kt) {
; #pragma unroll
;         for (int i = 0; i < NKR; ++i) { const int c = tid + i * 512; if (NKC % 512 == 0 || c < NKC) kreg[i] = *(const u32x4*)(Kb + (size_t)(kt * KT + c / KCH) * kpitch + (c % KCH) * 8); }
; #pragma unroll
;         for (int i = 0; i < NVR; ++i) { const int c = tid + i * 512; vreg[i] = *(const u32x4*)(Vtb + (size_t)(c / VCH) * vpitch + kt * KT + (c % VCH) * 8); }
;     };
;     auto lstore = [&](int buf) {
; #pragma unroll
;         for (int i = 0; i < NKR; ++i) { const int c = tid + i * 512; if (NKC % 512 == 0 || c < NKC) *(LAS u32x4*)(lds + buf * KBUF + (c / KCH) * KS + (c % KCH) * 16) = kreg[i]; }
; #pragma unroll
;         for (int i = 0; i < NVR; ++i) { const int c = tid + i * 512; LAS unsigned char* p = lds + VOFF + buf * VBUF + (c / VCH) * VS + (c % VCH) * 16;
;             *(LAS u32x2*)p = (u32x2){vreg[i].x, vreg[i].y}; *(LAS u32x2*)(p + 8) = (u32x2){vreg[i].z, vreg[i].w}; }
;     };
;     gload(0);
;     bf16x8 qf[DQK / 16];
; #pragma unroll
;     for (int ks = 0; ks < DQK / 16; ++ks) qf[ks] = *(const bf16x8*)(Qb + (size_t)(32 * w + r) * qpitch + 16 * ks + 8 * h);
;     ...
;     lrun = xhalf_sum(lrun);
;     const float inv = 1.0f / lrun;
;     bf16_t* orow = Ob + (size_t)(32 * w + r) * opitch;
; #pragma unroll
;     for (int d = 0; d < DV / 32; ++d)
; #pragma unroll
;         for (int g = 0; g < 4; ++g) { u32x2 wv; wv.x = pk2(o[d][4 * g] * inv, o[d][4 * g + 1] * inv); wv.y = pk2(o[d][4 * g + 2] * inv, o[d][4 * g + 3] * inv);
;             *(u32x2*)(orow + 32 * d + 8 * g + 4 * h) = wv; }
.LBB0_1479:
	v_mov_b32_e32 v2, v0
	s_nop 1
	v_permlane32_swap_b32_e32 v0, v2
	v_add_f32_e32 v0, v0, v2
	v_div_scale_f32 v2, s[2:3], v0, v0, 1.0
	v_rcp_f32_e32 v3, v2
	s_lshl_b64 s[2:3], s[26:27], 10
	s_add_u32 s2, s65, s2
	s_addc_u32 s3, s66, s3
	v_fma_f32 v4, -v2, v3, 1.0
	v_fmac_f32_e32 v3, v4, v3
	v_div_scale_f32 v4, vcc, 1.0, v0, 1.0
	v_mul_f32_e32 v5, v4, v3
	v_fma_f32 v6, -v2, v5, v4
	v_fmac_f32_e32 v5, v6, v3
	v_fma_f32 v2, -v2, v5, v4
	v_div_fmas_f32 v2, v2, v3, v5
	v_div_fixup_f32 v2, v2, v0, 1.0
	v_lshlrev_b64 v[4:5], 10, v[162:163]
	v_lshl_add_u64 v[4:5], s[2:3], 0, v[4:5]
	v_lshlrev_b32_e32 v0, 1, v180
	v_pk_mul_f32 v[6:7], v[32:33], v[2:3] op_sel_hi:[1,0]
	v_pk_mul_f32 v[8:9], v[34:35], v[2:3] op_sel_hi:[1,0]
	v_lshl_add_u64 v[4:5], v[4:5], 0, v[0:1]
	v_cvt_pk_bf16_f32 v6, v6, v7
	v_cvt_pk_bf16_f32 v7, v8, v9
	global_store_dwordx2 v[4:5], v[6:7], off
	v_pk_mul_f32 v[6:7], v[36:37], v[2:3] op_sel_hi:[1,0]
	v_pk_mul_f32 v[8:9], v[38:39], v[2:3] op_sel_hi:[1,0]
	v_cvt_pk_bf16_f32 v6, v6, v7
	v_cvt_pk_bf16_f32 v7, v8, v9
	global_store_dwordx2 v[4:5], v[6:7], off offset:16
	v_pk_mul_f32 v[6:7], v[40:41], v[2:3] op_sel_hi:[1,0]
	v_pk_mul_f32 v[8:9], v[42:43], v[2:3] op_sel_hi:[1,0]
	v_cvt_pk_bf16_f32 v6, v6, v7
	v_cvt_pk_bf16_f32 v7, v8, v9
	global_store_dwordx2 v[4:5], v[6:7], off offset:32
	v_pk_mul_f32 v[6:7], v[44:45], v[2:3] op_sel_hi:[1,0]
	v_pk_mul_f32 v[8:9], v[46:47], v[2:3] op_sel_hi:[1,0]
	v_cvt_pk_bf16_f32 v6, v6, v7
	v_cvt_pk_bf16_f32 v7, v8, v9
	global_store_dwordx2 v[4:5], v[6:7], off offset:48
	v_pk_mul_f32 v[6:7], v[16:17], v[2:3] op_sel_hi:[1,0]
	v_pk_mul_f32 v[8:9], v[18:19], v[2:3] op_sel_hi:[1,0]
	v_cvt_pk_bf16_f32 v6, v6, v7
	v_cvt_pk_bf16_f32 v7, v8, v9
	global_store_dwordx2 v[4:5], v[6:7], off offset:64
	v_pk_mul_f32 v[6:7], v[20:21], v[2:3] op_sel_hi:[1,0]
	v_pk_mul_f32 v[8:9], v[22:23], v[2:3] op_sel_hi:[1,0]
	v_cvt_pk_bf16_f32 v6, v6, v7
	v_cvt_pk_bf16_f32 v7, v8, v9
	global_store_dwordx2 v[4:5], v[6:7], off offset:80
	v_pk_mul_f32 v[6:7], v[24:25], v[2:3] op_sel_hi:[1,0]
	v_pk_mul_f32 v[8:9], v[26:27], v[2:3] op_sel_hi:[1,0]
	v_cvt_pk_bf16_f32 v6, v6, v7
	v_cvt_pk_bf16_f32 v7, v8, v9
	global_store_dwordx2 v[4:5], v[6:7], off offset:96
	v_pk_mul_f32 v[6:7], v[28:29], v[2:3] op_sel_hi:[1,0]
	v_pk_mul_f32 v[2:3], v[30:31], v[2:3] op_sel_hi:[1,0]
	v_cvt_pk_bf16_f32 v6, v6, v7
	v_cvt_pk_bf16_f32 v7, v2, v3
	s_mov_b64 s[2:3], 0
	s_and_b64 vcc, exec, s[34:35]
	global_store_dwordx2 v[4:5], v[6:7], off offset:112
	s_cbranch_vccnz .LBB0_1477
.LBB0_1480:
	v_mov_b32_e32 v155, v196
	s_and_b64 s[12:13], s[2:3], exec
	v_mul_hi_i32 v0, v155, s89
	v_lshrrev_b32_e32 v2, 31, v0
	v_ashrrev_i32_e32 v0, 1, v0
	v_add_u32_e32 v149, v0, v2
	v_mul_lo_u32 v0, v149, 12
	v_sub_u32_e32 v150, v155, v0
	v_add_u32_e32 v0, 0x200, v155
	v_mul_hi_i32 v4, v0, s89
	v_lshrrev_b32_e32 v5, 31, v4
	v_ashrrev_i32_e32 v4, 1, v4
	v_add_u32_e32 v151, v4, v5
	v_mul_lo_u32 v6, v151, 12
	v_sub_u32_e32 v152, v0, v6
	v_lshlrev_b32_e32 v58, 3, v150
	v_lshlrev_b32_e32 v60, 3, v152
	v_mad_i64_i32 v[2:3], s[34:35], v149, s88, v[160:161]
	v_ashrrev_i32_e32 v59, 31, v58
	v_mad_i64_i32 v[4:5], s[34:35], v151, s88, v[160:161]
	v_ashrrev_i32_e32 v61, 31, v60
	v_lshl_add_u64 v[2:3], v[58:59], 1, v[2:3]
	v_lshl_add_u64 v[4:5], v[60:61], 1, v[4:5]
	s_waitcnt vmcnt(0)
	global_load_dwordx4 v[96:99], v[2:3], off
	global_load_dwordx4 v[100:103], v[4:5], off
	v_add_u32_e32 v4, 0x400, v155
	v_mul_hi_i32 v2, v4, s89
	v_lshrrev_b32_e32 v3, 31, v2
	v_ashrrev_i32_e32 v2, 1, v2
	v_add_u32_e32 v153, v2, v3
	v_mul_lo_u32 v5, v153, 12
	v_sub_u32_e32 v154, v4, v5
	v_ashrrev_i32_e32 v4, 31, v155
	v_lshrrev_b32_e32 v4, 28, v4
	v_add_u32_e32 v6, v155, v4
	v_ashrrev_i32_e32 v68, 4, v6
	v_ashrrev_i32_e32 v69, 31, v68
	v_and_b32_e32 v6, -16, v6
	v_lshlrev_b32_e32 v62, 3, v154
	v_lshlrev_b64 v[64:65], 14, v[68:69]
	v_sub_u32_e32 v69, v155, v6
	v_mad_i64_i32 v[2:3], s[34:35], v153, s88, v[160:161]
	v_ashrrev_i32_e32 v63, 31, v62
	v_lshlrev_b32_e32 v66, 3, v69
	v_lshl_add_u64 v[2:3], v[62:63], 1, v[2:3]
	v_lshl_add_u64 v[4:5], s[20:21], 0, v[64:65]
	v_ashrrev_i32_e32 v67, 31, v66
	s_cselect_b32 s38, s60, s59
	v_lshl_add_u64 v[4:5], v[66:67], 1, v[4:5]
	global_load_dwordx4 v[104:107], v[2:3], off
	global_load_dwordx4 v[108:111], v[4:5], off
	v_ashrrev_i32_e32 v2, 31, v0
	s_or_b32 s26, s38, s18
	v_lshrrev_b32_e32 v2, 28, v2
	s_mul_i32 s12, s26, 0x600
	v_add_u32_e32 v4, v0, v2
	s_mul_hi_i32 s13, s26, 0x600
	s_add_u32 s12, s61, s12
	v_readfirstlane_b32 s27, v155
	v_ashrrev_i32_e32 v74, 4, v4
	s_addc_u32 s13, s64, s13
	v_ashrrev_i32_e32 v75, 31, v74
	v_and_b32_e32 v4, -16, v4
	s_ashr_i32 s39, s27, 1
	v_lshlrev_b64 v[70:71], 14, v[74:75]
	v_sub_u32_e32 v75, v0, v4
	v_mov_b32_e32 v0, s39
	v_bfe_u32 v148, v155, 5, 1
	v_lshlrev_b32_e32 v72, 3, v75
	v_bfi_b32 v162, s90, v0, v155
	v_mov_b64_e32 v[4:5], s[12:13]
	v_lshl_add_u64 v[2:3], s[20:21], 0, v[70:71]
	v_ashrrev_i32_e32 v73, 31, v72
	v_mad_i64_i32 v[4:5], s[12:13], v162, s88, v[4:5]
	v_lshlrev_b32_e32 v0, 4, v148
	v_lshl_add_u64 v[2:3], v[72:73], 1, v[2:3]
	v_lshl_add_u64 v[22:23], v[4:5], 0, v[0:1]
	global_load_dwordx4 v[112:115], v[2:3], off
	s_nop 0
	global_load_dwordx4 v[2:5], v[22:23], off
	global_load_dwordx4 v[6:9], v[22:23], off offset:32
	global_load_dwordx4 v[10:13], v[22:23], off offset:64
	global_load_dwordx4 v[14:17], v[22:23], off offset:96
	global_load_dwordx4 v[18:21], v[22:23], off offset:128
	s_nop 0
	global_load_dwordx4 v[22:25], v[22:23], off offset:160
	s_mov_b64 s[12:13], -1
	v_ashrrev_i32_e32 v163, 31, v162
	v_lshlrev_b32_e32 v0, 3, v148
	s_and_b64 vcc, exec, s[6:7]
	s_cbranch_vccz .LBB0_1484
; DI float xhalf_sum(float m) { auto rr = __builtin_amdgcn_permlane32_swap(__float_as_uint(m), __float_as_uint(m), false, false); return __uint_as_float(rr[0]) + __uint_as_float(rr[1]); }
; template <int DQK, int DV, bool CAUSAL, int KT, bool PRIO>
; DI void attn_unit(const bf16_t* Qb, int qpitch, const bf16_t* Kb, int kpitch, const bf16_t* Vtb, int vpitch, bf16_t* Ob, int opitch, int q0, int nt, LAS unsigned char* lds, float kbound, const float* qgain, const int* qpos, float qscale) {
;     ...
;     if (qgain) {
;         float v[DQK / 16][8]; float q2 = 0.f;
; #pragma unroll
;         for (int ks = 0; ks < DQK / 16; ++ks)
; #pragma unroll
;             for (int e = 0; e < 8; ++e) { v[ks][e] = __uint_as_float(((unsigned)(unsigned short)qf[ks][e]) << 16); q2 += v[ks][e] * v[ks][e]; }
;         q2 = xhalf_sum(q2);
	v_lshlrev_b32_e32 v129, 2, v0
	global_load_dwordx4 v[50:53], v129, s[54:55] offset:16
	global_load_dwordx4 v[54:57], v129, s[54:55]
	global_load_dwordx4 v[42:45], v129, s[54:55] offset:80
	global_load_dwordx4 v[46:49], v129, s[54:55] offset:64
	global_load_dwordx4 v[34:37], v129, s[54:55] offset:144
	global_load_dwordx4 v[38:41], v129, s[54:55] offset:128
	global_load_dwordx4 v[26:29], v129, s[54:55] offset:208
	global_load_dwordx4 v[30:33], v129, s[54:55] offset:192
	global_load_dwordx4 v[134:137], v129, s[54:55] offset:256
	global_load_dwordx4 v[138:141], v129, s[54:55] offset:272
	global_load_dwordx4 v[156:159], v129, s[54:55] offset:320
	global_load_dwordx4 v[164:167], v129, s[54:55] offset:336
	s_waitcnt vmcnt(0) lgkmcnt(0)
	v_and_b32_e32 v127, 0xffff0000, v2
	v_lshlrev_b32_e32 v126, 16, v2
	v_mul_f32_e32 v128, v127, v127
	v_and_b32_e32 v123, 0xffff0000, v3
	v_lshlrev_b32_e32 v122, 16, v3
	v_pk_fma_f32 v[178:179], v[126:127], v[126:127], v[128:129] op_sel_hi:[1,1,0]
	v_mul_f32_e32 v128, v123, v123
	v_pk_fma_f32 v[178:179], v[122:123], v[122:123], v[178:179]
	v_and_b32_e32 v125, 0xffff0000, v4
	v_lshlrev_b32_e32 v124, 16, v4
	v_pk_add_f32 v[178:179], v[128:129], v[178:179] op_sel_hi:[0,1]
	v_pk_fma_f32 v[178:179], v[124:125], v[124:125], v[178:179]
	v_mul_f32_e32 v128, v125, v125
	v_and_b32_e32 v121, 0xffff0000, v5
	v_lshlrev_b32_e32 v120, 16, v5
	v_pk_add_f32 v[178:179], v[128:129], v[178:179] op_sel_hi:[0,1]
	v_pk_fma_f32 v[178:179], v[120:121], v[120:121], v[178:179]
	v_mul_f32_e32 v128, v121, v121
	v_and_b32_e32 v119, 0xffff0000, v6
	v_lshlrev_b32_e32 v118, 16, v6
	v_pk_add_f32 v[178:179], v[128:129], v[178:179] op_sel_hi:[0,1]
	v_pk_fma_f32 v[178:179], v[118:119], v[118:119], v[178:179]
	v_mul_f32_e32 v128, v119, v119
	v_and_b32_e32 v95, 0xffff0000, v7
	v_lshlrev_b32_e32 v94, 16, v7
	v_pk_add_f32 v[178:179], v[128:129], v[178:179] op_sel_hi:[0,1]
	v_pk_fma_f32 v[178:179], v[94:95], v[94:95], v[178:179]
	v_mul_f32_e32 v128, v95, v95
	v_and_b32_e32 v117, 0xffff0000, v8
	v_lshlrev_b32_e32 v116, 16, v8
	v_pk_add_f32 v[178:179], v[128:129], v[178:179] op_sel_hi:[0,1]
	v_pk_fma_f32 v[178:179], v[116:117], v[116:117], v[178:179]
	v_mul_f32_e32 v128, v117, v117
	v_and_b32_e32 v93, 0xffff0000, v9
	v_lshlrev_b32_e32 v92, 16, v9
	v_pk_add_f32 v[178:179], v[128:129], v[178:179] op_sel_hi:[0,1]
	v_pk_fma_f32 v[178:179], v[92:93], v[92:93], v[178:179]
	v_mul_f32_e32 v128, v93, v93
	v_and_b32_e32 v91, 0xffff0000, v10
	v_lshlrev_b32_e32 v90, 16, v10
	v_pk_add_f32 v[178:179], v[128:129], v[178:179] op_sel_hi:[0,1]
	v_pk_fma_f32 v[178:179], v[90:91], v[90:91], v[178:179]
	v_mul_f32_e32 v128, v91, v91
	v_and_b32_e32 v87, 0xffff0000, v11
	v_lshlrev_b32_e32 v86, 16, v11
	v_pk_add_f32 v[178:179], v[128:129], v[178:179] op_sel_hi:[0,1]
	v_pk_fma_f32 v[178:179], v[86:87], v[86:87], v[178:179]
	v_mul_f32_e32 v128, v87, v87
	v_and_b32_e32 v89, 0xffff0000, v12
	v_lshlrev_b32_e32 v88, 16, v12
	v_pk_add_f32 v[178:179], v[128:129], v[178:179] op_sel_hi:[0,1]
	v_pk_fma_f32 v[178:179], v[88:89], v[88:89], v[178:179]
	v_mul_f32_e32 v128, v89, v89
	v_and_b32_e32 v85, 0xffff0000, v13
	v_lshlrev_b32_e32 v84, 16, v13
	v_pk_add_f32 v[178:179], v[128:129], v[178:179] op_sel_hi:[0,1]
	v_pk_fma_f32 v[178:179], v[84:85], v[84:85], v[178:179]
	v_mul_f32_e32 v128, v85, v85
	v_and_b32_e32 v83, 0xffff0000, v14
	v_lshlrev_b32_e32 v82, 16, v14
	v_pk_add_f32 v[178:179], v[128:129], v[178:179] op_sel_hi:[0,1]
	v_pk_fma_f32 v[178:179], v[82:83], v[82:83], v[178:179]
	v_mul_f32_e32 v128, v83, v83
	v_and_b32_e32 v79, 0xffff0000, v15
	v_lshlrev_b32_e32 v78, 16, v15
	v_pk_add_f32 v[178:179], v[128:129], v[178:179] op_sel_hi:[0,1]
	v_pk_fma_f32 v[178:179], v[78:79], v[78:79], v[178:179]
	v_mul_f32_e32 v128, v79, v79
	v_and_b32_e32 v81, 0xffff0000, v16
	v_lshlrev_b32_e32 v80, 16, v16
	v_pk_add_f32 v[178:179], v[128:129], v[178:179] op_sel_hi:[0,1]
	v_pk_fma_f32 v[178:179], v[80:81], v[80:81], v[178:179]
	v_mul_f32_e32 v128, v81, v81
	v_and_b32_e32 v77, 0xffff0000, v17
	v_lshlrev_b32_e32 v76, 16, v17
	v_pk_add_f32 v[178:179], v[128:129], v[178:179] op_sel_hi:[0,1]
	v_pk_fma_f32 v[178:179], v[76:77], v[76:77], v[178:179]
	v_mul_f32_e32 v128, v77, v77
	v_and_b32_e32 v133, 0xffff0000, v18
	v_lshlrev_b32_e32 v132, 16, v18
	v_pk_add_f32 v[178:179], v[128:129], v[178:179] op_sel_hi:[0,1]
	v_pk_fma_f32 v[178:179], v[132:133], v[132:133], v[178:179]
	v_mul_f32_e32 v128, v133, v133
	v_and_b32_e32 v147, 0xffff0000, v19
	v_lshlrev_b32_e32 v146, 16, v19
	v_pk_add_f32 v[178:179], v[128:129], v[178:179] op_sel_hi:[0,1]
	v_pk_fma_f32 v[178:179], v[146:147], v[146:147], v[178:179]
	v_mul_f32_e32 v128, v147, v147
	v_and_b32_e32 v145, 0xffff0000, v20
	v_lshlrev_b32_e32 v144, 16, v20
	v_pk_add_f32 v[178:179], v[128:129], v[178:179] op_sel_hi:[0,1]
	v_pk_fma_f32 v[178:179], v[144:145], v[144:145], v[178:179]
	v_mul_f32_e32 v128, v145, v145
	v_and_b32_e32 v131, 0xffff0000, v21
	v_lshlrev_b32_e32 v130, 16, v21
	v_pk_add_f32 v[178:179], v[128:129], v[178:179] op_sel_hi:[0,1]
	v_pk_fma_f32 v[178:179], v[130:131], v[130:131], v[178:179]
	v_mul_f32_e32 v128, v131, v131
	v_and_b32_e32 v173, 0xffff0000, v22
	v_lshlrev_b32_e32 v172, 16, v22
	v_pk_add_f32 v[178:179], v[128:129], v[178:179] op_sel_hi:[0,1]
	v_pk_fma_f32 v[178:179], v[172:173], v[172:173], v[178:179]
	v_mul_f32_e32 v128, v173, v173
	v_and_b32_e32 v171, 0xffff0000, v23
	v_lshlrev_b32_e32 v170, 16, v23
	v_pk_add_f32 v[178:179], v[128:129], v[178:179] op_sel_hi:[0,1]
	v_pk_fma_f32 v[178:179], v[170:171], v[170:171], v[178:179]
	v_mul_f32_e32 v128, v171, v171
; DI float xhalf_sum(float m) { auto rr = __builtin_amdgcn_permlane32_swap(__float_as_uint(m), __float_as_uint(m), false, false); return __uint_as_float(rr[0]) + __uint_as_float(rr[1]); }
; template <int DQK, int DV, bool CAUSAL, int KT, bool PRIO>
; DI void attn_unit(const bf16_t* Qb, int qpitch, const bf16_t* Kb, int kpitch, const bf16_t* Vtb, int vpitch, bf16_t* Ob, int opitch, int q0, int nt, LAS unsigned char* lds, float kbound, const float* qgain, const int* qpos, float qscale) {
;     ...
;         q2 = xhalf_sum(q2);
;         const float rq = __builtin_amdgcn_rsqf(q2 * (1.0f / (float)DQK) + EPS) * qscale;
; #pragma unroll
;         for (int ks = 0; ks < DQK / 16; ++ks) { const f32x4 g0 = *(const f32x4*)(qgain + 16 * ks + 8 * h), g1 = *(const f32x4*)(qgain + 16 * ks + 8 * h + 4);
; #pragma unroll
;             for (int e = 0; e < 4; ++e) { v[ks][e] *= rq * g0[e]; v[ks][4 + e] *= rq * g1[e]; } }
;         if (DQK == 96 && qpos) {
;         const float pos = (float)qpos[32 * w + r];
; #pragma unroll
;         for (int e = 0; e < 8; ++e) {
;             const float ang = pos * ROPE_INV[8 * h + e]; const double rev = (double)ang * 0.15915494309189535; const float f = (float)(rev - floor(rev));
;             const float c = __builtin_amdgcn_cosf(f), sn_ = __builtin_amdgcn_sinf(f), x1 = v[4][e], x2 = v[5][e];
;             v[4][e] = x1 * c - x2 * sn_; v[5][e] = x2 * c + x1 * sn_; }
	v_and_b32_e32 v169, 0xffff0000, v24
	v_lshlrev_b32_e32 v168, 16, v24
	v_pk_add_f32 v[178:179], v[128:129], v[178:179] op_sel_hi:[0,1]
	v_pk_fma_f32 v[178:179], v[168:169], v[168:169], v[178:179]
	v_mul_f32_e32 v128, v169, v169
	v_and_b32_e32 v143, 0xffff0000, v25
	v_lshlrev_b32_e32 v142, 16, v25
	v_pk_add_f32 v[178:179], v[128:129], v[178:179] op_sel_hi:[0,1]
	v_pk_fma_f32 v[178:179], v[142:143], v[142:143], v[178:179]
	v_mul_f32_e32 v128, v143, v143
	v_pk_add_f32 v[178:179], v[128:129], v[178:179] op_sel_hi:[0,1]
	v_mov_b32_e32 v128, v178
	s_nop 1
	v_permlane32_swap_b32_e32 v178, v128
	v_add_f32_e32 v128, v178, v128
	v_fmamk_f32 v128, v128, 0x3c2aaaab, v175
	v_rsq_f32_e32 v128, v128
	s_andn2_b64 vcc, exec, s[8:9]
	v_mul_f32_e32 v128, 0x3e16c740, v128
	v_pk_mul_f32 v[134:135], v[128:129], v[134:135] op_sel_hi:[0,1]
	v_pk_mul_f32 v[138:139], v[128:129], v[138:139] op_sel_hi:[0,1]
	v_pk_mul_f32 v[132:133], v[134:135], v[132:133]
	v_pk_mul_f32 v[134:135], v[138:139], v[144:145]
	v_pk_mul_f32 v[138:139], v[128:129], v[140:141] op_sel_hi:[0,1]
	v_pk_mul_f32 v[136:137], v[128:129], v[136:137] op_sel_hi:[0,1]
	v_pk_mul_f32 v[144:145], v[138:139], v[130:131]
	v_pk_mul_f32 v[130:131], v[128:129], v[156:157] op_sel_hi:[0,1]
	v_pk_mul_f32 v[146:147], v[136:137], v[146:147]
	v_pk_mul_f32 v[138:139], v[128:129], v[164:165] op_sel_hi:[0,1]
	v_pk_mul_f32 v[136:137], v[130:131], v[172:173]
	v_pk_mul_f32 v[130:131], v[128:129], v[158:159] op_sel_hi:[0,1]
	v_pk_mul_f32 v[156:157], v[128:129], v[166:167] op_sel_hi:[0,1]
	v_pk_mul_f32 v[138:139], v[138:139], v[168:169]
	v_pk_mul_f32 v[140:141], v[130:131], v[170:171]
	v_pk_mul_f32 v[142:143], v[156:157], v[142:143]
	s_cbranch_vccnz .LBB0_1483
	s_lshl_b32 s12, s38, 2
	s_add_u32 s12, s19, s12
	s_addc_u32 s13, s67, 0
	v_lshl_add_u64 v[130:131], v[162:163], 2, s[12:13]
	global_load_dword v130, v[130:131], off
	s_getpc_b64 s[12:13]
	s_add_u32 s12, s12, ROPE_INV@rel32@lo+4
	s_addc_u32 s13, s13, ROPE_INV@rel32@hi+12
	global_load_dwordx4 v[156:159], v129, s[12:13]
	global_load_dwordx4 v[164:167], v129, s[12:13] offset:16
	s_waitcnt vmcnt(2)
	v_cvt_f32_i32_e32 v129, v130
	s_waitcnt vmcnt(1)
	v_mul_f32_e32 v130, v156, v129
	v_mul_f32_e32 v156, v157, v129
	v_mul_f32_e32 v158, v158, v129
	v_mul_f32_e32 v168, v159, v129
	s_waitcnt vmcnt(0)
	v_mul_f32_e32 v169, v164, v129
	v_mul_f32_e32 v170, v165, v129
	v_mul_f32_e32 v171, v166, v129
	v_mul_f32_e32 v129, v167, v129
	v_cvt_f64_f32_e32 v[130:131], v130
	v_cvt_f64_f32_e32 v[156:157], v156
	v_cvt_f64_f32_e32 v[158:159], v158
	v_cvt_f64_f32_e32 v[164:165], v168
	v_cvt_f64_f32_e32 v[166:167], v169
	v_cvt_f64_f32_e32 v[168:169], v170
	v_cvt_f64_f32_e32 v[170:171], v171
	v_cvt_f64_f32_e32 v[172:173], v129
	v_mul_f64 v[178:179], v[130:131], s[10:11]
	v_mul_f64 v[180:181], v[156:157], s[10:11]
	v_mul_f64 v[182:183], v[158:159], s[10:11]
	v_mul_f64 v[184:185], v[164:165], s[10:11]
	v_mul_f64 v[186:187], v[166:167], s[10:11]
	v_mul_f64 v[188:189], v[168:169], s[10:11]
	v_mul_f64 v[190:191], v[170:171], s[10:11]
	v_mul_f64 v[192:193], v[172:173], s[10:11]
	v_floor_f64_e32 v[178:179], v[178:179]
	v_floor_f64_e32 v[180:181], v[180:181]
	v_floor_f64_e32 v[182:183], v[182:183]
	v_floor_f64_e32 v[184:185], v[184:185]
	v_floor_f64_e32 v[186:187], v[186:187]
	v_floor_f64_e32 v[188:189], v[188:189]
	v_floor_f64_e32 v[190:191], v[190:191]
	v_floor_f64_e32 v[192:193], v[192:193]
	v_fma_f64 v[130:131], v[130:131], s[10:11], -v[178:179]
	v_fma_f64 v[156:157], v[156:157], s[10:11], -v[180:181]
	v_fma_f64 v[158:159], v[158:159], s[10:11], -v[182:183]
	v_fma_f64 v[164:165], v[164:165], s[10:11], -v[184:185]
	v_fma_f64 v[166:167], v[166:167], s[10:11], -v[186:187]
	v_fma_f64 v[168:169], v[168:169], s[10:11], -v[188:189]
	v_fma_f64 v[170:171], v[170:171], s[10:11], -v[190:191]
	v_fma_f64 v[172:173], v[172:173], s[10:11], -v[192:193]
	v_cvt_f32_f64_e32 v129, v[130:131]
	v_cvt_f32_f64_e32 v157, v[156:157]
	v_cvt_f32_f64_e32 v159, v[158:159]
	v_cvt_f32_f64_e32 v165, v[164:165]
	v_cvt_f32_f64_e32 v167, v[166:167]
	v_cvt_f32_f64_e32 v169, v[168:169]
	v_cvt_f32_f64_e32 v171, v[170:171]
	v_cvt_f32_f64_e32 v173, v[172:173]
	v_sin_f32_e32 v156, v129
	v_cos_f32_e32 v131, v157
	v_sin_f32_e32 v157, v157
	v_cos_f32_e32 v158, v159
	v_sin_f32_e32 v164, v159
	v_cos_f32_e32 v159, v165
	v_sin_f32_e32 v165, v165
	v_cos_f32_e32 v166, v167
	v_sin_f32_e32 v168, v167
	v_cos_f32_e32 v167, v169
	v_sin_f32_e32 v169, v169
	v_cos_f32_e32 v170, v171
	v_sin_f32_e32 v172, v171
	v_cos_f32_e32 v171, v173
	v_sin_f32_e32 v173, v173
	v_cos_f32_e32 v130, v129
	v_pk_mul_f32 v[178:179], v[136:137], v[156:157]
	v_pk_mul_f32 v[156:157], v[132:133], v[156:157]
	v_pk_mul_f32 v[180:181], v[140:141], v[164:165]
	v_pk_mul_f32 v[164:165], v[146:147], v[164:165]
	v_pk_mul_f32 v[182:183], v[138:139], v[168:169]
	v_pk_mul_f32 v[168:169], v[134:135], v[168:169]
	v_pk_mul_f32 v[184:185], v[142:143], v[172:173]
	v_pk_mul_f32 v[172:173], v[144:145], v[172:173]
	v_pk_fma_f32 v[132:133], v[132:133], v[130:131], v[178:179] neg_lo:[0,0,1] neg_hi:[0,0,1]
	v_pk_fma_f32 v[136:137], v[136:137], v[130:131], v[156:157]
	v_pk_fma_f32 v[146:147], v[146:147], v[158:159], v[180:181] neg_lo:[0,0,1] neg_hi:[0,0,1]
	v_pk_fma_f32 v[140:141], v[140:141], v[158:159], v[164:165]
	v_pk_fma_f32 v[134:135], v[134:135], v[166:167], v[182:183] neg_lo:[0,0,1] neg_hi:[0,0,1]
	v_pk_fma_f32 v[138:139], v[138:139], v[166:167], v[168:169]
	v_pk_fma_f32 v[144:145], v[144:145], v[170:171], v[184:185] neg_lo:[0,0,1] neg_hi:[0,0,1]
	v_pk_fma_f32 v[142:143], v[142:143], v[170:171], v[172:173]

; template <int DQK, int DV, bool CAUSAL, int KT, bool PRIO>
; DI void attn_unit(const bf16_t* Qb, int qpitch, const bf16_t* Kb, int kpitch, const bf16_t* Vtb, int vpitch, bf16_t* Ob, int opitch, int q0, int nt, LAS unsigned char* lds, float kbound, const float* qgain, const int* qpos, float qscale) {
;     ...
;     auto gload = [&](int kt) {
; #pragma unroll
;         for (int i = 0; i < NKR; ++i) { const int c = tid + i * 512; if (NKC % 512 == 0 || c < NKC) kreg[i] = *(const u32x4*)(Kb + (size_t)(kt * KT + c / KCH) * kpitch + (c % KCH) * 8); }
; #pragma unroll
;         for (int i = 0; i < NVR; ++i) { const int c = tid + i * 512; vreg[i] = *(const u32x4*)(Vtb + (size_t)(c / VCH) * vpitch + kt * KT + (c % VCH) * 8); }
;     };
;     ...
;         if (kt + 1 < nt) gload(kt + 1);
.LBB0_1487:
	s_add_i32 s74, s12, 1
	s_cmp_lt_u32 s74, s68
	s_cselect_b64 s[38:39], -1, 0
	s_cmp_ge_u32 s74, s68
	s_cbranch_scc1 .LBB0_1489
	v_lshl_add_u64 v[2:3], s[4:5], 0, v[172:173]
	v_lshl_add_u64 v[4:5], s[4:5], 0, v[170:171]
	s_waitcnt vmcnt(0)
	global_load_dwordx4 v[96:99], v[2:3], off
	global_load_dwordx4 v[100:103], v[4:5], off
	v_lshl_add_u64 v[2:3], s[4:5], 0, v[168:169]
	v_lshl_add_u64 v[4:5], s[4:5], 0, v[166:167]
	global_load_dwordx4 v[104:107], v[2:3], off
	global_load_dwordx4 v[108:111], v[4:5], off
	v_lshl_add_u64 v[2:3], s[4:5], 0, v[164:165]
	global_load_dwordx4 v[112:115], v[2:3], off

; #define LAS __attribute__((address_space(3)))
; DI unsigned pk2(float lo, float hi) { typedef float v2f __attribute__((ext_vector_type(2))); typedef __bf16 v2b __attribute__((ext_vector_type(2))); v2f v = {lo, hi}; v2b b = __builtin_convertvector(v, v2b); return __builtin_bit_cast(unsigned, b); }
; #define MFMA32(a, b, c) __builtin_amdgcn_mfma_f32_32x32x16_bf16((a), (b), (c), 0, 0, 0)
; DI float xhalf_sum(float m) { auto rr = __builtin_amdgcn_permlane32_swap(__float_as_uint(m), __float_as_uint(m), false, false); return __uint_as_float(rr[0]) + __uint_as_float(rr[1]); }
; template <int DQK, int DV, bool CAUSAL, int KT, bool PRIO>
; DI void attn_unit(const bf16_t* Qb, int qpitch, const bf16_t* Kb, int kpitch, const bf16_t* Vtb, int vpitch, bf16_t* Ob, int opitch, int q0, int nt, LAS unsigned char* lds, float kbound, const float* qgain, const int* qpos, float qscale) {
;     ...
;                     for (int kb2 = 0; kb2 < 2; ++kb2) {
;                         f32x16& sx = kb2 == 0 ? s0 : s1;
; #pragma unroll
;                         for (int i = 0; i < 16; ++i) { sx[i] = __builtin_amdgcn_exp2f(sx[i]); ps += sx[i]; }
;                         if (PRIO) __builtin_amdgcn_s_setprio(1);
; #pragma unroll
;                         for (int sf = 0; sf < 2; ++sf) {
;                             u32x4 pw; pw.x = pk2(sx[8 * sf], sx[8 * sf + 1]); pw.y = pk2(sx[8 * sf + 2], sx[8 * sf + 3]); pw.z = pk2(sx[8 * sf + 4], sx[8 * sf + 5]); pw.w = pk2(sx[8 * sf + 6], sx[8 * sf + 7]);
;                             const bf16x8 pf = __builtin_bit_cast(bf16x8, pw);
; #pragma unroll
;                             for (int d = 0; d < DV / 32; ++d) {
;                                 const LAS unsigned char* vp = vb + d * 32 * VS + (32 * kb2 + 16 * sf) * 2;
;                                 const s16x4 lo = *(const LAS s16x4*)vp, hi = *(const LAS s16x4*)(vp + 16);
;                                 const bf16x8 a = (bf16x8){lo[0], lo[1], lo[2], lo[3], hi[0], hi[1], hi[2], hi[3]};
;                                 o[d] = MFMA32(a, pf, o[d]);
;                                 if (!PRIO) asm volatile("" ::: "memory");
;                             }
;                         }
;                         if (PRIO) __builtin_amdgcn_s_setprio(0);
;                     }
;                     lrun += ps;
;     ...
;     lrun = xhalf_sum(lrun);
;     const float inv = 1.0f / lrun;
.LBB0_1519:
	ds_read2_b64 v[88:91], v97 offset0:128 offset1:130
	v_exp_f32_e32 v96, v104
	v_exp_f32_e32 v104, v105
	v_exp_f32_e32 v105, v106
	v_exp_f32_e32 v106, v107
	v_exp_f32_e32 v107, v100
	v_exp_f32_e32 v109, v101
	v_exp_f32_e32 v110, v102
	v_exp_f32_e32 v111, v103
	v_cvt_pk_bf16_f32 v92, v96, v104
	v_cvt_pk_bf16_f32 v93, v105, v106
	v_cvt_pk_bf16_f32 v94, v107, v109
	v_cvt_pk_bf16_f32 v95, v110, v111
	v_exp_f32_e32 v113, v75
	v_exp_f32_e32 v114, v76
	s_waitcnt lgkmcnt(0)
	v_mfma_f32_32x32x16_bf16 v[48:63], v[88:91], v[92:95], v[48:63]
	ds_read2_b64 v[88:91], v170 offset0:160 offset1:162
	v_exp_f32_e32 v115, v77
	v_exp_f32_e32 v112, v86
	v_exp_f32_e32 v84, v84
	v_exp_f32_e32 v85, v85
	v_exp_f32_e32 v116, v68
	s_waitcnt lgkmcnt(0)
	v_mfma_f32_32x32x16_bf16 v[32:47], v[88:91], v[92:95], v[32:47]
	ds_read2_b64 v[88:91], v208 offset0:192 offset1:194
	ds_read2_b64 v[100:103], v209 offset0:224 offset1:226
	v_exp_f32_e32 v117, v69
	v_add_f32_e32 v96, 0, v96
	v_add_f32_e32 v96, v104, v96
	s_waitcnt lgkmcnt(1)
	v_mfma_f32_32x32x16_bf16 v[16:31], v[88:91], v[92:95], v[16:31]
	v_exp_f32_e32 v91, v74
	ds_read2_b64 v[74:77], v97 offset0:132 offset1:134
	v_exp_f32_e32 v90, v87
	v_cvt_pk_bf16_f32 v88, v114, v115
	v_cvt_pk_bf16_f32 v87, v91, v113
	v_cvt_pk_bf16_f32 v86, v112, v90
	s_waitcnt lgkmcnt(1)
	v_mfma_f32_32x32x16_bf16 v[0:15], v[100:103], v[92:95], v[0:15]
	v_exp_f32_e32 v92, v72
	v_exp_f32_e32 v93, v73
	v_exp_f32_e32 v94, v98
	v_exp_f32_e32 v95, v99
	v_exp_f32_e32 v98, v82
	v_cvt_pk_bf16_f32 v89, v92, v93
	v_exp_f32_e32 v99, v83
	v_exp_f32_e32 v100, v80
	s_waitcnt lgkmcnt(0)
	v_mfma_f32_32x32x16_bf16 v[48:63], v[74:77], v[86:89], v[48:63]
	ds_read2_b64 v[72:75], v170 offset0:164 offset1:166
	ds_read2_b64 v[76:79], v208 offset0:196 offset1:198
	v_exp_f32_e32 v102, v64
	v_exp_f32_e32 v103, v65
	v_exp_f32_e32 v101, v71
	s_waitcnt lgkmcnt(1)
	v_mfma_f32_32x32x16_bf16 v[32:47], v[72:75], v[86:89], v[32:47]
	ds_read2_b64 v[72:75], v209 offset0:228 offset1:230
	v_cvt_pk_bf16_f32 v71, v116, v117
	s_lshl_b64 s[4:5], s[4:5], 9
	s_lshl_b32 s6, s35, 7
	s_lshl_b64 s[4:5], s[4:5], 1
	s_add_u32 s4, s16, s4
	s_waitcnt lgkmcnt(1)
	v_mfma_f32_32x32x16_bf16 v[16:31], v[76:79], v[86:89], v[16:31]
	ds_read2_b64 v[76:79], v97 offset0:136 offset1:138
	s_addc_u32 s5, s17, s5
	s_lshl_b32 s6, s6, 1
	s_add_u32 s4, s4, s6
	s_addc_u32 s5, s5, 0
	v_mov_b32_e32 v175, v171
	s_waitcnt lgkmcnt(1)
	v_mfma_f32_32x32x16_bf16 v[0:15], v[72:75], v[86:89], v[0:15]
	v_exp_f32_e32 v86, v81
	v_cvt_pk_bf16_f32 v72, v94, v95
	v_cvt_pk_bf16_f32 v73, v98, v99
	v_cvt_pk_bf16_f32 v74, v84, v85
	v_cvt_pk_bf16_f32 v75, v100, v86
	ds_read2_b64 v[80:83], v170 offset0:168 offset1:170
	v_exp_f32_e32 v87, v66
	s_waitcnt lgkmcnt(1)
	v_mfma_f32_32x32x16_bf16 v[48:63], v[76:79], v[72:75], v[48:63]
	ds_read2_b64 v[76:79], v208 offset0:200 offset1:202
	v_exp_f32_e32 v88, v67
	ds_read2_b64 v[64:67], v209 offset0:232 offset1:234
	v_exp_f32_e32 v89, v70
	v_cvt_pk_bf16_f32 v68, v87, v88
	s_waitcnt lgkmcnt(1)
	v_mfma_f32_32x32x16_bf16 v[16:31], v[76:79], v[72:75], v[16:31]
	ds_read2_b64 v[76:79], v97 offset0:140 offset1:142
	v_cvt_pk_bf16_f32 v69, v89, v101
	v_cvt_pk_bf16_f32 v70, v102, v103
	s_add_i32 s34, s34, s86
	s_add_i32 s18, s18, s19
	s_cmpk_lt_i32 s34, 0x100
	s_waitcnt lgkmcnt(0)
	v_mfma_f32_32x32x16_bf16 v[48:63], v[76:79], v[68:71], v[48:63]
	v_add_f32_e32 v76, v105, v96
	v_add_f32_e32 v76, v106, v76
	v_add_f32_e32 v76, v107, v76
	v_add_f32_e32 v76, v109, v76
	v_add_f32_e32 v76, v110, v76
	v_add_f32_e32 v76, v111, v76
	v_add_f32_e32 v76, v112, v76
	v_mfma_f32_32x32x16_bf16 v[32:47], v[80:83], v[72:75], v[32:47]
	ds_read2_b64 v[80:83], v170 offset0:172 offset1:174
	v_add_f32_e32 v76, v90, v76
	v_add_f32_e32 v76, v91, v76
	v_add_f32_e32 v76, v113, v76
	v_add_f32_e32 v76, v114, v76
	v_add_f32_e32 v76, v115, v76
	v_mfma_f32_32x32x16_bf16 v[0:15], v[64:67], v[72:75], v[0:15]
	ds_read2_b64 v[64:67], v208 offset0:204 offset1:206
	v_add_f32_e32 v76, v92, v76
	v_add_f32_e32 v76, v93, v76
	ds_read2_b64 v[72:75], v209 offset0:236 offset1:238
	s_waitcnt lgkmcnt(0)
	v_mfma_f32_32x32x16_bf16 v[16:31], v[64:67], v[68:71], v[16:31]
	v_add_f32_e32 v64, v94, v76
	v_add_f32_e32 v64, v95, v64
	v_add_f32_e32 v64, v98, v64
	v_add_f32_e32 v64, v99, v64
	v_add_f32_e32 v64, v84, v64
	v_add_f32_e32 v64, v85, v64
	v_add_f32_e32 v64, v100, v64
	v_add_f32_e32 v64, v86, v64
	v_add_f32_e32 v64, v87, v64
	v_add_f32_e32 v64, v88, v64
	v_add_f32_e32 v64, v89, v64
	v_add_f32_e32 v64, v101, v64
	v_add_f32_e32 v64, v102, v64
	v_add_f32_e32 v64, v103, v64
	v_add_f32_e32 v64, v116, v64
	v_add_f32_e32 v64, v117, v64
	v_add_f32_e32 v64, v108, v64
	v_mov_b32_e32 v65, v64
	s_nop 1
	v_permlane32_swap_b32_e32 v64, v65
	v_add_f32_e32 v64, v64, v65
	v_div_scale_f32 v65, s[6:7], v64, v64, 1.0
	v_rcp_f32_e32 v66, v65
	v_mfma_f32_32x32x16_bf16 v[32:47], v[80:83], v[68:71], v[32:47]
	s_barrier
; DI unsigned pk2(float lo, float hi) { typedef float v2f __attribute__((ext_vector_type(2))); typedef __bf16 v2b __attribute__((ext_vector_type(2))); v2f v = {lo, hi}; v2b b = __builtin_convertvector(v, v2b); return __builtin_bit_cast(unsigned, b); }
; DI float xhalf_sum(float m) { auto rr = __builtin_amdgcn_permlane32_swap(__float_as_uint(m), __float_as_uint(m), false, false); return __uint_as_float(rr[0]) + __uint_as_float(rr[1]); }
; template <int DQK, int DV, bool CAUSAL, int KT, bool PRIO>
; DI void attn_unit(const bf16_t* Qb, int qpitch, const bf16_t* Kb, int kpitch, const bf16_t* Vtb, int vpitch, bf16_t* Ob, int opitch, int q0, int nt, LAS unsigned char* lds, float kbound, const float* qgain, const int* qpos, float qscale) {
;     ...
;     lrun = xhalf_sum(lrun);
;     const float inv = 1.0f / lrun;
;     bf16_t* orow = Ob + (size_t)(32 * w + r) * opitch;
; #pragma unroll
;     for (int d = 0; d < DV / 32; ++d)
; #pragma unroll
;         for (int g = 0; g < 4; ++g) { u32x2 wv; wv.x = pk2(o[d][4 * g] * inv, o[d][4 * g + 1] * inv); wv.y = pk2(o[d][4 * g + 2] * inv, o[d][4 * g + 3] * inv);
;             *(u32x2*)(orow + 32 * d + 8 * g + 4 * h) = wv; }
	v_fma_f32 v67, -v65, v66, 1.0
	v_fmac_f32_e32 v66, v67, v66
	v_div_scale_f32 v67, vcc, 1.0, v64, 1.0
	v_mfma_f32_32x32x16_bf16 v[0:15], v[72:75], v[68:71], v[0:15]
	v_mul_f32_e32 v68, v67, v66
	v_fma_f32 v69, -v65, v68, v67
	v_fmac_f32_e32 v68, v69, v66
	v_fma_f32 v65, -v65, v68, v67
	v_div_fmas_f32 v65, v65, v66, v68
	v_div_fixup_f32 v64, v65, v64, 1.0
	v_lshl_add_u64 v[66:67], s[4:5], 0, v[172:173]
	v_pk_mul_f32 v[48:49], v[48:49], v[64:65] op_sel_hi:[1,0]
	v_pk_mul_f32 v[50:51], v[50:51], v[64:65] op_sel_hi:[1,0]
	v_pk_mul_f32 v[32:33], v[32:33], v[64:65] op_sel_hi:[1,0]
	v_pk_mul_f32 v[34:35], v[34:35], v[64:65] op_sel_hi:[1,0]
	v_pk_mul_f32 v[16:17], v[16:17], v[64:65] op_sel_hi:[1,0]
	v_pk_mul_f32 v[18:19], v[18:19], v[64:65] op_sel_hi:[1,0]
	v_pk_mul_f32 v[0:1], v[0:1], v[64:65] op_sel_hi:[1,0]
	v_pk_mul_f32 v[2:3], v[2:3], v[64:65] op_sel_hi:[1,0]
	v_lshl_add_u64 v[66:67], v[66:67], 0, v[174:175]
	v_cvt_pk_bf16_f32 v48, v48, v49
	v_cvt_pk_bf16_f32 v49, v50, v51
	v_cvt_pk_bf16_f32 v32, v32, v33
	v_cvt_pk_bf16_f32 v33, v34, v35
	v_cvt_pk_bf16_f32 v16, v16, v17
	v_cvt_pk_bf16_f32 v17, v18, v19
	v_cvt_pk_bf16_f32 v0, v0, v1
	v_cvt_pk_bf16_f32 v1, v2, v3
	global_store_dwordx2 v[66:67], v[48:49], off
	v_pk_mul_f32 v[48:49], v[52:53], v[64:65] op_sel_hi:[1,0]
	v_pk_mul_f32 v[50:51], v[54:55], v[64:65] op_sel_hi:[1,0]
	global_store_dwordx2 v[66:67], v[32:33], off offset:64
	v_pk_mul_f32 v[32:33], v[36:37], v[64:65] op_sel_hi:[1,0]
	v_pk_mul_f32 v[34:35], v[38:39], v[64:65] op_sel_hi:[1,0]
	global_store_dwordx2 v[66:67], v[16:17], off offset:128
	v_pk_mul_f32 v[16:17], v[20:21], v[64:65] op_sel_hi:[1,0]
	v_pk_mul_f32 v[18:19], v[22:23], v[64:65] op_sel_hi:[1,0]
	global_store_dwordx2 v[66:67], v[0:1], off offset:192
	v_pk_mul_f32 v[0:1], v[4:5], v[64:65] op_sel_hi:[1,0]
	v_pk_mul_f32 v[2:3], v[6:7], v[64:65] op_sel_hi:[1,0]
	v_cvt_pk_bf16_f32 v48, v48, v49
	v_cvt_pk_bf16_f32 v49, v50, v51
	v_cvt_pk_bf16_f32 v32, v32, v33
	v_cvt_pk_bf16_f32 v33, v34, v35
	v_cvt_pk_bf16_f32 v16, v16, v17
	v_cvt_pk_bf16_f32 v17, v18, v19
	v_cvt_pk_bf16_f32 v0, v0, v1
	v_cvt_pk_bf16_f32 v1, v2, v3
	global_store_dwordx2 v[66:67], v[48:49], off offset:16
	v_pk_mul_f32 v[48:49], v[56:57], v[64:65] op_sel_hi:[1,0]
	v_pk_mul_f32 v[50:51], v[58:59], v[64:65] op_sel_hi:[1,0]
	global_store_dwordx2 v[66:67], v[32:33], off offset:80
	v_pk_mul_f32 v[32:33], v[40:41], v[64:65] op_sel_hi:[1,0]
	v_pk_mul_f32 v[34:35], v[42:43], v[64:65] op_sel_hi:[1,0]
	global_store_dwordx2 v[66:67], v[16:17], off offset:144
	v_pk_mul_f32 v[16:17], v[24:25], v[64:65] op_sel_hi:[1,0]
	v_pk_mul_f32 v[18:19], v[26:27], v[64:65] op_sel_hi:[1,0]
	global_store_dwordx2 v[66:67], v[0:1], off offset:208
	v_pk_mul_f32 v[0:1], v[8:9], v[64:65] op_sel_hi:[1,0]
	v_pk_mul_f32 v[2:3], v[10:11], v[64:65] op_sel_hi:[1,0]
	v_cvt_pk_bf16_f32 v48, v48, v49
	v_cvt_pk_bf16_f32 v49, v50, v51
	v_cvt_pk_bf16_f32 v32, v32, v33
	v_cvt_pk_bf16_f32 v33, v34, v35
	v_cvt_pk_bf16_f32 v16, v16, v17
	v_cvt_pk_bf16_f32 v17, v18, v19
	v_cvt_pk_bf16_f32 v0, v0, v1
	v_cvt_pk_bf16_f32 v1, v2, v3
	global_store_dwordx2 v[66:67], v[48:49], off offset:32
	v_pk_mul_f32 v[48:49], v[60:61], v[64:65] op_sel_hi:[1,0]
	v_pk_mul_f32 v[50:51], v[62:63], v[64:65] op_sel_hi:[1,0]
	global_store_dwordx2 v[66:67], v[32:33], off offset:96
	v_pk_mul_f32 v[32:33], v[44:45], v[64:65] op_sel_hi:[1,0]
	v_pk_mul_f32 v[34:35], v[46:47], v[64:65] op_sel_hi:[1,0]
	global_store_dwordx2 v[66:67], v[16:17], off offset:160
	v_pk_mul_f32 v[16:17], v[28:29], v[64:65] op_sel_hi:[1,0]
	v_pk_mul_f32 v[18:19], v[30:31], v[64:65] op_sel_hi:[1,0]
	global_store_dwordx2 v[66:67], v[0:1], off offset:224
	v_pk_mul_f32 v[0:1], v[12:13], v[64:65] op_sel_hi:[1,0]
	v_pk_mul_f32 v[2:3], v[14:15], v[64:65] op_sel_hi:[1,0]
	v_cvt_pk_bf16_f32 v48, v48, v49
	v_cvt_pk_bf16_f32 v49, v50, v51
	v_cvt_pk_bf16_f32 v32, v32, v33
	v_cvt_pk_bf16_f32 v33, v34, v35
	v_cvt_pk_bf16_f32 v16, v16, v17
	v_cvt_pk_bf16_f32 v17, v18, v19
	v_cvt_pk_bf16_f32 v0, v0, v1
	v_cvt_pk_bf16_f32 v1, v2, v3
	global_store_dwordx2 v[66:67], v[48:49], off offset:48
	global_store_dwordx2 v[66:67], v[32:33], off offset:112
	global_store_dwordx2 v[66:67], v[16:17], off offset:176
	global_store_dwordx2 v[66:67], v[0:1], off offset:240
	s_cbranch_scc0 .LBB0_1531
; #define LAS __attribute__((address_space(3)))
; template <int DQK, int DV, bool CAUSAL, int KT, bool PRIO>
; DI void attn_unit(const bf16_t* Qb, int qpitch, const bf16_t* Kb, int kpitch, const bf16_t* Vtb, int vpitch, bf16_t* Ob, int opitch, int q0, int nt, LAS unsigned char* lds, float kbound, const float* qgain, const int* qpos, float qscale) {
;     ...
;     auto gload = [&](int kt) {
; #pragma unroll
;         for (int i = 0; i < NKR; ++i) { const int c = tid + i * 512; if (NKC % 512 == 0 || c < NKC) kreg[i] = *(const u32x4*)(Kb + (size_t)(kt * KT + c / KCH) * kpitch + (c % KCH) * 8); }
; #pragma unroll
;         for (int i = 0; i < NVR; ++i) { const int c = tid + i * 512; vreg[i] = *(const u32x4*)(Vtb + (size_t)(c / VCH) * vpitch + kt * KT + (c % VCH) * 8); }
;     };
;     auto lstore = [&](int buf) {
; #pragma unroll
;         for (int i = 0; i < NKR; ++i) { const int c = tid + i * 512; if (NKC % 512 == 0 || c < NKC) *(LAS u32x4*)(lds + buf * KBUF + (c / KCH) * KS + (c % KCH) * 16) = kreg[i]; }
; #pragma unroll
;         for (int i = 0; i < NVR; ++i) { const int c = tid + i * 512; LAS unsigned char* p = lds + VOFF + buf * VBUF + (c / VCH) * VS + (c % VCH) * 16;
;             *(LAS u32x2*)p = (u32x2){vreg[i].x, vreg[i].y}; *(LAS u32x2*)(p + 8) = (u32x2){vreg[i].z, vreg[i].w}; }
;     };
;     gload(0);
;     bf16x8 qf[DQK / 16];
; #pragma unroll
;     for (int ks = 0; ks < DQK / 16; ++ks) qf[ks] = *(const bf16x8*)(Qb + (size_t)(32 * w + r) * qpitch + 16 * ks + 8 * h);
; __global__ void __launch_bounds__(512, 2) fwd_mega(Args args) {
;     ...
;         for (int p = bx; p < 256; p += G) {
;             const int qb = p & 31, hd = (p >> 5) & 3, b = p >> 7, q0 = qb * 256;
;             attn_unit<128, 128, false, 64, false>(QM + ((size_t)(b * SEQ + q0)) * 512 + hd * 128, 512, KM + (size_t)b * 256 * 512 + hd * 128, 512, VMT + (size_t)(b * 4 + hd) * 128 * 256, 256,
;                                        YC + ((size_t)(b * SEQ + q0)) * 512 + hd * 128, 512, q0, 4, lds, 0.f, args.in[21], nullptr, QSCALE_MEM);
.LBB0_1520:
	s_ashr_i32 s36, s34, 7
	s_and_b32 s4, s18, 0x1f00
	s_lshl_b32 s5, s36, 13
	s_or_b32 s4, s5, s4
	s_ashr_i32 s5, s4, 31
	s_bfe_u32 s35, s34, 0x20005
	s_lshl_b64 s[6:7], s[4:5], 10
	s_add_u32 s6, s10, s6
	s_addc_u32 s7, s11, s7
	s_lshl_b32 s38, s35, 8
	s_add_u32 s8, s6, s38
	s_addc_u32 s9, s7, 0
	s_ashr_i32 s37, s36, 31
	s_lshl_b64 s[6:7], s[36:37], 18
	s_add_u32 s6, s12, s6
	s_addc_u32 s7, s13, s7
	v_mov_b32_e32 v154, v196
	s_add_u32 s6, s6, s38
	s_addc_u32 s7, s7, 0
	v_ashrrev_i32_e32 v8, 31, v154
	s_lshl_b32 s36, s36, 2
	v_lshrrev_b32_e32 v0, 28, v8
	v_lshrrev_b32_e32 v8, 29, v8
	s_or_b32 s36, s36, s35
	v_add_u32_e32 v10, v154, v8
	s_ashr_i32 s37, s36, 31
	v_ashrrev_i32_e32 v138, 3, v10
	s_lshl_b64 s[36:37], s[36:37], 16
	v_ashrrev_i32_e32 v139, 31, v138
	v_and_b32_e32 v10, -8, v10
	s_add_u32 s36, s14, s36
	v_lshlrev_b64 v[8:9], 9, v[138:139]
	v_sub_u32_e32 v139, v154, v10
	s_addc_u32 s37, s15, s37
	v_add_u32_e32 v12, 0x200, v154
	v_lshlrev_b32_e32 v10, 3, v139
	v_ashrrev_i32_e32 v13, 31, v12
	v_lshl_add_u64 v[8:9], s[36:37], 0, v[8:9]
	v_ashrrev_i32_e32 v11, 31, v10
	v_lshl_add_u64 v[176:177], v[10:11], 1, v[8:9]
	v_lshrrev_b32_e32 v8, 29, v13
	v_add_u32_e32 v10, v12, v8
	v_ashrrev_i32_e32 v140, 3, v10
	v_add_u32_e32 v2, v154, v0
	v_ashrrev_i32_e32 v141, 31, v140
	v_readfirstlane_b32 s38, v154
	v_ashrrev_i32_e32 v130, 4, v2
	v_and_b32_e32 v2, -16, v2
	v_lshlrev_b64 v[8:9], 9, v[140:141]
	v_sub_u32_e32 v155, v154, v2
	v_lshrrev_b32_e32 v2, 28, v13
	v_lshl_add_u64 v[8:9], s[36:37], 0, v[8:9]
	s_ashr_i32 s36, s38, 1
	v_add_u32_e32 v4, v12, v2
	v_mov_b32_e32 v16, s36
	v_ashrrev_i32_e32 v134, 4, v4
	v_and_b32_e32 v4, -16, v4
	v_bfi_b32 v16, s20, v16, v154
	v_ashrrev_i32_e32 v131, 31, v130
	v_ashrrev_i32_e32 v135, 31, v134
	v_sub_u32_e32 v156, v12, v4
	v_and_b32_e32 v10, -8, v10
	v_ashrrev_i32_e32 v17, 31, v16
	v_bfe_u32 v50, v154, 5, 1
	s_waitcnt lgkmcnt(0)
	v_lshlrev_b64 v[0:1], 10, v[130:131]
	v_lshlrev_b32_e32 v132, 3, v155
	v_lshlrev_b64 v[2:3], 10, v[134:135]
	v_lshlrev_b32_e32 v136, 3, v156
	v_sub_u32_e32 v141, v12, v10
	v_lshlrev_b64 v[172:173], 10, v[16:17]
	v_lshl_add_u64 v[0:1], s[6:7], 0, v[0:1]
	v_ashrrev_i32_e32 v133, 31, v132
	v_lshl_add_u64 v[2:3], s[6:7], 0, v[2:3]
	v_ashrrev_i32_e32 v137, 31, v136
	v_lshlrev_b32_e32 v10, 3, v141
	v_lshl_add_u64 v[16:17], s[8:9], 0, v[172:173]
	v_lshlrev_b32_e32 v170, 4, v50
	v_lshl_add_u64 v[0:1], v[132:133], 1, v[0:1]
	v_lshl_add_u64 v[2:3], v[136:137], 1, v[2:3]
	v_ashrrev_i32_e32 v11, 31, v10
	v_lshl_add_u64 v[48:49], v[16:17], 0, v[170:171]
	global_load_dwordx4 v[4:7], v[0:1], off
	s_nop 0
	global_load_dwordx4 v[0:3], v[2:3], off
	v_lshl_add_u64 v[178:179], v[10:11], 1, v[8:9]
	global_load_dwordx4 v[12:15], v[176:177], off
	global_load_dwordx4 v[8:11], v[178:179], off
	global_load_dwordx4 v[16:19], v[48:49], off
	global_load_dwordx4 v[20:23], v[48:49], off offset:32
	global_load_dwordx4 v[24:27], v[48:49], off offset:64
	global_load_dwordx4 v[28:31], v[48:49], off offset:96
	global_load_dwordx4 v[32:35], v[48:49], off offset:128
	global_load_dwordx4 v[36:39], v[48:49], off offset:160
	global_load_dwordx4 v[40:43], v[48:49], off offset:192
	global_load_dwordx4 v[44:47], v[48:49], off offset:224
	v_lshlrev_b32_e32 v174, 3, v50
	s_and_b64 vcc, exec, s[2:3]
	s_cbranch_vccz .LBB0_1525
	v_lshlrev_b32_e32 v52, 2, v174
	global_load_dwordx4 v[104:107], v52, s[62:63] offset:16
	global_load_dwordx4 v[108:111], v52, s[62:63]
	global_load_dwordx4 v[96:99], v52, s[62:63] offset:80
	global_load_dwordx4 v[100:103], v52, s[62:63] offset:64
	global_load_dwordx4 v[88:91], v52, s[62:63] offset:144
	global_load_dwordx4 v[92:95], v52, s[62:63] offset:128
	global_load_dwordx4 v[80:83], v52, s[62:63] offset:208
	global_load_dwordx4 v[84:87], v52, s[62:63] offset:192
	global_load_dwordx4 v[72:75], v52, s[62:63] offset:272
	global_load_dwordx4 v[76:79], v52, s[62:63] offset:256
	global_load_dwordx4 v[64:67], v52, s[62:63] offset:336
	global_load_dwordx4 v[68:71], v52, s[62:63] offset:320
	global_load_dwordx4 v[56:59], v52, s[62:63] offset:400
	global_load_dwordx4 v[60:63], v52, s[62:63] offset:384
	global_load_dwordx4 v[48:51], v52, s[62:63] offset:464
	s_nop 0
	global_load_dwordx4 v[52:55], v52, s[62:63] offset:448
	s_waitcnt vmcnt(0) lgkmcnt(0)
; DI float xhalf_sum(float m) { auto rr = __builtin_amdgcn_permlane32_swap(__float_as_uint(m), __float_as_uint(m), false, false); return __uint_as_float(rr[0]) + __uint_as_float(rr[1]); }
; template <int DQK, int DV, bool CAUSAL, int KT, bool PRIO>
; DI void attn_unit(const bf16_t* Qb, int qpitch, const bf16_t* Kb, int kpitch, const bf16_t* Vtb, int vpitch, bf16_t* Ob, int opitch, int q0, int nt, LAS unsigned char* lds, float kbound, const float* qgain, const int* qpos, float qscale) {
;     ...
;         float v[DQK / 16][8]; float q2 = 0.f;
; #pragma unroll
;         for (int ks = 0; ks < DQK / 16; ++ks)
; #pragma unroll
;             for (int e = 0; e < 8; ++e) { v[ks][e] = __uint_as_float(((unsigned)(unsigned short)qf[ks][e]) << 16); q2 += v[ks][e] * v[ks][e]; }
;         q2 = xhalf_sum(q2);
	v_and_b32_e32 v203, 0xffff0000, v16
	v_lshlrev_b32_e32 v202, 16, v16
	v_mul_f32_e32 v204, v203, v203
	v_and_b32_e32 v201, 0xffff0000, v17
	v_lshlrev_b32_e32 v200, 16, v17
	v_pk_fma_f32 v[204:205], v[202:203], v[202:203], v[204:205] op_sel_hi:[1,1,0]
	v_mul_f32_e32 v206, v201, v201
	v_pk_fma_f32 v[204:205], v[200:201], v[200:201], v[204:205]
	v_and_b32_e32 v199, 0xffff0000, v18
	v_lshlrev_b32_e32 v198, 16, v18
	v_pk_add_f32 v[204:205], v[206:207], v[204:205] op_sel_hi:[0,1]
	v_pk_fma_f32 v[204:205], v[198:199], v[198:199], v[204:205]
	v_mul_f32_e32 v206, v199, v199
	v_and_b32_e32 v195, 0xffff0000, v19
	v_lshlrev_b32_e32 v194, 16, v19
	v_pk_add_f32 v[204:205], v[206:207], v[204:205] op_sel_hi:[0,1]
	v_pk_fma_f32 v[204:205], v[194:195], v[194:195], v[204:205]
	v_mul_f32_e32 v206, v195, v195
	v_and_b32_e32 v193, 0xffff0000, v20
	v_lshlrev_b32_e32 v192, 16, v20
	v_pk_add_f32 v[204:205], v[206:207], v[204:205] op_sel_hi:[0,1]
	v_pk_fma_f32 v[204:205], v[192:193], v[192:193], v[204:205]
	v_mul_f32_e32 v206, v193, v193
	v_and_b32_e32 v191, 0xffff0000, v21
	v_lshlrev_b32_e32 v190, 16, v21
	v_pk_add_f32 v[204:205], v[206:207], v[204:205] op_sel_hi:[0,1]
	v_pk_fma_f32 v[204:205], v[190:191], v[190:191], v[204:205]
	v_mul_f32_e32 v206, v191, v191
	v_and_b32_e32 v189, 0xffff0000, v22
	v_lshlrev_b32_e32 v188, 16, v22
	v_pk_add_f32 v[204:205], v[206:207], v[204:205] op_sel_hi:[0,1]
	v_pk_fma_f32 v[204:205], v[188:189], v[188:189], v[204:205]
	v_mul_f32_e32 v206, v189, v189
	v_and_b32_e32 v187, 0xffff0000, v23
	v_lshlrev_b32_e32 v186, 16, v23
	v_pk_add_f32 v[204:205], v[206:207], v[204:205] op_sel_hi:[0,1]
	v_pk_fma_f32 v[204:205], v[186:187], v[186:187], v[204:205]
	v_mul_f32_e32 v206, v187, v187
	v_and_b32_e32 v185, 0xffff0000, v24
	v_lshlrev_b32_e32 v184, 16, v24
	v_pk_add_f32 v[204:205], v[206:207], v[204:205] op_sel_hi:[0,1]
	v_pk_fma_f32 v[204:205], v[184:185], v[184:185], v[204:205]
	v_mul_f32_e32 v206, v185, v185
	v_and_b32_e32 v183, 0xffff0000, v25
	v_lshlrev_b32_e32 v182, 16, v25
	v_pk_add_f32 v[204:205], v[206:207], v[204:205] op_sel_hi:[0,1]
	v_pk_fma_f32 v[204:205], v[182:183], v[182:183], v[204:205]
	v_mul_f32_e32 v206, v183, v183
	v_and_b32_e32 v181, 0xffff0000, v26
	v_lshlrev_b32_e32 v180, 16, v26
	v_pk_add_f32 v[204:205], v[206:207], v[204:205] op_sel_hi:[0,1]
	v_pk_fma_f32 v[204:205], v[180:181], v[180:181], v[204:205]
	v_mul_f32_e32 v206, v181, v181
	v_and_b32_e32 v169, 0xffff0000, v27
	v_lshlrev_b32_e32 v168, 16, v27
	v_pk_add_f32 v[204:205], v[206:207], v[204:205] op_sel_hi:[0,1]
	v_pk_fma_f32 v[204:205], v[168:169], v[168:169], v[204:205]
	v_mul_f32_e32 v206, v169, v169
	v_and_b32_e32 v167, 0xffff0000, v28
	v_lshlrev_b32_e32 v166, 16, v28
	v_pk_add_f32 v[204:205], v[206:207], v[204:205] op_sel_hi:[0,1]
	v_pk_fma_f32 v[204:205], v[166:167], v[166:167], v[204:205]
	v_mul_f32_e32 v206, v167, v167
	v_and_b32_e32 v165, 0xffff0000, v29
	v_lshlrev_b32_e32 v164, 16, v29
	v_pk_add_f32 v[204:205], v[206:207], v[204:205] op_sel_hi:[0,1]
	v_pk_fma_f32 v[204:205], v[164:165], v[164:165], v[204:205]
	v_mul_f32_e32 v206, v165, v165
	v_and_b32_e32 v163, 0xffff0000, v30
	v_lshlrev_b32_e32 v162, 16, v30
	v_pk_add_f32 v[204:205], v[206:207], v[204:205] op_sel_hi:[0,1]
	v_pk_fma_f32 v[204:205], v[162:163], v[162:163], v[204:205]
	v_mul_f32_e32 v206, v163, v163
	v_and_b32_e32 v161, 0xffff0000, v31
	v_lshlrev_b32_e32 v160, 16, v31
	v_pk_add_f32 v[204:205], v[206:207], v[204:205] op_sel_hi:[0,1]
	v_pk_fma_f32 v[204:205], v[160:161], v[160:161], v[204:205]
	v_mul_f32_e32 v206, v161, v161
	v_and_b32_e32 v159, 0xffff0000, v32
	v_lshlrev_b32_e32 v158, 16, v32
	v_pk_add_f32 v[204:205], v[206:207], v[204:205] op_sel_hi:[0,1]
	v_pk_fma_f32 v[204:205], v[158:159], v[158:159], v[204:205]
	v_mul_f32_e32 v206, v159, v159
	v_and_b32_e32 v151, 0xffff0000, v33
	v_lshlrev_b32_e32 v150, 16, v33
	v_pk_add_f32 v[204:205], v[206:207], v[204:205] op_sel_hi:[0,1]
	v_pk_fma_f32 v[204:205], v[150:151], v[150:151], v[204:205]
	v_mul_f32_e32 v206, v151, v151
	v_and_b32_e32 v153, 0xffff0000, v34
	v_lshlrev_b32_e32 v152, 16, v34
	v_pk_add_f32 v[204:205], v[206:207], v[204:205] op_sel_hi:[0,1]
	v_pk_fma_f32 v[204:205], v[152:153], v[152:153], v[204:205]
	v_mul_f32_e32 v206, v153, v153
	v_and_b32_e32 v149, 0xffff0000, v35
	v_lshlrev_b32_e32 v148, 16, v35
	v_pk_add_f32 v[204:205], v[206:207], v[204:205] op_sel_hi:[0,1]
	v_pk_fma_f32 v[204:205], v[148:149], v[148:149], v[204:205]
	v_mul_f32_e32 v206, v149, v149
	v_and_b32_e32 v147, 0xffff0000, v36
	v_lshlrev_b32_e32 v146, 16, v36
	v_pk_add_f32 v[204:205], v[206:207], v[204:205] op_sel_hi:[0,1]
	v_pk_fma_f32 v[204:205], v[146:147], v[146:147], v[204:205]
	v_mul_f32_e32 v206, v147, v147
	v_and_b32_e32 v143, 0xffff0000, v37
	v_lshlrev_b32_e32 v142, 16, v37
	v_pk_add_f32 v[204:205], v[206:207], v[204:205] op_sel_hi:[0,1]
	v_pk_fma_f32 v[204:205], v[142:143], v[142:143], v[204:205]
	v_mul_f32_e32 v206, v143, v143
	v_and_b32_e32 v145, 0xffff0000, v38
	v_lshlrev_b32_e32 v144, 16, v38
	v_pk_add_f32 v[204:205], v[206:207], v[204:205] op_sel_hi:[0,1]
	v_pk_fma_f32 v[204:205], v[144:145], v[144:145], v[204:205]
	v_mul_f32_e32 v206, v145, v145
	v_and_b32_e32 v129, 0xffff0000, v39
	v_lshlrev_b32_e32 v128, 16, v39
	v_pk_add_f32 v[204:205], v[206:207], v[204:205] op_sel_hi:[0,1]
	v_pk_fma_f32 v[204:205], v[128:129], v[128:129], v[204:205]
	v_mul_f32_e32 v206, v129, v129
	v_and_b32_e32 v127, 0xffff0000, v40
	v_lshlrev_b32_e32 v126, 16, v40
	v_pk_add_f32 v[204:205], v[206:207], v[204:205] op_sel_hi:[0,1]
	v_pk_fma_f32 v[204:205], v[126:127], v[126:127], v[204:205]
	v_mul_f32_e32 v206, v127, v127
	v_and_b32_e32 v123, 0xffff0000, v41
; DI unsigned pk2(float lo, float hi) { typedef float v2f __attribute__((ext_vector_type(2))); typedef __bf16 v2b __attribute__((ext_vector_type(2))); v2f v = {lo, hi}; v2b b = __builtin_convertvector(v, v2b); return __builtin_bit_cast(unsigned, b); }
; DI float xhalf_sum(float m) { auto rr = __builtin_amdgcn_permlane32_swap(__float_as_uint(m), __float_as_uint(m), false, false); return __uint_as_float(rr[0]) + __uint_as_float(rr[1]); }
; template <int DQK, int DV, bool CAUSAL, int KT, bool PRIO>
; DI void attn_unit(const bf16_t* Qb, int qpitch, const bf16_t* Kb, int kpitch, const bf16_t* Vtb, int vpitch, bf16_t* Ob, int opitch, int q0, int nt, LAS unsigned char* lds, float kbound, const float* qgain, const int* qpos, float qscale) {
;     ...
;             for (int e = 0; e < 8; ++e) { v[ks][e] = __uint_as_float(((unsigned)(unsigned short)qf[ks][e]) << 16); q2 += v[ks][e] * v[ks][e]; }
;         q2 = xhalf_sum(q2);
;         const float rq = __builtin_amdgcn_rsqf(q2 * (1.0f / (float)DQK) + EPS) * qscale;
; #pragma unroll
;         for (int ks = 0; ks < DQK / 16; ++ks) { const f32x4 g0 = *(const f32x4*)(qgain + 16 * ks + 8 * h), g1 = *(const f32x4*)(qgain + 16 * ks + 8 * h + 4);
; #pragma unroll
;             for (int e = 0; e < 4; ++e) { v[ks][e] *= rq * g0[e]; v[ks][4 + e] *= rq * g1[e]; } }
;         if (DQK == 96 && qpos) {
;         const float pos = (float)qpos[32 * w + r];
; #pragma unroll
;         for (int e = 0; e < 8; ++e) {
;             const float ang = pos * ROPE_INV[8 * h + e]; const double rev = (double)ang * 0.15915494309189535; const float f = (float)(rev - floor(rev));
;             const float c = __builtin_amdgcn_cosf(f), sn_ = __builtin_amdgcn_sinf(f), x1 = v[4][e], x2 = v[5][e];
;             v[4][e] = x1 * c - x2 * sn_; v[5][e] = x2 * c + x1 * sn_; }
;         }
; #pragma unroll
;         for (int ks = 0; ks < DQK / 16; ++ks) { u32x4 pw; pw.x = pk2(v[ks][0], v[ks][1]); pw.y = pk2(v[ks][2], v[ks][3]); pw.z = pk2(v[ks][4], v[ks][5]); pw.w = pk2(v[ks][6], v[ks][7]); qf[ks] = __builtin_bit_cast(bf16x8, pw); }
	v_lshlrev_b32_e32 v122, 16, v41
	v_pk_add_f32 v[204:205], v[206:207], v[204:205] op_sel_hi:[0,1]
	v_pk_fma_f32 v[204:205], v[122:123], v[122:123], v[204:205]
	v_mul_f32_e32 v206, v123, v123
	v_and_b32_e32 v125, 0xffff0000, v42
	v_lshlrev_b32_e32 v124, 16, v42
	v_pk_add_f32 v[204:205], v[206:207], v[204:205] op_sel_hi:[0,1]
	v_pk_fma_f32 v[204:205], v[124:125], v[124:125], v[204:205]
	v_mul_f32_e32 v206, v125, v125
	v_and_b32_e32 v121, 0xffff0000, v43
	v_lshlrev_b32_e32 v120, 16, v43
	v_pk_add_f32 v[204:205], v[206:207], v[204:205] op_sel_hi:[0,1]
	v_pk_fma_f32 v[204:205], v[120:121], v[120:121], v[204:205]
	v_mul_f32_e32 v206, v121, v121
	v_and_b32_e32 v119, 0xffff0000, v44
	v_lshlrev_b32_e32 v118, 16, v44
	v_pk_add_f32 v[204:205], v[206:207], v[204:205] op_sel_hi:[0,1]
	v_pk_fma_f32 v[204:205], v[118:119], v[118:119], v[204:205]
	v_mul_f32_e32 v206, v119, v119
	v_and_b32_e32 v115, 0xffff0000, v45
	v_lshlrev_b32_e32 v114, 16, v45
	v_pk_add_f32 v[204:205], v[206:207], v[204:205] op_sel_hi:[0,1]
	v_pk_fma_f32 v[204:205], v[114:115], v[114:115], v[204:205]
	v_mul_f32_e32 v206, v115, v115
	v_and_b32_e32 v117, 0xffff0000, v46
	v_lshlrev_b32_e32 v116, 16, v46
	v_pk_add_f32 v[204:205], v[206:207], v[204:205] op_sel_hi:[0,1]
	v_pk_fma_f32 v[204:205], v[116:117], v[116:117], v[204:205]
	v_mul_f32_e32 v206, v117, v117
	v_and_b32_e32 v113, 0xffff0000, v47
	v_lshlrev_b32_e32 v112, 16, v47
	v_pk_add_f32 v[204:205], v[206:207], v[204:205] op_sel_hi:[0,1]
	v_pk_fma_f32 v[204:205], v[112:113], v[112:113], v[204:205]
	v_mul_f32_e32 v206, v113, v113
	v_pk_add_f32 v[204:205], v[206:207], v[204:205] op_sel_hi:[0,1]
	v_mov_b32_e32 v157, v204
	s_nop 1
	v_permlane32_swap_b32_e32 v204, v157
	v_add_f32_e32 v157, v204, v157
	v_fmamk_f32 v157, v157, 0x3c000000, v197
	v_rsq_f32_e32 v157, v157
	s_nop 0
	v_mul_f32_e32 v204, 0x3e0293ee, v157
	v_pk_mul_f32 v[108:109], v[108:109], v[204:205] op_sel_hi:[1,0]
	v_pk_mul_f32 v[104:105], v[104:105], v[204:205] op_sel_hi:[1,0]
	v_pk_mul_f32 v[110:111], v[110:111], v[204:205] op_sel_hi:[1,0]
	v_pk_mul_f32 v[106:107], v[106:107], v[204:205] op_sel_hi:[1,0]
	v_pk_mul_f32 v[100:101], v[100:101], v[204:205] op_sel_hi:[1,0]
	v_pk_mul_f32 v[96:97], v[96:97], v[204:205] op_sel_hi:[1,0]
	v_pk_mul_f32 v[102:103], v[102:103], v[204:205] op_sel_hi:[1,0]
	v_pk_mul_f32 v[98:99], v[98:99], v[204:205] op_sel_hi:[1,0]
	v_pk_mul_f32 v[92:93], v[92:93], v[204:205] op_sel_hi:[1,0]
	v_pk_mul_f32 v[88:89], v[204:205], v[88:89] op_sel_hi:[0,1]
	v_pk_mul_f32 v[94:95], v[94:95], v[204:205] op_sel_hi:[1,0]
	v_pk_mul_f32 v[90:91], v[204:205], v[90:91] op_sel_hi:[0,1]
	v_pk_mul_f32 v[84:85], v[204:205], v[84:85] op_sel_hi:[0,1]
	v_pk_mul_f32 v[80:81], v[204:205], v[80:81] op_sel_hi:[0,1]
	v_pk_mul_f32 v[86:87], v[204:205], v[86:87] op_sel_hi:[0,1]
	v_pk_mul_f32 v[82:83], v[204:205], v[82:83] op_sel_hi:[0,1]
	v_pk_mul_f32 v[76:77], v[204:205], v[76:77] op_sel_hi:[0,1]
	v_pk_mul_f32 v[72:73], v[204:205], v[72:73] op_sel_hi:[0,1]
	v_pk_mul_f32 v[78:79], v[204:205], v[78:79] op_sel_hi:[0,1]
	v_pk_mul_f32 v[74:75], v[204:205], v[74:75] op_sel_hi:[0,1]
	v_pk_mul_f32 v[68:69], v[204:205], v[68:69] op_sel_hi:[0,1]
	v_pk_mul_f32 v[64:65], v[204:205], v[64:65] op_sel_hi:[0,1]
	v_pk_mul_f32 v[70:71], v[204:205], v[70:71] op_sel_hi:[0,1]
	v_pk_mul_f32 v[66:67], v[204:205], v[66:67] op_sel_hi:[0,1]
	v_pk_mul_f32 v[60:61], v[204:205], v[60:61] op_sel_hi:[0,1]
	v_pk_mul_f32 v[56:57], v[204:205], v[56:57] op_sel_hi:[0,1]
	v_pk_mul_f32 v[62:63], v[204:205], v[62:63] op_sel_hi:[0,1]
	v_pk_mul_f32 v[58:59], v[204:205], v[58:59] op_sel_hi:[0,1]
	v_pk_mul_f32 v[52:53], v[204:205], v[52:53] op_sel_hi:[0,1]
	v_pk_mul_f32 v[48:49], v[204:205], v[48:49] op_sel_hi:[0,1]
	v_pk_mul_f32 v[54:55], v[204:205], v[54:55] op_sel_hi:[0,1]
	v_pk_mul_f32 v[50:51], v[204:205], v[50:51] op_sel_hi:[0,1]
	v_pk_mul_f32 v[108:109], v[108:109], v[202:203]
	v_pk_mul_f32 v[104:105], v[104:105], v[198:199]
	v_pk_mul_f32 v[198:199], v[110:111], v[200:201]
	v_pk_mul_f32 v[106:107], v[106:107], v[194:195]
	v_pk_mul_f32 v[100:101], v[100:101], v[192:193]
	v_pk_mul_f32 v[96:97], v[96:97], v[188:189]
	v_pk_mul_f32 v[102:103], v[102:103], v[190:191]
	v_pk_mul_f32 v[98:99], v[98:99], v[186:187]
	v_pk_mul_f32 v[92:93], v[92:93], v[184:185]
	v_pk_mul_f32 v[88:89], v[88:89], v[180:181]
	v_pk_mul_f32 v[94:95], v[94:95], v[182:183]
	v_pk_mul_f32 v[90:91], v[90:91], v[168:169]
	v_pk_mul_f32 v[84:85], v[84:85], v[166:167]
	v_pk_mul_f32 v[80:81], v[80:81], v[162:163]
	v_pk_mul_f32 v[86:87], v[86:87], v[164:165]
	v_pk_mul_f32 v[82:83], v[82:83], v[160:161]
	v_pk_mul_f32 v[76:77], v[76:77], v[158:159]
	v_pk_mul_f32 v[72:73], v[72:73], v[152:153]
	v_pk_mul_f32 v[78:79], v[78:79], v[150:151]
	v_pk_mul_f32 v[74:75], v[74:75], v[148:149]
	v_pk_mul_f32 v[68:69], v[68:69], v[146:147]
	v_pk_mul_f32 v[64:65], v[64:65], v[144:145]
	v_pk_mul_f32 v[70:71], v[70:71], v[142:143]
	v_pk_mul_f32 v[66:67], v[66:67], v[128:129]
	v_pk_mul_f32 v[60:61], v[60:61], v[126:127]
	v_pk_mul_f32 v[56:57], v[56:57], v[124:125]
	v_pk_mul_f32 v[62:63], v[62:63], v[122:123]
	v_pk_mul_f32 v[58:59], v[58:59], v[120:121]
	v_pk_mul_f32 v[52:53], v[52:53], v[118:119]
	v_pk_mul_f32 v[48:49], v[48:49], v[116:117]
	v_pk_mul_f32 v[54:55], v[54:55], v[114:115]
	v_pk_mul_f32 v[50:51], v[50:51], v[112:113]
	v_cvt_pk_bf16_f32 v110, v108, v109
	v_cvt_pk_bf16_f32 v111, v198, v199
	v_cvt_pk_bf16_f32 v112, v104, v105
	v_cvt_pk_bf16_f32 v113, v106, v107
	v_cvt_pk_bf16_f32 v122, v100, v101
	v_cvt_pk_bf16_f32 v123, v102, v103
	v_cvt_pk_bf16_f32 v124, v96, v97
	v_cvt_pk_bf16_f32 v125, v98, v99
	v_cvt_pk_bf16_f32 v118, v92, v93
	v_cvt_pk_bf16_f32 v119, v94, v95
	v_cvt_pk_bf16_f32 v120, v88, v89
	v_cvt_pk_bf16_f32 v121, v90, v91
	v_cvt_pk_bf16_f32 v126, v84, v85
	v_cvt_pk_bf16_f32 v127, v86, v87
	v_cvt_pk_bf16_f32 v128, v80, v81
	v_cvt_pk_bf16_f32 v129, v82, v83
	v_cvt_pk_bf16_f32 v114, v76, v77
	v_cvt_pk_bf16_f32 v115, v78, v79
	v_cvt_pk_bf16_f32 v116, v72, v73
	v_cvt_pk_bf16_f32 v117, v74, v75
	v_cvt_pk_bf16_f32 v106, v68, v69
	v_cvt_pk_bf16_f32 v107, v70, v71
	v_cvt_pk_bf16_f32 v108, v64, v65
	v_cvt_pk_bf16_f32 v109, v66, v67
	v_cvt_pk_bf16_f32 v102, v60, v61
	v_cvt_pk_bf16_f32 v103, v62, v63
	v_cvt_pk_bf16_f32 v104, v56, v57
	v_cvt_pk_bf16_f32 v105, v58, v59
	v_cvt_pk_bf16_f32 v98, v52, v53
	v_cvt_pk_bf16_f32 v99, v54, v55
	v_cvt_pk_bf16_f32 v100, v48, v49
	v_cvt_pk_bf16_f32 v101, v50, v51
	s_cbranch_execnz .LBB0_1523

; #define LAS __attribute__((address_space(3)))
; #define MFMA32(a, b, c) __builtin_amdgcn_mfma_f32_32x32x16_bf16((a), (b), (c), 0, 0, 0)
; template <int DQK, int DV, bool CAUSAL, int KT, bool PRIO>
; DI void attn_unit(const bf16_t* Qb, int qpitch, const bf16_t* Kb, int kpitch, const bf16_t* Vtb, int vpitch, bf16_t* Ob, int opitch, int q0, int nt, LAS unsigned char* lds, float kbound, const float* qgain, const int* qpos, float qscale) {
;     ...
;     lstore(0);
;     __syncthreads();
;     const int qabs = q0 + 32 * w + r, qlo = q0 + 32 * w;
;     for (int kt = 0; kt < nt; ++kt) {
;         const int buf = kt & 1;
;         if (kt + 1 < nt) gload(kt + 1);
;     ...
;                     const LAS unsigned char* kb = lds + buf * KBUF + (64 * hf + r) * KS + h * 16;
;                     if (PRIO) __builtin_amdgcn_s_setprio(1);
; #pragma unroll
;                     for (int ks = 0; ks < DQK / 16; ++ks) {
;                         const bf16x8 a0 = *(const LAS bf16x8*)(kb + ks * 32), a1 = *(const LAS bf16x8*)(kb + 32 * KS + ks * 32);
;                         s0 = MFMA32(a0, qf[ks], s0); s1 = MFMA32(a1, qf[ks], s1);
;                     }
;                     if (PRIO) __builtin_amdgcn_s_setprio(0);
;                     if (CAUSAL && key0 + 63 > qlo) {
; #pragma unroll
;                         for (int i = 0; i < 16; ++i) { const int key = key0 + (i & 3) + 8 * (i >> 2) + 4 * h; if (key > qabs) s0[i] = -1e30f; if (key + 32 > qabs) s1[i] = -1e30f; }
;                     }
;                     if (!PRIO) {
; #pragma unroll
;                         for (int i = 0; i < 16; ++i) { s0[i] -= mrun; s1[i] -= mrun; } }
;                     float rm = fmaxf(s0[0], s1[0]);
; #pragma unroll
;                     for (int i = 1; i < 16; ++i) rm = fmaxf(rm, fmaxf(s0[i], s1[i]));
;                     rm = xhalf_max(rm);
;                     if (first || __any(rm > THR)) {
;                         const float dl = first ? rm : fmaxf(rm, 0.f), f = __builtin_amdgcn_exp2f(-dl);
;                         mrun += dl; lrun *= f; first = false;
; #pragma unroll
;                         for (int i = 0; i < 16; ++i) { s0[i] -= dl; s1[i] -= dl; if (PRIO) negm[i] = -mrun; }
; #pragma unroll
;                         for (int d = 0; d < DV / 32; ++d)
; #pragma unroll
;                             for (int i = 0; i < 16; ++i) o[d][i] *= f;
;                     }
.LBB0_1523:
	s_waitcnt vmcnt(0) lgkmcnt(0)
	v_mul_lo_u32 v16, v130, s21
	v_add_u32_e32 v16, 0, v16
	v_lshlrev_b32_e32 v17, 4, v155
	v_add_u32_e32 v198, v16, v17
	ds_write_b128 v198, v[4:7]
	v_mul_lo_u32 v4, v134, s21
	v_add_u32_e32 v4, 0, v4
	v_lshlrev_b32_e32 v5, 4, v156
	v_add_u32_e32 v199, v4, v5
	ds_write_b128 v199, v[0:3]
	v_mul_lo_u32 v0, v138, s22
	v_add_u32_e32 v200, 0, v0
	v_lshlrev_b32_e32 v201, 4, v139
	v_add_u32_e32 v96, v200, v201
	v_add_u32_e32 v0, 0x8800, v96
	ds_write2_b64 v0, v[12:13], v[14:15] offset1:1
	v_mul_lo_u32 v0, v140, s22
	v_and_b32_e32 v32, 31, v154
	v_add_u32_e32 v202, 0, v0
	v_lshlrev_b32_e32 v203, 4, v141
	v_add_u32_e32 v97, v202, v203
	v_mad_u32_u24 v33, v32, s21, 0
	v_add_u32_e32 v0, 0x8800, v97
	v_add_u32_e32 v175, v33, v170
	ds_write2_b64 v0, v[8:9], v[10:11] offset1:1
	s_waitcnt lgkmcnt(0)
	s_barrier
	ds_read_b128 v[0:3], v175
	ds_read_b128 v[16:19], v175 offset:32
	s_waitcnt lgkmcnt(1)
	v_mfma_f32_32x32x16_bf16 v[0:15], v[0:3], v[110:113], 0
	ds_read_b128 v[20:23], v175 offset:8704
	ds_read_b128 v[24:27], v175 offset:8736
	v_lshl_add_u64 v[28:29], v[132:133], 1, s[6:7]
	v_lshl_add_u64 v[30:31], v[136:137], 1, s[6:7]
	s_waitcnt lgkmcnt(2)
	v_mfma_f32_32x32x16_bf16 v[0:15], v[16:19], v[122:125], v[0:15]
	s_waitcnt lgkmcnt(1)
	v_mfma_f32_32x32x16_bf16 v[80:95], v[20:23], v[110:113], 0
	ds_read_b128 v[16:19], v175 offset:64
	ds_read_b128 v[20:23], v175 offset:96
	s_waitcnt lgkmcnt(1)
	v_mfma_f32_32x32x16_bf16 v[0:15], v[16:19], v[118:121], v[0:15]
	v_mfma_f32_32x32x16_bf16 v[80:95], v[24:27], v[122:125], v[80:95]
	ds_read_b128 v[16:19], v175 offset:8768
	ds_read_b128 v[24:27], v175 offset:8800
	s_waitcnt lgkmcnt(2)
	v_mfma_f32_32x32x16_bf16 v[0:15], v[20:23], v[126:129], v[0:15]
	s_waitcnt lgkmcnt(1)
	v_mfma_f32_32x32x16_bf16 v[80:95], v[16:19], v[118:121], v[80:95]
	ds_read_b128 v[16:19], v175 offset:128
	ds_read_b128 v[20:23], v175 offset:160
	s_waitcnt lgkmcnt(1)
	v_mfma_f32_32x32x16_bf16 v[0:15], v[16:19], v[114:117], v[0:15]
	v_mfma_f32_32x32x16_bf16 v[80:95], v[24:27], v[126:129], v[80:95]
	ds_read_b128 v[16:19], v175 offset:8832
	ds_read_b128 v[24:27], v175 offset:8864
	s_waitcnt lgkmcnt(2)
	v_mfma_f32_32x32x16_bf16 v[0:15], v[20:23], v[106:109], v[0:15]
	s_waitcnt lgkmcnt(1)
	v_mfma_f32_32x32x16_bf16 v[80:95], v[16:19], v[114:117], v[80:95]
	ds_read_b128 v[16:19], v175 offset:192
	ds_read_b128 v[20:23], v175 offset:224
	s_waitcnt lgkmcnt(1)
	v_mfma_f32_32x32x16_bf16 v[0:15], v[16:19], v[102:105], v[0:15]
	ds_read_b128 v[16:19], v175 offset:8896
	v_mfma_f32_32x32x16_bf16 v[80:95], v[24:27], v[106:109], v[80:95]
	v_mul_i32_i24_e32 v24, 0xffffff78, v32
	v_add3_u32 v150, v33, v24, v174
	ds_read_b128 v[24:27], v175 offset:8928
	v_lshlrev_b64 v[32:33], 10, v[130:131]
	v_lshl_add_u64 v[180:181], v[28:29], 0, v[32:33]
	v_add_u32_e32 v204, 0x8800, v150
	v_add_u32_e32 v205, 0x9800, v150
	s_waitcnt lgkmcnt(1)
	v_mfma_f32_32x32x16_bf16 v[80:95], v[16:19], v[102:105], v[80:95]
	v_add_co_u32_e32 v16, vcc, s24, v180
	v_lshlrev_b64 v[18:19], 10, v[134:135]
	s_nop 0
	v_addc_co_u32_e32 v17, vcc, 0, v181, vcc
	v_lshl_add_u64 v[182:183], v[30:31], 0, v[18:19]
	v_add_co_u32_e32 v18, vcc, s24, v182
	s_waitcnt lgkmcnt(0)
	v_mfma_f32_32x32x16_bf16 v[80:95], v[24:27], v[98:101], v[80:95]
	v_addc_co_u32_e32 v19, vcc, 0, v183, vcc
	global_load_dwordx4 v[138:141], v[16:17], off
	global_load_dwordx4 v[142:145], v[18:19], off
	global_load_dwordx4 v[134:137], v[176:177], off offset:128
	global_load_dwordx4 v[130:133], v[178:179], off offset:128
	v_add_u32_e32 v206, 0xa800, v150
	v_add_u32_e32 v207, 0xb800, v150
	s_nop 4
	v_max_f32_e32 v16, v81, v81
	v_mfma_f32_32x32x16_bf16 v[0:15], v[20:23], v[98:101], v[0:15]
	s_nop 11
	v_max_f32_e32 v17, v1, v1
	v_max_f32_e32 v16, v17, v16
	v_max_f32_e32 v17, v82, v82
	v_max_f32_e32 v18, v2, v2
	v_max_f32_e32 v17, v18, v17
	v_max_f32_e32 v18, v83, v83
	v_max_f32_e32 v19, v3, v3
	v_max3_f32 v16, v0, v80, v16
	v_max_f32_e32 v18, v19, v18
	v_max3_f32 v16, v16, v17, v18
	v_max_f32_e32 v17, v84, v84
	v_max_f32_e32 v18, v4, v4
	v_max_f32_e32 v17, v18, v17
	v_max_f32_e32 v18, v85, v85
	v_max_f32_e32 v19, v5, v5
	v_max_f32_e32 v18, v19, v18
	v_max3_f32 v16, v16, v17, v18
	v_max_f32_e32 v17, v86, v86
	v_max_f32_e32 v18, v6, v6
	v_max_f32_e32 v17, v18, v17
	v_max_f32_e32 v18, v87, v87
	v_max_f32_e32 v19, v7, v7
	v_max_f32_e32 v18, v19, v18
	v_max3_f32 v16, v16, v17, v18
	v_max_f32_e32 v17, v88, v88
	v_max_f32_e32 v18, v8, v8
	v_max_f32_e32 v17, v18, v17
	v_max_f32_e32 v18, v89, v89
	v_max_f32_e32 v19, v9, v9
	v_max_f32_e32 v18, v19, v18
	v_max3_f32 v16, v16, v17, v18
	v_max_f32_e32 v17, v90, v90
	v_max_f32_e32 v18, v10, v10
	v_max_f32_e32 v17, v18, v17
	v_max_f32_e32 v18, v91, v91
	v_max_f32_e32 v19, v11, v11
	v_max_f32_e32 v18, v19, v18
	v_max3_f32 v16, v16, v17, v18
	v_max_f32_e32 v17, v92, v92
	v_max_f32_e32 v18, v12, v12
	v_max_f32_e32 v17, v18, v17
	v_max_f32_e32 v18, v93, v93
	v_max_f32_e32 v19, v13, v13
	v_max_f32_e32 v18, v19, v18
	v_max3_f32 v16, v16, v17, v18
	v_max_f32_e32 v17, v94, v94
	v_max_f32_e32 v18, v14, v14
	v_max_f32_e32 v17, v18, v17
	v_max_f32_e32 v18, v95, v95
	v_max_f32_e32 v19, v15, v15
	v_max_f32_e32 v18, v19, v18
	v_max3_f32 v16, v16, v17, v18
	v_mov_b32_e32 v17, v16
	s_nop 1
	v_permlane32_swap_b32_e32 v16, v17
	v_max_f32_e32 v17, v17, v17
	v_max_f32_e32 v16, v16, v16
	v_max_f32_e32 v151, v16, v17
	v_sub_f32_e32 v0, v0, v151
	v_sub_f32_e32 v1, v1, v151
	v_sub_f32_e32 v2, v2, v151
	v_sub_f32_e32 v3, v3, v151
	v_exp_f32_e32 v160, v0
	v_exp_f32_e32 v161, v1
	v_exp_f32_e32 v162, v2
	v_exp_f32_e32 v163, v3
	ds_read2_b64 v[0:3], v204 offset1:2
	v_sub_f32_e32 v4, v4, v151
	v_sub_f32_e32 v5, v5, v151
	v_exp_f32_e64 v16, -v151
	v_sub_f32_e32 v6, v6, v151
	v_sub_f32_e32 v7, v7, v151
	v_exp_f32_e32 v164, v4
	v_exp_f32_e32 v165, v5
	v_exp_f32_e32 v166, v6
	v_exp_f32_e32 v167, v7
	v_mul_f32_e32 v64, 0, v16
	v_mov_b32_e32 v65, v64
	v_mov_b32_e32 v66, v64
	v_mov_b32_e32 v67, v64
	v_mov_b32_e32 v68, v64
	v_mov_b32_e32 v69, v64
	v_mov_b32_e32 v70, v64
	v_mov_b32_e32 v71, v64
	v_mov_b32_e32 v72, v64
	v_mov_b32_e32 v73, v64
	v_mov_b32_e32 v74, v64
	v_mov_b32_e32 v75, v64
	v_mov_b32_e32 v76, v64
	v_mov_b32_e32 v77, v64
	v_mov_b32_e32 v78, v64
	v_mov_b32_e32 v79, v64
	v_cvt_pk_bf16_f32 v146, v160, v161
	v_cvt_pk_bf16_f32 v147, v162, v163
	v_cvt_pk_bf16_f32 v148, v164, v165
	v_cvt_pk_bf16_f32 v149, v166, v167
	ds_read2_b64 v[4:7], v205 offset0:32 offset1:34
	v_sub_f32_e32 v8, v8, v151
	s_waitcnt lgkmcnt(0)
; #define LAS __attribute__((address_space(3)))
; template <int DQK, int DV, bool CAUSAL, int KT, bool PRIO>
; DI void attn_unit(const bf16_t* Qb, int qpitch, const bf16_t* Kb, int kpitch, const bf16_t* Vtb, int vpitch, bf16_t* Ob, int opitch, int q0, int nt, LAS unsigned char* lds, float kbound, const float* qgain, const int* qpos, float qscale) {
;     ...
;                     const LAS unsigned char* kb = lds + buf * KBUF + (64 * hf + r) * KS + h * 16;
;                     if (PRIO) __builtin_amdgcn_s_setprio(1);
; #pragma unroll
;                     for (int ks = 0; ks < DQK / 16; ++ks) {
;                         const bf16x8 a0 = *(const LAS bf16x8*)(kb + ks * 32), a1 = *(const LAS bf16x8*)(kb + 32 * KS + ks * 32);
;                         s0 = MFMA32(a0, qf[ks], s0); s1 = MFMA32(a1, qf[ks], s1);
;                     }
;     ...
;                     for (int kb2 = 0; kb2 < 2; ++kb2) {
;                         f32x16& sx = kb2 == 0 ? s0 : s1;
; #pragma unroll
;                         for (int i = 0; i < 16; ++i) { sx[i] = __builtin_amdgcn_exp2f(sx[i]); ps += sx[i]; }
;                         if (PRIO) __builtin_amdgcn_s_setprio(1);
; #pragma unroll
;                         for (int sf = 0; sf < 2; ++sf) {
;                             u32x4 pw; pw.x = pk2(sx[8 * sf], sx[8 * sf + 1]); pw.y = pk2(sx[8 * sf + 2], sx[8 * sf + 3]); pw.z = pk2(sx[8 * sf + 4], sx[8 * sf + 5]); pw.w = pk2(sx[8 * sf + 6], sx[8 * sf + 7]);
;                             const bf16x8 pf = __builtin_bit_cast(bf16x8, pw);
; #pragma unroll
;                             for (int d = 0; d < DV / 32; ++d) {
;                                 const LAS unsigned char* vp = vb + d * 32 * VS + (32 * kb2 + 16 * sf) * 2;
;                                 const s16x4 lo = *(const LAS s16x4*)vp, hi = *(const LAS s16x4*)(vp + 16);
;                                 const bf16x8 a = (bf16x8){lo[0], lo[1], lo[2], lo[3], hi[0], hi[1], hi[2], hi[3]};
;                                 o[d] = MFMA32(a, pf, o[d]);
;                                 if (!PRIO) asm volatile("" ::: "memory");
;                             }
;                         }
;                         if (PRIO) __builtin_amdgcn_s_setprio(0);
;                     }
;                     lrun += ps;
;                 }
;             }
;         }
;         if (kt + 1 < nt) lstore(buf ^ 1);
;         __syncthreads();
	v_mfma_f32_32x32x16_bf16 v[48:63], v[0:3], v[146:149], v[64:79]
	ds_read2_b64 v[0:3], v206 offset0:64 offset1:66
	v_sub_f32_e32 v9, v9, v151
	v_sub_f32_e32 v10, v10, v151
	v_sub_f32_e32 v11, v11, v151
	v_sub_f32_e32 v12, v12, v151
	v_sub_f32_e32 v156, v13, v151
	v_mfma_f32_32x32x16_bf16 v[32:47], v[4:7], v[146:149], v[64:79]
	v_sub_f32_e32 v157, v14, v151
	v_sub_f32_e32 v158, v15, v151
	v_exp_f32_e32 v168, v8
	ds_read2_b64 v[152:155], v207 offset0:96 offset1:98
	v_exp_f32_e32 v169, v9
	v_exp_f32_e32 v170, v10
	v_exp_f32_e32 v184, v11
	s_waitcnt lgkmcnt(0)
	v_mfma_f32_32x32x16_bf16 v[16:31], v[0:3], v[146:149], v[64:79]
	v_exp_f32_e32 v185, v12
	v_mov_b64_e32 v[0:1], v[64:65]
	v_mov_b64_e32 v[2:3], v[66:67]
	v_mov_b64_e32 v[4:5], v[68:69]
	v_mov_b64_e32 v[6:7], v[70:71]
	v_mov_b64_e32 v[8:9], v[72:73]
	v_mov_b64_e32 v[10:11], v[74:75]
	v_mov_b64_e32 v[12:13], v[76:77]
	v_mov_b64_e32 v[14:15], v[78:79]
	ds_read2_b64 v[66:69], v204 offset0:4 offset1:6
	v_exp_f32_e32 v65, v156
	v_exp_f32_e32 v186, v157
	v_exp_f32_e32 v187, v158
	v_cvt_pk_bf16_f32 v70, v168, v169
	v_cvt_pk_bf16_f32 v71, v170, v184
	v_cvt_pk_bf16_f32 v72, v185, v65
	v_cvt_pk_bf16_f32 v73, v186, v187
	v_mfma_f32_32x32x16_bf16 v[0:15], v[152:155], v[146:149], v[0:15]
	v_sub_f32_e32 v78, v80, v151
	v_sub_f32_e32 v79, v84, v151
	v_sub_f32_e32 v80, v85, v151
	v_exp_f32_e32 v188, v78
	v_exp_f32_e32 v192, v79
	v_exp_f32_e32 v193, v80
	v_sub_f32_e32 v78, v88, v151
	s_waitcnt lgkmcnt(0)
	v_mfma_f32_32x32x16_bf16 v[48:63], v[66:69], v[70:73], v[48:63]
	ds_read2_b64 v[66:69], v205 offset0:36 offset1:38
	v_sub_f32_e32 v79, v89, v151
	v_sub_f32_e32 v80, v90, v151
	v_sub_f32_e32 v84, v94, v151
	v_sub_f32_e32 v85, v95, v151
	v_exp_f32_e32 v208, v78
	s_waitcnt lgkmcnt(0)
	v_mfma_f32_32x32x16_bf16 v[32:47], v[66:69], v[70:73], v[32:47]
	ds_read2_b64 v[66:69], v206 offset0:68 offset1:70
	ds_read2_b64 v[74:77], v207 offset0:100 offset1:102
	v_exp_f32_e32 v209, v79
	v_exp_f32_e32 v210, v80
	v_exp_f32_e32 v214, v84
	s_waitcnt lgkmcnt(0)
	v_mfma_f32_32x32x16_bf16 v[16:31], v[66:69], v[70:73], v[16:31]
	v_sub_f32_e32 v66, v81, v151
	v_sub_f32_e32 v67, v82, v151
	v_sub_f32_e32 v68, v83, v151
	v_exp_f32_e32 v189, v66
	v_exp_f32_e32 v190, v67
	v_exp_f32_e32 v191, v68
	ds_read2_b64 v[66:69], v204 offset0:8 offset1:10
	v_sub_f32_e32 v81, v86, v151
	v_sub_f32_e32 v82, v87, v151
	v_exp_f32_e32 v194, v81
	v_exp_f32_e32 v195, v82
	v_mfma_f32_32x32x16_bf16 v[0:15], v[74:77], v[70:73], v[0:15]
	v_cvt_pk_bf16_f32 v70, v188, v189
	v_cvt_pk_bf16_f32 v71, v190, v191
	v_cvt_pk_bf16_f32 v72, v192, v193
	v_cvt_pk_bf16_f32 v73, v194, v195
	v_sub_f32_e32 v81, v91, v151
	v_sub_f32_e32 v82, v92, v151
	s_waitcnt lgkmcnt(0)
	v_mfma_f32_32x32x16_bf16 v[48:63], v[66:69], v[70:73], v[48:63]
	ds_read2_b64 v[66:69], v205 offset0:40 offset1:42
	ds_read2_b64 v[74:77], v206 offset0:72 offset1:74
	v_sub_f32_e32 v83, v93, v151
	v_exp_f32_e32 v211, v81
	v_exp_f32_e32 v212, v82
	s_waitcnt lgkmcnt(0)
	v_mfma_f32_32x32x16_bf16 v[32:47], v[66:69], v[70:73], v[32:47]
	ds_read2_b64 v[66:69], v207 offset0:104 offset1:106
	v_exp_f32_e32 v213, v83
	v_exp_f32_e32 v215, v85
	v_cvt_pk_bf16_f32 v152, v208, v209
	v_cvt_pk_bf16_f32 v153, v210, v211
	v_cvt_pk_bf16_f32 v154, v212, v213
	v_mfma_f32_32x32x16_bf16 v[16:31], v[74:77], v[70:73], v[16:31]
	ds_read2_b64 v[74:77], v204 offset0:12 offset1:14
	v_cvt_pk_bf16_f32 v155, v214, v215
	s_waitcnt lgkmcnt(0)
	v_mfma_f32_32x32x16_bf16 v[0:15], v[66:69], v[70:73], v[0:15]
	ds_read2_b64 v[66:69], v205 offset0:44 offset1:46
	s_waitcnt lgkmcnt(0)
	v_mfma_f32_32x32x16_bf16 v[32:47], v[66:69], v[152:155], v[32:47]
	ds_read2_b64 v[66:69], v206 offset0:76 offset1:78
	ds_read2_b64 v[156:159], v207 offset0:108 offset1:110
	s_waitcnt vmcnt(0)
	ds_write_b128 v198, v[138:141] offset:17408
	ds_write_b128 v199, v[142:145] offset:17408
	s_waitcnt lgkmcnt(3)
	v_mfma_f32_32x32x16_bf16 v[16:31], v[66:69], v[152:155], v[16:31]
	v_add_u32_e32 v66, 0xcc00, v96
	ds_write2_b64 v66, v[134:135], v[136:137] offset1:1
	v_add_u32_e32 v66, 0xcc00, v97
	ds_write2_b64 v66, v[130:131], v[132:133] offset1:1
	s_waitcnt lgkmcnt(0)
	s_barrier
	ds_read_b128 v[66:69], v175 offset:17408
	ds_read_b128 v[130:133], v175 offset:17440
	v_mfma_f32_32x32x16_bf16 v[48:63], v[74:77], v[152:155], v[48:63]
	ds_read_b128 v[82:85], v175 offset:26112
	ds_read_b128 v[134:137], v175 offset:26144
	s_waitcnt lgkmcnt(3)
	v_mfma_f32_32x32x16_bf16 v[66:81], v[66:69], v[110:113], 0
	s_waitcnt lgkmcnt(1)
	v_mfma_f32_32x32x16_bf16 v[82:97], v[82:85], v[110:113], 0
	v_mfma_f32_32x32x16_bf16 v[66:81], v[130:133], v[122:125], v[66:81]
	s_waitcnt lgkmcnt(0)
	v_mfma_f32_32x32x16_bf16 v[82:97], v[134:137], v[122:125], v[82:97]
	ds_read_b128 v[130:133], v175 offset:17472
	ds_read_b128 v[134:137], v175 offset:17504
	s_waitcnt lgkmcnt(1)
	v_mfma_f32_32x32x16_bf16 v[66:81], v[130:133], v[118:121], v[66:81]
	ds_read_b128 v[130:133], v175 offset:26176
	ds_read_b128 v[138:141], v175 offset:26208
	s_waitcnt lgkmcnt(2)
	v_mfma_f32_32x32x16_bf16 v[66:81], v[134:137], v[126:129], v[66:81]
	s_waitcnt lgkmcnt(1)
	v_mfma_f32_32x32x16_bf16 v[82:97], v[130:133], v[118:121], v[82:97]
	ds_read_b128 v[130:133], v175 offset:17536
	ds_read_b128 v[134:137], v175 offset:17568
	ds_read_b128 v[146:149], v175 offset:17600
	s_waitcnt lgkmcnt(2)
	v_mfma_f32_32x32x16_bf16 v[66:81], v[130:133], v[114:117], v[66:81]
	ds_read_b128 v[130:133], v175 offset:26240
	v_mfma_f32_32x32x16_bf16 v[82:97], v[138:141], v[126:129], v[82:97]
	v_add_f32_e32 v138, 0, v160
	v_add_f32_e32 v138, v161, v138
	v_add_f32_e32 v138, v162, v138
	v_add_f32_e32 v138, v163, v138
	v_add_f32_e32 v142, v164, v138
	ds_read_b128 v[138:141], v175 offset:26272
	s_waitcnt lgkmcnt(1)
; #define LAS __attribute__((address_space(3)))
; #define MFMA32(a, b, c) __builtin_amdgcn_mfma_f32_32x32x16_bf16((a), (b), (c), 0, 0, 0)
; DI float xhalf_max(float m) { auto rr = __builtin_amdgcn_permlane32_swap(__float_as_uint(m), __float_as_uint(m), false, false); return __builtin_fmaxf(__uint_as_float(rr[0]), __uint_as_float(rr[1])); }
; template <int DQK, int DV, bool CAUSAL, int KT, bool PRIO>
; DI void attn_unit(const bf16_t* Qb, int qpitch, const bf16_t* Kb, int kpitch, const bf16_t* Vtb, int vpitch, bf16_t* Ob, int opitch, int q0, int nt, LAS unsigned char* lds, float kbound, const float* qgain, const int* qpos, float qscale) {
;     ...
;         if (kt + 1 < nt) gload(kt + 1);
;     ...
;                     for (int ks = 0; ks < DQK / 16; ++ks) {
;                         const bf16x8 a0 = *(const LAS bf16x8*)(kb + ks * 32), a1 = *(const LAS bf16x8*)(kb + 32 * KS + ks * 32);
;                         s0 = MFMA32(a0, qf[ks], s0); s1 = MFMA32(a1, qf[ks], s1);
;                     }
;                     if (PRIO) __builtin_amdgcn_s_setprio(0);
;                     if (CAUSAL && key0 + 63 > qlo) {
; #pragma unroll
;                         for (int i = 0; i < 16; ++i) { const int key = key0 + (i & 3) + 8 * (i >> 2) + 4 * h; if (key > qabs) s0[i] = -1e30f; if (key + 32 > qabs) s1[i] = -1e30f; }
;                     }
;                     if (!PRIO) {
; #pragma unroll
;                         for (int i = 0; i < 16; ++i) { s0[i] -= mrun; s1[i] -= mrun; } }
;                     float rm = fmaxf(s0[0], s1[0]);
; #pragma unroll
;                     for (int i = 1; i < 16; ++i) rm = fmaxf(rm, fmaxf(s0[i], s1[i]));
;                     rm = xhalf_max(rm);
;                     if (first || __any(rm > THR)) {
	v_mfma_f32_32x32x16_bf16 v[82:97], v[130:133], v[114:117], v[82:97]
	v_add_f32_e32 v130, v165, v142
	v_add_f32_e32 v130, v166, v130
	v_add_f32_e32 v130, v167, v130
	v_add_f32_e32 v130, v168, v130
	v_add_f32_e32 v130, v169, v130
	v_add_f32_e32 v130, v170, v130
	v_add_f32_e32 v130, v184, v130
	v_add_f32_e32 v130, v185, v130
	v_add_f32_e32 v65, v65, v130
	v_add_co_u32_e32 v130, vcc, s26, v180
	v_mfma_f32_32x32x16_bf16 v[66:81], v[134:137], v[106:109], v[66:81]
	s_nop 0
	v_addc_co_u32_e32 v131, vcc, 0, v181, vcc
	v_add_co_u32_e32 v132, vcc, s26, v182
	v_add_f32_e32 v65, v186, v65
	s_nop 0
	v_addc_co_u32_e32 v133, vcc, 0, v183, vcc
	s_waitcnt lgkmcnt(0)
	v_mfma_f32_32x32x16_bf16 v[82:97], v[138:141], v[106:109], v[82:97]
	global_load_dwordx4 v[138:141], v[130:131], off
	global_load_dwordx4 v[142:145], v[132:133], off
	global_load_dwordx4 v[134:137], v[176:177], off offset:256
	s_nop 0
	global_load_dwordx4 v[130:133], v[178:179], off offset:256
	ds_read_b128 v[160:163], v175 offset:26304
	ds_read_b128 v[164:167], v175 offset:17632
	v_add_f32_e32 v65, v187, v65
	v_add_f32_e32 v65, v188, v65
	v_add_f32_e32 v65, v189, v65
	v_add_f32_e32 v65, v190, v65
	v_add_f32_e32 v65, v191, v65
	v_mfma_f32_32x32x16_bf16 v[66:81], v[146:149], v[102:105], v[66:81]
	ds_read_b128 v[146:149], v175 offset:26336
	v_add_f32_e32 v65, v192, v65
	v_add_f32_e32 v65, v193, v65
	v_add_f32_e32 v65, v194, v65
	v_add_f32_e32 v65, v195, v65
	v_add_f32_e32 v65, v208, v65
	v_add_f32_e32 v65, v209, v65
	s_waitcnt lgkmcnt(0)
	v_mfma_f32_32x32x16_bf16 v[82:97], v[160:163], v[102:105], v[82:97]
	v_add_f32_e32 v65, v210, v65
	v_add_f32_e32 v65, v211, v65
	v_add_f32_e32 v65, v212, v65
	v_add_f32_e32 v65, v213, v65
	v_add_f32_e32 v65, v214, v65
	v_add_f32_e32 v170, v215, v65
	v_mov_b32_e32 v65, v151
	v_mfma_f32_32x32x16_bf16 v[66:81], v[164:167], v[98:101], v[66:81]
	v_add_f32_e64 v184, v64, v170
	v_add_f32_e64 v185, v65, v171
	v_mfma_f32_32x32x16_bf16 v[82:97], v[146:149], v[98:101], v[82:97]
	s_nop 8
	v_add_f32_e64 v146, v66, -v185
	v_add_f32_e64 v147, v67, -v185
	v_add_f32_e64 v148, v68, -v185
	v_add_f32_e64 v149, v69, -v185
	v_add_f32_e64 v74, v74, -v185
	v_add_f32_e64 v75, v75, -v185
	v_pk_add_f32 v[76:77], v[76:77], v[184:185] op_sel:[0,1] neg_lo:[0,1] neg_hi:[0,1]
	v_mfma_f32_32x32x16_bf16 v[0:15], v[156:159], v[152:155], v[0:15]
	v_add_f32_e64 v82, v82, -v185
	v_add_f32_e64 v83, v83, -v185
	v_add_f32_e64 v68, v84, -v185
	v_add_f32_e64 v69, v85, -v185
	v_add_f32_e64 v84, v70, -v185
	v_add_f32_e64 v85, v71, -v185
	v_pk_add_f32 v[70:71], v[78:79], v[184:185] op_sel:[0,1] neg_lo:[0,1] neg_hi:[0,1]
	v_max_f32_e32 v78, v147, v83
	v_pk_add_f32 v[64:65], v[86:87], v[184:185] op_sel:[0,1] neg_lo:[0,1] neg_hi:[0,1]
	v_pk_add_f32 v[86:87], v[72:73], v[184:185] op_sel:[0,1] neg_lo:[0,1] neg_hi:[0,1]
	v_pk_add_f32 v[72:73], v[80:81], v[184:185] op_sel:[0,1] neg_lo:[0,1] neg_hi:[0,1]
	v_max3_f32 v78, v146, v82, v78
	v_max_f32_e32 v79, v148, v68
	v_max_f32_e32 v80, v149, v69
	v_pk_add_f32 v[66:67], v[88:89], v[184:185] op_sel:[0,1] neg_lo:[0,1] neg_hi:[0,1]
	v_max3_f32 v78, v78, v79, v80
	v_max_f32_e32 v79, v84, v64
	v_max_f32_e32 v80, v85, v65
	v_pk_add_f32 v[186:187], v[90:91], v[184:185] op_sel:[0,1] neg_lo:[0,1] neg_hi:[0,1]
	v_max3_f32 v78, v78, v79, v80
	v_max_f32_e32 v79, v86, v66
	v_max_f32_e32 v80, v87, v67
	v_pk_add_f32 v[188:189], v[92:93], v[184:185] op_sel:[0,1] neg_lo:[0,1] neg_hi:[0,1]
	v_max3_f32 v78, v78, v79, v80
	v_max_f32_e32 v79, v74, v186
	v_max_f32_e32 v80, v75, v187
	v_pk_add_f32 v[190:191], v[94:95], v[184:185] op_sel:[0,1] neg_lo:[0,1] neg_hi:[0,1]
	v_max3_f32 v78, v78, v79, v80
	v_max_f32_e32 v79, v76, v188
	v_max_f32_e32 v80, v77, v189
	v_pk_add_f32 v[192:193], v[96:97], v[184:185] op_sel:[0,1] neg_lo:[0,1] neg_hi:[0,1]
	v_max3_f32 v78, v78, v79, v80
	v_max_f32_e32 v79, v70, v190
	v_max_f32_e32 v80, v71, v191
	v_max3_f32 v78, v78, v79, v80
	v_max_f32_e32 v79, v72, v192
	v_max_f32_e32 v80, v73, v193
	v_max3_f32 v78, v78, v79, v80
	v_mov_b32_e32 v79, v78
	s_nop 1
	v_permlane32_swap_b32_e32 v78, v79
	v_max_f32_e32 v79, v79, v79
	v_max_f32_e32 v78, v78, v78
	v_max_f32_e32 v78, v78, v79
	v_cmp_lt_f32_e32 vcc, s27, v78
	s_cbranch_vccz .LBB0_1526
; template <int DQK, int DV, bool CAUSAL, int KT, bool PRIO>
; DI void attn_unit(const bf16_t* Qb, int qpitch, const bf16_t* Kb, int kpitch, const bf16_t* Vtb, int vpitch, bf16_t* Ob, int opitch, int q0, int nt, LAS unsigned char* lds, float kbound, const float* qgain, const int* qpos, float qscale) {
;     ...
;                     if (first || __any(rm > THR)) {
;                         const float dl = first ? rm : fmaxf(rm, 0.f), f = __builtin_amdgcn_exp2f(-dl);
;                         mrun += dl; lrun *= f; first = false;
; #pragma unroll
;                         for (int i = 0; i < 16; ++i) { s0[i] -= dl; s1[i] -= dl; if (PRIO) negm[i] = -mrun; }
; #pragma unroll
;                         for (int d = 0; d < DV / 32; ++d)
; #pragma unroll
;                             for (int i = 0; i < 16; ++i) o[d][i] *= f;
;                     }
	v_max_f32_e32 v78, v78, v78
	v_max_f32_e32 v80, 0, v78
	v_exp_f32_e64 v78, -v80
	v_add_f32_e32 v194, v185, v80
	v_sub_f32_e32 v146, v146, v80
	v_sub_f32_e32 v147, v147, v80
	v_pk_mul_f32 v[62:63], v[62:63], v[78:79] op_sel_hi:[1,0]
	v_pk_mul_f32 v[60:61], v[60:61], v[78:79] op_sel_hi:[1,0]
	v_pk_mul_f32 v[58:59], v[58:59], v[78:79] op_sel_hi:[1,0]
	v_pk_mul_f32 v[56:57], v[56:57], v[78:79] op_sel_hi:[1,0]
	v_pk_mul_f32 v[54:55], v[54:55], v[78:79] op_sel_hi:[1,0]
	v_pk_mul_f32 v[52:53], v[52:53], v[78:79] op_sel_hi:[1,0]
	v_pk_mul_f32 v[50:51], v[50:51], v[78:79] op_sel_hi:[1,0]
	v_pk_mul_f32 v[48:49], v[48:49], v[78:79] op_sel_hi:[1,0]
	v_pk_mul_f32 v[46:47], v[46:47], v[78:79] op_sel_hi:[1,0]
	v_pk_mul_f32 v[44:45], v[44:45], v[78:79] op_sel_hi:[1,0]
	v_pk_mul_f32 v[42:43], v[42:43], v[78:79] op_sel_hi:[1,0]
	v_pk_mul_f32 v[40:41], v[40:41], v[78:79] op_sel_hi:[1,0]
	v_pk_mul_f32 v[38:39], v[38:39], v[78:79] op_sel_hi:[1,0]
	v_pk_mul_f32 v[36:37], v[36:37], v[78:79] op_sel_hi:[1,0]
	v_pk_mul_f32 v[34:35], v[34:35], v[78:79] op_sel_hi:[1,0]
	v_pk_mul_f32 v[32:33], v[32:33], v[78:79] op_sel_hi:[1,0]
	v_pk_mul_f32 v[30:31], v[30:31], v[78:79] op_sel_hi:[1,0]
	v_pk_mul_f32 v[28:29], v[28:29], v[78:79] op_sel_hi:[1,0]
	v_pk_mul_f32 v[26:27], v[26:27], v[78:79] op_sel_hi:[1,0]
	v_pk_mul_f32 v[24:25], v[24:25], v[78:79] op_sel_hi:[1,0]
	v_pk_mul_f32 v[22:23], v[22:23], v[78:79] op_sel_hi:[1,0]
	v_pk_mul_f32 v[20:21], v[20:21], v[78:79] op_sel_hi:[1,0]
	v_pk_mul_f32 v[18:19], v[18:19], v[78:79] op_sel_hi:[1,0]
	v_pk_mul_f32 v[16:17], v[16:17], v[78:79] op_sel_hi:[1,0]
	v_pk_mul_f32 v[14:15], v[14:15], v[78:79] op_sel_hi:[1,0]
	v_pk_mul_f32 v[12:13], v[12:13], v[78:79] op_sel_hi:[1,0]
	v_pk_mul_f32 v[10:11], v[10:11], v[78:79] op_sel_hi:[1,0]
	v_pk_mul_f32 v[8:9], v[8:9], v[78:79] op_sel_hi:[1,0]
	v_pk_mul_f32 v[6:7], v[6:7], v[78:79] op_sel_hi:[1,0]
	v_pk_mul_f32 v[4:5], v[4:5], v[78:79] op_sel_hi:[1,0]
	v_pk_mul_f32 v[2:3], v[2:3], v[78:79] op_sel_hi:[1,0]
	v_pk_mul_f32 v[0:1], v[0:1], v[78:79] op_sel_hi:[1,0]
	v_pk_mul_f32 v[78:79], v[184:185], v[78:79]
	v_sub_f32_e32 v148, v148, v80
	v_sub_f32_e32 v149, v149, v80
	v_sub_f32_e32 v84, v84, v80
	v_sub_f32_e32 v85, v85, v80
	v_sub_f32_e32 v86, v86, v80
	v_sub_f32_e32 v87, v87, v80
	v_sub_f32_e32 v74, v74, v80
	v_sub_f32_e32 v75, v75, v80
	v_sub_f32_e32 v76, v76, v80
	v_sub_f32_e32 v77, v77, v80
	v_sub_f32_e32 v70, v70, v80
	v_sub_f32_e32 v71, v71, v80
	v_sub_f32_e32 v72, v72, v80
	v_sub_f32_e32 v73, v73, v80
	v_sub_f32_e32 v82, v82, v80
	v_sub_f32_e32 v83, v83, v80
	v_sub_f32_e32 v68, v68, v80
	v_sub_f32_e32 v69, v69, v80
	v_sub_f32_e32 v64, v64, v80
	v_sub_f32_e32 v65, v65, v80
	v_sub_f32_e32 v66, v66, v80
	v_sub_f32_e32 v67, v67, v80
	v_sub_f32_e32 v186, v186, v80
	v_sub_f32_e32 v187, v187, v80
	v_sub_f32_e32 v188, v188, v80
	v_sub_f32_e32 v189, v189, v80
	v_sub_f32_e32 v190, v190, v80
	v_sub_f32_e32 v191, v191, v80
	v_sub_f32_e32 v192, v192, v80
	v_sub_f32_e32 v193, v193, v80
	v_mov_b32_e32 v195, v194
	v_mov_b32_e32 v184, v78
	v_mov_b32_e32 v96, v194
	s_branch .LBB0_1527

; template <int DQK, int DV, bool CAUSAL, int KT, bool PRIO>
; DI void attn_unit(const bf16_t* Qb, int qpitch, const bf16_t* Kb, int kpitch, const bf16_t* Vtb, int vpitch, bf16_t* Ob, int opitch, int q0, int nt, LAS unsigned char* lds, float kbound, const float* qgain, const int* qpos, float qscale) {
;     ...
;                     const LAS unsigned char* kb = lds + buf * KBUF + (64 * hf + r) * KS + h * 16;
;                     if (PRIO) __builtin_amdgcn_s_setprio(1);
; #pragma unroll
;                     for (int ks = 0; ks < DQK / 16; ++ks) {
;                         const bf16x8 a0 = *(const LAS bf16x8*)(kb + ks * 32), a1 = *(const LAS bf16x8*)(kb + 32 * KS + ks * 32);
;     ...
;                     const LAS unsigned char* vb = lds + VOFF + buf * VBUF + r * VS + h * 8 + 128 * hf;
;                     float ps = 0.f;
; #pragma unroll
;                     for (int kb2 = 0; kb2 < 2; ++kb2) {
;                         f32x16& sx = kb2 == 0 ? s0 : s1;
; #pragma unroll
;                         for (int i = 0; i < 16; ++i) { sx[i] = __builtin_amdgcn_exp2f(sx[i]); ps += sx[i]; }
;                         if (PRIO) __builtin_amdgcn_s_setprio(1);
; #pragma unroll
;                         for (int sf = 0; sf < 2; ++sf) {
;                             u32x4 pw; pw.x = pk2(sx[8 * sf], sx[8 * sf + 1]); pw.y = pk2(sx[8 * sf + 2], sx[8 * sf + 3]); pw.z = pk2(sx[8 * sf + 4], sx[8 * sf + 5]); pw.w = pk2(sx[8 * sf + 6], sx[8 * sf + 7]);
;                             const bf16x8 pf = __builtin_bit_cast(bf16x8, pw);
; #pragma unroll
;                             for (int d = 0; d < DV / 32; ++d) {
;                                 const LAS unsigned char* vp = vb + d * 32 * VS + (32 * kb2 + 16 * sf) * 2;
;                                 const s16x4 lo = *(const LAS s16x4*)vp, hi = *(const LAS s16x4*)(vp + 16);
;                                 const bf16x8 a = (bf16x8){lo[0], lo[1], lo[2], lo[3], hi[0], hi[1], hi[2], hi[3]};
;                                 o[d] = MFMA32(a, pf, o[d]);
;                                 if (!PRIO) asm volatile("" ::: "memory");
;                             }
;                         }
;                         if (PRIO) __builtin_amdgcn_s_setprio(0);
;                     }
;                     lrun += ps;
;                 }
;             }
;         }
;         if (kt + 1 < nt) lstore(buf ^ 1);
;         __syncthreads();
.LBB0_1527:
	v_add_u32_e32 v97, 0xc800, v150
	ds_read2_b64 v[78:81], v97 offset0:128 offset1:130
	v_exp_f32_e32 v185, v146
	v_exp_f32_e32 v218, v147
	v_exp_f32_e32 v219, v148
	v_exp_f32_e32 v220, v149
	v_exp_f32_e32 v221, v84
	v_exp_f32_e32 v222, v85
	v_exp_f32_e32 v223, v86
	v_exp_f32_e32 v224, v87
	v_cvt_pk_bf16_f32 v84, v185, v218
	v_cvt_pk_bf16_f32 v85, v219, v220
	v_cvt_pk_bf16_f32 v86, v221, v222
	v_cvt_pk_bf16_f32 v87, v223, v224
	v_add_u32_e32 v170, 0xd800, v150
	v_add_u32_e32 v208, 0xe800, v150
	s_waitcnt lgkmcnt(0)
	v_mfma_f32_32x32x16_bf16 v[48:63], v[78:81], v[84:87], v[48:63]
	ds_read2_b64 v[78:81], v170 offset0:160 offset1:162
	v_add_u32_e32 v209, 0xf800, v150
	v_exp_f32_e32 v225, v74
	v_exp_f32_e32 v226, v75
	v_exp_f32_e32 v227, v76
	v_exp_f32_e32 v228, v77
	s_waitcnt lgkmcnt(0)
	v_mfma_f32_32x32x16_bf16 v[32:47], v[78:81], v[84:87], v[32:47]
	ds_read2_b64 v[78:81], v208 offset0:192 offset1:194
	ds_read2_b64 v[88:91], v209 offset0:224 offset1:226
	ds_read2_b64 v[74:77], v97 offset0:132 offset1:134
	v_exp_f32_e32 v229, v70
	v_exp_f32_e32 v230, v71
	v_exp_f32_e32 v231, v72
	v_exp_f32_e32 v232, v73
	v_cvt_pk_bf16_f32 v70, v225, v226
	v_cvt_pk_bf16_f32 v71, v227, v228
	v_cvt_pk_bf16_f32 v72, v229, v230
	v_cvt_pk_bf16_f32 v73, v231, v232
	s_waitcnt lgkmcnt(0)
	v_mfma_f32_32x32x16_bf16 v[16:31], v[78:81], v[84:87], v[16:31]
	v_exp_f32_e32 v235, v68
	v_exp_f32_e32 v236, v69
	v_exp_f32_e32 v237, v64
	v_add3_u32 v64, v200, v201, s23
	v_exp_f32_e32 v233, v82
	v_exp_f32_e32 v234, v83
	v_exp_f32_e32 v238, v65
	v_mfma_f32_32x32x16_bf16 v[48:63], v[74:77], v[70:73], v[48:63]
	ds_read2_b64 v[74:77], v170 offset0:164 offset1:166
	v_exp_f32_e32 v239, v66
	v_exp_f32_e32 v240, v67
	v_cvt_pk_bf16_f32 v146, v233, v234
	v_cvt_pk_bf16_f32 v147, v235, v236
	v_cvt_pk_bf16_f32 v148, v237, v238
	s_waitcnt lgkmcnt(0)
	v_mfma_f32_32x32x16_bf16 v[32:47], v[74:77], v[70:73], v[32:47]
	ds_read2_b64 v[74:77], v208 offset0:196 offset1:198
	v_cvt_pk_bf16_f32 v149, v239, v240
	v_exp_f32_e32 v190, v190
	v_exp_f32_e32 v191, v191
	v_exp_f32_e32 v192, v192
	v_exp_f32_e32 v193, v193
	s_waitcnt lgkmcnt(0)
	v_mfma_f32_32x32x16_bf16 v[16:31], v[74:77], v[70:73], v[16:31]
	ds_read2_b64 v[74:77], v209 offset0:228 offset1:230
	v_mfma_f32_32x32x16_bf16 v[0:15], v[88:91], v[84:87], v[0:15]
	s_waitcnt lgkmcnt(0)
	v_mfma_f32_32x32x16_bf16 v[0:15], v[74:77], v[70:73], v[0:15]
	ds_read2_b64 v[68:71], v97 offset0:136 offset1:138
	ds_read2_b64 v[210:213], v170 offset0:168 offset1:170
	ds_read2_b64 v[214:217], v208 offset0:200 offset1:202
	ds_read2_b64 v[166:169], v209 offset0:232 offset1:234
	ds_read2_b64 v[162:165], v97 offset0:140 offset1:142
	ds_read2_b64 v[158:161], v170 offset0:172 offset1:174
	ds_read2_b64 v[150:153], v208 offset0:204 offset1:206
	ds_read2_b64 v[154:157], v209 offset0:236 offset1:238
	s_waitcnt vmcnt(0)
	ds_write_b128 v198, v[138:141]
	ds_write_b128 v199, v[142:145]
	ds_write2_b64 v64, v[134:135], v[136:137] offset1:1
	v_add3_u32 v64, v202, v203, s23
	ds_write2_b64 v64, v[130:131], v[132:133] offset1:1
	s_waitcnt lgkmcnt(0)
	s_barrier
	ds_read_b128 v[64:67], v175
	ds_read_b128 v[130:133], v175 offset:32
	v_mfma_f32_32x32x16_bf16 v[48:63], v[68:71], v[146:149], v[48:63]
	ds_read_b128 v[80:83], v175 offset:8704
	ds_read_b128 v[134:137], v175 offset:8736
	s_waitcnt lgkmcnt(3)
	v_mfma_f32_32x32x16_bf16 v[64:79], v[64:67], v[110:113], 0
	s_waitcnt lgkmcnt(1)
	v_mfma_f32_32x32x16_bf16 v[80:95], v[80:83], v[110:113], 0
	v_mfma_f32_32x32x16_bf16 v[64:79], v[130:133], v[122:125], v[64:79]
	s_waitcnt lgkmcnt(0)
	v_mfma_f32_32x32x16_bf16 v[80:95], v[134:137], v[122:125], v[80:95]
	ds_read_b128 v[130:133], v175 offset:64
	ds_read_b128 v[134:137], v175 offset:96
	s_waitcnt lgkmcnt(1)
	v_mfma_f32_32x32x16_bf16 v[64:79], v[130:133], v[118:121], v[64:79]
	ds_read_b128 v[130:133], v175 offset:8768
	ds_read_b128 v[138:141], v175 offset:8800
	s_waitcnt lgkmcnt(1)
	v_mfma_f32_32x32x16_bf16 v[80:95], v[130:133], v[118:121], v[80:95]
	v_add_f32_e32 v130, 0, v185
	v_exp_f32_e32 v185, v186
	v_mfma_f32_32x32x16_bf16 v[64:79], v[134:137], v[126:129], v[64:79]
	v_add_f32_e32 v134, v218, v130
	ds_read_b128 v[130:133], v175 offset:128
	v_add_f32_e32 v134, v219, v134
	v_add_f32_e32 v134, v220, v134
	v_add_f32_e32 v134, v221, v134
	v_add_f32_e32 v134, v222, v134
	v_add_f32_e32 v142, v223, v134
	s_waitcnt lgkmcnt(1)
	v_mfma_f32_32x32x16_bf16 v[80:95], v[138:141], v[126:129], v[80:95]
	ds_read_b128 v[134:137], v175 offset:8832
	ds_read_b128 v[138:141], v175 offset:160
	v_exp_f32_e32 v222, v187
	v_exp_f32_e32 v223, v188
	v_cvt_pk_bf16_f32 v220, v190, v191
	v_cvt_pk_bf16_f32 v221, v192, v193
	v_cvt_pk_bf16_f32 v218, v185, v222
	s_waitcnt lgkmcnt(2)
	v_mfma_f32_32x32x16_bf16 v[64:79], v[130:133], v[114:117], v[64:79]
	v_add_f32_e32 v130, v224, v142
	v_add_f32_e32 v130, v225, v130
	v_add_f32_e32 v130, v226, v130
	v_add_f32_e32 v130, v227, v130
	v_add_f32_e32 v130, v228, v130
	v_add_f32_e32 v142, v229, v130
	ds_read_b128 v[130:133], v175 offset:8864
	s_waitcnt lgkmcnt(2)
	v_mfma_f32_32x32x16_bf16 v[80:95], v[134:137], v[114:117], v[80:95]
	v_add_f32_e32 v134, v230, v142
	v_add_f32_e32 v134, v231, v134
	v_add_f32_e32 v142, v232, v134
	ds_read_b128 v[134:137], v175 offset:192
	v_exp_f32_e32 v224, v189
	s_nop 0
	v_cvt_pk_bf16_f32 v219, v223, v224
	s_waitcnt lgkmcnt(2)
	v_mfma_f32_32x32x16_bf16 v[64:79], v[138:141], v[106:109], v[64:79]
	s_waitcnt lgkmcnt(1)
	v_mfma_f32_32x32x16_bf16 v[80:95], v[130:133], v[106:109], v[80:95]
	v_add_f32_e32 v130, v233, v142
	v_add_f32_e32 v130, v234, v130
	v_add_f32_e32 v225, v235, v130
	ds_read_b128 v[130:133], v175 offset:8896
	ds_read_b128 v[186:189], v175 offset:224
	s_waitcnt lgkmcnt(2)
; #define LAS __attribute__((address_space(3)))
; template <int DQK, int DV, bool CAUSAL, int KT, bool PRIO>
; DI void attn_unit(const bf16_t* Qb, int qpitch, const bf16_t* Kb, int kpitch, const bf16_t* Vtb, int vpitch, bf16_t* Ob, int opitch, int q0, int nt, LAS unsigned char* lds, float kbound, const float* qgain, const int* qpos, float qscale) {
;     ...
;     auto gload = [&](int kt) {
; #pragma unroll
;         for (int i = 0; i < NKR; ++i) { const int c = tid + i * 512; if (NKC % 512 == 0 || c < NKC) kreg[i] = *(const u32x4*)(Kb + (size_t)(kt * KT + c / KCH) * kpitch + (c % KCH) * 8); }
; #pragma unroll
;     ...
;                     const LAS unsigned char* kb = lds + buf * KBUF + (64 * hf + r) * KS + h * 16;
;                     if (PRIO) __builtin_amdgcn_s_setprio(1);
; #pragma unroll
;                     for (int ks = 0; ks < DQK / 16; ++ks) {
;                         const bf16x8 a0 = *(const LAS bf16x8*)(kb + ks * 32), a1 = *(const LAS bf16x8*)(kb + 32 * KS + ks * 32);
;                         s0 = MFMA32(a0, qf[ks], s0); s1 = MFMA32(a1, qf[ks], s1);
;                     }
;                     if (PRIO) __builtin_amdgcn_s_setprio(0);
;                     if (CAUSAL && key0 + 63 > qlo) {
; #pragma unroll
;                         for (int i = 0; i < 16; ++i) { const int key = key0 + (i & 3) + 8 * (i >> 2) + 4 * h; if (key > qabs) s0[i] = -1e30f; if (key + 32 > qabs) s1[i] = -1e30f; }
;                     }
;                     if (!PRIO) {
; #pragma unroll
;                         for (int i = 0; i < 16; ++i) { s0[i] -= mrun; s1[i] -= mrun; } }
;                     float rm = fmaxf(s0[0], s1[0]);
; #pragma unroll
;                     for (int i = 1; i < 16; ++i) rm = fmaxf(rm, fmaxf(s0[i], s1[i]));
;                     rm = xhalf_max(rm);
;                     if (first || __any(rm > THR)) {
;                         const float dl = first ? rm : fmaxf(rm, 0.f), f = __builtin_amdgcn_exp2f(-dl);
;                         mrun += dl; lrun *= f; first = false;
; #pragma unroll
;                         for (int i = 0; i < 16; ++i) { s0[i] -= dl; s1[i] -= dl; if (PRIO) negm[i] = -mrun; }
; #pragma unroll
;                         for (int d = 0; d < DV / 32; ++d)
; #pragma unroll
;                             for (int i = 0; i < 16; ++i) o[d][i] *= f;
;                     }
	v_mfma_f32_32x32x16_bf16 v[64:79], v[134:137], v[102:105], v[64:79]
	v_add_co_u32_e32 v134, vcc, s33, v180
	s_nop 1
	v_addc_co_u32_e32 v135, vcc, 0, v181, vcc
	v_add_co_u32_e32 v136, vcc, s33, v182
	s_waitcnt lgkmcnt(1)
	v_mfma_f32_32x32x16_bf16 v[80:95], v[130:133], v[102:105], v[80:95]
	v_addc_co_u32_e32 v137, vcc, 0, v183, vcc
	ds_read_b128 v[180:183], v175 offset:8928
	global_load_dwordx4 v[138:141], v[134:135], off
	global_load_dwordx4 v[142:145], v[136:137], off
	s_nop 0
	global_load_dwordx4 v[134:137], v[176:177], off offset:384
	global_load_dwordx4 v[130:133], v[178:179], off offset:384
	v_add_f32_e32 v176, v236, v225
	v_add_f32_e32 v176, v237, v176
	v_add_f32_e32 v176, v238, v176
	v_add_f32_e32 v176, v239, v176
	s_waitcnt lgkmcnt(0)
	v_mfma_f32_32x32x16_bf16 v[64:79], v[186:189], v[98:101], v[64:79]
	v_add_f32_e32 v176, v240, v176
	v_add_f32_e32 v176, v185, v176
	v_add_f32_e32 v176, v222, v176
	v_add_f32_e32 v176, v223, v176
	v_add_f32_e32 v176, v224, v176
	v_add_f32_e32 v176, v190, v176
	v_add_f32_e32 v176, v191, v176
	v_mfma_f32_32x32x16_bf16 v[80:95], v[180:183], v[98:101], v[80:95]
	v_add_f32_e32 v176, v192, v176
	v_add_f32_e32 v176, v193, v176
	s_nop 1
	v_add_f32_e64 v186, v64, -v194
	v_add_f32_e64 v187, v65, -v195
	v_add_f32_e32 v190, v184, v176
	v_pk_add_f32 v[188:189], v[66:67], v[194:195] neg_lo:[0,1] neg_hi:[0,1]
	v_pk_add_f32 v[184:185], v[68:69], v[194:195] neg_lo:[0,1] neg_hi:[0,1]
	v_pk_add_f32 v[68:69], v[76:77], v[194:195] neg_lo:[0,1] neg_hi:[0,1]
	v_mfma_f32_32x32x16_bf16 v[32:47], v[210:213], v[146:149], v[32:47]
	s_nop 0
	v_add_f32_e64 v80, v80, -v194
	v_add_f32_e64 v81, v81, -v195
	v_add_f32_e64 v82, v82, -v194
	v_add_f32_e64 v83, v83, -v195
	v_max_f32_e32 v76, v187, v81
	v_pk_add_f32 v[64:65], v[84:85], v[194:195] neg_lo:[0,1] neg_hi:[0,1]
	v_pk_add_f32 v[84:85], v[70:71], v[194:195] neg_lo:[0,1] neg_hi:[0,1]
	v_pk_add_f32 v[70:71], v[78:79], v[194:195] neg_lo:[0,1] neg_hi:[0,1]
	v_max3_f32 v76, v186, v80, v76
	v_mfma_f32_32x32x16_bf16 v[16:31], v[214:217], v[146:149], v[16:31]
	v_max_f32_e32 v77, v188, v82
	v_max_f32_e32 v78, v189, v83
	v_add_f32_e64 v66, v86, -v194
	v_add_f32_e64 v67, v87, -v195
	v_max3_f32 v76, v76, v77, v78
	v_max_f32_e32 v77, v184, v64
	v_max_f32_e32 v78, v185, v65
	v_pk_add_f32 v[72:73], v[72:73], v[194:195] neg_lo:[0,1] neg_hi:[0,1]
	v_mfma_f32_32x32x16_bf16 v[0:15], v[166:169], v[146:149], v[0:15]
	v_add_f32_e64 v176, v88, -v194
	v_add_f32_e64 v177, v89, -v195
	v_max3_f32 v76, v76, v77, v78
	v_max_f32_e32 v77, v84, v66
	v_max_f32_e32 v78, v85, v67
	v_pk_add_f32 v[74:75], v[74:75], v[194:195] neg_lo:[0,1] neg_hi:[0,1]
	v_pk_add_f32 v[178:179], v[90:91], v[194:195] neg_lo:[0,1] neg_hi:[0,1]
	v_max3_f32 v76, v76, v77, v78
	v_max_f32_e32 v77, v72, v176
	v_max_f32_e32 v78, v73, v177
	v_pk_add_f32 v[182:183], v[92:93], v[194:195] neg_lo:[0,1] neg_hi:[0,1]
	v_max3_f32 v76, v76, v77, v78
	v_max_f32_e32 v77, v74, v178
	v_max_f32_e32 v78, v75, v179
	v_pk_add_f32 v[180:181], v[94:95], v[194:195] neg_lo:[0,1] neg_hi:[0,1]
	v_mfma_f32_32x32x16_bf16 v[48:63], v[162:165], v[218:221], v[48:63]
	v_max3_f32 v76, v76, v77, v78
	v_max_f32_e32 v77, v68, v182
	v_max_f32_e32 v78, v69, v183
	v_max3_f32 v76, v76, v77, v78
	v_max_f32_e32 v77, v70, v180
	v_max_f32_e32 v78, v71, v181
	v_max3_f32 v76, v76, v77, v78
	v_mfma_f32_32x32x16_bf16 v[32:47], v[158:161], v[218:221], v[32:47]
	v_mov_b32_e32 v77, v76
	s_nop 1
	v_permlane32_swap_b32_e32 v76, v77
	v_max_f32_e32 v77, v77, v77
	v_max_f32_e32 v76, v76, v76
	v_max_f32_e32 v76, v76, v77
	v_cmp_lt_f32_e32 vcc, s27, v76
	v_mfma_f32_32x32x16_bf16 v[16:31], v[150:153], v[218:221], v[16:31]
	v_mfma_f32_32x32x16_bf16 v[0:15], v[154:157], v[218:221], v[0:15]
	s_cbranch_vccz .LBB0_1529
	v_max_f32_e32 v76, v76, v76
	v_max_f32_e32 v77, 0, v76
	v_exp_f32_e64 v76, -v77
	v_sub_f32_e32 v186, v186, v77
	v_sub_f32_e32 v187, v187, v77
	v_sub_f32_e32 v188, v188, v77
	v_pk_mul_f32 v[62:63], v[62:63], v[76:77] op_sel_hi:[1,0]
	v_pk_mul_f32 v[60:61], v[60:61], v[76:77] op_sel_hi:[1,0]
	v_pk_mul_f32 v[58:59], v[58:59], v[76:77] op_sel_hi:[1,0]
	v_pk_mul_f32 v[56:57], v[56:57], v[76:77] op_sel_hi:[1,0]
	v_pk_mul_f32 v[54:55], v[54:55], v[76:77] op_sel_hi:[1,0]
	v_pk_mul_f32 v[52:53], v[52:53], v[76:77] op_sel_hi:[1,0]
	v_pk_mul_f32 v[50:51], v[50:51], v[76:77] op_sel_hi:[1,0]
	v_pk_mul_f32 v[48:49], v[48:49], v[76:77] op_sel_hi:[1,0]
	v_pk_mul_f32 v[46:47], v[46:47], v[76:77] op_sel_hi:[1,0]
	v_pk_mul_f32 v[44:45], v[44:45], v[76:77] op_sel_hi:[1,0]
	v_pk_mul_f32 v[42:43], v[42:43], v[76:77] op_sel_hi:[1,0]
	v_pk_mul_f32 v[40:41], v[40:41], v[76:77] op_sel_hi:[1,0]
	v_pk_mul_f32 v[38:39], v[38:39], v[76:77] op_sel_hi:[1,0]
	v_pk_mul_f32 v[36:37], v[36:37], v[76:77] op_sel_hi:[1,0]
	v_pk_mul_f32 v[34:35], v[34:35], v[76:77] op_sel_hi:[1,0]
	v_pk_mul_f32 v[32:33], v[32:33], v[76:77] op_sel_hi:[1,0]
	v_pk_mul_f32 v[30:31], v[30:31], v[76:77] op_sel_hi:[1,0]
	v_pk_mul_f32 v[28:29], v[28:29], v[76:77] op_sel_hi:[1,0]
	v_pk_mul_f32 v[26:27], v[26:27], v[76:77] op_sel_hi:[1,0]
	v_pk_mul_f32 v[24:25], v[24:25], v[76:77] op_sel_hi:[1,0]
	v_pk_mul_f32 v[22:23], v[22:23], v[76:77] op_sel_hi:[1,0]
	v_pk_mul_f32 v[20:21], v[20:21], v[76:77] op_sel_hi:[1,0]
	v_pk_mul_f32 v[18:19], v[18:19], v[76:77] op_sel_hi:[1,0]
	v_pk_mul_f32 v[16:17], v[16:17], v[76:77] op_sel_hi:[1,0]
	v_pk_mul_f32 v[14:15], v[14:15], v[76:77] op_sel_hi:[1,0]
	v_pk_mul_f32 v[12:13], v[12:13], v[76:77] op_sel_hi:[1,0]
	v_pk_mul_f32 v[10:11], v[10:11], v[76:77] op_sel_hi:[1,0]
	v_pk_mul_f32 v[8:9], v[8:9], v[76:77] op_sel_hi:[1,0]
	v_pk_mul_f32 v[6:7], v[6:7], v[76:77] op_sel_hi:[1,0]
	v_pk_mul_f32 v[4:5], v[4:5], v[76:77] op_sel_hi:[1,0]
	v_pk_mul_f32 v[2:3], v[2:3], v[76:77] op_sel_hi:[1,0]
	v_pk_mul_f32 v[0:1], v[0:1], v[76:77] op_sel_hi:[1,0]
	v_sub_f32_e32 v189, v189, v77
	v_sub_f32_e32 v184, v184, v77
	v_sub_f32_e32 v185, v185, v77
	v_sub_f32_e32 v84, v84, v77
	v_sub_f32_e32 v85, v85, v77
	v_sub_f32_e32 v72, v72, v77
	v_sub_f32_e32 v73, v73, v77
	v_sub_f32_e32 v74, v74, v77
	v_sub_f32_e32 v75, v75, v77
	v_sub_f32_e32 v68, v68, v77
	v_sub_f32_e32 v69, v69, v77
	v_sub_f32_e32 v70, v70, v77
	v_sub_f32_e32 v71, v71, v77
	v_sub_f32_e32 v80, v80, v77
	v_sub_f32_e32 v81, v81, v77
	v_sub_f32_e32 v82, v82, v77
	v_sub_f32_e32 v83, v83, v77
	v_sub_f32_e32 v64, v64, v77
	v_sub_f32_e32 v65, v65, v77
	v_sub_f32_e32 v66, v66, v77
	v_sub_f32_e32 v67, v67, v77
	v_sub_f32_e32 v176, v176, v77
	v_sub_f32_e32 v177, v177, v77
	v_sub_f32_e32 v178, v178, v77
	v_sub_f32_e32 v179, v179, v77
	v_sub_f32_e32 v182, v182, v77
	v_sub_f32_e32 v183, v183, v77
	v_sub_f32_e32 v180, v180, v77
	v_sub_f32_e32 v181, v181, v77
	v_add_f32_e32 v96, v96, v77
	v_mul_f32_e32 v190, v190, v76

; DI unsigned pk2(float lo, float hi) { typedef float v2f __attribute__((ext_vector_type(2))); typedef __bf16 v2b __attribute__((ext_vector_type(2))); v2f v = {lo, hi}; v2b b = __builtin_convertvector(v, v2b); return __builtin_bit_cast(unsigned, b); }
; DI float sigmoidf_(float v) { return __builtin_amdgcn_rcpf(1.0f + __expf(-v)); }
;     DI void operator()(const f32x4 (&acc)[2][2][4][2], const Unit& u, int wr, int wc, int fr, int fq) const {
;     ...
; #pragma unroll
;         for (int ai = 0; ai < 2; ++ai)
; #pragma unroll
;             for (int m = 0; m < 4; ++m) {
;                 const int row = row0 + ai * 128 + m * 16; const float rs = row_rstd<16>(P, row, 1.0f / 1024.0f);
; #pragma unroll
;                 for (int bj = 0; bj < 2; ++bj) {
;                     float v[8];
; #pragma unroll
;                     for (int n = 0; n < 2; ++n)
; #pragma unroll
;                         for (int i = 0; i < 4; ++i) v[4 * n + i] = sigmoidf_(acc[ai][bj][m][n][i] * rs + bv[bj][n][i]);
;                     u32x4 w; w.x = pk2(v[0], v[1]); w.y = pk2(v[2], v[3]); w.z = pk2(v[4], v[5]); w.w = pk2(v[6], v[7]);
;                     *(u32x4*)(G + (size_t)row * DM + cw + bj * 128) = w;
;                 }
;             }
.LBB0_1602:
	s_lshl_b32 s13, s61, 8
	v_lshl_add_u32 v166, s34, 8, v170
	s_ashr_i32 s12, s61, 2
	s_and_b32 s13, s13, 0x300
	v_ashrrev_i32_e32 v167, 31, v166
	v_or_b32_e32 v152, s13, v172
	s_ashr_i32 s13, s12, 31
	v_lshl_add_u64 v[164:165], v[166:167], 2, s[6:7]
	s_lshl_b64 s[38:39], s[12:13], 25
	s_lshl_b32 s12, s12, 10
	global_load_dword v230, v[164:165], off
	global_load_dword v231, v[164:165], off offset:64
	global_load_dword v232, v[164:165], off offset:128
	global_load_dword v233, v[164:165], off offset:192
	global_load_dword v234, v[164:165], off offset:512
	global_load_dword v235, v[164:165], off offset:576
	global_load_dword v236, v[164:165], off offset:640
	global_load_dword v237, v[164:165], off offset:704
	s_ashr_i32 s13, s12, 31
	s_lshl_b64 s[12:13], s[12:13], 2
	v_readlane_b32 s40, v249, 33
	v_readlane_b32 s41, v249, 34
	s_add_u32 s12, s40, s12
	s_addc_u32 s13, s41, s13
	v_lshlrev_b32_e32 v72, 2, v152
	global_load_dwordx4 v[92:95], v72, s[12:13]
	global_load_dwordx4 v[88:91], v72, s[12:13] offset:16
	global_load_dwordx4 v[84:87], v72, s[12:13] offset:512
	s_nop 0
	global_load_dwordx4 v[72:75], v72, s[12:13] offset:528
	v_lshlrev_b64 v[162:163], 11, v[166:167]
	s_add_u32 s12, s80, s38
	v_lshlrev_b32_e32 v152, 1, v152
	s_addc_u32 s13, s81, s39
	v_readlane_b32 s42, v249, 35
	v_readlane_b32 s43, v249, 36
	v_readlane_b32 s44, v249, 37
	v_readlane_b32 s45, v249, 38
	v_readlane_b32 s46, v249, 39
	v_readlane_b32 s47, v249, 40
	v_readlane_b32 s48, v249, 41
	v_readlane_b32 s49, v249, 42
	v_readlane_b32 s50, v249, 43
	v_readlane_b32 s51, v249, 44
	v_readlane_b32 s52, v249, 45
	v_readlane_b32 s53, v249, 46
	v_readlane_b32 s54, v249, 47
	v_readlane_b32 s55, v249, 48
	s_waitcnt vmcnt(0) lgkmcnt(0)
	v_fmamk_f32 v167, v230, 0x3a800000, v176
	v_rsq_f32_e32 v167, v167
	v_lshl_add_u64 v[168:169], s[12:13], 0, v[152:153]
	v_lshl_add_u64 v[162:163], v[168:169], 0, v[162:163]
	v_fma_f32 v140, v140, v167, v92
	v_fma_f32 v141, v141, v167, v93
	v_fma_f32 v142, v142, v167, v94
	v_fma_f32 v128, v128, v167, v72
	v_fma_f32 v129, v129, v167, v73
	v_mul_f32_e32 v128, 0xbfb8aa3b, v128
	v_fma_f32 v143, v143, v167, v95
	v_fma_f32 v136, v136, v167, v88
	v_fma_f32 v137, v137, v167, v89
	v_fma_f32 v138, v138, v167, v90
	v_fma_f32 v139, v139, v167, v91
	v_mul_f32_e32 v129, 0xbfb8aa3b, v129
	v_exp_f32_e32 v128, v128
	v_mul_f32_e32 v140, 0xbfb8aa3b, v140
	v_mul_f32_e32 v141, 0xbfb8aa3b, v141
	v_mul_f32_e32 v142, 0xbfb8aa3b, v142
	v_mul_f32_e32 v143, 0xbfb8aa3b, v143
	v_mul_f32_e32 v136, 0xbfb8aa3b, v136
	v_mul_f32_e32 v137, 0xbfb8aa3b, v137
	v_mul_f32_e32 v138, 0xbfb8aa3b, v138
	v_mul_f32_e32 v139, 0xbfb8aa3b, v139
	v_exp_f32_e32 v129, v129
	v_exp_f32_e32 v140, v140
	v_exp_f32_e32 v141, v141
	v_exp_f32_e32 v142, v142
	v_exp_f32_e32 v143, v143
	v_exp_f32_e32 v136, v136
	v_exp_f32_e32 v137, v137
	v_exp_f32_e32 v138, v138
	v_exp_f32_e32 v139, v139
	v_fma_f32 v132, v132, v167, v84
	v_fma_f32 v133, v133, v167, v85
	v_fma_f32 v134, v134, v167, v86
	v_fma_f32 v135, v135, v167, v87
	v_add_f32_e32 v128, 1.0, v128
	v_mul_f32_e32 v132, 0xbfb8aa3b, v132
	v_mul_f32_e32 v133, 0xbfb8aa3b, v133
	v_mul_f32_e32 v134, 0xbfb8aa3b, v134
	v_mul_f32_e32 v135, 0xbfb8aa3b, v135
	v_rcp_f32_e32 v180, v128
	v_add_f32_e32 v128, 1.0, v129
	v_fma_f32 v129, v130, v167, v74
	v_exp_f32_e32 v132, v132
	v_exp_f32_e32 v133, v133
	v_exp_f32_e32 v134, v134
	v_exp_f32_e32 v135, v135
	v_add_f32_e32 v140, 1.0, v140
	v_add_f32_e32 v141, 1.0, v141
	v_add_f32_e32 v142, 1.0, v142
	v_add_f32_e32 v143, 1.0, v143
	v_add_f32_e32 v136, 1.0, v136
	v_add_f32_e32 v137, 1.0, v137
	v_add_f32_e32 v138, 1.0, v138
	v_add_f32_e32 v139, 1.0, v139
	v_mul_f32_e32 v129, 0xbfb8aa3b, v129
	v_fma_f32 v130, v131, v167, v75
	v_rcp_f32_e32 v140, v140
	v_rcp_f32_e32 v141, v141
	v_rcp_f32_e32 v142, v142
	v_rcp_f32_e32 v143, v143
	v_rcp_f32_e32 v136, v136
	v_rcp_f32_e32 v137, v137
	v_rcp_f32_e32 v138, v138
	v_rcp_f32_e32 v139, v139
	v_exp_f32_e32 v129, v129
	v_mul_f32_e32 v130, 0xbfb8aa3b, v130
	v_exp_f32_e32 v130, v130
	v_add_f32_e32 v132, 1.0, v132
	v_add_f32_e32 v133, 1.0, v133
	v_add_f32_e32 v134, 1.0, v134
	v_add_f32_e32 v135, 1.0, v135
	v_rcp_f32_e32 v152, v132
	v_rcp_f32_e32 v177, v133
	v_rcp_f32_e32 v178, v134
	v_rcp_f32_e32 v179, v135
	v_cvt_pk_bf16_f32 v132, v140, v141
	v_cvt_pk_bf16_f32 v133, v142, v143
	v_cvt_pk_bf16_f32 v134, v136, v137
	v_cvt_pk_bf16_f32 v135, v138, v139
	v_rcp_f32_e32 v131, v128
	v_add_f32_e32 v128, 1.0, v129
	global_store_dwordx4 v[162:163], v[132:135], off
	v_cvt_pk_bf16_f32 v129, v178, v179
	s_nop 0
	v_rcp_f32_e32 v132, v128
	v_add_f32_e32 v128, 1.0, v130
	v_rcp_f32_e32 v133, v128
	v_cvt_pk_bf16_f32 v128, v152, v177
	v_cvt_pk_bf16_f32 v130, v180, v131
	v_cvt_pk_bf16_f32 v131, v132, v133
	global_store_dwordx4 v[162:163], v[128:131], off offset:256
	s_nop 1
	v_or_b32_e32 v128, 16, v166
	v_ashrrev_i32_e32 v129, 31, v128
	v_lshl_add_u64 v[130:131], v[128:129], 2, s[6:7]
	s_nop 0
	v_lshlrev_b64 v[128:129], 11, v[128:129]
	v_lshl_add_u64 v[128:129], v[168:169], 0, v[128:129]
	v_fmamk_f32 v130, v231, 0x3a800000, v176
	v_rsq_f32_e32 v130, v130
	s_nop 0
	v_fma_f32 v112, v112, v130, v72
	v_fma_f32 v113, v113, v130, v73
	v_mul_f32_e32 v112, 0xbfb8aa3b, v112
	v_fma_f32 v124, v124, v130, v92
	v_fma_f32 v125, v125, v130, v93
	v_fma_f32 v126, v126, v130, v94
	v_fma_f32 v127, v127, v130, v95
	v_fma_f32 v120, v120, v130, v88
	v_fma_f32 v121, v121, v130, v89
	v_fma_f32 v122, v122, v130, v90
	v_fma_f32 v123, v123, v130, v91
	v_mul_f32_e32 v113, 0xbfb8aa3b, v113
	v_exp_f32_e32 v112, v112
	v_mul_f32_e32 v124, 0xbfb8aa3b, v124
	v_mul_f32_e32 v125, 0xbfb8aa3b, v125
	v_mul_f32_e32 v126, 0xbfb8aa3b, v126
; DI unsigned pk2(float lo, float hi) { typedef float v2f __attribute__((ext_vector_type(2))); typedef __bf16 v2b __attribute__((ext_vector_type(2))); v2f v = {lo, hi}; v2b b = __builtin_convertvector(v, v2b); return __builtin_bit_cast(unsigned, b); }
; DI float sigmoidf_(float v) { return __builtin_amdgcn_rcpf(1.0f + __expf(-v)); }
;     DI void operator()(const f32x4 (&acc)[2][2][4][2], const Unit& u, int wr, int wc, int fr, int fq) const {
;     ...
;             for (int m = 0; m < 4; ++m) {
;                 const int row = row0 + ai * 128 + m * 16; const float rs = row_rstd<16>(P, row, 1.0f / 1024.0f);
; #pragma unroll
;                 for (int bj = 0; bj < 2; ++bj) {
;                     float v[8];
; #pragma unroll
;                     for (int n = 0; n < 2; ++n)
; #pragma unroll
;                         for (int i = 0; i < 4; ++i) v[4 * n + i] = sigmoidf_(acc[ai][bj][m][n][i] * rs + bv[bj][n][i]);
;                     u32x4 w; w.x = pk2(v[0], v[1]); w.y = pk2(v[2], v[3]); w.z = pk2(v[4], v[5]); w.w = pk2(v[6], v[7]);
;                     *(u32x4*)(G + (size_t)row * DM + cw + bj * 128) = w;
;                 }
;             }
	v_mul_f32_e32 v127, 0xbfb8aa3b, v127
	v_mul_f32_e32 v120, 0xbfb8aa3b, v120
	v_mul_f32_e32 v121, 0xbfb8aa3b, v121
	v_mul_f32_e32 v122, 0xbfb8aa3b, v122
	v_mul_f32_e32 v123, 0xbfb8aa3b, v123
	v_exp_f32_e32 v113, v113
	v_exp_f32_e32 v124, v124
	v_exp_f32_e32 v125, v125
	v_exp_f32_e32 v126, v126
	v_exp_f32_e32 v127, v127
	v_exp_f32_e32 v120, v120
	v_exp_f32_e32 v121, v121
	v_exp_f32_e32 v122, v122
	v_exp_f32_e32 v123, v123
	v_fma_f32 v116, v116, v130, v84
	v_fma_f32 v117, v117, v130, v85
	v_fma_f32 v118, v118, v130, v86
	v_fma_f32 v119, v119, v130, v87
	v_add_f32_e32 v112, 1.0, v112
	v_mul_f32_e32 v116, 0xbfb8aa3b, v116
	v_mul_f32_e32 v117, 0xbfb8aa3b, v117
	v_mul_f32_e32 v118, 0xbfb8aa3b, v118
	v_mul_f32_e32 v119, 0xbfb8aa3b, v119
	v_rcp_f32_e32 v135, v112
	v_add_f32_e32 v112, 1.0, v113
	v_fma_f32 v113, v114, v130, v74
	v_exp_f32_e32 v116, v116
	v_exp_f32_e32 v117, v117
	v_exp_f32_e32 v118, v118
	v_exp_f32_e32 v119, v119
	v_add_f32_e32 v124, 1.0, v124
	v_add_f32_e32 v125, 1.0, v125
	v_add_f32_e32 v126, 1.0, v126
	v_add_f32_e32 v127, 1.0, v127
	v_add_f32_e32 v120, 1.0, v120
	v_add_f32_e32 v121, 1.0, v121
	v_add_f32_e32 v122, 1.0, v122
	v_add_f32_e32 v123, 1.0, v123
	v_mul_f32_e32 v113, 0xbfb8aa3b, v113
	v_fma_f32 v114, v115, v130, v75
	v_rcp_f32_e32 v124, v124
	v_rcp_f32_e32 v125, v125
	v_rcp_f32_e32 v126, v126
	v_rcp_f32_e32 v127, v127
	v_rcp_f32_e32 v120, v120
	v_rcp_f32_e32 v121, v121
	v_rcp_f32_e32 v122, v122
	v_rcp_f32_e32 v123, v123
	v_exp_f32_e32 v113, v113
	v_mul_f32_e32 v114, 0xbfb8aa3b, v114
	v_exp_f32_e32 v114, v114
	v_add_f32_e32 v116, 1.0, v116
	v_add_f32_e32 v117, 1.0, v117
	v_add_f32_e32 v118, 1.0, v118
	v_add_f32_e32 v119, 1.0, v119
	v_rcp_f32_e32 v131, v116
	v_rcp_f32_e32 v132, v117
	v_rcp_f32_e32 v133, v118
	v_rcp_f32_e32 v134, v119
	v_cvt_pk_bf16_f32 v116, v124, v125
	v_cvt_pk_bf16_f32 v117, v126, v127
	v_cvt_pk_bf16_f32 v118, v120, v121
	v_cvt_pk_bf16_f32 v119, v122, v123
	v_rcp_f32_e32 v115, v112
	v_add_f32_e32 v112, 1.0, v113
	global_store_dwordx4 v[128:129], v[116:119], off
	v_cvt_pk_bf16_f32 v113, v133, v134
	s_nop 0
	v_rcp_f32_e32 v116, v112
	v_add_f32_e32 v112, 1.0, v114
	v_rcp_f32_e32 v117, v112
	v_cvt_pk_bf16_f32 v112, v131, v132
	v_cvt_pk_bf16_f32 v114, v135, v115
	v_cvt_pk_bf16_f32 v115, v116, v117
	global_store_dwordx4 v[128:129], v[112:115], off offset:256
	s_nop 1
	v_or_b32_e32 v112, 32, v166
	v_ashrrev_i32_e32 v113, 31, v112
	v_lshl_add_u64 v[114:115], v[112:113], 2, s[6:7]
	s_nop 0
	v_lshlrev_b64 v[112:113], 11, v[112:113]
	v_lshl_add_u64 v[112:113], v[168:169], 0, v[112:113]
	v_fmamk_f32 v114, v232, 0x3a800000, v176
	v_rsq_f32_e32 v114, v114
	s_nop 0
	v_fma_f32 v96, v96, v114, v72
	v_fma_f32 v97, v97, v114, v73
	v_mul_f32_e32 v96, 0xbfb8aa3b, v96
	v_fma_f32 v108, v108, v114, v92
	v_fma_f32 v109, v109, v114, v93
	v_fma_f32 v110, v110, v114, v94
	v_fma_f32 v111, v111, v114, v95
	v_fma_f32 v104, v104, v114, v88
	v_fma_f32 v105, v105, v114, v89
	v_fma_f32 v106, v106, v114, v90
	v_fma_f32 v107, v107, v114, v91
	v_mul_f32_e32 v97, 0xbfb8aa3b, v97
	v_exp_f32_e32 v96, v96
	v_mul_f32_e32 v108, 0xbfb8aa3b, v108
	v_mul_f32_e32 v109, 0xbfb8aa3b, v109
	v_mul_f32_e32 v110, 0xbfb8aa3b, v110
	v_mul_f32_e32 v111, 0xbfb8aa3b, v111
	v_mul_f32_e32 v104, 0xbfb8aa3b, v104
	v_mul_f32_e32 v105, 0xbfb8aa3b, v105
	v_mul_f32_e32 v106, 0xbfb8aa3b, v106
	v_mul_f32_e32 v107, 0xbfb8aa3b, v107
	v_exp_f32_e32 v97, v97
	v_exp_f32_e32 v108, v108
	v_exp_f32_e32 v109, v109
	v_exp_f32_e32 v110, v110
	v_exp_f32_e32 v111, v111
	v_exp_f32_e32 v104, v104
	v_exp_f32_e32 v105, v105
	v_exp_f32_e32 v106, v106
	v_exp_f32_e32 v107, v107
	v_fma_f32 v100, v100, v114, v84
	v_fma_f32 v101, v101, v114, v85
	v_fma_f32 v102, v102, v114, v86
	v_fma_f32 v103, v103, v114, v87
	v_add_f32_e32 v96, 1.0, v96
	v_mul_f32_e32 v100, 0xbfb8aa3b, v100
	v_mul_f32_e32 v101, 0xbfb8aa3b, v101
	v_mul_f32_e32 v102, 0xbfb8aa3b, v102
	v_mul_f32_e32 v103, 0xbfb8aa3b, v103
	v_rcp_f32_e32 v119, v96
	v_add_f32_e32 v96, 1.0, v97
	v_fma_f32 v97, v98, v114, v74
	v_exp_f32_e32 v100, v100
	v_exp_f32_e32 v101, v101
	v_exp_f32_e32 v102, v102
	v_exp_f32_e32 v103, v103
	v_add_f32_e32 v108, 1.0, v108
	v_add_f32_e32 v109, 1.0, v109
	v_add_f32_e32 v110, 1.0, v110
	v_add_f32_e32 v111, 1.0, v111
	v_add_f32_e32 v104, 1.0, v104
	v_add_f32_e32 v105, 1.0, v105
	v_add_f32_e32 v106, 1.0, v106
	v_add_f32_e32 v107, 1.0, v107
	v_mul_f32_e32 v97, 0xbfb8aa3b, v97
	v_fma_f32 v98, v99, v114, v75
	v_rcp_f32_e32 v108, v108
	v_rcp_f32_e32 v109, v109
	v_rcp_f32_e32 v110, v110
	v_rcp_f32_e32 v111, v111
	v_rcp_f32_e32 v104, v104
	v_rcp_f32_e32 v105, v105
	v_rcp_f32_e32 v106, v106
	v_rcp_f32_e32 v107, v107
	v_exp_f32_e32 v97, v97
	v_mul_f32_e32 v98, 0xbfb8aa3b, v98
	v_exp_f32_e32 v98, v98
	v_add_f32_e32 v100, 1.0, v100
	v_add_f32_e32 v101, 1.0, v101
	v_add_f32_e32 v102, 1.0, v102
	v_add_f32_e32 v103, 1.0, v103
	v_rcp_f32_e32 v115, v100
	v_rcp_f32_e32 v116, v101
	v_rcp_f32_e32 v117, v102
	v_rcp_f32_e32 v118, v103
	v_cvt_pk_bf16_f32 v100, v108, v109
	v_cvt_pk_bf16_f32 v101, v110, v111
	v_cvt_pk_bf16_f32 v102, v104, v105
	v_cvt_pk_bf16_f32 v103, v106, v107
	v_rcp_f32_e32 v99, v96
	v_add_f32_e32 v96, 1.0, v97
	global_store_dwordx4 v[112:113], v[100:103], off
	v_cvt_pk_bf16_f32 v97, v117, v118
	s_nop 0
	v_rcp_f32_e32 v100, v96
	v_add_f32_e32 v96, 1.0, v98
	v_rcp_f32_e32 v101, v96
	v_cvt_pk_bf16_f32 v96, v115, v116
	v_cvt_pk_bf16_f32 v98, v119, v99
	v_cvt_pk_bf16_f32 v99, v100, v101
	global_store_dwordx4 v[112:113], v[96:99], off offset:256
	s_nop 1
	v_or_b32_e32 v96, 48, v166
	v_ashrrev_i32_e32 v97, 31, v96
	v_lshl_add_u64 v[98:99], v[96:97], 2, s[6:7]
	s_nop 0
	v_lshlrev_b64 v[96:97], 11, v[96:97]
; DI unsigned pk2(float lo, float hi) { typedef float v2f __attribute__((ext_vector_type(2))); typedef __bf16 v2b __attribute__((ext_vector_type(2))); v2f v = {lo, hi}; v2b b = __builtin_convertvector(v, v2b); return __builtin_bit_cast(unsigned, b); }
; DI float sigmoidf_(float v) { return __builtin_amdgcn_rcpf(1.0f + __expf(-v)); }
;     DI void operator()(const f32x4 (&acc)[2][2][4][2], const Unit& u, int wr, int wc, int fr, int fq) const {
;     ...
;             for (int m = 0; m < 4; ++m) {
;                 const int row = row0 + ai * 128 + m * 16; const float rs = row_rstd<16>(P, row, 1.0f / 1024.0f);
; #pragma unroll
;                 for (int bj = 0; bj < 2; ++bj) {
;                     float v[8];
; #pragma unroll
;                     for (int n = 0; n < 2; ++n)
; #pragma unroll
;                         for (int i = 0; i < 4; ++i) v[4 * n + i] = sigmoidf_(acc[ai][bj][m][n][i] * rs + bv[bj][n][i]);
;                     u32x4 w; w.x = pk2(v[0], v[1]); w.y = pk2(v[2], v[3]); w.z = pk2(v[4], v[5]); w.w = pk2(v[6], v[7]);
;                     *(u32x4*)(G + (size_t)row * DM + cw + bj * 128) = w;
;                 }
;             }
	v_lshl_add_u64 v[96:97], v[168:169], 0, v[96:97]
	v_fmamk_f32 v98, v233, 0x3a800000, v176
	v_rsq_f32_e32 v98, v98
	s_nop 0
	v_fma_f32 v64, v64, v98, v72
	v_fma_f32 v65, v65, v98, v73
	v_mul_f32_e32 v64, 0xbfb8aa3b, v64
	v_fma_f32 v80, v80, v98, v92
	v_fma_f32 v81, v81, v98, v93
	v_fma_f32 v82, v82, v98, v94
	v_fma_f32 v83, v83, v98, v95
	v_fma_f32 v76, v76, v98, v88
	v_fma_f32 v77, v77, v98, v89
	v_fma_f32 v78, v78, v98, v90
	v_fma_f32 v79, v79, v98, v91
	v_mul_f32_e32 v65, 0xbfb8aa3b, v65
	v_exp_f32_e32 v64, v64
	v_mul_f32_e32 v80, 0xbfb8aa3b, v80
	v_mul_f32_e32 v81, 0xbfb8aa3b, v81
	v_mul_f32_e32 v82, 0xbfb8aa3b, v82
	v_mul_f32_e32 v83, 0xbfb8aa3b, v83
	v_mul_f32_e32 v76, 0xbfb8aa3b, v76
	v_mul_f32_e32 v77, 0xbfb8aa3b, v77
	v_mul_f32_e32 v78, 0xbfb8aa3b, v78
	v_mul_f32_e32 v79, 0xbfb8aa3b, v79
	v_exp_f32_e32 v65, v65
	v_exp_f32_e32 v80, v80
	v_exp_f32_e32 v81, v81
	v_exp_f32_e32 v82, v82
	v_exp_f32_e32 v83, v83
	v_exp_f32_e32 v76, v76
	v_exp_f32_e32 v77, v77
	v_exp_f32_e32 v78, v78
	v_exp_f32_e32 v79, v79
	v_fma_f32 v68, v68, v98, v84
	v_fma_f32 v69, v69, v98, v85
	v_fma_f32 v70, v70, v98, v86
	v_fma_f32 v71, v71, v98, v87
	v_add_f32_e32 v64, 1.0, v64
	v_mul_f32_e32 v68, 0xbfb8aa3b, v68
	v_mul_f32_e32 v69, 0xbfb8aa3b, v69
	v_mul_f32_e32 v70, 0xbfb8aa3b, v70
	v_mul_f32_e32 v71, 0xbfb8aa3b, v71
	v_rcp_f32_e32 v103, v64
	v_add_f32_e32 v64, 1.0, v65
	v_fma_f32 v65, v66, v98, v74
	v_exp_f32_e32 v68, v68
	v_exp_f32_e32 v69, v69
	v_exp_f32_e32 v70, v70
	v_exp_f32_e32 v71, v71
	v_add_f32_e32 v80, 1.0, v80
	v_add_f32_e32 v81, 1.0, v81
	v_add_f32_e32 v82, 1.0, v82
	v_add_f32_e32 v83, 1.0, v83
	v_add_f32_e32 v76, 1.0, v76
	v_add_f32_e32 v77, 1.0, v77
	v_add_f32_e32 v78, 1.0, v78
	v_add_f32_e32 v79, 1.0, v79
	v_mul_f32_e32 v65, 0xbfb8aa3b, v65
	v_fma_f32 v66, v67, v98, v75
	v_rcp_f32_e32 v80, v80
	v_rcp_f32_e32 v81, v81
	v_rcp_f32_e32 v82, v82
	v_rcp_f32_e32 v83, v83
	v_rcp_f32_e32 v76, v76
	v_rcp_f32_e32 v77, v77
	v_rcp_f32_e32 v78, v78
	v_rcp_f32_e32 v79, v79
	v_exp_f32_e32 v65, v65
	v_mul_f32_e32 v66, 0xbfb8aa3b, v66
	v_exp_f32_e32 v66, v66
	v_add_f32_e32 v68, 1.0, v68
	v_add_f32_e32 v69, 1.0, v69
	v_add_f32_e32 v70, 1.0, v70
	v_add_f32_e32 v71, 1.0, v71
	v_rcp_f32_e32 v99, v68
	v_rcp_f32_e32 v100, v69
	v_rcp_f32_e32 v101, v70
	v_rcp_f32_e32 v102, v71
	v_cvt_pk_bf16_f32 v68, v80, v81
	v_cvt_pk_bf16_f32 v69, v82, v83
	v_cvt_pk_bf16_f32 v70, v76, v77
	v_cvt_pk_bf16_f32 v71, v78, v79
	v_rcp_f32_e32 v67, v64
	v_add_f32_e32 v64, 1.0, v65
	global_store_dwordx4 v[96:97], v[68:71], off
	v_cvt_pk_bf16_f32 v65, v101, v102
	s_nop 0
	v_rcp_f32_e32 v68, v64
	v_add_f32_e32 v64, 1.0, v66
	v_rcp_f32_e32 v69, v64
	v_cvt_pk_bf16_f32 v64, v99, v100
	v_cvt_pk_bf16_f32 v66, v103, v67
	v_cvt_pk_bf16_f32 v67, v68, v69
	global_store_dwordx4 v[96:97], v[64:67], off offset:256
	s_nop 0
	s_nop 0
	v_lshl_add_u64 v[64:65], v[162:163], 0, s[0:1]
	v_fmamk_f32 v66, v234, 0x3a800000, v176
	v_rsq_f32_e32 v68, v66
	v_add_co_u32_e32 v66, vcc, s57, v162
	v_fma_f32 v48, v48, v68, v72
	v_fma_f32 v49, v49, v68, v73
	v_mul_f32_e32 v48, 0xbfb8aa3b, v48
	v_fma_f32 v60, v60, v68, v92
	v_fma_f32 v61, v61, v68, v93
	v_fma_f32 v62, v62, v68, v94
	v_fma_f32 v63, v63, v68, v95
	v_fma_f32 v56, v56, v68, v88
	v_fma_f32 v57, v57, v68, v89
	v_fma_f32 v58, v58, v68, v90
	v_fma_f32 v59, v59, v68, v91
	v_mul_f32_e32 v49, 0xbfb8aa3b, v49
	v_exp_f32_e32 v48, v48
	v_mul_f32_e32 v60, 0xbfb8aa3b, v60
	v_mul_f32_e32 v61, 0xbfb8aa3b, v61
	v_mul_f32_e32 v62, 0xbfb8aa3b, v62
	v_mul_f32_e32 v63, 0xbfb8aa3b, v63
	v_mul_f32_e32 v56, 0xbfb8aa3b, v56
	v_mul_f32_e32 v57, 0xbfb8aa3b, v57
	v_mul_f32_e32 v58, 0xbfb8aa3b, v58
	v_mul_f32_e32 v59, 0xbfb8aa3b, v59
	v_exp_f32_e32 v49, v49
	v_exp_f32_e32 v60, v60
	v_exp_f32_e32 v61, v61
	v_exp_f32_e32 v62, v62
	v_exp_f32_e32 v63, v63
	v_exp_f32_e32 v56, v56
	v_exp_f32_e32 v57, v57
	v_exp_f32_e32 v58, v58
	v_exp_f32_e32 v59, v59
	v_fma_f32 v52, v52, v68, v84
	v_fma_f32 v53, v53, v68, v85
	v_fma_f32 v54, v54, v68, v86
	v_fma_f32 v55, v55, v68, v87
	v_add_f32_e32 v48, 1.0, v48
	v_mul_f32_e32 v52, 0xbfb8aa3b, v52
	v_mul_f32_e32 v53, 0xbfb8aa3b, v53
	v_mul_f32_e32 v54, 0xbfb8aa3b, v54
	v_mul_f32_e32 v55, 0xbfb8aa3b, v55
	v_rcp_f32_e32 v77, v48
	v_add_f32_e32 v48, 1.0, v49
	v_fma_f32 v49, v50, v68, v74
	v_exp_f32_e32 v52, v52
	v_exp_f32_e32 v53, v53
	v_exp_f32_e32 v54, v54
	v_exp_f32_e32 v55, v55
	v_add_f32_e32 v60, 1.0, v60
	v_add_f32_e32 v61, 1.0, v61
	v_add_f32_e32 v62, 1.0, v62
	v_add_f32_e32 v63, 1.0, v63
	v_add_f32_e32 v56, 1.0, v56
	v_add_f32_e32 v57, 1.0, v57
	v_add_f32_e32 v58, 1.0, v58
	v_add_f32_e32 v59, 1.0, v59
	v_mul_f32_e32 v49, 0xbfb8aa3b, v49
	v_fma_f32 v50, v51, v68, v75
	v_rcp_f32_e32 v60, v60
	v_rcp_f32_e32 v61, v61
	v_rcp_f32_e32 v62, v62
	v_rcp_f32_e32 v63, v63
	v_rcp_f32_e32 v56, v56
	v_rcp_f32_e32 v57, v57
	v_rcp_f32_e32 v58, v58
	v_rcp_f32_e32 v59, v59
	v_exp_f32_e32 v49, v49
	v_mul_f32_e32 v50, 0xbfb8aa3b, v50
	v_exp_f32_e32 v50, v50
	v_add_f32_e32 v52, 1.0, v52
	v_add_f32_e32 v53, 1.0, v53
	v_add_f32_e32 v54, 1.0, v54
	v_add_f32_e32 v55, 1.0, v55
	v_addc_co_u32_e32 v67, vcc, 0, v163, vcc
	v_rcp_f32_e32 v69, v52
	v_rcp_f32_e32 v70, v53
	v_rcp_f32_e32 v71, v54
	v_rcp_f32_e32 v76, v55
	v_cvt_pk_bf16_f32 v52, v60, v61
	v_cvt_pk_bf16_f32 v53, v62, v63
	v_cvt_pk_bf16_f32 v54, v56, v57
	v_cvt_pk_bf16_f32 v55, v58, v59
	v_rcp_f32_e32 v51, v48
	v_add_f32_e32 v48, 1.0, v49
	global_store_dwordx4 v[66:67], v[52:55], off
	v_cvt_pk_bf16_f32 v49, v71, v76
	s_nop 0
	v_rcp_f32_e32 v52, v48
	v_add_f32_e32 v48, 1.0, v50
	v_rcp_f32_e32 v53, v48
	v_cvt_pk_bf16_f32 v48, v69, v70
	v_cvt_pk_bf16_f32 v50, v77, v51
	v_cvt_pk_bf16_f32 v51, v52, v53
; DI unsigned pk2(float lo, float hi) { typedef float v2f __attribute__((ext_vector_type(2))); typedef __bf16 v2b __attribute__((ext_vector_type(2))); v2f v = {lo, hi}; v2b b = __builtin_convertvector(v, v2b); return __builtin_bit_cast(unsigned, b); }
; DI float sigmoidf_(float v) { return __builtin_amdgcn_rcpf(1.0f + __expf(-v)); }
;     DI void operator()(const f32x4 (&acc)[2][2][4][2], const Unit& u, int wr, int wc, int fr, int fq) const {
;     ...
;             for (int m = 0; m < 4; ++m) {
;                 const int row = row0 + ai * 128 + m * 16; const float rs = row_rstd<16>(P, row, 1.0f / 1024.0f);
; #pragma unroll
;                 for (int bj = 0; bj < 2; ++bj) {
;                     float v[8];
; #pragma unroll
;                     for (int n = 0; n < 2; ++n)
; #pragma unroll
;                         for (int i = 0; i < 4; ++i) v[4 * n + i] = sigmoidf_(acc[ai][bj][m][n][i] * rs + bv[bj][n][i]);
;                     u32x4 w; w.x = pk2(v[0], v[1]); w.y = pk2(v[2], v[3]); w.z = pk2(v[4], v[5]); w.w = pk2(v[6], v[7]);
;                     *(u32x4*)(G + (size_t)row * DM + cw + bj * 128) = w;
;                 }
;             }
	global_store_dwordx4 v[64:65], v[48:51], off offset:256
	s_nop 0
	s_nop 0
	v_lshl_add_u64 v[48:49], v[162:163], 0, s[14:15]
	v_fmamk_f32 v50, v235, 0x3a800000, v176
	v_rsq_f32_e32 v52, v50
	v_add_co_u32_e32 v50, vcc, s58, v162
	v_fma_f32 v32, v32, v52, v72
	v_fma_f32 v33, v33, v52, v73
	v_mul_f32_e32 v32, 0xbfb8aa3b, v32
	v_fma_f32 v44, v44, v52, v92
	v_fma_f32 v45, v45, v52, v93
	v_fma_f32 v46, v46, v52, v94
	v_fma_f32 v47, v47, v52, v95
	v_fma_f32 v40, v40, v52, v88
	v_fma_f32 v41, v41, v52, v89
	v_fma_f32 v42, v42, v52, v90
	v_fma_f32 v43, v43, v52, v91
	v_mul_f32_e32 v33, 0xbfb8aa3b, v33
	v_exp_f32_e32 v32, v32
	v_mul_f32_e32 v44, 0xbfb8aa3b, v44
	v_mul_f32_e32 v45, 0xbfb8aa3b, v45
	v_mul_f32_e32 v46, 0xbfb8aa3b, v46
	v_mul_f32_e32 v47, 0xbfb8aa3b, v47
	v_mul_f32_e32 v40, 0xbfb8aa3b, v40
	v_mul_f32_e32 v41, 0xbfb8aa3b, v41
	v_mul_f32_e32 v42, 0xbfb8aa3b, v42
	v_mul_f32_e32 v43, 0xbfb8aa3b, v43
	v_exp_f32_e32 v33, v33
	v_exp_f32_e32 v44, v44
	v_exp_f32_e32 v45, v45
	v_exp_f32_e32 v46, v46
	v_exp_f32_e32 v47, v47
	v_exp_f32_e32 v40, v40
	v_exp_f32_e32 v41, v41
	v_exp_f32_e32 v42, v42
	v_exp_f32_e32 v43, v43
	v_fma_f32 v36, v36, v52, v84
	v_fma_f32 v37, v37, v52, v85
	v_fma_f32 v38, v38, v52, v86
	v_fma_f32 v39, v39, v52, v87
	v_add_f32_e32 v32, 1.0, v32
	v_mul_f32_e32 v36, 0xbfb8aa3b, v36
	v_mul_f32_e32 v37, 0xbfb8aa3b, v37
	v_mul_f32_e32 v38, 0xbfb8aa3b, v38
	v_mul_f32_e32 v39, 0xbfb8aa3b, v39
	v_rcp_f32_e32 v57, v32
	v_add_f32_e32 v32, 1.0, v33
	v_fma_f32 v33, v34, v52, v74
	v_exp_f32_e32 v36, v36
	v_exp_f32_e32 v37, v37
	v_exp_f32_e32 v38, v38
	v_exp_f32_e32 v39, v39
	v_add_f32_e32 v44, 1.0, v44
	v_add_f32_e32 v45, 1.0, v45
	v_add_f32_e32 v46, 1.0, v46
	v_add_f32_e32 v47, 1.0, v47
	v_add_f32_e32 v40, 1.0, v40
	v_add_f32_e32 v41, 1.0, v41
	v_add_f32_e32 v42, 1.0, v42
	v_add_f32_e32 v43, 1.0, v43
	v_mul_f32_e32 v33, 0xbfb8aa3b, v33
	v_fma_f32 v34, v35, v52, v75
	v_rcp_f32_e32 v44, v44
	v_rcp_f32_e32 v45, v45
	v_rcp_f32_e32 v46, v46
	v_rcp_f32_e32 v47, v47
	v_rcp_f32_e32 v40, v40
	v_rcp_f32_e32 v41, v41
	v_rcp_f32_e32 v42, v42
	v_rcp_f32_e32 v43, v43
	v_exp_f32_e32 v33, v33
	v_mul_f32_e32 v34, 0xbfb8aa3b, v34
	v_exp_f32_e32 v34, v34
	v_add_f32_e32 v36, 1.0, v36
	v_add_f32_e32 v37, 1.0, v37
	v_add_f32_e32 v38, 1.0, v38
	v_add_f32_e32 v39, 1.0, v39
	v_addc_co_u32_e32 v51, vcc, 0, v163, vcc
	v_rcp_f32_e32 v53, v36
	v_rcp_f32_e32 v54, v37
	v_rcp_f32_e32 v55, v38
	v_rcp_f32_e32 v56, v39
	v_cvt_pk_bf16_f32 v36, v44, v45
	v_cvt_pk_bf16_f32 v37, v46, v47
	v_cvt_pk_bf16_f32 v38, v40, v41
	v_cvt_pk_bf16_f32 v39, v42, v43
	v_rcp_f32_e32 v35, v32
	v_add_f32_e32 v32, 1.0, v33
	global_store_dwordx4 v[50:51], v[36:39], off
	v_cvt_pk_bf16_f32 v33, v55, v56
	s_nop 0
	v_rcp_f32_e32 v36, v32
	v_add_f32_e32 v32, 1.0, v34
	v_rcp_f32_e32 v37, v32
	v_cvt_pk_bf16_f32 v32, v53, v54
	v_cvt_pk_bf16_f32 v34, v57, v35
	v_cvt_pk_bf16_f32 v35, v36, v37
	global_store_dwordx4 v[48:49], v[32:35], off offset:256
	s_nop 0
	s_nop 0
	v_lshl_add_u64 v[32:33], v[162:163], 0, s[16:17]
	v_fmamk_f32 v34, v236, 0x3a800000, v176
	v_rsq_f32_e32 v36, v34
	v_add_co_u32_e32 v34, vcc, s59, v162
	v_fma_f32 v16, v16, v36, v72
	v_fma_f32 v17, v17, v36, v73
	v_mul_f32_e32 v16, 0xbfb8aa3b, v16
	v_fma_f32 v28, v28, v36, v92
	v_fma_f32 v29, v29, v36, v93
	v_fma_f32 v30, v30, v36, v94
	v_fma_f32 v31, v31, v36, v95
	v_fma_f32 v24, v24, v36, v88
	v_fma_f32 v25, v25, v36, v89
	v_fma_f32 v26, v26, v36, v90
	v_fma_f32 v27, v27, v36, v91
	v_mul_f32_e32 v17, 0xbfb8aa3b, v17
	v_exp_f32_e32 v16, v16
	v_mul_f32_e32 v28, 0xbfb8aa3b, v28
	v_mul_f32_e32 v29, 0xbfb8aa3b, v29
	v_mul_f32_e32 v30, 0xbfb8aa3b, v30
	v_mul_f32_e32 v31, 0xbfb8aa3b, v31
	v_mul_f32_e32 v24, 0xbfb8aa3b, v24
	v_mul_f32_e32 v25, 0xbfb8aa3b, v25
	v_mul_f32_e32 v26, 0xbfb8aa3b, v26
	v_mul_f32_e32 v27, 0xbfb8aa3b, v27
	v_exp_f32_e32 v17, v17
	v_exp_f32_e32 v28, v28
	v_exp_f32_e32 v29, v29
	v_exp_f32_e32 v30, v30
	v_exp_f32_e32 v31, v31
	v_exp_f32_e32 v24, v24
	v_exp_f32_e32 v25, v25
	v_exp_f32_e32 v26, v26
	v_exp_f32_e32 v27, v27
	v_fma_f32 v20, v20, v36, v84
	v_fma_f32 v21, v21, v36, v85
	v_fma_f32 v22, v22, v36, v86
	v_fma_f32 v23, v23, v36, v87
	v_add_f32_e32 v16, 1.0, v16
	v_mul_f32_e32 v20, 0xbfb8aa3b, v20
	v_mul_f32_e32 v21, 0xbfb8aa3b, v21
	v_mul_f32_e32 v22, 0xbfb8aa3b, v22
	v_mul_f32_e32 v23, 0xbfb8aa3b, v23
	v_rcp_f32_e32 v41, v16
	v_add_f32_e32 v16, 1.0, v17
	v_fma_f32 v17, v18, v36, v74
; DI unsigned pk2(float lo, float hi) { typedef float v2f __attribute__((ext_vector_type(2))); typedef __bf16 v2b __attribute__((ext_vector_type(2))); v2f v = {lo, hi}; v2b b = __builtin_convertvector(v, v2b); return __builtin_bit_cast(unsigned, b); }
; DI float sigmoidf_(float v) { return __builtin_amdgcn_rcpf(1.0f + __expf(-v)); }
;     DI void operator()(const f32x4 (&acc)[2][2][4][2], const Unit& u, int wr, int wc, int fr, int fq) const {
;     ...
;             for (int m = 0; m < 4; ++m) {
;                 const int row = row0 + ai * 128 + m * 16; const float rs = row_rstd<16>(P, row, 1.0f / 1024.0f);
; #pragma unroll
;                 for (int bj = 0; bj < 2; ++bj) {
;                     float v[8];
; #pragma unroll
;                     for (int n = 0; n < 2; ++n)
; #pragma unroll
;                         for (int i = 0; i < 4; ++i) v[4 * n + i] = sigmoidf_(acc[ai][bj][m][n][i] * rs + bv[bj][n][i]);
;                     u32x4 w; w.x = pk2(v[0], v[1]); w.y = pk2(v[2], v[3]); w.z = pk2(v[4], v[5]); w.w = pk2(v[6], v[7]);
;                     *(u32x4*)(G + (size_t)row * DM + cw + bj * 128) = w;
;                 }
;             }
	v_exp_f32_e32 v20, v20
	v_exp_f32_e32 v21, v21
	v_exp_f32_e32 v22, v22
	v_exp_f32_e32 v23, v23
	v_add_f32_e32 v28, 1.0, v28
	v_add_f32_e32 v29, 1.0, v29
	v_add_f32_e32 v30, 1.0, v30
	v_add_f32_e32 v31, 1.0, v31
	v_add_f32_e32 v24, 1.0, v24
	v_add_f32_e32 v25, 1.0, v25
	v_add_f32_e32 v26, 1.0, v26
	v_add_f32_e32 v27, 1.0, v27
	v_mul_f32_e32 v17, 0xbfb8aa3b, v17
	v_fma_f32 v18, v19, v36, v75
	v_rcp_f32_e32 v28, v28
	v_rcp_f32_e32 v29, v29
	v_rcp_f32_e32 v30, v30
	v_rcp_f32_e32 v31, v31
	v_rcp_f32_e32 v24, v24
	v_rcp_f32_e32 v25, v25
	v_rcp_f32_e32 v26, v26
	v_rcp_f32_e32 v27, v27
	v_exp_f32_e32 v17, v17
	v_mul_f32_e32 v18, 0xbfb8aa3b, v18
	v_exp_f32_e32 v18, v18
	v_add_f32_e32 v20, 1.0, v20
	v_add_f32_e32 v21, 1.0, v21
	v_add_f32_e32 v22, 1.0, v22
	v_add_f32_e32 v23, 1.0, v23
	v_addc_co_u32_e32 v35, vcc, 0, v163, vcc
	v_rcp_f32_e32 v37, v20
	v_rcp_f32_e32 v38, v21
	v_rcp_f32_e32 v39, v22
	v_rcp_f32_e32 v40, v23
	v_cvt_pk_bf16_f32 v20, v28, v29
	v_cvt_pk_bf16_f32 v21, v30, v31
	v_cvt_pk_bf16_f32 v22, v24, v25
	v_cvt_pk_bf16_f32 v23, v26, v27
	v_rcp_f32_e32 v19, v16
	v_add_f32_e32 v16, 1.0, v17
	global_store_dwordx4 v[34:35], v[20:23], off
	v_cvt_pk_bf16_f32 v17, v39, v40
	s_nop 0
	v_rcp_f32_e32 v20, v16
	v_add_f32_e32 v16, 1.0, v18
	v_rcp_f32_e32 v21, v16
	v_cvt_pk_bf16_f32 v16, v37, v38
	v_cvt_pk_bf16_f32 v18, v41, v19
	v_cvt_pk_bf16_f32 v19, v20, v21
	global_store_dwordx4 v[32:33], v[16:19], off offset:256
	s_nop 0
	s_nop 0
	v_lshl_add_u64 v[16:17], v[162:163], 0, s[18:19]
	v_fmamk_f32 v18, v237, 0x3a800000, v176
	v_rsq_f32_e32 v20, v18
	v_add_co_u32_e32 v18, vcc, s60, v162
	v_fma_f32 v0, v0, v20, v72
	v_fma_f32 v1, v1, v20, v73
	v_mul_f32_e32 v0, 0xbfb8aa3b, v0
	v_fma_f32 v12, v12, v20, v92
	v_fma_f32 v13, v13, v20, v93
	v_fma_f32 v14, v14, v20, v94
	v_fmac_f32_e32 v95, v15, v20
	v_fma_f32 v8, v8, v20, v88
	v_fma_f32 v9, v9, v20, v89
	v_fma_f32 v10, v10, v20, v90
	v_fmac_f32_e32 v91, v11, v20
	v_mul_f32_e32 v1, 0xbfb8aa3b, v1
	v_exp_f32_e32 v0, v0
	v_fmac_f32_e32 v87, v7, v20
	v_mul_f32_e32 v7, 0xbfb8aa3b, v12
	v_mul_f32_e32 v11, 0xbfb8aa3b, v13
	v_mul_f32_e32 v12, 0xbfb8aa3b, v14
	v_mul_f32_e32 v13, 0xbfb8aa3b, v95
	v_mul_f32_e32 v8, 0xbfb8aa3b, v8
	v_mul_f32_e32 v9, 0xbfb8aa3b, v9
	v_mul_f32_e32 v10, 0xbfb8aa3b, v10
	v_mul_f32_e32 v14, 0xbfb8aa3b, v91
	v_exp_f32_e32 v1, v1
	v_exp_f32_e32 v7, v7
	v_exp_f32_e32 v11, v11
	v_exp_f32_e32 v12, v12
	v_exp_f32_e32 v13, v13
	v_exp_f32_e32 v8, v8
	v_exp_f32_e32 v9, v9
	v_exp_f32_e32 v10, v10
	v_exp_f32_e32 v14, v14
	v_fma_f32 v4, v4, v20, v84
	v_fma_f32 v5, v5, v20, v85
	v_fma_f32 v6, v6, v20, v86
	v_add_f32_e32 v0, 1.0, v0
	v_mul_f32_e32 v4, 0xbfb8aa3b, v4
	v_mul_f32_e32 v5, 0xbfb8aa3b, v5
	v_mul_f32_e32 v6, 0xbfb8aa3b, v6
	v_rcp_f32_e32 v24, v0
	v_add_f32_e32 v0, 1.0, v1
	v_fma_f32 v1, v2, v20, v74
	v_exp_f32_e32 v4, v4
	v_exp_f32_e32 v5, v5
	v_exp_f32_e32 v6, v6
	v_add_f32_e32 v7, 1.0, v7
	v_add_f32_e32 v11, 1.0, v11
	v_add_f32_e32 v12, 1.0, v12
	v_add_f32_e32 v13, 1.0, v13
	v_add_f32_e32 v8, 1.0, v8
	v_add_f32_e32 v9, 1.0, v9
	v_add_f32_e32 v10, 1.0, v10
	v_add_f32_e32 v14, 1.0, v14
	v_mul_f32_e32 v1, 0xbfb8aa3b, v1
	v_fmac_f32_e32 v75, v3, v20
	v_mul_f32_e32 v15, 0xbfb8aa3b, v87
	v_rcp_f32_e32 v7, v7
	v_rcp_f32_e32 v11, v11
	v_rcp_f32_e32 v12, v12
	v_rcp_f32_e32 v13, v13
	v_rcp_f32_e32 v8, v8
	v_rcp_f32_e32 v9, v9
	v_rcp_f32_e32 v10, v10
	v_rcp_f32_e32 v14, v14
	v_exp_f32_e32 v1, v1
	v_mul_f32_e32 v2, 0xbfb8aa3b, v75
	v_exp_f32_e32 v15, v15
	v_exp_f32_e32 v2, v2
	v_add_f32_e32 v4, 1.0, v4
	v_add_f32_e32 v5, 1.0, v5
	v_add_f32_e32 v6, 1.0, v6
	v_addc_co_u32_e32 v19, vcc, 0, v163, vcc
	v_rcp_f32_e32 v21, v4
	v_rcp_f32_e32 v22, v5
	v_rcp_f32_e32 v23, v6
	v_cvt_pk_bf16_f32 v4, v7, v11
	v_cvt_pk_bf16_f32 v5, v12, v13
	v_cvt_pk_bf16_f32 v6, v8, v9
	v_cvt_pk_bf16_f32 v7, v10, v14
	v_rcp_f32_e32 v3, v0
	v_add_f32_e32 v0, 1.0, v1
	v_add_f32_e32 v15, 1.0, v15
	global_store_dwordx4 v[18:19], v[4:7], off
	v_rcp_f32_e32 v15, v15
	s_andn2_b64 vcc, exec, s[2:3]
	v_rcp_f32_e32 v4, v0
	v_add_f32_e32 v0, 1.0, v2
	v_rcp_f32_e32 v5, v0
	v_cvt_pk_bf16_f32 v0, v21, v22
	v_cvt_pk_bf16_f32 v1, v23, v15
	v_cvt_pk_bf16_f32 v2, v24, v3
	v_cvt_pk_bf16_f32 v3, v4, v5
	s_mov_b64 s[2:3], -1
	global_store_dwordx4 v[16:17], v[0:3], off offset:256
	s_cbranch_vccnz .LBB0_1591
	s_andn2_b64 vcc, exec, s[4:5]
	s_cbranch_vccnz .LBB0_1590
	s_barrier
	s_branch .LBB0_1590

; DI unsigned pk2(float lo, float hi) { typedef float v2f __attribute__((ext_vector_type(2))); typedef __bf16 v2b __attribute__((ext_vector_type(2))); v2f v = {lo, hi}; v2b b = __builtin_convertvector(v, v2b); return __builtin_bit_cast(unsigned, b); }
; DI float siluf_(float v) { return v * sigmoidf_(v); }
;     DI void operator()(const f32x4 (&acc)[2][2][4][2], const Unit& u, int wr, int wc, int fr, int fq) const {
;     ...
; #pragma unroll
;         for (int ai = 0; ai < 2; ++ai)
; #pragma unroll
;             for (int m = 0; m < 4; ++m) {
;                 const int row = row0 + ai * 128 + m * 16; const float rs = row_rstd<NP>(P, row, 1.0f / 1024.0f);
;                 float a[8];
; #pragma unroll
;                 for (int n = 0; n < 2; ++n)
; #pragma unroll
;                     for (int i = 0; i < 4; ++i) { const float g = acc[ai][0][m][n][i] * rs, uu = acc[ai][1][m][n][i] * rs; a[4 * n + i] = siluf_(g) * uu; }
;                 u32x4 w; w.x = pk2(a[0], a[1]); w.y = pk2(a[2], a[3]); w.z = pk2(a[4], a[5]); w.w = pk2(a[6], a[7]);
;                 *(u32x4*)(O + (size_t)row * FF + col0) = w;
;             }
.Lp10_nopf:
	v_rsq_f32_e32 v164, v238
	s_nop 0
	v_pk_mul_f32 v[124:125], v[124:125], v[164:165] op_sel_hi:[1,0]
	v_pk_mul_f32 v[126:127], v[126:127], v[164:165] op_sel_hi:[1,0]
	v_pk_mul_f32 v[120:121], v[120:121], v[164:165] op_sel_hi:[1,0]
	v_pk_mul_f32 v[122:123], v[122:123], v[164:165] op_sel_hi:[1,0]
	v_pk_mul_f32 v[116:117], v[116:117], v[164:165] op_sel_hi:[1,0]
	v_pk_mul_f32 v[118:119], v[118:119], v[164:165] op_sel_hi:[1,0]
	v_pk_mul_f32 v[112:113], v[112:113], v[164:165] op_sel_hi:[1,0]
	v_pk_mul_f32 v[114:115], v[114:115], v[164:165] op_sel_hi:[1,0]
	v_mul_f32_e32 v145, 0xbfb8aa3b, v124
	v_mul_f32_e32 v159, 0xbfb8aa3b, v125
	v_mul_f32_e32 v163, 0xbfb8aa3b, v126
	v_mul_f32_e32 v164, 0xbfb8aa3b, v127
	v_mul_f32_e32 v165, 0xbfb8aa3b, v120
	v_mul_f32_e32 v168, 0xbfb8aa3b, v121
	v_mul_f32_e32 v169, 0xbfb8aa3b, v122
	v_mul_f32_e32 v170, 0xbfb8aa3b, v123
	v_exp_f32_e32 v145, v145
	v_exp_f32_e32 v159, v159
	v_exp_f32_e32 v163, v163
	v_exp_f32_e32 v164, v164
	v_exp_f32_e32 v165, v165
	v_exp_f32_e32 v168, v168
	v_exp_f32_e32 v169, v169
	v_exp_f32_e32 v170, v170
	v_add_f32_e32 v145, 1.0, v145
	v_add_f32_e32 v159, 1.0, v159
	v_add_f32_e32 v163, 1.0, v163
	v_add_f32_e32 v171, 1.0, v164
	v_add_f32_e32 v172, 1.0, v165
	v_add_f32_e32 v173, 1.0, v168
	v_add_f32_e32 v174, 1.0, v169
	v_add_f32_e32 v175, 1.0, v170
	v_rcp_f32_e32 v164, v145
	v_rcp_f32_e32 v165, v159
	v_rcp_f32_e32 v168, v163
	v_rcp_f32_e32 v169, v171
	v_rcp_f32_e32 v170, v172
	v_rcp_f32_e32 v171, v173
	v_rcp_f32_e32 v172, v174
	v_rcp_f32_e32 v173, v175
	v_pk_mul_f32 v[124:125], v[124:125], v[164:165]
	v_pk_mul_f32 v[126:127], v[126:127], v[168:169]
	v_pk_mul_f32 v[120:121], v[120:121], v[170:171]
	v_pk_mul_f32 v[122:123], v[122:123], v[172:173]
	v_pk_mul_f32 v[116:117], v[116:117], v[124:125]
	v_pk_mul_f32 v[118:119], v[118:119], v[126:127]
	v_pk_mul_f32 v[120:121], v[112:113], v[120:121]
	v_pk_mul_f32 v[122:123], v[114:115], v[122:123]
	v_cvt_pk_bf16_f32 v112, v116, v117
	v_cvt_pk_bf16_f32 v113, v118, v119
	v_cvt_pk_bf16_f32 v114, v120, v121
	v_cvt_pk_bf16_f32 v115, v122, v123
	global_store_dwordx4 v[160:161], v[112:115], off
	s_nop 0
	s_nop 0
	v_or_b32_e32 v112, 32, v144
	v_mad_i64_i32 v[114:115], s[12:13], v162, s54, v[146:147]
	v_lshl_add_u64 v[114:115], v[114:115], 0, v[148:149]
	v_rsq_f32_e32 v116, v239
	v_ashrrev_i32_e32 v113, 31, v112
	v_pk_mul_f32 v[108:109], v[108:109], v[116:117] op_sel_hi:[1,0]
	v_pk_mul_f32 v[110:111], v[110:111], v[116:117] op_sel_hi:[1,0]
	v_pk_mul_f32 v[104:105], v[104:105], v[116:117] op_sel_hi:[1,0]
	v_pk_mul_f32 v[106:107], v[106:107], v[116:117] op_sel_hi:[1,0]
	v_pk_mul_f32 v[100:101], v[100:101], v[116:117] op_sel_hi:[1,0]
	v_pk_mul_f32 v[102:103], v[102:103], v[116:117] op_sel_hi:[1,0]
	v_pk_mul_f32 v[96:97], v[96:97], v[116:117] op_sel_hi:[1,0]
	v_pk_mul_f32 v[98:99], v[98:99], v[116:117] op_sel_hi:[1,0]
	v_mul_f32_e32 v113, 0xbfb8aa3b, v108
	v_mul_f32_e32 v116, 0xbfb8aa3b, v109
	v_mul_f32_e32 v117, 0xbfb8aa3b, v110
	v_mul_f32_e32 v120, 0xbfb8aa3b, v111
	v_mul_f32_e32 v121, 0xbfb8aa3b, v104
	v_mul_f32_e32 v122, 0xbfb8aa3b, v105
	v_mul_f32_e32 v123, 0xbfb8aa3b, v106
	v_mul_f32_e32 v124, 0xbfb8aa3b, v107
	v_exp_f32_e32 v113, v113
	v_exp_f32_e32 v116, v116
	v_exp_f32_e32 v117, v117
	v_exp_f32_e32 v120, v120
	v_exp_f32_e32 v121, v121
	v_exp_f32_e32 v122, v122
	v_exp_f32_e32 v123, v123
	v_exp_f32_e32 v124, v124
	v_add_f32_e32 v113, 1.0, v113
	v_add_f32_e32 v125, 1.0, v116
	v_add_f32_e32 v126, 1.0, v117
	v_add_f32_e32 v127, 1.0, v120
	v_add_f32_e32 v145, 1.0, v121
	v_add_f32_e32 v159, 1.0, v122
	v_add_f32_e32 v160, 1.0, v123
	v_add_f32_e32 v161, 1.0, v124
	v_rcp_f32_e32 v116, v113
	v_rcp_f32_e32 v117, v125
	v_rcp_f32_e32 v120, v126
	v_rcp_f32_e32 v121, v127
	v_rcp_f32_e32 v122, v145
	v_rcp_f32_e32 v123, v159
	v_rcp_f32_e32 v124, v160
	v_rcp_f32_e32 v125, v161
	v_pk_mul_f32 v[108:109], v[108:109], v[116:117]
	v_pk_mul_f32 v[110:111], v[110:111], v[120:121]
	v_pk_mul_f32 v[104:105], v[104:105], v[122:123]
	v_pk_mul_f32 v[106:107], v[106:107], v[124:125]
	v_pk_mul_f32 v[100:101], v[100:101], v[108:109]
	v_pk_mul_f32 v[102:103], v[102:103], v[110:111]
	v_pk_mul_f32 v[104:105], v[96:97], v[104:105]
	v_pk_mul_f32 v[106:107], v[98:99], v[106:107]
	v_cvt_pk_bf16_f32 v96, v100, v101
	v_cvt_pk_bf16_f32 v97, v102, v103
	v_cvt_pk_bf16_f32 v98, v104, v105
	v_cvt_pk_bf16_f32 v99, v106, v107
	global_store_dwordx4 v[114:115], v[96:99], off
	s_nop 0
	s_nop 0
	v_or_b32_e32 v96, 48, v144
	v_mad_i64_i32 v[98:99], s[12:13], v112, s54, v[146:147]
	v_lshl_add_u64 v[98:99], v[98:99], 0, v[148:149]
	v_rsq_f32_e32 v100, v240
	v_ashrrev_i32_e32 v97, 31, v96
	v_pk_mul_f32 v[92:93], v[92:93], v[100:101] op_sel_hi:[1,0]
	v_pk_mul_f32 v[94:95], v[94:95], v[100:101] op_sel_hi:[1,0]
	v_pk_mul_f32 v[88:89], v[88:89], v[100:101] op_sel_hi:[1,0]
	v_pk_mul_f32 v[90:91], v[90:91], v[100:101] op_sel_hi:[1,0]
	v_pk_mul_f32 v[84:85], v[84:85], v[100:101] op_sel_hi:[1,0]
	v_pk_mul_f32 v[86:87], v[86:87], v[100:101] op_sel_hi:[1,0]
	v_pk_mul_f32 v[80:81], v[80:81], v[100:101] op_sel_hi:[1,0]
	v_pk_mul_f32 v[82:83], v[82:83], v[100:101] op_sel_hi:[1,0]
	v_mul_f32_e32 v97, 0xbfb8aa3b, v92
	v_mul_f32_e32 v100, 0xbfb8aa3b, v93
	v_mul_f32_e32 v101, 0xbfb8aa3b, v94
	v_mul_f32_e32 v104, 0xbfb8aa3b, v95
	v_mul_f32_e32 v105, 0xbfb8aa3b, v88
	v_mul_f32_e32 v106, 0xbfb8aa3b, v89
	v_mul_f32_e32 v107, 0xbfb8aa3b, v90
	v_mul_f32_e32 v108, 0xbfb8aa3b, v91
	v_exp_f32_e32 v97, v97
	v_exp_f32_e32 v100, v100
	v_exp_f32_e32 v101, v101
	v_exp_f32_e32 v104, v104
	v_exp_f32_e32 v105, v105
	v_exp_f32_e32 v106, v106
	v_exp_f32_e32 v107, v107
	v_exp_f32_e32 v108, v108
	v_add_f32_e32 v97, 1.0, v97
; DI unsigned pk2(float lo, float hi) { typedef float v2f __attribute__((ext_vector_type(2))); typedef __bf16 v2b __attribute__((ext_vector_type(2))); v2f v = {lo, hi}; v2b b = __builtin_convertvector(v, v2b); return __builtin_bit_cast(unsigned, b); }
; DI float siluf_(float v) { return v * sigmoidf_(v); }
;     DI void operator()(const f32x4 (&acc)[2][2][4][2], const Unit& u, int wr, int wc, int fr, int fq) const {
;     ...
; #pragma unroll
;         for (int ai = 0; ai < 2; ++ai)
; #pragma unroll
;             for (int m = 0; m < 4; ++m) {
;                 const int row = row0 + ai * 128 + m * 16; const float rs = row_rstd<NP>(P, row, 1.0f / 1024.0f);
;                 float a[8];
; #pragma unroll
;                 for (int n = 0; n < 2; ++n)
; #pragma unroll
;                     for (int i = 0; i < 4; ++i) { const float g = acc[ai][0][m][n][i] * rs, uu = acc[ai][1][m][n][i] * rs; a[4 * n + i] = siluf_(g) * uu; }
;                 u32x4 w; w.x = pk2(a[0], a[1]); w.y = pk2(a[2], a[3]); w.z = pk2(a[4], a[5]); w.w = pk2(a[6], a[7]);
;                 *(u32x4*)(O + (size_t)row * FF + col0) = w;
;             }
	v_add_f32_e32 v109, 1.0, v100
	v_add_f32_e32 v110, 1.0, v101
	v_add_f32_e32 v111, 1.0, v104
	v_add_f32_e32 v112, 1.0, v105
	v_add_f32_e32 v113, 1.0, v106
	v_add_f32_e32 v114, 1.0, v107
	v_add_f32_e32 v115, 1.0, v108
	v_rcp_f32_e32 v100, v97
	v_rcp_f32_e32 v101, v109
	v_rcp_f32_e32 v104, v110
	v_rcp_f32_e32 v105, v111
	v_rcp_f32_e32 v106, v112
	v_rcp_f32_e32 v107, v113
	v_rcp_f32_e32 v108, v114
	v_rcp_f32_e32 v109, v115
	v_pk_mul_f32 v[92:93], v[92:93], v[100:101]
	v_pk_mul_f32 v[94:95], v[94:95], v[104:105]
	v_pk_mul_f32 v[88:89], v[88:89], v[106:107]
	v_pk_mul_f32 v[90:91], v[90:91], v[108:109]
	v_pk_mul_f32 v[84:85], v[84:85], v[92:93]
	v_pk_mul_f32 v[86:87], v[86:87], v[94:95]
	v_pk_mul_f32 v[88:89], v[80:81], v[88:89]
	v_pk_mul_f32 v[90:91], v[82:83], v[90:91]
	v_cvt_pk_bf16_f32 v80, v84, v85
	v_cvt_pk_bf16_f32 v81, v86, v87
	v_cvt_pk_bf16_f32 v82, v88, v89
	v_cvt_pk_bf16_f32 v83, v90, v91
	global_store_dwordx4 v[98:99], v[80:83], off
	s_nop 0
	s_nop 0
	v_mad_i64_i32 v[82:83], s[12:13], v96, s54, v[146:147]
	v_lshl_add_u64 v[82:83], v[82:83], 0, v[148:149]
	v_rsq_f32_e32 v80, v241
	s_nop 0
	v_pk_mul_f32 v[76:77], v[76:77], v[80:81] op_sel_hi:[1,0]
	v_pk_mul_f32 v[78:79], v[78:79], v[80:81] op_sel_hi:[1,0]
	v_pk_mul_f32 v[72:73], v[72:73], v[80:81] op_sel_hi:[1,0]
	v_pk_mul_f32 v[74:75], v[74:75], v[80:81] op_sel_hi:[1,0]
	v_pk_mul_f32 v[68:69], v[68:69], v[80:81] op_sel_hi:[1,0]
	v_pk_mul_f32 v[70:71], v[70:71], v[80:81] op_sel_hi:[1,0]
	v_pk_mul_f32 v[64:65], v[64:65], v[80:81] op_sel_hi:[1,0]
	v_pk_mul_f32 v[66:67], v[66:67], v[80:81] op_sel_hi:[1,0]
	v_mul_f32_e32 v80, 0xbfb8aa3b, v76
	v_mul_f32_e32 v81, 0xbfb8aa3b, v77
	v_mul_f32_e32 v84, 0xbfb8aa3b, v78
	v_mul_f32_e32 v85, 0xbfb8aa3b, v79
	v_mul_f32_e32 v86, 0xbfb8aa3b, v72
	v_mul_f32_e32 v87, 0xbfb8aa3b, v73
	v_mul_f32_e32 v88, 0xbfb8aa3b, v74
	v_mul_f32_e32 v89, 0xbfb8aa3b, v75
	v_exp_f32_e32 v80, v80
	v_exp_f32_e32 v81, v81
	v_exp_f32_e32 v84, v84
	v_exp_f32_e32 v85, v85
	v_exp_f32_e32 v86, v86
	v_exp_f32_e32 v87, v87
	v_exp_f32_e32 v88, v88
	v_exp_f32_e32 v89, v89
	v_add_f32_e32 v80, 1.0, v80
	v_add_f32_e32 v81, 1.0, v81
	v_add_f32_e32 v84, 1.0, v84
	v_add_f32_e32 v85, 1.0, v85
	v_add_f32_e32 v86, 1.0, v86
	v_add_f32_e32 v87, 1.0, v87
	v_add_f32_e32 v88, 1.0, v88
	v_add_f32_e32 v89, 1.0, v89
	v_rcp_f32_e32 v80, v80
	v_rcp_f32_e32 v81, v81
	v_rcp_f32_e32 v84, v84
	v_rcp_f32_e32 v85, v85
	v_rcp_f32_e32 v86, v86
	v_rcp_f32_e32 v87, v87
	v_rcp_f32_e32 v88, v88
	v_rcp_f32_e32 v89, v89
	v_pk_mul_f32 v[76:77], v[76:77], v[80:81]
	v_pk_mul_f32 v[78:79], v[78:79], v[84:85]
	v_pk_mul_f32 v[72:73], v[72:73], v[86:87]
	v_pk_mul_f32 v[74:75], v[74:75], v[88:89]
	v_pk_mul_f32 v[68:69], v[68:69], v[76:77]
	v_pk_mul_f32 v[70:71], v[70:71], v[78:79]
	v_pk_mul_f32 v[72:73], v[64:65], v[72:73]
	v_pk_mul_f32 v[74:75], v[66:67], v[74:75]
	v_cvt_pk_bf16_f32 v64, v68, v69
	v_cvt_pk_bf16_f32 v65, v70, v71
	v_cvt_pk_bf16_f32 v66, v72, v73
	v_cvt_pk_bf16_f32 v67, v74, v75
	global_store_dwordx4 v[82:83], v[64:67], off
	s_nop 0
	s_nop 0
	v_add_u32_e32 v65, 0x80, v144
	v_mad_i64_i32 v[66:67], s[12:13], v65, s54, v[146:147]
	v_lshl_add_u64 v[66:67], v[66:67], 0, v[148:149]
	v_rsq_f32_e32 v64, v242
	s_nop 0
	v_pk_mul_f32 v[60:61], v[60:61], v[64:65] op_sel_hi:[1,0]
	v_pk_mul_f32 v[62:63], v[62:63], v[64:65] op_sel_hi:[1,0]
	v_pk_mul_f32 v[56:57], v[56:57], v[64:65] op_sel_hi:[1,0]
	v_pk_mul_f32 v[58:59], v[58:59], v[64:65] op_sel_hi:[1,0]
	v_pk_mul_f32 v[52:53], v[52:53], v[64:65] op_sel_hi:[1,0]
	v_pk_mul_f32 v[54:55], v[54:55], v[64:65] op_sel_hi:[1,0]
	v_pk_mul_f32 v[48:49], v[48:49], v[64:65] op_sel_hi:[1,0]
	v_pk_mul_f32 v[50:51], v[50:51], v[64:65] op_sel_hi:[1,0]
	v_mul_f32_e32 v64, 0xbfb8aa3b, v60
	v_mul_f32_e32 v65, 0xbfb8aa3b, v61
	v_mul_f32_e32 v68, 0xbfb8aa3b, v62
	v_mul_f32_e32 v69, 0xbfb8aa3b, v63
	v_mul_f32_e32 v70, 0xbfb8aa3b, v56
	v_mul_f32_e32 v71, 0xbfb8aa3b, v57
	v_mul_f32_e32 v72, 0xbfb8aa3b, v58
	v_mul_f32_e32 v73, 0xbfb8aa3b, v59
	v_exp_f32_e32 v64, v64
	v_exp_f32_e32 v65, v65
	v_exp_f32_e32 v68, v68
	v_exp_f32_e32 v69, v69
	v_exp_f32_e32 v70, v70
	v_exp_f32_e32 v71, v71
	v_exp_f32_e32 v72, v72
	v_exp_f32_e32 v73, v73
	v_add_f32_e32 v64, 1.0, v64
	v_add_f32_e32 v65, 1.0, v65
	v_add_f32_e32 v68, 1.0, v68
	v_add_f32_e32 v69, 1.0, v69
	v_add_f32_e32 v70, 1.0, v70
	v_add_f32_e32 v71, 1.0, v71
	v_add_f32_e32 v72, 1.0, v72
	v_add_f32_e32 v73, 1.0, v73
	v_rcp_f32_e32 v64, v64
	v_rcp_f32_e32 v65, v65
	v_rcp_f32_e32 v68, v68
	v_rcp_f32_e32 v69, v69
	v_rcp_f32_e32 v70, v70
	v_rcp_f32_e32 v71, v71
	v_rcp_f32_e32 v72, v72
	v_rcp_f32_e32 v73, v73
	v_pk_mul_f32 v[60:61], v[60:61], v[64:65]
	v_pk_mul_f32 v[62:63], v[62:63], v[68:69]
	v_pk_mul_f32 v[56:57], v[56:57], v[70:71]
	v_pk_mul_f32 v[58:59], v[58:59], v[72:73]
	v_pk_mul_f32 v[52:53], v[52:53], v[60:61]
	v_pk_mul_f32 v[54:55], v[54:55], v[62:63]
	v_pk_mul_f32 v[56:57], v[48:49], v[56:57]
	v_pk_mul_f32 v[58:59], v[50:51], v[58:59]
	v_cvt_pk_bf16_f32 v48, v52, v53
	v_cvt_pk_bf16_f32 v49, v54, v55
	v_cvt_pk_bf16_f32 v50, v56, v57
	v_cvt_pk_bf16_f32 v51, v58, v59
	global_store_dwordx4 v[66:67], v[48:51], off
	s_nop 0
	s_nop 0
	v_add_u32_e32 v49, 0x90, v144
	v_mad_i64_i32 v[50:51], s[12:13], v49, s54, v[146:147]
	v_lshl_add_u64 v[50:51], v[50:51], 0, v[148:149]
	v_rsq_f32_e32 v48, v243
	s_nop 0
	v_pk_mul_f32 v[44:45], v[44:45], v[48:49] op_sel_hi:[1,0]
	v_pk_mul_f32 v[46:47], v[46:47], v[48:49] op_sel_hi:[1,0]
	v_pk_mul_f32 v[40:41], v[40:41], v[48:49] op_sel_hi:[1,0]
	v_pk_mul_f32 v[42:43], v[42:43], v[48:49] op_sel_hi:[1,0]
	v_pk_mul_f32 v[36:37], v[36:37], v[48:49] op_sel_hi:[1,0]
	v_pk_mul_f32 v[38:39], v[38:39], v[48:49] op_sel_hi:[1,0]
; DI unsigned pk2(float lo, float hi) { typedef float v2f __attribute__((ext_vector_type(2))); typedef __bf16 v2b __attribute__((ext_vector_type(2))); v2f v = {lo, hi}; v2b b = __builtin_convertvector(v, v2b); return __builtin_bit_cast(unsigned, b); }
; DI float siluf_(float v) { return v * sigmoidf_(v); }
;     DI void operator()(const f32x4 (&acc)[2][2][4][2], const Unit& u, int wr, int wc, int fr, int fq) const {
;     ...
; #pragma unroll
;         for (int ai = 0; ai < 2; ++ai)
; #pragma unroll
;             for (int m = 0; m < 4; ++m) {
;                 const int row = row0 + ai * 128 + m * 16; const float rs = row_rstd<NP>(P, row, 1.0f / 1024.0f);
;                 float a[8];
; #pragma unroll
;                 for (int n = 0; n < 2; ++n)
; #pragma unroll
;                     for (int i = 0; i < 4; ++i) { const float g = acc[ai][0][m][n][i] * rs, uu = acc[ai][1][m][n][i] * rs; a[4 * n + i] = siluf_(g) * uu; }
;                 u32x4 w; w.x = pk2(a[0], a[1]); w.y = pk2(a[2], a[3]); w.z = pk2(a[4], a[5]); w.w = pk2(a[6], a[7]);
;                 *(u32x4*)(O + (size_t)row * FF + col0) = w;
;             }
	v_pk_mul_f32 v[32:33], v[32:33], v[48:49] op_sel_hi:[1,0]
	v_pk_mul_f32 v[34:35], v[34:35], v[48:49] op_sel_hi:[1,0]
	v_mul_f32_e32 v48, 0xbfb8aa3b, v44
	v_mul_f32_e32 v49, 0xbfb8aa3b, v45
	v_mul_f32_e32 v52, 0xbfb8aa3b, v46
	v_mul_f32_e32 v53, 0xbfb8aa3b, v47
	v_mul_f32_e32 v54, 0xbfb8aa3b, v40
	v_mul_f32_e32 v55, 0xbfb8aa3b, v41
	v_mul_f32_e32 v56, 0xbfb8aa3b, v42
	v_mul_f32_e32 v57, 0xbfb8aa3b, v43
	v_exp_f32_e32 v48, v48
	v_exp_f32_e32 v49, v49
	v_exp_f32_e32 v52, v52
	v_exp_f32_e32 v53, v53
	v_exp_f32_e32 v54, v54
	v_exp_f32_e32 v55, v55
	v_exp_f32_e32 v56, v56
	v_exp_f32_e32 v57, v57
	v_add_f32_e32 v48, 1.0, v48
	v_add_f32_e32 v49, 1.0, v49
	v_add_f32_e32 v52, 1.0, v52
	v_add_f32_e32 v53, 1.0, v53
	v_add_f32_e32 v54, 1.0, v54
	v_add_f32_e32 v55, 1.0, v55
	v_add_f32_e32 v56, 1.0, v56
	v_add_f32_e32 v57, 1.0, v57
	v_rcp_f32_e32 v48, v48
	v_rcp_f32_e32 v49, v49
	v_rcp_f32_e32 v52, v52
	v_rcp_f32_e32 v53, v53
	v_rcp_f32_e32 v54, v54
	v_rcp_f32_e32 v55, v55
	v_rcp_f32_e32 v56, v56
	v_rcp_f32_e32 v57, v57
	v_pk_mul_f32 v[44:45], v[44:45], v[48:49]
	v_pk_mul_f32 v[46:47], v[46:47], v[52:53]
	v_pk_mul_f32 v[40:41], v[40:41], v[54:55]
	v_pk_mul_f32 v[42:43], v[42:43], v[56:57]
	v_pk_mul_f32 v[36:37], v[36:37], v[44:45]
	v_pk_mul_f32 v[38:39], v[38:39], v[46:47]
	v_pk_mul_f32 v[40:41], v[32:33], v[40:41]
	v_pk_mul_f32 v[42:43], v[34:35], v[42:43]
	v_cvt_pk_bf16_f32 v32, v36, v37
	v_cvt_pk_bf16_f32 v33, v38, v39
	v_cvt_pk_bf16_f32 v34, v40, v41
	v_cvt_pk_bf16_f32 v35, v42, v43
	global_store_dwordx4 v[50:51], v[32:35], off
	s_nop 0
	s_nop 0
	v_add_u32_e32 v33, 0xa0, v144
	v_mad_i64_i32 v[34:35], s[12:13], v33, s54, v[146:147]
	v_lshl_add_u64 v[34:35], v[34:35], 0, v[148:149]
	v_rsq_f32_e32 v32, v244
	s_nop 0
	v_pk_mul_f32 v[28:29], v[28:29], v[32:33] op_sel_hi:[1,0]
	v_pk_mul_f32 v[30:31], v[30:31], v[32:33] op_sel_hi:[1,0]
	v_pk_mul_f32 v[24:25], v[24:25], v[32:33] op_sel_hi:[1,0]
	v_pk_mul_f32 v[26:27], v[26:27], v[32:33] op_sel_hi:[1,0]
	v_pk_mul_f32 v[20:21], v[20:21], v[32:33] op_sel_hi:[1,0]
	v_pk_mul_f32 v[22:23], v[22:23], v[32:33] op_sel_hi:[1,0]
	v_pk_mul_f32 v[16:17], v[16:17], v[32:33] op_sel_hi:[1,0]
	v_pk_mul_f32 v[18:19], v[18:19], v[32:33] op_sel_hi:[1,0]
	v_mul_f32_e32 v32, 0xbfb8aa3b, v28
	v_mul_f32_e32 v33, 0xbfb8aa3b, v29
	v_mul_f32_e32 v36, 0xbfb8aa3b, v30
	v_mul_f32_e32 v37, 0xbfb8aa3b, v31
	v_mul_f32_e32 v38, 0xbfb8aa3b, v24
	v_mul_f32_e32 v39, 0xbfb8aa3b, v25
	v_mul_f32_e32 v40, 0xbfb8aa3b, v26
	v_mul_f32_e32 v41, 0xbfb8aa3b, v27
	v_exp_f32_e32 v32, v32
	v_exp_f32_e32 v33, v33
	v_exp_f32_e32 v36, v36
	v_exp_f32_e32 v37, v37
	v_exp_f32_e32 v38, v38
	v_exp_f32_e32 v39, v39
	v_exp_f32_e32 v40, v40
	v_exp_f32_e32 v41, v41
	v_add_f32_e32 v32, 1.0, v32
	v_add_f32_e32 v33, 1.0, v33
	v_add_f32_e32 v36, 1.0, v36
	v_add_f32_e32 v37, 1.0, v37
	v_add_f32_e32 v38, 1.0, v38
	v_add_f32_e32 v39, 1.0, v39
	v_add_f32_e32 v40, 1.0, v40
	v_add_f32_e32 v41, 1.0, v41
	v_rcp_f32_e32 v32, v32
	v_rcp_f32_e32 v33, v33
	v_rcp_f32_e32 v36, v36
	v_rcp_f32_e32 v37, v37
	v_rcp_f32_e32 v38, v38
	v_rcp_f32_e32 v39, v39
	v_rcp_f32_e32 v40, v40
	v_rcp_f32_e32 v41, v41
	v_pk_mul_f32 v[28:29], v[28:29], v[32:33]
	v_pk_mul_f32 v[30:31], v[30:31], v[36:37]
	v_pk_mul_f32 v[24:25], v[24:25], v[38:39]
	v_pk_mul_f32 v[26:27], v[26:27], v[40:41]
	v_pk_mul_f32 v[20:21], v[20:21], v[28:29]
	v_pk_mul_f32 v[22:23], v[22:23], v[30:31]
	v_pk_mul_f32 v[24:25], v[16:17], v[24:25]
	v_pk_mul_f32 v[26:27], v[18:19], v[26:27]
	v_cvt_pk_bf16_f32 v16, v20, v21
	v_cvt_pk_bf16_f32 v17, v22, v23
	v_cvt_pk_bf16_f32 v18, v24, v25
	v_cvt_pk_bf16_f32 v19, v26, v27
	global_store_dwordx4 v[34:35], v[16:19], off
	s_nop 0
	s_nop 0
	v_add_u32_e32 v17, 0xb0, v144
	v_mad_i64_i32 v[18:19], s[12:13], v17, s54, v[146:147]
	v_lshl_add_u64 v[18:19], v[18:19], 0, v[148:149]
	v_rsq_f32_e32 v16, v245
	s_nop 0
	v_pk_mul_f32 v[12:13], v[12:13], v[16:17] op_sel_hi:[1,0]
	v_pk_mul_f32 v[14:15], v[14:15], v[16:17] op_sel_hi:[1,0]
	v_pk_mul_f32 v[8:9], v[8:9], v[16:17] op_sel_hi:[1,0]
	v_pk_mul_f32 v[10:11], v[10:11], v[16:17] op_sel_hi:[1,0]
	v_pk_mul_f32 v[4:5], v[4:5], v[16:17] op_sel_hi:[1,0]
	v_pk_mul_f32 v[6:7], v[6:7], v[16:17] op_sel_hi:[1,0]
	v_pk_mul_f32 v[0:1], v[0:1], v[16:17] op_sel_hi:[1,0]
	v_pk_mul_f32 v[2:3], v[2:3], v[16:17] op_sel_hi:[1,0]
	v_mul_f32_e32 v16, 0xbfb8aa3b, v12
	v_mul_f32_e32 v17, 0xbfb8aa3b, v13
	v_mul_f32_e32 v20, 0xbfb8aa3b, v14
	v_mul_f32_e32 v21, 0xbfb8aa3b, v15
	v_mul_f32_e32 v22, 0xbfb8aa3b, v8
	v_mul_f32_e32 v23, 0xbfb8aa3b, v9
	v_mul_f32_e32 v24, 0xbfb8aa3b, v10
	v_mul_f32_e32 v25, 0xbfb8aa3b, v11
	v_exp_f32_e32 v16, v16
	v_exp_f32_e32 v17, v17
	v_exp_f32_e32 v20, v20
	v_exp_f32_e32 v21, v21
	v_exp_f32_e32 v22, v22
	v_exp_f32_e32 v23, v23
	v_exp_f32_e32 v24, v24
	v_exp_f32_e32 v25, v25
	v_add_f32_e32 v16, 1.0, v16
	v_add_f32_e32 v17, 1.0, v17
	v_add_f32_e32 v20, 1.0, v20
	v_add_f32_e32 v21, 1.0, v21
	v_add_f32_e32 v22, 1.0, v22
	v_add_f32_e32 v23, 1.0, v23
	v_add_f32_e32 v24, 1.0, v24
	v_add_f32_e32 v25, 1.0, v25
	v_rcp_f32_e32 v16, v16
	v_rcp_f32_e32 v17, v17
	v_rcp_f32_e32 v20, v20
	v_rcp_f32_e32 v21, v21
	v_rcp_f32_e32 v22, v22
	v_rcp_f32_e32 v23, v23
	v_rcp_f32_e32 v24, v24
	v_rcp_f32_e32 v25, v25
	v_pk_mul_f32 v[12:13], v[12:13], v[16:17]
	v_pk_mul_f32 v[14:15], v[14:15], v[20:21]
	v_pk_mul_f32 v[8:9], v[8:9], v[22:23]
	v_pk_mul_f32 v[10:11], v[10:11], v[24:25]
	v_pk_mul_f32 v[4:5], v[4:5], v[12:13]
	v_pk_mul_f32 v[6:7], v[6:7], v[14:15]
	v_pk_mul_f32 v[8:9], v[0:1], v[8:9]
	v_pk_mul_f32 v[10:11], v[2:3], v[10:11]
	v_cvt_pk_bf16_f32 v0, v4, v5
	v_cvt_pk_bf16_f32 v1, v6, v7
	v_cvt_pk_bf16_f32 v2, v8, v9
	v_cvt_pk_bf16_f32 v3, v10, v11
	global_store_dwordx4 v[18:19], v[0:3], off
	s_cbranch_vccnz .LBB0_1819
	s_andn2_b64 vcc, exec, s[4:5]
	s_cbranch_vccnz .LBB0_1818
	s_barrier
	s_branch .LBB0_1818
